# flat_* global-memory ops converted to global_* (LDS-aperture volatile flats kept)
# baseline (speedup 1.0000x reference)
; __device__ __forceinline__ int my_tid() { int t = (int)threadIdx.x; asm volatile("" : "+v"(t)); return t; }
; __device__ __forceinline__ int my_bid() { int t = (int)blockIdx.x; asm volatile("" : "+s"(t)); return t; }
; __device__ __forceinline__ int my_gdim() { int t = (int)gridDim.x; asm volatile("" : "+s"(t)); return t; }
; __device__ void phase_final_norm(const float* xin, const float* g, float* out) {
;     const int tid = my_tid(), wid = tid >> 6, lane = tid & 63;
;     const int gw = my_bid() * 8 + wid, nw = my_gdim() * 8;
;     f32x4 gv[4];
; #pragma unroll
;     for (int i = 0; i < 4; ++i) gv[i] = *(const f32x4*)(g + i * 256 + lane * 4);
;     for (int rb = gw * 4; rb < MTOK; rb += nw * 4) {
;         f32x4 x[4][4];
; #pragma unroll
;         for (int q = 0; q < 4; ++q)
; #pragma unroll
;             for (int i = 0; i < 4; ++i) x[q][i] = __builtin_nontemporal_load((const f32x4*)(xin + (size_t)(rb + q) * DM + i * 256 + lane * 4));
; #pragma unroll
;         for (int q = 0; q < 4; ++q) { float ss = 0.f;
; #pragma unroll
;             for (int i = 0; i < 4; ++i) ss += (x[q][i][0] * x[q][i][0] + x[q][i][1] * x[q][i][1]) + (x[q][i][2] * x[q][i][2] + x[q][i][3] * x[q][i][3]);
;             ss = wave_sum(ss);
;             const float rstd = rsqrtf(ss * (1.0f / DM) + EPS);
; #pragma unroll
;             for (int i = 0; i < 4; ++i) __builtin_nontemporal_store(x[q][i] * rstd * gv[i], (f32x4*)(out + (size_t)(rb + q) * DM + i * 256 + lane * 4)); }
;     }
; __device__ void run_phase(const Params& p, unsigned char* lds, int ph) {
;     unsigned char* ws = p.ws;
;     float* xs = p.out;
;     float* modp = (float*)(ws + WS_MOD);
;     bf16_t* hbuf = (bf16_t*)(ws + WS_HBUF);
;     if (ph == 0) { phase_prologue(p, lds); return; }
;     if (ph == N_PHASES - 1) { phase_final_norm(xs, p.in[I_FNG], p.out); return; }
.LBB0_11:
	v_readlane_b32 s12, v254, 23
	v_readlane_b32 s13, v254, 24
	v_readlane_b32 s14, v254, 25
	v_readlane_b32 s15, v254, 26
	s_mov_b64 s[6:7], s[12:13]
	s_mov_b64 s[0:1], s[14:15]
	v_readlane_b32 s16, v254, 27
	v_readlane_b32 s17, v254, 28
	v_readlane_b32 s18, v254, 29
	v_readlane_b32 s19, v254, 30
	v_readlane_b32 s20, v254, 31
	v_readlane_b32 s21, v254, 32
	v_readlane_b32 s22, v254, 33
	v_readlane_b32 s23, v254, 34
	v_readlane_b32 s24, v254, 35
	v_readlane_b32 s25, v254, 36
	v_readlane_b32 s26, v254, 37
	v_readlane_b32 s27, v254, 38
	v_writelane_b32 v254, s0, 55
	s_mov_b64 s[82:83], s[18:19]
	s_mov_b64 s[8:9], s[64:65]
	v_writelane_b32 v254, s1, 56
	s_mov_b64 s[0:1], s[16:17]
	s_mov_b64 s[10:11], s[66:67]
	v_writelane_b32 v254, s0, 57
	s_mov_b64 s[90:91], s[24:25]
	s_nop 0
	v_writelane_b32 v254, s1, 58
	s_mov_b64 s[0:1], s[20:21]
	s_mov_b64 s[20:21], s[26:27]
	v_writelane_b32 v254, s0, 59
	s_nop 1
	v_writelane_b32 v254, s1, 60
	s_nop 0
	v_readlane_b32 s56, v254, 39
	v_readlane_b32 s57, v254, 40
	v_readlane_b32 s58, v254, 41
	v_readlane_b32 s59, v254, 42
	v_readlane_b32 s60, v254, 43
	v_readlane_b32 s61, v254, 44
	v_readlane_b32 s62, v254, 45
	v_readlane_b32 s63, v254, 46
	s_mov_b64 s[26:27], s[56:57]
	s_mov_b64 s[2:3], s[58:59]
	s_mov_b64 s[16:17], s[60:61]
	s_mov_b64 s[0:1], s[62:63]
	v_readlane_b32 s64, v254, 47
	v_readlane_b32 s65, v254, 48
	v_readlane_b32 s66, v254, 49
	v_readlane_b32 s67, v254, 50
	v_readlane_b32 s68, v254, 51
	v_readlane_b32 s69, v254, 52
	v_readlane_b32 s70, v254, 53
	v_readlane_b32 s71, v254, 54
	v_writelane_b32 v254, s0, 61
	s_mov_b64 s[4:5], s[66:67]
	s_mov_b64 s[60:61], s[68:69]
	v_writelane_b32 v254, s1, 62
	s_mov_b64 s[0:1], s[64:65]
	s_mov_b64 s[66:67], s[10:11]
	v_writelane_b32 v254, s0, 63
	s_mov_b64 s[64:65], s[8:9]
	v_readlane_b32 s12, v254, 19
	v_readlane_b32 s13, v254, 20
	v_readlane_b32 s14, v254, 21
	v_readlane_b32 s15, v254, 22
	v_readlane_b32 s18, v254, 17
	v_writelane_b32 v255, s1, 0
	s_mov_b64 s[8:9], s[70:71]
	s_mov_b64 s[62:63], s[12:13]
	s_mov_b64 s[0:1], s[14:15]
	s_mov_b64 s[86:87], s[64:65]
	v_readlane_b32 s19, v254, 18
	s_mov_b64 s[14:15], -1
	s_mov_b64 s[10:11], 0
	s_cmp_lt_i32 s66, 17
	s_mov_b64 s[12:13], 0
	s_mov_b64 s[68:69], s[20:21]
	s_cbranch_scc1 .LBB0_24
	s_cmp_eq_u32 s66, 17
	s_mov_b64 s[12:13], -1
	s_cbranch_scc0 .LBB0_17
	s_waitcnt vmcnt(0)
	v_mov_b32_e32 v18, v212
	v_readlane_b32 s12, v254, 0
	v_ashrrev_i32_e32 v0, 4, v18
	v_and_b32_e32 v0, -4, v0
	v_lshl_add_u32 v66, s12, 5, v0
	s_mov_b32 s12, 0x8000
	s_load_dword s14, s[80:81], 0x0
	v_cmp_gt_i32_e32 vcc, s12, v66
	s_waitcnt lgkmcnt(0)
	s_and_saveexec_b64 s[12:13], vcc
	s_cbranch_execz .LBB0_16
	v_lshlrev_b32_e32 v0, 4, v18
	v_and_b32_e32 v0, 0x3f0, v0
	v_lshl_add_u64 v[14:15], s[0:1], 0, v[0:1]
	global_load_dwordx4 v[2:5], v[14:15], off
	global_load_dwordx4 v[6:9], v[14:15], off offset:1024
	global_load_dwordx4 v[10:13], v[14:15], off offset:2048
	s_nop 0
	global_load_dwordx4 v[14:17], v[14:15], off offset:3072
	v_ashrrev_i32_e32 v67, 31, v66
	v_lshlrev_b64 v[20:21], 12, v[66:67]
	v_and_b32_e32 v0, 63, v18
	s_lshl_b32 s14, s14, 5
	v_lshl_or_b32 v20, v0, 4, v20
	v_lshl_add_u64 v[18:19], s[18:19], 0, v[20:21]
	s_mov_b64 s[0:1], 0x3c00
	s_ashr_i32 s15, s14, 31
	v_lshl_add_u64 v[68:69], v[18:19], 0, s[0:1]
	s_lshl_b64 s[20:21], s[14:15], 12
	s_mov_b64 s[24:25], 0
.LBB0_15:
	v_add_co_u32_e32 v110, vcc, 0xffffc400, v68
	v_add_u32_e32 v66, s14, v66
	s_nop 0
	v_addc_co_u32_e32 v111, vcc, -1, v69, vcc
	v_add_co_u32_e32 v112, vcc, 0xffffc800, v68
	s_nop 1
	v_addc_co_u32_e32 v113, vcc, -1, v69, vcc
	global_load_dwordx4 v[94:97], v[110:111], off nt
	global_load_dwordx4 v[98:101], v[112:113], off nt
	v_add_co_u32_e32 v114, vcc, 0xffffcc00, v68
	s_mov_b64 s[0:1], vcc
	v_add_co_u32_e32 v86, vcc, 0xffffd000, v68
	s_waitcnt vmcnt(0) lgkmcnt(0)
	v_pk_mul_f32 v[26:27], v[96:97], v[96:97]
	v_addc_co_u32_e32 v87, vcc, -1, v69, vcc
	global_load_dwordx4 v[102:105], v[86:87], off nt
	v_addc_co_u32_e64 v115, vcc, -1, v69, s[0:1]
	global_load_dwordx4 v[106:109], v[114:115], off nt
	v_add_co_u32_e32 v88, vcc, 0xffffd400, v68
	v_pk_mul_f32 v[28:29], v[94:95], v[94:95]
	s_nop 0
	v_addc_co_u32_e32 v89, vcc, -1, v69, vcc
	v_add_co_u32_e32 v90, vcc, 0xffffd800, v68
	v_pk_mov_b32 v[42:43], v[28:29], v[26:27] op_sel:[1,0]
	s_nop 0
	v_addc_co_u32_e32 v91, vcc, -1, v69, vcc
	global_load_dwordx4 v[58:61], v[88:89], off nt
	global_load_dwordx4 v[50:53], v[90:91], off nt
	v_add_co_u32_e32 v92, vcc, 0xffffdc00, v68
	v_mov_b32_e32 v29, v27
	s_nop 0
	v_addc_co_u32_e32 v93, vcc, -1, v69, vcc
	v_add_co_u32_e32 v80, vcc, 0xffffe000, v68
	v_pk_add_f32 v[26:27], v[42:43], v[28:29]
	s_nop 0
	v_addc_co_u32_e32 v81, vcc, -1, v69, vcc
	global_load_dwordx4 v[62:65], v[92:93], off nt
	global_load_dwordx4 v[54:57], v[80:81], off nt
	v_add_co_u32_e32 v78, vcc, 0xffffe400, v68
	v_pk_mul_f32 v[28:29], v[100:101], v[100:101]
	s_nop 0
	v_addc_co_u32_e32 v79, vcc, -1, v69, vcc
	v_add_co_u32_e32 v82, vcc, 0xffffe800, v68
	v_pk_mul_f32 v[42:43], v[98:99], v[98:99]
	s_nop 0
	v_addc_co_u32_e32 v83, vcc, -1, v69, vcc
	global_load_dwordx4 v[38:41], v[78:79], off nt
	global_load_dwordx4 v[30:33], v[82:83], off nt
	v_add_co_u32_e32 v84, vcc, 0xffffec00, v68
	v_pk_mov_b32 v[44:45], v[42:43], v[28:29] op_sel:[1,0]
	s_nop 0
	v_addc_co_u32_e32 v85, vcc, -1, v69, vcc
	v_add_co_u32_e32 v72, vcc, 0xfffff000, v68
	v_mov_b32_e32 v43, v29
	s_nop 0
	v_addc_co_u32_e32 v73, vcc, -1, v69, vcc
	global_load_dwordx4 v[46:49], v[84:85], off nt
	global_load_dwordx4 v[34:37], v[72:73], off nt
	v_pk_add_f32 v[28:29], v[44:45], v[42:43]
	v_pk_add_f32 v[26:27], v[26:27], v[26:27] op_sel:[0,1] op_sel_hi:[1,0]
	v_pk_add_f32 v[28:29], v[28:29], v[28:29] op_sel:[0,1] op_sel_hi:[1,0]
	v_add_co_u32_e32 v70, vcc, 0xfffff400, v68
	s_waitcnt vmcnt(0) lgkmcnt(0)
; __device__ void phase_final_norm(const float* xin, const float* g, float* out) {
;     ...
;         for (int q = 0; q < 4; ++q) { float ss = 0.f;
; #pragma unroll
;             for (int i = 0; i < 4; ++i) ss += (x[q][i][0] * x[q][i][0] + x[q][i][1] * x[q][i][1]) + (x[q][i][2] * x[q][i][2] + x[q][i][3] * x[q][i][3]);
;             ss = wave_sum(ss);
;             const float rstd = rsqrtf(ss * (1.0f / DM) + EPS);
; #pragma unroll
;             for (int i = 0; i < 4; ++i) __builtin_nontemporal_store(x[q][i] * rstd * gv[i], (f32x4*)(out + (size_t)(rb + q) * DM + i * 256 + lane * 4)); }
	v_mul_f32_e32 v0, v102, v102
	v_mul_f32_e32 v42, v103, v103
	v_mov_b32_e32 v27, v0
	v_mov_b32_e32 v29, v42
	v_mul_f32_e32 v0, v107, v107
	v_mul_f32_e32 v43, v104, v104
	v_pk_add_f32 v[26:27], v[26:27], v[28:29]
	v_pk_fma_f32 v[28:29], v[106:107], v[106:107], v[0:1] op_sel_hi:[1,1,0]
	v_mul_f32_e32 v0, v109, v109
	v_mul_f32_e32 v44, v105, v105
	v_mov_b32_e32 v29, v43
	v_pk_fma_f32 v[42:43], v[108:109], v[108:109], v[0:1] op_sel_hi:[1,1,0]
	v_addc_co_u32_e32 v71, vcc, -1, v69, vcc
	v_mov_b32_e32 v43, v44
	v_pk_add_f32 v[28:29], v[28:29], v[42:43]
	v_add_co_u32_e32 v74, vcc, 0xfffff800, v68
	v_pk_add_f32 v[26:27], v[26:27], v[28:29]
	s_nop 0
	v_addc_co_u32_e32 v75, vcc, -1, v69, vcc
	v_add_f32_e32 v0, v26, v27
	v_mov_b32_e32 v26, v1
	global_load_dwordx4 v[22:25], v[70:71], off nt
	global_load_dwordx4 v[18:21], v[74:75], off nt
	v_add_f32_dpp v0, v0, v0 row_shr:1 row_mask:0xf bank_mask:0xf bound_ctrl:1
	v_add_co_u32_e32 v76, vcc, 0xfffffc00, v68
	s_nop 0
	v_add_f32_dpp v0, v0, v0 row_shr:2 row_mask:0xf bank_mask:0xf bound_ctrl:1
	v_addc_co_u32_e32 v77, vcc, -1, v69, vcc
	s_nop 0
	v_add_f32_dpp v0, v0, v0 row_shr:4 row_mask:0xf bank_mask:0xf bound_ctrl:1
	s_nop 1
	v_add_f32_dpp v0, v0, v0 row_shr:8 row_mask:0xf bank_mask:0xf bound_ctrl:1
	s_nop 1
	v_mov_b32_dpp v26, v0 row_bcast:15 row_mask:0xa bank_mask:0xf
	v_add_f32_e32 v0, v0, v26
	v_mov_b32_e32 v26, v1
	s_nop 1
	v_mov_b32_dpp v26, v0 row_bcast:31 row_mask:0xc bank_mask:0xf
	v_add_f32_e32 v0, v0, v26
	s_nop 0
	v_readlane_b32 s0, v0, 63
	s_nop 1
	v_fma_f32 v0, s0, v217, v213
	v_mul_f32_e32 v26, 0x4b800000, v0
	v_cmp_gt_f32_e64 s[0:1], s44, v0
	s_nop 1
	v_cndmask_b32_e64 v0, v0, v26, s[0:1]
	v_rsq_f32_e32 v0, v0
	global_load_dwordx4 v[42:45], v[76:77], off nt
	global_load_dwordx4 v[26:29], v[68:69], off nt
	v_mul_f32_e32 v67, 0x45800000, v0
	v_cndmask_b32_e64 v0, v0, v67, s[0:1]
	v_pk_mul_f32 v[94:95], v[94:95], v[0:1] op_sel_hi:[1,0]
	v_pk_mul_f32 v[96:97], v[96:97], v[0:1] op_sel_hi:[1,0]
	v_pk_mul_f32 v[94:95], v[2:3], v[94:95]
	v_pk_mul_f32 v[96:97], v[4:5], v[96:97]
	global_store_dwordx4 v[110:111], v[94:97], off nt
	v_mul_f32_e32 v67, v55, v55
	s_nop 0
	v_pk_mul_f32 v[94:95], v[98:99], v[0:1] op_sel_hi:[1,0]
	v_pk_mul_f32 v[96:97], v[100:101], v[0:1] op_sel_hi:[1,0]
	v_pk_mul_f32 v[94:95], v[6:7], v[94:95]
	v_pk_mul_f32 v[96:97], v[8:9], v[96:97]
	global_store_dwordx4 v[112:113], v[94:97], off nt
	v_pk_mul_f32 v[98:99], v[60:61], v[60:61]
	v_pk_mul_f32 v[100:101], v[58:59], v[58:59]
	v_pk_mul_f32 v[94:95], v[106:107], v[0:1] op_sel_hi:[1,0]
	v_pk_mul_f32 v[96:97], v[108:109], v[0:1] op_sel_hi:[1,0]
	v_pk_mul_f32 v[94:95], v[10:11], v[94:95]
	v_pk_mul_f32 v[96:97], v[12:13], v[96:97]
	global_store_dwordx4 v[114:115], v[94:97], off nt
	s_nop 1
	v_pk_mul_f32 v[94:95], v[102:103], v[0:1] op_sel_hi:[1,0]
	v_pk_mov_b32 v[102:103], v[100:101], v[98:99] op_sel:[1,0]
	v_mov_b32_e32 v101, v99
	v_pk_add_f32 v[98:99], v[102:103], v[100:101]
	v_pk_mul_f32 v[100:101], v[52:53], v[52:53]
	v_pk_mul_f32 v[102:103], v[50:51], v[50:51]
	v_pk_mul_f32 v[96:97], v[104:105], v[0:1] op_sel_hi:[1,0]
	v_pk_mov_b32 v[104:105], v[102:103], v[100:101] op_sel:[1,0]
	v_mov_b32_e32 v103, v101
	v_pk_add_f32 v[100:101], v[104:105], v[102:103]
	v_mul_f32_e32 v0, v54, v54
	v_pk_add_f32 v[98:99], v[98:99], v[98:99] op_sel:[0,1] op_sel_hi:[1,0]
	v_pk_add_f32 v[100:101], v[100:101], v[100:101] op_sel:[0,1] op_sel_hi:[1,0]
	v_mov_b32_e32 v99, v0
	v_mov_b32_e32 v101, v67
	v_mul_f32_e32 v0, v63, v63
	v_mul_f32_e32 v102, v56, v56
	v_pk_add_f32 v[98:99], v[98:99], v[100:101]
	v_pk_fma_f32 v[100:101], v[62:63], v[62:63], v[0:1] op_sel_hi:[1,1,0]
	v_mul_f32_e32 v0, v65, v65
	v_mul_f32_e32 v104, v57, v57
	v_mov_b32_e32 v101, v102
	v_pk_fma_f32 v[102:103], v[64:65], v[64:65], v[0:1] op_sel_hi:[1,1,0]
	v_mov_b32_e32 v67, v1
	v_mov_b32_e32 v103, v104
	v_pk_add_f32 v[100:101], v[100:101], v[102:103]
	v_pk_mul_f32 v[96:97], v[16:17], v[96:97]
	v_pk_add_f32 v[98:99], v[98:99], v[100:101]
	v_pk_mul_f32 v[94:95], v[14:15], v[94:95]
	v_add_f32_e32 v0, v98, v99
	global_store_dwordx4 v[86:87], v[94:97], off nt
	s_nop 0
	v_add_f32_dpp v0, v0, v0 row_shr:1 row_mask:0xf bank_mask:0xf bound_ctrl:1
	s_nop 1
	v_add_f32_dpp v0, v0, v0 row_shr:2 row_mask:0xf bank_mask:0xf bound_ctrl:1
	s_nop 1
	v_add_f32_dpp v0, v0, v0 row_shr:4 row_mask:0xf bank_mask:0xf bound_ctrl:1
	s_nop 1
	v_add_f32_dpp v0, v0, v0 row_shr:8 row_mask:0xf bank_mask:0xf bound_ctrl:1
	s_nop 1
	v_mov_b32_dpp v67, v0 row_bcast:15 row_mask:0xa bank_mask:0xf
	v_add_f32_e32 v0, v0, v67
	v_mov_b32_e32 v67, v1
	s_nop 1
	v_mov_b32_dpp v67, v0 row_bcast:31 row_mask:0xc bank_mask:0xf
	v_add_f32_e32 v0, v0, v67
	s_nop 0
	v_readlane_b32 s0, v0, 63
	s_nop 1
	v_fma_f32 v0, s0, v217, v213
	v_mul_f32_e32 v67, 0x4b800000, v0
	v_cmp_gt_f32_e32 vcc, s44, v0
	s_nop 1
	v_cndmask_b32_e32 v0, v0, v67, vcc
	v_rsq_f32_e32 v0, v0
	s_nop 0
	v_mul_f32_e32 v67, 0x45800000, v0
	v_cndmask_b32_e32 v0, v0, v67, vcc
	v_pk_mul_f32 v[50:51], v[50:51], v[0:1] op_sel_hi:[1,0]
	v_pk_mul_f32 v[52:53], v[52:53], v[0:1] op_sel_hi:[1,0]
	v_pk_mul_f32 v[50:51], v[6:7], v[50:51]
	v_pk_mul_f32 v[52:53], v[8:9], v[52:53]
	global_store_dwordx4 v[90:91], v[50:53], off nt
	v_pk_mul_f32 v[58:59], v[58:59], v[0:1] op_sel_hi:[1,0]
	v_pk_mul_f32 v[60:61], v[60:61], v[0:1] op_sel_hi:[1,0]
	v_pk_mul_f32 v[50:51], v[62:63], v[0:1] op_sel_hi:[1,0]
	v_pk_mul_f32 v[52:53], v[64:65], v[0:1] op_sel_hi:[1,0]
	v_pk_mul_f32 v[50:51], v[10:11], v[50:51]
	v_pk_mul_f32 v[52:53], v[12:13], v[52:53]
	v_pk_mul_f32 v[60:61], v[4:5], v[60:61]
	v_pk_mul_f32 v[58:59], v[2:3], v[58:59]
	global_store_dwordx4 v[92:93], v[50:53], off nt
; __device__ void phase_final_norm(const float* xin, const float* g, float* out) {
;     ...
;     for (int rb = gw * 4; rb < MTOK; rb += nw * 4) {
;         f32x4 x[4][4];
; #pragma unroll
;         for (int q = 0; q < 4; ++q)
; #pragma unroll
;             for (int i = 0; i < 4; ++i) x[q][i] = __builtin_nontemporal_load((const f32x4*)(xin + (size_t)(rb + q) * DM + i * 256 + lane * 4));
; #pragma unroll
;         for (int q = 0; q < 4; ++q) { float ss = 0.f;
; #pragma unroll
;             for (int i = 0; i < 4; ++i) ss += (x[q][i][0] * x[q][i][0] + x[q][i][1] * x[q][i][1]) + (x[q][i][2] * x[q][i][2] + x[q][i][3] * x[q][i][3]);
;             ss = wave_sum(ss);
;             const float rstd = rsqrtf(ss * (1.0f / DM) + EPS);
; #pragma unroll
;             for (int i = 0; i < 4; ++i) __builtin_nontemporal_store(x[q][i] * rstd * gv[i], (f32x4*)(out + (size_t)(rb + q) * DM + i * 256 + lane * 4)); }
;     }
	global_store_dwordx4 v[88:89], v[58:61], off nt
	s_nop 0
	v_pk_mul_f32 v[50:51], v[54:55], v[0:1] op_sel_hi:[1,0]
	v_pk_mul_f32 v[52:53], v[56:57], v[0:1] op_sel_hi:[1,0]
	v_pk_mul_f32 v[54:55], v[40:41], v[40:41]
	v_pk_mul_f32 v[56:57], v[38:39], v[38:39]
	v_mul_f32_e32 v0, v34, v34
	v_pk_mov_b32 v[58:59], v[56:57], v[54:55] op_sel:[1,0]
	v_mov_b32_e32 v57, v55
	v_pk_add_f32 v[54:55], v[58:59], v[56:57]
	v_pk_mul_f32 v[56:57], v[32:33], v[32:33]
	v_pk_mul_f32 v[58:59], v[30:31], v[30:31]
	v_pk_add_f32 v[54:55], v[54:55], v[54:55] op_sel:[0,1] op_sel_hi:[1,0]
	v_pk_mov_b32 v[60:61], v[58:59], v[56:57] op_sel:[1,0]
	v_mov_b32_e32 v59, v57
	v_pk_add_f32 v[56:57], v[60:61], v[58:59]
	v_mul_f32_e32 v58, v35, v35
	v_pk_add_f32 v[56:57], v[56:57], v[56:57] op_sel:[0,1] op_sel_hi:[1,0]
	v_mov_b32_e32 v55, v0
	v_mov_b32_e32 v57, v58
	v_mul_f32_e32 v0, v47, v47
	v_mul_f32_e32 v59, v36, v36
	v_pk_add_f32 v[54:55], v[54:55], v[56:57]
	v_pk_fma_f32 v[56:57], v[46:47], v[46:47], v[0:1] op_sel_hi:[1,1,0]
	v_mul_f32_e32 v0, v49, v49
	v_mul_f32_e32 v60, v37, v37
	v_mov_b32_e32 v57, v59
	v_pk_fma_f32 v[58:59], v[48:49], v[48:49], v[0:1] op_sel_hi:[1,1,0]
	v_pk_mul_f32 v[52:53], v[16:17], v[52:53]
	v_mov_b32_e32 v59, v60
	v_pk_add_f32 v[56:57], v[56:57], v[58:59]
	v_pk_mul_f32 v[50:51], v[14:15], v[50:51]
	v_pk_add_f32 v[54:55], v[54:55], v[56:57]
	global_store_dwordx4 v[80:81], v[50:53], off nt
	v_add_f32_e32 v0, v54, v55
	v_mov_b32_e32 v54, v1
	s_nop 0
	v_add_f32_dpp v0, v0, v0 row_shr:1 row_mask:0xf bank_mask:0xf bound_ctrl:1
	s_nop 1
	v_add_f32_dpp v0, v0, v0 row_shr:2 row_mask:0xf bank_mask:0xf bound_ctrl:1
	s_nop 1
	v_add_f32_dpp v0, v0, v0 row_shr:4 row_mask:0xf bank_mask:0xf bound_ctrl:1
	s_nop 1
	v_add_f32_dpp v0, v0, v0 row_shr:8 row_mask:0xf bank_mask:0xf bound_ctrl:1
	s_nop 1
	v_mov_b32_dpp v54, v0 row_bcast:15 row_mask:0xa bank_mask:0xf
	v_add_f32_e32 v0, v0, v54
	v_mov_b32_e32 v54, v1
	s_nop 1
	v_mov_b32_dpp v54, v0 row_bcast:31 row_mask:0xc bank_mask:0xf
	v_add_f32_e32 v0, v0, v54
	s_nop 0
	v_readlane_b32 s0, v0, 63
	s_nop 1
	v_fma_f32 v0, s0, v217, v213
	v_mul_f32_e32 v54, 0x4b800000, v0
	v_cmp_gt_f32_e32 vcc, s44, v0
	s_nop 1
	v_cndmask_b32_e32 v0, v0, v54, vcc
	v_rsq_f32_e32 v0, v0
	s_nop 0
	v_mul_f32_e32 v50, 0x45800000, v0
	v_cndmask_b32_e32 v0, v0, v50, vcc
	v_pk_mul_f32 v[30:31], v[30:31], v[0:1] op_sel_hi:[1,0]
	v_pk_mul_f32 v[32:33], v[32:33], v[0:1] op_sel_hi:[1,0]
	v_pk_mul_f32 v[30:31], v[6:7], v[30:31]
	v_pk_mul_f32 v[32:33], v[8:9], v[32:33]
	global_store_dwordx4 v[82:83], v[30:33], off nt
	v_pk_mul_f32 v[38:39], v[38:39], v[0:1] op_sel_hi:[1,0]
	v_pk_mul_f32 v[40:41], v[40:41], v[0:1] op_sel_hi:[1,0]
	v_pk_mul_f32 v[30:31], v[46:47], v[0:1] op_sel_hi:[1,0]
	v_pk_mul_f32 v[32:33], v[48:49], v[0:1] op_sel_hi:[1,0]
	v_pk_mul_f32 v[30:31], v[10:11], v[30:31]
	v_pk_mul_f32 v[32:33], v[12:13], v[32:33]
	v_pk_mul_f32 v[40:41], v[4:5], v[40:41]
	v_pk_mul_f32 v[38:39], v[2:3], v[38:39]
	global_store_dwordx4 v[84:85], v[30:33], off nt
	global_store_dwordx4 v[78:79], v[38:41], off nt
	s_nop 0
	v_pk_mul_f32 v[30:31], v[34:35], v[0:1] op_sel_hi:[1,0]
	v_pk_mul_f32 v[32:33], v[36:37], v[0:1] op_sel_hi:[1,0]
	s_waitcnt vmcnt(0) lgkmcnt(0)
	v_pk_mul_f32 v[34:35], v[24:25], v[24:25]
	v_pk_mul_f32 v[36:37], v[22:23], v[22:23]
	v_mul_f32_e32 v0, v26, v26
	v_pk_mov_b32 v[38:39], v[36:37], v[34:35] op_sel:[1,0]
	v_mov_b32_e32 v37, v35
	v_pk_add_f32 v[34:35], v[38:39], v[36:37]
	v_pk_mul_f32 v[36:37], v[20:21], v[20:21]
	v_pk_mul_f32 v[38:39], v[18:19], v[18:19]
	v_pk_add_f32 v[34:35], v[34:35], v[34:35] op_sel:[0,1] op_sel_hi:[1,0]
	v_pk_mov_b32 v[40:41], v[38:39], v[36:37] op_sel:[1,0]
	v_mov_b32_e32 v39, v37
	v_pk_add_f32 v[36:37], v[40:41], v[38:39]
	v_mul_f32_e32 v38, v27, v27
	v_pk_add_f32 v[36:37], v[36:37], v[36:37] op_sel:[0,1] op_sel_hi:[1,0]
	v_mov_b32_e32 v35, v0
	v_mov_b32_e32 v37, v38
	v_mul_f32_e32 v0, v43, v43
	v_mul_f32_e32 v39, v28, v28
	v_pk_add_f32 v[34:35], v[34:35], v[36:37]
	v_pk_fma_f32 v[36:37], v[42:43], v[42:43], v[0:1] op_sel_hi:[1,1,0]
	v_mul_f32_e32 v0, v45, v45
	v_mul_f32_e32 v40, v29, v29
	v_mov_b32_e32 v37, v39
	v_pk_fma_f32 v[38:39], v[44:45], v[44:45], v[0:1] op_sel_hi:[1,1,0]
	v_pk_mul_f32 v[32:33], v[16:17], v[32:33]
	v_mov_b32_e32 v39, v40
	v_pk_add_f32 v[36:37], v[36:37], v[38:39]
	v_pk_mul_f32 v[30:31], v[14:15], v[30:31]
	v_pk_add_f32 v[34:35], v[34:35], v[36:37]
	global_store_dwordx4 v[72:73], v[30:33], off nt
	v_add_f32_e32 v0, v34, v35
	v_mov_b32_e32 v34, v1
	s_nop 0
	v_add_f32_dpp v0, v0, v0 row_shr:1 row_mask:0xf bank_mask:0xf bound_ctrl:1
	s_nop 1
	v_add_f32_dpp v0, v0, v0 row_shr:2 row_mask:0xf bank_mask:0xf bound_ctrl:1
	s_nop 1
	v_add_f32_dpp v0, v0, v0 row_shr:4 row_mask:0xf bank_mask:0xf bound_ctrl:1
	s_nop 1
	v_add_f32_dpp v0, v0, v0 row_shr:8 row_mask:0xf bank_mask:0xf bound_ctrl:1
	s_nop 1
	v_mov_b32_dpp v34, v0 row_bcast:15 row_mask:0xa bank_mask:0xf
	v_add_f32_e32 v0, v0, v34
	v_mov_b32_e32 v34, v1
	s_nop 1
	v_mov_b32_dpp v34, v0 row_bcast:31 row_mask:0xc bank_mask:0xf
	v_add_f32_e32 v0, v0, v34
	s_nop 0
	v_readlane_b32 s0, v0, 63
	s_nop 1
	v_fma_f32 v0, s0, v217, v213
	v_mul_f32_e32 v34, 0x4b800000, v0
	v_cmp_gt_f32_e32 vcc, s44, v0
	s_nop 1
	v_cndmask_b32_e32 v0, v0, v34, vcc
	v_rsq_f32_e32 v0, v0
	s_nop 0
	v_mul_f32_e32 v30, 0x45800000, v0
	v_cndmask_b32_e32 v0, v0, v30, vcc
	v_pk_mul_f32 v[18:19], v[18:19], v[0:1] op_sel_hi:[1,0]
	v_pk_mul_f32 v[20:21], v[20:21], v[0:1] op_sel_hi:[1,0]
	v_pk_mul_f32 v[18:19], v[6:7], v[18:19]
	v_pk_mul_f32 v[20:21], v[8:9], v[20:21]
	global_store_dwordx4 v[74:75], v[18:21], off nt
	v_pk_mul_f32 v[22:23], v[22:23], v[0:1] op_sel_hi:[1,0]
	v_pk_mul_f32 v[24:25], v[24:25], v[0:1] op_sel_hi:[1,0]
	v_pk_mul_f32 v[18:19], v[42:43], v[0:1] op_sel_hi:[1,0]
	v_pk_mul_f32 v[20:21], v[44:45], v[0:1] op_sel_hi:[1,0]
	v_pk_mul_f32 v[18:19], v[10:11], v[18:19]
	v_pk_mul_f32 v[20:21], v[12:13], v[20:21]
	global_store_dwordx4 v[76:77], v[18:21], off nt
	v_cmp_lt_i32_e32 vcc, s72, v66
	v_pk_mul_f32 v[24:25], v[4:5], v[24:25]
	v_pk_mul_f32 v[18:19], v[26:27], v[0:1] op_sel_hi:[1,0]
	v_pk_mul_f32 v[20:21], v[28:29], v[0:1] op_sel_hi:[1,0]
	v_pk_mul_f32 v[18:19], v[14:15], v[18:19]
	v_pk_mul_f32 v[20:21], v[16:17], v[20:21]
	v_pk_mul_f32 v[22:23], v[2:3], v[22:23]
	global_store_dwordx4 v[68:69], v[18:21], off nt
	s_or_b64 s[24:25], vcc, s[24:25]
	v_lshl_add_u64 v[68:69], v[68:69], 0, s[20:21]
	global_store_dwordx4 v[70:71], v[22:25], off nt
	s_andn2_b64 exec, exec, s[24:25]
	s_cbranch_execnz .LBB0_15

; __device__ __forceinline__ unsigned pack2(float lo, float hi) { return pg8::cvt_pk_bf16(lo, hi); }
; __device__ __forceinline__ float silu_f(float x) { return x * __builtin_amdgcn_rcpf(1.0f + __expf(-x)); }
; __device__ void fix_panel(const float* halo, const float* cw  , bf16_t* act, int pm) {
;     ...
;         float a0[8], a1[8];
; #pragma unroll
;         for (int q = 0; q < 2; ++q) {
;             const f32x4 z4 = (f32x4){0.f, 0.f, 0.f, 0.f};
;             const f32x4 g0 = *(const f32x4*)(ht + 4 * q), g1 = *(const f32x4*)(ht + 256 + 4 * q), u0 = *(const f32x4*)(ht + 128 + 4 * q), u1 = *(const f32x4*)(ht + 384 + 4 * q);
;             const f32x4 gb0 = first ? z4 : *(const f32x4*)(hp + 512 + 4 * q), gb1 = first ? z4 : *(const f32x4*)(hp + 768 + 4 * q);
;             const f32x4 ub0 = first ? z4 : *(const f32x4*)(hp + 640 + 4 * q), ub1 = first ? z4 : *(const f32x4*)(hp + 896 + 4 * q);
;             const f32x4 wg0 = *(const f32x4*)(cw + j + 4 * q), wg1 = *(const f32x4*)(cw + NUP + j + 4 * q), wg2 = *(const f32x4*)(cw + 2 * NUP + j + 4 * q);
;             const f32x4 wu0 = *(const f32x4*)(cw + DFF + j + 4 * q), wu1 = *(const f32x4*)(cw + NUP + DFF + j + 4 * q), wu2 = *(const f32x4*)(cw + 2 * NUP + DFF + j + 4 * q);
; #pragma unroll
;             for (int e = 0; e < 4; ++e) {
;                 a0[4 * q + e] = silu_f(wg0[e] * gb0[e] + wg1[e] * gb1[e] + wg2[e] * g0[e]) * (wu0[e] * ub0[e] + wu1[e] * ub1[e] + wu2[e] * u0[e]);
;                 a1[4 * q + e] = silu_f(wg0[e] * gb1[e] + wg1[e] * g0[e] + wg2[e] * g1[e]) * (wu0[e] * ub1[e] + wu1[e] * u0[e] + wu2[e] * u1[e]); }
;         }
;         u32x4 w0, w1;
;         w0.x = pack2(a0[0], a0[1]); w0.y = pack2(a0[2], a0[3]); w0.z = pack2(a0[4], a0[5]); w0.w = pack2(a0[6], a0[7]);
;         w1.x = pack2(a1[0], a1[1]); w1.y = pack2(a1[2], a1[3]); w1.z = pack2(a1[4], a1[5]); w1.w = pack2(a1[6], a1[7]);
;         *(u32x4*)(act + (size_t)(pm * 256) * DFF + j) = w0;
;         *(u32x4*)(act + (size_t)(pm * 256 + 1) * DFF + j) = w1;
.LBB0_27:
	s_waitcnt vmcnt(0) lgkmcnt(0)
	v_pk_mul_f32 v[106:107], v[50:51], v[86:87]
	v_pk_mul_f32 v[102:103], v[52:53], v[88:89]
	v_pk_fma_f32 v[54:55], v[54:55], v[78:79], v[106:107]
	v_pk_fma_f32 v[56:57], v[56:57], v[80:81], v[102:103]
	v_pk_fma_f32 v[54:55], v[46:47], v[82:83], v[54:55]
	v_pk_mul_f32 v[46:47], v[46:47], v[86:87]
	v_mul_f32_e32 v0, 0xbfb8aa3b, v54
	v_exp_f32_e32 v0, v0
	v_pk_fma_f32 v[46:47], v[50:51], v[78:79], v[46:47]
	v_pk_fma_f32 v[56:57], v[48:49], v[84:85], v[56:57]
	v_pk_fma_f32 v[42:43], v[42:43], v[82:83], v[46:47]
	v_add_f32_e32 v0, 1.0, v0
	v_rcp_f32_e32 v102, v0
	v_mul_f32_e32 v0, 0xbfb8aa3b, v55
	v_exp_f32_e32 v0, v0
	v_pk_mul_f32 v[106:107], v[58:59], v[74:75]
	v_pk_mul_f32 v[48:49], v[48:49], v[88:89]
	v_pk_fma_f32 v[62:63], v[62:63], v[66:67], v[106:107]
	v_add_f32_e32 v0, 1.0, v0
	v_rcp_f32_e32 v103, v0
	v_mul_f32_e32 v0, 0xbfb8aa3b, v42
	v_exp_f32_e32 v0, v0
	v_pk_fma_f32 v[62:63], v[38:39], v[70:71], v[62:63]
	v_pk_mul_f32 v[38:39], v[38:39], v[74:75]
	v_pk_fma_f32 v[48:49], v[52:53], v[80:81], v[48:49]
	v_add_f32_e32 v0, 1.0, v0
	v_rcp_f32_e32 v46, v0
	v_mul_f32_e32 v0, 0xbfb8aa3b, v43
	v_exp_f32_e32 v0, v0
	v_pk_fma_f32 v[38:39], v[58:59], v[66:67], v[38:39]
	v_pk_fma_f32 v[44:45], v[44:45], v[84:85], v[48:49]
	v_pk_fma_f32 v[30:31], v[30:31], v[70:71], v[38:39]
	v_add_f32_e32 v0, 1.0, v0
	v_rcp_f32_e32 v47, v0
	v_mul_f32_e32 v0, 0xbfb8aa3b, v56
	v_exp_f32_e32 v0, v0
	v_pk_mul_f32 v[54:55], v[54:55], v[102:103]
	v_pk_mul_f32 v[42:43], v[42:43], v[46:47]
	v_pk_mul_f32 v[102:103], v[60:61], v[76:77]
	v_add_f32_e32 v0, 1.0, v0
	v_pk_mul_f32 v[58:59], v[30:31], v[42:43]
	v_rcp_f32_e32 v30, v0
	v_mul_f32_e32 v0, 0xbfb8aa3b, v57
	v_exp_f32_e32 v0, v0
	v_pk_fma_f32 v[64:65], v[64:65], v[68:69], v[102:103]
	v_pk_mul_f32 v[62:63], v[62:63], v[54:55]
	v_pk_fma_f32 v[64:65], v[40:41], v[72:73], v[64:65]
	v_add_f32_e32 v0, 1.0, v0
	v_rcp_f32_e32 v31, v0
	v_mul_f32_e32 v0, 0xbfb8aa3b, v44
	v_exp_f32_e32 v0, v0
	v_pk_mul_f32 v[40:41], v[40:41], v[76:77]
	v_pk_mul_f32 v[30:31], v[56:57], v[30:31]
	v_pk_fma_f32 v[40:41], v[60:61], v[68:69], v[40:41]
	v_add_f32_e32 v0, 1.0, v0
	v_pk_mul_f32 v[60:61], v[64:65], v[30:31]
	v_rcp_f32_e32 v30, v0
	v_mul_f32_e32 v0, 0xbfb8aa3b, v45
	v_exp_f32_e32 v0, v0
	v_pk_fma_f32 v[32:33], v[32:33], v[72:73], v[40:41]
	s_lshl_b32 s38, s55, 8
	s_mul_i32 s0, s55, 0x160000
	v_add_f32_e32 v0, 1.0, v0
	v_rcp_f32_e32 v31, v0
	s_mul_hi_i32 s1, s38, 0x1600
	s_add_u32 s0, s43, s0
	s_addc_u32 s1, s47, s1
	v_pk_mul_f32 v[30:31], v[44:45], v[30:31]
	s_nop 0
	v_pk_mul_f32 v[64:65], v[32:33], v[30:31]
	global_load_dwordx4 v[30:33], v[104:105], off offset:16
	global_load_dwordx4 v[54:57], v[96:97], off offset:16
	global_load_dwordx4 v[50:53], v[98:99], off offset:16
	global_load_dwordx4 v[38:41], v[100:101], off offset:16
	global_load_dwordx4 v[42:45], v[94:95], off offset:16
	global_load_dwordx4 v[46:49], v[92:93], off offset:16
	s_waitcnt vmcnt(0) lgkmcnt(0)
	v_pk_mul_f32 v[68:69], v[18:19], v[54:55]
	v_pk_mul_f32 v[66:67], v[20:21], v[56:57]
	v_pk_fma_f32 v[68:69], v[34:35], v[30:31], v[68:69]
	v_pk_fma_f32 v[34:35], v[36:37], v[32:33], v[66:67]
	v_pk_fma_f32 v[36:37], v[22:23], v[50:51], v[68:69]
	v_pk_mul_f32 v[22:23], v[22:23], v[54:55]
	v_mul_f32_e32 v0, 0xbfb8aa3b, v36
	v_exp_f32_e32 v0, v0
	v_pk_fma_f32 v[18:19], v[18:19], v[30:31], v[22:23]
	v_pk_fma_f32 v[34:35], v[24:25], v[52:53], v[34:35]
	v_pk_fma_f32 v[14:15], v[14:15], v[50:51], v[18:19]
	v_add_f32_e32 v0, 1.0, v0
	v_rcp_f32_e32 v66, v0
	v_mul_f32_e32 v0, 0xbfb8aa3b, v37
	v_exp_f32_e32 v0, v0
	v_pk_mul_f32 v[68:69], v[10:11], v[42:43]
	v_pk_mul_f32 v[24:25], v[24:25], v[56:57]
	v_pk_fma_f32 v[26:27], v[26:27], v[38:39], v[68:69]
	v_add_f32_e32 v0, 1.0, v0
	v_rcp_f32_e32 v67, v0
	v_mul_f32_e32 v0, 0xbfb8aa3b, v14
	v_exp_f32_e32 v0, v0
	v_pk_fma_f32 v[26:27], v[6:7], v[46:47], v[26:27]
	v_pk_mul_f32 v[36:37], v[36:37], v[66:67]
	v_pk_mul_f32 v[66:67], v[12:13], v[44:45]
	v_add_f32_e32 v0, 1.0, v0
	v_rcp_f32_e32 v18, v0
	v_mul_f32_e32 v0, 0xbfb8aa3b, v15
	v_exp_f32_e32 v0, v0
	v_pk_fma_f32 v[28:29], v[28:29], v[40:41], v[66:67]
	v_pk_mul_f32 v[6:7], v[6:7], v[42:43]
	v_pk_fma_f32 v[28:29], v[8:9], v[48:49], v[28:29]
	v_add_f32_e32 v0, 1.0, v0
	v_rcp_f32_e32 v19, v0
	v_mul_f32_e32 v0, 0xbfb8aa3b, v34
	v_exp_f32_e32 v0, v0
	v_pk_mul_f32 v[8:9], v[8:9], v[44:45]
	v_pk_fma_f32 v[6:7], v[10:11], v[38:39], v[6:7]
	v_pk_mul_f32 v[14:15], v[14:15], v[18:19]
	v_pk_fma_f32 v[8:9], v[12:13], v[40:41], v[8:9]
	v_pk_fma_f32 v[2:3], v[2:3], v[46:47], v[6:7]
	v_add_f32_e32 v0, 1.0, v0
	v_pk_fma_f32 v[4:5], v[4:5], v[48:49], v[8:9]
	v_pk_mul_f32 v[8:9], v[2:3], v[14:15]
	v_rcp_f32_e32 v2, v0
	v_mul_f32_e32 v0, 0xbfb8aa3b, v35
	v_exp_f32_e32 v0, v0
	v_pk_fma_f32 v[20:21], v[20:21], v[32:33], v[24:25]
	v_cvt_pk_bf16_f32 v8, v8, v9
	v_pk_fma_f32 v[16:17], v[16:17], v[52:53], v[20:21]
	v_add_f32_e32 v0, 1.0, v0
	v_rcp_f32_e32 v3, v0
	v_mul_f32_e32 v0, 0xbfb8aa3b, v16
	v_exp_f32_e32 v0, v0
	v_pk_mul_f32 v[26:27], v[26:27], v[36:37]
	v_pk_mul_f32 v[2:3], v[34:35], v[2:3]
	v_add_f32_e32 v0, 1.0, v0
	v_pk_mul_f32 v[6:7], v[28:29], v[2:3]
	v_rcp_f32_e32 v2, v0
	v_mul_f32_e32 v0, 0xbfb8aa3b, v17
	v_exp_f32_e32 v0, v0
	s_nop 0
	v_add_f32_e32 v0, 1.0, v0
	v_rcp_f32_e32 v3, v0
	s_nop 0
	v_pk_mul_f32 v[2:3], v[16:17], v[2:3]
	s_nop 0
	v_pk_mul_f32 v[10:11], v[4:5], v[2:3]
	v_cvt_pk_bf16_f32 v2, v62, v63
	v_cvt_pk_bf16_f32 v9, v10, v11
	v_lshlrev_b64 v[10:11], 1, v[90:91]
	v_lshl_add_u64 v[12:13], s[0:1], 0, v[10:11]
	s_or_b32 s0, s38, 1
	s_mul_hi_i32 s1, s0, 0x1600
	s_mulk_i32 s0, 0x1600
	s_add_u32 s0, s43, s0
	v_cvt_pk_bf16_f32 v3, v60, v61
	v_cvt_pk_bf16_f32 v4, v26, v27
	v_cvt_pk_bf16_f32 v5, v6, v7
	s_addc_u32 s1, s47, s1
	v_cvt_pk_bf16_f32 v6, v58, v59
	v_cvt_pk_bf16_f32 v7, v64, v65
	global_store_dwordx4 v[12:13], v[2:5], off
	s_nop 1
	v_lshl_add_u64 v[2:3], s[0:1], 0, v[10:11]
	global_store_dwordx4 v[2:3], v[6:9], off

;     __host__ __device__ bool next(int i, Unit& u) const {
;         const long L = (long)i * G + c; if (L >= nwg) return false;
;         int wgid = (int)L; { const int q = nwg / NXCD, r = nwg % NXCD, xcd = wgid % NXCD, off = wgid / NXCD; wgid = (xcd < r ? xcd * (q + 1) : r * (q + 1) + (xcd - r) * q) + off; }
;         const int nig = WGM * nN, gid = wgid / nig, fm = gid * WGM, gsz = (nM - fm) < WGM ? (nM - fm) : WGM;
;         u.pm = fm + ((wgid % nig) % gsz); u.pn = (wgid % nig) / gsz; return true;
; __device__ void fix_panel(const float* halo, const float* cw  , bf16_t* act, int pm) {
;     ...
;     if (t < 22 * 16) {
;         const int c = (t & 15) * 8, pn = t >> 4, j = pn * 128 + c;
;         const float* ht = halo + (size_t)(pm * 22 + pn) * 1024 + c;
;         const bool first = ((pm * 256) & (SEQ - 1)) == 0;
;         const float* hp = halo + (size_t)((first ? pm : pm - 1) * 22 + pn) * 1024 + c;
;         float a0[8], a1[8];
; #pragma unroll
;         for (int q = 0; q < 2; ++q) {
;             const f32x4 z4 = (f32x4){0.f, 0.f, 0.f, 0.f};
;             const f32x4 g0 = *(const f32x4*)(ht + 4 * q), g1 = *(const f32x4*)(ht + 256 + 4 * q), u0 = *(const f32x4*)(ht + 128 + 4 * q), u1 = *(const f32x4*)(ht + 384 + 4 * q);
;             const f32x4 gb0 = first ? z4 : *(const f32x4*)(hp + 512 + 4 * q), gb1 = first ? z4 : *(const f32x4*)(hp + 768 + 4 * q);
;             const f32x4 ub0 = first ? z4 : *(const f32x4*)(hp + 640 + 4 * q), ub1 = first ? z4 : *(const f32x4*)(hp + 896 + 4 * q);
;             const f32x4 wg0 = *(const f32x4*)(cw + j + 4 * q), wg1 = *(const f32x4*)(cw + NUP + j + 4 * q), wg2 = *(const f32x4*)(cw + 2 * NUP + j + 4 * q);
;             const f32x4 wu0 = *(const f32x4*)(cw + DFF + j + 4 * q), wu1 = *(const f32x4*)(cw + NUP + DFF + j + 4 * q), wu2 = *(const f32x4*)(cw + 2 * NUP + DFF + j + 4 * q);
.LBB0_36:
	s_ashr_i32 s0, s37, 3
	s_add_i32 s0, s39, s0
	s_ashr_i32 s1, s0, 31
	s_lshr_b32 s1, s1, 27
	s_add_i32 s1, s0, s1
	s_ashr_i32 s37, s1, 5
	s_lshl_b32 s55, s37, 3
	s_sub_i32 s37, 0x80, s55
	s_min_i32 s37, s37, 8
	s_abs_i32 s37, s37
	v_cvt_f32_u32_e32 v0, s37
	s_sub_i32 s38, 0, s37
	s_andn2_b32 s1, s1, 31
	s_sub_i32 s0, s0, s1
	v_rcp_iflag_f32_e32 v0, v0
	s_ashr_i32 s1, s0, 31
	s_abs_i32 s0, s0
	v_mul_f32_e32 v0, 0x4f7ffffe, v0
	v_cvt_u32_f32_e32 v0, v0
	s_nop 0
	v_readfirstlane_b32 s39, v0
	s_mul_i32 s38, s38, s39
	s_mul_hi_u32 s38, s39, s38
	s_add_i32 s39, s39, s38
	s_mul_hi_u32 s38, s0, s39
	s_mul_i32 s38, s38, s37
	s_sub_i32 s0, s0, s38
	s_sub_i32 s38, s0, s37
	s_cmp_ge_u32 s0, s37
	s_cselect_b32 s0, s38, s0
	s_sub_i32 s38, s0, s37
	s_cmp_ge_u32 s0, s37
	s_cselect_b32 s0, s38, s0
	s_xor_b32 s0, s0, s1
	s_sub_i32 s0, s0, s1
	s_add_i32 s55, s55, s0
	s_cmp_lg_u32 s55, s36
	s_cbranch_scc0 .LBB0_29
	v_mov_b32_e32 v0, v212
	s_movk_i32 s0, 0x160
	s_nop 0
	v_cmp_gt_i32_e32 vcc, s0, v0
	s_and_saveexec_b64 s[36:37], vcc
	s_cbranch_execz .LBB0_28
	s_waitcnt vmcnt(0)
	v_lshlrev_b32_e32 v2, 3, v0
	v_and_b32_e32 v5, 0x78, v2
	v_ashrrev_i32_e32 v4, 4, v0
	v_mad_u64_u32 v[2:3], s[0:1], s55, 22, v[4:5]
	v_ashrrev_i32_e32 v3, 31, v2
	v_lshlrev_b64 v[2:3], 12, v[2:3]
	v_lshl_add_u64 v[2:3], s[12:13], 0, v[2:3]
	v_lshlrev_b32_e32 v0, 2, v5
	v_lshl_add_u64 v[2:3], v[2:3], 0, v[0:1]
	global_load_dwordx4 v[46:49], v[2:3], off
	global_load_dwordx4 v[38:41], v[2:3], off offset:512
	global_load_dwordx4 v[42:45], v[2:3], off offset:1024
	global_load_dwordx4 v[30:33], v[2:3], off offset:1536
	s_and_b32 s0, s55, 31
	s_cmp_lg_u32 s0, 0
	s_cselect_b64 s[38:39], -1, 0
	s_cmp_lg_u64 s[38:39], 0
	s_subb_u32 s1, s55, 0
	s_cmp_eq_u32 s0, 0
	v_mad_u64_u32 v[6:7], s[0:1], s1, 22, v[4:5]
	v_ashrrev_i32_e32 v7, 31, v6
	v_lshlrev_b64 v[6:7], 12, v[6:7]
	v_lshl_add_u64 v[6:7], s[12:13], 0, v[6:7]
	v_lshl_add_u64 v[102:103], v[6:7], 0, v[0:1]
	v_mov_b32_e32 v50, 0
	v_mov_b32_e32 v54, 0
	v_mov_b32_e32 v55, 0
	v_mov_b32_e32 v56, 0
	v_mov_b32_e32 v57, 0
	s_cbranch_scc1 .LBB0_40
	global_load_dwordx4 v[54:57], v[102:103], off offset:2048
.LBB0_40:
	v_cndmask_b32_e64 v0, 0, 1, s[38:39]
	v_cmp_ne_u32_e64 s[0:1], 1, v0
	s_andn2_b64 vcc, exec, s[38:39]
	v_mov_b32_e32 v51, 0
	v_mov_b32_e32 v52, 0
	v_mov_b32_e32 v53, 0
	s_cbranch_vccnz .LBB0_42
	global_load_dwordx4 v[50:53], v[102:103], off offset:3072
.LBB0_42:
	v_mov_b32_e32 v58, 0
	s_and_b64 vcc, exec, s[0:1]
	v_mov_b32_e32 v62, 0
	v_mov_b32_e32 v63, 0
	v_mov_b32_e32 v64, 0
	v_mov_b32_e32 v65, 0
	s_cbranch_vccnz .LBB0_44
	global_load_dwordx4 v[62:65], v[102:103], off offset:2560
.LBB0_44:
	s_and_b64 vcc, exec, s[0:1]
	v_mov_b32_e32 v59, 0
	v_mov_b32_e32 v60, 0
	v_mov_b32_e32 v61, 0
	s_cbranch_vccnz .LBB0_46
	global_load_dwordx4 v[58:61], v[102:103], off offset:3584
.LBB0_46:
	v_lshl_or_b32 v90, v4, 7, v5
	v_ashrrev_i32_e32 v91, 31, v90
	v_lshlrev_b64 v[4:5], 2, v[90:91]
	v_lshl_add_u64 v[104:105], s[14:15], 0, v[4:5]
	v_lshl_add_u64 v[96:97], s[20:21], 0, v[4:5]
	v_lshl_add_u64 v[98:99], s[24:25], 0, v[4:5]
	v_lshl_add_u64 v[100:101], s[28:29], 0, v[4:5]
	v_lshl_add_u64 v[94:95], s[30:31], 0, v[4:5]
	v_lshl_add_u64 v[92:93], s[34:35], 0, v[4:5]
	global_load_dwordx4 v[78:81], v[104:105], off
	global_load_dwordx4 v[86:89], v[96:97], off
	global_load_dwordx4 v[82:85], v[98:99], off
	global_load_dwordx4 v[66:69], v[100:101], off
	global_load_dwordx4 v[74:77], v[94:95], off
	global_load_dwordx4 v[70:73], v[92:93], off
	global_load_dwordx4 v[22:25], v[2:3], off offset:16
	global_load_dwordx4 v[6:9], v[2:3], off offset:528
	global_load_dwordx4 v[14:17], v[2:3], off offset:1040
	s_nop 0
	global_load_dwordx4 v[2:5], v[2:3], off offset:1552
	v_mov_b32_e32 v18, 0
	s_and_b64 vcc, exec, s[0:1]
	v_mov_b32_e32 v34, 0
	v_mov_b32_e32 v35, 0
	v_mov_b32_e32 v36, 0
	v_mov_b32_e32 v37, 0
	s_cbranch_vccnz .LBB0_48
	global_load_dwordx4 v[34:37], v[102:103], off offset:2064
.LBB0_48:
	s_and_b64 vcc, exec, s[0:1]
	v_mov_b32_e32 v19, 0
	v_mov_b32_e32 v20, 0
	v_mov_b32_e32 v21, 0
	s_cbranch_vccnz .LBB0_50
	global_load_dwordx4 v[18:21], v[102:103], off offset:3088
.LBB0_50:
	v_mov_b32_e32 v10, 0
	s_and_b64 vcc, exec, s[0:1]
	v_mov_b32_e32 v26, 0
	v_mov_b32_e32 v27, 0
	v_mov_b32_e32 v28, 0
	v_mov_b32_e32 v29, 0
	s_cbranch_vccnz .LBB0_52
	global_load_dwordx4 v[26:29], v[102:103], off offset:2576
.LBB0_52:
	s_and_b64 vcc, exec, s[0:1]
	v_mov_b32_e32 v11, 0
	v_mov_b32_e32 v12, 0
	v_mov_b32_e32 v13, 0
	s_cbranch_vccnz .LBB0_27
	global_load_dwordx4 v[10:13], v[102:103], off offset:3600
	s_branch .LBB0_27

;     __device__ __forceinline__ void operator()(const f32x4 (&acc)[2][2][4][2], const Unit& u, int wr, int wc, int fr, int fq) const {
;     ...
;         asm volatile("s_waitcnt lgkmcnt(0)\n\ts_barrier" ::: "memory");
;         const int colj = u.pn * 128 + wc * 32 + 8 * fq;
;         float* hb = halo + (size_t)(u.pm * 22 + u.pn) * 1024 + wc * 32 + 8 * fq;
; #pragma unroll
;         for (int n = 0; n < 2; ++n) {
;             f32x4 wgt[3][2];
; #pragma unroll
;             for (int i = 0; i < 3; ++i)
; #pragma unroll
;                 for (int bj = 0; bj < 2; ++bj) wgt[i][bj] = *(const f32x4*)(cw + i * 5632 + bj * 2816 + colj + 4 * n);
; #pragma unroll
;             for (int ai = 0; ai < 2; ++ai) {
;                 const bool top = (wr == 0 && ai == 0);
;                 f32x4 h1[2], h2[2];
;                 const float* sx = xch + (wr == 1 ? wc : 4 + wc) * 256 + (wr == 1 ? ai * 2 : 0) * 64 + fq * 8 + n * 4;
; #pragma unroll
;                 for (int bj = 0; bj < 2; ++bj) {
;                     if (!top) { h2[bj] = *(const f32x4*)(sx + bj * 32); h1[bj] = *(const f32x4*)(sx + 64 + bj * 32); }
;                     else { h2[bj] = (f32x4){0.f, 0.f, 0.f, 0.f}; h1[bj] = (f32x4){0.f, 0.f, 0.f, 0.f}; }
;                 }
.LBB0_72:
	s_or_b64 exec, exec, s[14:15]
	v_lshl_or_b32 v190, s78, 7, v206
	v_ashrrev_i32_e32 v191, 31, v190
	v_lshl_add_u64 v[192:193], v[190:191], 2, s[24:25]
	v_add_co_u32_e32 v98, vcc, 0x2000, v192
	s_waitcnt lgkmcnt(0)
	s_barrier
	v_mov_b32_e32 v158, 0
	s_nop 0
	v_addc_co_u32_e32 v99, vcc, 0, v193, vcc
	v_add_co_u32_e32 v106, vcc, 0x5000, v192
	global_load_dwordx4 v[102:105], v[192:193], off
	s_nop 0
	global_load_dwordx4 v[98:101], v[98:99], off offset:3072
	v_addc_co_u32_e32 v107, vcc, 0, v193, vcc
	v_add_co_u32_e32 v108, vcc, 0x8000, v192
	v_mov_b32_e32 v159, 0
	s_nop 0
	v_addc_co_u32_e32 v109, vcc, 0, v193, vcc
	v_add_co_u32_e32 v114, vcc, 0xb000, v192
	global_load_dwordx4 v[110:113], v[106:107], off offset:2048
	s_nop 0
	global_load_dwordx4 v[106:109], v[108:109], off offset:1024
	v_addc_co_u32_e32 v115, vcc, 0, v193, vcc
	v_add_co_u32_e32 v116, vcc, 0xd000, v192
	v_mov_b32_e32 v160, 0
	s_nop 0
	v_addc_co_u32_e32 v117, vcc, 0, v193, vcc
	global_load_dwordx4 v[118:121], v[114:115], off
	s_nop 0
	global_load_dwordx4 v[114:117], v[116:117], off offset:3072
	s_and_b64 vcc, exec, s[28:29]
	v_mov_b32_e32 v161, 0
	v_mov_b32_e32 v154, 0
	v_mov_b32_e32 v155, 0
	v_mov_b32_e32 v156, 0
	v_mov_b32_e32 v157, 0
	s_cbranch_vccz .LBB0_74
	ds_read_b128 v[158:161], v204
	ds_read_b128 v[154:157], v204 offset:256

; __device__ __forceinline__ unsigned cvt_pk_bf16(float lo, float hi) { f32x2_t_ v = {lo, hi}; bf16x2_t_ b = __builtin_convertvector(v, bf16x2_t_); return __builtin_bit_cast(unsigned, b); }
; __device__ __forceinline__ float dpp_ror1(float v) { return __builtin_bit_cast(float, __builtin_amdgcn_update_dpp(0, __builtin_bit_cast(int, v), 0x121, 0xf, 0xf, false)); }
; __device__ __forceinline__ float dpp_ror2(float v) { return __builtin_bit_cast(float, __builtin_amdgcn_update_dpp(0, __builtin_bit_cast(int, v), 0x122, 0xf, 0xf, false)); }
;     __device__ __forceinline__ void operator()(const f32x4 (&acc)[2][2][4][2], const Unit& u, int wr, int wc, int fr, int fq) const {
;     ...
;                 for (int m = 0; m < 4; ++m) {
;                     float cv[2][4];
; #pragma unroll
;                     for (int bj = 0; bj < 2; ++bj)
; #pragma unroll
;                         for (int e = 0; e < 4; ++e) {
;                             const float x = acc[ai][bj][m][n][e];
;                             const float r1s = dpp_ror1(x), r2s = dpp_ror2(x);
;                             float r1p, r2p;
;                             if (m > 0) { const float xp = acc[ai][bj][m > 0 ? m - 1 : 0][n][e]; r1p = dpp_ror1(xp); r2p = dpp_ror2(xp); }
;                             else { r1p = h1[bj][e]; r2p = (fr == 0) ? h2[bj][e] : h1[bj][e]; }
;                             const float p1 = (fr == 0) ? r1p : r1s, p2 = (fr < 2) ? r2p : r2s;
;                             cv[bj][e] = wgt[0][bj][e] * p2 + wgt[1][bj][e] * p1 + wgt[2][bj][e] * x;
;                         }
;                     const int r = u.pm * BM + ai * HALF + wr * 64 + m * 16 + fr;
;                     if (top && m == 0 && fr < 2) {
; #pragma unroll
;                         for (int bj = 0; bj < 2; ++bj) *(f32x4*)(hb + fr * 256 + bj * 128 + 4 * n) = acc[0][bj][0][n];
;                     } else {
;                         float o[4];
; #pragma unroll
;                         for (int c = 0; c < 4; ++c) { const float g = cv[0][c]; o[c] = g * __builtin_amdgcn_rcpf(1.0f + __expf(-g)) * cv[1][c]; }
;                         u32x2 w; w.x = cvt_pk_bf16(o[0], o[1]); w.y = cvt_pk_bf16(o[2], o[3]);
;                         *(u32x2*)(act + (size_t)r * 2816 + colj + 4 * n) = w;
;                     }
.LBB0_78:
	v_mov_b32_e32 v229, v1
	v_mov_b32_e32 v231, v1
	v_mov_b32_e32 v230, v1
	v_mov_b32_e32 v232, v1
	v_mov_b32_e32 v210, v1
	v_mov_b32_e32 v226, v1
	v_mov_b32_e32 v224, v1
	v_mov_b32_e32 v228, v1
	v_mov_b32_e32 v233, v1
	v_mov_b32_e32 v235, v1
	v_mov_b32_e32 v234, v1
	v_mov_b32_e32 v236, v1
	v_mov_b32_e32 v209, v1
	v_mov_b32_e32 v225, v1
	v_mov_b32_e32 v211, v1
	v_mov_b32_e32 v227, v1
	s_xor_b64 s[36:37], s[36:37], -1
	v_lshl_add_u32 v208, s92, 8, v194
	v_mov_b32_dpp v229, v150 row_ror:1 row_mask:0xf bank_mask:0xf
	v_mov_b32_dpp v231, v150 row_ror:2 row_mask:0xf bank_mask:0xf
	v_mov_b32_dpp v230, v151 row_ror:1 row_mask:0xf bank_mask:0xf
	v_mov_b32_dpp v232, v151 row_ror:2 row_mask:0xf bank_mask:0xf
	v_mov_b32_dpp v210, v152 row_ror:1 row_mask:0xf bank_mask:0xf
	v_mov_b32_dpp v226, v152 row_ror:2 row_mask:0xf bank_mask:0xf
	v_mov_b32_dpp v224, v153 row_ror:1 row_mask:0xf bank_mask:0xf
	v_mov_b32_dpp v228, v153 row_ror:2 row_mask:0xf bank_mask:0xf
	v_mov_b32_dpp v233, v146 row_ror:1 row_mask:0xf bank_mask:0xf
	v_mov_b32_dpp v235, v146 row_ror:2 row_mask:0xf bank_mask:0xf
	v_mov_b32_dpp v234, v147 row_ror:1 row_mask:0xf bank_mask:0xf
	v_mov_b32_dpp v236, v147 row_ror:2 row_mask:0xf bank_mask:0xf
	v_mov_b32_dpp v209, v148 row_ror:1 row_mask:0xf bank_mask:0xf
	v_mov_b32_dpp v225, v148 row_ror:2 row_mask:0xf bank_mask:0xf
	v_mov_b32_dpp v211, v149 row_ror:1 row_mask:0xf bank_mask:0xf
	v_mov_b32_dpp v227, v149 row_ror:2 row_mask:0xf bank_mask:0xf
	s_and_saveexec_b64 s[56:57], s[36:37]
	s_xor_b64 vcc, exec, s[56:57]
	s_cbranch_execz .LBB0_80
	s_waitcnt lgkmcnt(0)
	v_cndmask_b32_e64 v158, v154, v158, s[8:9]
	v_cndmask_b32_e64 v159, v155, v159, s[8:9]
	v_cndmask_b32_e64 v159, v232, v159, s[10:11]
	v_cndmask_b32_e64 v158, v231, v158, s[10:11]
	s_waitcnt vmcnt(0)
	v_pk_mul_f32 v[158:159], v[102:103], v[158:159]
	v_cndmask_b32_e64 v155, v230, v155, s[8:9]
	v_cndmask_b32_e64 v154, v229, v154, s[8:9]
	v_pk_fma_f32 v[154:155], v[110:111], v[154:155], v[158:159]
	v_cndmask_b32_e64 v166, v162, v166, s[8:9]
	v_pk_fma_f32 v[154:155], v[150:151], v[118:119], v[154:155]
	v_cndmask_b32_e64 v167, v163, v167, s[8:9]
	v_mul_f32_e32 v158, 0xbfb8aa3b, v154
	v_mul_f32_e32 v159, 0xbfb8aa3b, v155
	v_exp_f32_e32 v158, v158
	v_exp_f32_e32 v159, v159
	v_cndmask_b32_e64 v167, v236, v167, s[10:11]
	v_cndmask_b32_e64 v166, v235, v166, s[10:11]
	v_add_f32_e32 v158, 1.0, v158
	v_add_f32_e32 v159, 1.0, v159
	v_rcp_f32_e32 v158, v158
	v_rcp_f32_e32 v159, v159
	v_pk_mul_f32 v[166:167], v[98:99], v[166:167]
	v_cndmask_b32_e64 v163, v234, v163, s[8:9]
	v_cndmask_b32_e64 v162, v233, v162, s[8:9]
	v_pk_mul_f32 v[154:155], v[154:155], v[158:159]
	v_cndmask_b32_e64 v158, v156, v160, s[8:9]
	v_cndmask_b32_e64 v159, v157, v161, s[8:9]
	v_cndmask_b32_e64 v159, v228, v159, s[10:11]
	v_cndmask_b32_e64 v158, v226, v158, s[10:11]
	v_pk_mul_f32 v[158:159], v[104:105], v[158:159]
	v_cndmask_b32_e64 v157, v224, v157, s[8:9]
	v_cndmask_b32_e64 v156, v210, v156, s[8:9]
	v_pk_fma_f32 v[156:157], v[112:113], v[156:157], v[158:159]
	v_cndmask_b32_e64 v158, v164, v168, s[8:9]
	v_cndmask_b32_e64 v159, v165, v169, s[8:9]
	v_cndmask_b32_e64 v159, v227, v159, s[10:11]
	v_cndmask_b32_e64 v158, v225, v158, s[10:11]
	v_pk_fma_f32 v[156:157], v[152:153], v[120:121], v[156:157]
	v_pk_mul_f32 v[158:159], v[100:101], v[158:159]
	v_cndmask_b32_e64 v161, v211, v165, s[8:9]
	v_cndmask_b32_e64 v160, v209, v164, s[8:9]
	v_pk_fma_f32 v[158:159], v[108:109], v[160:161], v[158:159]
	v_mul_f32_e32 v160, 0xbfb8aa3b, v156
	v_mul_f32_e32 v161, 0xbfb8aa3b, v157
	v_exp_f32_e32 v160, v160
	v_exp_f32_e32 v161, v161
	v_pk_fma_f32 v[162:163], v[106:107], v[162:163], v[166:167]
	v_pk_fma_f32 v[158:159], v[148:149], v[116:117], v[158:159]
	v_add_f32_e32 v160, 1.0, v160
	v_add_f32_e32 v161, 1.0, v161
	v_rcp_f32_e32 v160, v160
	v_rcp_f32_e32 v161, v161
	v_pk_fma_f32 v[162:163], v[146:147], v[114:115], v[162:163]
	s_movk_i32 s1, 0x1600
	v_pk_mul_f32 v[154:155], v[154:155], v[162:163]
	v_pk_mul_f32 v[156:157], v[156:157], v[160:161]
	v_cvt_pk_bf16_f32 v154, v154, v155
	v_pk_mul_f32 v[156:157], v[156:157], v[158:159]
	s_nop 0
	v_cvt_pk_bf16_f32 v155, v156, v157
	v_mov_b64_e32 v[156:157], s[30:31]
	v_mad_i64_i32 v[156:157], s[56:57], v208, s1, v[156:157]
	v_lshl_add_u64 v[156:157], v[190:191], 1, v[156:157]
	global_store_dwordx2 v[156:157], v[154:155], off
.LBB0_80:
	s_or_saveexec_b64 vcc, vcc
	s_mul_i32 s1, s92, 22
	s_add_i32 s56, s1, s78
	s_ashr_i32 s57, s56, 31
	s_lshl_b64 s[56:57], s[56:57], 12
	s_waitcnt lgkmcnt(0)
	v_lshl_add_u64 v[154:155], v[184:185], 0, s[56:57]
	s_xor_b64 exec, exec, vcc
	s_cbranch_execz .LBB0_82
	global_store_dwordx4 v[154:155], v[150:153], off
	global_store_dwordx4 v[154:155], v[146:149], off offset:512
; __device__ __forceinline__ unsigned cvt_pk_bf16(float lo, float hi) { f32x2_t_ v = {lo, hi}; bf16x2_t_ b = __builtin_convertvector(v, bf16x2_t_); return __builtin_bit_cast(unsigned, b); }
; __device__ __forceinline__ float dpp_ror1(float v) { return __builtin_bit_cast(float, __builtin_amdgcn_update_dpp(0, __builtin_bit_cast(int, v), 0x121, 0xf, 0xf, false)); }
; __device__ __forceinline__ float dpp_ror2(float v) { return __builtin_bit_cast(float, __builtin_amdgcn_update_dpp(0, __builtin_bit_cast(int, v), 0x122, 0xf, 0xf, false)); }
;     __device__ __forceinline__ void operator()(const f32x4 (&acc)[2][2][4][2], const Unit& u, int wr, int wc, int fr, int fq) const {
;     ...
;                 for (int m = 0; m < 4; ++m) {
;                     float cv[2][4];
; #pragma unroll
;                     for (int bj = 0; bj < 2; ++bj)
; #pragma unroll
;                         for (int e = 0; e < 4; ++e) {
;                             const float x = acc[ai][bj][m][n][e];
;                             const float r1s = dpp_ror1(x), r2s = dpp_ror2(x);
;                             float r1p, r2p;
;                             if (m > 0) { const float xp = acc[ai][bj][m > 0 ? m - 1 : 0][n][e]; r1p = dpp_ror1(xp); r2p = dpp_ror2(xp); }
;                             else { r1p = h1[bj][e]; r2p = (fr == 0) ? h2[bj][e] : h1[bj][e]; }
;                             const float p1 = (fr == 0) ? r1p : r1s, p2 = (fr < 2) ? r2p : r2s;
;                             cv[bj][e] = wgt[0][bj][e] * p2 + wgt[1][bj][e] * p1 + wgt[2][bj][e] * x;
;                         }
;                     const int r = u.pm * BM + ai * HALF + wr * 64 + m * 16 + fr;
;                     if (top && m == 0 && fr < 2) {
; #pragma unroll
;                         for (int bj = 0; bj < 2; ++bj) *(f32x4*)(hb + fr * 256 + bj * 128 + 4 * n) = acc[0][bj][0][n];
;                     } else {
;                         float o[4];
; #pragma unroll
;                         for (int c = 0; c < 4; ++c) { const float g = cv[0][c]; o[c] = g * __builtin_amdgcn_rcpf(1.0f + __expf(-g)) * cv[1][c]; }
;                         u32x2 w; w.x = cvt_pk_bf16(o[0], o[1]); w.y = cvt_pk_bf16(o[2], o[3]);
;                         *(u32x2*)(act + (size_t)r * 2816 + colj + 4 * n) = w;
.LBB0_82:
	s_or_b64 exec, exec, vcc
	v_mov_b32_e32 v157, v1
	v_mov_b32_e32 v158, v1
	v_mov_b32_e32 v159, v1
	v_mov_b32_e32 v160, v1
	v_mov_b32_e32 v162, v1
	v_mov_b32_e32 v156, v1
	v_mov_b32_dpp v157, v142 row_ror:2 row_mask:0xf bank_mask:0xf
	v_mov_b32_dpp v158, v150 row_ror:1 row_mask:0xf bank_mask:0xf
	v_mov_b32_dpp v159, v150 row_ror:2 row_mask:0xf bank_mask:0xf
	v_mov_b32_e32 v150, v1
	v_mov_b32_dpp v160, v143 row_ror:2 row_mask:0xf bank_mask:0xf
	v_mov_b32_e32 v161, v1
	v_mov_b32_dpp v162, v151 row_ror:2 row_mask:0xf bank_mask:0xf
	v_mov_b32_e32 v229, v1
	v_mov_b32_e32 v230, v1
	v_mov_b32_e32 v233, v1
	v_mov_b32_e32 v234, v1
	v_mov_b32_dpp v156, v142 row_ror:1 row_mask:0xf bank_mask:0xf
	v_mov_b32_dpp v150, v143 row_ror:1 row_mask:0xf bank_mask:0xf
	v_mov_b32_dpp v161, v151 row_ror:1 row_mask:0xf bank_mask:0xf
	v_mov_b32_e32 v167, v1
	v_mov_b32_e32 v168, v1
	v_mov_b32_e32 v169, v1
	v_mov_b32_e32 v209, v1
	v_mov_b32_e32 v210, v1
	v_mov_b32_e32 v224, v1
	v_mov_b32_e32 v225, v1
	v_mov_b32_e32 v226, v1
	v_mov_b32_dpp v229, v148 row_ror:1 row_mask:0xf bank_mask:0xf
	v_mov_b32_dpp v230, v148 row_ror:2 row_mask:0xf bank_mask:0xf
	v_mov_b32_dpp v233, v149 row_ror:1 row_mask:0xf bank_mask:0xf
	v_mov_b32_dpp v234, v149 row_ror:2 row_mask:0xf bank_mask:0xf
	v_cndmask_b32_e64 v149, v160, v162, s[10:11]
	v_cndmask_b32_e64 v148, v157, v159, s[10:11]
	v_mov_b32_dpp v167, v153 row_ror:1 row_mask:0xf bank_mask:0xf
	v_mov_b32_dpp v168, v153 row_ror:2 row_mask:0xf bank_mask:0xf
	v_mov_b32_e32 v153, v1
	v_mov_b32_dpp v169, v138 row_ror:2 row_mask:0xf bank_mask:0xf
	v_mov_b32_dpp v209, v146 row_ror:1 row_mask:0xf bank_mask:0xf
	v_mov_b32_dpp v210, v146 row_ror:2 row_mask:0xf bank_mask:0xf
	v_mov_b32_e32 v211, v1
	v_mov_b32_dpp v224, v139 row_ror:2 row_mask:0xf bank_mask:0xf
	v_mov_b32_dpp v225, v147 row_ror:1 row_mask:0xf bank_mask:0xf
	v_mov_b32_dpp v226, v147 row_ror:2 row_mask:0xf bank_mask:0xf
	v_cndmask_b32_e64 v147, v150, v161, s[8:9]
	v_cndmask_b32_e64 v146, v156, v158, s[8:9]
	s_waitcnt vmcnt(0)
	v_pk_mul_f32 v[148:149], v[102:103], v[148:149]
	v_mov_b32_dpp v153, v138 row_ror:1 row_mask:0xf bank_mask:0xf
	v_mov_b32_dpp v211, v139 row_ror:1 row_mask:0xf bank_mask:0xf
	v_pk_fma_f32 v[146:147], v[110:111], v[146:147], v[148:149]
	v_cndmask_b32_e64 v149, v224, v226, s[10:11]
	v_cndmask_b32_e64 v148, v169, v210, s[10:11]
	v_pk_fma_f32 v[142:143], v[142:143], v[118:119], v[146:147]
	v_cndmask_b32_e64 v147, v211, v225, s[8:9]
	v_cndmask_b32_e64 v146, v153, v209, s[8:9]
	v_pk_mul_f32 v[148:149], v[98:99], v[148:149]
	v_mov_b32_e32 v163, v1
	v_pk_fma_f32 v[146:147], v[106:107], v[146:147], v[148:149]
	v_mov_b32_e32 v164, v1
	v_pk_fma_f32 v[138:139], v[138:139], v[114:115], v[146:147]
	v_mul_f32_e32 v146, 0xbfb8aa3b, v142
	v_mul_f32_e32 v147, 0xbfb8aa3b, v143
	v_exp_f32_e32 v146, v146
	v_exp_f32_e32 v147, v147
	v_mov_b32_e32 v165, v1
	v_mov_b32_e32 v166, v1
	v_add_f32_e32 v146, 1.0, v146
	v_add_f32_e32 v147, 1.0, v147
	v_rcp_f32_e32 v146, v146
	v_rcp_f32_e32 v147, v147
	v_mov_b32_e32 v151, v1
	v_mov_b32_dpp v163, v144 row_ror:2 row_mask:0xf bank_mask:0xf
	v_mov_b32_dpp v164, v152 row_ror:1 row_mask:0xf bank_mask:0xf
	v_mov_b32_dpp v165, v152 row_ror:2 row_mask:0xf bank_mask:0xf
	v_mov_b32_e32 v152, v1
	v_mov_b32_dpp v166, v145 row_ror:2 row_mask:0xf bank_mask:0xf
	v_mov_b32_dpp v151, v144 row_ror:1 row_mask:0xf bank_mask:0xf
	v_mov_b32_dpp v152, v145 row_ror:1 row_mask:0xf bank_mask:0xf
	v_pk_mul_f32 v[142:143], v[142:143], v[146:147]
	v_cndmask_b32_e64 v147, v166, v168, s[10:11]
	v_cndmask_b32_e64 v146, v163, v165, s[10:11]
	v_mov_b32_e32 v228, v1
	v_mov_b32_e32 v232, v1
	v_pk_mul_f32 v[138:139], v[142:143], v[138:139]
	v_cndmask_b32_e64 v143, v152, v167, s[8:9]
	v_cndmask_b32_e64 v142, v151, v164, s[8:9]
	v_pk_mul_f32 v[146:147], v[104:105], v[146:147]
	v_mov_b32_e32 v227, v1
	v_mov_b32_dpp v228, v140 row_ror:2 row_mask:0xf bank_mask:0xf
	v_mov_b32_e32 v231, v1
	v_mov_b32_dpp v232, v141 row_ror:2 row_mask:0xf bank_mask:0xf
	v_pk_fma_f32 v[142:143], v[112:113], v[142:143], v[146:147]
	v_mov_b32_dpp v227, v140 row_ror:1 row_mask:0xf bank_mask:0xf
	v_mov_b32_dpp v231, v141 row_ror:1 row_mask:0xf bank_mask:0xf
	v_pk_fma_f32 v[142:143], v[144:145], v[120:121], v[142:143]
	v_cndmask_b32_e64 v145, v232, v234, s[10:11]
	v_cndmask_b32_e64 v144, v228, v230, s[10:11]
	v_pk_mul_f32 v[144:145], v[100:101], v[144:145]
	v_cndmask_b32_e64 v147, v231, v233, s[8:9]
	v_cndmask_b32_e64 v146, v227, v229, s[8:9]
	v_pk_fma_f32 v[144:145], v[108:109], v[146:147], v[144:145]
	v_or_b32_e32 v235, 16, v208
	v_pk_fma_f32 v[140:141], v[140:141], v[116:117], v[144:145]
	v_mul_f32_e32 v144, 0xbfb8aa3b, v142
	v_mul_f32_e32 v145, 0xbfb8aa3b, v143
	v_exp_f32_e32 v144, v144
	v_exp_f32_e32 v145, v145
	s_movk_i32 s1, 0x1600
	v_mov_b32_e32 v149, v1
	v_add_f32_e32 v144, 1.0, v144
	v_add_f32_e32 v145, 1.0, v145
	v_rcp_f32_e32 v144, v144
	v_rcp_f32_e32 v145, v145
	v_mov_b32_e32 v159, v1
	v_mov_b32_e32 v148, v1
	v_mov_b32_dpp v149, v134 row_ror:2 row_mask:0xf bank_mask:0xf
	v_pk_mul_f32 v[142:143], v[142:143], v[144:145]
	v_cvt_pk_bf16_f32 v144, v138, v139
	v_pk_mul_f32 v[140:141], v[142:143], v[140:141]
	v_lshlrev_b64 v[142:143], 1, v[190:191]
	v_cvt_pk_bf16_f32 v145, v140, v141
	v_mov_b64_e32 v[140:141], s[30:31]
	v_mad_i64_i32 v[138:139], s[56:57], v235, s1, v[140:141]
	v_mov_b32_e32 v158, v1
	v_mov_b32_dpp v159, v135 row_ror:2 row_mask:0xf bank_mask:0xf
	v_lshl_add_u64 v[138:139], v[138:139], 0, v[142:143]
	v_mov_b32_dpp v148, v134 row_ror:1 row_mask:0xf bank_mask:0xf
	v_mov_b32_dpp v158, v135 row_ror:1 row_mask:0xf bank_mask:0xf
	v_mov_b32_e32 v168, v1
	v_mov_b32_e32 v210, v1
; __device__ __forceinline__ unsigned cvt_pk_bf16(float lo, float hi) { f32x2_t_ v = {lo, hi}; bf16x2_t_ b = __builtin_convertvector(v, bf16x2_t_); return __builtin_bit_cast(unsigned, b); }
; __device__ __forceinline__ float dpp_ror1(float v) { return __builtin_bit_cast(float, __builtin_amdgcn_update_dpp(0, __builtin_bit_cast(int, v), 0x121, 0xf, 0xf, false)); }
; __device__ __forceinline__ float dpp_ror2(float v) { return __builtin_bit_cast(float, __builtin_amdgcn_update_dpp(0, __builtin_bit_cast(int, v), 0x122, 0xf, 0xf, false)); }
;     __device__ __forceinline__ void operator()(const f32x4 (&acc)[2][2][4][2], const Unit& u, int wr, int wc, int fr, int fq) const {
;     ...
;                 for (int m = 0; m < 4; ++m) {
;                     float cv[2][4];
; #pragma unroll
;                     for (int bj = 0; bj < 2; ++bj)
; #pragma unroll
;                         for (int e = 0; e < 4; ++e) {
;                             const float x = acc[ai][bj][m][n][e];
;                             const float r1s = dpp_ror1(x), r2s = dpp_ror2(x);
;                             float r1p, r2p;
;                             if (m > 0) { const float xp = acc[ai][bj][m > 0 ? m - 1 : 0][n][e]; r1p = dpp_ror1(xp); r2p = dpp_ror2(xp); }
;                             else { r1p = h1[bj][e]; r2p = (fr == 0) ? h2[bj][e] : h1[bj][e]; }
;                             const float p1 = (fr == 0) ? r1p : r1s, p2 = (fr < 2) ? r2p : r2s;
;                             cv[bj][e] = wgt[0][bj][e] * p2 + wgt[1][bj][e] * p1 + wgt[2][bj][e] * x;
;                         }
;                     const int r = u.pm * BM + ai * HALF + wr * 64 + m * 16 + fr;
;                     if (top && m == 0 && fr < 2) {
; #pragma unroll
;                         for (int bj = 0; bj < 2; ++bj) *(f32x4*)(hb + fr * 256 + bj * 128 + 4 * n) = acc[0][bj][0][n];
;                     } else {
;                         float o[4];
; #pragma unroll
;                         for (int c = 0; c < 4; ++c) { const float g = cv[0][c]; o[c] = g * __builtin_amdgcn_rcpf(1.0f + __expf(-g)) * cv[1][c]; }
;                         u32x2 w; w.x = cvt_pk_bf16(o[0], o[1]); w.y = cvt_pk_bf16(o[2], o[3]);
;                         *(u32x2*)(act + (size_t)r * 2816 + colj + 4 * n) = w;
	v_cndmask_b32_e64 v147, v159, v160, s[10:11]
	v_cndmask_b32_e64 v146, v149, v157, s[10:11]
	global_store_dwordx2 v[138:139], v[144:145], off
	v_mov_b32_e32 v167, v1
	v_mov_b32_dpp v168, v130 row_ror:2 row_mask:0xf bank_mask:0xf
	v_mov_b32_e32 v209, v1
	v_mov_b32_dpp v210, v131 row_ror:2 row_mask:0xf bank_mask:0xf
	v_cndmask_b32_e64 v145, v158, v150, s[8:9]
	v_cndmask_b32_e64 v144, v148, v156, s[8:9]
	v_pk_mul_f32 v[146:147], v[102:103], v[146:147]
	v_mov_b32_dpp v167, v130 row_ror:1 row_mask:0xf bank_mask:0xf
	v_mov_b32_dpp v209, v131 row_ror:1 row_mask:0xf bank_mask:0xf
	v_pk_fma_f32 v[144:145], v[110:111], v[144:145], v[146:147]
	v_cndmask_b32_e64 v147, v210, v224, s[10:11]
	v_cndmask_b32_e64 v146, v168, v169, s[10:11]
	v_pk_fma_f32 v[134:135], v[134:135], v[118:119], v[144:145]
	v_cndmask_b32_e64 v145, v209, v211, s[8:9]
	v_cndmask_b32_e64 v144, v167, v153, s[8:9]
	v_pk_mul_f32 v[146:147], v[98:99], v[146:147]
	v_mov_b32_e32 v162, v1
	v_pk_fma_f32 v[144:145], v[106:107], v[144:145], v[146:147]
	v_mov_b32_e32 v165, v1
	v_pk_fma_f32 v[130:131], v[130:131], v[114:115], v[144:145]
	v_mul_f32_e32 v144, 0xbfb8aa3b, v134
	v_mul_f32_e32 v145, 0xbfb8aa3b, v135
	v_exp_f32_e32 v144, v144
	v_exp_f32_e32 v145, v145
	v_mov_b32_e32 v161, v1
	v_mov_b32_dpp v162, v136 row_ror:2 row_mask:0xf bank_mask:0xf
	v_add_f32_e32 v144, 1.0, v144
	v_add_f32_e32 v145, 1.0, v145
	v_rcp_f32_e32 v144, v144
	v_rcp_f32_e32 v145, v145
	v_mov_b32_e32 v164, v1
	v_mov_b32_dpp v165, v137 row_ror:2 row_mask:0xf bank_mask:0xf
	v_mov_b32_dpp v161, v136 row_ror:1 row_mask:0xf bank_mask:0xf
	v_mov_b32_dpp v164, v137 row_ror:1 row_mask:0xf bank_mask:0xf
	v_pk_mul_f32 v[134:135], v[134:135], v[144:145]
	v_cndmask_b32_e64 v145, v165, v166, s[10:11]
	v_cndmask_b32_e64 v144, v162, v163, s[10:11]
	v_mov_b32_e32 v226, v1
	v_mov_b32_e32 v230, v1
	v_pk_mul_f32 v[130:131], v[134:135], v[130:131]
	v_cndmask_b32_e64 v135, v164, v152, s[8:9]
	v_cndmask_b32_e64 v134, v161, v151, s[8:9]
	v_pk_mul_f32 v[144:145], v[104:105], v[144:145]
	v_mov_b32_e32 v225, v1
	v_mov_b32_dpp v226, v132 row_ror:2 row_mask:0xf bank_mask:0xf
	v_mov_b32_e32 v229, v1
	v_mov_b32_dpp v230, v133 row_ror:2 row_mask:0xf bank_mask:0xf
	v_pk_fma_f32 v[134:135], v[112:113], v[134:135], v[144:145]
	v_mov_b32_dpp v225, v132 row_ror:1 row_mask:0xf bank_mask:0xf
	v_mov_b32_dpp v229, v133 row_ror:1 row_mask:0xf bank_mask:0xf
	v_pk_fma_f32 v[134:135], v[136:137], v[120:121], v[134:135]
	v_cndmask_b32_e64 v137, v230, v232, s[10:11]
	v_cndmask_b32_e64 v136, v226, v228, s[10:11]
	v_pk_mul_f32 v[136:137], v[100:101], v[136:137]
	v_cndmask_b32_e64 v145, v229, v231, s[8:9]
	v_cndmask_b32_e64 v144, v225, v227, s[8:9]
	v_pk_fma_f32 v[136:137], v[108:109], v[144:145], v[136:137]
	v_or_b32_e32 v233, 32, v208
	v_pk_fma_f32 v[132:133], v[132:133], v[116:117], v[136:137]
	v_mul_f32_e32 v136, 0xbfb8aa3b, v134
	v_mul_f32_e32 v137, 0xbfb8aa3b, v135
	v_exp_f32_e32 v136, v136
	v_exp_f32_e32 v137, v137
	v_mov_b32_e32 v147, v1
	v_mov_b32_e32 v151, v1
	v_add_f32_e32 v136, 1.0, v136
	v_add_f32_e32 v137, 1.0, v137
	v_rcp_f32_e32 v136, v136
	v_rcp_f32_e32 v137, v137
	v_mov_b32_e32 v146, v1
	v_mov_b32_dpp v147, v122 row_ror:2 row_mask:0xf bank_mask:0xf
	v_mov_b32_e32 v150, v1
	v_pk_mul_f32 v[134:135], v[134:135], v[136:137]
	v_mov_b32_dpp v151, v123 row_ror:2 row_mask:0xf bank_mask:0xf
	v_pk_mul_f32 v[132:133], v[134:135], v[132:133]
	v_cvt_pk_bf16_f32 v134, v130, v131
	v_mad_i64_i32 v[130:131], s[56:57], v233, s1, v[140:141]
	v_cvt_pk_bf16_f32 v135, v132, v133
	v_lshl_add_u64 v[130:131], v[130:131], 0, v[142:143]
	global_store_dwordx2 v[130:131], v[134:135], off
	v_mov_b32_e32 v134, v1
	v_mov_b32_e32 v135, v1
	v_mov_b32_e32 v132, v1
	v_mov_b32_dpp v134, v126 row_ror:2 row_mask:0xf bank_mask:0xf
	v_mov_b32_e32 v133, v1
	v_mov_b32_dpp v135, v127 row_ror:2 row_mask:0xf bank_mask:0xf
	v_mov_b32_dpp v132, v126 row_ror:1 row_mask:0xf bank_mask:0xf
	v_mov_b32_dpp v133, v127 row_ror:1 row_mask:0xf bank_mask:0xf
	v_cndmask_b32_e64 v135, v135, v159, s[10:11]
	v_cndmask_b32_e64 v134, v134, v149, s[10:11]
	v_cndmask_b32_e64 v133, v133, v158, s[8:9]
	v_cndmask_b32_e64 v132, v132, v148, s[8:9]
	v_pk_mul_f32 v[134:135], v[102:103], v[134:135]
	v_mov_b32_dpp v146, v122 row_ror:1 row_mask:0xf bank_mask:0xf
	v_mov_b32_dpp v150, v123 row_ror:1 row_mask:0xf bank_mask:0xf
	v_pk_fma_f32 v[132:133], v[110:111], v[132:133], v[134:135]
	v_cndmask_b32_e64 v135, v151, v210, s[10:11]
	v_cndmask_b32_e64 v134, v147, v168, s[10:11]
	v_pk_fma_f32 v[126:127], v[126:127], v[118:119], v[132:133]
	v_cndmask_b32_e64 v133, v150, v209, s[8:9]
	v_cndmask_b32_e64 v132, v146, v167, s[8:9]
	v_pk_mul_f32 v[134:135], v[98:99], v[134:135]
	v_mov_b32_e32 v137, v1
	v_pk_fma_f32 v[132:133], v[106:107], v[132:133], v[134:135]
	v_mov_b32_e32 v145, v1
	v_pk_fma_f32 v[122:123], v[122:123], v[114:115], v[132:133]
	v_mul_f32_e32 v132, 0xbfb8aa3b, v126
	v_mul_f32_e32 v133, 0xbfb8aa3b, v127
	v_exp_f32_e32 v132, v132
	v_exp_f32_e32 v133, v133
	v_mov_b32_e32 v136, v1
	v_mov_b32_dpp v137, v128 row_ror:2 row_mask:0xf bank_mask:0xf
	v_add_f32_e32 v132, 1.0, v132
	v_add_f32_e32 v133, 1.0, v133
	v_rcp_f32_e32 v132, v132
	v_rcp_f32_e32 v133, v133
	v_mov_b32_e32 v144, v1
	v_mov_b32_dpp v145, v129 row_ror:2 row_mask:0xf bank_mask:0xf
	v_mov_b32_dpp v136, v128 row_ror:1 row_mask:0xf bank_mask:0xf
	v_mov_b32_dpp v144, v129 row_ror:1 row_mask:0xf bank_mask:0xf
	v_pk_mul_f32 v[126:127], v[126:127], v[132:133]
	v_cndmask_b32_e64 v133, v145, v165, s[10:11]
	v_cndmask_b32_e64 v132, v137, v162, s[10:11]
	v_mov_b32_e32 v153, v1
	v_mov_b32_e32 v157, v1
	v_pk_mul_f32 v[122:123], v[126:127], v[122:123]
	v_cndmask_b32_e64 v127, v144, v164, s[8:9]
;     __device__ __forceinline__ void operator()(const f32x4 (&acc)[2][2][4][2], const Unit& u, int wr, int wc, int fr, int fq) const {
;     ...
;             for (int ai = 0; ai < 2; ++ai) {
;                 const bool top = (wr == 0 && ai == 0);
;                 f32x4 h1[2], h2[2];
;                 const float* sx = xch + (wr == 1 ? wc : 4 + wc) * 256 + (wr == 1 ? ai * 2 : 0) * 64 + fq * 8 + n * 4;
; #pragma unroll
;                 for (int bj = 0; bj < 2; ++bj) {
;                     if (!top) { h2[bj] = *(const f32x4*)(sx + bj * 32); h1[bj] = *(const f32x4*)(sx + 64 + bj * 32); }
;                     else { h2[bj] = (f32x4){0.f, 0.f, 0.f, 0.f}; h1[bj] = (f32x4){0.f, 0.f, 0.f, 0.f}; }
;                 }
; #pragma unroll
;                 for (int m = 0; m < 4; ++m) {
;                     float cv[2][4];
; #pragma unroll
;                     for (int bj = 0; bj < 2; ++bj)
; #pragma unroll
;                         for (int e = 0; e < 4; ++e) {
;                             const float x = acc[ai][bj][m][n][e];
;                             const float r1s = dpp_ror1(x), r2s = dpp_ror2(x);
;                             float r1p, r2p;
;                             if (m > 0) { const float xp = acc[ai][bj][m > 0 ? m - 1 : 0][n][e]; r1p = dpp_ror1(xp); r2p = dpp_ror2(xp); }
;                             else { r1p = h1[bj][e]; r2p = (fr == 0) ? h2[bj][e] : h1[bj][e]; }
;                             const float p1 = (fr == 0) ? r1p : r1s, p2 = (fr < 2) ? r2p : r2s;
;                             cv[bj][e] = wgt[0][bj][e] * p2 + wgt[1][bj][e] * p1 + wgt[2][bj][e] * x;
;                         }
;                     const int r = u.pm * BM + ai * HALF + wr * 64 + m * 16 + fr;
;                     if (top && m == 0 && fr < 2) {
; #pragma unroll
;                         for (int bj = 0; bj < 2; ++bj) *(f32x4*)(hb + fr * 256 + bj * 128 + 4 * n) = acc[0][bj][0][n];
;                     } else {
;                         float o[4];
; #pragma unroll
;                         for (int c = 0; c < 4; ++c) { const float g = cv[0][c]; o[c] = g * __builtin_amdgcn_rcpf(1.0f + __expf(-g)) * cv[1][c]; }
;                         u32x2 w; w.x = cvt_pk_bf16(o[0], o[1]); w.y = cvt_pk_bf16(o[2], o[3]);
;                         *(u32x2*)(act + (size_t)r * 2816 + colj + 4 * n) = w;
	v_cndmask_b32_e64 v126, v136, v161, s[8:9]
	v_pk_mul_f32 v[132:133], v[104:105], v[132:133]
	v_mov_b32_e32 v152, v1
	v_mov_b32_dpp v153, v124 row_ror:2 row_mask:0xf bank_mask:0xf
	v_mov_b32_e32 v156, v1
	v_mov_b32_dpp v157, v125 row_ror:2 row_mask:0xf bank_mask:0xf
	v_pk_fma_f32 v[126:127], v[112:113], v[126:127], v[132:133]
	v_mov_b32_dpp v152, v124 row_ror:1 row_mask:0xf bank_mask:0xf
	v_mov_b32_dpp v156, v125 row_ror:1 row_mask:0xf bank_mask:0xf
	v_pk_fma_f32 v[126:127], v[128:129], v[120:121], v[126:127]
	v_cndmask_b32_e64 v129, v157, v230, s[10:11]
	v_cndmask_b32_e64 v128, v153, v226, s[10:11]
	v_pk_mul_f32 v[128:129], v[100:101], v[128:129]
	v_cndmask_b32_e64 v133, v156, v229, s[8:9]
	v_cndmask_b32_e64 v132, v152, v225, s[8:9]
	v_pk_fma_f32 v[128:129], v[108:109], v[132:133], v[128:129]
	v_or_b32_e32 v160, 48, v208
	v_pk_fma_f32 v[124:125], v[124:125], v[116:117], v[128:129]
	v_mul_f32_e32 v128, 0xbfb8aa3b, v126
	v_mul_f32_e32 v129, 0xbfb8aa3b, v127
	v_exp_f32_e32 v128, v128
	v_exp_f32_e32 v129, v129
	v_mov_b32_e32 v152, v1
	v_mov_b32_e32 v156, v1
	v_add_f32_e32 v128, 1.0, v128
	v_add_f32_e32 v129, 1.0, v129
	v_rcp_f32_e32 v128, v128
	v_rcp_f32_e32 v129, v129
	v_mov_b32_e32 v137, v1
	v_mov_b32_dpp v152, v94 row_ror:2 row_mask:0xf bank_mask:0xf
	v_mov_b32_e32 v153, v1
	v_pk_mul_f32 v[126:127], v[126:127], v[128:129]
	v_mov_b32_dpp v156, v95 row_ror:2 row_mask:0xf bank_mask:0xf
	v_pk_mul_f32 v[124:125], v[126:127], v[124:125]
	v_cvt_pk_bf16_f32 v126, v122, v123
	v_mad_i64_i32 v[122:123], s[56:57], v160, s1, v[140:141]
	v_cvt_pk_bf16_f32 v127, v124, v125
	v_lshl_add_u64 v[122:123], v[122:123], 0, v[142:143]
	global_store_dwordx2 v[122:123], v[126:127], off
	ds_read_b128 v[124:127], v205
	ds_read_b128 v[132:135], v205 offset:256
	ds_read_b128 v[144:147], v205 offset:128
	ds_read_b128 v[148:151], v205 offset:384
	v_mov_b32_dpp v137, v94 row_ror:1 row_mask:0xf bank_mask:0xf
	v_mov_b32_dpp v153, v95 row_ror:1 row_mask:0xf bank_mask:0xf
	s_waitcnt lgkmcnt(0)
	v_cndmask_b32_e64 v128, v132, v124, s[8:9]
	v_cndmask_b32_e64 v129, v133, v125, s[8:9]
	v_cndmask_b32_e64 v129, v156, v129, s[10:11]
	v_cndmask_b32_e64 v128, v152, v128, s[10:11]
	v_mov_b32_e32 v162, v1
	v_mov_b32_e32 v164, v1
	v_cndmask_b32_e64 v125, v153, v133, s[8:9]
	v_cndmask_b32_e64 v124, v137, v132, s[8:9]
	v_pk_mul_f32 v[128:129], v[102:103], v[128:129]
	v_mov_b32_e32 v161, v1
	v_mov_b32_dpp v162, v90 row_ror:2 row_mask:0xf bank_mask:0xf
	v_mov_b32_e32 v163, v1
	v_mov_b32_dpp v164, v91 row_ror:2 row_mask:0xf bank_mask:0xf
	v_pk_fma_f32 v[124:125], v[110:111], v[124:125], v[128:129]
	v_cndmask_b32_e64 v128, v148, v144, s[8:9]
	v_cndmask_b32_e64 v129, v149, v145, s[8:9]
	v_mov_b32_dpp v161, v90 row_ror:1 row_mask:0xf bank_mask:0xf
	v_mov_b32_dpp v163, v91 row_ror:1 row_mask:0xf bank_mask:0xf
	v_cndmask_b32_e64 v129, v164, v129, s[10:11]
	v_cndmask_b32_e64 v128, v162, v128, s[10:11]
	v_pk_fma_f32 v[94:95], v[94:95], v[118:119], v[124:125]
	v_cndmask_b32_e64 v125, v163, v149, s[8:9]
	v_cndmask_b32_e64 v124, v161, v148, s[8:9]
	v_pk_mul_f32 v[128:129], v[98:99], v[128:129]
	v_mov_b32_e32 v158, v1
	v_pk_fma_f32 v[124:125], v[106:107], v[124:125], v[128:129]
	v_mov_b32_e32 v160, v1
	v_pk_fma_f32 v[90:91], v[90:91], v[114:115], v[124:125]
	v_mul_f32_e32 v124, 0xbfb8aa3b, v94
	v_mul_f32_e32 v125, 0xbfb8aa3b, v95
	v_exp_f32_e32 v124, v124
	v_exp_f32_e32 v125, v125
	v_mov_b32_e32 v157, v1
	v_mov_b32_dpp v158, v96 row_ror:2 row_mask:0xf bank_mask:0xf
	v_add_f32_e32 v124, 1.0, v124
	v_add_f32_e32 v125, 1.0, v125
	v_rcp_f32_e32 v124, v124
	v_rcp_f32_e32 v125, v125
	v_mov_b32_e32 v159, v1
	v_mov_b32_dpp v160, v97 row_ror:2 row_mask:0xf bank_mask:0xf
	v_mov_b32_dpp v157, v96 row_ror:1 row_mask:0xf bank_mask:0xf
	v_pk_mul_f32 v[94:95], v[94:95], v[124:125]
	v_cndmask_b32_e64 v124, v134, v126, s[8:9]
	v_cndmask_b32_e64 v125, v135, v127, s[8:9]
	v_mov_b32_dpp v159, v97 row_ror:1 row_mask:0xf bank_mask:0xf
	v_cndmask_b32_e64 v125, v160, v125, s[10:11]
	v_cndmask_b32_e64 v124, v158, v124, s[10:11]
	v_pk_mul_f32 v[90:91], v[94:95], v[90:91]
	v_cndmask_b32_e64 v95, v159, v135, s[8:9]
	v_cndmask_b32_e64 v94, v157, v134, s[8:9]
	v_pk_mul_f32 v[124:125], v[104:105], v[124:125]
	v_mov_b32_e32 v166, v1
	v_mov_b32_e32 v168, v1
	v_pk_fma_f32 v[94:95], v[112:113], v[94:95], v[124:125]
	v_mov_b32_e32 v165, v1
	v_mov_b32_dpp v166, v92 row_ror:2 row_mask:0xf bank_mask:0xf
	v_mov_b32_e32 v167, v1
	v_mov_b32_dpp v168, v93 row_ror:2 row_mask:0xf bank_mask:0xf
	v_pk_fma_f32 v[94:95], v[96:97], v[120:121], v[94:95]
	v_cndmask_b32_e64 v96, v150, v146, s[8:9]
	v_cndmask_b32_e64 v97, v151, v147, s[8:9]
	v_mov_b32_dpp v165, v92 row_ror:1 row_mask:0xf bank_mask:0xf
	v_mov_b32_dpp v167, v93 row_ror:1 row_mask:0xf bank_mask:0xf
	v_cndmask_b32_e64 v97, v168, v97, s[10:11]
	v_cndmask_b32_e64 v96, v166, v96, s[10:11]
	v_pk_mul_f32 v[96:97], v[100:101], v[96:97]
	v_cndmask_b32_e64 v125, v167, v151, s[8:9]
	v_cndmask_b32_e64 v124, v165, v150, s[8:9]
	v_pk_fma_f32 v[96:97], v[108:109], v[124:125], v[96:97]
	v_add_u32_e32 v136, 0x80, v208
	v_pk_fma_f32 v[92:93], v[92:93], v[116:117], v[96:97]
	v_mul_f32_e32 v96, 0xbfb8aa3b, v94
	v_mul_f32_e32 v97, 0xbfb8aa3b, v95
	v_exp_f32_e32 v96, v96
	v_exp_f32_e32 v97, v97
	v_cvt_pk_bf16_f32 v90, v90, v91
	v_mov_b32_e32 v135, v1
	v_add_f32_e32 v96, 1.0, v96
	v_add_f32_e32 v97, 1.0, v97
	v_rcp_f32_e32 v96, v96
	v_rcp_f32_e32 v97, v97
	v_mov_b32_e32 v144, v1
	v_mov_b32_e32 v134, v1
	v_mov_b32_dpp v135, v82 row_ror:2 row_mask:0xf bank_mask:0xf
	v_pk_mul_f32 v[94:95], v[94:95], v[96:97]
	v_mov_b32_e32 v97, v1
	v_pk_mul_f32 v[92:93], v[94:95], v[92:93]
	v_mov_b32_e32 v95, v1
	v_cvt_pk_bf16_f32 v91, v92, v93
; __device__ __forceinline__ unsigned cvt_pk_bf16(float lo, float hi) { f32x2_t_ v = {lo, hi}; bf16x2_t_ b = __builtin_convertvector(v, bf16x2_t_); return __builtin_bit_cast(unsigned, b); }
; __device__ __forceinline__ float dpp_ror1(float v) { return __builtin_bit_cast(float, __builtin_amdgcn_update_dpp(0, __builtin_bit_cast(int, v), 0x121, 0xf, 0xf, false)); }
; __device__ __forceinline__ float dpp_ror2(float v) { return __builtin_bit_cast(float, __builtin_amdgcn_update_dpp(0, __builtin_bit_cast(int, v), 0x122, 0xf, 0xf, false)); }
;     __device__ __forceinline__ void operator()(const f32x4 (&acc)[2][2][4][2], const Unit& u, int wr, int wc, int fr, int fq) const {
;     ...
;                 for (int m = 0; m < 4; ++m) {
;                     float cv[2][4];
; #pragma unroll
;                     for (int bj = 0; bj < 2; ++bj)
; #pragma unroll
;                         for (int e = 0; e < 4; ++e) {
;                             const float x = acc[ai][bj][m][n][e];
;                             const float r1s = dpp_ror1(x), r2s = dpp_ror2(x);
;                             float r1p, r2p;
;                             if (m > 0) { const float xp = acc[ai][bj][m > 0 ? m - 1 : 0][n][e]; r1p = dpp_ror1(xp); r2p = dpp_ror2(xp); }
;                             else { r1p = h1[bj][e]; r2p = (fr == 0) ? h2[bj][e] : h1[bj][e]; }
;                             const float p1 = (fr == 0) ? r1p : r1s, p2 = (fr < 2) ? r2p : r2s;
;                             cv[bj][e] = wgt[0][bj][e] * p2 + wgt[1][bj][e] * p1 + wgt[2][bj][e] * x;
;                         }
;                     const int r = u.pm * BM + ai * HALF + wr * 64 + m * 16 + fr;
;                     if (top && m == 0 && fr < 2) {
; #pragma unroll
;                         for (int bj = 0; bj < 2; ++bj) *(f32x4*)(hb + fr * 256 + bj * 128 + 4 * n) = acc[0][bj][0][n];
;                     } else {
;                         float o[4];
; #pragma unroll
;                         for (int c = 0; c < 4; ++c) { const float g = cv[0][c]; o[c] = g * __builtin_amdgcn_rcpf(1.0f + __expf(-g)) * cv[1][c]; }
;                         u32x2 w; w.x = cvt_pk_bf16(o[0], o[1]); w.y = cvt_pk_bf16(o[2], o[3]);
;                         *(u32x2*)(act + (size_t)r * 2816 + colj + 4 * n) = w;
	v_mad_i64_i32 v[92:93], s[56:57], v136, s1, v[140:141]
	v_mov_b32_e32 v94, v1
	v_mov_b32_dpp v95, v86 row_ror:2 row_mask:0xf bank_mask:0xf
	v_mov_b32_e32 v96, v1
	v_mov_b32_dpp v97, v87 row_ror:2 row_mask:0xf bank_mask:0xf
	v_lshl_add_u64 v[124:125], v[92:93], 0, v[142:143]
	v_mov_b32_dpp v94, v86 row_ror:1 row_mask:0xf bank_mask:0xf
	v_mov_b32_dpp v96, v87 row_ror:1 row_mask:0xf bank_mask:0xf
	v_cndmask_b32_e64 v93, v97, v156, s[10:11]
	v_cndmask_b32_e64 v92, v95, v152, s[10:11]
	global_store_dwordx2 v[124:125], v[90:91], off
	v_mov_b32_e32 v136, v1
	v_mov_b32_dpp v144, v83 row_ror:2 row_mask:0xf bank_mask:0xf
	v_cndmask_b32_e64 v91, v96, v153, s[8:9]
	v_cndmask_b32_e64 v90, v94, v137, s[8:9]
	v_pk_mul_f32 v[92:93], v[102:103], v[92:93]
	v_mov_b32_dpp v134, v82 row_ror:1 row_mask:0xf bank_mask:0xf
	v_mov_b32_dpp v136, v83 row_ror:1 row_mask:0xf bank_mask:0xf
	v_pk_fma_f32 v[90:91], v[110:111], v[90:91], v[92:93]
	v_cndmask_b32_e64 v93, v144, v164, s[10:11]
	v_cndmask_b32_e64 v92, v135, v162, s[10:11]
	v_pk_fma_f32 v[86:87], v[86:87], v[118:119], v[90:91]
	v_cndmask_b32_e64 v91, v136, v163, s[8:9]
	v_cndmask_b32_e64 v90, v134, v161, s[8:9]
	v_pk_mul_f32 v[92:93], v[98:99], v[92:93]
	v_mov_b32_e32 v129, v1
	v_pk_fma_f32 v[90:91], v[106:107], v[90:91], v[92:93]
	v_mov_b32_e32 v133, v1
	v_pk_fma_f32 v[82:83], v[82:83], v[114:115], v[90:91]
	v_mul_f32_e32 v90, 0xbfb8aa3b, v86
	v_mul_f32_e32 v91, 0xbfb8aa3b, v87
	v_exp_f32_e32 v90, v90
	v_exp_f32_e32 v91, v91
	v_mov_b32_e32 v128, v1
	v_mov_b32_dpp v129, v88 row_ror:2 row_mask:0xf bank_mask:0xf
	v_add_f32_e32 v90, 1.0, v90
	v_add_f32_e32 v91, 1.0, v91
	v_rcp_f32_e32 v90, v90
	v_rcp_f32_e32 v91, v91
	v_mov_b32_e32 v132, v1
	v_mov_b32_dpp v133, v89 row_ror:2 row_mask:0xf bank_mask:0xf
	v_mov_b32_dpp v128, v88 row_ror:1 row_mask:0xf bank_mask:0xf
	v_mov_b32_dpp v132, v89 row_ror:1 row_mask:0xf bank_mask:0xf
	v_pk_mul_f32 v[86:87], v[86:87], v[90:91]
	v_cndmask_b32_e64 v91, v133, v160, s[10:11]
	v_cndmask_b32_e64 v90, v129, v158, s[10:11]
	v_mov_b32_e32 v146, v1
	v_mov_b32_e32 v148, v1
	v_pk_mul_f32 v[82:83], v[86:87], v[82:83]
	v_cndmask_b32_e64 v87, v132, v159, s[8:9]
	v_cndmask_b32_e64 v86, v128, v157, s[8:9]
	v_pk_mul_f32 v[90:91], v[104:105], v[90:91]
	v_mov_b32_e32 v145, v1
	v_mov_b32_dpp v146, v84 row_ror:2 row_mask:0xf bank_mask:0xf
	v_mov_b32_e32 v147, v1
	v_mov_b32_dpp v148, v85 row_ror:2 row_mask:0xf bank_mask:0xf
	v_pk_fma_f32 v[86:87], v[112:113], v[86:87], v[90:91]
	v_mov_b32_dpp v145, v84 row_ror:1 row_mask:0xf bank_mask:0xf
	v_mov_b32_dpp v147, v85 row_ror:1 row_mask:0xf bank_mask:0xf
	v_pk_fma_f32 v[86:87], v[88:89], v[120:121], v[86:87]
	v_cndmask_b32_e64 v89, v148, v168, s[10:11]
	v_cndmask_b32_e64 v88, v146, v166, s[10:11]
	v_pk_mul_f32 v[88:89], v[100:101], v[88:89]
	v_cndmask_b32_e64 v91, v147, v167, s[8:9]
	v_cndmask_b32_e64 v90, v145, v165, s[8:9]
	v_pk_fma_f32 v[88:89], v[108:109], v[90:91], v[88:89]
	v_add_u32_e32 v126, 0x90, v208
	v_pk_fma_f32 v[84:85], v[84:85], v[116:117], v[88:89]
	v_mul_f32_e32 v88, 0xbfb8aa3b, v86
	v_mul_f32_e32 v89, 0xbfb8aa3b, v87
	v_exp_f32_e32 v88, v88
	v_exp_f32_e32 v89, v89
	v_cvt_pk_bf16_f32 v82, v82, v83
	v_mov_b32_e32 v149, v1
	v_add_f32_e32 v88, 1.0, v88
	v_add_f32_e32 v89, 1.0, v89
	v_rcp_f32_e32 v88, v88
	v_rcp_f32_e32 v89, v89
	v_mov_b32_e32 v151, v1
	v_mov_b32_e32 v137, v1
	v_mov_b32_dpp v149, v74 row_ror:2 row_mask:0xf bank_mask:0xf
	v_pk_mul_f32 v[86:87], v[86:87], v[88:89]
	v_mov_b32_e32 v89, v1
	v_pk_mul_f32 v[84:85], v[86:87], v[84:85]
	v_mov_b32_e32 v87, v1
	v_cvt_pk_bf16_f32 v83, v84, v85
	v_mad_i64_i32 v[84:85], s[56:57], v126, s1, v[140:141]
	v_mov_b32_e32 v86, v1
	v_mov_b32_dpp v87, v78 row_ror:2 row_mask:0xf bank_mask:0xf
	v_mov_b32_e32 v88, v1
	v_mov_b32_dpp v89, v79 row_ror:2 row_mask:0xf bank_mask:0xf
	v_lshl_add_u64 v[126:127], v[84:85], 0, v[142:143]
	v_mov_b32_dpp v86, v78 row_ror:1 row_mask:0xf bank_mask:0xf
	v_mov_b32_dpp v88, v79 row_ror:1 row_mask:0xf bank_mask:0xf
	v_cndmask_b32_e64 v85, v89, v97, s[10:11]
	v_cndmask_b32_e64 v84, v87, v95, s[10:11]
	global_store_dwordx2 v[126:127], v[82:83], off
	v_mov_b32_e32 v150, v1
	v_mov_b32_dpp v151, v75 row_ror:2 row_mask:0xf bank_mask:0xf
	v_cndmask_b32_e64 v83, v88, v96, s[8:9]
	v_cndmask_b32_e64 v82, v86, v94, s[8:9]
	v_pk_mul_f32 v[84:85], v[102:103], v[84:85]
	v_mov_b32_dpp v137, v74 row_ror:1 row_mask:0xf bank_mask:0xf
	v_mov_b32_dpp v150, v75 row_ror:1 row_mask:0xf bank_mask:0xf
	v_pk_fma_f32 v[82:83], v[110:111], v[82:83], v[84:85]
	v_cndmask_b32_e64 v85, v151, v144, s[10:11]
	v_cndmask_b32_e64 v84, v149, v135, s[10:11]
	v_pk_fma_f32 v[78:79], v[78:79], v[118:119], v[82:83]
	v_cndmask_b32_e64 v83, v150, v136, s[8:9]
	v_cndmask_b32_e64 v82, v137, v134, s[8:9]
	v_pk_mul_f32 v[84:85], v[98:99], v[84:85]
	v_mov_b32_e32 v91, v1
	v_pk_fma_f32 v[82:83], v[106:107], v[82:83], v[84:85]
	v_mov_b32_e32 v93, v1
	v_pk_fma_f32 v[74:75], v[74:75], v[114:115], v[82:83]
	v_mul_f32_e32 v82, 0xbfb8aa3b, v78
	v_mul_f32_e32 v83, 0xbfb8aa3b, v79
	v_exp_f32_e32 v82, v82
	v_exp_f32_e32 v83, v83
	v_mov_b32_e32 v90, v1
	v_mov_b32_dpp v91, v80 row_ror:2 row_mask:0xf bank_mask:0xf
	v_add_f32_e32 v82, 1.0, v82
	v_add_f32_e32 v83, 1.0, v83
	v_rcp_f32_e32 v82, v82
	v_rcp_f32_e32 v83, v83
	v_mov_b32_e32 v92, v1
	v_mov_b32_dpp v93, v81 row_ror:2 row_mask:0xf bank_mask:0xf
	v_mov_b32_dpp v90, v80 row_ror:1 row_mask:0xf bank_mask:0xf
	v_mov_b32_dpp v92, v81 row_ror:1 row_mask:0xf bank_mask:0xf
	v_pk_mul_f32 v[78:79], v[78:79], v[82:83]
	v_cndmask_b32_e64 v83, v93, v133, s[10:11]
	v_cndmask_b32_e64 v82, v91, v129, s[10:11]
	v_mov_b32_e32 v153, v1
	v_mov_b32_e32 v157, v1
	v_pk_mul_f32 v[74:75], v[78:79], v[74:75]
;     __device__ __forceinline__ void operator()(const f32x4 (&acc)[2][2][4][2], const Unit& u, int wr, int wc, int fr, int fq) const {
;     ...
;         for (int n = 0; n < 2; ++n) {
;             f32x4 wgt[3][2];
; #pragma unroll
;             for (int i = 0; i < 3; ++i)
; #pragma unroll
;                 for (int bj = 0; bj < 2; ++bj) wgt[i][bj] = *(const f32x4*)(cw + i * 5632 + bj * 2816 + colj + 4 * n);
; #pragma unroll
;             for (int ai = 0; ai < 2; ++ai) {
;                 const bool top = (wr == 0 && ai == 0);
;                 f32x4 h1[2], h2[2];
;                 const float* sx = xch + (wr == 1 ? wc : 4 + wc) * 256 + (wr == 1 ? ai * 2 : 0) * 64 + fq * 8 + n * 4;
; #pragma unroll
;                 for (int bj = 0; bj < 2; ++bj) {
;                     if (!top) { h2[bj] = *(const f32x4*)(sx + bj * 32); h1[bj] = *(const f32x4*)(sx + 64 + bj * 32); }
;                     else { h2[bj] = (f32x4){0.f, 0.f, 0.f, 0.f}; h1[bj] = (f32x4){0.f, 0.f, 0.f, 0.f}; }
;                 }
; #pragma unroll
;                 for (int m = 0; m < 4; ++m) {
;                     float cv[2][4];
; #pragma unroll
;                     for (int bj = 0; bj < 2; ++bj)
; #pragma unroll
;                         for (int e = 0; e < 4; ++e) {
;                             const float x = acc[ai][bj][m][n][e];
;                             const float r1s = dpp_ror1(x), r2s = dpp_ror2(x);
;                             float r1p, r2p;
;                             if (m > 0) { const float xp = acc[ai][bj][m > 0 ? m - 1 : 0][n][e]; r1p = dpp_ror1(xp); r2p = dpp_ror2(xp); }
;                             else { r1p = h1[bj][e]; r2p = (fr == 0) ? h2[bj][e] : h1[bj][e]; }
;                             const float p1 = (fr == 0) ? r1p : r1s, p2 = (fr < 2) ? r2p : r2s;
;                             cv[bj][e] = wgt[0][bj][e] * p2 + wgt[1][bj][e] * p1 + wgt[2][bj][e] * x;
;                         }
;                     const int r = u.pm * BM + ai * HALF + wr * 64 + m * 16 + fr;
;                     if (top && m == 0 && fr < 2) {
; #pragma unroll
;                         for (int bj = 0; bj < 2; ++bj) *(f32x4*)(hb + fr * 256 + bj * 128 + 4 * n) = acc[0][bj][0][n];
;                     } else {
;                         float o[4];
; #pragma unroll
	v_cndmask_b32_e64 v79, v92, v132, s[8:9]
	v_cndmask_b32_e64 v78, v90, v128, s[8:9]
	v_pk_mul_f32 v[82:83], v[104:105], v[82:83]
	v_mov_b32_e32 v152, v1
	v_mov_b32_dpp v153, v76 row_ror:2 row_mask:0xf bank_mask:0xf
	v_mov_b32_e32 v156, v1
	v_mov_b32_dpp v157, v77 row_ror:2 row_mask:0xf bank_mask:0xf
	v_pk_fma_f32 v[78:79], v[112:113], v[78:79], v[82:83]
	v_mov_b32_dpp v152, v76 row_ror:1 row_mask:0xf bank_mask:0xf
	v_mov_b32_dpp v156, v77 row_ror:1 row_mask:0xf bank_mask:0xf
	v_pk_fma_f32 v[78:79], v[80:81], v[120:121], v[78:79]
	v_cndmask_b32_e64 v81, v157, v148, s[10:11]
	v_cndmask_b32_e64 v80, v153, v146, s[10:11]
	v_pk_mul_f32 v[80:81], v[100:101], v[80:81]
	v_cndmask_b32_e64 v83, v156, v147, s[8:9]
	v_cndmask_b32_e64 v82, v152, v145, s[8:9]
	v_pk_fma_f32 v[80:81], v[108:109], v[82:83], v[80:81]
	v_add_u32_e32 v158, 0xa0, v208
	v_pk_fma_f32 v[76:77], v[76:77], v[116:117], v[80:81]
	v_mul_f32_e32 v80, 0xbfb8aa3b, v78
	v_mul_f32_e32 v81, 0xbfb8aa3b, v79
	v_exp_f32_e32 v80, v80
	v_exp_f32_e32 v81, v81
	v_cvt_pk_bf16_f32 v74, v74, v75
	v_mov_b32_e32 v84, v1
	v_add_f32_e32 v80, 1.0, v80
	v_add_f32_e32 v81, 1.0, v81
	v_rcp_f32_e32 v80, v80
	v_rcp_f32_e32 v81, v81
	v_mov_b32_e32 v85, v1
	v_mov_b32_dpp v84, v6 row_ror:2 row_mask:0xf bank_mask:0xf
	v_mov_b32_e32 v83, v1
	v_pk_mul_f32 v[78:79], v[78:79], v[80:81]
	v_mov_b32_dpp v85, v7 row_ror:2 row_mask:0xf bank_mask:0xf
	v_pk_mul_f32 v[76:77], v[78:79], v[76:77]
	v_mov_b32_e32 v78, v1
	v_cvt_pk_bf16_f32 v75, v76, v77
	v_mad_i64_i32 v[76:77], s[56:57], v158, s1, v[140:141]
	v_lshl_add_u64 v[128:129], v[76:77], 0, v[142:143]
	v_mov_b32_e32 v76, v1
	v_mov_b32_e32 v77, v1
	global_store_dwordx2 v[128:129], v[74:75], off
	v_mov_b32_e32 v74, v1
	v_mov_b32_dpp v76, v14 row_ror:2 row_mask:0xf bank_mask:0xf
	v_mov_b32_e32 v75, v1
	v_mov_b32_dpp v77, v15 row_ror:2 row_mask:0xf bank_mask:0xf
	v_mov_b32_dpp v74, v14 row_ror:1 row_mask:0xf bank_mask:0xf
	v_mov_b32_dpp v75, v15 row_ror:1 row_mask:0xf bank_mask:0xf
	v_mov_b32_e32 v79, v1
	v_cndmask_b32_e64 v77, v77, v89, s[10:11]
	v_cndmask_b32_e64 v76, v76, v87, s[10:11]
	v_mov_b32_dpp v78, v6 row_ror:1 row_mask:0xf bank_mask:0xf
	v_mov_b32_dpp v79, v7 row_ror:1 row_mask:0xf bank_mask:0xf
	v_cndmask_b32_e64 v75, v75, v88, s[8:9]
	v_cndmask_b32_e64 v74, v74, v86, s[8:9]
	v_pk_mul_f32 v[76:77], v[102:103], v[76:77]
	v_mov_b32_e32 v81, v1
	v_pk_fma_f32 v[74:75], v[110:111], v[74:75], v[76:77]
	v_cndmask_b32_e64 v77, v79, v150, s[8:9]
	v_cndmask_b32_e64 v76, v78, v137, s[8:9]
	v_cndmask_b32_e64 v79, v85, v151, s[10:11]
	v_cndmask_b32_e64 v78, v84, v149, s[10:11]
	v_pk_fma_f32 v[74:75], v[14:15], v[118:119], v[74:75]
	v_pk_mul_f32 v[78:79], v[98:99], v[78:79]
	v_mov_b32_e32 v80, v1
	v_pk_fma_f32 v[76:77], v[106:107], v[76:77], v[78:79]
	v_mul_f32_e32 v78, 0xbfb8aa3b, v74
	v_mul_f32_e32 v79, 0xbfb8aa3b, v75
	v_exp_f32_e32 v78, v78
	v_exp_f32_e32 v79, v79
	v_mov_b32_dpp v81, v16 row_ror:2 row_mask:0xf bank_mask:0xf
	v_mov_b32_e32 v82, v1
	v_add_f32_e32 v78, 1.0, v78
	v_add_f32_e32 v79, 1.0, v79
	v_rcp_f32_e32 v78, v78
	v_rcp_f32_e32 v79, v79
	v_mov_b32_dpp v83, v17 row_ror:2 row_mask:0xf bank_mask:0xf
	v_mov_b32_dpp v80, v16 row_ror:1 row_mask:0xf bank_mask:0xf
	v_mov_b32_dpp v82, v17 row_ror:1 row_mask:0xf bank_mask:0xf
	v_mov_b32_e32 v95, v1
	v_mov_b32_e32 v97, v1
	v_pk_fma_f32 v[76:77], v[6:7], v[114:115], v[76:77]
	v_pk_mul_f32 v[74:75], v[74:75], v[78:79]
	v_cndmask_b32_e64 v79, v83, v93, s[10:11]
	v_cndmask_b32_e64 v78, v81, v91, s[10:11]
	v_mov_b32_e32 v94, v1
	v_mov_b32_dpp v95, v8 row_ror:2 row_mask:0xf bank_mask:0xf
	v_mov_b32_e32 v96, v1
	v_mov_b32_dpp v97, v9 row_ror:2 row_mask:0xf bank_mask:0xf
	v_pk_mul_f32 v[74:75], v[74:75], v[76:77]
	v_cndmask_b32_e64 v77, v82, v92, s[8:9]
	v_cndmask_b32_e64 v76, v80, v90, s[8:9]
	v_pk_mul_f32 v[78:79], v[104:105], v[78:79]
	v_mov_b32_dpp v94, v8 row_ror:1 row_mask:0xf bank_mask:0xf
	v_mov_b32_dpp v96, v9 row_ror:1 row_mask:0xf bank_mask:0xf
	v_pk_fma_f32 v[76:77], v[112:113], v[76:77], v[78:79]
	v_cndmask_b32_e64 v79, v97, v157, s[10:11]
	v_cndmask_b32_e64 v78, v95, v153, s[10:11]
	v_pk_fma_f32 v[76:77], v[16:17], v[120:121], v[76:77]
	v_pk_mul_f32 v[78:79], v[100:101], v[78:79]
	v_cndmask_b32_e64 v81, v96, v156, s[8:9]
	v_cndmask_b32_e64 v80, v94, v152, s[8:9]
	v_pk_fma_f32 v[78:79], v[108:109], v[80:81], v[78:79]
	v_mul_f32_e32 v80, 0xbfb8aa3b, v76
	v_mul_f32_e32 v81, 0xbfb8aa3b, v77
	v_exp_f32_e32 v80, v80
	v_exp_f32_e32 v81, v81
	v_pk_fma_f32 v[78:79], v[8:9], v[116:117], v[78:79]
	v_add_u32_e32 v132, 0xb0, v208
	v_add_f32_e32 v80, 1.0, v80
	v_add_f32_e32 v81, 1.0, v81
	v_rcp_f32_e32 v80, v80
	v_rcp_f32_e32 v81, v81
	v_cvt_pk_bf16_f32 v74, v74, v75
	s_mov_b64 s[78:79], -1
	s_mov_b32 s59, s68
	v_pk_mul_f32 v[76:77], v[76:77], v[80:81]
	s_nop 0
	v_pk_mul_f32 v[76:77], v[76:77], v[78:79]
	v_add_co_u32_e32 v78, vcc, 0x2000, v192
	v_cvt_pk_bf16_f32 v75, v76, v77
	s_nop 0
	v_addc_co_u32_e32 v79, vcc, 0, v193, vcc
	v_add_co_u32_e32 v82, vcc, 0x5000, v192
	v_mad_i64_i32 v[76:77], s[56:57], v132, s1, v[140:141]
	s_nop 0
	v_addc_co_u32_e32 v83, vcc, 0, v193, vcc
	v_add_co_u32_e32 v86, vcc, 0x8000, v192
	v_lshl_add_u64 v[114:115], v[76:77], 0, v[142:143]
	s_nop 0
	v_addc_co_u32_e32 v87, vcc, 0, v193, vcc
	v_add_co_u32_e32 v90, vcc, 0xb000, v192
	global_store_dwordx2 v[114:115], v[74:75], off
	s_nop 0
	v_addc_co_u32_e32 v91, vcc, 0, v193, vcc
	v_add_co_u32_e32 v94, vcc, 0xd000, v192
	global_load_dwordx4 v[74:77], v[192:193], off offset:16
	s_nop 0
	v_addc_co_u32_e32 v95, vcc, 0, v193, vcc
	global_load_dwordx4 v[78:81], v[78:79], off offset:3088
	s_and_b64 vcc, exec, s[14:15]
	global_load_dwordx4 v[82:85], v[82:83], off offset:2064
	s_nop 0
	global_load_dwordx4 v[86:89], v[86:87], off offset:1040
	s_nop 0
	global_load_dwordx4 v[90:93], v[90:91], off offset:16
	s_nop 0
	global_load_dwordx4 v[94:97], v[94:95], off offset:3088
	s_cbranch_vccnz .LBB0_84
	ds_read_b128 v[102:105], v204 offset:16
	ds_read_b128 v[98:101], v204 offset:272
	s_cbranch_execnz .LBB0_86
	s_branch .LBB0_85

; __device__ __forceinline__ unsigned cvt_pk_bf16(float lo, float hi) { f32x2_t_ v = {lo, hi}; bf16x2_t_ b = __builtin_convertvector(v, bf16x2_t_); return __builtin_bit_cast(unsigned, b); }
; __device__ __forceinline__ float dpp_ror1(float v) { return __builtin_bit_cast(float, __builtin_amdgcn_update_dpp(0, __builtin_bit_cast(int, v), 0x121, 0xf, 0xf, false)); }
; __device__ __forceinline__ float dpp_ror2(float v) { return __builtin_bit_cast(float, __builtin_amdgcn_update_dpp(0, __builtin_bit_cast(int, v), 0x122, 0xf, 0xf, false)); }
;     __device__ __forceinline__ void operator()(const f32x4 (&acc)[2][2][4][2], const Unit& u, int wr, int wc, int fr, int fq) const {
;     ...
;                 for (int m = 0; m < 4; ++m) {
;                     float cv[2][4];
; #pragma unroll
;                     for (int bj = 0; bj < 2; ++bj)
; #pragma unroll
;                         for (int e = 0; e < 4; ++e) {
;                             const float x = acc[ai][bj][m][n][e];
;                             const float r1s = dpp_ror1(x), r2s = dpp_ror2(x);
;                             float r1p, r2p;
;                             if (m > 0) { const float xp = acc[ai][bj][m > 0 ? m - 1 : 0][n][e]; r1p = dpp_ror1(xp); r2p = dpp_ror2(xp); }
;                             else { r1p = h1[bj][e]; r2p = (fr == 0) ? h2[bj][e] : h1[bj][e]; }
;                             const float p1 = (fr == 0) ? r1p : r1s, p2 = (fr < 2) ? r2p : r2s;
;                             cv[bj][e] = wgt[0][bj][e] * p2 + wgt[1][bj][e] * p1 + wgt[2][bj][e] * x;
;                         }
;                     const int r = u.pm * BM + ai * HALF + wr * 64 + m * 16 + fr;
;                     if (top && m == 0 && fr < 2) {
; #pragma unroll
;                         for (int bj = 0; bj < 2; ++bj) *(f32x4*)(hb + fr * 256 + bj * 128 + 4 * n) = acc[0][bj][0][n];
;                     } else {
;                         float o[4];
; #pragma unroll
;                         for (int c = 0; c < 4; ++c) { const float g = cv[0][c]; o[c] = g * __builtin_amdgcn_rcpf(1.0f + __expf(-g)) * cv[1][c]; }
;                         u32x2 w; w.x = cvt_pk_bf16(o[0], o[1]); w.y = cvt_pk_bf16(o[2], o[3]);
;                         *(u32x2*)(act + (size_t)r * 2816 + colj + 4 * n) = w;
;                     }
.LBB0_90:
	v_mov_b32_e32 v134, v1
	v_mov_b32_e32 v136, v1
	v_mov_b32_e32 v135, v1
	v_mov_b32_e32 v137, v1
	v_mov_b32_e32 v116, v1
	v_mov_b32_e32 v120, v1
	v_mov_b32_e32 v119, v1
	v_mov_b32_e32 v133, v1
	v_mov_b32_e32 v140, v1
	v_mov_b32_e32 v142, v1
	v_mov_b32_e32 v141, v1
	v_mov_b32_e32 v143, v1
	v_mov_b32_e32 v117, v1
	v_mov_b32_e32 v121, v1
	v_mov_b32_e32 v118, v1
	v_mov_b32_e32 v132, v1
	v_mov_b32_dpp v134, v70 row_ror:1 row_mask:0xf bank_mask:0xf
	v_mov_b32_dpp v136, v70 row_ror:2 row_mask:0xf bank_mask:0xf
	v_mov_b32_dpp v135, v71 row_ror:1 row_mask:0xf bank_mask:0xf
	v_mov_b32_dpp v137, v71 row_ror:2 row_mask:0xf bank_mask:0xf
	v_mov_b32_dpp v116, v72 row_ror:1 row_mask:0xf bank_mask:0xf
	v_mov_b32_dpp v120, v72 row_ror:2 row_mask:0xf bank_mask:0xf
	v_mov_b32_dpp v119, v73 row_ror:1 row_mask:0xf bank_mask:0xf
	v_mov_b32_dpp v133, v73 row_ror:2 row_mask:0xf bank_mask:0xf
	v_mov_b32_dpp v140, v66 row_ror:1 row_mask:0xf bank_mask:0xf
	v_mov_b32_dpp v142, v66 row_ror:2 row_mask:0xf bank_mask:0xf
	v_mov_b32_dpp v141, v67 row_ror:1 row_mask:0xf bank_mask:0xf
	v_mov_b32_dpp v143, v67 row_ror:2 row_mask:0xf bank_mask:0xf
	v_mov_b32_dpp v117, v68 row_ror:1 row_mask:0xf bank_mask:0xf
	v_mov_b32_dpp v121, v68 row_ror:2 row_mask:0xf bank_mask:0xf
	v_mov_b32_dpp v118, v69 row_ror:1 row_mask:0xf bank_mask:0xf
	v_mov_b32_dpp v132, v69 row_ror:2 row_mask:0xf bank_mask:0xf
	s_and_saveexec_b64 s[14:15], s[36:37]
	s_xor_b64 s[14:15], exec, s[14:15]
	s_cbranch_execz .LBB0_92
	s_waitcnt lgkmcnt(0)
	v_cndmask_b32_e64 v102, v98, v102, s[8:9]
	v_cndmask_b32_e64 v103, v99, v103, s[8:9]
	v_cndmask_b32_e64 v103, v137, v103, s[10:11]
	v_cndmask_b32_e64 v102, v136, v102, s[10:11]
	s_waitcnt vmcnt(0)
	v_pk_mul_f32 v[102:103], v[74:75], v[102:103]
	v_cndmask_b32_e64 v99, v135, v99, s[8:9]
	v_cndmask_b32_e64 v98, v134, v98, s[8:9]
	v_pk_fma_f32 v[98:99], v[82:83], v[98:99], v[102:103]
	v_cndmask_b32_e64 v111, v107, v111, s[8:9]
	v_pk_fma_f32 v[98:99], v[70:71], v[90:91], v[98:99]
	v_cndmask_b32_e64 v110, v106, v110, s[8:9]
	v_mul_f32_e32 v102, 0xbfb8aa3b, v98
	v_mul_f32_e32 v103, 0xbfb8aa3b, v99
	v_exp_f32_e32 v102, v102
	v_exp_f32_e32 v103, v103
	v_cndmask_b32_e64 v110, v142, v110, s[10:11]
	v_cndmask_b32_e64 v111, v143, v111, s[10:11]
	v_add_f32_e32 v102, 1.0, v102
	v_add_f32_e32 v103, 1.0, v103
	v_rcp_f32_e32 v102, v102
	v_rcp_f32_e32 v103, v103
	v_pk_mul_f32 v[110:111], v[78:79], v[110:111]
	v_cndmask_b32_e64 v106, v140, v106, s[8:9]
	v_cndmask_b32_e64 v107, v141, v107, s[8:9]
	v_pk_mul_f32 v[98:99], v[98:99], v[102:103]
	v_cndmask_b32_e64 v102, v100, v104, s[8:9]
	v_cndmask_b32_e64 v103, v101, v105, s[8:9]
	v_cndmask_b32_e64 v103, v133, v103, s[10:11]
	v_cndmask_b32_e64 v102, v120, v102, s[10:11]
	v_pk_mul_f32 v[102:103], v[76:77], v[102:103]
	v_cndmask_b32_e64 v101, v119, v101, s[8:9]
	v_cndmask_b32_e64 v100, v116, v100, s[8:9]
	v_pk_fma_f32 v[100:101], v[84:85], v[100:101], v[102:103]
	v_cndmask_b32_e64 v103, v109, v113, s[8:9]
	v_cndmask_b32_e64 v102, v108, v112, s[8:9]
	v_cndmask_b32_e64 v102, v121, v102, s[10:11]
	v_cndmask_b32_e64 v103, v132, v103, s[10:11]
	v_pk_fma_f32 v[100:101], v[72:73], v[92:93], v[100:101]
	v_pk_mul_f32 v[102:103], v[80:81], v[102:103]
	v_cndmask_b32_e64 v104, v117, v108, s[8:9]
	v_cndmask_b32_e64 v105, v118, v109, s[8:9]
	v_pk_fma_f32 v[102:103], v[88:89], v[104:105], v[102:103]
	v_mul_f32_e32 v104, 0xbfb8aa3b, v100
	v_mul_f32_e32 v105, 0xbfb8aa3b, v101
	v_exp_f32_e32 v104, v104
	v_exp_f32_e32 v105, v105
	v_pk_fma_f32 v[106:107], v[86:87], v[106:107], v[110:111]
	v_pk_fma_f32 v[102:103], v[68:69], v[96:97], v[102:103]
	v_add_f32_e32 v104, 1.0, v104
	v_add_f32_e32 v105, 1.0, v105
	v_rcp_f32_e32 v104, v104
	v_rcp_f32_e32 v105, v105
	v_pk_fma_f32 v[106:107], v[66:67], v[94:95], v[106:107]
	v_pk_mul_f32 v[100:101], v[100:101], v[104:105]
	v_pk_mul_f32 v[98:99], v[98:99], v[106:107]
	v_pk_mul_f32 v[100:101], v[100:101], v[102:103]
	v_cvt_pk_bf16_f32 v98, v98, v99
	v_cvt_pk_bf16_f32 v99, v100, v101
	v_mov_b64_e32 v[100:101], s[30:31]
	v_mad_i64_i32 v[100:101], s[36:37], v208, s1, v[100:101]
	v_lshl_add_u64 v[100:101], v[190:191], 1, v[100:101]
	global_store_dwordx2 v[100:101], v[98:99], off offset:8
.LBB0_92:
	s_andn2_saveexec_b64 s[14:15], s[14:15]
	s_cbranch_execz .LBB0_94
	global_store_dwordx4 v[154:155], v[70:73], off offset:16
	global_store_dwordx4 v[154:155], v[66:69], off offset:528
; __device__ __forceinline__ unsigned cvt_pk_bf16(float lo, float hi) { f32x2_t_ v = {lo, hi}; bf16x2_t_ b = __builtin_convertvector(v, bf16x2_t_); return __builtin_bit_cast(unsigned, b); }
; __device__ __forceinline__ float dpp_ror1(float v) { return __builtin_bit_cast(float, __builtin_amdgcn_update_dpp(0, __builtin_bit_cast(int, v), 0x121, 0xf, 0xf, false)); }
; __device__ __forceinline__ float dpp_ror2(float v) { return __builtin_bit_cast(float, __builtin_amdgcn_update_dpp(0, __builtin_bit_cast(int, v), 0x122, 0xf, 0xf, false)); }
;     __device__ __forceinline__ void operator()(const f32x4 (&acc)[2][2][4][2], const Unit& u, int wr, int wc, int fr, int fq) const {
;     ...
;                 for (int m = 0; m < 4; ++m) {
;                     float cv[2][4];
; #pragma unroll
;                     for (int bj = 0; bj < 2; ++bj)
; #pragma unroll
;                         for (int e = 0; e < 4; ++e) {
;                             const float x = acc[ai][bj][m][n][e];
;                             const float r1s = dpp_ror1(x), r2s = dpp_ror2(x);
;                             float r1p, r2p;
;                             if (m > 0) { const float xp = acc[ai][bj][m > 0 ? m - 1 : 0][n][e]; r1p = dpp_ror1(xp); r2p = dpp_ror2(xp); }
;                             else { r1p = h1[bj][e]; r2p = (fr == 0) ? h2[bj][e] : h1[bj][e]; }
;                             const float p1 = (fr == 0) ? r1p : r1s, p2 = (fr < 2) ? r2p : r2s;
;                             cv[bj][e] = wgt[0][bj][e] * p2 + wgt[1][bj][e] * p1 + wgt[2][bj][e] * x;
;                         }
;                     const int r = u.pm * BM + ai * HALF + wr * 64 + m * 16 + fr;
;                     if (top && m == 0 && fr < 2) {
; #pragma unroll
;                         for (int bj = 0; bj < 2; ++bj) *(f32x4*)(hb + fr * 256 + bj * 128 + 4 * n) = acc[0][bj][0][n];
;                     } else {
;                         float o[4];
; #pragma unroll
;                         for (int c = 0; c < 4; ++c) { const float g = cv[0][c]; o[c] = g * __builtin_amdgcn_rcpf(1.0f + __expf(-g)) * cv[1][c]; }
;                         u32x2 w; w.x = cvt_pk_bf16(o[0], o[1]); w.y = cvt_pk_bf16(o[2], o[3]);
;                         *(u32x2*)(act + (size_t)r * 2816 + colj + 4 * n) = w;
.LBB0_94:
	s_or_b64 exec, exec, s[14:15]
	s_waitcnt lgkmcnt(0)
	v_mov_b32_e32 v99, v1
	v_mov_b32_e32 v100, v1
	v_mov_b32_e32 v101, v1
	v_mov_b32_e32 v102, v1
	v_mov_b32_e32 v104, v1
	v_mov_b32_e32 v98, v1
	v_mov_b32_dpp v99, v62 row_ror:2 row_mask:0xf bank_mask:0xf
	v_mov_b32_dpp v100, v70 row_ror:1 row_mask:0xf bank_mask:0xf
	v_mov_b32_dpp v101, v70 row_ror:2 row_mask:0xf bank_mask:0xf
	v_mov_b32_e32 v70, v1
	v_mov_b32_dpp v102, v63 row_ror:2 row_mask:0xf bank_mask:0xf
	v_mov_b32_e32 v103, v1
	v_mov_b32_dpp v104, v71 row_ror:2 row_mask:0xf bank_mask:0xf
	v_mov_b32_e32 v132, v1
	v_mov_b32_e32 v133, v1
	v_mov_b32_e32 v136, v1
	v_mov_b32_e32 v137, v1
	v_mov_b32_dpp v98, v62 row_ror:1 row_mask:0xf bank_mask:0xf
	v_mov_b32_dpp v70, v63 row_ror:1 row_mask:0xf bank_mask:0xf
	v_mov_b32_dpp v103, v71 row_ror:1 row_mask:0xf bank_mask:0xf
	v_mov_b32_e32 v109, v1
	v_mov_b32_e32 v110, v1
	v_mov_b32_e32 v111, v1
	v_mov_b32_e32 v112, v1
	v_mov_b32_e32 v113, v1
	v_mov_b32_e32 v117, v1
	v_mov_b32_e32 v118, v1
	v_mov_b32_e32 v119, v1
	v_mov_b32_dpp v132, v68 row_ror:1 row_mask:0xf bank_mask:0xf
	v_mov_b32_dpp v133, v68 row_ror:2 row_mask:0xf bank_mask:0xf
	v_mov_b32_dpp v136, v69 row_ror:1 row_mask:0xf bank_mask:0xf
	v_mov_b32_dpp v137, v69 row_ror:2 row_mask:0xf bank_mask:0xf
	v_cndmask_b32_e64 v69, v102, v104, s[10:11]
	v_cndmask_b32_e64 v68, v99, v101, s[10:11]
	v_mov_b32_dpp v109, v73 row_ror:1 row_mask:0xf bank_mask:0xf
	v_mov_b32_dpp v110, v73 row_ror:2 row_mask:0xf bank_mask:0xf
	v_mov_b32_e32 v73, v1
	v_mov_b32_dpp v111, v58 row_ror:2 row_mask:0xf bank_mask:0xf
	v_mov_b32_dpp v112, v66 row_ror:1 row_mask:0xf bank_mask:0xf
	v_mov_b32_dpp v113, v66 row_ror:2 row_mask:0xf bank_mask:0xf
	v_mov_b32_e32 v116, v1
	v_mov_b32_dpp v117, v59 row_ror:2 row_mask:0xf bank_mask:0xf
	v_mov_b32_dpp v118, v67 row_ror:1 row_mask:0xf bank_mask:0xf
	v_mov_b32_dpp v119, v67 row_ror:2 row_mask:0xf bank_mask:0xf
	v_cndmask_b32_e64 v67, v70, v103, s[8:9]
	v_cndmask_b32_e64 v66, v98, v100, s[8:9]
	s_waitcnt vmcnt(0)
	v_pk_mul_f32 v[68:69], v[74:75], v[68:69]
	v_mov_b32_dpp v73, v58 row_ror:1 row_mask:0xf bank_mask:0xf
	v_mov_b32_dpp v116, v59 row_ror:1 row_mask:0xf bank_mask:0xf
	v_pk_fma_f32 v[66:67], v[82:83], v[66:67], v[68:69]
	v_cndmask_b32_e64 v69, v117, v119, s[10:11]
	v_cndmask_b32_e64 v68, v111, v113, s[10:11]
	v_pk_fma_f32 v[62:63], v[62:63], v[90:91], v[66:67]
	v_cndmask_b32_e64 v67, v116, v118, s[8:9]
	v_cndmask_b32_e64 v66, v73, v112, s[8:9]
	v_pk_mul_f32 v[68:69], v[78:79], v[68:69]
	v_mov_b32_e32 v105, v1
	v_pk_fma_f32 v[66:67], v[86:87], v[66:67], v[68:69]
	v_mov_b32_e32 v106, v1
	v_pk_fma_f32 v[58:59], v[58:59], v[94:95], v[66:67]
	v_mul_f32_e32 v66, 0xbfb8aa3b, v62
	v_mul_f32_e32 v67, 0xbfb8aa3b, v63
	v_exp_f32_e32 v66, v66
	v_exp_f32_e32 v67, v67
	v_mov_b32_e32 v107, v1
	v_mov_b32_e32 v108, v1
	v_add_f32_e32 v66, 1.0, v66
	v_add_f32_e32 v67, 1.0, v67
	v_rcp_f32_e32 v66, v66
	v_rcp_f32_e32 v67, v67
	v_mov_b32_e32 v71, v1
	v_mov_b32_dpp v105, v64 row_ror:2 row_mask:0xf bank_mask:0xf
	v_mov_b32_dpp v106, v72 row_ror:1 row_mask:0xf bank_mask:0xf
	v_mov_b32_dpp v107, v72 row_ror:2 row_mask:0xf bank_mask:0xf
	v_mov_b32_e32 v72, v1
	v_mov_b32_dpp v108, v65 row_ror:2 row_mask:0xf bank_mask:0xf
	v_mov_b32_dpp v71, v64 row_ror:1 row_mask:0xf bank_mask:0xf
	v_mov_b32_dpp v72, v65 row_ror:1 row_mask:0xf bank_mask:0xf
	v_pk_mul_f32 v[62:63], v[62:63], v[66:67]
	v_cndmask_b32_e64 v67, v108, v110, s[10:11]
	v_cndmask_b32_e64 v66, v105, v107, s[10:11]
	v_mov_b32_e32 v121, v1
	v_mov_b32_e32 v135, v1
	v_pk_mul_f32 v[58:59], v[62:63], v[58:59]
	v_cndmask_b32_e64 v63, v72, v109, s[8:9]
	v_cndmask_b32_e64 v62, v71, v106, s[8:9]
	v_pk_mul_f32 v[66:67], v[76:77], v[66:67]
	v_mov_b32_e32 v120, v1
	v_mov_b32_dpp v121, v60 row_ror:2 row_mask:0xf bank_mask:0xf
	v_mov_b32_e32 v134, v1
	v_mov_b32_dpp v135, v61 row_ror:2 row_mask:0xf bank_mask:0xf
	v_pk_fma_f32 v[62:63], v[84:85], v[62:63], v[66:67]
	v_mov_b32_dpp v120, v60 row_ror:1 row_mask:0xf bank_mask:0xf
	v_mov_b32_dpp v134, v61 row_ror:1 row_mask:0xf bank_mask:0xf
	v_pk_fma_f32 v[62:63], v[64:65], v[92:93], v[62:63]
	v_cndmask_b32_e64 v65, v135, v137, s[10:11]
	v_cndmask_b32_e64 v64, v121, v133, s[10:11]
	v_pk_mul_f32 v[64:65], v[80:81], v[64:65]
	v_cndmask_b32_e64 v67, v134, v136, s[8:9]
	v_cndmask_b32_e64 v66, v120, v132, s[8:9]
	v_pk_fma_f32 v[64:65], v[88:89], v[66:67], v[64:65]
	v_cvt_pk_bf16_f32 v58, v58, v59
	v_pk_fma_f32 v[60:61], v[60:61], v[96:97], v[64:65]
	v_mul_f32_e32 v64, 0xbfb8aa3b, v62
	v_mul_f32_e32 v65, 0xbfb8aa3b, v63
	v_exp_f32_e32 v64, v64
	v_exp_f32_e32 v65, v65
	v_mov_b32_e32 v101, v1
	v_mov_b32_e32 v104, v1
	v_add_f32_e32 v64, 1.0, v64
	v_add_f32_e32 v65, 1.0, v65
	v_rcp_f32_e32 v64, v64
	v_rcp_f32_e32 v65, v65
	v_mov_b32_e32 v100, v1
	v_mov_b32_dpp v101, v50 row_ror:2 row_mask:0xf bank_mask:0xf
	v_mov_b32_e32 v103, v1
	v_pk_mul_f32 v[62:63], v[62:63], v[64:65]
	v_mov_b32_e32 v65, v1
	v_pk_mul_f32 v[60:61], v[62:63], v[60:61]
	v_mov_b32_e32 v63, v1
	v_mov_b32_e32 v62, v1
	v_mov_b32_e32 v64, v1
	v_mov_b32_dpp v63, v54 row_ror:2 row_mask:0xf bank_mask:0xf
	v_mov_b32_dpp v65, v55 row_ror:2 row_mask:0xf bank_mask:0xf
	v_cvt_pk_bf16_f32 v59, v60, v61
	v_mov_b32_dpp v62, v54 row_ror:1 row_mask:0xf bank_mask:0xf
	v_mov_b32_dpp v64, v55 row_ror:1 row_mask:0xf bank_mask:0xf
	v_cndmask_b32_e64 v61, v65, v102, s[10:11]
	v_cndmask_b32_e64 v60, v63, v99, s[10:11]
	global_store_dwordx2 v[138:139], v[58:59], off offset:8
	v_mov_b32_dpp v104, v51 row_ror:2 row_mask:0xf bank_mask:0xf
	v_cndmask_b32_e64 v59, v64, v70, s[8:9]
	v_cndmask_b32_e64 v58, v62, v98, s[8:9]
	v_pk_mul_f32 v[60:61], v[74:75], v[60:61]
;     __device__ __forceinline__ void operator()(const f32x4 (&acc)[2][2][4][2], const Unit& u, int wr, int wc, int fr, int fq) const {
;     ...
;             for (int ai = 0; ai < 2; ++ai) {
;                 const bool top = (wr == 0 && ai == 0);
;                 f32x4 h1[2], h2[2];
;                 const float* sx = xch + (wr == 1 ? wc : 4 + wc) * 256 + (wr == 1 ? ai * 2 : 0) * 64 + fq * 8 + n * 4;
; #pragma unroll
;                 for (int bj = 0; bj < 2; ++bj) {
;                     if (!top) { h2[bj] = *(const f32x4*)(sx + bj * 32); h1[bj] = *(const f32x4*)(sx + 64 + bj * 32); }
;                     else { h2[bj] = (f32x4){0.f, 0.f, 0.f, 0.f}; h1[bj] = (f32x4){0.f, 0.f, 0.f, 0.f}; }
;                 }
;     ...
;                 for (int m = 0; m < 4; ++m) {
;                     float cv[2][4];
; #pragma unroll
;                     for (int bj = 0; bj < 2; ++bj)
; #pragma unroll
;                         for (int e = 0; e < 4; ++e) {
;                             const float x = acc[ai][bj][m][n][e];
;                             const float r1s = dpp_ror1(x), r2s = dpp_ror2(x);
;                             float r1p, r2p;
;                             if (m > 0) { const float xp = acc[ai][bj][m > 0 ? m - 1 : 0][n][e]; r1p = dpp_ror1(xp); r2p = dpp_ror2(xp); }
;                             else { r1p = h1[bj][e]; r2p = (fr == 0) ? h2[bj][e] : h1[bj][e]; }
;                             const float p1 = (fr == 0) ? r1p : r1s, p2 = (fr < 2) ? r2p : r2s;
;                             cv[bj][e] = wgt[0][bj][e] * p2 + wgt[1][bj][e] * p1 + wgt[2][bj][e] * x;
;                         }
;                     const int r = u.pm * BM + ai * HALF + wr * 64 + m * 16 + fr;
;                     if (top && m == 0 && fr < 2) {
; #pragma unroll
;                         for (int bj = 0; bj < 2; ++bj) *(f32x4*)(hb + fr * 256 + bj * 128 + 4 * n) = acc[0][bj][0][n];
;                     } else {
;                         float o[4];
; #pragma unroll
;                         for (int c = 0; c < 4; ++c) { const float g = cv[0][c]; o[c] = g * __builtin_amdgcn_rcpf(1.0f + __expf(-g)) * cv[1][c]; }
;                         u32x2 w; w.x = cvt_pk_bf16(o[0], o[1]); w.y = cvt_pk_bf16(o[2], o[3]);
;                         *(u32x2*)(act + (size_t)r * 2816 + colj + 4 * n) = w;
	v_mov_b32_dpp v100, v50 row_ror:1 row_mask:0xf bank_mask:0xf
	v_mov_b32_dpp v103, v51 row_ror:1 row_mask:0xf bank_mask:0xf
	v_pk_fma_f32 v[58:59], v[82:83], v[58:59], v[60:61]
	v_cndmask_b32_e64 v61, v104, v117, s[10:11]
	v_cndmask_b32_e64 v60, v101, v111, s[10:11]
	v_pk_fma_f32 v[54:55], v[54:55], v[90:91], v[58:59]
	v_cndmask_b32_e64 v59, v103, v116, s[8:9]
	v_cndmask_b32_e64 v58, v100, v73, s[8:9]
	v_pk_mul_f32 v[60:61], v[78:79], v[60:61]
	v_mov_b32_e32 v67, v1
	v_pk_fma_f32 v[58:59], v[86:87], v[58:59], v[60:61]
	v_mov_b32_e32 v69, v1
	v_pk_fma_f32 v[50:51], v[50:51], v[94:95], v[58:59]
	v_mul_f32_e32 v58, 0xbfb8aa3b, v54
	v_mul_f32_e32 v59, 0xbfb8aa3b, v55
	v_exp_f32_e32 v58, v58
	v_exp_f32_e32 v59, v59
	v_mov_b32_e32 v66, v1
	v_mov_b32_dpp v67, v56 row_ror:2 row_mask:0xf bank_mask:0xf
	v_add_f32_e32 v58, 1.0, v58
	v_add_f32_e32 v59, 1.0, v59
	v_rcp_f32_e32 v58, v58
	v_rcp_f32_e32 v59, v59
	v_mov_b32_e32 v68, v1
	v_mov_b32_dpp v69, v57 row_ror:2 row_mask:0xf bank_mask:0xf
	v_mov_b32_dpp v66, v56 row_ror:1 row_mask:0xf bank_mask:0xf
	v_mov_b32_dpp v68, v57 row_ror:1 row_mask:0xf bank_mask:0xf
	v_pk_mul_f32 v[54:55], v[54:55], v[58:59]
	v_cndmask_b32_e64 v59, v69, v108, s[10:11]
	v_cndmask_b32_e64 v58, v67, v105, s[10:11]
	v_mov_b32_e32 v107, v1
	v_mov_b32_e32 v110, v1
	v_pk_mul_f32 v[50:51], v[54:55], v[50:51]
	v_cndmask_b32_e64 v55, v68, v72, s[8:9]
	v_cndmask_b32_e64 v54, v66, v71, s[8:9]
	v_pk_mul_f32 v[58:59], v[76:77], v[58:59]
	v_mov_b32_e32 v106, v1
	v_mov_b32_dpp v107, v52 row_ror:2 row_mask:0xf bank_mask:0xf
	v_mov_b32_e32 v109, v1
	v_mov_b32_dpp v110, v53 row_ror:2 row_mask:0xf bank_mask:0xf
	v_pk_fma_f32 v[54:55], v[84:85], v[54:55], v[58:59]
	v_mov_b32_dpp v106, v52 row_ror:1 row_mask:0xf bank_mask:0xf
	v_mov_b32_dpp v109, v53 row_ror:1 row_mask:0xf bank_mask:0xf
	v_pk_fma_f32 v[54:55], v[56:57], v[92:93], v[54:55]
	v_cndmask_b32_e64 v57, v110, v135, s[10:11]
	v_cndmask_b32_e64 v56, v107, v121, s[10:11]
	v_pk_mul_f32 v[56:57], v[80:81], v[56:57]
	v_cndmask_b32_e64 v59, v109, v134, s[8:9]
	v_cndmask_b32_e64 v58, v106, v120, s[8:9]
	v_pk_fma_f32 v[56:57], v[88:89], v[58:59], v[56:57]
	v_cvt_pk_bf16_f32 v50, v50, v51
	v_pk_fma_f32 v[52:53], v[52:53], v[96:97], v[56:57]
	v_mul_f32_e32 v56, 0xbfb8aa3b, v54
	v_mul_f32_e32 v57, 0xbfb8aa3b, v55
	v_exp_f32_e32 v56, v56
	v_exp_f32_e32 v57, v57
	v_mov_b32_e32 v59, v1
	v_mov_b32_e32 v61, v1
	v_add_f32_e32 v56, 1.0, v56
	v_add_f32_e32 v57, 1.0, v57
	v_rcp_f32_e32 v56, v56
	v_rcp_f32_e32 v57, v57
	v_mov_b32_e32 v58, v1
	v_mov_b32_dpp v59, v42 row_ror:2 row_mask:0xf bank_mask:0xf
	v_mov_b32_e32 v60, v1
	v_pk_mul_f32 v[54:55], v[54:55], v[56:57]
	v_mov_b32_dpp v61, v43 row_ror:2 row_mask:0xf bank_mask:0xf
	v_pk_mul_f32 v[52:53], v[54:55], v[52:53]
	v_mov_b32_dpp v58, v42 row_ror:1 row_mask:0xf bank_mask:0xf
	v_cvt_pk_bf16_f32 v51, v52, v53
	v_mov_b32_e32 v52, v1
	v_mov_b32_e32 v53, v1
	global_store_dwordx2 v[130:131], v[50:51], off offset:8
	v_mov_b32_e32 v50, v1
	v_mov_b32_dpp v52, v46 row_ror:2 row_mask:0xf bank_mask:0xf
	v_mov_b32_e32 v51, v1
	v_mov_b32_dpp v53, v47 row_ror:2 row_mask:0xf bank_mask:0xf
	v_mov_b32_dpp v50, v46 row_ror:1 row_mask:0xf bank_mask:0xf
	v_mov_b32_dpp v51, v47 row_ror:1 row_mask:0xf bank_mask:0xf
	v_cndmask_b32_e64 v53, v53, v65, s[10:11]
	v_cndmask_b32_e64 v52, v52, v63, s[10:11]
	v_cndmask_b32_e64 v51, v51, v64, s[8:9]
	v_cndmask_b32_e64 v50, v50, v62, s[8:9]
	v_pk_mul_f32 v[52:53], v[74:75], v[52:53]
	v_mov_b32_dpp v60, v43 row_ror:1 row_mask:0xf bank_mask:0xf
	v_pk_fma_f32 v[50:51], v[82:83], v[50:51], v[52:53]
	v_cndmask_b32_e64 v53, v61, v104, s[10:11]
	v_cndmask_b32_e64 v52, v59, v101, s[10:11]
	v_pk_fma_f32 v[46:47], v[46:47], v[90:91], v[50:51]
	v_cndmask_b32_e64 v51, v60, v103, s[8:9]
	v_cndmask_b32_e64 v50, v58, v100, s[8:9]
	v_pk_mul_f32 v[52:53], v[78:79], v[52:53]
	v_mov_b32_e32 v55, v1
	v_pk_fma_f32 v[50:51], v[86:87], v[50:51], v[52:53]
	v_mov_b32_e32 v57, v1
	v_pk_fma_f32 v[42:43], v[42:43], v[94:95], v[50:51]
	v_mul_f32_e32 v50, 0xbfb8aa3b, v46
	v_mul_f32_e32 v51, 0xbfb8aa3b, v47
	v_exp_f32_e32 v50, v50
	v_exp_f32_e32 v51, v51
	v_mov_b32_e32 v54, v1
	v_mov_b32_dpp v55, v48 row_ror:2 row_mask:0xf bank_mask:0xf
	v_add_f32_e32 v50, 1.0, v50
	v_add_f32_e32 v51, 1.0, v51
	v_rcp_f32_e32 v50, v50
	v_rcp_f32_e32 v51, v51
	v_mov_b32_e32 v56, v1
	v_mov_b32_dpp v57, v49 row_ror:2 row_mask:0xf bank_mask:0xf
	v_mov_b32_dpp v54, v48 row_ror:1 row_mask:0xf bank_mask:0xf
	v_mov_b32_dpp v56, v49 row_ror:1 row_mask:0xf bank_mask:0xf
	v_pk_mul_f32 v[46:47], v[46:47], v[50:51]
	v_cndmask_b32_e64 v51, v57, v69, s[10:11]
	v_cndmask_b32_e64 v50, v55, v67, s[10:11]
	v_mov_b32_e32 v71, v1
	v_mov_b32_e32 v73, v1
	v_pk_mul_f32 v[42:43], v[46:47], v[42:43]
	v_cndmask_b32_e64 v47, v56, v68, s[8:9]
	v_cndmask_b32_e64 v46, v54, v66, s[8:9]
	v_pk_mul_f32 v[50:51], v[76:77], v[50:51]
	v_mov_b32_e32 v70, v1
	v_mov_b32_dpp v71, v44 row_ror:2 row_mask:0xf bank_mask:0xf
	v_mov_b32_e32 v72, v1
	v_mov_b32_dpp v73, v45 row_ror:2 row_mask:0xf bank_mask:0xf
	v_pk_fma_f32 v[46:47], v[84:85], v[46:47], v[50:51]
	v_mov_b32_dpp v70, v44 row_ror:1 row_mask:0xf bank_mask:0xf
	v_mov_b32_dpp v72, v45 row_ror:1 row_mask:0xf bank_mask:0xf
	v_pk_fma_f32 v[46:47], v[48:49], v[92:93], v[46:47]
	v_cndmask_b32_e64 v49, v73, v110, s[10:11]
	v_cndmask_b32_e64 v48, v71, v107, s[10:11]
	v_pk_mul_f32 v[48:49], v[80:81], v[48:49]
	v_cndmask_b32_e64 v51, v72, v109, s[8:9]
	v_cndmask_b32_e64 v50, v70, v106, s[8:9]
	v_pk_fma_f32 v[48:49], v[88:89], v[50:51], v[48:49]
	v_cvt_pk_bf16_f32 v42, v42, v43
	v_pk_fma_f32 v[44:45], v[44:45], v[96:97], v[48:49]
	v_mul_f32_e32 v48, 0xbfb8aa3b, v46
	v_mul_f32_e32 v49, 0xbfb8aa3b, v47
	v_exp_f32_e32 v48, v48
	v_exp_f32_e32 v49, v49
	v_mov_b32_e32 v58, v1
	v_mov_b32_e32 v59, v1
	v_add_f32_e32 v48, 1.0, v48
	v_add_f32_e32 v49, 1.0, v49
	v_rcp_f32_e32 v48, v48
	v_rcp_f32_e32 v49, v49
	v_mov_b32_e32 v60, v1
	v_mov_b32_e32 v61, v1
	v_mov_b32_dpp v58, v38 row_ror:1 row_mask:0xf bank_mask:0xf
	v_pk_mul_f32 v[46:47], v[46:47], v[48:49]
	v_mov_b32_dpp v59, v38 row_ror:2 row_mask:0xf bank_mask:0xf
	v_pk_mul_f32 v[44:45], v[46:47], v[44:45]
	v_mov_b32_dpp v60, v39 row_ror:1 row_mask:0xf bank_mask:0xf
	v_cvt_pk_bf16_f32 v43, v44, v45
	global_store_dwordx2 v[122:123], v[42:43], off offset:8
	ds_read_b128 v[42:45], v205 offset:16
	ds_read_b128 v[46:49], v205 offset:272
	ds_read_b128 v[50:53], v205 offset:144
	ds_read_b128 v[54:57], v205 offset:400
	v_mov_b32_dpp v61, v39 row_ror:2 row_mask:0xf bank_mask:0xf
	v_mov_b32_e32 v67, v1
	s_waitcnt lgkmcnt(0)
; __device__ __forceinline__ unsigned cvt_pk_bf16(float lo, float hi) { f32x2_t_ v = {lo, hi}; bf16x2_t_ b = __builtin_convertvector(v, bf16x2_t_); return __builtin_bit_cast(unsigned, b); }
; __device__ __forceinline__ float dpp_ror1(float v) { return __builtin_bit_cast(float, __builtin_amdgcn_update_dpp(0, __builtin_bit_cast(int, v), 0x121, 0xf, 0xf, false)); }
; __device__ __forceinline__ float dpp_ror2(float v) { return __builtin_bit_cast(float, __builtin_amdgcn_update_dpp(0, __builtin_bit_cast(int, v), 0x122, 0xf, 0xf, false)); }
;     __device__ __forceinline__ void operator()(const f32x4 (&acc)[2][2][4][2], const Unit& u, int wr, int wc, int fr, int fq) const {
;     ...
;                 for (int m = 0; m < 4; ++m) {
;                     float cv[2][4];
; #pragma unroll
;                     for (int bj = 0; bj < 2; ++bj)
; #pragma unroll
;                         for (int e = 0; e < 4; ++e) {
;                             const float x = acc[ai][bj][m][n][e];
;                             const float r1s = dpp_ror1(x), r2s = dpp_ror2(x);
;                             float r1p, r2p;
;                             if (m > 0) { const float xp = acc[ai][bj][m > 0 ? m - 1 : 0][n][e]; r1p = dpp_ror1(xp); r2p = dpp_ror2(xp); }
;                             else { r1p = h1[bj][e]; r2p = (fr == 0) ? h2[bj][e] : h1[bj][e]; }
;                             const float p1 = (fr == 0) ? r1p : r1s, p2 = (fr < 2) ? r2p : r2s;
;                             cv[bj][e] = wgt[0][bj][e] * p2 + wgt[1][bj][e] * p1 + wgt[2][bj][e] * x;
;                         }
;                     const int r = u.pm * BM + ai * HALF + wr * 64 + m * 16 + fr;
;                     if (top && m == 0 && fr < 2) {
; #pragma unroll
;                         for (int bj = 0; bj < 2; ++bj) *(f32x4*)(hb + fr * 256 + bj * 128 + 4 * n) = acc[0][bj][0][n];
;                     } else {
;                         float o[4];
; #pragma unroll
;                         for (int c = 0; c < 4; ++c) { const float g = cv[0][c]; o[c] = g * __builtin_amdgcn_rcpf(1.0f + __expf(-g)) * cv[1][c]; }
;                         u32x2 w; w.x = cvt_pk_bf16(o[0], o[1]); w.y = cvt_pk_bf16(o[2], o[3]);
;                         *(u32x2*)(act + (size_t)r * 2816 + colj + 4 * n) = w;
	v_cndmask_b32_e64 v98, v46, v42, s[8:9]
	v_cndmask_b32_e64 v99, v47, v43, s[8:9]
	v_cndmask_b32_e64 v43, v60, v47, s[8:9]
	v_cndmask_b32_e64 v42, v58, v46, s[8:9]
	v_cndmask_b32_e64 v47, v61, v99, s[10:11]
	v_cndmask_b32_e64 v46, v59, v98, s[10:11]
	v_mov_b32_e32 v69, v1
	v_pk_mul_f32 v[46:47], v[74:75], v[46:47]
	v_mov_b32_e32 v66, v1
	v_mov_b32_dpp v67, v34 row_ror:2 row_mask:0xf bank_mask:0xf
	v_mov_b32_e32 v68, v1
	v_mov_b32_dpp v69, v35 row_ror:2 row_mask:0xf bank_mask:0xf
	v_pk_fma_f32 v[42:43], v[82:83], v[42:43], v[46:47]
	v_cndmask_b32_e64 v46, v54, v50, s[8:9]
	v_cndmask_b32_e64 v47, v55, v51, s[8:9]
	v_mov_b32_dpp v66, v34 row_ror:1 row_mask:0xf bank_mask:0xf
	v_mov_b32_dpp v68, v35 row_ror:1 row_mask:0xf bank_mask:0xf
	v_cndmask_b32_e64 v47, v69, v47, s[10:11]
	v_cndmask_b32_e64 v46, v67, v46, s[10:11]
	v_pk_fma_f32 v[38:39], v[38:39], v[90:91], v[42:43]
	v_cndmask_b32_e64 v43, v68, v55, s[8:9]
	v_cndmask_b32_e64 v42, v66, v54, s[8:9]
	v_pk_mul_f32 v[46:47], v[78:79], v[46:47]
	v_mov_b32_e32 v63, v1
	v_pk_fma_f32 v[42:43], v[86:87], v[42:43], v[46:47]
	v_mov_b32_e32 v65, v1
	v_pk_fma_f32 v[34:35], v[34:35], v[94:95], v[42:43]
	v_mul_f32_e32 v42, 0xbfb8aa3b, v38
	v_mul_f32_e32 v43, 0xbfb8aa3b, v39
	v_exp_f32_e32 v42, v42
	v_exp_f32_e32 v43, v43
	v_mov_b32_e32 v62, v1
	v_mov_b32_dpp v63, v40 row_ror:2 row_mask:0xf bank_mask:0xf
	v_add_f32_e32 v42, 1.0, v42
	v_add_f32_e32 v43, 1.0, v43
	v_rcp_f32_e32 v42, v42
	v_rcp_f32_e32 v43, v43
	v_mov_b32_e32 v64, v1
	v_mov_b32_dpp v65, v41 row_ror:2 row_mask:0xf bank_mask:0xf
	v_mov_b32_dpp v62, v40 row_ror:1 row_mask:0xf bank_mask:0xf
	v_pk_mul_f32 v[38:39], v[38:39], v[42:43]
	v_cndmask_b32_e64 v42, v48, v44, s[8:9]
	v_cndmask_b32_e64 v43, v49, v45, s[8:9]
	v_mov_b32_dpp v64, v41 row_ror:1 row_mask:0xf bank_mask:0xf
	v_cndmask_b32_e64 v43, v65, v43, s[10:11]
	v_cndmask_b32_e64 v42, v63, v42, s[10:11]
	v_pk_mul_f32 v[34:35], v[38:39], v[34:35]
	v_cndmask_b32_e64 v39, v64, v49, s[8:9]
	v_cndmask_b32_e64 v38, v62, v48, s[8:9]
	v_pk_mul_f32 v[42:43], v[76:77], v[42:43]
	v_mov_b32_e32 v71, v1
	v_mov_b32_e32 v73, v1
	v_pk_fma_f32 v[38:39], v[84:85], v[38:39], v[42:43]
	v_mov_b32_e32 v70, v1
	v_mov_b32_dpp v71, v36 row_ror:2 row_mask:0xf bank_mask:0xf
	v_mov_b32_e32 v72, v1
	v_mov_b32_dpp v73, v37 row_ror:2 row_mask:0xf bank_mask:0xf
	v_pk_fma_f32 v[38:39], v[40:41], v[92:93], v[38:39]
	v_cndmask_b32_e64 v40, v56, v52, s[8:9]
	v_cndmask_b32_e64 v41, v57, v53, s[8:9]
	v_mov_b32_dpp v70, v36 row_ror:1 row_mask:0xf bank_mask:0xf
	v_mov_b32_dpp v72, v37 row_ror:1 row_mask:0xf bank_mask:0xf
	v_cndmask_b32_e64 v41, v73, v41, s[10:11]
	v_cndmask_b32_e64 v40, v71, v40, s[10:11]
	v_pk_mul_f32 v[40:41], v[80:81], v[40:41]
	v_cndmask_b32_e64 v43, v72, v57, s[8:9]
	v_cndmask_b32_e64 v42, v70, v56, s[8:9]
	v_pk_fma_f32 v[40:41], v[88:89], v[42:43], v[40:41]
	v_cvt_pk_bf16_f32 v34, v34, v35
	v_pk_fma_f32 v[36:37], v[36:37], v[96:97], v[40:41]
	v_mul_f32_e32 v40, 0xbfb8aa3b, v38
	v_mul_f32_e32 v41, 0xbfb8aa3b, v39
	v_exp_f32_e32 v40, v40
	v_exp_f32_e32 v41, v41
	v_mov_b32_e32 v47, v1
	v_mov_b32_e32 v49, v1
	v_add_f32_e32 v40, 1.0, v40
	v_add_f32_e32 v41, 1.0, v41
	v_rcp_f32_e32 v40, v40
	v_rcp_f32_e32 v41, v41
	v_mov_b32_e32 v46, v1
	v_mov_b32_dpp v47, v26 row_ror:2 row_mask:0xf bank_mask:0xf
	v_mov_b32_e32 v48, v1
	v_pk_mul_f32 v[38:39], v[38:39], v[40:41]
	v_mov_b32_e32 v41, v1
	v_pk_mul_f32 v[36:37], v[38:39], v[36:37]
	v_mov_b32_e32 v39, v1
	v_mov_b32_e32 v38, v1
	v_mov_b32_e32 v40, v1
	v_mov_b32_dpp v39, v30 row_ror:2 row_mask:0xf bank_mask:0xf
	v_mov_b32_dpp v41, v31 row_ror:2 row_mask:0xf bank_mask:0xf
	v_cvt_pk_bf16_f32 v35, v36, v37
	v_mov_b32_dpp v38, v30 row_ror:1 row_mask:0xf bank_mask:0xf
	v_mov_b32_dpp v40, v31 row_ror:1 row_mask:0xf bank_mask:0xf
	v_cndmask_b32_e64 v37, v41, v61, s[10:11]
	v_cndmask_b32_e64 v36, v39, v59, s[10:11]
	global_store_dwordx2 v[124:125], v[34:35], off offset:8
	v_mov_b32_dpp v49, v27 row_ror:2 row_mask:0xf bank_mask:0xf
	v_cndmask_b32_e64 v35, v40, v60, s[8:9]
	v_cndmask_b32_e64 v34, v38, v58, s[8:9]
	v_pk_mul_f32 v[36:37], v[74:75], v[36:37]
	v_mov_b32_dpp v46, v26 row_ror:1 row_mask:0xf bank_mask:0xf
	v_mov_b32_dpp v48, v27 row_ror:1 row_mask:0xf bank_mask:0xf
	v_pk_fma_f32 v[34:35], v[82:83], v[34:35], v[36:37]
	v_cndmask_b32_e64 v37, v49, v69, s[10:11]
	v_cndmask_b32_e64 v36, v47, v67, s[10:11]
	v_pk_fma_f32 v[30:31], v[30:31], v[90:91], v[34:35]
	v_cndmask_b32_e64 v35, v48, v68, s[8:9]
	v_cndmask_b32_e64 v34, v46, v66, s[8:9]
	v_pk_mul_f32 v[36:37], v[78:79], v[36:37]
	v_mov_b32_e32 v43, v1
	v_pk_fma_f32 v[34:35], v[86:87], v[34:35], v[36:37]
	v_mov_b32_e32 v45, v1
	v_pk_fma_f32 v[26:27], v[26:27], v[94:95], v[34:35]
	v_mul_f32_e32 v34, 0xbfb8aa3b, v30
	v_mul_f32_e32 v35, 0xbfb8aa3b, v31
	v_exp_f32_e32 v34, v34
	v_exp_f32_e32 v35, v35
	v_mov_b32_e32 v42, v1
	v_mov_b32_dpp v43, v32 row_ror:2 row_mask:0xf bank_mask:0xf
	v_add_f32_e32 v34, 1.0, v34
	v_add_f32_e32 v35, 1.0, v35
	v_rcp_f32_e32 v34, v34
	v_rcp_f32_e32 v35, v35
	v_mov_b32_e32 v44, v1
	v_mov_b32_dpp v45, v33 row_ror:2 row_mask:0xf bank_mask:0xf
	v_mov_b32_dpp v42, v32 row_ror:1 row_mask:0xf bank_mask:0xf
	v_mov_b32_dpp v44, v33 row_ror:1 row_mask:0xf bank_mask:0xf
	v_pk_mul_f32 v[30:31], v[30:31], v[34:35]
	v_cndmask_b32_e64 v35, v45, v65, s[10:11]
	v_cndmask_b32_e64 v34, v43, v63, s[10:11]
	v_mov_b32_e32 v51, v1
	v_mov_b32_e32 v53, v1
	v_pk_mul_f32 v[26:27], v[30:31], v[26:27]
	v_cndmask_b32_e64 v31, v44, v64, s[8:9]
	v_cndmask_b32_e64 v30, v42, v62, s[8:9]
	v_pk_mul_f32 v[34:35], v[76:77], v[34:35]
	v_mov_b32_e32 v50, v1
	v_mov_b32_dpp v51, v28 row_ror:2 row_mask:0xf bank_mask:0xf
	v_mov_b32_e32 v52, v1
; __device__ __forceinline__ unsigned cvt_pk_bf16(float lo, float hi) { f32x2_t_ v = {lo, hi}; bf16x2_t_ b = __builtin_convertvector(v, bf16x2_t_); return __builtin_bit_cast(unsigned, b); }
; __device__ __forceinline__ float dpp_ror1(float v) { return __builtin_bit_cast(float, __builtin_amdgcn_update_dpp(0, __builtin_bit_cast(int, v), 0x121, 0xf, 0xf, false)); }
; __device__ __forceinline__ float dpp_ror2(float v) { return __builtin_bit_cast(float, __builtin_amdgcn_update_dpp(0, __builtin_bit_cast(int, v), 0x122, 0xf, 0xf, false)); }
;     __device__ __forceinline__ void operator()(const f32x4 (&acc)[2][2][4][2], const Unit& u, int wr, int wc, int fr, int fq) const {
;     ...
;                 for (int m = 0; m < 4; ++m) {
;                     float cv[2][4];
; #pragma unroll
;                     for (int bj = 0; bj < 2; ++bj)
; #pragma unroll
;                         for (int e = 0; e < 4; ++e) {
;                             const float x = acc[ai][bj][m][n][e];
;                             const float r1s = dpp_ror1(x), r2s = dpp_ror2(x);
;                             float r1p, r2p;
;                             if (m > 0) { const float xp = acc[ai][bj][m > 0 ? m - 1 : 0][n][e]; r1p = dpp_ror1(xp); r2p = dpp_ror2(xp); }
;                             else { r1p = h1[bj][e]; r2p = (fr == 0) ? h2[bj][e] : h1[bj][e]; }
;                             const float p1 = (fr == 0) ? r1p : r1s, p2 = (fr < 2) ? r2p : r2s;
;                             cv[bj][e] = wgt[0][bj][e] * p2 + wgt[1][bj][e] * p1 + wgt[2][bj][e] * x;
;                         }
;                     const int r = u.pm * BM + ai * HALF + wr * 64 + m * 16 + fr;
;                     if (top && m == 0 && fr < 2) {
; #pragma unroll
;                         for (int bj = 0; bj < 2; ++bj) *(f32x4*)(hb + fr * 256 + bj * 128 + 4 * n) = acc[0][bj][0][n];
;                     } else {
;                         float o[4];
; #pragma unroll
;                         for (int c = 0; c < 4; ++c) { const float g = cv[0][c]; o[c] = g * __builtin_amdgcn_rcpf(1.0f + __expf(-g)) * cv[1][c]; }
;                         u32x2 w; w.x = cvt_pk_bf16(o[0], o[1]); w.y = cvt_pk_bf16(o[2], o[3]);
;                         *(u32x2*)(act + (size_t)r * 2816 + colj + 4 * n) = w;
	v_mov_b32_dpp v53, v29 row_ror:2 row_mask:0xf bank_mask:0xf
	v_pk_fma_f32 v[30:31], v[84:85], v[30:31], v[34:35]
	v_mov_b32_dpp v50, v28 row_ror:1 row_mask:0xf bank_mask:0xf
	v_mov_b32_dpp v52, v29 row_ror:1 row_mask:0xf bank_mask:0xf
	v_pk_fma_f32 v[30:31], v[32:33], v[92:93], v[30:31]
	v_cndmask_b32_e64 v33, v53, v73, s[10:11]
	v_cndmask_b32_e64 v32, v51, v71, s[10:11]
	v_pk_mul_f32 v[32:33], v[80:81], v[32:33]
	v_cndmask_b32_e64 v35, v52, v72, s[8:9]
	v_cndmask_b32_e64 v34, v50, v70, s[8:9]
	v_pk_fma_f32 v[32:33], v[88:89], v[34:35], v[32:33]
	v_cvt_pk_bf16_f32 v26, v26, v27
	v_pk_fma_f32 v[28:29], v[28:29], v[96:97], v[32:33]
	v_mul_f32_e32 v32, 0xbfb8aa3b, v30
	v_mul_f32_e32 v33, 0xbfb8aa3b, v31
	v_exp_f32_e32 v32, v32
	v_exp_f32_e32 v33, v33
	v_mov_b32_e32 v55, v1
	v_mov_b32_e32 v57, v1
	v_add_f32_e32 v32, 1.0, v32
	v_add_f32_e32 v33, 1.0, v33
	v_rcp_f32_e32 v32, v32
	v_rcp_f32_e32 v33, v33
	v_mov_b32_e32 v54, v1
	v_mov_b32_dpp v55, v18 row_ror:2 row_mask:0xf bank_mask:0xf
	v_mov_b32_e32 v56, v1
	v_pk_mul_f32 v[30:31], v[30:31], v[32:33]
	v_mov_b32_e32 v33, v1
	v_pk_mul_f32 v[28:29], v[30:31], v[28:29]
	v_mov_b32_e32 v31, v1
	v_mov_b32_e32 v30, v1
	v_mov_b32_e32 v32, v1
	v_mov_b32_dpp v31, v22 row_ror:2 row_mask:0xf bank_mask:0xf
	v_mov_b32_dpp v33, v23 row_ror:2 row_mask:0xf bank_mask:0xf
	v_cvt_pk_bf16_f32 v27, v28, v29
	v_mov_b32_dpp v30, v22 row_ror:1 row_mask:0xf bank_mask:0xf
	v_mov_b32_dpp v32, v23 row_ror:1 row_mask:0xf bank_mask:0xf
	v_cndmask_b32_e64 v29, v33, v41, s[10:11]
	v_cndmask_b32_e64 v28, v31, v39, s[10:11]
	global_store_dwordx2 v[126:127], v[26:27], off offset:8
	v_mov_b32_dpp v57, v19 row_ror:2 row_mask:0xf bank_mask:0xf
	v_cndmask_b32_e64 v27, v32, v40, s[8:9]
	v_cndmask_b32_e64 v26, v30, v38, s[8:9]
	v_pk_mul_f32 v[28:29], v[74:75], v[28:29]
	v_mov_b32_dpp v54, v18 row_ror:1 row_mask:0xf bank_mask:0xf
	v_mov_b32_dpp v56, v19 row_ror:1 row_mask:0xf bank_mask:0xf
	v_pk_fma_f32 v[26:27], v[82:83], v[26:27], v[28:29]
	v_cndmask_b32_e64 v29, v57, v49, s[10:11]
	v_cndmask_b32_e64 v28, v55, v47, s[10:11]
	v_pk_fma_f32 v[22:23], v[22:23], v[90:91], v[26:27]
	v_cndmask_b32_e64 v27, v56, v48, s[8:9]
	v_cndmask_b32_e64 v26, v54, v46, s[8:9]
	v_pk_mul_f32 v[28:29], v[78:79], v[28:29]
	v_mov_b32_e32 v35, v1
	v_pk_fma_f32 v[26:27], v[86:87], v[26:27], v[28:29]
	v_mov_b32_e32 v37, v1
	v_pk_fma_f32 v[18:19], v[18:19], v[94:95], v[26:27]
	v_mul_f32_e32 v26, 0xbfb8aa3b, v22
	v_mul_f32_e32 v27, 0xbfb8aa3b, v23
	v_exp_f32_e32 v26, v26
	v_exp_f32_e32 v27, v27
	v_mov_b32_e32 v34, v1
	v_mov_b32_dpp v35, v24 row_ror:2 row_mask:0xf bank_mask:0xf
	v_add_f32_e32 v26, 1.0, v26
	v_add_f32_e32 v27, 1.0, v27
	v_rcp_f32_e32 v26, v26
	v_rcp_f32_e32 v27, v27
	v_mov_b32_e32 v36, v1
	v_mov_b32_dpp v37, v25 row_ror:2 row_mask:0xf bank_mask:0xf
	v_mov_b32_dpp v34, v24 row_ror:1 row_mask:0xf bank_mask:0xf
	v_mov_b32_dpp v36, v25 row_ror:1 row_mask:0xf bank_mask:0xf
	v_pk_mul_f32 v[22:23], v[22:23], v[26:27]
	v_cndmask_b32_e64 v27, v37, v45, s[10:11]
	v_cndmask_b32_e64 v26, v35, v43, s[10:11]
	v_mov_b32_e32 v59, v1
	v_mov_b32_e32 v61, v1
	v_pk_mul_f32 v[18:19], v[22:23], v[18:19]
	v_cndmask_b32_e64 v23, v36, v44, s[8:9]
	v_cndmask_b32_e64 v22, v34, v42, s[8:9]
	v_pk_mul_f32 v[26:27], v[76:77], v[26:27]
	v_mov_b32_e32 v58, v1
	v_mov_b32_dpp v59, v20 row_ror:2 row_mask:0xf bank_mask:0xf
	v_mov_b32_e32 v60, v1
	v_mov_b32_dpp v61, v21 row_ror:2 row_mask:0xf bank_mask:0xf
	v_pk_fma_f32 v[22:23], v[84:85], v[22:23], v[26:27]
	v_mov_b32_dpp v58, v20 row_ror:1 row_mask:0xf bank_mask:0xf
	v_mov_b32_dpp v60, v21 row_ror:1 row_mask:0xf bank_mask:0xf
	v_pk_fma_f32 v[22:23], v[24:25], v[92:93], v[22:23]
	v_cndmask_b32_e64 v25, v61, v53, s[10:11]
	v_cndmask_b32_e64 v24, v59, v51, s[10:11]
	v_pk_mul_f32 v[24:25], v[80:81], v[24:25]
	v_cndmask_b32_e64 v27, v60, v52, s[8:9]
	v_cndmask_b32_e64 v26, v58, v50, s[8:9]
	v_pk_fma_f32 v[24:25], v[88:89], v[26:27], v[24:25]
	v_cvt_pk_bf16_f32 v18, v18, v19
	v_pk_fma_f32 v[20:21], v[20:21], v[96:97], v[24:25]
	v_mul_f32_e32 v24, 0xbfb8aa3b, v22
	v_mul_f32_e32 v25, 0xbfb8aa3b, v23
	v_exp_f32_e32 v24, v24
	v_exp_f32_e32 v25, v25
	v_mov_b32_e32 v28, v1
	v_mov_b32_e32 v29, v1
	v_add_f32_e32 v24, 1.0, v24
	v_add_f32_e32 v25, 1.0, v25
; __device__ __forceinline__ unsigned cvt_pk_bf16(float lo, float hi) { f32x2_t_ v = {lo, hi}; bf16x2_t_ b = __builtin_convertvector(v, bf16x2_t_); return __builtin_bit_cast(unsigned, b); }
; __device__ __forceinline__ float dpp_ror1(float v) { return __builtin_bit_cast(float, __builtin_amdgcn_update_dpp(0, __builtin_bit_cast(int, v), 0x121, 0xf, 0xf, false)); }
;     __device__ __forceinline__ void operator()(const f32x4 (&acc)[2][2][4][2], const Unit& u, int wr, int wc, int fr, int fq) const {
;     ...
;                 for (int m = 0; m < 4; ++m) {
;                     float cv[2][4];
; #pragma unroll
;                     for (int bj = 0; bj < 2; ++bj)
; #pragma unroll
;                         for (int e = 0; e < 4; ++e) {
;                             const float x = acc[ai][bj][m][n][e];
;                             const float r1s = dpp_ror1(x), r2s = dpp_ror2(x);
;                             float r1p, r2p;
;                             if (m > 0) { const float xp = acc[ai][bj][m > 0 ? m - 1 : 0][n][e]; r1p = dpp_ror1(xp); r2p = dpp_ror2(xp); }
;                             else { r1p = h1[bj][e]; r2p = (fr == 0) ? h2[bj][e] : h1[bj][e]; }
;                             const float p1 = (fr == 0) ? r1p : r1s, p2 = (fr < 2) ? r2p : r2s;
;                             cv[bj][e] = wgt[0][bj][e] * p2 + wgt[1][bj][e] * p1 + wgt[2][bj][e] * x;
;                         }
;                     const int r = u.pm * BM + ai * HALF + wr * 64 + m * 16 + fr;
;                     if (top && m == 0 && fr < 2) {
; #pragma unroll
;                         for (int bj = 0; bj < 2; ++bj) *(f32x4*)(hb + fr * 256 + bj * 128 + 4 * n) = acc[0][bj][0][n];
;                     } else {
;                         float o[4];
; #pragma unroll
;                         for (int c = 0; c < 4; ++c) { const float g = cv[0][c]; o[c] = g * __builtin_amdgcn_rcpf(1.0f + __expf(-g)) * cv[1][c]; }
;                         u32x2 w; w.x = cvt_pk_bf16(o[0], o[1]); w.y = cvt_pk_bf16(o[2], o[3]);
;                         *(u32x2*)(act + (size_t)r * 2816 + colj + 4 * n) = w;
;     ...
;         if (wr == 1 && fr >= 14) {
; #pragma unroll
;             for (int bj = 0; bj < 2; ++bj)
; #pragma unroll
;                 for (int n = 0; n < 2; ++n) *(f32x4*)(hb + (2 + fr - 14) * 256 + bj * 128 + 4 * n) = acc[1][bj][3][n];
;         }
	v_rcp_f32_e32 v24, v24
	v_rcp_f32_e32 v25, v25
	v_mov_b32_dpp v28, v2 row_ror:2 row_mask:0xf bank_mask:0xf
	v_mov_b32_dpp v29, v3 row_ror:2 row_mask:0xf bank_mask:0xf
	v_mov_b32_e32 v27, v1
	v_pk_mul_f32 v[22:23], v[22:23], v[24:25]
	v_mov_b32_e32 v25, v1
	v_pk_mul_f32 v[20:21], v[22:23], v[20:21]
	v_mov_b32_e32 v22, v1
	v_cvt_pk_bf16_f32 v19, v20, v21
	v_mov_b32_e32 v20, v1
	v_mov_b32_e32 v21, v1
	global_store_dwordx2 v[128:129], v[18:19], off offset:8
	v_mov_b32_e32 v18, v1
	v_mov_b32_dpp v20, v10 row_ror:2 row_mask:0xf bank_mask:0xf
	v_mov_b32_e32 v19, v1
	v_mov_b32_dpp v21, v11 row_ror:2 row_mask:0xf bank_mask:0xf
	v_mov_b32_dpp v18, v10 row_ror:1 row_mask:0xf bank_mask:0xf
	v_mov_b32_dpp v19, v11 row_ror:1 row_mask:0xf bank_mask:0xf
	v_mov_b32_e32 v23, v1
	v_cndmask_b32_e64 v21, v21, v33, s[10:11]
	v_cndmask_b32_e64 v20, v20, v31, s[10:11]
	v_mov_b32_dpp v22, v2 row_ror:1 row_mask:0xf bank_mask:0xf
	v_mov_b32_dpp v23, v3 row_ror:1 row_mask:0xf bank_mask:0xf
	v_cndmask_b32_e64 v19, v19, v32, s[8:9]
	v_cndmask_b32_e64 v18, v18, v30, s[8:9]
	v_pk_mul_f32 v[20:21], v[74:75], v[20:21]
	v_mov_b32_e32 v24, v1
	v_pk_fma_f32 v[18:19], v[82:83], v[18:19], v[20:21]
	v_cndmask_b32_e64 v21, v23, v56, s[8:9]
	v_cndmask_b32_e64 v20, v22, v54, s[8:9]
	v_cndmask_b32_e64 v23, v29, v57, s[10:11]
	v_cndmask_b32_e64 v22, v28, v55, s[10:11]
	v_pk_fma_f32 v[18:19], v[10:11], v[90:91], v[18:19]
	v_pk_mul_f32 v[22:23], v[78:79], v[22:23]
	v_mov_b32_dpp v25, v12 row_ror:2 row_mask:0xf bank_mask:0xf
	v_pk_fma_f32 v[20:21], v[86:87], v[20:21], v[22:23]
	v_mul_f32_e32 v22, 0xbfb8aa3b, v18
	v_mul_f32_e32 v23, 0xbfb8aa3b, v19
	v_exp_f32_e32 v22, v22
	v_exp_f32_e32 v23, v23
	v_mov_b32_e32 v26, v1
	v_mov_b32_dpp v27, v13 row_ror:2 row_mask:0xf bank_mask:0xf
	v_add_f32_e32 v22, 1.0, v22
	v_add_f32_e32 v23, 1.0, v23
	v_rcp_f32_e32 v22, v22
	v_rcp_f32_e32 v23, v23
	v_mov_b32_dpp v24, v12 row_ror:1 row_mask:0xf bank_mask:0xf
	v_mov_b32_dpp v26, v13 row_ror:1 row_mask:0xf bank_mask:0xf
	v_mov_b32_e32 v39, v1
	v_mov_b32_e32 v41, v1
	v_pk_fma_f32 v[20:21], v[2:3], v[94:95], v[20:21]
	v_pk_mul_f32 v[18:19], v[18:19], v[22:23]
	v_cndmask_b32_e64 v23, v27, v37, s[10:11]
	v_cndmask_b32_e64 v22, v25, v35, s[10:11]
	v_mov_b32_e32 v38, v1
	v_mov_b32_dpp v39, v4 row_ror:2 row_mask:0xf bank_mask:0xf
	v_mov_b32_e32 v40, v1
	v_mov_b32_dpp v41, v5 row_ror:2 row_mask:0xf bank_mask:0xf
	v_pk_mul_f32 v[18:19], v[18:19], v[20:21]
	v_cndmask_b32_e64 v21, v26, v36, s[8:9]
	v_cndmask_b32_e64 v20, v24, v34, s[8:9]
	v_pk_mul_f32 v[22:23], v[76:77], v[22:23]
	v_mov_b32_dpp v38, v4 row_ror:1 row_mask:0xf bank_mask:0xf
	v_mov_b32_dpp v40, v5 row_ror:1 row_mask:0xf bank_mask:0xf
	v_pk_fma_f32 v[20:21], v[84:85], v[20:21], v[22:23]
	v_cndmask_b32_e64 v23, v41, v61, s[10:11]
	v_cndmask_b32_e64 v22, v39, v59, s[10:11]
	v_pk_fma_f32 v[20:21], v[12:13], v[92:93], v[20:21]
	v_pk_mul_f32 v[22:23], v[80:81], v[22:23]
	v_cndmask_b32_e64 v25, v40, v60, s[8:9]
	v_cndmask_b32_e64 v24, v38, v58, s[8:9]
	v_pk_fma_f32 v[22:23], v[88:89], v[24:25], v[22:23]
	v_mul_f32_e32 v24, 0xbfb8aa3b, v20
	v_mul_f32_e32 v25, 0xbfb8aa3b, v21
	v_exp_f32_e32 v24, v24
	v_exp_f32_e32 v25, v25
	v_pk_fma_f32 v[22:23], v[4:5], v[96:97], v[22:23]
	v_cvt_pk_bf16_f32 v18, v18, v19
	v_add_f32_e32 v24, 1.0, v24
	v_add_f32_e32 v25, 1.0, v25
	v_rcp_f32_e32 v24, v24
	v_rcp_f32_e32 v25, v25
	s_nop 0
	v_pk_mul_f32 v[20:21], v[20:21], v[24:25]
	s_nop 0
	v_pk_mul_f32 v[20:21], v[20:21], v[22:23]
	s_nop 0
	v_cvt_pk_bf16_f32 v19, v20, v21
	global_store_dwordx2 v[114:115], v[18:19], off offset:8
	s_and_saveexec_b64 s[14:15], s[76:77]
	s_cbranch_execz .LBB0_96
	v_add_co_u32_e32 v18, vcc, 0xffffd000, v154
	s_nop 1
	v_addc_co_u32_e32 v19, vcc, -1, v155, vcc
	global_store_dwordx4 v[18:19], v[14:17], off
	s_nop 1
	v_add_co_u32_e32 v14, vcc, 0xffffd010, v154
	s_nop 1
	v_addc_co_u32_e32 v15, vcc, -1, v155, vcc
	global_store_dwordx4 v[14:15], v[10:13], off
	s_nop 1
	v_add_co_u32_e32 v10, vcc, 0xffffd200, v154
	s_nop 1
	v_addc_co_u32_e32 v11, vcc, -1, v155, vcc
	global_store_dwordx4 v[10:11], v[6:9], off
	s_nop 1
	v_add_co_u32_e32 v6, vcc, 0xffffd210, v154
	s_nop 1
	v_addc_co_u32_e32 v7, vcc, -1, v155, vcc
	global_store_dwordx4 v[6:7], v[2:5], off

;     __device__ __forceinline__ void operator()(const f32x4 (&acc)[2][2][4][2], const Unit& u, int wr, int wc, int fr, int fq) const {
;         const int col0 = u.pn * BM + wc * 32 + 4 * fq;
;         const int rbase = row_off + u.pm * BM;
;         const float* gp = gate + (size_t)(rbase >> 13) * 6144 + col0;
;         f32x4 gv[2][2];
; #pragma unroll
;         for (int bj = 0; bj < 2; ++bj)
; #pragma unroll
;             for (int n = 0; n < 2; ++n) gv[bj][n] = *(const f32x4*)(gp + bj * HALF + n * 16);
; #pragma unroll
;         for (int ai = 0; ai < 2; ++ai) {
;             f32x4 bs[4][2][2];
; #pragma unroll
;             for (int m = 0; m < 4; ++m) { const size_t off = (size_t)(rbase + ai * HALF + wr * 64 + m * 16 + fr) * 1024 + col0;
; #pragma unroll
;                 for (int bj = 0; bj < 2; ++bj)
; #pragma unroll
;                     for (int n = 0; n < 2; ++n) bs[m][bj][n] = *(const f32x4*)(base + off + bj * HALF + n * 16); }
;             __builtin_amdgcn_sched_barrier(0);
; #pragma unroll
;             for (int m = 0; m < 4; ++m) { const size_t off = (size_t)(rbase + ai * HALF + wr * 64 + m * 16 + fr) * 1024 + col0;
; #pragma unroll
;                 for (int bj = 0; bj < 2; ++bj)
; #pragma unroll
;                     for (int n = 0; n < 2; ++n) *(f32x4*)(out + off + bj * HALF + n * 16) = bs[m][bj][n] + gv[bj][n] * acc[ai][bj][m][n]; }
;             __builtin_amdgcn_sched_barrier(0);
;         }
.LBB0_123:
	s_lshr_b32 s24, s84, 5
	s_mulk_i32 s24, 0x1800
	v_lshl_or_b32 v130, s92, 8, v160
	s_ashr_i32 s25, s24, 31
	v_lshl_add_u32 v156, s84, 8, v158
	s_lshl_b64 s[24:25], s[24:25], 2
	v_ashrrev_i32_e32 v131, 31, v130
	v_or_b32_e32 v186, 16, v156
	v_or_b32_e32 v202, 32, v156
	v_or_b32_e32 v232, 48, v156
	s_add_u32 s24, s74, s24
	v_lshlrev_b64 v[152:153], 2, v[130:131]
	v_ashrrev_i32_e32 v157, 31, v156
	v_ashrrev_i32_e32 v187, 31, v186
	v_ashrrev_i32_e32 v203, 31, v202
	v_ashrrev_i32_e32 v233, 31, v232
	s_addc_u32 s25, s75, s25
	v_lshl_add_u64 v[154:155], s[18:19], 0, v[152:153]
	v_lshlrev_b64 v[210:211], 12, v[156:157]
	v_lshlrev_b64 v[248:249], 12, v[186:187]
	v_lshlrev_b64 v[250:251], 12, v[202:203]
	v_lshlrev_b64 v[252:253], 12, v[232:233]
	v_lshl_add_u64 v[130:131], s[24:25], 0, v[152:153]
	v_lshl_add_u64 v[182:183], v[154:155], 0, v[210:211]
	v_lshl_add_u64 v[198:199], v[154:155], 0, v[248:249]
	v_lshl_add_u64 v[228:229], v[154:155], 0, v[250:251]
	v_lshl_add_u64 v[244:245], v[154:155], 0, v[252:253]
	global_load_dwordx4 v[142:145], v[130:131], off
	global_load_dwordx4 v[138:141], v[130:131], off offset:64
	global_load_dwordx4 v[134:137], v[130:131], off offset:512
	s_nop 0
	global_load_dwordx4 v[130:133], v[130:131], off offset:576
	s_nop 0
	global_load_dwordx4 v[162:165], v[182:183], off
	global_load_dwordx4 v[166:169], v[182:183], off offset:64
	global_load_dwordx4 v[178:181], v[182:183], off offset:512
	s_nop 0
	global_load_dwordx4 v[182:185], v[182:183], off offset:576
	s_nop 0
	global_load_dwordx4 v[186:189], v[198:199], off
	global_load_dwordx4 v[190:193], v[198:199], off offset:64
	global_load_dwordx4 v[194:197], v[198:199], off offset:512
	s_nop 0
	global_load_dwordx4 v[198:201], v[198:199], off offset:576
	s_nop 0
	global_load_dwordx4 v[202:205], v[228:229], off
	global_load_dwordx4 v[206:209], v[228:229], off offset:64
	global_load_dwordx4 v[224:227], v[228:229], off offset:512
	s_nop 0
	global_load_dwordx4 v[228:231], v[228:229], off offset:576
	s_nop 0
	global_load_dwordx4 v[232:235], v[244:245], off
	global_load_dwordx4 v[236:239], v[244:245], off offset:64
	global_load_dwordx4 v[240:243], v[244:245], off offset:512
	s_nop 0
	global_load_dwordx4 v[244:247], v[244:245], off offset:576
	s_waitcnt vmcnt(0) lgkmcnt(0)
	v_pk_fma_f32 v[126:127], v[126:127], v[142:143], v[162:163]
	v_lshl_add_u64 v[162:163], s[18:19], 0, v[210:211]
	v_lshl_add_u64 v[162:163], v[162:163], 0, v[152:153]
	v_pk_fma_f32 v[116:117], v[116:117], v[136:137], v[180:181]
	v_pk_fma_f32 v[114:115], v[114:115], v[134:135], v[178:179]
	global_store_dwordx4 v[162:163], v[114:117], off offset:512
	v_pk_fma_f32 v[100:101], v[100:101], v[136:137], v[196:197]
	v_pk_fma_f32 v[98:99], v[98:99], v[134:135], v[194:195]
	v_lshl_add_u64 v[114:115], s[18:19], 0, v[248:249]
	v_lshl_add_u64 v[114:115], v[114:115], 0, v[152:153]
	global_store_dwordx4 v[114:115], v[98:101], off offset:512
	v_pk_fma_f32 v[84:85], v[84:85], v[136:137], v[226:227]
	v_pk_fma_f32 v[82:83], v[82:83], v[134:135], v[224:225]
	v_lshl_add_u64 v[98:99], s[18:19], 0, v[250:251]
	v_lshl_add_u64 v[98:99], v[98:99], 0, v[152:153]
	v_pk_fma_f32 v[108:109], v[108:109], v[132:133], v[184:185]
	v_pk_fma_f32 v[106:107], v[106:107], v[130:131], v[182:183]
	v_pk_fma_f32 v[92:93], v[92:93], v[132:133], v[200:201]
	v_pk_fma_f32 v[90:91], v[90:91], v[130:131], v[198:199]
	global_store_dwordx4 v[98:99], v[82:85], off offset:512
	v_pk_fma_f32 v[76:77], v[76:77], v[132:133], v[230:231]
	v_pk_fma_f32 v[74:75], v[74:75], v[130:131], v[228:229]
	v_lshl_add_u64 v[82:83], s[18:19], 0, v[252:253]
	global_store_dwordx4 v[162:163], v[106:109], off offset:576
	global_store_dwordx4 v[114:115], v[90:93], off offset:576
	global_store_dwordx4 v[98:99], v[74:77], off offset:576
	v_pk_fma_f32 v[108:109], v[120:121], v[144:145], v[188:189]
	v_pk_fma_f32 v[106:107], v[118:119], v[142:143], v[186:187]
	v_pk_fma_f32 v[92:93], v[104:105], v[144:145], v[204:205]
	v_pk_fma_f32 v[90:91], v[102:103], v[142:143], v[202:203]
	v_pk_fma_f32 v[76:77], v[88:89], v[144:145], v[234:235]
	v_pk_fma_f32 v[74:75], v[86:87], v[142:143], v[232:233]
	v_lshl_add_u64 v[82:83], v[82:83], 0, v[152:153]
	v_pk_fma_f32 v[128:129], v[128:129], v[144:145], v[164:165]
	v_pk_fma_f32 v[124:125], v[124:125], v[140:141], v[168:169]
	v_pk_fma_f32 v[122:123], v[122:123], v[138:139], v[166:167]
	global_store_dwordx4 v[114:115], v[106:109], off
	global_store_dwordx4 v[98:99], v[90:93], off
	global_store_dwordx4 v[82:83], v[74:77], off
	v_pk_fma_f32 v[108:109], v[112:113], v[140:141], v[192:193]
	v_pk_fma_f32 v[106:107], v[110:111], v[138:139], v[190:191]
	v_pk_fma_f32 v[92:93], v[96:97], v[140:141], v[208:209]
	v_pk_fma_f32 v[90:91], v[94:95], v[138:139], v[206:207]
	v_pk_fma_f32 v[76:77], v[80:81], v[140:141], v[238:239]
	v_pk_fma_f32 v[74:75], v[78:79], v[138:139], v[236:237]
	v_pk_fma_f32 v[72:73], v[72:73], v[136:137], v[242:243]
	v_pk_fma_f32 v[70:71], v[70:71], v[134:135], v[240:241]
	v_pk_fma_f32 v[68:69], v[68:69], v[132:133], v[246:247]
	v_pk_fma_f32 v[66:67], v[66:67], v[130:131], v[244:245]
	global_store_dwordx4 v[162:163], v[126:129], off
;     __device__ __forceinline__ void operator()(const f32x4 (&acc)[2][2][4][2], const Unit& u, int wr, int wc, int fr, int fq) const {
;     ...
;         for (int ai = 0; ai < 2; ++ai) {
;             f32x4 bs[4][2][2];
; #pragma unroll
;             for (int m = 0; m < 4; ++m) { const size_t off = (size_t)(rbase + ai * HALF + wr * 64 + m * 16 + fr) * 1024 + col0;
; #pragma unroll
;                 for (int bj = 0; bj < 2; ++bj)
; #pragma unroll
;                     for (int n = 0; n < 2; ++n) bs[m][bj][n] = *(const f32x4*)(base + off + bj * HALF + n * 16); }
;             __builtin_amdgcn_sched_barrier(0);
; #pragma unroll
;             for (int m = 0; m < 4; ++m) { const size_t off = (size_t)(rbase + ai * HALF + wr * 64 + m * 16 + fr) * 1024 + col0;
; #pragma unroll
;                 for (int bj = 0; bj < 2; ++bj)
; #pragma unroll
;                     for (int n = 0; n < 2; ++n) *(f32x4*)(out + off + bj * HALF + n * 16) = bs[m][bj][n] + gv[bj][n] * acc[ai][bj][m][n]; }
;             __builtin_amdgcn_sched_barrier(0);
;         }
	global_store_dwordx4 v[162:163], v[122:125], off offset:64
	global_store_dwordx4 v[114:115], v[106:109], off offset:64
	global_store_dwordx4 v[98:99], v[90:93], off offset:64
	global_store_dwordx4 v[82:83], v[74:77], off offset:64
	global_store_dwordx4 v[82:83], v[70:73], off offset:512
	global_store_dwordx4 v[82:83], v[66:69], off offset:576
	s_nop 1
	v_add_u32_e32 v66, 0x80, v156
	v_add_u32_e32 v82, 0x90, v156
	v_add_u32_e32 v98, 0xa0, v156
	v_add_u32_e32 v114, 0xb0, v156
	v_ashrrev_i32_e32 v67, 31, v66
	v_ashrrev_i32_e32 v83, 31, v82
	v_ashrrev_i32_e32 v99, 31, v98
	v_ashrrev_i32_e32 v115, 31, v114
	v_lshlrev_b64 v[162:163], 12, v[66:67]
	v_lshlrev_b64 v[164:165], 12, v[82:83]
	v_lshlrev_b64 v[166:167], 12, v[98:99]
	v_lshlrev_b64 v[156:157], 12, v[114:115]
	v_lshl_add_u64 v[78:79], v[154:155], 0, v[162:163]
	v_lshl_add_u64 v[94:95], v[154:155], 0, v[164:165]
	v_lshl_add_u64 v[110:111], v[154:155], 0, v[166:167]
	v_lshl_add_u64 v[126:127], v[154:155], 0, v[156:157]
	global_load_dwordx4 v[66:69], v[78:79], off
	global_load_dwordx4 v[70:73], v[78:79], off offset:64
	global_load_dwordx4 v[74:77], v[78:79], off offset:512
	s_nop 0
	global_load_dwordx4 v[78:81], v[78:79], off offset:576
	s_nop 0
	global_load_dwordx4 v[82:85], v[94:95], off
	global_load_dwordx4 v[86:89], v[94:95], off offset:64
	global_load_dwordx4 v[90:93], v[94:95], off offset:512
	s_nop 0
	global_load_dwordx4 v[94:97], v[94:95], off offset:576
	s_nop 0
	global_load_dwordx4 v[98:101], v[110:111], off
	global_load_dwordx4 v[102:105], v[110:111], off offset:64
	global_load_dwordx4 v[106:109], v[110:111], off offset:512
	s_nop 0
	global_load_dwordx4 v[110:113], v[110:111], off offset:576
	s_nop 0
	global_load_dwordx4 v[114:117], v[126:127], off
	global_load_dwordx4 v[118:121], v[126:127], off offset:64
	global_load_dwordx4 v[122:125], v[126:127], off offset:512
	s_nop 0
	global_load_dwordx4 v[126:129], v[126:127], off offset:576
	s_waitcnt vmcnt(0) lgkmcnt(0)
	v_pk_fma_f32 v[62:63], v[62:63], v[142:143], v[66:67]
	v_lshl_add_u64 v[66:67], s[18:19], 0, v[162:163]
	v_lshl_add_u64 v[66:67], v[66:67], 0, v[152:153]
	v_pk_fma_f32 v[52:53], v[52:53], v[136:137], v[76:77]
	v_pk_fma_f32 v[50:51], v[50:51], v[134:135], v[74:75]
	global_store_dwordx4 v[66:67], v[50:53], off offset:512
	v_pk_fma_f32 v[36:37], v[36:37], v[136:137], v[92:93]
	v_pk_fma_f32 v[34:35], v[34:35], v[134:135], v[90:91]
	v_lshl_add_u64 v[50:51], s[18:19], 0, v[164:165]
	v_lshl_add_u64 v[50:51], v[50:51], 0, v[152:153]
	global_store_dwordx4 v[50:51], v[34:37], off offset:512
	v_pk_fma_f32 v[20:21], v[20:21], v[136:137], v[108:109]
	v_pk_fma_f32 v[18:19], v[18:19], v[134:135], v[106:107]
	v_lshl_add_u64 v[34:35], s[18:19], 0, v[166:167]
	v_lshl_add_u64 v[34:35], v[34:35], 0, v[152:153]
	v_pk_fma_f32 v[44:45], v[44:45], v[132:133], v[80:81]
	v_pk_fma_f32 v[42:43], v[42:43], v[130:131], v[78:79]
	v_pk_fma_f32 v[28:29], v[28:29], v[132:133], v[96:97]
	v_pk_fma_f32 v[26:27], v[26:27], v[130:131], v[94:95]
	global_store_dwordx4 v[34:35], v[18:21], off offset:512
	v_pk_fma_f32 v[12:13], v[12:13], v[132:133], v[112:113]
	v_pk_fma_f32 v[10:11], v[10:11], v[130:131], v[110:111]
	v_lshl_add_u64 v[18:19], s[18:19], 0, v[156:157]
	global_store_dwordx4 v[66:67], v[42:45], off offset:576
	global_store_dwordx4 v[50:51], v[26:29], off offset:576
	global_store_dwordx4 v[34:35], v[10:13], off offset:576
	v_pk_fma_f32 v[44:45], v[56:57], v[144:145], v[84:85]
	v_pk_fma_f32 v[42:43], v[54:55], v[142:143], v[82:83]
	v_pk_fma_f32 v[28:29], v[40:41], v[144:145], v[100:101]
	v_pk_fma_f32 v[26:27], v[38:39], v[142:143], v[98:99]
	v_pk_fma_f32 v[12:13], v[24:25], v[144:145], v[116:117]
	v_pk_fma_f32 v[10:11], v[22:23], v[142:143], v[114:115]
	v_lshl_add_u64 v[18:19], v[18:19], 0, v[152:153]
	v_pk_fma_f32 v[64:65], v[64:65], v[144:145], v[68:69]
	v_pk_fma_f32 v[60:61], v[60:61], v[140:141], v[72:73]
	v_pk_fma_f32 v[58:59], v[58:59], v[138:139], v[70:71]
	global_store_dwordx4 v[50:51], v[42:45], off
	global_store_dwordx4 v[34:35], v[26:29], off
	global_store_dwordx4 v[18:19], v[10:13], off
	v_pk_fma_f32 v[44:45], v[48:49], v[140:141], v[88:89]
	v_pk_fma_f32 v[42:43], v[46:47], v[138:139], v[86:87]
	v_pk_fma_f32 v[28:29], v[32:33], v[140:141], v[104:105]
	v_pk_fma_f32 v[26:27], v[30:31], v[138:139], v[102:103]
	v_pk_fma_f32 v[12:13], v[16:17], v[140:141], v[120:121]
	v_pk_fma_f32 v[10:11], v[14:15], v[138:139], v[118:119]
	v_pk_fma_f32 v[8:9], v[8:9], v[136:137], v[124:125]
	v_pk_fma_f32 v[6:7], v[6:7], v[134:135], v[122:123]
	v_pk_fma_f32 v[4:5], v[4:5], v[132:133], v[128:129]
	v_pk_fma_f32 v[2:3], v[2:3], v[130:131], v[126:127]
	global_store_dwordx4 v[66:67], v[62:65], off
	global_store_dwordx4 v[66:67], v[58:61], off offset:64
	global_store_dwordx4 v[50:51], v[42:45], off offset:64
	global_store_dwordx4 v[34:35], v[26:29], off offset:64
	global_store_dwordx4 v[18:19], v[10:13], off offset:64
	global_store_dwordx4 v[18:19], v[6:9], off offset:512
	global_store_dwordx4 v[18:19], v[2:5], off offset:576
	s_and_b64 vcc, exec, s[6:7]
	s_mov_b64 s[6:7], -1
	s_cbranch_vccnz .LBB0_108
	s_andn2_b64 vcc, exec, s[12:13]
	s_cbranch_vccnz .LBB0_107
	s_barrier
	s_branch .LBB0_107

; __device__ __forceinline__ int my_bid() { int t = (int)blockIdx.x; asm volatile("" : "+s"(t)); return t; }
; __device__ __forceinline__ int my_gdim() { int t = (int)gridDim.x; asm volatile("" : "+s"(t)); return t; }
; __device__ __forceinline__ void phase_norm(const Params& p, unsigned char* lds, const float* __restrict__ xin, const float* g, const float* mod  , int shift_off, int scale_off, bf16_t* __restrict__ hout, const float* wsc  , float* scal) {
;     ...
;     const int gw = my_bid() * 8 + wid, nw = my_gdim() * 8;
;     for (int rb = gw * 4; rb < MTOK; rb += nw * 4) {
;         const int b = rb >> 13;
;         float cs[16], sh[16];
; #pragma unroll
;         for (int i = 0; i < 2; ++i)
; #pragma unroll
;             for (int j = 0; j < 8; ++j) { const int k = i * 512 + lane * 8 + j; cs[i * 8 + j] = g[k] * (1.0f + mod[(size_t)b * 6144 + scale_off + k]); sh[i * 8 + j] = mod[(size_t)b * 6144 + shift_off + k]; }
;         { const int r4 = 0;
;             f32x4 xq[4][4];
; #pragma unroll
;             for (int q = 0; q < 4; ++q) { const float* xp = xin + (size_t)(rb + r4 + q) * DM + lane * 8;
;                 xq[q][0] = __builtin_nontemporal_load((const f32x4*)xp); xq[q][1] = __builtin_nontemporal_load((const f32x4*)(xp + 4)); xq[q][2] = __builtin_nontemporal_load((const f32x4*)(xp + 512)); xq[q][3] = __builtin_nontemporal_load((const f32x4*)(xp + 516)); }
; #pragma unroll
;             for (int q = 0; q < 4; ++q) {
;             const int row = rb + r4 + q;
;             const f32x4 x0 = xq[q][0], x1 = xq[q][1], x2 = xq[q][2], x3 = xq[q][3];
;             float xv[16] = {x0[0], x0[1], x0[2], x0[3], x1[0], x1[1], x1[2], x1[3], x2[0], x2[1], x2[2], x2[3], x3[0], x3[1], x3[2], x3[3]};
;             float ss = 0.f;
; #pragma unroll
;             for (int i = 0; i < 16; ++i) ss += xv[i] * xv[i];
;             ss = wave_sum(ss);
;             const float rstd = rsqrtf(ss * (1.0f / DM) + EPS);
; __device__ void run_phase(const Params& p, unsigned char* lds, int ph) {
;     ...
;     case 5:
;         phase_norm(p, lds, xs, p.in[I_NFG] + l * DM, modl, 3072, 4096, hbuf, nullptr, nullptr);
.LBB0_129:
	s_and_b64 vcc, exec, s[0:1]
	s_cbranch_vccz .LBB0_161
	s_cmp_gt_i32 s59, 4
	s_mov_b64 s[0:1], -1
	s_cbranch_scc0 .LBB0_135
	s_waitcnt vmcnt(0)
	v_mov_b32_e32 v18, v212
	v_readlane_b32 s0, v254, 0
	v_ashrrev_i32_e32 v0, 4, v18
	v_and_b32_e32 v0, -4, v0
	v_lshl_add_u32 v94, s0, 5, v0
	s_mov_b32 s0, 0x8000
	s_load_dword s6, s[80:81], 0x0
	v_cmp_gt_i32_e32 vcc, s0, v94
	s_waitcnt lgkmcnt(0)
	s_and_saveexec_b64 s[0:1], vcc
	s_movk_i32 s14, 0xc7f0
	s_movk_i32 s15, 0xcff0
	s_movk_i32 s20, 0xd7f0
	s_movk_i32 s21, 0xc800
	s_movk_i32 s24, 0xdff0
	s_movk_i32 s25, 0xe7f0
	s_movk_i32 s28, 0xeff0
	s_movk_i32 s29, 0xf7f0
	s_mov_b64 s[30:31], 0x4000
	s_mov_b64 s[34:35], 0x3000
	s_movk_i32 s36, 0xe800
	s_movk_i32 s37, 0xd800
	s_cbranch_execz .LBB0_134
	v_readlane_b32 s8, v255, 3
	v_readlane_b32 s9, v255, 4
	s_lshl_b32 s8, s8, 10
	s_ashr_i32 s9, s8, 31
	s_lshl_b64 s[8:9], s[8:9], 2
	v_lshlrev_b32_e32 v0, 3, v18
	s_add_u32 s8, s22, s8
	v_and_b32_e32 v20, 0x1f8, v0
	s_addc_u32 s9, s23, s9
	v_lshlrev_b32_e32 v0, 2, v20
	v_lshl_add_u64 v[14:15], s[8:9], 0, v[0:1]
	global_load_dwordx4 v[2:5], v[14:15], off
	global_load_dwordx4 v[6:9], v[14:15], off offset:16
	global_load_dwordx4 v[10:13], v[14:15], off offset:2048
	s_nop 0
	global_load_dwordx4 v[14:17], v[14:15], off offset:2064
	v_ashrrev_i32_e32 v95, 31, v94
	v_lshlrev_b64 v[28:29], 11, v[94:95]
	v_and_b32_e32 v0, 63, v18
	v_lshl_or_b32 v28, v0, 4, v28
	v_lshl_add_u64 v[18:19], s[86:87], 0, v[28:29]
	s_mov_b64 s[8:9], 0x3601c00
	v_lshl_add_u64 v[98:99], v[18:19], 0, s[8:9]
	v_lshlrev_b64 v[18:19], 12, v[94:95]
	s_lshl_b32 s6, s6, 5
	v_lshl_or_b32 v18, v0, 5, v18
	v_or_b32_e32 v22, 4, v20
	v_or_b32_e32 v24, 0x200, v20
	v_or_b32_e32 v26, 0x204, v20
	s_ashr_i32 s7, s6, 31
	v_lshl_add_u64 v[18:19], s[18:19], 0, v[18:19]
	s_mov_b64 s[10:11], 0x3810
	s_mov_b64 s[38:39], s[70:71]
	s_lshl_b64 s[8:9], s[6:7], 11
	v_lshl_add_u64 v[100:101], v[18:19], 0, s[10:11]
	s_lshl_b64 s[10:11], s[6:7], 12
	s_mov_b64 s[12:13], 0
	v_lshlrev_b32_e32 v0, 2, v20
	v_lshlrev_b32_e32 v102, 2, v22
	v_lshlrev_b32_e32 v104, 2, v24
	v_lshlrev_b32_e32 v106, 2, v26
	s_waitcnt vmcnt(0) lgkmcnt(0)
	v_mov_b32_e32 v96, v17
.LBB0_133:
	v_ashrrev_i32_e32 v17, 13, v94
	v_mul_i32_i24_e32 v18, 0x1800, v17
	v_ashrrev_i32_e32 v19, 31, v18
	v_lshl_add_u64 v[18:19], v[18:19], 2, s[38:39]
	v_lshl_add_u64 v[20:21], v[18:19], 0, s[30:31]
	v_lshl_add_u64 v[18:19], v[18:19], 0, s[34:35]
	v_mov_b32_e32 v103, v1
	v_mov_b32_e32 v105, v1
	v_mov_b32_e32 v107, v1
	v_lshl_add_u64 v[50:51], v[18:19], 0, v[0:1]
	v_lshl_add_u64 v[54:55], v[18:19], 0, v[102:103]
	v_lshl_add_u64 v[120:121], v[18:19], 0, v[104:105]
	v_lshl_add_u64 v[124:125], v[18:19], 0, v[106:107]
	v_add_co_u32_e32 v18, vcc, s14, v100
	v_lshl_add_u64 v[52:53], v[20:21], 0, v[0:1]
	s_nop 0
	v_addc_co_u32_e32 v19, vcc, -1, v101, vcc
	global_load_dwordx4 v[46:49], v[18:19], off nt
	v_add_co_u32_e32 v18, vcc, s21, v100
	v_lshl_add_u64 v[56:57], v[20:21], 0, v[102:103]
	s_nop 0
	v_addc_co_u32_e32 v19, vcc, -1, v101, vcc
	global_load_dwordx4 v[58:61], v[18:19], off nt
	v_lshl_add_u64 v[118:119], v[20:21], 0, v[104:105]
	v_lshl_add_u64 v[20:21], v[20:21], 0, v[106:107]
	v_add_co_u32_e32 v18, vcc, s15, v100
	global_load_dwordx4 v[26:29], v[20:21], off
	s_nop 0
	v_addc_co_u32_e32 v19, vcc, -1, v101, vcc
	global_load_dwordx4 v[86:89], v[18:19], off nt
	v_add_co_u32_e32 v18, vcc, s33, v100
	v_add_u32_e32 v94, s6, v94
	s_nop 0
	v_addc_co_u32_e32 v19, vcc, -1, v101, vcc
	global_load_dwordx4 v[90:93], v[18:19], off nt
	v_add_co_u32_e32 v18, vcc, s20, v100
	s_waitcnt vmcnt(0) lgkmcnt(0)
	v_mul_f32_e32 v17, v47, v47
	v_addc_co_u32_e32 v19, vcc, -1, v101, vcc
	global_load_dwordx4 v[74:77], v[18:19], off nt
	v_add_co_u32_e32 v18, vcc, s37, v100
	v_fmac_f32_e32 v17, v46, v46
	s_nop 0
	v_addc_co_u32_e32 v19, vcc, -1, v101, vcc
	global_load_dwordx4 v[78:81], v[18:19], off nt
	v_add_co_u32_e32 v18, vcc, s24, v100
	v_fmac_f32_e32 v17, v48, v48
	s_nop 0
	v_addc_co_u32_e32 v19, vcc, -1, v101, vcc
	global_load_dwordx4 v[82:85], v[18:19], off nt
	v_add_co_u32_e32 v18, vcc, s40, v100
	v_fmac_f32_e32 v17, v49, v49
	s_nop 0
	v_addc_co_u32_e32 v19, vcc, -1, v101, vcc
	global_load_dwordx4 v[22:25], v[18:19], off nt
	v_add_co_u32_e32 v18, vcc, s25, v100
	v_fmac_f32_e32 v17, v58, v58
	s_nop 0
	v_addc_co_u32_e32 v19, vcc, -1, v101, vcc
	global_load_dwordx4 v[62:65], v[18:19], off nt
	v_add_co_u32_e32 v18, vcc, s36, v100
	v_fmac_f32_e32 v17, v59, v59
	s_nop 0
	v_addc_co_u32_e32 v19, vcc, -1, v101, vcc
	global_load_dwordx4 v[66:69], v[18:19], off nt
	v_add_co_u32_e32 v18, vcc, s28, v100
	v_fmac_f32_e32 v17, v60, v60
	s_nop 0
	v_addc_co_u32_e32 v19, vcc, -1, v101, vcc
	global_load_dwordx4 v[70:73], v[18:19], off nt
	v_add_co_u32_e32 v18, vcc, s42, v100
	v_add_f32_e32 v122, 1.0, v28
	s_nop 0
	v_addc_co_u32_e32 v19, vcc, -1, v101, vcc
	v_add_co_u32_e32 v28, vcc, s29, v100
	v_fmac_f32_e32 v17, v61, v61
	v_add_f32_e32 v108, 1.0, v29
	v_addc_co_u32_e32 v29, vcc, -1, v101, vcc
	v_fmac_f32_e32 v17, v86, v86
	global_load_dwordx4 v[18:21], v[18:19], off nt
	v_fmac_f32_e32 v17, v87, v87
	global_load_dwordx4 v[30:33], v[28:29], off nt
	v_add_co_u32_e32 v28, vcc, s75, v100
	v_fmac_f32_e32 v17, v88, v88
	s_nop 0
	v_addc_co_u32_e32 v29, vcc, -1, v101, vcc
	global_load_dwordx4 v[34:37], v[28:29], off nt
	v_add_co_u32_e32 v28, vcc, -16, v100
	v_fmac_f32_e32 v17, v89, v89
	v_pk_mul_f32 v[110:111], v[90:91], v[90:91]
	v_addc_co_u32_e32 v29, vcc, -1, v101, vcc
	v_add_f32_e32 v17, v110, v17
	global_load_dwordx4 v[42:45], v[28:29], off nt
	global_load_dwordx4 v[38:41], v[100:101], off nt
	v_add_f32_e32 v17, v111, v17
	global_load_dwordx4 v[110:113], v[52:53], off
	v_pk_mul_f32 v[28:29], v[92:93], v[92:93]
	global_load_dwordx4 v[50:53], v[50:51], off
	v_add_f32_e32 v17, v28, v17
	v_add_f32_e32 v17, v29, v17
	v_mov_b32_e32 v28, v1
	v_pk_add_f32 v[26:27], v[26:27], 1.0 op_sel_hi:[1,0]
	v_add_f32_dpp v17, v17, v17 row_shr:1 row_mask:0xf bank_mask:0xf bound_ctrl:1
	v_lshl_add_u64 v[100:101], v[100:101], 0, s[10:11]
	s_waitcnt vmcnt(0) lgkmcnt(0)
; __device__ __forceinline__ float wave_sum(float v) {
;     v += dpp_row_shr_(v, 1); v += dpp_row_shr_(v, 2); v += dpp_row_shr_(v, 4); v += dpp_row_shr_(v, 8);
;     v += __builtin_bit_cast(float, __builtin_amdgcn_update_dpp(0, __builtin_bit_cast(int, v), 0x142, 0xa, 0xf, false));
;     v += __builtin_bit_cast(float, __builtin_amdgcn_update_dpp(0, __builtin_bit_cast(int, v), 0x143, 0xc, 0xf, false));
; __device__ __forceinline__ void phase_norm(const Params& p, unsigned char* lds, const float* __restrict__ xin, const float* g, const float* mod  , int shift_off, int scale_off, bf16_t* __restrict__ hout, const float* wsc  , float* scal) {
;     ...
;             for (int j = 0; j < 8; ++j) { const int k = i * 512 + lane * 8 + j; cs[i * 8 + j] = g[k] * (1.0f + mod[(size_t)b * 6144 + scale_off + k]); sh[i * 8 + j] = mod[(size_t)b * 6144 + shift_off + k]; }
;         { const int r4 = 0;
;             f32x4 xq[4][4];
; #pragma unroll
;             for (int q = 0; q < 4; ++q) { const float* xp = xin + (size_t)(rb + r4 + q) * DM + lane * 8;
;                 xq[q][0] = __builtin_nontemporal_load((const f32x4*)xp); xq[q][1] = __builtin_nontemporal_load((const f32x4*)(xp + 4)); xq[q][2] = __builtin_nontemporal_load((const f32x4*)(xp + 512)); xq[q][3] = __builtin_nontemporal_load((const f32x4*)(xp + 516)); }
; #pragma unroll
;             for (int q = 0; q < 4; ++q) {
;             const int row = rb + r4 + q;
;             const f32x4 x0 = xq[q][0], x1 = xq[q][1], x2 = xq[q][2], x3 = xq[q][3];
;             float xv[16] = {x0[0], x0[1], x0[2], x0[3], x1[0], x1[1], x1[2], x1[3], x2[0], x2[1], x2[2], x2[3], x3[0], x3[1], x3[2], x3[3]};
;             float ss = 0.f;
; #pragma unroll
;             for (int i = 0; i < 16; ++i) ss += xv[i] * xv[i];
;             ss = wave_sum(ss);
;             const float rstd = rsqrtf(ss * (1.0f / DM) + EPS);
;             float h[16];
; #pragma unroll
;             for (int i = 0; i < 16; ++i) h[i] = xv[i] * rstd * cs[i] + sh[i];
;             u32x4 w0, w1;
;             w0.x = pack2(h[0], h[1]); w0.y = pack2(h[2], h[3]); w0.z = pack2(h[4], h[5]); w0.w = pack2(h[6], h[7]);
;             w1.x = pack2(h[8], h[9]); w1.y = pack2(h[10], h[11]); w1.z = pack2(h[12], h[13]); w1.w = pack2(h[14], h[15]);
;             bf16_t* hp = hout + (size_t)row * DM + lane * 8;
;             *(u32x4*)hp = w0; *(u32x4*)(hp + 512) = w1;
	v_mov_b32_e32 v97, v41
	v_add_f32_dpp v17, v17, v17 row_shr:2 row_mask:0xf bank_mask:0xf bound_ctrl:1
	s_nop 1
	v_add_f32_dpp v17, v17, v17 row_shr:4 row_mask:0xf bank_mask:0xf bound_ctrl:1
	s_nop 1
	v_add_f32_dpp v17, v17, v17 row_shr:8 row_mask:0xf bank_mask:0xf bound_ctrl:1
	s_nop 1
	v_mov_b32_dpp v28, v17 row_bcast:15 row_mask:0xa bank_mask:0xf
	v_add_f32_e32 v17, v17, v28
	v_mov_b32_e32 v28, v1
	s_nop 1
	v_mov_b32_dpp v28, v17 row_bcast:31 row_mask:0xc bank_mask:0xf
	v_add_f32_e32 v17, v17, v28
	s_nop 0
	v_readlane_b32 s7, v17, 63
	s_nop 1
	v_fma_f32 v17, s7, v217, v213
	v_cmp_gt_f32_e32 vcc, s44, v17
	v_mul_f32_e32 v28, 0x4b800000, v17
	s_movk_i32 s7, 0xe400
	v_cndmask_b32_e32 v17, v17, v28, vcc
	v_rsq_f32_e32 v17, v17
	s_nop 0
	v_mul_f32_e32 v28, 0x45800000, v17
	v_cndmask_b32_e32 v126, v17, v28, vcc
	v_pk_add_f32 v[28:29], v[110:111], 1.0 op_sel_hi:[1,0]
	v_mov_b32_e32 v17, v92
	v_pk_mul_f32 v[110:111], v[2:3], v[28:29]
	v_pk_mul_f32 v[28:29], v[46:47], v[126:127] op_sel_hi:[1,0]
	v_mov_b32_e32 v123, v126
	v_pk_fma_f32 v[128:129], v[110:111], v[28:29], v[50:51]
	v_pk_add_f32 v[28:29], v[112:113], 1.0 op_sel_hi:[1,0]
	v_add_co_u32_e32 v92, vcc, s7, v98
	v_pk_mul_f32 v[112:113], v[4:5], v[28:29]
	v_pk_mul_f32 v[28:29], v[48:49], v[126:127] op_sel_hi:[1,0]
	global_load_dwordx4 v[46:49], v[56:57], off
	v_pk_fma_f32 v[130:131], v[112:113], v[28:29], v[52:53]
	global_load_dwordx4 v[54:57], v[54:55], off
	s_waitcnt vmcnt(0) lgkmcnt(0)
	v_pk_add_f32 v[28:29], v[46:47], 1.0 op_sel_hi:[1,0]
	s_nop 0
	v_pk_mul_f32 v[114:115], v[6:7], v[28:29]
	v_pk_mul_f32 v[28:29], v[58:59], v[126:127] op_sel_hi:[1,0]
	s_nop 0
	v_pk_fma_f32 v[132:133], v[114:115], v[28:29], v[54:55]
	v_pk_add_f32 v[28:29], v[48:49], 1.0 op_sel_hi:[1,0]
	global_load_dwordx4 v[46:49], v[118:119], off
	v_pk_mul_f32 v[116:117], v[8:9], v[28:29]
	v_pk_mul_f32 v[28:29], v[60:61], v[126:127] op_sel_hi:[1,0]
	global_load_dwordx4 v[58:61], v[120:121], off
	v_pk_fma_f32 v[134:135], v[116:117], v[28:29], v[56:57]
	v_pk_mul_f32 v[120:121], v[14:15], v[26:27]
	s_waitcnt vmcnt(0) lgkmcnt(0)
	v_pk_add_f32 v[28:29], v[46:47], 1.0 op_sel_hi:[1,0]
	s_nop 0
	v_pk_mul_f32 v[118:119], v[10:11], v[28:29]
	v_pk_mul_f32 v[28:29], v[86:87], v[126:127] op_sel_hi:[1,0]
	s_nop 0
	v_pk_fma_f32 v[46:47], v[118:119], v[28:29], v[58:59]
	v_pk_add_f32 v[28:29], v[48:49], 1.0 op_sel_hi:[1,0]
	v_cvt_pk_bf16_f32 v46, v46, v47
	v_pk_mul_f32 v[86:87], v[12:13], v[28:29]
	v_pk_mul_f32 v[28:29], v[88:89], v[126:127] op_sel_hi:[1,0]
	v_pk_mul_f32 v[88:89], v[90:91], v[126:127] op_sel_hi:[1,0]
	v_pk_fma_f32 v[48:49], v[86:87], v[28:29], v[60:61]
	global_load_dwordx4 v[26:29], v[124:125], off
	v_mul_f32_e32 v91, v93, v126
	v_cvt_pk_bf16_f32 v124, v132, v133
	v_cvt_pk_bf16_f32 v125, v134, v135
	v_addc_co_u32_e32 v93, vcc, -1, v99, vcc
	v_cvt_pk_bf16_f32 v47, v48, v49
	v_mov_b32_e32 v49, v1
	v_pk_mul_f32 v[126:127], v[38:39], v[38:39]
	s_waitcnt vmcnt(0) lgkmcnt(0)
	v_pk_fma_f32 v[136:137], v[120:121], v[88:89], v[26:27]
	v_pk_mul_f32 v[88:89], v[16:17], v[122:123]
	v_mul_f32_e32 v17, v75, v75
	v_fmac_f32_e32 v17, v74, v74
	v_fmac_f32_e32 v17, v76, v76
	v_fmac_f32_e32 v17, v77, v77
	v_fmac_f32_e32 v17, v78, v78
	v_fmac_f32_e32 v17, v79, v79
	v_fmac_f32_e32 v17, v80, v80
	v_fmac_f32_e32 v17, v81, v81
	v_fmac_f32_e32 v17, v82, v82
	v_fmac_f32_e32 v17, v83, v83
	v_cvt_pk_bf16_f32 v122, v128, v129
	v_cvt_pk_bf16_f32 v123, v130, v131
	v_fmac_f32_e32 v17, v84, v84
	global_store_dwordx4 v[92:93], v[122:125], off
	v_fmac_f32_e32 v17, v85, v85
	v_pk_mul_f32 v[92:93], v[24:25], v[24:25]
	v_pk_mul_f32 v[122:123], v[22:23], v[22:23]
	v_pk_mul_f32 v[124:125], v[18:19], v[18:19]
	v_add_f32_e32 v17, v122, v17
	v_add_f32_e32 v17, v123, v17
	v_add_f32_e32 v17, v92, v17
	v_add_f32_e32 v17, v93, v17
	v_pk_mul_f32 v[122:123], v[20:21], v[20:21]
	v_cvt_pk_bf16_f32 v48, v136, v137
	v_add_f32_dpp v17, v17, v17 row_shr:1 row_mask:0xf bank_mask:0xf bound_ctrl:1
	s_nop 1
	v_add_f32_dpp v17, v17, v17 row_shr:2 row_mask:0xf bank_mask:0xf bound_ctrl:1
	s_nop 1
	v_add_f32_dpp v17, v17, v17 row_shr:4 row_mask:0xf bank_mask:0xf bound_ctrl:1
	s_nop 1
	v_add_f32_dpp v17, v17, v17 row_shr:8 row_mask:0xf bank_mask:0xf bound_ctrl:1
	s_nop 1
	v_mov_b32_dpp v49, v17 row_bcast:15 row_mask:0xa bank_mask:0xf
	v_add_f32_e32 v17, v17, v49
	v_mov_b32_e32 v49, v1
	s_nop 1
	v_mov_b32_dpp v49, v17 row_bcast:31 row_mask:0xc bank_mask:0xf
	v_add_f32_e32 v17, v17, v49
	s_nop 0
	v_readlane_b32 s7, v17, 63
	s_nop 1
	v_fma_f32 v17, s7, v217, v213
	v_cmp_gt_f32_e32 vcc, s44, v17
	v_mul_f32_e32 v49, 0x4b800000, v17
	s_nop 0
	v_cndmask_b32_e32 v17, v17, v49, vcc
	v_rsq_f32_e32 v17, v17
	s_nop 0
	v_mul_f32_e32 v49, 0x45800000, v17
	v_cndmask_b32_e32 v92, v17, v49, vcc
	v_mul_f32_e32 v17, v63, v63
	v_fmac_f32_e32 v17, v62, v62
	v_fmac_f32_e32 v17, v64, v64
	v_fmac_f32_e32 v17, v65, v65
	v_fmac_f32_e32 v17, v66, v66
	v_fmac_f32_e32 v17, v67, v67
	v_fmac_f32_e32 v17, v68, v68
	v_fmac_f32_e32 v17, v69, v69
	v_fmac_f32_e32 v17, v70, v70
	v_fmac_f32_e32 v17, v71, v71
	v_fmac_f32_e32 v17, v72, v72
	v_fmac_f32_e32 v17, v73, v73
	v_add_f32_e32 v17, v124, v17
	v_add_f32_e32 v17, v125, v17
	v_add_f32_e32 v17, v122, v17
	v_add_f32_e32 v17, v123, v17
	v_mov_b32_e32 v49, v1
	v_pk_mul_f32 v[124:125], v[40:41], v[40:41]
	v_add_f32_dpp v17, v17, v17 row_shr:1 row_mask:0xf bank_mask:0xf bound_ctrl:1
	v_pk_mul_f32 v[22:23], v[22:23], v[92:93] op_sel_hi:[1,0]
	v_pk_mul_f32 v[74:75], v[74:75], v[92:93] op_sel_hi:[1,0]
	v_add_f32_dpp v17, v17, v17 row_shr:2 row_mask:0xf bank_mask:0xf bound_ctrl:1
	v_pk_fma_f32 v[22:23], v[120:121], v[22:23], v[26:27]
	v_pk_fma_f32 v[74:75], v[110:111], v[74:75], v[50:51]
; __device__ __forceinline__ unsigned pack2(float lo, float hi) { return pg8::cvt_pk_bf16(lo, hi); }
; __device__ __forceinline__ void phase_norm(const Params& p, unsigned char* lds, const float* __restrict__ xin, const float* g, const float* mod  , int shift_off, int scale_off, bf16_t* __restrict__ hout, const float* wsc  , float* scal) {
;     ...
;             for (int q = 0; q < 4; ++q) {
;             const int row = rb + r4 + q;
;             const f32x4 x0 = xq[q][0], x1 = xq[q][1], x2 = xq[q][2], x3 = xq[q][3];
;             float xv[16] = {x0[0], x0[1], x0[2], x0[3], x1[0], x1[1], x1[2], x1[3], x2[0], x2[1], x2[2], x2[3], x3[0], x3[1], x3[2], x3[3]};
;             float ss = 0.f;
; #pragma unroll
;             for (int i = 0; i < 16; ++i) ss += xv[i] * xv[i];
;             ss = wave_sum(ss);
;             const float rstd = rsqrtf(ss * (1.0f / DM) + EPS);
;             float h[16];
; #pragma unroll
;             for (int i = 0; i < 16; ++i) h[i] = xv[i] * rstd * cs[i] + sh[i];
;             u32x4 w0, w1;
;             w0.x = pack2(h[0], h[1]); w0.y = pack2(h[2], h[3]); w0.z = pack2(h[4], h[5]); w0.w = pack2(h[6], h[7]);
;             w1.x = pack2(h[8], h[9]); w1.y = pack2(h[10], h[11]); w1.z = pack2(h[12], h[13]); w1.w = pack2(h[14], h[15]);
;             bf16_t* hp = hout + (size_t)row * DM + lane * 8;
;             *(u32x4*)hp = w0; *(u32x4*)(hp + 512) = w1;
	v_add_f32_dpp v17, v17, v17 row_shr:4 row_mask:0xf bank_mask:0xf bound_ctrl:1
	v_pk_mul_f32 v[76:77], v[76:77], v[92:93] op_sel_hi:[1,0]
	v_pk_mul_f32 v[78:79], v[78:79], v[92:93] op_sel_hi:[1,0]
	v_add_f32_dpp v17, v17, v17 row_shr:8 row_mask:0xf bank_mask:0xf bound_ctrl:1
	v_pk_fma_f32 v[76:77], v[112:113], v[76:77], v[52:53]
	v_pk_mul_f32 v[80:81], v[80:81], v[92:93] op_sel_hi:[1,0]
	v_mov_b32_dpp v49, v17 row_bcast:15 row_mask:0xa bank_mask:0xf
	v_add_f32_e32 v17, v17, v49
	v_mov_b32_e32 v49, v1
	v_pk_fma_f32 v[78:79], v[114:115], v[78:79], v[54:55]
	v_pk_fma_f32 v[80:81], v[116:117], v[80:81], v[56:57]
	v_mov_b32_dpp v49, v17 row_bcast:31 row_mask:0xc bank_mask:0xf
	v_add_f32_e32 v17, v17, v49
	v_pk_mul_f32 v[82:83], v[82:83], v[92:93] op_sel_hi:[1,0]
	v_readlane_b32 s7, v17, 63
	v_pk_mul_f32 v[84:85], v[84:85], v[92:93] op_sel_hi:[1,0]
	v_pk_mul_f32 v[24:25], v[24:25], v[92:93] op_sel_hi:[1,0]
	v_fma_f32 v17, s7, v217, v213
	v_cmp_gt_f32_e32 vcc, s44, v17
	v_mul_f32_e32 v49, 0x4b800000, v17
	v_pk_fma_f32 v[82:83], v[118:119], v[82:83], v[58:59]
	v_cndmask_b32_e32 v17, v17, v49, vcc
	v_rsq_f32_e32 v17, v17
	v_pk_fma_f32 v[84:85], v[86:87], v[84:85], v[60:61]
	v_mul_f32_e32 v49, 0x45800000, v17
	v_cndmask_b32_e32 v122, v17, v49, vcc
	v_mul_f32_e32 v17, v31, v31
	v_fmac_f32_e32 v17, v30, v30
	v_fmac_f32_e32 v17, v32, v32
	v_fmac_f32_e32 v17, v33, v33
	v_fmac_f32_e32 v17, v34, v34
	v_fmac_f32_e32 v17, v35, v35
	v_fmac_f32_e32 v17, v36, v36
	v_fmac_f32_e32 v17, v37, v37
	v_fmac_f32_e32 v17, v42, v42
	v_fmac_f32_e32 v17, v43, v43
	v_fmac_f32_e32 v17, v44, v44
	v_fmac_f32_e32 v17, v45, v45
	v_add_f32_e32 v17, v126, v17
	v_add_f32_e32 v17, v127, v17
	v_add_f32_e32 v17, v124, v17
	v_add_f32_e32 v17, v125, v17
	v_mov_b32_e32 v49, v1
	v_pk_mul_f32 v[18:19], v[18:19], v[122:123] op_sel_hi:[1,0]
	v_add_f32_dpp v17, v17, v17 row_shr:1 row_mask:0xf bank_mask:0xf bound_ctrl:1
	v_pk_mul_f32 v[62:63], v[62:63], v[122:123] op_sel_hi:[1,0]
	v_pk_fma_f32 v[18:19], v[120:121], v[18:19], v[26:27]
	v_add_f32_dpp v17, v17, v17 row_shr:2 row_mask:0xf bank_mask:0xf bound_ctrl:1
	v_pk_fma_f32 v[62:63], v[110:111], v[62:63], v[50:51]
	v_pk_mul_f32 v[64:65], v[64:65], v[122:123] op_sel_hi:[1,0]
	v_add_f32_dpp v17, v17, v17 row_shr:4 row_mask:0xf bank_mask:0xf bound_ctrl:1
	v_pk_fma_f32 v[64:65], v[112:113], v[64:65], v[52:53]
	v_pk_mul_f32 v[66:67], v[66:67], v[122:123] op_sel_hi:[1,0]
	v_add_f32_dpp v17, v17, v17 row_shr:8 row_mask:0xf bank_mask:0xf bound_ctrl:1
	v_pk_fma_f32 v[66:67], v[114:115], v[66:67], v[54:55]
	v_pk_mul_f32 v[68:69], v[68:69], v[122:123] op_sel_hi:[1,0]
	v_mov_b32_dpp v49, v17 row_bcast:15 row_mask:0xa bank_mask:0xf
	v_add_f32_e32 v17, v17, v49
	v_mov_b32_e32 v49, v1
	v_pk_fma_f32 v[68:69], v[116:117], v[68:69], v[56:57]
	v_pk_mul_f32 v[20:21], v[20:21], v[122:123] op_sel_hi:[1,0]
	v_mov_b32_dpp v49, v17 row_bcast:31 row_mask:0xc bank_mask:0xf
	v_add_f32_e32 v17, v17, v49
	v_pk_mul_f32 v[70:71], v[70:71], v[122:123] op_sel_hi:[1,0]
	v_readlane_b32 s7, v17, 63
	v_pk_mul_f32 v[72:73], v[72:73], v[122:123] op_sel_hi:[1,0]
	v_pk_fma_f32 v[70:71], v[118:119], v[70:71], v[58:59]
	v_fma_f32 v17, s7, v217, v213
	v_cmp_gt_f32_e32 vcc, s44, v17
	v_mul_f32_e32 v49, 0x4b800000, v17
	s_movk_i32 s7, 0xec00
	v_cndmask_b32_e32 v17, v17, v49, vcc
	v_rsq_f32_e32 v17, v17
	v_pk_fma_f32 v[72:73], v[86:87], v[72:73], v[60:61]
	v_mul_f32_e32 v49, 0x45800000, v17
	v_cndmask_b32_e32 v90, v17, v49, vcc
	v_pk_mul_f32 v[38:39], v[38:39], v[90:91] op_sel_hi:[1,0]
	v_mov_b32_e32 v109, v90
	v_pk_mul_f32 v[30:31], v[30:31], v[90:91] op_sel_hi:[1,0]
	v_pk_fma_f32 v[26:27], v[120:121], v[38:39], v[26:27]
	v_mul_f32_e32 v38, v40, v90
	v_pk_mul_f32 v[40:41], v[96:97], v[108:109]
	v_pk_fma_f32 v[30:31], v[110:111], v[30:31], v[50:51]
	v_pk_mul_f32 v[32:33], v[32:33], v[90:91] op_sel_hi:[1,0]
	v_pk_mul_f32 v[34:35], v[34:35], v[90:91] op_sel_hi:[1,0]
	v_pk_mul_f32 v[36:37], v[36:37], v[90:91] op_sel_hi:[1,0]
	v_pk_mul_f32 v[42:43], v[42:43], v[90:91] op_sel_hi:[1,0]
	v_pk_mul_f32 v[44:45], v[44:45], v[90:91] op_sel_hi:[1,0]
	v_mov_b32_e32 v50, v88
	v_mov_b32_e32 v51, v40
	v_mov_b32_e32 v90, v89
	v_pk_fma_f32 v[32:33], v[112:113], v[32:33], v[52:53]
	v_pk_fma_f32 v[52:53], v[50:51], v[90:91], v[28:29]
	v_pk_fma_f32 v[34:35], v[114:115], v[34:35], v[54:55]
	v_cvt_pk_bf16_f32 v49, v52, v53
	v_add_co_u32_e32 v52, vcc, s36, v98
	v_cvt_pk_bf16_f32 v54, v22, v23
	s_nop 0
	v_addc_co_u32_e32 v53, vcc, -1, v99, vcc
	v_add_co_u32_e32 v22, vcc, s7, v98
	global_store_dwordx4 v[52:53], v[46:49], off
	s_nop 0
	v_addc_co_u32_e32 v23, vcc, -1, v99, vcc
	v_cvt_pk_bf16_f32 v46, v74, v75
	v_cvt_pk_bf16_f32 v47, v76, v77
	v_cvt_pk_bf16_f32 v48, v78, v79
	v_cvt_pk_bf16_f32 v49, v80, v81
	global_store_dwordx4 v[22:23], v[46:49], off
	v_add_co_u32_e32 v22, vcc, s42, v98
	v_pk_fma_f32 v[24:25], v[50:51], v[24:25], v[28:29]
	s_nop 0
	v_addc_co_u32_e32 v23, vcc, -1, v99, vcc
	s_movk_i32 s7, 0xf400
	v_cvt_pk_bf16_f32 v52, v82, v83
	v_cvt_pk_bf16_f32 v53, v84, v85
	v_cvt_pk_bf16_f32 v55, v24, v25
	v_cvt_pk_bf16_f32 v48, v18, v19
	v_add_co_u32_e32 v18, vcc, s7, v98
	global_store_dwordx4 v[22:23], v[52:55], off
	v_pk_fma_f32 v[24:25], v[50:51], v[20:21], v[28:29]
	v_cvt_pk_bf16_f32 v20, v62, v63
	v_cvt_pk_bf16_f32 v21, v64, v65
	v_cvt_pk_bf16_f32 v22, v66, v67
	v_cvt_pk_bf16_f32 v23, v68, v69
	v_addc_co_u32_e32 v19, vcc, -1, v99, vcc
	global_store_dwordx4 v[18:19], v[20:23], off
	v_add_co_u32_e32 v18, vcc, s75, v98
	v_cvt_pk_bf16_f32 v49, v24, v25
	s_nop 0
	v_addc_co_u32_e32 v19, vcc, -1, v99, vcc
	v_cvt_pk_bf16_f32 v24, v26, v27
	v_add_co_u32_e32 v26, vcc, 0xfffffc00, v98
	v_pk_fma_f32 v[36:37], v[116:117], v[36:37], v[56:57]
	v_cvt_pk_bf16_f32 v46, v70, v71
	v_cvt_pk_bf16_f32 v47, v72, v73
	v_mov_b32_e32 v39, v41
	v_addc_co_u32_e32 v27, vcc, -1, v99, vcc
	v_pk_fma_f32 v[42:43], v[118:119], v[42:43], v[58:59]
	v_pk_fma_f32 v[44:45], v[86:87], v[44:45], v[60:61]
	global_store_dwordx4 v[18:19], v[46:49], off
	v_pk_fma_f32 v[28:29], v[50:51], v[38:39], v[28:29]
	v_cvt_pk_bf16_f32 v18, v30, v31
	v_cvt_pk_bf16_f32 v19, v32, v33
	v_cvt_pk_bf16_f32 v20, v34, v35
	v_cvt_pk_bf16_f32 v21, v36, v37
	v_cmp_lt_i32_e32 vcc, s72, v94
	v_cvt_pk_bf16_f32 v22, v42, v43
	v_cvt_pk_bf16_f32 v23, v44, v45
	v_cvt_pk_bf16_f32 v25, v28, v29
	global_store_dwordx4 v[26:27], v[18:21], off
	global_store_dwordx4 v[98:99], v[22:25], off
	v_lshl_add_u64 v[98:99], v[98:99], 0, s[8:9]
	s_or_b64 s[12:13], vcc, s[12:13]
	s_andn2_b64 exec, exec, s[12:13]
	s_cbranch_execnz .LBB0_133

;     __device__ __forceinline__ void operator()(const f32x4 (&acc)[2][2][4][2], const Unit& u, int wr, int wc, int fr, int fq) const {
;         const int col0 = u.pn * BM + wc * 32 + 4 * fq;
;         const int rbase = row_off + u.pm * BM;
;         const float* gp = gate + (size_t)(rbase >> 13) * 6144 + col0;
;         f32x4 gv[2][2];
; #pragma unroll
;         for (int bj = 0; bj < 2; ++bj)
; #pragma unroll
;             for (int n = 0; n < 2; ++n) gv[bj][n] = *(const f32x4*)(gp + bj * HALF + n * 16);
; #pragma unroll
;         for (int ai = 0; ai < 2; ++ai) {
;             f32x4 bs[4][2][2];
; #pragma unroll
;             for (int m = 0; m < 4; ++m) { const size_t off = (size_t)(rbase + ai * HALF + wr * 64 + m * 16 + fr) * 1024 + col0;
; #pragma unroll
;                 for (int bj = 0; bj < 2; ++bj)
; #pragma unroll
;                     for (int n = 0; n < 2; ++n) bs[m][bj][n] = *(const f32x4*)(base + off + bj * HALF + n * 16); }
;             __builtin_amdgcn_sched_barrier(0);
; #pragma unroll
;             for (int m = 0; m < 4; ++m) { const size_t off = (size_t)(rbase + ai * HALF + wr * 64 + m * 16 + fr) * 1024 + col0;
; #pragma unroll
;                 for (int bj = 0; bj < 2; ++bj)
; #pragma unroll
;                     for (int n = 0; n < 2; ++n) *(f32x4*)(out + off + bj * HALF + n * 16) = bs[m][bj][n] + gv[bj][n] * acc[ai][bj][m][n]; }
.LBB0_156:
	s_lshr_b32 s11, s22, 5
	s_mul_i32 s24, s11, 0x1800
	s_ashr_i32 s25, s24, 31
	v_lshl_or_b32 v130, s77, 8, v160
	s_lshl_b64 s[24:25], s[24:25], 2
	s_add_u32 s24, s55, s24
	v_ashrrev_i32_e32 v131, 31, v130
	s_addc_u32 s25, s72, s25
	v_lshlrev_b64 v[152:153], 2, v[130:131]
	v_lshl_add_u32 v156, s22, 8, v158
	v_lshl_add_u64 v[130:131], s[24:25], 0, v[152:153]
	v_readlane_b32 s24, v255, 5
	v_or_b32_e32 v186, 16, v156
	v_or_b32_e32 v202, 32, v156
	v_or_b32_e32 v232, 48, v156
	v_readlane_b32 s25, v255, 6
	v_ashrrev_i32_e32 v157, 31, v156
	v_ashrrev_i32_e32 v187, 31, v186
	v_ashrrev_i32_e32 v203, 31, v202
	v_ashrrev_i32_e32 v233, 31, v232
	v_lshl_add_u64 v[154:155], s[24:25], 0, v[152:153]
	v_lshlrev_b64 v[210:211], 12, v[156:157]
	v_lshlrev_b64 v[248:249], 12, v[186:187]
	v_lshlrev_b64 v[250:251], 12, v[202:203]
	v_lshlrev_b64 v[252:253], 12, v[232:233]
	v_lshl_add_u64 v[182:183], v[154:155], 0, v[210:211]
	v_lshl_add_u64 v[198:199], v[154:155], 0, v[248:249]
	v_lshl_add_u64 v[228:229], v[154:155], 0, v[250:251]
	v_lshl_add_u64 v[244:245], v[154:155], 0, v[252:253]
	global_load_dwordx4 v[142:145], v[130:131], off
	global_load_dwordx4 v[138:141], v[130:131], off offset:64
	global_load_dwordx4 v[134:137], v[130:131], off offset:512
	s_nop 0
	global_load_dwordx4 v[130:133], v[130:131], off offset:576
	s_nop 0
	global_load_dwordx4 v[162:165], v[182:183], off
	global_load_dwordx4 v[166:169], v[182:183], off offset:64
	global_load_dwordx4 v[178:181], v[182:183], off offset:512
	s_nop 0
	global_load_dwordx4 v[182:185], v[182:183], off offset:576
	s_nop 0
	global_load_dwordx4 v[186:189], v[198:199], off
	global_load_dwordx4 v[190:193], v[198:199], off offset:64
	global_load_dwordx4 v[194:197], v[198:199], off offset:512
	s_nop 0
	global_load_dwordx4 v[198:201], v[198:199], off offset:576
	s_nop 0
	global_load_dwordx4 v[202:205], v[228:229], off
	global_load_dwordx4 v[206:209], v[228:229], off offset:64
	global_load_dwordx4 v[224:227], v[228:229], off offset:512
	s_nop 0
	global_load_dwordx4 v[228:231], v[228:229], off offset:576
	s_nop 0
	global_load_dwordx4 v[232:235], v[244:245], off
	global_load_dwordx4 v[236:239], v[244:245], off offset:64
	global_load_dwordx4 v[240:243], v[244:245], off offset:512
	s_nop 0
	global_load_dwordx4 v[244:247], v[244:245], off offset:576
	s_waitcnt vmcnt(0) lgkmcnt(0)
	v_pk_fma_f32 v[126:127], v[126:127], v[142:143], v[162:163]
	v_lshl_add_u64 v[162:163], s[18:19], 0, v[210:211]
	v_lshl_add_u64 v[162:163], v[162:163], 0, v[152:153]
	v_pk_fma_f32 v[116:117], v[116:117], v[136:137], v[180:181]
	v_pk_fma_f32 v[114:115], v[114:115], v[134:135], v[178:179]
	global_store_dwordx4 v[162:163], v[114:117], off offset:512
	v_pk_fma_f32 v[100:101], v[100:101], v[136:137], v[196:197]
	v_pk_fma_f32 v[98:99], v[98:99], v[134:135], v[194:195]
	v_lshl_add_u64 v[114:115], s[18:19], 0, v[248:249]
	v_lshl_add_u64 v[114:115], v[114:115], 0, v[152:153]
	global_store_dwordx4 v[114:115], v[98:101], off offset:512
	v_pk_fma_f32 v[84:85], v[84:85], v[136:137], v[226:227]
	v_pk_fma_f32 v[82:83], v[82:83], v[134:135], v[224:225]
	v_lshl_add_u64 v[98:99], s[18:19], 0, v[250:251]
	v_lshl_add_u64 v[98:99], v[98:99], 0, v[152:153]
	v_pk_fma_f32 v[108:109], v[108:109], v[132:133], v[184:185]
	v_pk_fma_f32 v[106:107], v[106:107], v[130:131], v[182:183]
	v_pk_fma_f32 v[92:93], v[92:93], v[132:133], v[200:201]
	v_pk_fma_f32 v[90:91], v[90:91], v[130:131], v[198:199]
	global_store_dwordx4 v[98:99], v[82:85], off offset:512
	v_pk_fma_f32 v[76:77], v[76:77], v[132:133], v[230:231]
	v_pk_fma_f32 v[74:75], v[74:75], v[130:131], v[228:229]
	v_lshl_add_u64 v[82:83], s[18:19], 0, v[252:253]
	global_store_dwordx4 v[162:163], v[106:109], off offset:576
	global_store_dwordx4 v[114:115], v[90:93], off offset:576
	global_store_dwordx4 v[98:99], v[74:77], off offset:576
	v_pk_fma_f32 v[108:109], v[120:121], v[144:145], v[188:189]
	v_pk_fma_f32 v[106:107], v[118:119], v[142:143], v[186:187]
	v_pk_fma_f32 v[92:93], v[104:105], v[144:145], v[204:205]
	v_pk_fma_f32 v[90:91], v[102:103], v[142:143], v[202:203]
	v_pk_fma_f32 v[76:77], v[88:89], v[144:145], v[234:235]
	v_pk_fma_f32 v[74:75], v[86:87], v[142:143], v[232:233]
	v_lshl_add_u64 v[82:83], v[82:83], 0, v[152:153]
	v_pk_fma_f32 v[128:129], v[128:129], v[144:145], v[164:165]
	v_pk_fma_f32 v[124:125], v[124:125], v[140:141], v[168:169]
	v_pk_fma_f32 v[122:123], v[122:123], v[138:139], v[166:167]
	global_store_dwordx4 v[114:115], v[106:109], off
	global_store_dwordx4 v[98:99], v[90:93], off
	global_store_dwordx4 v[82:83], v[74:77], off
	v_pk_fma_f32 v[108:109], v[112:113], v[140:141], v[192:193]
	v_pk_fma_f32 v[106:107], v[110:111], v[138:139], v[190:191]
	v_pk_fma_f32 v[92:93], v[96:97], v[140:141], v[208:209]
	v_pk_fma_f32 v[90:91], v[94:95], v[138:139], v[206:207]
	v_pk_fma_f32 v[76:77], v[80:81], v[140:141], v[238:239]
	v_pk_fma_f32 v[74:75], v[78:79], v[138:139], v[236:237]
	v_pk_fma_f32 v[72:73], v[72:73], v[136:137], v[242:243]
	v_pk_fma_f32 v[70:71], v[70:71], v[134:135], v[240:241]
	v_pk_fma_f32 v[68:69], v[68:69], v[132:133], v[246:247]
	v_pk_fma_f32 v[66:67], v[66:67], v[130:131], v[244:245]
	global_store_dwordx4 v[162:163], v[126:129], off
;     __device__ __forceinline__ void operator()(const f32x4 (&acc)[2][2][4][2], const Unit& u, int wr, int wc, int fr, int fq) const {
;     ...
;             for (int m = 0; m < 4; ++m) { const size_t off = (size_t)(rbase + ai * HALF + wr * 64 + m * 16 + fr) * 1024 + col0;
; #pragma unroll
;                 for (int bj = 0; bj < 2; ++bj)
; #pragma unroll
;                     for (int n = 0; n < 2; ++n) bs[m][bj][n] = *(const f32x4*)(base + off + bj * HALF + n * 16); }
;             __builtin_amdgcn_sched_barrier(0);
; #pragma unroll
;             for (int m = 0; m < 4; ++m) { const size_t off = (size_t)(rbase + ai * HALF + wr * 64 + m * 16 + fr) * 1024 + col0;
; #pragma unroll
;                 for (int bj = 0; bj < 2; ++bj)
; #pragma unroll
;                     for (int n = 0; n < 2; ++n) *(f32x4*)(out + off + bj * HALF + n * 16) = bs[m][bj][n] + gv[bj][n] * acc[ai][bj][m][n]; }
;             __builtin_amdgcn_sched_barrier(0);
;         }
	global_store_dwordx4 v[162:163], v[122:125], off offset:64
	global_store_dwordx4 v[114:115], v[106:109], off offset:64
	global_store_dwordx4 v[98:99], v[90:93], off offset:64
	global_store_dwordx4 v[82:83], v[74:77], off offset:64
	global_store_dwordx4 v[82:83], v[70:73], off offset:512
	global_store_dwordx4 v[82:83], v[66:69], off offset:576
	s_nop 1
	v_add_u32_e32 v66, 0x80, v156
	v_add_u32_e32 v82, 0x90, v156
	v_add_u32_e32 v98, 0xa0, v156
	v_add_u32_e32 v114, 0xb0, v156
	v_ashrrev_i32_e32 v67, 31, v66
	v_ashrrev_i32_e32 v83, 31, v82
	v_ashrrev_i32_e32 v99, 31, v98
	v_ashrrev_i32_e32 v115, 31, v114
	v_lshlrev_b64 v[162:163], 12, v[66:67]
	v_lshlrev_b64 v[164:165], 12, v[82:83]
	v_lshlrev_b64 v[166:167], 12, v[98:99]
	v_lshlrev_b64 v[156:157], 12, v[114:115]
	v_lshl_add_u64 v[78:79], v[154:155], 0, v[162:163]
	v_lshl_add_u64 v[94:95], v[154:155], 0, v[164:165]
	v_lshl_add_u64 v[110:111], v[154:155], 0, v[166:167]
	v_lshl_add_u64 v[126:127], v[154:155], 0, v[156:157]
	global_load_dwordx4 v[66:69], v[78:79], off
	global_load_dwordx4 v[70:73], v[78:79], off offset:64
	global_load_dwordx4 v[74:77], v[78:79], off offset:512
	s_nop 0
	global_load_dwordx4 v[78:81], v[78:79], off offset:576
	s_nop 0
	global_load_dwordx4 v[82:85], v[94:95], off
	global_load_dwordx4 v[86:89], v[94:95], off offset:64
	global_load_dwordx4 v[90:93], v[94:95], off offset:512
	s_nop 0
	global_load_dwordx4 v[94:97], v[94:95], off offset:576
	s_nop 0
	global_load_dwordx4 v[98:101], v[110:111], off
	global_load_dwordx4 v[102:105], v[110:111], off offset:64
	global_load_dwordx4 v[106:109], v[110:111], off offset:512
	s_nop 0
	global_load_dwordx4 v[110:113], v[110:111], off offset:576
	s_nop 0
	global_load_dwordx4 v[114:117], v[126:127], off
	global_load_dwordx4 v[118:121], v[126:127], off offset:64
	global_load_dwordx4 v[122:125], v[126:127], off offset:512
	s_nop 0
	global_load_dwordx4 v[126:129], v[126:127], off offset:576
	s_waitcnt vmcnt(0) lgkmcnt(0)
	v_pk_fma_f32 v[62:63], v[62:63], v[142:143], v[66:67]
	v_lshl_add_u64 v[66:67], s[18:19], 0, v[162:163]
	v_lshl_add_u64 v[66:67], v[66:67], 0, v[152:153]
	v_pk_fma_f32 v[52:53], v[52:53], v[136:137], v[76:77]
	v_pk_fma_f32 v[50:51], v[50:51], v[134:135], v[74:75]
	global_store_dwordx4 v[66:67], v[50:53], off offset:512
	v_pk_fma_f32 v[36:37], v[36:37], v[136:137], v[92:93]
	v_pk_fma_f32 v[34:35], v[34:35], v[134:135], v[90:91]
	v_lshl_add_u64 v[50:51], s[18:19], 0, v[164:165]
	v_lshl_add_u64 v[50:51], v[50:51], 0, v[152:153]
	global_store_dwordx4 v[50:51], v[34:37], off offset:512
	v_pk_fma_f32 v[20:21], v[20:21], v[136:137], v[108:109]
	v_pk_fma_f32 v[18:19], v[18:19], v[134:135], v[106:107]
	v_lshl_add_u64 v[34:35], s[18:19], 0, v[166:167]
	v_lshl_add_u64 v[34:35], v[34:35], 0, v[152:153]
	v_pk_fma_f32 v[44:45], v[44:45], v[132:133], v[80:81]
	v_pk_fma_f32 v[42:43], v[42:43], v[130:131], v[78:79]
	v_pk_fma_f32 v[28:29], v[28:29], v[132:133], v[96:97]
	v_pk_fma_f32 v[26:27], v[26:27], v[130:131], v[94:95]
	global_store_dwordx4 v[34:35], v[18:21], off offset:512
	v_pk_fma_f32 v[12:13], v[12:13], v[132:133], v[112:113]
	v_pk_fma_f32 v[10:11], v[10:11], v[130:131], v[110:111]
	v_lshl_add_u64 v[18:19], s[18:19], 0, v[156:157]
	global_store_dwordx4 v[66:67], v[42:45], off offset:576
	global_store_dwordx4 v[50:51], v[26:29], off offset:576
	global_store_dwordx4 v[34:35], v[10:13], off offset:576
	v_pk_fma_f32 v[44:45], v[56:57], v[144:145], v[84:85]
	v_pk_fma_f32 v[42:43], v[54:55], v[142:143], v[82:83]
	v_pk_fma_f32 v[28:29], v[40:41], v[144:145], v[100:101]
	v_pk_fma_f32 v[26:27], v[38:39], v[142:143], v[98:99]
	v_pk_fma_f32 v[12:13], v[24:25], v[144:145], v[116:117]
	v_pk_fma_f32 v[10:11], v[22:23], v[142:143], v[114:115]
	v_lshl_add_u64 v[18:19], v[18:19], 0, v[152:153]
	v_pk_fma_f32 v[64:65], v[64:65], v[144:145], v[68:69]
	v_pk_fma_f32 v[60:61], v[60:61], v[140:141], v[72:73]
	v_pk_fma_f32 v[58:59], v[58:59], v[138:139], v[70:71]
	global_store_dwordx4 v[50:51], v[42:45], off
	global_store_dwordx4 v[34:35], v[26:29], off
	global_store_dwordx4 v[18:19], v[10:13], off
	v_pk_fma_f32 v[44:45], v[48:49], v[140:141], v[88:89]
	v_pk_fma_f32 v[42:43], v[46:47], v[138:139], v[86:87]
	v_pk_fma_f32 v[28:29], v[32:33], v[140:141], v[104:105]
	v_pk_fma_f32 v[26:27], v[30:31], v[138:139], v[102:103]
	v_pk_fma_f32 v[12:13], v[16:17], v[140:141], v[120:121]
	v_pk_fma_f32 v[10:11], v[14:15], v[138:139], v[118:119]
	v_pk_fma_f32 v[8:9], v[8:9], v[136:137], v[124:125]
	v_pk_fma_f32 v[6:7], v[6:7], v[134:135], v[122:123]
	v_pk_fma_f32 v[4:5], v[4:5], v[132:133], v[128:129]
	v_pk_fma_f32 v[2:3], v[2:3], v[130:131], v[126:127]
	global_store_dwordx4 v[66:67], v[62:65], off
	global_store_dwordx4 v[66:67], v[58:61], off offset:64
	global_store_dwordx4 v[50:51], v[42:45], off offset:64
	global_store_dwordx4 v[34:35], v[26:29], off offset:64
	global_store_dwordx4 v[18:19], v[10:13], off offset:64
	global_store_dwordx4 v[18:19], v[6:9], off offset:512
	global_store_dwordx4 v[18:19], v[2:5], off offset:576
	s_andn2_b64 vcc, exec, s[6:7]
	s_mov_b64 s[6:7], -1
	s_cbranch_vccnz .LBB0_145
	s_andn2_b64 vcc, exec, s[0:1]
	s_cbranch_vccnz .LBB0_144
	s_barrier
	s_branch .LBB0_144

; __device__ __forceinline__ int my_tid() { int t = (int)threadIdx.x; asm volatile("" : "+v"(t)); return t; }
; __device__ __forceinline__ int my_bid() { int t = (int)blockIdx.x; asm volatile("" : "+s"(t)); return t; }
; __device__ __forceinline__ int my_gdim() { int t = (int)gridDim.x; asm volatile("" : "+s"(t)); return t; }
; __device__ void phase_finalize(const unsigned char* __restrict__ prep, const bf16_t* __restrict__ pz, const float* gn, bf16_t* __restrict__ mix) {
;     const int tid = my_tid(), wid = tid >> 6, lane = tid & 63;
;     const int gw = my_bid() * 8 + wid, nw = my_gdim() * 8;
;     const int hh = lane >> 4, d0 = (lane & 15) * 8;
;     float gv[8];
; #pragma unroll
;     for (int j = 0; j < 8; ++j) gv[j] = gn[d0 + j];
;     for (int rb = gw * 4; rb < MTOK; rb += nw * 4) {
;         u32x4 oq[4], zq[4];
; #pragma unroll
;         for (int q = 0; q < 4; ++q) { const int row = rb + q, b = row >> 13, t = row & (SEQ - 1), n = t >> 6, c = t & 63;
;             oq[q] = __builtin_nontemporal_load((const u32x4*)(prep + (size_t)(((b * 4 + hh) * 128) + n) * PREP_UNIT + 57344 + (d0 >> 6) * 8192 + (c * 64 + (d0 & 63)) * 2));
;             zq[q] = __builtin_nontemporal_load((const u32x4*)(pz + (size_t)row * 512 + lane * 8)); }
; #pragma unroll
.LBB0_162:
	s_and_b64 vcc, exec, s[0:1]
	s_cbranch_vccz .LBB0_699
	s_cmp_gt_i32 s59, 1
	s_mov_b64 s[0:1], -1
	s_cbranch_scc0 .LBB0_666
	s_cmp_gt_i32 s59, 2
	s_cbranch_scc0 .LBB0_169
	s_waitcnt vmcnt(0)
	v_mov_b32_e32 v11, v212
	v_readlane_b32 s0, v254, 0
	v_ashrrev_i32_e32 v10, 4, v11
	v_and_b32_e32 v0, -4, v10
	s_mov_b32 s6, 0x8000
	v_lshl_add_u32 v34, s0, 5, v0
	s_load_dword s1, s[80:81], 0x0
	v_cmp_gt_i32_e32 vcc, s6, v34
	s_waitcnt lgkmcnt(0)
	s_and_saveexec_b64 s[6:7], vcc
	s_mov_b32 s14, 0x3600000
	s_mov_b32 s15, 0x3601000
	s_brev_b32 s18, 60
	s_cbranch_execz .LBB0_168
	v_readlane_b32 s8, v255, 3
	v_readlane_b32 s9, v255, 4
	s_lshl_b32 s8, s8, 7
	s_ashr_i32 s9, s8, 31
	s_lshl_b64 s[8:9], s[8:9], 2
	s_add_u32 s4, s4, s8
	v_lshlrev_b32_e32 v0, 5, v11
	s_addc_u32 s5, s5, s9
	v_and_b32_e32 v0, 0x1e0, v0
	v_lshl_add_u64 v[6:7], s[4:5], 0, v[0:1]
	global_load_dwordx4 v[2:5], v[6:7], off
	s_nop 0
	global_load_dwordx4 v[6:9], v[6:7], off offset:16
	v_lshlrev_b32_e32 v0, 3, v11
	v_and_b32_e32 v12, 63, v11
	v_bfe_u32 v68, v11, 4, 2
	v_lshlrev_b32_e32 v11, 10, v11
	v_and_b32_e32 v36, 0x2000, v11
	v_and_b32_e32 v11, 64, v218
	v_and_b32_e32 v69, 56, v0
	v_xor_b32_e32 v0, 1, v218
	v_add_u32_e32 v11, 64, v11
	v_cmp_lt_i32_e32 vcc, v0, v11
	v_ashrrev_i32_e32 v35, 31, v34
	s_lshl_b32 s4, s1, 5
	v_cndmask_b32_e32 v0, v218, v0, vcc
	v_lshlrev_b32_e32 v70, 2, v0
	v_xor_b32_e32 v0, 2, v218
	v_cmp_lt_i32_e32 vcc, v0, v11
	v_lshlrev_b32_e32 v38, 4, v12
	v_lshlrev_b64 v[12:13], 11, v[34:35]
	v_cndmask_b32_e32 v0, v218, v0, vcc
	v_lshlrev_b32_e32 v71, 2, v0
	v_xor_b32_e32 v0, 4, v218
	v_cmp_lt_i32_e32 vcc, v0, v11
	v_lshl_add_u64 v[40:41], s[86:87], 0, v[12:13]
	s_ashr_i32 s5, s4, 31
	v_cndmask_b32_e32 v0, v218, v0, vcc
	v_lshlrev_b32_e32 v72, 2, v0
	v_xor_b32_e32 v0, 8, v218
	v_cmp_lt_i32_e32 vcc, v0, v11
	v_lshlrev_b64 v[12:13], 10, v[34:35]
	v_mov_b32_e32 v37, v1
	v_cndmask_b32_e32 v0, v218, v0, vcc
	v_lshlrev_b32_e32 v73, 2, v0
	v_lshlrev_b32_e32 v0, 6, v10
	v_and_b32_e32 v0, 0xffffff00, v0
	v_mov_b32_e32 v39, v1
	s_lshl_b64 s[8:9], s[4:5], 11
	v_lshl_add_u64 v[42:43], s[86:87], 0, v[12:13]
	s_lshl_b64 s[10:11], s[4:5], 10
	v_lshl_add_u32 v35, s0, 11, v0
	s_lshl_b32 s5, s1, 11
	s_mov_b64 s[12:13], 0
.LBB0_167:
	v_ashrrev_i32_e32 v10, 11, v34
	s_mov_b32 s0, 0x1fffffc
	v_bfe_u32 v0, v34, 6, 7
	v_and_or_b32 v10, v10, s0, v68
	v_lshl_or_b32 v0, v10, 7, v0
	v_mov_b64_e32 v[10:11], s[86:87]
	v_mad_i64_i32 v[10:11], s[0:1], v0, s73, v[10:11]
	v_lshl_add_u64 v[10:11], v[10:11], 0, v[36:37]
	s_mov_b64 s[0:1], 0x1560e000
	v_lshl_add_u64 v[10:11], v[10:11], 0, s[0:1]
	s_movk_i32 s0, 0xf00
	v_and_or_b32 v0, v35, s0, v69
	v_lshlrev_b32_e32 v0, 1, v0
	v_lshl_add_u64 v[12:13], v[10:11], 0, v[0:1]
	global_load_dwordx4 v[56:59], v[12:13], off nt
	v_lshl_add_u64 v[12:13], v[42:43], 0, v[38:39]
	s_mov_b32 s0, 0x13600000
	v_add_co_u32_e32 v12, vcc, s0, v12
	v_add_u32_e32 v0, 64, v35
	s_nop 0
	v_addc_co_u32_e32 v13, vcc, 0, v13, vcc
	global_load_dwordx4 v[74:77], v[12:13], off nt
	s_movk_i32 s0, 0xf40
	v_and_or_b32 v0, v0, s0, v69
	v_lshlrev_b32_e32 v0, 1, v0
	v_lshl_add_u64 v[14:15], v[10:11], 0, v[0:1]
	global_load_dwordx4 v[30:33], v[14:15], off nt
	global_load_dwordx4 v[26:29], v[12:13], off offset:1024 nt
	v_add_u32_e32 v0, 0x80, v35
	s_movk_i32 s0, 0xf80
	v_and_or_b32 v0, v0, s0, v69
	v_lshlrev_b32_e32 v0, 1, v0
	v_lshl_add_u64 v[14:15], v[10:11], 0, v[0:1]
	v_add_u32_e32 v0, 0xc0, v35
	s_movk_i32 s0, 0xfc0
	v_and_or_b32 v0, v0, s0, v69
	v_lshlrev_b32_e32 v0, 1, v0
	v_lshl_add_u64 v[10:11], v[10:11], 0, v[0:1]
	global_load_dwordx4 v[22:25], v[14:15], off nt
	global_load_dwordx4 v[18:21], v[12:13], off offset:2048 nt
	s_mov_b32 s0, 0x358637bd
	global_load_dwordx4 v[14:17], v[10:11], off nt
	s_nop 0
	global_load_dwordx4 v[10:13], v[12:13], off offset:3072 nt
	v_add_u32_e32 v34, s4, v34
	v_lshl_add_u64 v[42:43], v[42:43], 0, s[10:11]
	v_add_u32_e32 v35, s5, v35
	s_waitcnt vmcnt(0) lgkmcnt(0)
	v_lshlrev_b32_e32 v46, 16, v58
	v_and_b32_e32 v47, 0xffff0000, v58
	v_lshlrev_b32_e32 v44, 16, v59
	v_and_b32_e32 v45, 0xffff0000, v59
	v_pk_mul_f32 v[64:65], v[46:47], v[46:47]
	v_pk_mul_f32 v[60:61], v[44:45], v[44:45]
	v_lshlrev_b32_e32 v48, 16, v76
	v_mul_f32_e32 v0, 0xbfb8aa3b, v48
	v_exp_f32_e32 v0, v0
	v_and_b32_e32 v49, 0xffff0000, v76
	v_lshlrev_b32_e32 v52, 16, v75
	v_and_b32_e32 v53, 0xffff0000, v75
	v_add_f32_e32 v0, 1.0, v0
	v_rcp_f32_e32 v50, v0
	v_mul_f32_e32 v0, 0xbfb8aa3b, v49
	v_exp_f32_e32 v0, v0
	v_lshlrev_b32_e32 v62, 16, v77
	v_and_b32_e32 v63, 0xffff0000, v77
	v_lshlrev_b32_e32 v82, 16, v28
	v_add_f32_e32 v0, 1.0, v0
	v_rcp_f32_e32 v51, v0
	v_mul_f32_e32 v0, 0xbfb8aa3b, v52
	v_exp_f32_e32 v0, v0
	v_and_b32_e32 v83, 0xffff0000, v28
	v_pk_mul_f32 v[48:49], v[50:51], v[48:49]
	v_lshlrev_b32_e32 v50, 16, v57
	v_add_f32_e32 v0, 1.0, v0
	v_rcp_f32_e32 v54, v0
	v_mul_f32_e32 v0, 0xbfb8aa3b, v53
	v_exp_f32_e32 v0, v0
	v_and_b32_e32 v51, 0xffff0000, v57
	v_and_b32_e32 v57, 0xffff0000, v74
	v_lshlrev_b32_e32 v86, 16, v27
	v_add_f32_e32 v0, 1.0, v0
	v_rcp_f32_e32 v55, v0
	v_lshlrev_b32_e32 v78, 16, v29
	v_and_b32_e32 v79, 0xffff0000, v29
	v_and_b32_e32 v87, 0xffff0000, v27
	v_pk_mul_f32 v[52:53], v[54:55], v[52:53]
	v_lshlrev_b32_e32 v54, 16, v56
	v_and_b32_e32 v55, 0xffff0000, v56
	v_lshlrev_b32_e32 v56, 16, v74
	v_mul_f32_e32 v0, 0xbfb8aa3b, v56
	v_exp_f32_e32 v0, v0
	v_lshlrev_b32_e32 v84, 16, v31
	v_and_b32_e32 v85, 0xffff0000, v31
	v_and_b32_e32 v31, 0xffff0000, v26
	v_add_f32_e32 v0, 1.0, v0
	v_rcp_f32_e32 v58, v0
	v_mul_f32_e32 v0, 0xbfb8aa3b, v57
	v_exp_f32_e32 v0, v0
	v_mov_b32_e32 v91, v55
	v_pk_mul_f32 v[66:67], v[50:51], v[50:51]
	v_lshlrev_b32_e32 v80, 16, v32
; __device__ __forceinline__ unsigned pack2(float lo, float hi) { return pg8::cvt_pk_bf16(lo, hi); }
; __device__ __forceinline__ float silu_f(float x) { return x * __builtin_amdgcn_rcpf(1.0f + __expf(-x)); }
; __device__ void phase_finalize(const unsigned char* __restrict__ prep, const bf16_t* __restrict__ pz, const float* gn, bf16_t* __restrict__ mix) {
;     ...
;         for (int q = 0; q < 4; ++q) { const int row = rb + q;
;             float ov[8]; unpack8(oq[q], ov);
;             float ss = 0.f;
; #pragma unroll
;             for (int j = 0; j < 8; ++j) ss += ov[j] * ov[j];
;             ss += __shfl_xor(ss, 1); ss += __shfl_xor(ss, 2); ss += __shfl_xor(ss, 4); ss += __shfl_xor(ss, 8);
;             const float rstd = rsqrtf(ss * (1.0f / 128.0f) + EPS);
;             float zf[8]; unpack8(zq[q], zf);
;             float r[8];
; #pragma unroll
;             for (int j = 0; j < 8; ++j) r[j] = ov[j] * rstd * gv[j] * silu_f(zf[j]);
;             u32x4 w; w.x = pack2(r[0], r[1]); w.y = pack2(r[2], r[3]); w.z = pack2(r[4], r[5]); w.w = pack2(r[6], r[7]);
;             *(u32x4*)(mix + (size_t)row * DM + 512 + lane * 8) = w; }
	v_add_f32_e32 v0, 1.0, v0
	v_rcp_f32_e32 v59, v0
	v_mul_f32_e32 v0, 0xbfb8aa3b, v62
	v_exp_f32_e32 v0, v0
	v_and_b32_e32 v81, 0xffff0000, v32
	v_pk_mul_f32 v[56:57], v[58:59], v[56:57]
	v_lshlrev_b32_e32 v74, 16, v33
	v_add_f32_e32 v0, 1.0, v0
	v_rcp_f32_e32 v58, v0
	v_mul_f32_e32 v0, 0xbfb8aa3b, v63
	v_exp_f32_e32 v0, v0
	v_and_b32_e32 v75, 0xffff0000, v33
	v_pk_mul_f32 v[32:33], v[80:81], v[80:81]
	v_pk_mul_f32 v[76:77], v[74:75], v[74:75]
	v_add_f32_e32 v0, 1.0, v0
	v_rcp_f32_e32 v59, v0
	v_mul_f32_e32 v0, 0xbfb8aa3b, v82
	v_exp_f32_e32 v0, v0
	v_pk_mul_f32 v[58:59], v[58:59], v[62:63]
	v_lshl_add_u64 v[62:63], v[40:41], 0, v[38:39]
	v_add_f32_e32 v0, 1.0, v0
	v_rcp_f32_e32 v28, v0
	v_mul_f32_e32 v0, 0xbfb8aa3b, v83
	v_exp_f32_e32 v0, v0
	v_lshl_add_u64 v[40:41], v[40:41], 0, s[8:9]
	v_add_f32_e32 v0, 1.0, v0
	v_rcp_f32_e32 v29, v0
	v_mul_f32_e32 v0, 0xbfb8aa3b, v86
	v_exp_f32_e32 v0, v0
	v_pk_mul_f32 v[82:83], v[28:29], v[82:83]
	v_pk_mul_f32 v[28:29], v[84:85], v[84:85]
	v_add_f32_e32 v0, 1.0, v0
	v_rcp_f32_e32 v88, v0
	v_mul_f32_e32 v0, 0xbfb8aa3b, v87
	v_exp_f32_e32 v0, v0
	s_nop 0
	v_add_f32_e32 v0, 1.0, v0
	v_rcp_f32_e32 v89, v0
	s_nop 0
	v_pk_mul_f32 v[86:87], v[88:89], v[86:87]
	v_lshlrev_b32_e32 v88, 16, v30
	v_and_b32_e32 v89, 0xffff0000, v30
	v_lshlrev_b32_e32 v30, 16, v26
	v_mul_f32_e32 v0, 0xbfb8aa3b, v30
	v_exp_f32_e32 v0, v0
	v_mov_b32_e32 v90, v89
	v_pk_mul_f32 v[90:91], v[90:91], v[90:91]
	v_add_f32_e32 v0, 1.0, v0
	v_rcp_f32_e32 v26, v0
	v_mul_f32_e32 v0, 0xbfb8aa3b, v31
	v_exp_f32_e32 v0, v0
	s_nop 0
	v_add_f32_e32 v0, 1.0, v0
	v_rcp_f32_e32 v27, v0
	s_nop 0
	v_pk_mul_f32 v[30:31], v[26:27], v[30:31]
	v_mov_b32_e32 v26, v88
	v_mov_b32_e32 v27, v54
	v_pk_fma_f32 v[26:27], v[26:27], v[26:27], v[90:91]
	v_mov_b32_e32 v90, v28
	v_mov_b32_e32 v91, v66
	v_pk_add_f32 v[26:27], v[90:91], v[26:27]
	v_mov_b32_e32 v66, v29
	v_pk_add_f32 v[26:27], v[66:67], v[26:27]
	v_mov_b32_e32 v28, v32
	v_mov_b32_e32 v29, v64
	v_pk_add_f32 v[26:27], v[28:29], v[26:27]
	v_mov_b32_e32 v64, v33
	v_pk_add_f32 v[26:27], v[64:65], v[26:27]
	v_mov_b32_e32 v28, v76
	v_mov_b32_e32 v29, v60
	v_pk_add_f32 v[26:27], v[28:29], v[26:27]
	v_mov_b32_e32 v60, v77
	v_pk_add_f32 v[26:27], v[60:61], v[26:27]
	ds_bpermute_b32 v29, v70, v27
	ds_bpermute_b32 v28, v70, v26
	v_mov_b64_e32 v[32:33], s[0:1]
	v_lshlrev_b32_e32 v66, 16, v11
	v_and_b32_e32 v67, 0xffff0000, v11
	v_lshlrev_b32_e32 v64, 16, v15
	s_waitcnt lgkmcnt(0)
	v_pk_add_f32 v[26:27], v[26:27], v[28:29]
	ds_bpermute_b32 v29, v71, v27
	ds_bpermute_b32 v28, v71, v26
	v_and_b32_e32 v65, 0xffff0000, v15
	v_and_b32_e32 v15, 0xffff0000, v10
	s_waitcnt lgkmcnt(0)
	v_pk_add_f32 v[26:27], v[26:27], v[28:29]
	ds_bpermute_b32 v29, v72, v27
	ds_bpermute_b32 v28, v72, v26
	s_waitcnt lgkmcnt(0)
	v_pk_add_f32 v[26:27], v[26:27], v[28:29]
	ds_bpermute_b32 v29, v73, v27
	ds_bpermute_b32 v28, v73, v26
	s_waitcnt lgkmcnt(0)
	v_pk_add_f32 v[26:27], v[26:27], v[28:29]
	s_nop 0
	v_pk_fma_f32 v[60:61], v[26:27], s[18:19], v[32:33] op_sel_hi:[1,0,0]
	s_nop 0
	v_mul_f32_e32 v0, 0x4b800000, v61
	v_cmp_gt_f32_e64 s[0:1], s44, v61
	v_cmp_gt_f32_e32 vcc, s44, v60
	s_nop 0
	v_cndmask_b32_e64 v0, v61, v0, s[0:1]
	v_rsq_f32_e32 v0, v0
	v_and_b32_e32 v61, 0xffff0000, v12
	v_mul_f32_e32 v26, 0x45800000, v0
	v_cndmask_b32_e64 v0, v0, v26, s[0:1]
	v_pk_mul_f32 v[26:27], v[0:1], v[54:55] op_sel_hi:[0,1]
	v_pk_mul_f32 v[28:29], v[0:1], v[50:51] op_sel_hi:[0,1]
	v_pk_mul_f32 v[46:47], v[0:1], v[46:47] op_sel_hi:[0,1]
	v_pk_mul_f32 v[44:45], v[0:1], v[44:45] op_sel_hi:[0,1]
	v_mul_f32_e32 v0, 0x4b800000, v60
	v_cndmask_b32_e32 v0, v60, v0, vcc
	v_pk_mul_f32 v[26:27], v[2:3], v[26:27]
	v_pk_mul_f32 v[28:29], v[4:5], v[28:29]
	v_pk_mul_f32 v[44:45], v[8:9], v[44:45]
	v_rsq_f32_e32 v0, v0
	v_pk_mul_f32 v[26:27], v[56:57], v[26:27]
	v_pk_mul_f32 v[28:29], v[52:53], v[28:29]
	v_pk_mul_f32 v[46:47], v[6:7], v[46:47]
	v_pk_mul_f32 v[44:45], v[58:59], v[44:45]
	v_pk_mul_f32 v[46:47], v[48:49], v[46:47]
	v_cvt_pk_bf16_f32 v26, v26, v27
	v_cvt_pk_bf16_f32 v27, v28, v29
	v_cvt_pk_bf16_f32 v29, v44, v45
	v_add_co_u32_e64 v44, s[0:1], s14, v62
	v_cvt_pk_bf16_f32 v28, v46, v47
	s_nop 0
	v_addc_co_u32_e64 v45, s[0:1], 0, v63, s[0:1]
	global_store_dwordx4 v[44:45], v[26:29], off offset:1024
	v_mul_f32_e32 v46, 0xbfb8aa3b, v78
	v_exp_f32_e32 v46, v46
	v_mul_f32_e32 v26, 0x45800000, v0
	v_cndmask_b32_e32 v0, v0, v26, vcc
	v_pk_mul_f32 v[26:27], v[0:1], v[88:89] op_sel_hi:[0,1]
	v_pk_mul_f32 v[26:27], v[2:3], v[26:27]
	v_pk_mul_f32 v[28:29], v[0:1], v[84:85] op_sel_hi:[0,1]
	v_pk_mul_f32 v[26:27], v[30:31], v[26:27]
	v_pk_mul_f32 v[30:31], v[0:1], v[80:81] op_sel_hi:[0,1]
	v_pk_mul_f32 v[48:49], v[0:1], v[74:75] op_sel_hi:[0,1]
	v_mul_f32_e32 v0, 0xbfb8aa3b, v79
	v_exp_f32_e32 v0, v0
	v_add_f32_e32 v46, 1.0, v46
	v_rcp_f32_e32 v46, v46
	v_pk_mul_f32 v[28:29], v[4:5], v[28:29]
	v_add_f32_e32 v0, 1.0, v0
	v_rcp_f32_e32 v47, v0
	v_pk_mul_f32 v[48:49], v[8:9], v[48:49]
	v_pk_mul_f32 v[28:29], v[86:87], v[28:29]
	v_cvt_pk_bf16_f32 v26, v26, v27
	v_pk_mul_f32 v[46:47], v[46:47], v[78:79]
	v_cvt_pk_bf16_f32 v27, v28, v29
	v_pk_mul_f32 v[46:47], v[46:47], v[48:49]
	v_pk_mul_f32 v[30:31], v[6:7], v[30:31]
	v_cvt_pk_bf16_f32 v29, v46, v47
	v_lshlrev_b32_e32 v46, 16, v20
	v_mul_f32_e32 v0, 0xbfb8aa3b, v46
	v_exp_f32_e32 v0, v0
	v_and_b32_e32 v47, 0xffff0000, v20
	v_pk_mul_f32 v[30:31], v[82:83], v[30:31]
	v_lshlrev_b32_e32 v50, 16, v19
	v_add_f32_e32 v0, 1.0, v0
	v_rcp_f32_e32 v20, v0
	v_mul_f32_e32 v0, 0xbfb8aa3b, v47
	v_exp_f32_e32 v0, v0
	v_cvt_pk_bf16_f32 v28, v30, v31
	v_lshlrev_b32_e32 v30, 16, v21
	v_and_b32_e32 v31, 0xffff0000, v21
	v_add_f32_e32 v0, 1.0, v0
; __device__ __forceinline__ unsigned pack2(float lo, float hi) { return pg8::cvt_pk_bf16(lo, hi); }
; __device__ __forceinline__ float silu_f(float x) { return x * __builtin_amdgcn_rcpf(1.0f + __expf(-x)); }
; __device__ void phase_finalize(const unsigned char* __restrict__ prep, const bf16_t* __restrict__ pz, const float* gn, bf16_t* __restrict__ mix) {
;     ...
;         for (int q = 0; q < 4; ++q) { const int row = rb + q;
;             float ov[8]; unpack8(oq[q], ov);
;             float ss = 0.f;
; #pragma unroll
;             for (int j = 0; j < 8; ++j) ss += ov[j] * ov[j];
;             ss += __shfl_xor(ss, 1); ss += __shfl_xor(ss, 2); ss += __shfl_xor(ss, 4); ss += __shfl_xor(ss, 8);
;             const float rstd = rsqrtf(ss * (1.0f / 128.0f) + EPS);
;             float zf[8]; unpack8(zq[q], zf);
;             float r[8];
; #pragma unroll
;             for (int j = 0; j < 8; ++j) r[j] = ov[j] * rstd * gv[j] * silu_f(zf[j]);
;             u32x4 w; w.x = pack2(r[0], r[1]); w.y = pack2(r[2], r[3]); w.z = pack2(r[4], r[5]); w.w = pack2(r[6], r[7]);
;             *(u32x4*)(mix + (size_t)row * DM + 512 + lane * 8) = w; }
	v_rcp_f32_e32 v21, v0
	v_mul_f32_e32 v0, 0xbfb8aa3b, v50
	v_exp_f32_e32 v0, v0
	v_and_b32_e32 v51, 0xffff0000, v19
	v_pk_mul_f32 v[20:21], v[20:21], v[46:47]
	v_lshlrev_b32_e32 v46, 16, v23
	v_add_f32_e32 v0, 1.0, v0
	v_rcp_f32_e32 v52, v0
	v_mul_f32_e32 v0, 0xbfb8aa3b, v51
	v_exp_f32_e32 v0, v0
	v_and_b32_e32 v47, 0xffff0000, v23
	v_and_b32_e32 v23, 0xffff0000, v18
	v_lshlrev_b32_e32 v60, 16, v12
	v_add_f32_e32 v0, 1.0, v0
	v_rcp_f32_e32 v53, v0
	v_lshlrev_b32_e32 v56, 16, v13
	v_and_b32_e32 v57, 0xffff0000, v13
	v_pk_mul_f32 v[48:49], v[46:47], v[46:47]
	v_pk_mul_f32 v[50:51], v[52:53], v[50:51]
	v_lshlrev_b32_e32 v52, 16, v22
	v_and_b32_e32 v53, 0xffff0000, v22
	v_lshlrev_b32_e32 v22, 16, v18
	v_mul_f32_e32 v0, 0xbfb8aa3b, v22
	v_exp_f32_e32 v0, v0
	v_mov_b32_e32 v77, v53
	global_store_dwordx4 v[44:45], v[26:29], off offset:3072
	v_lshlrev_b32_e32 v44, 16, v24
	v_add_f32_e32 v0, 1.0, v0
	v_rcp_f32_e32 v18, v0
	v_mul_f32_e32 v0, 0xbfb8aa3b, v23
	v_exp_f32_e32 v0, v0
	v_and_b32_e32 v45, 0xffff0000, v24
	v_lshlrev_b32_e32 v58, 16, v16
	v_and_b32_e32 v59, 0xffff0000, v16
	v_add_f32_e32 v0, 1.0, v0
	v_rcp_f32_e32 v19, v0
	v_mul_f32_e32 v0, 0xbfb8aa3b, v30
	v_exp_f32_e32 v0, v0
	v_lshlrev_b32_e32 v26, 16, v25
	v_pk_mul_f32 v[18:19], v[18:19], v[22:23]
	v_and_b32_e32 v27, 0xffff0000, v25
	v_add_f32_e32 v0, 1.0, v0
	v_rcp_f32_e32 v22, v0
	v_mul_f32_e32 v0, 0xbfb8aa3b, v31
	v_exp_f32_e32 v0, v0
	v_pk_mul_f32 v[24:25], v[44:45], v[44:45]
	v_pk_mul_f32 v[28:29], v[26:27], v[26:27]
	v_add_f32_e32 v0, 1.0, v0
	v_rcp_f32_e32 v23, v0
	v_mul_f32_e32 v0, 0xbfb8aa3b, v60
	v_exp_f32_e32 v0, v0
	v_pk_mul_f32 v[22:23], v[22:23], v[30:31]
	v_lshlrev_b32_e32 v30, 16, v17
	v_add_f32_e32 v0, 1.0, v0
	v_rcp_f32_e32 v12, v0
	v_mul_f32_e32 v0, 0xbfb8aa3b, v61
	v_exp_f32_e32 v0, v0
	v_and_b32_e32 v31, 0xffff0000, v17
	v_pk_mul_f32 v[16:17], v[58:59], v[58:59]
	v_pk_mul_f32 v[54:55], v[30:31], v[30:31]
	v_add_f32_e32 v0, 1.0, v0
	v_rcp_f32_e32 v13, v0
	v_mul_f32_e32 v0, 0xbfb8aa3b, v66
	v_exp_f32_e32 v0, v0
	v_pk_mul_f32 v[60:61], v[12:13], v[60:61]
	v_pk_mul_f32 v[12:13], v[64:65], v[64:65]
	v_add_f32_e32 v0, 1.0, v0
	v_rcp_f32_e32 v74, v0
	v_mul_f32_e32 v0, 0xbfb8aa3b, v67
	v_exp_f32_e32 v0, v0
	s_nop 0
	v_add_f32_e32 v0, 1.0, v0
	v_rcp_f32_e32 v75, v0
	s_nop 0
	v_pk_mul_f32 v[66:67], v[74:75], v[66:67]
	v_lshlrev_b32_e32 v74, 16, v14
	v_and_b32_e32 v75, 0xffff0000, v14
	v_lshlrev_b32_e32 v14, 16, v10
	v_mul_f32_e32 v0, 0xbfb8aa3b, v14
	v_exp_f32_e32 v0, v0
	v_mov_b32_e32 v76, v75
	v_pk_mul_f32 v[76:77], v[76:77], v[76:77]
	v_add_f32_e32 v0, 1.0, v0
	v_rcp_f32_e32 v10, v0
	v_mul_f32_e32 v0, 0xbfb8aa3b, v15
	v_exp_f32_e32 v0, v0
	s_nop 0
	v_add_f32_e32 v0, 1.0, v0
	v_rcp_f32_e32 v11, v0
	s_nop 0
	v_pk_mul_f32 v[14:15], v[10:11], v[14:15]
	v_mov_b32_e32 v10, v74
	v_mov_b32_e32 v11, v52
	v_pk_fma_f32 v[10:11], v[10:11], v[10:11], v[76:77]
	v_mov_b32_e32 v76, v12
	v_mov_b32_e32 v77, v48
	v_pk_add_f32 v[10:11], v[76:77], v[10:11]
	v_mov_b32_e32 v48, v13
	v_pk_add_f32 v[10:11], v[48:49], v[10:11]
	v_mov_b32_e32 v12, v16
	v_mov_b32_e32 v13, v24
	v_pk_add_f32 v[10:11], v[12:13], v[10:11]
	v_mov_b32_e32 v24, v17
	v_pk_add_f32 v[10:11], v[24:25], v[10:11]
	v_mov_b32_e32 v12, v54
	v_mov_b32_e32 v13, v28
	v_pk_add_f32 v[10:11], v[12:13], v[10:11]
	v_mov_b32_e32 v28, v55
	v_pk_add_f32 v[10:11], v[28:29], v[10:11]
	ds_bpermute_b32 v13, v70, v11
	ds_bpermute_b32 v12, v70, v10
	s_waitcnt lgkmcnt(0)
	v_pk_add_f32 v[10:11], v[10:11], v[12:13]
	ds_bpermute_b32 v13, v71, v11
	ds_bpermute_b32 v12, v71, v10
	s_waitcnt lgkmcnt(0)
	v_pk_add_f32 v[10:11], v[10:11], v[12:13]
	ds_bpermute_b32 v13, v72, v11
	ds_bpermute_b32 v12, v72, v10
	s_waitcnt lgkmcnt(0)
	v_pk_add_f32 v[10:11], v[10:11], v[12:13]
	ds_bpermute_b32 v13, v73, v11
	ds_bpermute_b32 v12, v73, v10
	s_waitcnt lgkmcnt(0)
	v_pk_add_f32 v[10:11], v[10:11], v[12:13]
	s_nop 0
	v_pk_fma_f32 v[16:17], v[10:11], s[18:19], v[32:33] op_sel_hi:[1,0,0]
	s_nop 0
	v_mul_f32_e32 v0, 0x4b800000, v17
	v_cmp_gt_f32_e64 s[0:1], s44, v17
	v_cmp_gt_f32_e32 vcc, s44, v16
	s_nop 0
	v_cndmask_b32_e64 v0, v17, v0, s[0:1]
	v_rsq_f32_e32 v0, v0
	s_nop 0
	v_mul_f32_e32 v10, 0x45800000, v0
	v_cndmask_b32_e64 v0, v0, v10, s[0:1]
	v_pk_mul_f32 v[10:11], v[0:1], v[52:53] op_sel_hi:[0,1]
	v_pk_mul_f32 v[10:11], v[2:3], v[10:11]
	v_pk_mul_f32 v[12:13], v[0:1], v[46:47] op_sel_hi:[0,1]
	v_pk_mul_f32 v[10:11], v[18:19], v[10:11]
	v_pk_mul_f32 v[18:19], v[0:1], v[44:45] op_sel_hi:[0,1]
	v_pk_mul_f32 v[18:19], v[6:7], v[18:19]
	v_pk_mul_f32 v[12:13], v[4:5], v[12:13]
	v_pk_mul_f32 v[18:19], v[20:21], v[18:19]
	v_pk_mul_f32 v[20:21], v[0:1], v[26:27] op_sel_hi:[0,1]
	v_mul_f32_e32 v0, 0x4b800000, v16
	v_cndmask_b32_e32 v0, v16, v0, vcc
	v_rsq_f32_e32 v0, v0
	v_pk_mul_f32 v[12:13], v[50:51], v[12:13]
	v_pk_mul_f32 v[20:21], v[8:9], v[20:21]
	v_cvt_pk_bf16_f32 v10, v10, v11
	v_pk_mul_f32 v[20:21], v[22:23], v[20:21]
	v_cvt_pk_bf16_f32 v11, v12, v13
	v_cvt_pk_bf16_f32 v12, v18, v19
	v_add_co_u32_e64 v18, s[0:1], s15, v62
	v_cvt_pk_bf16_f32 v13, v20, v21
	s_nop 0
	v_addc_co_u32_e64 v19, s[0:1], 0, v63, s[0:1]
	global_store_dwordx4 v[18:19], v[10:13], off offset:1024
	v_mul_f32_e32 v16, 0xbfb8aa3b, v56
	v_exp_f32_e32 v16, v16
	v_mul_f32_e32 v10, 0x45800000, v0
	v_cndmask_b32_e32 v0, v0, v10, vcc
	v_pk_mul_f32 v[10:11], v[0:1], v[74:75] op_sel_hi:[0,1]
	v_pk_mul_f32 v[10:11], v[2:3], v[10:11]
	v_pk_mul_f32 v[12:13], v[0:1], v[64:65] op_sel_hi:[0,1]
	v_pk_mul_f32 v[10:11], v[14:15], v[10:11]
	v_pk_mul_f32 v[14:15], v[0:1], v[58:59] op_sel_hi:[0,1]
	v_pk_mul_f32 v[20:21], v[0:1], v[30:31] op_sel_hi:[0,1]
	v_mul_f32_e32 v0, 0xbfb8aa3b, v57
	v_exp_f32_e32 v0, v0
	v_add_f32_e32 v16, 1.0, v16
	v_rcp_f32_e32 v16, v16
	v_pk_mul_f32 v[12:13], v[4:5], v[12:13]
	v_add_f32_e32 v0, 1.0, v0
	v_rcp_f32_e32 v17, v0
	v_pk_mul_f32 v[14:15], v[6:7], v[14:15]
	v_pk_mul_f32 v[20:21], v[8:9], v[20:21]
	v_pk_mul_f32 v[12:13], v[66:67], v[12:13]
	v_pk_mul_f32 v[16:17], v[16:17], v[56:57]
	v_pk_mul_f32 v[14:15], v[60:61], v[14:15]
	v_pk_mul_f32 v[16:17], v[16:17], v[20:21]
	v_cmp_lt_i32_e32 vcc, s72, v34
	v_cvt_pk_bf16_f32 v10, v10, v11
	v_cvt_pk_bf16_f32 v11, v12, v13
	v_cvt_pk_bf16_f32 v12, v14, v15
	v_cvt_pk_bf16_f32 v13, v16, v17
	s_or_b64 s[12:13], vcc, s[12:13]
	global_store_dwordx4 v[18:19], v[10:13], off offset:3072
	s_andn2_b64 exec, exec, s[12:13]
	s_cbranch_execnz .LBB0_167

; __device__ __forceinline__ int my_tid() { int t = (int)threadIdx.x; asm volatile("" : "+v"(t)); return t; }
; __device__ __forceinline__ int fetch_item(unsigned* ctr, unsigned char* lds) {
;     volatile int* slot = (volatile int*)(lds + LDS_SLOT);
;     __syncthreads();
;     if (my_tid() == 0) *slot = (int)atomicAdd(ctr, 1u);
;     __syncthreads();
;     return *slot;
; }
; __device__ void run_phase(const Params& p, unsigned char* lds, int ph) {
;     ...
;         for (;;) {
;             const int it = fetch_item(ctr, lds);
;             if (it >= 3120) break;
;             if (it < 16) { const int bh = it;
;                 fcum_unit(lds, bh, (const float*)(ws + WS_SCAL), p.in[I_FGB] + l * 4, (float*)(ws + WS_F) , (const bf16_t*)(ws + WS_PAB) + (size_t)(bh >> 2) * SEQ * 1536 + 1024 + (bh & 3) * 64, (float*)(ws + WS_KN) + bh * 128, (const bf16_t*)(ws + WS_PAB) + (size_t)(bh >> 2) * SEQ * 1536 + 256 + (bh & 3) * 64, p.in[I_REL] + (size_t)(l * 4 + (bh & 3)) * 320, (float*)(ws + WS_AB) + bh * 2, uflag + 2048 + bh, fval); }
;             else if (it < 48) { const int j = it - 16;
;                 for (int rep = 0; rep < REP_SCAN; ++rep) { scan_unit(lds, j >> 1, j & 1, ws + WS_PREP, (const float*)(ws + WS_EGL), uflag + (j >> 1) * 128, fval); __syncthreads(); } }
;             else if (it < 2096) { const int j = it - 48, n = j >> 4, bh = j & 15, h = bh & 3;
;                 prep_unit(lds, bh, n, (const bf16_t*)(ws + WS_PC), (const float*)(ws + WS_SCAL), p.in[I_CONVW] + (size_t)l * 4 * 1536, p.in[I_ALOG][l * 4 + h], p.in[I_DTB][l * 4 + h],
;                           ws + WS_PREP + (size_t)(bh * 128 + n) * PREP_UNIT, (float*)(ws + WS_EGL), uflag + bh * 128 + n, fval); }
;             else if (it < 2608) { const int j = it - 2096, qb = j & 31, bh = j >> 5, b = bh >> 2, h = bh & 3;
;                 for (int rep = 0; rep < REP_A; ++rep) { attn_unit<1>(lds, b, qb, pab + h * 64, pab + 256 + h * 64, pab + 512 + h * 64, 1536, hbuf + h * 64, DM, nullptr, p.in[I_REL] + (size_t)(l * 4 + h) * 320, (const float*)(ws + WS_AB) + bh * 2, uflag + 2048 + bh, fval); __syncthreads(); } }
;             else { const int j = it - 2608, qb = 31 - (j >> 4), bh = j & 15, b = bh >> 2, h = bh & 3;
.LBB0_174:
	v_mov_b32_e32 v0, v212
	s_waitcnt lgkmcnt(0)
	s_barrier
	s_nop 0
	v_cmp_eq_u32_e32 vcc, 0, v0
	s_and_saveexec_b64 s[0:1], vcc
	s_cbranch_execz .LBB0_176
	v_readlane_b32 s4, v255, 7
	v_readlane_b32 s5, v255, 8
	s_mov_b64 s[2:3], src_shared_base
	s_add_i32 s2, 0, 0x26400
	s_waitcnt vmcnt(0)
	v_mov_b64_e32 v[2:3], s[4:5]
	global_atomic_add v0, v[2:3], v214, off offset:32 sc0
	s_cmp_lg_u32 s2, -1
	s_cselect_b32 s2, s2, 0
	s_cselect_b32 s3, s3, 0
	v_mov_b32_e32 v2, s2
	v_mov_b32_e32 v3, s3
	s_waitcnt vmcnt(0) lgkmcnt(0)
	flat_store_dword v[2:3], v0 sc0 sc1
	s_waitcnt vmcnt(0)
.LBB0_176:
	s_or_b64 exec, exec, s[0:1]
	s_mov_b64 s[0:1], src_shared_base
	s_add_i32 s0, 0, 0x26400
	s_cmp_lg_u32 s0, -1
	s_cselect_b32 s0, s0, 0
	s_cselect_b32 s1, s1, 0
	s_waitcnt vmcnt(0)
	v_mov_b32_e32 v2, s0
	v_mov_b32_e32 v3, s1
	s_waitcnt lgkmcnt(0)
	s_barrier
	flat_load_dword v90, v[2:3] sc0 sc1
	s_waitcnt vmcnt(0)
	s_movk_i32 s0, 0xc30
	s_waitcnt lgkmcnt(0)
	v_cmp_gt_i32_e32 vcc, s0, v90
	s_mov_b64 s[0:1], -1
	s_and_saveexec_b64 s[30:31], vcc
	s_cbranch_execz .LBB0_173
	v_cmp_lt_i32_e32 vcc, 15, v90
	s_and_saveexec_b64 s[0:1], vcc
	s_xor_b64 s[4:5], exec, s[0:1]
	s_cbranch_execz .LBB0_620
	s_mov_b64 s[56:57], s[4:5]
	v_cmp_lt_u32_e32 vcc, 47, v90
	s_and_saveexec_b64 s[0:1], vcc
	s_xor_b64 s[4:5], exec, s[0:1]
	s_cbranch_execz .LBB0_450
	v_writelane_b32 v255, s4, 45
	s_movk_i32 s0, 0x82f
	v_cmp_lt_u32_e32 vcc, s0, v90
	v_writelane_b32 v255, s5, 46
	s_and_saveexec_b64 s[0:1], vcc
	s_xor_b64 s[0:1], exec, s[0:1]
	s_cbranch_execz .LBB0_302
	v_writelane_b32 v255, s0, 47
	s_nop 1
	v_writelane_b32 v255, s1, 48
	s_movk_i32 s0, 0xa2f
	v_cmp_lt_u32_e32 vcc, s0, v90
	s_and_saveexec_b64 s[0:1], vcc
	s_xor_b64 s[0:1], exec, s[0:1]
	v_writelane_b32 v255, s0, 49
	s_nop 1
	v_writelane_b32 v255, s1, 50
	s_cbranch_execz .LBB0_257
	v_and_b32_e32 v6, 15, v90
	v_mov_b32_e32 v146, v212
	s_mov_b64 s[0:1], exec
	v_readlane_b32 s2, v254, 1
	v_readlane_b32 s3, v254, 2
	s_and_b64 s[2:3], s[0:1], s[2:3]
	s_mov_b64 exec, s[2:3]
	s_cbranch_execz .LBB0_186
	v_readlane_b32 s2, v255, 27
	v_lshlrev_b32_e32 v0, 2, v6
	v_readlane_b32 s3, v255, 28
	s_nop 1
	v_lshl_add_u64 v[2:3], s[2:3], 0, v[0:1]
	global_load_dword v0, v[2:3], off sc1
	s_waitcnt vmcnt(0) lgkmcnt(0)
	v_cmp_gt_u32_e32 vcc, s73, v0
	s_and_saveexec_b64 s[2:3], vcc
	s_cbranch_execz .LBB0_185
	s_mov_b64 s[4:5], 0
.LBB0_184:
	s_sleep 4
	global_load_dword v0, v[2:3], off sc1
	s_waitcnt vmcnt(0) lgkmcnt(0)
	v_cmp_le_u32_e32 vcc, s73, v0
	s_or_b64 s[4:5], vcc, s[4:5]
	s_andn2_b64 exec, exec, s[4:5]
	s_cbranch_execnz .LBB0_184

; template <int MODE>
; __device__ void attn_unit(unsigned char* lds, int b, int qb, const bf16_t* Qp, const bf16_t* Kp, const bf16_t* Vp, int ld, bf16_t* Op, int ldo, const float* Fbh, const float* reltab, const float* knsuf, const unsigned* fflag, unsigned fval) {
;     ...
;     handoff_wait_one(fflag, fval);
;     const float Fref = MODE == 0 ? Fbh[q0] : 0.f;
;     float* ktab = (float*)(lds + 40960); float* ftab = (float*)(lds + 41472); volatile int* flags = (volatile int*)(lds + 41984);
;     const int nt = kt1 - kt0 + 1;
;     if (MODE == 0) { for (int i = tid; i <= kt1; i += NTHR) { ktab[i] = knsuf[i]; ftab[i] = (Fref - Fbh[64 * i + 63]) * LOG2E; } }
;     if (MODE == 1) { for (int i = tid; i < 640; i += NTHR) { int rel = 575 - i; rel = rel < -63 ? -63 : (rel > 256 ? 256 : rel); ext[i] = reltab[rel + 63] * LOG2E; } }
;     bf16x8 qf[2][2];
; #pragma unroll
;     for (int nq = 0; nq < 2; ++nq)
; #pragma unroll
;         for (int ks = 0; ks < 2; ++ks) qf[nq][ks] = *(const bf16x8*)(Qp + (rowbase + qw0 + 16 * nq + cl) * ld + 32 * ks + quad * 8);
;     float mrun[2] = {-1e30f, -1e30f}, lrun[2] = {0.f, 0.f};
;     float qn[2] = {0.f, 0.f};
;     {
; #pragma unroll
;         for (int nq = 0; nq < 2; ++nq) { float ss = 0.f;
; #pragma unroll
;             for (int ks = 0; ks < 2; ++ks)
; #pragma unroll
;                 for (int j = 0; j < 8; ++j) { const float f = __uint_as_float(((unsigned)(unsigned short)qf[nq][ks][j]) << 16); ss += f * f; }
;             ss += __shfl_xor(ss, 16); ss += __shfl_xor(ss, 32); qn[nq] = sqrtf(ss) * 1.0001f; }
;     }
;     bool done = false;
;     float Rref[2] = {0.f, 0.f};
;     if (MODE == 1) { const float ka = knsuf[0], bm = knsuf[1]; Rref[0] = qn[0] * ka + bm + 1.0f; Rref[1] = qn[1] * ka + bm + 1.0f; }
;     else {
; #pragma unroll
;         for (int nq = 0; nq < 2; ++nq) { const int qrow = qw0 + 16 * nq + cl; Rref[nq] = qn[nq] * knsuf[qrow >> 6] + (Fref - Fbh[qrow]) * LOG2E + 1.0f; }
;     }
;     f32x4 o[4][2];
; #pragma unroll
;     for (int dt = 0; dt < 4; ++dt)
; #pragma unroll
;         for (int nq = 0; nq < 2; ++nq) o[dt][nq] = (f32x4){0.f, 0.f, 0.f, 0.f};
;     const int skey = tid >> 3, sdch = tid & 7;
;     const int vkey = tid & 63, vdch = tid >> 6;
;     const int vpos = (vkey & 32) + ((vkey >> 2) & 3) * 8 + ((vkey >> 4) & 1) * 4 + (vkey & 3);
.LBB0_186:
	s_or_b64 exec, exec, s[0:1]
	v_add_u32_e32 v0, 0xfffff5d0, v90
	v_lshrrev_b32_e32 v38, 4, v0
	v_readlane_b32 s0, v255, 23
	v_sub_u32_e32 v8, 31, v38
	v_lshlrev_b32_e32 v0, 15, v6
	v_readlane_b32 s1, v255, 24
	s_barrier
	s_nop 0
	v_lshl_add_u64 v[148:149], s[0:1], 0, v[0:1]
	v_lshlrev_b32_e32 v0, 10, v8
	v_lshl_add_u64 v[2:3], v[148:149], 0, v[0:1]
	global_load_dword v181, v[2:3], off
	v_lshlrev_b32_e32 v180, 2, v8
	v_or_b32_e32 v7, 3, v180
	v_cmp_le_i32_e32 vcc, v146, v7
	v_lshlrev_b32_e32 v0, 9, v6
	s_and_saveexec_b64 s[0:1], vcc
	s_cbranch_execz .LBB0_189
	s_add_i32 s2, 0, 0xa000
	v_lshl_add_u32 v9, v146, 2, s2
	v_ashrrev_i32_e32 v147, 31, v146
	v_readlane_b32 s2, v255, 25
	v_lshl_add_u64 v[4:5], v[146:147], 2, v[0:1]
	v_readlane_b32 s3, v255, 26
	v_lshlrev_b32_e32 v2, 6, v146
	v_mov_b32_e32 v10, v146
	v_lshl_add_u64 v[4:5], s[2:3], 0, v[4:5]
	s_mov_b64 s[2:3], 0
.LBB0_188:
	global_load_dword v3, v[4:5], off
	v_add_u32_e32 v10, 0x200, v10
	v_cmp_gt_i32_e32 vcc, v10, v7
	v_lshl_add_u64 v[4:5], v[4:5], 0, s[94:95]
	s_or_b64 s[2:3], vcc, s[2:3]
	s_waitcnt vmcnt(0) lgkmcnt(0)
	ds_write_b32 v9, v3
	v_ashrrev_i32_e32 v3, 31, v2
	v_lshl_add_u64 v[12:13], v[2:3], 2, v[148:149]
	global_load_dword v3, v[12:13], off offset:252
	v_add_u32_e32 v2, 0x8000, v2
	s_waitcnt vmcnt(0) lgkmcnt(0)
	v_sub_f32_e32 v3, v181, v3
	v_mul_f32_e32 v3, 0x3fb8aa3b, v3
	ds_write_b32 v9, v3 offset:512
	v_add_u32_e32 v9, 0x800, v9
	s_andn2_b64 exec, exec, s[2:3]
	s_cbranch_execnz .LBB0_188
.LBB0_189:
	s_or_b64 exec, exec, s[0:1]
	v_lshlrev_b32_e32 v2, 6, v90
	v_and_b32_e32 v2, 0xc0, v2
	v_readlane_b32 s0, v255, 15
	v_lshlrev_b32_e32 v152, 1, v2
	v_mov_b32_e32 v153, v1
	v_readlane_b32 s1, v255, 16
	v_lshlrev_b32_e32 v32, 8, v8
	v_mov_b32_e32 v155, v1
	v_lshl_add_u64 v[2:3], s[0:1], 0, v[152:153]
	v_readlane_b32 s0, v255, 17
	v_readlane_b32 s1, v255, 18
	v_and_b32_e32 v39, 15, v146
	v_and_b32_e32 v30, 48, v146
	v_lshl_add_u64 v[26:27], s[0:1], 0, v[152:153]
	v_readlane_b32 s0, v255, 19
	v_readlane_b32 s1, v255, 20
	v_mov_b32_e32 v31, v1
	v_lshl_add_u64 v[2:3], v[2:3], 0, v[30:31]
	v_lshl_add_u64 v[28:29], s[0:1], 0, v[152:153]
	v_readlane_b32 s0, v255, 25
	v_readlane_b32 s1, v255, 26
	v_ashrrev_i32_e32 v153, 6, v146
	v_lshl_add_u32 v158, v153, 5, v32
	v_lshl_add_u64 v[18:19], s[0:1], 0, v[0:1]
	v_lshlrev_b32_e32 v0, 11, v6
	v_and_b32_e32 v154, 0x6000, v0
	v_ashrrev_i32_e32 v159, 31, v158
	v_lshl_add_u64 v[150:151], v[158:159], 0, v[154:155]
	v_or_b32_e32 v150, v150, v39
	v_mad_u64_u32 v[10:11], s[0:1], v150, s53, v[2:3]
	v_mad_i32_i24 v11, v151, s53, v11
	v_lshlrev_b32_e32 v33, 6, v7
	global_load_dwordx4 v[2:5], v[10:11], off
	global_load_dwordx4 v[6:9], v[10:11], off offset:64
	s_mov_b64 s[0:1], 0xc000
	v_lshl_add_u64 v[14:15], v[10:11], 0, s[0:1]
	s_mov_b32 s0, 0xc000
	v_add_co_u32_e32 v10, vcc, s0, v10
	v_and_b32_e32 v21, 64, v218
	s_nop 0
	v_addc_co_u32_e32 v11, vcc, 0, v11, vcc
	global_load_dwordx4 v[10:13], v[10:11], off
	s_nop 0
	global_load_dwordx4 v[14:17], v[14:15], off offset:64
	v_xor_b32_e32 v20, 16, v218
	v_add_u32_e32 v21, 64, v21
	v_cmp_lt_i32_e32 vcc, v20, v21
	v_or_b32_e32 v160, v158, v39
	v_ashrrev_i32_e32 v161, 31, v160
	v_cndmask_b32_e32 v20, v218, v20, vcc
	v_lshlrev_b32_e32 v157, 2, v20
	v_xor_b32_e32 v20, 32, v218
	v_cmp_lt_i32_e32 vcc, v20, v21
	v_or_b32_e32 v0, v33, v154
	v_and_b32_e32 v156, 63, v146
	v_cndmask_b32_e32 v20, v218, v20, vcc
	v_lshlrev_b32_e32 v159, 2, v20
	v_ashrrev_i32_e32 v162, 3, v146
	v_and_b32_e32 v42, 7, v146
	v_lshlrev_b32_e32 v34, 3, v153
	v_lshlrev_b32_e32 v36, 4, v42
	v_mov_b32_e32 v37, v1
	v_ashrrev_i32_e32 v35, 31, v34
	v_cmp_gt_i32_e32 vcc, 64, v146
	v_mov_b32_e32 v182, 0
	s_waitcnt vmcnt(0) lgkmcnt(0)
	v_and_b32_e32 v21, 0xffff0000, v2
	v_lshlrev_b32_e32 v20, 16, v2
	v_mul_f32_e32 v21, v21, v21
	v_fmac_f32_e32 v21, v20, v20
	v_lshlrev_b32_e32 v20, 16, v3
	v_fmac_f32_e32 v21, v20, v20
	v_and_b32_e32 v20, 0xffff0000, v3
	v_fmac_f32_e32 v21, v20, v20
	v_lshlrev_b32_e32 v20, 16, v4
	v_fmac_f32_e32 v21, v20, v20
	v_and_b32_e32 v20, 0xffff0000, v4
	v_fmac_f32_e32 v21, v20, v20
	v_lshlrev_b32_e32 v20, 16, v5
	v_fmac_f32_e32 v21, v20, v20
	v_and_b32_e32 v20, 0xffff0000, v5
	v_fmac_f32_e32 v21, v20, v20
	v_lshlrev_b32_e32 v20, 16, v6
	v_fmac_f32_e32 v21, v20, v20
	v_and_b32_e32 v20, 0xffff0000, v6
	v_fmac_f32_e32 v21, v20, v20
	v_lshlrev_b32_e32 v20, 16, v7
	v_fmac_f32_e32 v21, v20, v20
	v_and_b32_e32 v20, 0xffff0000, v7
	v_fmac_f32_e32 v21, v20, v20
	v_lshlrev_b32_e32 v20, 16, v8
	v_fmac_f32_e32 v21, v20, v20
	v_and_b32_e32 v20, 0xffff0000, v8
	v_fmac_f32_e32 v21, v20, v20
	v_lshlrev_b32_e32 v20, 16, v9
	v_fmac_f32_e32 v21, v20, v20
	v_and_b32_e32 v20, 0xffff0000, v9
	v_fmac_f32_e32 v21, v20, v20
	ds_bpermute_b32 v20, v157, v21
	s_waitcnt lgkmcnt(0)
	v_add_f32_e32 v50, v21, v20
	v_and_b32_e32 v21, 0xffff0000, v10
	v_lshlrev_b32_e32 v20, 16, v10
	v_mul_f32_e32 v21, v21, v21
	v_fmac_f32_e32 v21, v20, v20
	v_lshlrev_b32_e32 v20, 16, v11
	v_fmac_f32_e32 v21, v20, v20
	v_and_b32_e32 v20, 0xffff0000, v11
	v_fmac_f32_e32 v21, v20, v20
	v_lshlrev_b32_e32 v20, 16, v12
	v_fmac_f32_e32 v21, v20, v20
	v_and_b32_e32 v20, 0xffff0000, v12
	v_fmac_f32_e32 v21, v20, v20
	v_lshlrev_b32_e32 v20, 16, v13
	v_fmac_f32_e32 v21, v20, v20
	v_and_b32_e32 v20, 0xffff0000, v13
	v_fmac_f32_e32 v21, v20, v20
	v_lshlrev_b32_e32 v20, 16, v14
	v_fmac_f32_e32 v21, v20, v20
	v_and_b32_e32 v20, 0xffff0000, v14
	v_fmac_f32_e32 v21, v20, v20
	v_lshlrev_b32_e32 v20, 16, v15
	v_fmac_f32_e32 v21, v20, v20
	v_and_b32_e32 v20, 0xffff0000, v15
	v_fmac_f32_e32 v21, v20, v20
	v_lshlrev_b32_e32 v20, 16, v16
	v_fmac_f32_e32 v21, v20, v20
	v_and_b32_e32 v20, 0xffff0000, v16
	v_fmac_f32_e32 v21, v20, v20
	v_lshlrev_b32_e32 v20, 16, v17
	v_fmac_f32_e32 v21, v20, v20
	v_and_b32_e32 v20, 0xffff0000, v17
	v_fmac_f32_e32 v21, v20, v20
	ds_bpermute_b32 v20, v157, v21
	ds_bpermute_b32 v51, v159, v50
	s_waitcnt lgkmcnt(1)
	v_add_f32_e32 v52, v21, v20
	v_ashrrev_i32_e32 v20, 6, v158
	v_ashrrev_i32_e32 v21, 31, v20
	v_lshl_add_u64 v[18:19], v[20:21], 2, v[18:19]
	global_load_dword v31, v[18:19], off
	v_lshl_add_u64 v[18:19], v[160:161], 2, v[148:149]
	global_load_dword v41, v[18:19], off
	global_load_dword v40, v[18:19], off offset:64
	v_add_u32_e32 v18, v162, v0
	v_or_b32_e32 v0, v156, v0
	v_mul_u32_u24_e32 v0, 0x600, v0
	v_lshlrev_b32_e32 v0, 1, v0
	v_mad_i64_i32 v[18:19], s[0:1], v18, s53, v[26:27]
	v_lshl_add_u64 v[22:23], v[28:29], 0, v[0:1]
	v_lshl_add_u64 v[18:19], v[18:19], 0, v[36:37]
	v_lshl_add_u64 v[22:23], v[34:35], 1, v[22:23]
	global_load_dwordx4 v[18:21], v[18:19], off
	ds_bpermute_b32 v53, v159, v52
	global_load_dwordx4 v[22:25], v[22:23], off
	v_mov_b32_e32 v161, 0
	s_and_saveexec_b64 s[0:1], vcc
	s_cbranch_execz .LBB0_191
	v_add_u32_e32 v44, v146, v33
	v_ashrrev_i32_e32 v45, 31, v44
	v_lshl_add_u64 v[44:45], v[44:45], 2, v[148:149]
	global_load_dword v161, v[44:45], off
; #define ATT_LOAD(S, r) do { if ((r) < nt) { const int t_ = ATT_TILE(r); rk##S = *(const u32x4*)(Kp + (rowbase + (size_t)t_ * 64 + skey) * ld + sdch * 8); rv##S = *(const u32x4*)(Vp + (rowbase + (size_t)t_ * 64 + vkey) * ld + vdch * 8); \
;         if (MODE == 0 && tid < 64) rf##S = Fbh[t_ * 64 + tid]; } } while (0)
; template <int MODE>
; __device__ void attn_unit(unsigned char* lds, int b, int qb, const bf16_t* Qp, const bf16_t* Kp, const bf16_t* Vp, int ld, bf16_t* Op, int ldo, const float* Fbh, const float* reltab, const float* knsuf, const unsigned* fflag, unsigned fval) {
;     ...
;     ATT_LOAD(0, 0); ATT_LOAD(1, 1); ATT_LOAD(2, 2);
;     ATT_STORE(0, 0);
;     __syncthreads();
.LBB0_191:
	s_or_b64 exec, exec, s[0:1]
	v_or3_b32 v33, v32, v154, s46
	v_add_u32_e32 v37, v162, v33
	v_or_b32_e32 v33, v156, v33
	v_mul_u32_u24_e32 v33, 0x600, v33
	v_lshlrev_b32_e32 v0, 3, v42
	v_lshlrev_b32_e32 v44, 1, v33
	v_mov_b32_e32 v45, v1
	v_mad_i64_i32 v[42:43], s[0:1], v37, s53, v[26:27]
	v_lshlrev_b32_e32 v0, 1, v0
	v_lshl_add_u64 v[44:45], v[28:29], 0, v[44:45]
	v_lshl_add_u64 v[42:43], v[42:43], 0, v[0:1]
	v_lshl_add_u64 v[46:47], v[34:35], 1, v[44:45]
	global_load_dwordx4 v[42:45], v[42:43], off
	s_nop 0
	global_load_dwordx4 v[46:49], v[46:47], off
	v_ashrrev_i32_e32 v163, 31, v162
	s_and_saveexec_b64 s[0:1], vcc
	s_cbranch_execz .LBB0_193
	v_ashrrev_i32_e32 v147, 31, v146
	v_mov_b32_e32 v33, v1
	v_lshl_add_u64 v[54:55], v[146:147], 0, v[32:33]
	v_lshl_add_u64 v[54:55], v[54:55], 2, v[148:149]
	global_load_dword v182, v[54:55], off offset:512
.LBB0_193:
	s_or_b64 exec, exec, s[0:1]
	v_or3_b32 v33, v32, v154, 64
	v_add_u32_e32 v37, v162, v33
	v_or_b32_e32 v33, v156, v33
	v_mul_u32_u24_e32 v33, 0x600, v33
	v_mad_i64_i32 v[54:55], s[0:1], v37, s53, v[26:27]
	v_lshlrev_b32_e32 v56, 1, v33
	v_mov_b32_e32 v57, v1
	v_lshl_add_u64 v[54:55], v[54:55], 0, v[0:1]
	v_lshl_add_u64 v[56:57], v[28:29], 0, v[56:57]
	v_lshl_add_u64 v[56:57], v[34:35], 1, v[56:57]
	global_load_dwordx4 v[58:61], v[54:55], off
	global_load_dwordx4 v[62:65], v[56:57], off
	v_mov_b32_e32 v147, 0
	s_and_saveexec_b64 s[0:1], vcc
	s_cbranch_execz .LBB0_195
	v_ashrrev_i32_e32 v147, 31, v146
	v_mov_b32_e32 v33, v1
	v_lshl_add_u64 v[32:33], v[146:147], 0, v[32:33]
	v_lshl_add_u64 v[32:33], v[32:33], 2, v[148:149]
	global_load_dword v147, v[32:33], off offset:256

.LBB0_199:
	v_cmp_le_u32_e64 s[0:1], v202, v180
	s_and_saveexec_b64 s[2:3], s[0:1]
	s_cbranch_execz .LBB0_203
	s_movk_i32 s4, 0xff01
	v_add3_u32 v0, v154, v200, s4
	v_lshl_add_u64 v[18:19], v[0:1], 0, v[162:163]
	v_add3_u32 v0, v201, v200, s4
	v_mad_u64_u32 v[20:21], s[0:1], v18, s53, v[166:167]
	v_mul_u32_u24_e32 v0, 0xc00, v0
	v_mad_i32_i24 v21, v19, s53, v21
	v_lshl_add_u64 v[22:23], v[168:169], 0, v[0:1]
	global_load_dwordx4 v[18:21], v[20:21], off
	s_nop 0
	global_load_dwordx4 v[22:25], v[22:23], off
	s_movk_i32 s8, 0xff01
	s_and_saveexec_b64 s[0:1], vcc
	s_cbranch_execz .LBB0_202
	v_add3_u32 v82, v146, v200, s8
	v_ashrrev_i32_e32 v83, 31, v82
	v_lshl_add_u64 v[82:83], v[82:83], 2, v[148:149]
	global_load_dword v161, v[82:83], off

.LBB0_216:
	s_or_b64 exec, exec, s[2:3]
	s_and_b32 s0, s41, 8
	s_lshl_b32 s0, s0, 2
	s_add_i32 s43, s0, 0
	s_mov_b64 s[36:37], src_shared_base
	s_add_i32 s38, s43, 0xa400
	s_mov_b32 s39, s37
	v_mov_b64_e32 v[82:83], s[38:39]
	s_add_i32 s36, s43, 0xa404
	s_waitcnt lgkmcnt(0)
	s_barrier
	flat_load_dword v84, v[82:83] sc0 sc1
	s_waitcnt vmcnt(0)
	v_mov_b64_e32 v[82:83], s[36:37]
	s_add_i32 s2, s43, 0xa408
	s_mov_b32 s3, s37
	flat_load_dword v85, v[82:83] sc0 sc1
	s_waitcnt vmcnt(0)
	v_mov_b64_e32 v[82:83], s[2:3]
	s_add_i32 s24, s43, 0xa40c
	s_mov_b32 s25, s37
	flat_load_dword v86, v[82:83] sc0 sc1
	s_waitcnt vmcnt(0)
	v_mov_b64_e32 v[82:83], s[24:25]
	s_add_i32 s96, s43, 0xa410
	s_mov_b32 s97, s37
	flat_load_dword v87, v[82:83] sc0 sc1
	s_waitcnt vmcnt(0)
	v_mov_b64_e32 v[82:83], s[96:97]
	s_add_i32 s92, s43, 0xa414
	s_mov_b32 s93, s37
	flat_load_dword v88, v[82:83] sc0 sc1
	s_waitcnt vmcnt(0)
	v_mov_b64_e32 v[82:83], s[92:93]
	s_add_i32 s78, s43, 0xa418
	s_mov_b32 s79, s37
	flat_load_dword v89, v[82:83] sc0 sc1
	s_waitcnt vmcnt(0)
	v_mov_b64_e32 v[82:83], s[78:79]
	s_add_i32 s76, s43, 0xa41c
	s_mov_b32 s77, s37
	flat_load_dword v90, v[82:83] sc0 sc1
	s_waitcnt vmcnt(0)
	v_mov_b64_e32 v[82:83], s[76:77]
	flat_load_dword v82, v[82:83] sc0 sc1
	s_waitcnt vmcnt(0) lgkmcnt(0)
	v_cmp_ne_u32_e64 s[8:9], 0, v90
	v_cmp_ne_u32_e64 s[0:1], 0, v82
	s_and_b64 s[4:5], s[0:1], s[8:9]
	v_cmp_ne_u32_e64 s[0:1], 0, v89
	s_and_b64 s[4:5], s[4:5], s[0:1]
	v_cmp_ne_u32_e64 s[0:1], 0, v88
	s_and_b64 s[4:5], s[4:5], s[0:1]
	v_cmp_ne_u32_e64 s[0:1], 0, v87
	s_and_b64 s[4:5], s[4:5], s[0:1]
	v_cmp_ne_u32_e64 s[0:1], 0, v86
	s_and_b64 s[4:5], s[4:5], s[0:1]
	v_cmp_ne_u32_e64 s[0:1], 0, v85
	s_and_b64 s[4:5], s[4:5], s[0:1]
	v_cmp_ne_u32_e64 s[0:1], 0, v84
	s_and_b64 s[34:35], s[4:5], s[0:1]
	s_xor_b64 s[4:5], s[34:35], -1
	v_cmp_lt_u32_e64 s[0:1], v0, v189
	s_and_b64 s[0:1], s[0:1], s[4:5]
	s_and_saveexec_b64 s[4:5], s[0:1]
	s_cbranch_execz .LBB0_235
	v_cmp_lt_u32_e64 s[0:1], v202, v180
	s_and_saveexec_b64 s[8:9], s[0:1]
	s_cbranch_execz .LBB0_221
	v_add_u32_e32 v42, 1, v178
	v_ashrrev_i32_e32 v43, 31, v42
	v_lshlrev_b64 v[42:43], 6, v[42:43]
	v_lshl_add_u64 v[42:43], v[42:43], 0, v[154:155]
	v_lshl_add_u64 v[44:45], v[42:43], 0, v[162:163]
	v_or_b32_e32 v42, v42, v156
	v_mad_u64_u32 v[46:47], s[0:1], v44, s53, v[166:167]
	v_mad_u64_u32 v[48:49], s[0:1], v42, s53, v[168:169]
	v_mad_i32_i24 v47, v45, s53, v47
	v_mad_i32_i24 v49, v43, s53, v49
	global_load_dwordx4 v[42:45], v[46:47], off
	s_nop 0
	global_load_dwordx4 v[46:49], v[48:49], off
	s_and_saveexec_b64 s[0:1], vcc
	s_cbranch_execz .LBB0_220
	s_movk_i32 s10, 0xfec1
	v_add3_u32 v82, v146, v200, s10
	v_ashrrev_i32_e32 v83, 31, v82
	v_lshl_add_u64 v[82:83], v[82:83], 2, v[148:149]
	global_load_dword v182, v[82:83], off

.LBB0_235:
	s_or_b64 exec, exec, s[4:5]
	v_add_u32_e32 v0, 2, v202
	v_cmp_lt_u32_e64 s[0:1], v0, v189
	s_xor_b64 s[4:5], s[34:35], -1
	s_and_b64 s[0:1], s[0:1], s[4:5]
	s_and_saveexec_b64 s[4:5], s[0:1]
	s_xor_b64 s[4:5], exec, s[4:5]
	s_cbranch_execz .LBB0_254
	v_add_u32_e32 v0, 5, v202
	v_cmp_lt_u32_e64 s[0:1], v0, v189
	s_and_saveexec_b64 s[8:9], s[0:1]
	s_cbranch_execz .LBB0_240
	v_ashrrev_i32_e32 v179, 31, v178
	v_lshlrev_b64 v[58:59], 6, v[178:179]
	v_lshl_add_u64 v[58:59], v[58:59], 0, v[154:155]
	v_lshl_add_u64 v[60:61], v[58:59], 0, v[162:163]
	v_or_b32_e32 v0, v58, v156
	v_mad_u64_u32 v[62:63], s[0:1], v60, s53, v[166:167]
	v_mad_u64_u32 v[64:65], s[0:1], v0, s53, v[168:169]
	v_mad_i32_i24 v63, v61, s53, v63
	v_mad_i32_i24 v65, v59, s53, v65
	global_load_dwordx4 v[58:61], v[62:63], off
	s_nop 0
	global_load_dwordx4 v[62:65], v[64:65], off
	s_and_saveexec_b64 s[0:1], vcc
	s_cbranch_execz .LBB0_239
	s_movk_i32 s10, 0xfe81
	v_add3_u32 v82, v146, v200, s10
	v_ashrrev_i32_e32 v83, 31, v82
	v_lshl_add_u64 v[82:83], v[82:83], 2, v[148:149]
	global_load_dword v147, v[82:83], off

; __device__ __forceinline__ unsigned pack2(float lo, float hi) { return pg8::cvt_pk_bf16(lo, hi); }
; __device__ __forceinline__ void handoff_wait_one(const unsigned* flag, unsigned val) {
;     if (threadIdx.x == 0) {
;         while (__hip_atomic_load(flag, __ATOMIC_RELAXED, __HIP_MEMORY_SCOPE_AGENT) < val) __builtin_amdgcn_s_sleep(4);
; template <int MODE>
; __device__ void attn_unit(unsigned char* lds, int b, int qb, const bf16_t* Qp, const bf16_t* Kp, const bf16_t* Vp, int ld, bf16_t* Op, int ldo, const float* Fbh, const float* reltab, const float* knsuf, const unsigned* fflag, unsigned fval) {
;     ...
; #pragma unroll
;     for (int nq = 0; nq < 2; ++nq) {
;         float l = lrun[nq]; l += __shfl_xor(l, 16); l += __shfl_xor(l, 32);
;         const float inv = 1.0f / l;
;         bf16_t* op = Op + (rowbase + qw0 + 16 * nq + cl) * ldo + quad * 4;
; #pragma unroll
;         for (int dt = 0; dt < 4; ++dt) { u32x2 w; w.x = pack2(o[dt][nq][0] * inv, o[dt][nq][1] * inv); w.y = pack2(o[dt][nq][2] * inv, o[dt][nq][3] * inv); *(u32x2*)(op + 16 * dt) = w; }
;     }
.LBB0_256:
	s_or_b64 exec, exec, s[28:29]
	v_readlane_b32 s0, v255, 21
	v_mov_b32_e32 v153, v1
	v_readlane_b32 s1, v255, 22
	v_lshlrev_b32_e32 v0, 1, v183
	s_nop 0
	v_lshl_add_u64 v[2:3], s[0:1], 0, v[152:153]
	v_lshl_add_u64 v[2:3], v[2:3], 0, v[0:1]
	ds_bpermute_b32 v0, v157, v165
	s_waitcnt lgkmcnt(0)
	v_add_f32_e32 v0, v165, v0
	ds_bpermute_b32 v4, v159, v0
	s_waitcnt lgkmcnt(0)
	v_add_f32_e32 v0, v0, v4
	v_div_scale_f32 v4, s[0:1], v0, v0, 1.0
	v_rcp_f32_e32 v5, v4
	s_nop 0
	v_fma_f32 v6, -v4, v5, 1.0
	v_fmac_f32_e32 v5, v6, v5
	v_div_scale_f32 v6, vcc, 1.0, v0, 1.0
	v_mul_f32_e32 v7, v6, v5
	v_fma_f32 v8, -v4, v7, v6
	v_fmac_f32_e32 v7, v8, v5
	v_fma_f32 v4, -v4, v7, v6
	v_div_fmas_f32 v4, v4, v5, v7
	v_div_fixup_f32 v0, v4, v0, 1.0
	v_lshlrev_b64 v[4:5], 11, v[150:151]
	v_pk_mul_f32 v[8:9], v[70:71], v[0:1] op_sel_hi:[1,0]
	v_pk_mul_f32 v[10:11], v[72:73], v[0:1] op_sel_hi:[1,0]
	v_lshl_add_u64 v[6:7], v[2:3], 0, v[4:5]
	v_cvt_pk_bf16_f32 v8, v8, v9
	v_cvt_pk_bf16_f32 v9, v10, v11
	global_store_dwordx2 v[6:7], v[8:9], off
	v_pk_mul_f32 v[8:9], v[50:51], v[0:1] op_sel_hi:[1,0]
	v_pk_mul_f32 v[10:11], v[52:53], v[0:1] op_sel_hi:[1,0]
	v_cvt_pk_bf16_f32 v8, v8, v9
	v_cvt_pk_bf16_f32 v9, v10, v11
	global_store_dwordx2 v[6:7], v[8:9], off offset:32
	v_pk_mul_f32 v[8:9], v[54:55], v[0:1] op_sel_hi:[1,0]
	v_pk_mul_f32 v[10:11], v[56:57], v[0:1] op_sel_hi:[1,0]
	v_cvt_pk_bf16_f32 v8, v8, v9
	v_cvt_pk_bf16_f32 v9, v10, v11
	global_store_dwordx2 v[6:7], v[8:9], off offset:64
	v_pk_mul_f32 v[8:9], v[66:67], v[0:1] op_sel_hi:[1,0]
	v_pk_mul_f32 v[10:11], v[68:69], v[0:1] op_sel_hi:[1,0]
	ds_bpermute_b32 v0, v157, v164
	v_cvt_pk_bf16_f32 v8, v8, v9
	v_cvt_pk_bf16_f32 v9, v10, v11
	global_store_dwordx2 v[6:7], v[8:9], off offset:96
	v_or_b32_e32 v4, 0x8000, v4
	s_waitcnt lgkmcnt(0)
	v_add_f32_e32 v0, v164, v0
	ds_bpermute_b32 v6, v159, v0
	v_lshl_add_u64 v[2:3], v[2:3], 0, v[4:5]
	s_waitcnt lgkmcnt(0)
	v_add_f32_e32 v0, v0, v6
	v_div_scale_f32 v6, s[0:1], v0, v0, 1.0
	v_rcp_f32_e32 v7, v6
	s_nop 0
	v_fma_f32 v8, -v6, v7, 1.0
	v_fmac_f32_e32 v7, v8, v7
	v_div_scale_f32 v8, vcc, 1.0, v0, 1.0
	v_mul_f32_e32 v9, v8, v7
	v_fma_f32 v10, -v6, v9, v8
	v_fmac_f32_e32 v9, v10, v7
	v_fma_f32 v6, -v6, v9, v8
	v_div_fmas_f32 v6, v6, v7, v9
	v_div_fixup_f32 v0, v6, v0, 1.0
	v_pk_mul_f32 v[4:5], v[38:39], v[0:1] op_sel_hi:[1,0]
	v_pk_mul_f32 v[6:7], v[40:41], v[0:1] op_sel_hi:[1,0]
	v_cvt_pk_bf16_f32 v4, v4, v5
	v_cvt_pk_bf16_f32 v5, v6, v7
	global_store_dwordx2 v[2:3], v[4:5], off
	v_pk_mul_f32 v[4:5], v[26:27], v[0:1] op_sel_hi:[1,0]
	v_pk_mul_f32 v[6:7], v[28:29], v[0:1] op_sel_hi:[1,0]
	v_cvt_pk_bf16_f32 v4, v4, v5
	v_cvt_pk_bf16_f32 v5, v6, v7
	global_store_dwordx2 v[2:3], v[4:5], off offset:32
	v_pk_mul_f32 v[4:5], v[34:35], v[0:1] op_sel_hi:[1,0]
	v_pk_mul_f32 v[6:7], v[36:37], v[0:1] op_sel_hi:[1,0]
	v_cvt_pk_bf16_f32 v4, v4, v5
	v_cvt_pk_bf16_f32 v5, v6, v7
	global_store_dwordx2 v[2:3], v[4:5], off offset:64
	v_pk_mul_f32 v[4:5], v[30:31], v[0:1] op_sel_hi:[1,0]
	v_pk_mul_f32 v[6:7], v[32:33], v[0:1] op_sel_hi:[1,0]
	v_cvt_pk_bf16_f32 v4, v4, v5
	v_cvt_pk_bf16_f32 v5, v6, v7
	global_store_dwordx2 v[2:3], v[4:5], off offset:96
	s_waitcnt lgkmcnt(0)
	s_barrier
.LBB0_257:
	v_readlane_b32 s0, v255, 49
	v_readlane_b32 s1, v255, 50
	s_andn2_saveexec_b64 s[10:11], s[0:1]
	s_cbranch_execz .LBB0_301
	v_add_u32_e32 v86, 0xfffff7d0, v90
	v_lshrrev_b32_e32 v4, 5, v86
	v_mov_b32_e32 v24, v212
	s_mov_b64 s[0:1], exec
	v_readlane_b32 s2, v254, 1
	v_readlane_b32 s3, v254, 2
	s_and_b64 s[2:3], s[0:1], s[2:3]
	s_mov_b64 exec, s[2:3]
	s_cbranch_execz .LBB0_263
	v_readlane_b32 s2, v255, 27
	v_lshlrev_b32_e32 v0, 2, v4
	v_readlane_b32 s3, v255, 28
	s_nop 1
	v_lshl_add_u64 v[2:3], s[2:3], 0, v[0:1]
	global_load_dword v0, v[2:3], off sc1
	s_waitcnt vmcnt(0) lgkmcnt(0)
	v_cmp_gt_u32_e32 vcc, s73, v0
	s_and_saveexec_b64 s[2:3], vcc
	s_cbranch_execz .LBB0_262
	s_mov_b64 s[4:5], 0

; template <int MODE>
; __device__ void attn_unit(unsigned char* lds, int b, int qb, const bf16_t* Qp, const bf16_t* Kp, const bf16_t* Vp, int ld, bf16_t* Op, int ldo, const float* Fbh, const float* reltab, const float* knsuf, const unsigned* fflag, unsigned fval) {
;     ...
;     if (MODE == 1) { for (int i = tid; i < 640; i += NTHR) { int rel = 575 - i; rel = rel < -63 ? -63 : (rel > 256 ? 256 : rel); ext[i] = reltab[rel + 63] * LOG2E; } }
;     bf16x8 qf[2][2];
; #pragma unroll
;     for (int nq = 0; nq < 2; ++nq)
; #pragma unroll
;         for (int ks = 0; ks < 2; ++ks) qf[nq][ks] = *(const bf16x8*)(Qp + (rowbase + qw0 + 16 * nq + cl) * ld + 32 * ks + quad * 8);
;     float mrun[2] = {-1e30f, -1e30f}, lrun[2] = {0.f, 0.f};
;     float qn[2] = {0.f, 0.f};
;     {
; #pragma unroll
;         for (int nq = 0; nq < 2; ++nq) { float ss = 0.f;
; #pragma unroll
;             for (int ks = 0; ks < 2; ++ks)
; #pragma unroll
;                 for (int j = 0; j < 8; ++j) { const float f = __uint_as_float(((unsigned)(unsigned short)qf[nq][ks][j]) << 16); ss += f * f; }
;             ss += __shfl_xor(ss, 16); ss += __shfl_xor(ss, 32); qn[nq] = sqrtf(ss) * 1.0001f; }
;     }
;     bool done = false;
;     float Rref[2] = {0.f, 0.f};
;     if (MODE == 1) { const float ka = knsuf[0], bm = knsuf[1]; Rref[0] = qn[0] * ka + bm + 1.0f; Rref[1] = qn[1] * ka + bm + 1.0f; }
;     else {
; #pragma unroll
;         for (int nq = 0; nq < 2; ++nq) { const int qrow = qw0 + 16 * nq + cl; Rref[nq] = qn[nq] * knsuf[qrow >> 6] + (Fref - Fbh[qrow]) * LOG2E + 1.0f; }
;     }
;     f32x4 o[4][2];
; #pragma unroll
;     for (int dt = 0; dt < 4; ++dt)
; #pragma unroll
;         for (int nq = 0; nq < 2; ++nq) o[dt][nq] = (f32x4){0.f, 0.f, 0.f, 0.f};
;     const int skey = tid >> 3, sdch = tid & 7;
;     const int vkey = tid & 63, vdch = tid >> 6;
;     const int vpos = (vkey & 32) + ((vkey >> 2) & 3) * 8 + ((vkey >> 4) & 1) * 4 + (vkey & 3);
;     u32x4 rk0, rv0, rk1, rv1, rk2, rv2; float rf0 = 0.f, rf1 = 0.f, rf2 = 0.f;
.LBB0_265:
	v_mov_b32_e32 v7, 0x100
	s_movk_i32 s4, 0xffc1
	v_med3_i32 v8, v6, s4, v7
	v_ashrrev_i32_e32 v9, 31, v8
	v_lshl_add_u64 v[8:9], v[8:9], 2, v[2:3]
	global_load_dword v7, v[8:9], off offset:252
	v_add_u32_e32 v5, 0x200, v5
	v_cmp_lt_i32_e32 vcc, s5, v5
	v_add_u32_e32 v6, 0xfffffe00, v6
	s_or_b64 s[2:3], vcc, s[2:3]
	s_waitcnt vmcnt(0) lgkmcnt(0)
	v_mul_f32_e32 v7, 0x3fb8aa3b, v7
	ds_write_b32 v0, v7
	v_add_u32_e32 v0, 0x800, v0
	s_andn2_b64 exec, exec, s[2:3]
	s_cbranch_execnz .LBB0_265
.LBB0_266:
	s_or_b64 exec, exec, s[0:1]
	v_readlane_b32 s0, v255, 13
	v_lshlrev_b32_e32 v0, 7, v130
	v_readlane_b32 s1, v255, 14
	v_and_b32_e32 v5, 31, v86
	v_ashrrev_i32_e32 v80, 6, v24
	v_lshl_add_u64 v[6:7], s[0:1], 0, v[0:1]
	v_readlane_b32 s0, v255, 29
	v_readlane_b32 s1, v255, 30
	v_lshlrev_b32_e32 v87, 6, v86
	v_lshlrev_b32_e32 v8, 2, v5
	v_lshl_add_u64 v[20:21], s[0:1], 0, v[0:1]
	v_readlane_b32 s0, v255, 31
	v_readlane_b32 s1, v255, 32
	v_cmp_lt_u32_e32 vcc, 2, v5
	v_and_b32_e32 v88, 15, v24
	v_lshl_add_u64 v[2:3], s[0:1], 0, v[0:1]
	v_lshlrev_b32_e32 v0, 3, v4
	v_readlane_b32 s0, v255, 33
	v_lshlrev_b32_e32 v4, 8, v5
	v_readlane_b32 s1, v255, 34
	v_lshl_add_u32 v78, v80, 5, v4
	v_add_u32_e32 v5, -8, v8
	v_lshl_add_u64 v[22:23], s[0:1], 0, v[0:1]
	v_and_b32_e32 v0, 0x7fffe000, v87
	v_ashrrev_i32_e32 v79, 31, v78
	v_cndmask_b32_e32 v120, 0, v5, vcc
	v_or_b32_e32 v5, 3, v8
	v_lshl_add_u64 v[118:119], v[78:79], 0, v[0:1]
	v_and_b32_e32 v82, 48, v24
	v_mov_b32_e32 v83, v1
	v_sub_u32_e32 v131, v5, v120
	v_or_b32_e32 v118, v118, v88
	v_lshl_add_u64 v[4:5], v[6:7], 0, v[82:83]
	v_mad_u64_u32 v[12:13], s[0:1], v118, s53, v[4:5]
	v_mad_i32_i24 v13, v119, s53, v13
	global_load_dwordx4 v[4:7], v[12:13], off
	global_load_dwordx4 v[8:11], v[12:13], off offset:64
	s_mov_b64 s[0:1], 0xc000
	v_lshl_add_u64 v[16:17], v[12:13], 0, s[0:1]
	s_mov_b32 s0, 0xc000
	v_add_co_u32_e64 v12, s[0:1], s0, v12
	v_and_b32_e32 v26, 64, v218
	s_nop 0
	v_addc_co_u32_e64 v13, s[0:1], 0, v13, s[0:1]
	global_load_dwordx4 v[12:15], v[12:13], off
	s_nop 0
	global_load_dwordx4 v[16:19], v[16:17], off offset:64
	v_xor_b32_e32 v25, 16, v218
	global_load_dwordx2 v[76:77], v[22:23], off
	v_add_u32_e32 v26, 64, v26
	v_cmp_lt_i32_e64 s[0:1], v25, v26
	v_cmp_lt_i32_e32 vcc, -1, v131
	v_and_b32_e32 v89, 63, v24
	v_cndmask_b32_e64 v25, v218, v25, s[0:1]
	v_lshlrev_b32_e32 v128, 2, v25
	v_xor_b32_e32 v25, 32, v218
	v_cmp_lt_i32_e64 s[0:1], v25, v26
	v_ashrrev_i32_e32 v84, 3, v24
	v_and_b32_e32 v91, 7, v24
	v_cndmask_b32_e64 v25, v218, v25, s[0:1]
	v_lshlrev_b32_e32 v129, 2, v25
	s_waitcnt vmcnt(0) lgkmcnt(0)
	v_and_b32_e32 v26, 0xffff0000, v4
	v_lshlrev_b32_e32 v25, 16, v4
	v_mul_f32_e32 v26, v26, v26
	v_fmac_f32_e32 v26, v25, v25
	v_lshlrev_b32_e32 v25, 16, v5
	v_fmac_f32_e32 v26, v25, v25
	v_and_b32_e32 v25, 0xffff0000, v5
	v_fmac_f32_e32 v26, v25, v25
	v_lshlrev_b32_e32 v25, 16, v6
	v_fmac_f32_e32 v26, v25, v25
	v_and_b32_e32 v25, 0xffff0000, v6
	v_fmac_f32_e32 v26, v25, v25
	v_lshlrev_b32_e32 v25, 16, v7
	v_fmac_f32_e32 v26, v25, v25
	v_and_b32_e32 v25, 0xffff0000, v7
	v_fmac_f32_e32 v26, v25, v25
	v_lshlrev_b32_e32 v25, 16, v8
	v_fmac_f32_e32 v26, v25, v25
	v_and_b32_e32 v25, 0xffff0000, v8
	v_fmac_f32_e32 v26, v25, v25
	v_lshlrev_b32_e32 v25, 16, v9
	v_fmac_f32_e32 v26, v25, v25
	v_and_b32_e32 v25, 0xffff0000, v9
	v_fmac_f32_e32 v26, v25, v25
	v_lshlrev_b32_e32 v25, 16, v10
	v_fmac_f32_e32 v26, v25, v25
	v_and_b32_e32 v25, 0xffff0000, v10
	v_fmac_f32_e32 v26, v25, v25
	v_lshlrev_b32_e32 v25, 16, v11
	v_fmac_f32_e32 v26, v25, v25
	v_and_b32_e32 v25, 0xffff0000, v11
	v_fmac_f32_e32 v26, v25, v25
	ds_bpermute_b32 v25, v128, v26
	s_waitcnt lgkmcnt(0)
	v_add_f32_e32 v79, v26, v25
	v_and_b32_e32 v26, 0xffff0000, v12
	v_lshlrev_b32_e32 v25, 16, v12
	v_mul_f32_e32 v26, v26, v26
	v_fmac_f32_e32 v26, v25, v25
	v_lshlrev_b32_e32 v25, 16, v13
	v_fmac_f32_e32 v26, v25, v25
	v_and_b32_e32 v25, 0xffff0000, v13
	v_fmac_f32_e32 v26, v25, v25
	v_lshlrev_b32_e32 v25, 16, v14
	v_fmac_f32_e32 v26, v25, v25
	v_and_b32_e32 v25, 0xffff0000, v14
	v_fmac_f32_e32 v26, v25, v25
	v_lshlrev_b32_e32 v25, 16, v15
	v_fmac_f32_e32 v26, v25, v25
	v_and_b32_e32 v25, 0xffff0000, v15
	v_fmac_f32_e32 v26, v25, v25
	v_lshlrev_b32_e32 v25, 16, v16
	v_fmac_f32_e32 v26, v25, v25
	v_and_b32_e32 v25, 0xffff0000, v16
	v_fmac_f32_e32 v26, v25, v25
	v_lshlrev_b32_e32 v25, 16, v17
	v_fmac_f32_e32 v26, v25, v25
	v_and_b32_e32 v25, 0xffff0000, v17
	v_fmac_f32_e32 v26, v25, v25
	v_lshlrev_b32_e32 v25, 16, v18
	v_fmac_f32_e32 v26, v25, v25
	v_and_b32_e32 v25, 0xffff0000, v18
	v_fmac_f32_e32 v26, v25, v25
	v_lshlrev_b32_e32 v25, 16, v19
	v_fmac_f32_e32 v26, v25, v25
	v_and_b32_e32 v25, 0xffff0000, v19
	v_fmac_f32_e32 v26, v25, v25
	ds_bpermute_b32 v25, v128, v26
	ds_bpermute_b32 v81, v129, v79
	s_waitcnt lgkmcnt(1)
	v_add_f32_e32 v83, v26, v25
	ds_bpermute_b32 v90, v129, v83
	s_and_saveexec_b64 s[0:1], vcc
	s_cbranch_execz .LBB0_268
	v_mov_b32_e32 v121, v1
	v_lshlrev_b64 v[22:23], 6, v[120:121]
	v_lshl_add_u64 v[22:23], v[22:23], 0, v[0:1]
	v_ashrrev_i32_e32 v85, 31, v84
	v_lshl_add_u64 v[26:27], v[22:23], 0, v[84:85]
	v_mad_u64_u32 v[28:29], s[2:3], v26, s53, v[20:21]
	v_mad_i32_i24 v29, v27, s53, v29
	v_lshlrev_b32_e32 v26, 4, v91
	v_mov_b32_e32 v27, v1
	v_or_b32_e32 v22, v22, v89
	v_lshl_add_u64 v[26:27], v[28:29], 0, v[26:27]
	v_mad_u64_u32 v[28:29], s[2:3], v22, s53, v[2:3]
	v_lshlrev_b32_e32 v22, 3, v80
	v_mad_u32_u24 v29, v23, s53, v29
	v_ashrrev_i32_e32 v23, 31, v22
	v_lshl_add_u64 v[22:23], v[22:23], 1, v[28:29]
	global_load_dwordx4 v[36:39], v[26:27], off
	global_load_dwordx4 v[40:43], v[22:23], off
; #define ATT_LOAD(S, r) do { if ((r) < nt) { const int t_ = ATT_TILE(r); rk##S = *(const u32x4*)(Kp + (rowbase + (size_t)t_ * 64 + skey) * ld + sdch * 8); rv##S = *(const u32x4*)(Vp + (rowbase + (size_t)t_ * 64 + vkey) * ld + vdch * 8); \
;         if (MODE == 0 && tid < 64) rf##S = Fbh[t_ * 64 + tid]; } } while (0)
; template <int MODE>
; __device__ void attn_unit(unsigned char* lds, int b, int qb, const bf16_t* Qp, const bf16_t* Kp, const bf16_t* Vp, int ld, bf16_t* Op, int ldo, const float* Fbh, const float* reltab, const float* knsuf, const unsigned* fflag, unsigned fval) {
;     ...
;     ATT_LOAD(0, 0); ATT_LOAD(1, 1); ATT_LOAD(2, 2);
;     ATT_STORE(0, 0);
;     __syncthreads();
.LBB0_268:
	s_or_b64 exec, exec, s[0:1]
	v_cmp_lt_i32_e64 s[0:1], 0, v131
	s_and_saveexec_b64 s[2:3], s[0:1]
	s_cbranch_execz .LBB0_270
	v_or_b32_e32 v22, 1, v120
	v_mov_b32_e32 v23, v1
	v_lshlrev_b64 v[22:23], 6, v[22:23]
	v_lshl_add_u64 v[22:23], v[22:23], 0, v[0:1]
	v_ashrrev_i32_e32 v85, 31, v84
	v_lshl_add_u64 v[26:27], v[22:23], 0, v[84:85]
	v_mad_u64_u32 v[28:29], s[0:1], v26, s53, v[20:21]
	v_mad_i32_i24 v29, v27, s53, v29
	v_lshlrev_b32_e32 v26, 4, v91
	v_mov_b32_e32 v27, v1
	v_or_b32_e32 v22, v22, v89
	v_lshl_add_u64 v[26:27], v[28:29], 0, v[26:27]
	v_mad_u64_u32 v[28:29], s[0:1], v22, s53, v[2:3]
	v_lshlrev_b32_e32 v22, 3, v80
	v_mad_u32_u24 v29, v23, s53, v29
	v_ashrrev_i32_e32 v23, 31, v22
	v_lshl_add_u64 v[22:23], v[22:23], 1, v[28:29]
	global_load_dwordx4 v[44:47], v[26:27], off
	global_load_dwordx4 v[52:55], v[22:23], off
.LBB0_270:
	s_or_b64 exec, exec, s[2:3]
	v_cmp_lt_i32_e64 s[0:1], 1, v131
	s_and_saveexec_b64 s[2:3], s[0:1]
	s_cbranch_execz .LBB0_272
	v_or_b32_e32 v22, 2, v120
	v_mov_b32_e32 v23, v1
	v_lshlrev_b64 v[22:23], 6, v[22:23]
	v_lshl_add_u64 v[22:23], v[22:23], 0, v[0:1]
	v_ashrrev_i32_e32 v85, 31, v84
	v_lshl_add_u64 v[26:27], v[22:23], 0, v[84:85]
	v_mad_u64_u32 v[20:21], s[0:1], v26, s53, v[20:21]
	v_mad_i32_i24 v21, v27, s53, v21
	v_lshlrev_b32_e32 v0, 4, v91
	v_lshl_add_u64 v[20:21], v[20:21], 0, v[0:1]
	v_or_b32_e32 v0, v22, v89
	v_mad_u64_u32 v[2:3], s[0:1], v0, s53, v[2:3]
	v_lshlrev_b32_e32 v22, 3, v80
	v_mad_u32_u24 v3, v23, s53, v3
	v_ashrrev_i32_e32 v23, 31, v22
	v_lshl_add_u64 v[2:3], v[22:23], 1, v[2:3]
	global_load_dwordx4 v[60:63], v[20:21], off
	global_load_dwordx4 v[64:67], v[2:3], off

.LBB0_278:
	s_add_i32 s14, s15, 3
	v_cmp_le_i32_e64 s[6:7], s14, v131
	v_cmp_gt_i32_e64 s[8:9], s14, v131
	s_and_saveexec_b64 s[0:1], s[6:7]
	s_cbranch_execz .LBB0_280
	s_waitcnt vmcnt(0)
	v_lshl_add_u64 v[36:37], v[126:127], 0, v[0:1]
	v_add_co_u32_e32 v36, vcc, 0x7690000, v36
	v_lshl_add_u64 v[40:41], v[124:125], 0, v[0:1]
	s_nop 0
	v_addc_co_u32_e32 v37, vcc, 0, v37, vcc
	v_add_co_u32_e32 v40, vcc, 0x7690000, v40
	global_load_dwordx4 v[36:39], v[36:37], off offset:512
	s_nop 0
	v_addc_co_u32_e32 v41, vcc, 0, v41, vcc
	global_load_dwordx4 v[40:43], v[40:41], off offset:1024

.LBB0_284:
	s_or_b64 exec, exec, s[0:1]
	s_waitcnt lgkmcnt(0)
	s_barrier
	s_and_saveexec_b64 s[4:5], vcc
	s_cbranch_execz .LBB0_292
	s_add_i32 s0, s15, 4
	v_cmp_le_i32_e32 vcc, s0, v131
	s_and_saveexec_b64 s[0:1], vcc
	s_cbranch_execz .LBB0_287
	s_waitcnt vmcnt(0)
	v_lshl_add_u64 v[44:45], v[126:127], 0, v[0:1]
	v_add_co_u32_e32 v44, vcc, 0x76c0000, v44
	v_lshl_add_u64 v[52:53], v[124:125], 0, v[0:1]
	s_nop 0
	v_addc_co_u32_e32 v45, vcc, 0, v45, vcc
	v_add_co_u32_e32 v52, vcc, 0x76c0000, v52
	global_load_dwordx4 v[44:47], v[44:45], off offset:512
	s_nop 0
	v_addc_co_u32_e32 v53, vcc, 0, v53, vcc
	global_load_dwordx4 v[52:55], v[52:53], off offset:1024

.LBB0_292:
	s_or_b64 exec, exec, s[4:5]
	s_and_b64 s[0:1], exec, s[8:9]
	s_or_b64 s[2:3], s[0:1], s[2:3]
	s_add_i32 s0, s15, 2
	v_cmp_le_i32_e32 vcc, s0, v131
	s_and_saveexec_b64 s[4:5], vcc
	s_cbranch_execz .LBB0_277
	s_add_i32 s0, s15, 5
	v_cmp_le_i32_e32 vcc, s0, v131
	s_and_saveexec_b64 s[0:1], vcc
	s_cbranch_execz .LBB0_295
	s_waitcnt vmcnt(0)
	v_lshl_add_u64 v[60:61], v[126:127], 0, v[0:1]
	v_add_co_u32_e32 v60, vcc, 0x76f0000, v60
	v_lshl_add_u64 v[64:65], v[124:125], 0, v[0:1]
	s_nop 0
	v_addc_co_u32_e32 v61, vcc, 0, v61, vcc
	v_add_co_u32_e32 v64, vcc, 0x76f0000, v64
	global_load_dwordx4 v[60:63], v[60:61], off offset:512
	s_nop 0
	v_addc_co_u32_e32 v65, vcc, 0, v65, vcc
	global_load_dwordx4 v[64:67], v[64:65], off offset:1024

; __device__ __forceinline__ unsigned pack2(float lo, float hi) { return pg8::cvt_pk_bf16(lo, hi); }
; template <int MODE>
; __device__ void attn_unit(unsigned char* lds, int b, int qb, const bf16_t* Qp, const bf16_t* Kp, const bf16_t* Vp, int ld, bf16_t* Op, int ldo, const float* Fbh, const float* reltab, const float* knsuf, const unsigned* fflag, unsigned fval) {
;     ...
; #pragma unroll
;     for (int nq = 0; nq < 2; ++nq) {
;         float l = lrun[nq]; l += __shfl_xor(l, 16); l += __shfl_xor(l, 32);
;         const float inv = 1.0f / l;
;         bf16_t* op = Op + (rowbase + qw0 + 16 * nq + cl) * ldo + quad * 4;
; #pragma unroll
;         for (int dt = 0; dt < 4; ++dt) { u32x2 w; w.x = pack2(o[dt][nq][0] * inv, o[dt][nq][1] * inv); w.y = pack2(o[dt][nq][2] * inv, o[dt][nq][3] * inv); *(u32x2*)(op + 16 * dt) = w; }
;     }
.LBB0_300:
	s_or_b64 exec, exec, s[12:13]
	v_lshlrev_b32_e32 v0, 6, v130
	v_lshlrev_b32_e32 v0, 1, v0
	v_lshl_add_u64 v[2:3], s[26:27], 0, v[0:1]
	v_lshlrev_b32_e32 v0, 1, v121
	v_lshl_add_u64 v[2:3], v[2:3], 0, v[0:1]
	ds_bpermute_b32 v0, v128, v123
	s_waitcnt lgkmcnt(0)
	v_add_f32_e32 v0, v123, v0
	ds_bpermute_b32 v4, v129, v0
	s_waitcnt lgkmcnt(0)
	v_add_f32_e32 v0, v0, v4
	v_div_scale_f32 v4, s[0:1], v0, v0, 1.0
	v_rcp_f32_e32 v5, v4
	s_nop 0
	v_fma_f32 v6, -v4, v5, 1.0
	v_fmac_f32_e32 v5, v6, v5
	v_div_scale_f32 v6, vcc, 1.0, v0, 1.0
	v_mul_f32_e32 v7, v6, v5
	v_fma_f32 v8, -v4, v7, v6
	v_fmac_f32_e32 v7, v8, v5
	v_fma_f32 v4, -v4, v7, v6
	v_div_fmas_f32 v4, v4, v5, v7
	v_div_fixup_f32 v0, v4, v0, 1.0
	v_lshlrev_b64 v[4:5], 11, v[118:119]
	v_pk_mul_f32 v[8:9], v[72:73], v[0:1] op_sel_hi:[1,0]
	v_pk_mul_f32 v[10:11], v[74:75], v[0:1] op_sel_hi:[1,0]
	v_lshl_add_u64 v[6:7], v[2:3], 0, v[4:5]
	v_cvt_pk_bf16_f32 v8, v8, v9
	v_cvt_pk_bf16_f32 v9, v10, v11
	global_store_dwordx2 v[6:7], v[8:9], off
	v_pk_mul_f32 v[8:9], v[48:49], v[0:1] op_sel_hi:[1,0]
	v_pk_mul_f32 v[10:11], v[50:51], v[0:1] op_sel_hi:[1,0]
	v_cvt_pk_bf16_f32 v8, v8, v9
	v_cvt_pk_bf16_f32 v9, v10, v11
	global_store_dwordx2 v[6:7], v[8:9], off offset:32
	v_pk_mul_f32 v[8:9], v[56:57], v[0:1] op_sel_hi:[1,0]
	v_pk_mul_f32 v[10:11], v[58:59], v[0:1] op_sel_hi:[1,0]
	v_cvt_pk_bf16_f32 v8, v8, v9
	v_cvt_pk_bf16_f32 v9, v10, v11
	global_store_dwordx2 v[6:7], v[8:9], off offset:64
	v_pk_mul_f32 v[8:9], v[68:69], v[0:1] op_sel_hi:[1,0]
	v_pk_mul_f32 v[10:11], v[70:71], v[0:1] op_sel_hi:[1,0]
	ds_bpermute_b32 v0, v128, v122
	v_cvt_pk_bf16_f32 v8, v8, v9
	v_cvt_pk_bf16_f32 v9, v10, v11
	global_store_dwordx2 v[6:7], v[8:9], off offset:96
	v_or_b32_e32 v4, 0x8000, v4
	s_waitcnt lgkmcnt(0)
	v_add_f32_e32 v0, v122, v0
	ds_bpermute_b32 v6, v129, v0
	v_lshl_add_u64 v[2:3], v[2:3], 0, v[4:5]
	s_waitcnt lgkmcnt(0)
	v_add_f32_e32 v0, v0, v6
	v_div_scale_f32 v6, s[0:1], v0, v0, 1.0
	v_rcp_f32_e32 v7, v6
	s_nop 0
	v_fma_f32 v8, -v6, v7, 1.0
	v_fmac_f32_e32 v7, v8, v7
	v_div_scale_f32 v8, vcc, 1.0, v0, 1.0
	v_mul_f32_e32 v9, v8, v7
	v_fma_f32 v10, -v6, v9, v8
	v_fmac_f32_e32 v9, v10, v7
	v_fma_f32 v6, -v6, v9, v8
	v_div_fmas_f32 v6, v6, v7, v9
	v_div_fixup_f32 v0, v6, v0, 1.0
	v_pk_mul_f32 v[4:5], v[32:33], v[0:1] op_sel_hi:[1,0]
	v_pk_mul_f32 v[6:7], v[34:35], v[0:1] op_sel_hi:[1,0]
	v_cvt_pk_bf16_f32 v4, v4, v5
	v_cvt_pk_bf16_f32 v5, v6, v7
	global_store_dwordx2 v[2:3], v[4:5], off
	v_pk_mul_f32 v[4:5], v[20:21], v[0:1] op_sel_hi:[1,0]
	v_pk_mul_f32 v[6:7], v[22:23], v[0:1] op_sel_hi:[1,0]
	v_cvt_pk_bf16_f32 v4, v4, v5
	v_cvt_pk_bf16_f32 v5, v6, v7
	global_store_dwordx2 v[2:3], v[4:5], off offset:32
	v_pk_mul_f32 v[4:5], v[28:29], v[0:1] op_sel_hi:[1,0]
	v_pk_mul_f32 v[6:7], v[30:31], v[0:1] op_sel_hi:[1,0]
	v_cvt_pk_bf16_f32 v4, v4, v5
	v_cvt_pk_bf16_f32 v5, v6, v7
	global_store_dwordx2 v[2:3], v[4:5], off offset:64
	v_pk_mul_f32 v[4:5], v[24:25], v[0:1] op_sel_hi:[1,0]
	v_pk_mul_f32 v[6:7], v[26:27], v[0:1] op_sel_hi:[1,0]
	v_cvt_pk_bf16_f32 v4, v4, v5
	v_cvt_pk_bf16_f32 v5, v6, v7
	global_store_dwordx2 v[2:3], v[4:5], off offset:96
	s_waitcnt lgkmcnt(0)
	s_barrier

; __device__ __forceinline__ float softplus_f(float x) { return fmaxf(x, 0.f) + log1pf(__expf(-fabsf(x))); }
; __device__ void prep_unit(unsigned char* lds, int bh, int n, const bf16_t* pc, const float* scal, const float* convw  , float alog, float dtb, unsigned char* unit, float* egl, unsigned* flag, unsigned fval) {
;     ...
;     } else if (tid < 448) {
;         const int t = tid - 384; const float* sp = scal + (row0 + t) * 16;
;         bet[t] = 1.0f / (1.0f + __expf(-sp[4 + h]));
;         gc[t] = -__expf(alog) * softplus_f(sp[8 + h] + dtb);
;     }
; __device__ void run_phase(const Params& p, unsigned char* lds, int ph) {
;     ...
;             else if (it < 2096) { const int j = it - 48, n = j >> 4, bh = j & 15, h = bh & 3;
;                 prep_unit(lds, bh, n, (const bf16_t*)(ws + WS_PC), (const float*)(ws + WS_SCAL), p.in[I_CONVW] + (size_t)l * 4 * 1536, p.in[I_ALOG][l * 4 + h], p.in[I_DTB][l * 4 + h],
;                           ws + WS_PREP + (size_t)(bh * 128 + n) * PREP_UNIT, (float*)(ws + WS_EGL), uflag + bh * 128 + n, fval); }
.LBB0_302:
	s_or_saveexec_b64 s[12:13], s[0:1]
	v_readlane_b32 s4, v255, 45
	v_readlane_b32 s5, v255, 46
	s_xor_b64 exec, exec, s[12:13]
	s_cbranch_execz .LBB0_449
	v_and_b32_e32 v2, 3, v90
	v_or_b32_e32 v4, s48, v2
	v_ashrrev_i32_e32 v5, 31, v4
	v_readlane_b32 s0, v254, 61
	v_lshlrev_b64 v[4:5], 2, v[4:5]
	v_readlane_b32 s1, v254, 62
	v_subrev_u32_e32 v0, 48, v90
	v_lshrrev_b32_e32 v0, 4, v0
	v_lshl_add_u64 v[6:7], s[0:1], 0, v[4:5]
	v_readlane_b32 s0, v254, 63
	v_readlane_b32 s1, v255, 0
	global_load_dword v3, v[6:7], off
	v_mov_b32_e32 v156, v212
	v_lshl_add_u64 v[4:5], s[0:1], 0, v[4:5]
	global_load_dword v4, v[4:5], off
	v_lshlrev_b32_e32 v5, 11, v90
	s_movk_i32 s0, 0x17f
	v_and_b32_e32 v6, 0x6000, v5
	v_and_b32_e32 v157, 63, v156
	v_mov_b32_e32 v7, v1
	v_lshlrev_b64 v[8:9], 6, v[0:1]
	v_cmp_lt_i32_e32 vcc, s0, v156
	s_movk_i32 s0, 0x7f
	v_lshl_add_u64 v[22:23], v[8:9], 0, v[6:7]
	v_cmp_gt_u32_e64 s[10:11], s46, v156
	v_cmp_lt_u32_e64 s[8:9], s0, v156
	v_cmp_gt_u32_e64 s[6:7], 8, v157
	s_and_saveexec_b64 s[0:1], vcc
	s_xor_b64 s[0:1], exec, s[0:1]
	s_cbranch_execz .LBB0_307
	s_movk_i32 s2, 0x1c0
	v_cmp_gt_u32_e32 vcc, s2, v156
	s_and_saveexec_b64 s[2:3], vcc
	s_cbranch_execz .LBB0_306
	v_add_u32_e32 v6, 0xfffffe80, v156
	v_mov_b32_e32 v7, v1
	v_lshl_add_u64 v[8:9], v[22:23], 0, v[6:7]
	v_readlane_b32 s4, v255, 37
	v_lshlrev_b64 v[8:9], 6, v[8:9]
	v_readlane_b32 s5, v255, 38
	v_lshlrev_b32_e32 v10, 2, v2
	v_mov_b32_e32 v11, v1
	v_lshl_add_u64 v[8:9], s[4:5], 0, v[8:9]
	v_lshl_add_u64 v[8:9], v[8:9], 0, v[10:11]
	v_lshl_add_u32 v5, v6, 2, 0
	v_add_u32_e32 v6, 0x22100, v5
	s_waitcnt vmcnt(0) lgkmcnt(0)
	v_mul_f32_e32 v2, 0x3fb8aa3b, v3
	v_add_u32_e32 v3, 0x22000, v5
	global_load_dword v5, v[8:9], off offset:16
	v_exp_f32_e32 v2, v2
	s_waitcnt vmcnt(0) lgkmcnt(0)
	v_mul_f32_e32 v5, 0xbfb8aa3b, v5
	v_exp_f32_e32 v5, v5
	s_nop 0
	v_add_f32_e32 v5, 1.0, v5
	v_div_scale_f32 v7, s[4:5], v5, v5, 1.0
	v_rcp_f32_e32 v10, v7
	s_mov_b32 s4, 0xbfb8aa3b
	v_fma_f32 v11, -v7, v10, 1.0
	v_fmac_f32_e32 v10, v11, v10
	v_div_scale_f32 v11, vcc, 1.0, v5, 1.0
	v_mul_f32_e32 v12, v11, v10
	v_fma_f32 v13, -v7, v12, v11
	v_fmac_f32_e32 v12, v13, v10
	v_fma_f32 v7, -v7, v12, v11
	v_div_fmas_f32 v7, v7, v10, v12
	v_div_fixup_f32 v5, v7, v5, 1.0
	ds_write_b32 v6, v5
	global_load_dword v5, v[8:9], off offset:32
	s_waitcnt vmcnt(0) lgkmcnt(0)
	v_add_f32_e32 v5, v4, v5
	v_max_f32_e32 v4, 0, v5
	v_mul_f32_e64 v5, |v5|, s4
	v_exp_f32_e32 v5, v5
	s_mov_b32 s4, 0x3f2aaaab
	v_add_f32_e32 v8, 1.0, v5
	v_add_f32_e32 v6, -1.0, v8
	v_sub_f32_e32 v7, v6, v8
	v_add_f32_e32 v7, 1.0, v7
	v_sub_f32_e32 v6, v5, v6
	v_add_f32_e32 v9, v6, v7
	v_frexp_mant_f32_e32 v6, v8
	v_cmp_gt_f32_e32 vcc, s4, v6
	v_cvt_f64_f32_e32 v[6:7], v8
	v_frexp_exp_i32_f64_e32 v6, v[6:7]
	v_subbrev_co_u32_e32 v6, vcc, 0, v6, vcc
	v_sub_u32_e32 v7, 0, v6
	v_ldexp_f32 v8, v8, v7
	v_ldexp_f32 v7, v9, v7
	v_add_f32_e32 v9, -1.0, v8
	v_add_f32_e32 v10, 1.0, v9
	v_sub_f32_e32 v10, v8, v10
	v_add_f32_e32 v10, v7, v10
	v_add_f32_e32 v11, v9, v10
	v_sub_f32_e32 v9, v11, v9
	v_sub_f32_e32 v9, v10, v9
	v_add_f32_e32 v10, 1.0, v8
	v_add_f32_e32 v12, -1.0, v10
	v_sub_f32_e32 v8, v8, v12
	v_add_f32_e32 v7, v7, v8
	v_add_f32_e32 v8, v10, v7
	v_sub_f32_e32 v10, v8, v10
	v_sub_f32_e32 v7, v7, v10
	v_rcp_f32_e32 v10, v8
	v_cvt_f32_i32_e32 v6, v6
	s_mov_b32 s4, 0x3f317218
	v_mul_f32_e32 v12, v11, v10
	v_mul_f32_e32 v13, v8, v12
	v_fma_f32 v14, v12, v8, -v13
	v_fmac_f32_e32 v14, v12, v7
	v_add_f32_e32 v15, v13, v14
	v_sub_f32_e32 v16, v11, v15
	v_sub_f32_e32 v11, v11, v16
	v_sub_f32_e32 v13, v15, v13
	v_sub_f32_e32 v11, v11, v15
	v_add_f32_e32 v9, v9, v11
	v_sub_f32_e32 v11, v13, v14
	v_add_f32_e32 v9, v11, v9
	v_add_f32_e32 v11, v16, v9
	v_mul_f32_e32 v13, v10, v11
	v_mul_f32_e32 v14, v8, v13
	v_fma_f32 v8, v13, v8, -v14
	v_fmac_f32_e32 v8, v13, v7
	v_sub_f32_e32 v7, v16, v11
	v_add_f32_e32 v7, v9, v7
	v_add_f32_e32 v9, v14, v8
	v_sub_f32_e32 v15, v11, v9
	v_sub_f32_e32 v11, v11, v15
	v_sub_f32_e32 v14, v9, v14
	v_sub_f32_e32 v9, v11, v9
	v_add_f32_e32 v7, v7, v9
	v_sub_f32_e32 v8, v14, v8
	v_add_f32_e32 v7, v8, v7
	v_add_f32_e32 v8, v12, v13
	v_add_f32_e32 v7, v15, v7
	v_sub_f32_e32 v9, v8, v12
	v_mul_f32_e32 v7, v10, v7
	v_sub_f32_e32 v9, v13, v9
	v_add_f32_e32 v7, v9, v7
	v_mul_f32_e32 v12, 0x3f317218, v6
	v_add_f32_e32 v9, v8, v7
	v_fma_f32 v13, v6, s4, -v12
	v_mul_f32_e32 v10, v9, v9
	v_fmac_f32_e32 v13, 0xb102e308, v6
	v_sub_f32_e32 v6, v9, v8
	v_fmamk_f32 v11, v10, 0x3e9b6dac, v216
	v_sub_f32_e32 v6, v7, v6
	v_add_f32_e32 v7, v12, v13
	v_fmaak_f32 v11, v10, v11, 0x3f2aaada
	v_sub_f32_e32 v8, v7, v12
	v_ldexp_f32 v12, v9, 1
	v_mul_f32_e32 v9, v9, v10
	v_mul_f32_e32 v9, v9, v11
	v_add_f32_e32 v10, v12, v9
	v_sub_f32_e32 v11, v10, v12
	v_ldexp_f32 v6, v6, 1
	v_sub_f32_e32 v9, v9, v11
	v_add_f32_e32 v6, v6, v9
	v_add_f32_e32 v9, v10, v6
	v_sub_f32_e32 v10, v9, v10
	v_sub_f32_e32 v6, v6, v10
	v_add_f32_e32 v10, v7, v9
	v_sub_f32_e32 v11, v10, v7
	v_sub_f32_e32 v12, v10, v11
	v_sub_f32_e32 v8, v13, v8
	v_sub_f32_e32 v7, v7, v12
	v_sub_f32_e32 v9, v9, v11
	v_add_f32_e32 v7, v9, v7
	v_add_f32_e32 v9, v8, v6
	v_sub_f32_e32 v11, v9, v8
	v_sub_f32_e32 v12, v9, v11
	v_sub_f32_e32 v8, v8, v12
	v_sub_f32_e32 v6, v6, v11
	v_add_f32_e32 v7, v9, v7
	v_add_f32_e32 v6, v6, v8
	v_add_f32_e32 v8, v10, v7
	v_sub_f32_e32 v9, v8, v10
	v_sub_f32_e32 v7, v7, v9
	v_add_f32_e32 v6, v6, v7
	s_mov_b32 s4, 0x7f800000
	v_add_f32_e32 v6, v8, v6
	v_cmp_neq_f32_e32 vcc, s4, v5
	s_mov_b32 s4, 0x33800000
	s_nop 0
	v_cndmask_b32_e32 v6, v220, v6, vcc
	v_cmp_ngt_f32_e32 vcc, -1.0, v5
	s_nop 1
	v_cndmask_b32_e32 v6, v221, v6, vcc
	v_cmp_neq_f32_e32 vcc, -1.0, v5
	s_nop 1
	v_cndmask_b32_e32 v6, v222, v6, vcc
	v_cmp_lt_f32_e64 vcc, |v5|, s4
	s_nop 1
	v_cndmask_b32_e32 v5, v6, v5, vcc
	v_add_f32_e32 v4, v4, v5
	v_mul_f32_e64 v2, v4, -v2
	ds_write_b32 v3, v2

; __device__ void prep_unit(unsigned char* lds, int bh, int n, const bf16_t* pc, const float* scal, const float* convw  , float alog, float dtb, unsigned char* unit, float* egl, unsigned* flag, unsigned fval) {
;     ...
;     if (tid < 384) {
;         const int part = tid >> 7, cg8 = (tid & 127) >> 3, run = tid & 7, col = part * 512 + h * 128 + cg8 * 8;
;         float w[4][8];
; #pragma unroll
;         for (int i = 0; i < 4; ++i) { const f32x4 w0 = *(const f32x4*)(convw + i * 1536 + col), w1 = *(const f32x4*)(convw + i * 1536 + col + 4);
; #pragma unroll
;             for (int j = 0; j < 4; ++j) { w[i][j] = w0[j]; w[i][4 + j] = w1[j]; } }
;         u32x4 xr[11];
; #pragma unroll
;         for (int i = 0; i < 11; ++i) { const int tl = run * 8 - 3 + i; const bool ok = (n > 0) || (tl >= 0);
;             xr[i] = ok ? __builtin_nontemporal_load((const u32x4*)(pc + (row0 + tl) * 1536 + col)) : (u32x4){0u, 0u, 0u, 0u}; }
;         float y[8][8];
; #pragma unroll
;         for (int t = 0; t < 8; ++t)
; #pragma unroll
;             for (int j = 0; j < 8; ++j) y[t][j] = 0.f;
; #pragma unroll
;         for (int i = 0; i < 11; ++i) { float xf[8]; unpack8(xr[i], xf);
; #pragma unroll
;             for (int t = 0; t < 8; ++t) { const int wi = i - t; if (wi >= 0 && wi < 4) {
; #pragma unroll
;                 for (int j = 0; j < 8; ++j) y[t][j] += w[wi][j] * xf[j]; } } }
.LBB0_307:
	s_or_saveexec_b64 s[0:1], s[0:1]
	v_and_b32_e32 v91, 7, v156
	s_xor_b64 exec, exec, s[0:1]
	s_cbranch_execz .LBB0_318
	v_ashrrev_i32_e32 v18, 7, v156
	s_waitcnt vmcnt(0)
	v_and_b32_e32 v42, 0x78, v156
	s_waitcnt lgkmcnt(0)
	v_lshlrev_b32_e32 v3, 9, v18
	v_lshlrev_b32_e32 v2, 7, v2
	v_or3_b32 v20, v3, v2, v42
	v_readlane_b32 s2, v255, 41
	v_ashrrev_i32_e32 v21, 31, v20
	v_readlane_b32 s3, v255, 42
	v_lshlrev_b32_e32 v19, 3, v91
	v_mov_b32_e32 v82, 0
	v_lshl_add_u64 v[10:11], v[20:21], 2, s[2:3]
	v_add_co_u32_e32 v2, vcc, 0x1000, v10
	global_load_dwordx4 v[66:69], v[10:11], off
	global_load_dwordx4 v[14:17], v[10:11], off offset:16
	v_addc_co_u32_e32 v3, vcc, 0, v11, vcc
	v_add_co_u32_e32 v6, vcc, 0x3000, v10
	global_load_dwordx4 v[70:73], v[2:3], off offset:2048
	s_nop 0
	global_load_dwordx4 v[2:5], v[2:3], off offset:2064
	v_addc_co_u32_e32 v7, vcc, 0, v11, vcc
	v_add_co_u32_e32 v10, vcc, 0x4000, v10
	global_load_dwordx4 v[74:77], v[6:7], off
	s_nop 0
	global_load_dwordx4 v[6:9], v[6:7], off offset:16
	v_addc_co_u32_e32 v11, vcc, 0, v11, vcc
	global_load_dwordx4 v[78:81], v[10:11], off offset:2048
	s_nop 0
	global_load_dwordx4 v[10:13], v[10:11], off offset:2064
	v_readlane_b32 s2, v255, 35
	v_readlane_b32 s3, v255, 36
	v_mov_b32_e32 v86, 0
	v_mov_b32_e32 v87, 0
	v_lshl_add_u64 v[24:25], v[20:21], 1, s[2:3]
	v_or_b32_e32 v20, v91, v0
	v_cmp_ne_u32_e32 vcc, 0, v20
	v_mov_b32_e32 v88, 0
	v_mov_b32_e32 v89, 0
	s_and_saveexec_b64 s[2:3], vcc
	s_cbranch_execz .LBB0_310
	v_add_u32_e32 v20, -3, v19
	v_ashrrev_i32_e32 v21, 31, v20
	v_lshl_add_u64 v[20:21], v[22:23], 0, v[20:21]
	v_mad_u64_u32 v[26:27], s[4:5], v20, s53, v[24:25]
	v_mad_i32_i24 v27, v21, s53, v27
	global_load_dwordx4 v[86:89], v[26:27], off nt
.LBB0_310:
	s_or_b64 exec, exec, s[2:3]
	v_mov_b32_e32 v83, 0
	v_mov_b32_e32 v84, 0
	v_mov_b32_e32 v85, 0
	s_and_saveexec_b64 s[2:3], vcc
	s_cbranch_execz .LBB0_312
	v_add_u32_e32 v20, -2, v19
	v_ashrrev_i32_e32 v21, 31, v20
	v_lshl_add_u64 v[20:21], v[22:23], 0, v[20:21]
	v_mad_u64_u32 v[26:27], s[4:5], v20, s53, v[24:25]
	v_mad_i32_i24 v27, v21, s53, v27
	global_load_dwordx4 v[82:85], v[26:27], off nt
.LBB0_312:
	s_or_b64 exec, exec, s[2:3]
	v_mov_b32_e32 v54, 0
	v_mov_b32_e32 v55, 0
	v_mov_b32_e32 v56, 0
	v_mov_b32_e32 v57, 0
	s_and_saveexec_b64 s[2:3], vcc
	s_cbranch_execz .LBB0_314
	v_add_u32_e32 v20, -1, v19
	v_ashrrev_i32_e32 v21, 31, v20
	v_lshl_add_u64 v[20:21], v[22:23], 0, v[20:21]
	v_mad_u64_u32 v[26:27], s[4:5], v20, s53, v[24:25]
	v_mad_i32_i24 v27, v21, s53, v27
	global_load_dwordx4 v[54:57], v[26:27], off nt
.LBB0_314:
	s_or_b64 exec, exec, s[2:3]
	v_cmp_eq_u32_e32 vcc, 1, v18
	v_mov_b32_e32 v20, 0x11000
	v_mov_b32_e32 v21, 0x8800
	v_or_b32_e32 v22, v19, v22
	v_cndmask_b32_e32 v20, v20, v21, vcc
	v_cmp_gt_i32_e32 vcc, 2, v18
	v_mad_u64_u32 v[18:19], s[2:3], v22, s53, v[24:25]
	v_mad_u32_u24 v19, v23, s53, v19
	global_load_dwordx4 v[58:61], v[18:19], off nt
	v_or_b32_e32 v18, 1, v22
	v_mad_u64_u32 v[18:19], s[2:3], v18, s53, v[24:25]
	v_mad_u32_u24 v19, v23, s53, v19
	global_load_dwordx4 v[62:65], v[18:19], off nt
	v_or_b32_e32 v18, 2, v22
	v_mad_u64_u32 v[18:19], s[2:3], v18, s53, v[24:25]
	v_mad_u32_u24 v19, v23, s53, v19
	global_load_dwordx4 v[44:47], v[18:19], off nt
	v_or_b32_e32 v18, 3, v22
	v_mad_u64_u32 v[18:19], s[2:3], v18, s53, v[24:25]
	v_mad_u32_u24 v19, v23, s53, v19
	global_load_dwordx4 v[48:51], v[18:19], off nt
	v_or_b32_e32 v18, 4, v22
	v_mad_u64_u32 v[18:19], s[2:3], v18, s53, v[24:25]
	v_mad_u32_u24 v19, v23, s53, v19
	global_load_dwordx4 v[34:37], v[18:19], off nt
	v_or_b32_e32 v18, 5, v22
	v_mad_u64_u32 v[18:19], s[2:3], v18, s53, v[24:25]
	v_mad_u32_u24 v19, v23, s53, v19
	global_load_dwordx4 v[38:41], v[18:19], off nt
	v_or_b32_e32 v18, 6, v22
	v_or_b32_e32 v22, 7, v22
	v_mad_u64_u32 v[18:19], s[2:3], v18, s53, v[24:25]
	v_mad_u64_u32 v[24:25], s[2:3], v22, s53, v[24:25]
	v_add_u32_e32 v20, 0, v20
	v_mad_u32_u24 v19, v23, s53, v19
	v_mad_u32_u24 v25, v23, s53, v25
	v_cndmask_b32_e64 v43, v20, 0, s[10:11]
	global_load_dwordx4 v[18:21], v[18:19], off nt
	s_waitcnt vmcnt(0) lgkmcnt(0)
	v_and_b32_e32 v130, 0xffff0000, v84
	global_load_dwordx4 v[22:25], v[24:25], off nt
	v_and_b32_e32 v26, 0xffff0000, v88
	v_mov_b32_e32 v27, v130
	v_pk_fma_f32 v[136:137], v[14:15], v[26:27], 0 op_sel:[1,0,0] op_sel_hi:[1,1,0]
	v_lshlrev_b32_e32 v138, 16, v56
	v_lshlrev_b32_e32 v27, 16, v84
	v_lshlrev_b32_e32 v26, 16, v88
	v_pk_fma_f32 v[28:29], v[14:15], v[26:27], 0 op_sel_hi:[0,1,0]
	v_and_b32_e32 v128, 0xffff0000, v85
	v_lshlrev_b32_e32 v133, 16, v85
	v_lshlrev_b32_e32 v84, 16, v87
	v_lshlrev_b32_e32 v85, 16, v83
	v_and_b32_e32 v126, 0xffff0000, v89
	v_lshlrev_b32_e32 v132, 16, v89
	v_pk_fma_f32 v[88:89], v[68:69], v[84:85], 0 op_sel_hi:[0,1,0]
	v_and_b32_e32 v131, 0xffff0000, v56
	v_mov_b32_e32 v56, v77
	v_lshlrev_b32_e32 v158, 5, v91
	v_lshlrev_b32_e32 v104, 16, v57
	v_mov_b32_e32 v127, v128
	v_lshlrev_b32_e32 v139, 16, v60
	v_pk_mov_b32 v[26:27], v[26:27], v[138:139] op_sel:[1,0]
	v_mov_b32_e32 v134, v139
	v_pk_fma_f32 v[144:145], v[2:3], v[26:27], v[28:29] op_sel_hi:[0,1,1]
	v_pk_fma_f32 v[26:27], v[14:15], v[138:139], 0 op_sel_hi:[0,1,0]
	v_lshlrev_b32_e32 v135, 16, v64
	v_pk_fma_f32 v[120:121], v[2:3], v[134:135], v[26:27] op_sel_hi:[0,1,1]
	v_lshlrev_b32_e32 v26, 16, v55
	v_lshlrev_b32_e32 v27, 16, v59
	v_pk_mov_b32 v[84:85], v[84:85], v[26:27] op_sel:[1,0]
	v_lshlrev_b32_e32 v29, 16, v63
	v_pk_fma_f32 v[84:85], v[72:73], v[84:85], v[88:89] op_sel_hi:[0,1,1]
	v_mov_b32_e32 v28, v27
	v_pk_fma_f32 v[32:33], v[68:69], v[26:27], 0 op_sel_hi:[0,1,0]
	v_pk_fma_f32 v[26:27], v[76:77], v[26:27], v[84:85] op_sel_hi:[0,1,1]
; __device__ __forceinline__ float silu_f(float x) { return x * __builtin_amdgcn_rcpf(1.0f + __expf(-x)); }
; __device__ void prep_unit(unsigned char* lds, int bh, int n, const bf16_t* pc, const float* scal, const float* convw  , float alog, float dtb, unsigned char* unit, float* egl, unsigned* flag, unsigned fval) {
;     ...
;         for (int i = 0; i < 11; ++i) { float xf[8]; unpack8(xr[i], xf);
; #pragma unroll
;             for (int t = 0; t < 8; ++t) { const int wi = i - t; if (wi >= 0 && wi < 4) {
; #pragma unroll
;                 for (int j = 0; j < 8; ++j) y[t][j] += w[wi][j] * xf[j]; } } }
;         float* XT = part == 0 ? qT : (part == 1 ? kT : vT);
;         float sq[8];
; #pragma unroll
;         for (int t = 0; t < 8; ++t) sq[t] = 0.f;
; #pragma unroll
;         for (int j = 0; j < 8; ++j) {
; #pragma unroll
;             for (int t = 0; t < 8; ++t) { y[t][j] = silu_f(y[t][j]); sq[t] += y[t][j] * y[t][j]; }
	v_lshlrev_b32_e32 v31, 16, v45
	v_mov_b32_e32 v30, v29
	v_pk_fma_f32 v[150:151], v[80:81], v[28:29], v[26:27] op_sel_hi:[0,1,1]
	v_pk_fma_f32 v[26:27], v[72:73], v[28:29], v[32:33] op_sel_hi:[0,1,1]
	v_lshlrev_b32_e32 v53, 16, v49
	v_mov_b32_e32 v52, v31
	v_pk_fma_f32 v[26:27], v[76:77], v[30:31], v[26:27] op_sel_hi:[0,1,1]
	v_pk_fma_f32 v[140:141], v[80:81], v[52:53], v[26:27] op_sel_hi:[0,1,1]
	v_and_b32_e32 v27, 0xffff0000, v59
	v_and_b32_e32 v26, 0xffff0000, v55
	v_and_b32_e32 v29, 0xffff0000, v83
	v_and_b32_e32 v28, 0xffff0000, v87
	v_mov_b32_e32 v32, v69
	v_lshlrev_b32_e32 v117, 16, v50
	v_and_b32_e32 v93, 0xffff0000, v50
	v_pk_fma_f32 v[84:85], v[32:33], v[28:29], 0 op_sel_hi:[0,1,0]
	v_mov_b32_e32 v50, v73
	v_pk_mov_b32 v[28:29], v[28:29], v[26:27] op_sel:[1,0]
	v_lshlrev_b32_e32 v116, 16, v46
	v_pk_fma_f32 v[28:29], v[50:51], v[28:29], v[84:85] op_sel_hi:[0,1,1]
	v_and_b32_e32 v143, 0xffff0000, v49
	v_and_b32_e32 v142, 0xffff0000, v45
	v_and_b32_e32 v153, 0xffff0000, v63
	v_mov_b32_e32 v152, v27
	v_pk_fma_f32 v[154:155], v[56:57], v[26:27], v[28:29] op_sel_hi:[0,1,1]
	v_pk_fma_f32 v[26:27], v[32:33], v[26:27], 0 op_sel_hi:[0,1,0]
	v_pk_mov_b32 v[124:125], v[134:135], v[116:117] op_sel:[1,0]
	v_pk_fma_f32 v[26:27], v[50:51], v[152:153], v[26:27] op_sel_hi:[0,1,1]
	v_pk_mov_b32 v[28:29], v[152:153], v[142:143] op_sel:[1,0]
	v_lshlrev_b32_e32 v109, 16, v40
	v_lshlrev_b32_e32 v108, 16, v36
	v_pk_fma_f32 v[146:147], v[56:57], v[28:29], v[26:27] op_sel_hi:[0,1,1]
	v_pk_fma_f32 v[26:27], v[14:15], v[124:125], 0 op_sel_hi:[0,1,0]
	v_pk_mov_b32 v[112:113], v[116:117], v[108:109] op_sel:[1,0]
	v_pk_fma_f32 v[110:111], v[2:3], v[116:117], v[26:27] op_sel_hi:[0,1,1]
	v_pk_fma_f32 v[26:27], v[14:15], v[112:113], 0 op_sel_hi:[0,1,0]
	v_pk_fma_f32 v[98:99], v[2:3], v[108:109], v[26:27] op_sel_hi:[0,1,1]
	v_and_b32_e32 v115, 0xffff0000, v39
	v_and_b32_e32 v114, 0xffff0000, v35
	v_pk_fma_f32 v[26:27], v[32:33], v[28:29], 0 op_sel_hi:[0,1,0]
	v_pk_fma_f32 v[26:27], v[50:51], v[142:143], v[26:27] op_sel_hi:[0,1,1]
	v_pk_mov_b32 v[28:29], v[142:143], v[114:115] op_sel:[1,0]
	s_waitcnt vmcnt(0) lgkmcnt(0)
	v_and_b32_e32 v95, 0xffff0000, v23
	v_and_b32_e32 v94, 0xffff0000, v19
	v_pk_fma_f32 v[118:119], v[56:57], v[28:29], v[26:27] op_sel_hi:[0,1,1]
	v_pk_fma_f32 v[26:27], v[32:33], v[28:29], 0 op_sel_hi:[0,1,0]
	v_pk_fma_f32 v[26:27], v[50:51], v[114:115], v[26:27] op_sel_hi:[0,1,1]
	v_pk_mov_b32 v[28:29], v[114:115], v[94:95] op_sel:[1,0]
	v_and_b32_e32 v92, 0xffff0000, v46
	v_pk_fma_f32 v[100:101], v[56:57], v[28:29], v[26:27] op_sel_hi:[0,1,1]
	v_lshlrev_b32_e32 v26, 16, v35
	v_lshlrev_b32_e32 v27, 16, v39
	v_pk_mov_b32 v[32:33], v[52:53], v[26:27] op_sel:[1,0]
	v_lshlrev_b32_e32 v29, 16, v19
	v_pk_fma_f32 v[148:149], v[68:69], v[32:33], 0 op_sel_hi:[0,1,0]
	v_lshlrev_b32_e32 v69, 16, v23
	v_pk_fma_f32 v[30:31], v[68:69], v[30:31], 0 op_sel_hi:[0,1,0]
	v_pk_fma_f32 v[30:31], v[72:73], v[52:53], v[30:31] op_sel_hi:[0,1,1]
	v_pk_fma_f32 v[30:31], v[76:77], v[32:33], v[30:31] op_sel_hi:[0,1,1]
	v_mov_b32_e32 v28, v27
	v_pk_fma_f32 v[122:123], v[80:81], v[26:27], v[30:31] op_sel_hi:[0,1,1]
	v_pk_fma_f32 v[26:27], v[72:73], v[26:27], v[148:149] op_sel_hi:[0,1,1]
	v_mov_b32_e32 v68, v29
	v_pk_fma_f32 v[26:27], v[76:77], v[28:29], v[26:27] op_sel_hi:[0,1,1]
	v_mov_b32_e32 v46, v81
	v_pk_fma_f32 v[80:81], v[80:81], v[68:69], v[26:27] op_sel_hi:[0,1,1]
	v_lshlrev_b32_e32 v27, 16, v82
	v_lshlrev_b32_e32 v26, 16, v86
	v_lshlrev_b32_e32 v28, 16, v54
	v_mov_b32_e32 v30, v27
	v_mov_b32_e32 v31, v28
	v_pk_fma_f32 v[26:27], v[66:67], v[26:27], 0 op_sel_hi:[0,1,0]
	v_lshlrev_b32_e32 v29, 16, v58
	v_pk_fma_f32 v[26:27], v[70:71], v[30:31], v[26:27] op_sel_hi:[0,1,1]
	v_lshlrev_b32_e32 v33, 16, v62
	v_mov_b32_e32 v32, v29
	v_pk_fma_f32 v[26:27], v[74:75], v[28:29], v[26:27] op_sel_hi:[0,1,1]
	v_pk_fma_f32 v[26:27], v[78:79], v[32:33], v[26:27] op_sel_hi:[0,1,1]
	v_mul_f32_e32 v19, 0xbfb8aa3b, v26
	v_exp_f32_e32 v19, v19
	v_pk_fma_f32 v[28:29], v[66:67], v[28:29], 0 op_sel_hi:[0,1,0]
	v_pk_fma_f32 v[28:29], v[70:71], v[32:33], v[28:29] op_sel_hi:[0,1,1]
	v_and_b32_e32 v55, 0xffff0000, v58
	v_add_f32_e32 v19, 1.0, v19
	v_rcp_f32_e32 v30, v19
	v_mul_f32_e32 v19, 0xbfb8aa3b, v27
	v_exp_f32_e32 v19, v19
	v_and_b32_e32 v59, 0xffff0000, v62
	v_mov_b32_e32 v58, v55
	v_and_b32_e32 v49, 0xffff0000, v48
	v_add_f32_e32 v19, 1.0, v19
	v_rcp_f32_e32 v31, v19
	v_and_b32_e32 v35, 0xffff0000, v38
	v_and_b32_e32 v88, 0xffff0000, v20
	v_lshlrev_b32_e32 v96, 16, v20
	v_pk_mul_f32 v[30:31], v[26:27], v[30:31]
	v_lshlrev_b32_e32 v27, 16, v48
	v_lshlrev_b32_e32 v26, 16, v44
	v_pk_mov_b32 v[52:53], v[32:33], v[26:27] op_sel:[1,0]
	v_and_b32_e32 v48, 0xffff0000, v44
	v_pk_fma_f32 v[28:29], v[74:75], v[52:53], v[28:29] op_sel_hi:[0,1,1]
	v_pk_fma_f32 v[28:29], v[78:79], v[26:27], v[28:29] op_sel_hi:[0,1,1]
	v_mul_f32_e32 v19, 0xbfb8aa3b, v28
	v_exp_f32_e32 v19, v19
	v_pk_fma_f32 v[52:53], v[66:67], v[52:53], 0 op_sel_hi:[0,1,0]
	v_and_b32_e32 v106, 0xffff0000, v60
	v_and_b32_e32 v107, 0xffff0000, v64
	v_add_f32_e32 v19, 1.0, v19
	v_rcp_f32_e32 v32, v19
	v_mul_f32_e32 v19, 0xbfb8aa3b, v29
	v_exp_f32_e32 v19, v19
	v_lshlrev_b32_e32 v105, 16, v61
	v_pk_mov_b32 v[62:63], v[130:131], v[106:107] op_sel:[1,0]
	v_and_b32_e32 v85, 0xffff0000, v40
	v_add_f32_e32 v19, 1.0, v19
	v_rcp_f32_e32 v33, v19
	v_mov_b32_e32 v40, v5
	v_lshlrev_b32_e32 v77, 16, v51
	v_lshlrev_b32_e32 v76, 16, v47
	v_pk_mul_f32 v[32:33], v[28:29], v[32:33]
	v_lshlrev_b32_e32 v29, 16, v38
	v_lshlrev_b32_e32 v28, 16, v34
	v_pk_mov_b32 v[68:69], v[26:27], v[28:29] op_sel:[1,0]
	v_pk_fma_f32 v[26:27], v[70:71], v[26:27], v[52:53] op_sel_hi:[0,1,1]
; __device__ __forceinline__ float silu_f(float x) { return x * __builtin_amdgcn_rcpf(1.0f + __expf(-x)); }
; __device__ void prep_unit(unsigned char* lds, int bh, int n, const bf16_t* pc, const float* scal, const float* convw  , float alog, float dtb, unsigned char* unit, float* egl, unsigned* flag, unsigned fval) {
;     ...
;         for (int i = 0; i < 11; ++i) { float xf[8]; unpack8(xr[i], xf);
; #pragma unroll
;             for (int t = 0; t < 8; ++t) { const int wi = i - t; if (wi >= 0 && wi < 4) {
; #pragma unroll
;                 for (int j = 0; j < 8; ++j) y[t][j] += w[wi][j] * xf[j]; } } }
;         float* XT = part == 0 ? qT : (part == 1 ? kT : vT);
;         float sq[8];
; #pragma unroll
;         for (int t = 0; t < 8; ++t) sq[t] = 0.f;
; #pragma unroll
;         for (int j = 0; j < 8; ++j) {
; #pragma unroll
;             for (int t = 0; t < 8; ++t) { y[t][j] = silu_f(y[t][j]); sq[t] += y[t][j] * y[t][j]; }
;             f32x4 a, c;
;             a[0] = y[0][j]; a[1] = y[1][j]; a[2] = y[2][j]; a[3] = y[3][j]; c[0] = y[4][j]; c[1] = y[5][j]; c[2] = y[6][j]; c[3] = y[7][j];
;             *(f32x4*)(XT + (cg8 * 8 + j) * 68 + run * 8) = a; *(f32x4*)(XT + (cg8 * 8 + j) * 68 + run * 8 + 4) = c;
;         }
	v_pk_fma_f32 v[26:27], v[74:75], v[68:69], v[26:27] op_sel_hi:[0,1,1]
	v_pk_fma_f32 v[26:27], v[78:79], v[28:29], v[26:27] op_sel_hi:[0,1,1]
	v_mul_f32_e32 v19, 0xbfb8aa3b, v26
	v_exp_f32_e32 v19, v19
	v_pk_fma_f32 v[68:69], v[66:67], v[68:69], 0 op_sel_hi:[0,1,0]
	v_and_b32_e32 v34, 0xffff0000, v34
	v_and_b32_e32 v84, 0xffff0000, v36
	v_add_f32_e32 v19, 1.0, v19
	v_rcp_f32_e32 v52, v19
	v_mul_f32_e32 v19, 0xbfb8aa3b, v27
	v_exp_f32_e32 v19, v19
	v_lshlrev_b32_e32 v97, 16, v24
	v_pk_mov_b32 v[102:103], v[108:109], v[96:97] op_sel:[1,0]
	v_and_b32_e32 v89, 0xffff0000, v24
	v_add_f32_e32 v19, 1.0, v19
	v_rcp_f32_e32 v53, v19
	s_nop 0
	v_pk_mul_f32 v[26:27], v[26:27], v[52:53]
	v_lshlrev_b32_e32 v52, 16, v18
	v_lshlrev_b32_e32 v53, 16, v22
	v_pk_mov_b32 v[72:73], v[28:29], v[52:53] op_sel:[1,0]
	v_pk_fma_f32 v[28:29], v[70:71], v[28:29], v[68:69] op_sel_hi:[0,1,1]
	v_pk_fma_f32 v[28:29], v[74:75], v[72:73], v[28:29] op_sel_hi:[0,1,1]
	v_pk_fma_f32 v[28:29], v[78:79], v[52:53], v[28:29] op_sel_hi:[0,1,1]
	v_mul_f32_e32 v19, 0xbfb8aa3b, v28
	v_exp_f32_e32 v19, v19
	v_and_b32_e32 v18, 0xffff0000, v18
	v_add_f32_e32 v19, 1.0, v19
	v_rcp_f32_e32 v52, v19
	v_mul_f32_e32 v19, 0xbfb8aa3b, v29
	v_exp_f32_e32 v19, v19
	s_nop 0
	v_add_f32_e32 v19, 1.0, v19
	v_rcp_f32_e32 v53, v19
	v_mul_u32_u24_e32 v19, 0x110, v42
	v_add3_u32 v83, v43, v158, v19
	v_and_b32_e32 v43, 0xffff0000, v82
	v_and_b32_e32 v42, 0xffff0000, v86
	v_pk_mul_f32 v[28:29], v[28:29], v[52:53]
	v_and_b32_e32 v53, 0xffff0000, v54
	v_mov_b32_e32 v52, v43
	v_pk_fma_f32 v[42:43], v[66:67], v[42:43], 0 op_sel:[1,0,0] op_sel_hi:[1,1,0]
	v_mov_b32_e32 v54, v53
	v_pk_fma_f32 v[42:43], v[70:71], v[52:53], v[42:43] op_sel:[1,0,0]
	v_pk_fma_f32 v[44:45], v[66:67], v[54:55], 0 op_sel:[1,0,0] op_sel_hi:[1,1,0]
	v_pk_fma_f32 v[42:43], v[74:75], v[54:55], v[42:43] op_sel:[1,0,0]
	v_pk_fma_f32 v[44:45], v[70:71], v[58:59], v[44:45] op_sel:[1,0,0]
	v_pk_fma_f32 v[42:43], v[78:79], v[58:59], v[42:43] op_sel:[1,0,0]
	v_mov_b32_e32 v86, v17
	v_mul_f32_e32 v19, 0xbfb8aa3b, v42
	v_exp_f32_e32 v19, v19
	v_mov_b32_e32 v82, v13
	ds_write_b128 v83, v[30:33]
	ds_write_b128 v83, v[26:29] offset:16
	v_add_f32_e32 v19, 1.0, v19
	v_rcp_f32_e32 v52, v19
	v_mul_f32_e32 v19, 0xbfb8aa3b, v43
	v_exp_f32_e32 v19, v19
	s_nop 0
	v_add_f32_e32 v19, 1.0, v19
	v_rcp_f32_e32 v53, v19
	s_nop 0
	v_pk_mul_f32 v[42:43], v[42:43], v[52:53]
	v_pk_mov_b32 v[52:53], v[58:59], v[48:49] op_sel:[1,0]
	v_pk_fma_f32 v[58:59], v[2:3], v[130:131], v[136:137] op_sel:[1,0,0]
	v_pk_fma_f32 v[44:45], v[74:75], v[52:53], v[44:45] op_sel:[1,0,0]
	v_pk_fma_f32 v[38:39], v[66:67], v[52:53], 0 op_sel:[1,0,0] op_sel_hi:[1,1,0]
	v_pk_fma_f32 v[44:45], v[78:79], v[48:49], v[44:45] op_sel:[1,0,0]
	v_pk_fma_f32 v[38:39], v[70:71], v[48:49], v[38:39] op_sel:[1,0,0]
	v_mul_f32_e32 v19, 0xbfb8aa3b, v44
	v_exp_f32_e32 v19, v19
	v_pk_fma_f32 v[58:59], v[6:7], v[62:63], v[58:59] op_sel:[1,0,0]
	v_add_f32_e32 v19, 1.0, v19
	v_rcp_f32_e32 v54, v19
	v_mul_f32_e32 v19, 0xbfb8aa3b, v45
	v_exp_f32_e32 v19, v19
	v_pk_fma_f32 v[58:59], v[10:11], v[106:107], v[58:59] op_sel:[1,0,0]
	v_add_f32_e32 v19, 1.0, v19
	v_rcp_f32_e32 v55, v19
	s_nop 0
	v_pk_mul_f32 v[44:45], v[44:45], v[54:55]
	v_pk_mov_b32 v[54:55], v[48:49], v[34:35] op_sel:[1,0]
	s_nop 0
	v_pk_fma_f32 v[38:39], v[74:75], v[54:55], v[38:39] op_sel:[1,0,0]
	s_nop 0
	v_pk_fma_f32 v[38:39], v[78:79], v[34:35], v[38:39] op_sel:[1,0,0]
	s_nop 0
	v_mul_f32_e32 v19, 0xbfb8aa3b, v38
	v_exp_f32_e32 v19, v19
	s_nop 0
	v_add_f32_e32 v19, 1.0, v19
	v_rcp_f32_e32 v48, v19
	v_mul_f32_e32 v19, 0xbfb8aa3b, v39
	v_exp_f32_e32 v19, v19
	s_nop 0
	v_add_f32_e32 v19, 1.0, v19
	v_rcp_f32_e32 v49, v19
	v_and_b32_e32 v19, 0xffff0000, v22
	v_pk_fma_f32 v[22:23], v[66:67], v[54:55], 0 op_sel:[1,0,0] op_sel_hi:[1,1,0]
	v_lshlrev_b32_e32 v67, 16, v65
	v_pk_mul_f32 v[52:53], v[38:39], v[48:49]
	v_pk_mov_b32 v[38:39], v[34:35], v[18:19] op_sel:[1,0]
	v_pk_fma_f32 v[22:23], v[70:71], v[34:35], v[22:23] op_sel:[1,0,0]
	v_pk_fma_f32 v[48:49], v[16:17], v[132:133], 0 op_sel_hi:[0,1,0]
	v_pk_fma_f32 v[22:23], v[74:75], v[38:39], v[22:23] op_sel:[1,0,0]
	v_pk_fma_f32 v[74:75], v[14:15], v[62:63], 0 op_sel:[1,0,0] op_sel_hi:[1,1,0]
	v_pk_fma_f32 v[18:19], v[78:79], v[18:19], v[22:23] op_sel:[1,0,0]
	v_pk_fma_f32 v[62:63], v[46:47], v[152:153], v[154:155] op_sel_hi:[0,1,1]
	v_mul_f32_e32 v20, 0xbfb8aa3b, v18
	v_exp_f32_e32 v20, v20
	v_mov_b32_e32 v66, v105
	v_mov_b32_e32 v78, v9
	v_and_b32_e32 v71, 0xffff0000, v65
	v_add_f32_e32 v20, 1.0, v20
	v_rcp_f32_e32 v22, v20
	v_mul_f32_e32 v20, 0xbfb8aa3b, v19
	v_exp_f32_e32 v20, v20
	v_pk_fma_f32 v[74:75], v[2:3], v[106:107], v[74:75] op_sel:[1,0,0]
	v_add_f32_e32 v20, 1.0, v20
	v_rcp_f32_e32 v23, v20
	v_mul_f32_e32 v20, 0xbfb8aa3b, v80
	v_exp_f32_e32 v20, v20
	v_pk_mul_f32 v[54:55], v[18:19], v[22:23]
	v_mul_f32_e32 v18, 0xbfb8aa3b, v150
	v_exp_f32_e32 v18, v18
	v_and_b32_e32 v23, 0xffff0000, v61
	v_pk_mov_b32 v[60:61], v[132:133], v[104:105] op_sel:[1,0]
	v_and_b32_e32 v22, 0xffff0000, v57
	v_add_f32_e32 v18, 1.0, v18
	v_rcp_f32_e32 v38, v18
	v_mul_f32_e32 v18, 0xbfb8aa3b, v151
	v_exp_f32_e32 v18, v18
	v_pk_fma_f32 v[48:49], v[4:5], v[60:61], v[48:49] op_sel_hi:[0,1,1]
	v_mul_f32_e32 v5, 0xbfb8aa3b, v62
	v_exp_f32_e32 v5, v5
	v_add_f32_e32 v18, 1.0, v18
	v_rcp_f32_e32 v39, v18
	v_pk_fma_f32 v[48:49], v[8:9], v[104:105], v[48:49] op_sel_hi:[0,1,1]
	v_add_f32_e32 v5, 1.0, v5
	v_pk_fma_f32 v[68:69], v[12:13], v[66:67], v[48:49] op_sel_hi:[0,1,1]
	v_pk_mul_f32 v[48:49], v[150:151], v[38:39]
	v_rcp_f32_e32 v38, v5
	v_mul_f32_e32 v5, 0xbfb8aa3b, v63
	v_exp_f32_e32 v5, v5
; __device__ __forceinline__ float silu_f(float x) { return x * __builtin_amdgcn_rcpf(1.0f + __expf(-x)); }
; __device__ void prep_unit(unsigned char* lds, int bh, int n, const bf16_t* pc, const float* scal, const float* convw  , float alog, float dtb, unsigned char* unit, float* egl, unsigned* flag, unsigned fval) {
;     ...
;         for (int i = 0; i < 11; ++i) { float xf[8]; unpack8(xr[i], xf);
; #pragma unroll
;             for (int t = 0; t < 8; ++t) { const int wi = i - t; if (wi >= 0 && wi < 4) {
; #pragma unroll
;                 for (int j = 0; j < 8; ++j) y[t][j] += w[wi][j] * xf[j]; } } }
;         float* XT = part == 0 ? qT : (part == 1 ? kT : vT);
;         float sq[8];
; #pragma unroll
;         for (int t = 0; t < 8; ++t) sq[t] = 0.f;
; #pragma unroll
;         for (int j = 0; j < 8; ++j) {
; #pragma unroll
;             for (int t = 0; t < 8; ++t) { y[t][j] = silu_f(y[t][j]); sq[t] += y[t][j] * y[t][j]; }
;             f32x4 a, c;
;             a[0] = y[0][j]; a[1] = y[1][j]; a[2] = y[2][j]; a[3] = y[3][j]; c[0] = y[4][j]; c[1] = y[5][j]; c[2] = y[6][j]; c[3] = y[7][j];
;             *(f32x4*)(XT + (cg8 * 8 + j) * 68 + run * 8) = a; *(f32x4*)(XT + (cg8 * 8 + j) * 68 + run * 8 + 4) = c;
;         }
	v_pk_fma_f32 v[60:61], v[6:7], v[138:139], v[144:145] op_sel_hi:[0,1,1]
	v_pk_fma_f32 v[60:61], v[10:11], v[134:135], v[60:61] op_sel_hi:[0,1,1]
	v_mov_b32_e32 v129, v22
	v_add_f32_e32 v5, 1.0, v5
	v_rcp_f32_e32 v39, v5
	v_mul_f32_e32 v5, 0xbfb8aa3b, v60
	v_exp_f32_e32 v5, v5
	v_pk_fma_f32 v[56:57], v[86:87], v[126:127], 0 op_sel_hi:[0,1,0]
	v_pk_fma_f32 v[56:57], v[40:41], v[128:129], v[56:57] op_sel_hi:[0,1,1]
	v_mov_b32_e32 v70, v23
	v_pk_fma_f32 v[56:57], v[78:79], v[22:23], v[56:57] op_sel_hi:[0,1,1]
	v_add_f32_e32 v5, 1.0, v5
	v_pk_fma_f32 v[72:73], v[82:83], v[70:71], v[56:57] op_sel_hi:[0,1,1]
	v_pk_mul_f32 v[56:57], v[62:63], v[38:39]
	v_rcp_f32_e32 v38, v5
	v_mul_f32_e32 v5, 0xbfb8aa3b, v61
	v_exp_f32_e32 v5, v5
	v_mul_f32_e32 v18, 0xbfb8aa3b, v140
	v_exp_f32_e32 v18, v18
	v_pk_fma_f32 v[62:63], v[46:47], v[142:143], v[146:147] op_sel_hi:[0,1,1]
	v_add_f32_e32 v5, 1.0, v5
	v_rcp_f32_e32 v39, v5
	v_mul_f32_e32 v5, 0xbfb8aa3b, v58
	v_exp_f32_e32 v5, v5
	v_add_f32_e32 v18, 1.0, v18
	v_pk_mul_f32 v[60:61], v[60:61], v[38:39]
	v_rcp_f32_e32 v34, v18
	v_add_f32_e32 v5, 1.0, v5
	v_rcp_f32_e32 v38, v5
	v_mul_f32_e32 v5, 0xbfb8aa3b, v59
	v_exp_f32_e32 v5, v5
	v_mul_f32_e32 v18, 0xbfb8aa3b, v141
	v_exp_f32_e32 v18, v18
	v_pk_mov_b32 v[126:127], v[106:107], v[92:93] op_sel:[1,0]
	v_add_f32_e32 v5, 1.0, v5
	v_rcp_f32_e32 v39, v5
	v_mul_f32_e32 v5, 0xbfb8aa3b, v68
	v_exp_f32_e32 v5, v5
	v_add_f32_e32 v18, 1.0, v18
	v_pk_mul_f32 v[64:65], v[58:59], v[38:39]
	v_rcp_f32_e32 v35, v18
	v_add_f32_e32 v5, 1.0, v5
	v_rcp_f32_e32 v38, v5
	v_mul_f32_e32 v5, 0xbfb8aa3b, v69
	v_exp_f32_e32 v5, v5
	v_pk_fma_f32 v[58:59], v[6:7], v[124:125], v[120:121] op_sel_hi:[0,1,1]
	v_pk_fma_f32 v[116:117], v[10:11], v[116:117], v[58:59] op_sel_hi:[0,1,1]
	v_pk_mov_b32 v[124:125], v[66:67], v[76:77] op_sel:[1,0]
	v_add_f32_e32 v5, 1.0, v5
	v_rcp_f32_e32 v39, v5
	v_mul_f32_e32 v5, 0xbfb8aa3b, v72
	v_exp_f32_e32 v5, v5
	v_pk_fma_f32 v[22:23], v[86:87], v[22:23], 0 op_sel_hi:[0,1,0]
	v_pk_mul_f32 v[68:69], v[68:69], v[38:39]
	v_pk_fma_f32 v[22:23], v[40:41], v[70:71], v[22:23] op_sel_hi:[0,1,1]
	v_add_f32_e32 v5, 1.0, v5
	v_rcp_f32_e32 v38, v5
	v_mul_f32_e32 v5, 0xbfb8aa3b, v73
	v_exp_f32_e32 v5, v5
	v_lshlrev_b32_e32 v106, 16, v37
	v_pk_fma_f32 v[120:121], v[14:15], v[126:127], 0 op_sel:[1,0,0] op_sel_hi:[1,1,0]
	v_lshlrev_b32_e32 v107, 16, v41
	v_add_f32_e32 v5, 1.0, v5
	v_rcp_f32_e32 v39, v5
	v_mul_f32_e32 v5, 0xbfb8aa3b, v62
	v_exp_f32_e32 v5, v5
	v_add_f32_e32 v20, 1.0, v20
	v_pk_mul_f32 v[72:73], v[72:73], v[38:39]
	v_and_b32_e32 v39, 0xffff0000, v51
	v_add_f32_e32 v5, 1.0, v5
	v_pk_mul_f32 v[50:51], v[140:141], v[34:35]
	v_rcp_f32_e32 v34, v5
	v_mul_f32_e32 v5, 0xbfb8aa3b, v63
	v_exp_f32_e32 v5, v5
	v_and_b32_e32 v38, 0xffff0000, v47
	v_rcp_f32_e32 v148, v20
	v_mul_f32_e32 v20, 0xbfb8aa3b, v81
	v_add_f32_e32 v5, 1.0, v5
	v_rcp_f32_e32 v35, v5
	v_mul_f32_e32 v5, 0xbfb8aa3b, v116
	v_exp_f32_e32 v5, v5
	v_exp_f32_e32 v20, v20
	v_pk_mul_f32 v[58:59], v[62:63], v[34:35]
	v_mul_f32_e32 v18, 0xbfb8aa3b, v122
	v_add_f32_e32 v5, 1.0, v5
	v_rcp_f32_e32 v34, v5
	v_mul_f32_e32 v5, 0xbfb8aa3b, v117
	v_exp_f32_e32 v5, v5
	v_add_f32_e32 v20, 1.0, v20
	v_rcp_f32_e32 v149, v20
	v_mul_f32_e32 v19, 0xbfb8aa3b, v123
	v_add_f32_e32 v5, 1.0, v5
	v_rcp_f32_e32 v35, v5
	v_exp_f32_e32 v18, v18
	v_exp_f32_e32 v19, v19
	ds_write_b128 v83, v[42:45] offset:272
	ds_write_b128 v83, v[52:55] offset:288
	v_pk_mul_f32 v[62:63], v[116:117], v[34:35]
	v_pk_fma_f32 v[34:35], v[16:17], v[104:105], 0 op_sel_hi:[0,1,0]
	v_pk_fma_f32 v[34:35], v[4:5], v[66:67], v[34:35] op_sel_hi:[0,1,1]
	v_pk_fma_f32 v[66:67], v[6:7], v[126:127], v[74:75] op_sel:[1,0,0]
	v_pk_mov_b32 v[116:117], v[70:71], v[38:39] op_sel:[1,0]
	v_pk_fma_f32 v[66:67], v[10:11], v[92:93], v[66:67] op_sel:[1,0,0]
	v_pk_fma_f32 v[34:35], v[8:9], v[124:125], v[34:35] op_sel_hi:[0,1,1]
	v_mul_f32_e32 v5, 0xbfb8aa3b, v66
	v_exp_f32_e32 v5, v5
	v_pk_fma_f32 v[34:35], v[12:13], v[76:77], v[34:35] op_sel_hi:[0,1,1]
	v_pk_fma_f32 v[22:23], v[78:79], v[116:117], v[22:23] op_sel_hi:[0,1,1]
	v_pk_fma_f32 v[22:23], v[82:83], v[38:39], v[22:23] op_sel_hi:[0,1,1]
	v_add_f32_e32 v5, 1.0, v5
	v_rcp_f32_e32 v70, v5
	v_mul_f32_e32 v5, 0xbfb8aa3b, v67
	v_exp_f32_e32 v5, v5
	v_and_b32_e32 v104, 0xffff0000, v37
	v_pk_mov_b32 v[36:37], v[92:93], v[84:85] op_sel:[1,0]
	v_pk_fma_f32 v[92:93], v[2:3], v[92:93], v[120:121] op_sel:[1,0,0]
	v_add_f32_e32 v5, 1.0, v5
	v_rcp_f32_e32 v71, v5
	v_mul_f32_e32 v5, 0xbfb8aa3b, v34
	v_exp_f32_e32 v5, v5
	v_and_b32_e32 v105, 0xffff0000, v41
	v_pk_mul_f32 v[66:67], v[66:67], v[70:71]
	v_add_f32_e32 v18, 1.0, v18
	v_add_f32_e32 v5, 1.0, v5
	v_rcp_f32_e32 v70, v5
	v_mul_f32_e32 v5, 0xbfb8aa3b, v35
	v_exp_f32_e32 v5, v5
	v_add_f32_e32 v19, 1.0, v19
	v_rcp_f32_e32 v18, v18
	v_rcp_f32_e32 v19, v19
	v_add_f32_e32 v5, 1.0, v5
	v_rcp_f32_e32 v71, v5
	v_mul_f32_e32 v5, 0xbfb8aa3b, v22
	v_exp_f32_e32 v5, v5
	v_pk_mul_f32 v[18:19], v[122:123], v[18:19]
	v_pk_mul_f32 v[70:71], v[34:35], v[70:71]
	ds_write_b128 v83, v[48:51] offset:544
	ds_write_b128 v83, v[56:59] offset:816
	ds_write_b128 v83, v[60:63] offset:1088
	v_add_f32_e32 v5, 1.0, v5
	v_rcp_f32_e32 v34, v5
	v_mul_f32_e32 v5, 0xbfb8aa3b, v23
	v_exp_f32_e32 v5, v5
	ds_write_b128 v83, v[64:67] offset:1360
	ds_write_b128 v83, v[68:71] offset:1632
	v_add_f32_e32 v5, 1.0, v5
	v_rcp_f32_e32 v35, v5
	s_nop 0
	v_pk_mul_f32 v[74:75], v[22:23], v[34:35]
	v_pk_fma_f32 v[22:23], v[6:7], v[112:113], v[110:111] op_sel_hi:[0,1,1]
	v_pk_fma_f32 v[110:111], v[14:15], v[36:37], 0 op_sel:[1,0,0] op_sel_hi:[1,1,0]
	v_pk_fma_f32 v[14:15], v[46:47], v[114:115], v[118:119] op_sel_hi:[0,1,1]
; __device__ __forceinline__ float silu_f(float x) { return x * __builtin_amdgcn_rcpf(1.0f + __expf(-x)); }
; __device__ void prep_unit(unsigned char* lds, int bh, int n, const bf16_t* pc, const float* scal, const float* convw  , float alog, float dtb, unsigned char* unit, float* egl, unsigned* flag, unsigned fval) {
;     ...
;         for (int j = 0; j < 8; ++j) {
; #pragma unroll
;             for (int t = 0; t < 8; ++t) { y[t][j] = silu_f(y[t][j]); sq[t] += y[t][j] * y[t][j]; }
;             f32x4 a, c;
;             a[0] = y[0][j]; a[1] = y[1][j]; a[2] = y[2][j]; a[3] = y[3][j]; c[0] = y[4][j]; c[1] = y[5][j]; c[2] = y[6][j]; c[3] = y[7][j];
;             *(f32x4*)(XT + (cg8 * 8 + j) * 68 + run * 8) = a; *(f32x4*)(XT + (cg8 * 8 + j) * 68 + run * 8 + 4) = c;
;         }
;         if (part < 2) {
	v_mul_f32_e32 v5, 0xbfb8aa3b, v14
	v_exp_f32_e32 v5, v5
	v_pk_fma_f32 v[34:35], v[10:11], v[108:109], v[22:23] op_sel_hi:[0,1,1]
	v_pk_fma_f32 v[36:37], v[6:7], v[36:37], v[92:93] op_sel:[1,0,0]
	v_pk_mov_b32 v[112:113], v[76:77], v[106:107] op_sel:[1,0]
	v_add_f32_e32 v5, 1.0, v5
	v_rcp_f32_e32 v22, v5
	v_mul_f32_e32 v5, 0xbfb8aa3b, v15
	v_exp_f32_e32 v5, v5
	v_pk_fma_f32 v[36:37], v[10:11], v[84:85], v[36:37] op_sel:[1,0,0]
	v_pk_fma_f32 v[108:109], v[86:87], v[116:117], 0 op_sel_hi:[0,1,0]
	v_pk_mov_b32 v[114:115], v[38:39], v[104:105] op_sel:[1,0]
	v_add_f32_e32 v5, 1.0, v5
	v_rcp_f32_e32 v23, v5
	v_mul_f32_e32 v5, 0xbfb8aa3b, v34
	v_exp_f32_e32 v5, v5
	v_pk_fma_f32 v[2:3], v[2:3], v[84:85], v[110:111] op_sel:[1,0,0]
	v_pk_mul_f32 v[22:23], v[14:15], v[22:23]
	v_add_f32_e32 v5, 1.0, v5
	v_rcp_f32_e32 v14, v5
	v_mul_f32_e32 v5, 0xbfb8aa3b, v35
	v_exp_f32_e32 v5, v5
	s_nop 0
	v_add_f32_e32 v5, 1.0, v5
	v_rcp_f32_e32 v15, v5
	v_mul_f32_e32 v5, 0xbfb8aa3b, v37
	v_exp_f32_e32 v5, v5
	v_pk_mul_f32 v[34:35], v[34:35], v[14:15]
	v_pk_fma_f32 v[14:15], v[16:17], v[124:125], 0 op_sel_hi:[0,1,0]
	v_add_f32_e32 v5, 1.0, v5
	v_pk_fma_f32 v[14:15], v[4:5], v[76:77], v[14:15] op_sel_hi:[0,1,1]
	v_pk_fma_f32 v[14:15], v[8:9], v[112:113], v[14:15] op_sel_hi:[0,1,1]
	v_pk_fma_f32 v[76:77], v[12:13], v[106:107], v[14:15] op_sel_hi:[0,1,1]
	v_rcp_f32_e32 v93, v5
	v_mul_f32_e32 v5, 0xbfb8aa3b, v77
	v_exp_f32_e32 v5, v5
	v_pk_fma_f32 v[14:15], v[40:41], v[38:39], v[108:109] op_sel_hi:[0,1,1]
	v_pk_fma_f32 v[14:15], v[78:79], v[114:115], v[14:15] op_sel_hi:[0,1,1]
	v_pk_fma_f32 v[108:109], v[82:83], v[104:105], v[14:15] op_sel_hi:[0,1,1]
	v_add_f32_e32 v5, 1.0, v5
	v_rcp_f32_e32 v117, v5
	v_mul_f32_e32 v5, 0xbfb8aa3b, v36
	v_exp_f32_e32 v5, v5
	v_pk_fma_f32 v[16:17], v[16:17], v[112:113], 0 op_sel_hi:[0,1,0]
	v_add_f32_e32 v5, 1.0, v5
	v_rcp_f32_e32 v92, v5
	v_mul_f32_e32 v5, 0xbfb8aa3b, v76
	v_exp_f32_e32 v5, v5
	v_pk_mul_f32 v[14:15], v[36:37], v[92:93]
	v_lshlrev_b32_e32 v93, 16, v25
	v_add_f32_e32 v5, 1.0, v5
	v_rcp_f32_e32 v116, v5
	v_mul_f32_e32 v5, 0xbfb8aa3b, v108
	v_exp_f32_e32 v5, v5
	v_lshlrev_b32_e32 v92, 16, v21
	v_pk_mul_f32 v[38:39], v[76:77], v[116:117]
	v_add_f32_e32 v5, 1.0, v5
	v_rcp_f32_e32 v36, v5
	v_mul_f32_e32 v5, 0xbfb8aa3b, v109
	v_exp_f32_e32 v5, v5
	s_nop 0
	v_add_f32_e32 v5, 1.0, v5
	v_rcp_f32_e32 v37, v5
	s_nop 0
	v_pk_mul_f32 v[76:77], v[108:109], v[36:37]
	v_pk_fma_f32 v[36:37], v[6:7], v[102:103], v[98:99] op_sel_hi:[0,1,1]
	v_and_b32_e32 v99, 0xffff0000, v25
	v_pk_fma_f32 v[24:25], v[46:47], v[94:95], v[100:101] op_sel_hi:[0,1,1]
	v_mul_f32_e32 v5, 0xbfb8aa3b, v24
	v_exp_f32_e32 v5, v5
	v_pk_fma_f32 v[36:37], v[10:11], v[96:97], v[36:37] op_sel_hi:[0,1,1]
	v_and_b32_e32 v98, 0xffff0000, v21
	v_pk_mul_f32 v[20:21], v[80:81], v[148:149]
	v_add_f32_e32 v5, 1.0, v5
	v_rcp_f32_e32 v46, v5
	v_mul_f32_e32 v5, 0xbfb8aa3b, v25
	v_exp_f32_e32 v5, v5
	v_pk_mov_b32 v[80:81], v[84:85], v[88:89] op_sel:[1,0]
	v_pk_mov_b32 v[94:95], v[104:105], v[98:99] op_sel:[1,0]
	v_pk_fma_f32 v[2:3], v[6:7], v[80:81], v[2:3] op_sel:[1,0,0]
	v_add_f32_e32 v5, 1.0, v5
	v_rcp_f32_e32 v47, v5
	v_mul_f32_e32 v5, 0xbfb8aa3b, v36
	v_exp_f32_e32 v5, v5
	v_pk_fma_f32 v[2:3], v[10:11], v[88:89], v[2:3] op_sel:[1,0,0]
	v_pk_mul_f32 v[24:25], v[24:25], v[46:47]
	v_add_f32_e32 v5, 1.0, v5
	v_rcp_f32_e32 v46, v5
	v_mul_f32_e32 v5, 0xbfb8aa3b, v37
	v_exp_f32_e32 v5, v5
	s_nop 0
	v_add_f32_e32 v5, 1.0, v5
	v_rcp_f32_e32 v47, v5
	v_mul_f32_e32 v5, 0xbfb8aa3b, v3
	v_exp_f32_e32 v5, v5
	v_pk_mul_f32 v[36:37], v[36:37], v[46:47]
	v_pk_fma_f32 v[46:47], v[86:87], v[114:115], 0 op_sel_hi:[0,1,0]
	v_add_f32_e32 v5, 1.0, v5
	v_rcp_f32_e32 v5, v5
	v_pk_mov_b32 v[86:87], v[106:107], v[92:93] op_sel:[1,0]
	v_pk_fma_f32 v[10:11], v[40:41], v[104:105], v[46:47] op_sel_hi:[0,1,1]
	v_pk_fma_f32 v[10:11], v[78:79], v[94:95], v[10:11] op_sel_hi:[0,1,1]
	v_pk_fma_f32 v[6:7], v[4:5], v[106:107], v[16:17] op_sel_hi:[0,1,1]
	v_pk_fma_f32 v[6:7], v[8:9], v[86:87], v[6:7] op_sel_hi:[0,1,1]
	v_pk_fma_f32 v[6:7], v[12:13], v[92:93], v[6:7] op_sel_hi:[0,1,1]
	v_mul_f32_e32 v4, 0xbfb8aa3b, v7
	v_exp_f32_e32 v4, v4
	v_pk_fma_f32 v[10:11], v[82:83], v[98:99], v[10:11] op_sel_hi:[0,1,1]
	ds_write_b128 v83, v[18:21] offset:560
	ds_write_b128 v83, v[22:25] offset:832
	ds_write_b128 v83, v[34:37] offset:1104
	v_add_f32_e32 v4, 1.0, v4
	v_rcp_f32_e32 v9, v4
	v_mul_f32_e32 v4, 0xbfb8aa3b, v2
	v_exp_f32_e32 v4, v4
	s_nop 0
	v_add_f32_e32 v4, 1.0, v4
	v_rcp_f32_e32 v4, v4
	s_nop 0
	v_pk_mul_f32 v[16:17], v[2:3], v[4:5]
	v_mul_f32_e32 v2, 0xbfb8aa3b, v6
	v_exp_f32_e32 v2, v2
	v_mul_f32_e32 v3, 0xbfb8aa3b, v11
	v_exp_f32_e32 v3, v3
	v_add_f32_e32 v2, 1.0, v2
	v_rcp_f32_e32 v8, v2
	v_mul_f32_e32 v2, 0xbfb8aa3b, v10
	v_exp_f32_e32 v2, v2
	v_add_f32_e32 v3, 1.0, v3
	v_rcp_f32_e32 v3, v3
	v_pk_mul_f32 v[40:41], v[6:7], v[8:9]
	v_add_f32_e32 v2, 1.0, v2
	v_rcp_f32_e32 v2, v2
	ds_write_b128 v83, v[14:17] offset:1376
	ds_write_b128 v83, v[38:41] offset:1648
	v_pk_mul_f32 v[78:79], v[10:11], v[2:3]
	ds_write_b128 v83, v[72:75] offset:1904
	ds_write_b128 v83, v[76:79] offset:1920
	s_and_saveexec_b64 s[2:3], vcc
	s_cbranch_execz .LBB0_317
; __device__ void prep_unit(unsigned char* lds, int bh, int n, const bf16_t* pc, const float* scal, const float* convw  , float alog, float dtb, unsigned char* unit, float* egl, unsigned* flag, unsigned fval) {
;     ...
;         if (part < 2) {
; #pragma unroll
;             for (int t = 0; t < 8; ++t) { float v = sq[t]; v += __shfl_xor(v, 8); v += __shfl_xor(v, 16); v += __shfl_xor(v, 32); sq[t] = v; }
;             if ((lane >> 3) == 0) {
; #pragma unroll
;                 for (int t = 0; t < 8; ++t) ssp[(part * 2 + (wid & 1)) * 64 + run * 8 + t] = sq[t];
;             }
;         }
	v_pk_mul_f32 v[10:11], v[52:53], v[52:53]
	v_and_b32_e32 v5, 64, v218
	v_pk_fma_f32 v[10:11], v[26:27], v[26:27], v[10:11]
	v_xor_b32_e32 v4, 8, v218
	v_pk_fma_f32 v[10:11], v[18:19], v[18:19], v[10:11]
	v_add_u32_e32 v5, 64, v5
	v_pk_fma_f32 v[10:11], v[22:23], v[22:23], v[10:11]
	v_pk_mul_f32 v[46:47], v[54:55], v[54:55]
	v_pk_mul_f32 v[6:7], v[44:45], v[44:45]
	v_pk_mul_f32 v[2:3], v[42:43], v[42:43]
	v_cmp_lt_i32_e32 vcc, v4, v5
	v_pk_fma_f32 v[10:11], v[34:35], v[34:35], v[10:11]
	v_pk_fma_f32 v[2:3], v[30:31], v[30:31], v[2:3]
	v_cndmask_b32_e32 v4, v218, v4, vcc
	v_pk_fma_f32 v[6:7], v[32:33], v[32:33], v[6:7]
	v_pk_fma_f32 v[10:11], v[14:15], v[14:15], v[10:11]
	v_pk_fma_f32 v[14:15], v[28:29], v[28:29], v[46:47]
	v_lshlrev_b32_e32 v42, 2, v4
	v_xor_b32_e32 v4, 16, v218
	v_pk_fma_f32 v[2:3], v[48:49], v[48:49], v[2:3]
	v_pk_fma_f32 v[6:7], v[50:51], v[50:51], v[6:7]
	v_pk_fma_f32 v[14:15], v[20:21], v[20:21], v[14:15]
	v_cmp_lt_i32_e32 vcc, v4, v5
	v_pk_fma_f32 v[2:3], v[56:57], v[56:57], v[2:3]
	v_pk_fma_f32 v[6:7], v[58:59], v[58:59], v[6:7]
	v_pk_fma_f32 v[14:15], v[24:25], v[24:25], v[14:15]
	v_cndmask_b32_e32 v4, v218, v4, vcc
	v_pk_fma_f32 v[2:3], v[60:61], v[60:61], v[2:3]
	v_pk_fma_f32 v[6:7], v[62:63], v[62:63], v[6:7]
	v_pk_fma_f32 v[14:15], v[36:37], v[36:37], v[14:15]
	v_lshlrev_b32_e32 v43, 2, v4
	v_xor_b32_e32 v4, 32, v218
	v_pk_fma_f32 v[2:3], v[64:65], v[64:65], v[2:3]
	v_pk_fma_f32 v[6:7], v[66:67], v[66:67], v[6:7]
	v_pk_fma_f32 v[14:15], v[16:17], v[16:17], v[14:15]
	v_cmp_lt_i32_e32 vcc, v4, v5
	v_pk_fma_f32 v[2:3], v[68:69], v[68:69], v[2:3]
	v_pk_fma_f32 v[6:7], v[70:71], v[70:71], v[6:7]
	v_pk_fma_f32 v[10:11], v[38:39], v[38:39], v[10:11]
	v_pk_fma_f32 v[14:15], v[40:41], v[40:41], v[14:15]
	v_cndmask_b32_e32 v4, v218, v4, vcc
	v_pk_fma_f32 v[2:3], v[72:73], v[72:73], v[2:3]
	v_pk_fma_f32 v[6:7], v[74:75], v[74:75], v[6:7]
	v_pk_fma_f32 v[10:11], v[76:77], v[76:77], v[10:11]
	v_pk_fma_f32 v[14:15], v[78:79], v[78:79], v[14:15]
	v_lshlrev_b32_e32 v44, 2, v4
	ds_bpermute_b32 v4, v42, v2
	ds_bpermute_b32 v5, v42, v3
	ds_bpermute_b32 v8, v42, v6
	ds_bpermute_b32 v9, v42, v7
	ds_bpermute_b32 v12, v42, v10
	ds_bpermute_b32 v13, v42, v11
	ds_bpermute_b32 v16, v42, v14
	ds_bpermute_b32 v17, v42, v15
	s_waitcnt lgkmcnt(6)
	v_pk_add_f32 v[2:3], v[2:3], v[4:5]
	s_waitcnt lgkmcnt(4)
	v_pk_add_f32 v[6:7], v[6:7], v[8:9]
	s_waitcnt lgkmcnt(2)
	v_pk_add_f32 v[10:11], v[10:11], v[12:13]
	ds_bpermute_b32 v4, v43, v2
	s_waitcnt lgkmcnt(1)
	v_pk_add_f32 v[14:15], v[14:15], v[16:17]
	ds_bpermute_b32 v5, v43, v3
	ds_bpermute_b32 v8, v43, v6
	ds_bpermute_b32 v9, v43, v7
	ds_bpermute_b32 v12, v43, v10
	ds_bpermute_b32 v13, v43, v11
	ds_bpermute_b32 v16, v43, v14
	ds_bpermute_b32 v17, v43, v15
	s_waitcnt lgkmcnt(6)
	v_pk_add_f32 v[2:3], v[2:3], v[4:5]
	s_waitcnt lgkmcnt(4)
	v_pk_add_f32 v[6:7], v[6:7], v[8:9]
	s_waitcnt lgkmcnt(2)
	v_pk_add_f32 v[10:11], v[10:11], v[12:13]
	ds_bpermute_b32 v4, v44, v2
	s_waitcnt lgkmcnt(1)
	v_pk_add_f32 v[14:15], v[14:15], v[16:17]
	ds_bpermute_b32 v5, v44, v3
	ds_bpermute_b32 v8, v44, v6
	ds_bpermute_b32 v9, v44, v7
	ds_bpermute_b32 v12, v44, v10
	ds_bpermute_b32 v13, v44, v11
	ds_bpermute_b32 v16, v44, v14
	ds_bpermute_b32 v17, v44, v15
	s_and_b64 exec, exec, s[6:7]
	s_cbranch_execz .LBB0_317
	v_and_b32_e32 v18, 0x3fffffc0, v156
	v_lshlrev_b32_e32 v18, 2, v18
	v_readlane_b32 s4, v254, 7
	s_waitcnt lgkmcnt(6)
	v_pk_add_f32 v[2:3], v[2:3], v[4:5]
	s_waitcnt lgkmcnt(4)
	v_pk_add_f32 v[4:5], v[6:7], v[8:9]
	v_add3_u32 v18, s4, v18, v158
	ds_write_b128 v18, v[2:5]
	s_waitcnt lgkmcnt(3)
	v_pk_add_f32 v[2:3], v[10:11], v[12:13]
	s_waitcnt lgkmcnt(1)
	v_pk_add_f32 v[4:5], v[14:15], v[16:17]
	ds_write_b128 v18, v[2:5] offset:16

; __device__ __forceinline__ unsigned pack2(float lo, float hi) { return pg8::cvt_pk_bf16(lo, hi); }
; __device__ void prep_unit(unsigned char* lds, int bh, int n, const bf16_t* pc, const float* scal, const float* convw  , float alog, float dtb, unsigned char* unit, float* egl, unsigned* flag, unsigned fval) {
;     ...
;         for (int it = 0; it < 2; ++it) {
;             const int q = u + 256 * it, f = q >> 6, L = q & 63, mt = f >> 1, ks = f & 1, quad = L >> 4, r = L & 15, i_ = 16 * mt + r;
;             const f32x4 a0 = *(const f32x4*)(At + i_ * 68 + 32 * ks + 4 * quad), a1 = *(const f32x4*)(At + i_ * 68 + 32 * ks + 16 + 4 * quad);
;             u32x4 w; w.x = pack2(a0[0], a0[1]); w.y = pack2(a0[2], a0[3]); w.z = pack2(a1[0], a1[1]); w.w = pack2(a1[2], a1[3]);
;             __builtin_amdgcn_raw_buffer_store_b128(w, ur, 49152 + q * 16, 0, 16);
;         }
;         if (u == 0) __hip_atomic_store(egl + bh * 128 + n, __expf(glast), __ATOMIC_RELAXED, __HIP_MEMORY_SCOPE_AGENT);
.LBB0_401:
	v_readfirstlane_b32 s8, v94
	v_readfirstlane_b32 s9, v95
	v_readfirstlane_b32 s10, v174
	v_readfirstlane_b32 s11, v175
	v_cmp_eq_u64_e32 vcc, s[8:9], v[94:95]
	s_nop 0
	v_cmp_eq_u64_e64 s[0:1], s[10:11], v[174:175]
	s_and_b64 s[0:1], vcc, s[0:1]
	s_and_saveexec_b64 s[0:1], s[0:1]
	buffer_store_dwordx4 v[2:5], v6, s[8:11], 0 offen sc1
	s_xor_b64 exec, exec, s[0:1]
	s_cbranch_execnz .LBB0_401
	s_mov_b64 exec, s[14:15]
	v_cmp_eq_u32_e32 vcc, 0, v22
	s_and_b64 exec, exec, vcc
	s_cbranch_execz .LBB0_404
	v_mul_f32_e32 v2, 0x3fb8aa3b, v23
	v_exp_f32_e32 v6, v2
	v_lshlrev_b32_e32 v2, 2, v109
	v_mov_b32_e32 v3, v1
	v_lshl_add_u64 v[2:3], s[54:55], 0, v[2:3]
	v_lshlrev_b32_e32 v4, 2, v0
	v_mov_b32_e32 v5, v1
	v_lshl_add_u64 v[2:3], v[2:3], 0, v[4:5]
	global_store_dword v[2:3], v6, off sc1

; __device__ __forceinline__ void handoff_publish_wt(unsigned* flag, unsigned val) {
;     asm volatile("s_waitcnt vmcnt(0)" ::: "memory");
;     __syncthreads();
;     if (threadIdx.x == 0) __hip_atomic_store(flag, val, __ATOMIC_RELAXED, __HIP_MEMORY_SCOPE_AGENT);
; }
; __device__ void prep_unit(unsigned char* lds, int bh, int n, const bf16_t* pc, const float* scal, const float* convw  , float alog, float dtb, unsigned char* unit, float* egl, unsigned* flag, unsigned fval) {
;     ...
; #pragma unroll
;     for (int it = 0; it < 2; ++it) { const int q = tid + NTHR * it; __builtin_amdgcn_raw_buffer_store_b128(*(const u32x4*)((const unsigned char*)stage + q * 16), ur, q * 16, 0, 16); }
;     handoff_publish_wt(flag, fval);
.LBB0_445:
	v_readfirstlane_b32 s8, v94
	v_readfirstlane_b32 s9, v95
	v_readfirstlane_b32 s10, v174
	v_readfirstlane_b32 s11, v175
	v_cmp_eq_u64_e32 vcc, s[8:9], v[94:95]
	s_nop 0
	v_cmp_eq_u64_e64 s[0:1], s[10:11], v[174:175]
	s_and_b64 s[0:1], vcc, s[0:1]
	s_and_saveexec_b64 s[0:1], s[0:1]
	s_waitcnt lgkmcnt(0)
	buffer_store_dwordx4 v[2:5], v6, s[8:11], 0 offen sc1
	s_xor_b64 exec, exec, s[0:1]
	s_cbranch_execnz .LBB0_445
	s_mov_b64 exec, s[2:3]
	s_waitcnt vmcnt(0)
	s_barrier
	s_mov_b64 s[0:1], exec
	v_readlane_b32 s2, v254, 1
	v_readlane_b32 s3, v254, 2
	s_and_b64 s[2:3], s[0:1], s[2:3]
	v_readlane_b32 s4, v255, 45
	s_xor_b64 s[0:1], s[2:3], s[0:1]
	v_readlane_b32 s5, v255, 46
	s_mov_b64 exec, s[2:3]
	s_cbranch_execz .LBB0_448
	v_readlane_b32 s2, v255, 11
	v_lshlrev_b32_e32 v2, 2, v109
	v_mov_b32_e32 v3, v1
	v_readlane_b32 s3, v255, 12
	v_lshlrev_b32_e32 v0, 2, v0
	s_nop 0
	v_lshl_add_u64 v[2:3], s[2:3], 0, v[2:3]
	v_lshl_add_u64 v[2:3], v[2:3], 0, v[0:1]
	global_store_dword v[2:3], v226, off sc1

; __device__ __forceinline__ int scan_wait(unsigned char* lds, const unsigned* uflag, int ready, int need, unsigned fval) {
;     volatile int* slot = (volatile int*)(lds + LDS_SLOT_C + 4);
;     if (threadIdx.x < 64) {
;         const int lane = threadIdx.x; int r = ready;
;         for (;;) {
;             const int idx = r + lane; unsigned v = fval;
;             if (idx < 128) v = __hip_atomic_load(uflag + idx, __ATOMIC_RELAXED, __HIP_MEMORY_SCOPE_AGENT);
;             const unsigned long long notready = __ballot(v < fval);
;             const int cnt = notready ? (int)__builtin_ctzll(notready) : 64;
;             r += cnt; if (r > 128) r = 128;
;             if (r >= need) break;
;             __builtin_amdgcn_s_sleep(8);
;         }
.LBB0_456:
	v_add_u32_e32 v0, s9, v212
	v_cmp_gt_i32_e32 vcc, s46, v0
	s_mov_b64 s[6:7], 0
	s_and_saveexec_b64 s[4:5], vcc
	s_cbranch_execz .LBB0_454
	v_lshl_add_u64 v[2:3], v[0:1], 2, v[178:179]
	global_load_dword v0, v[2:3], off sc1
	s_waitcnt vmcnt(0) lgkmcnt(0)
	v_cmp_gt_u32_e32 vcc, s73, v0
	s_and_b64 s[6:7], vcc, exec
	s_branch .LBB0_454

; #define CP_LOAD(R, c) do { SCAN_WAIT(c); if ((c) < 128) { const unsigned char* uc_ = ubase + (size_t)(c) * PREP_UNIT; \
;             _Pragma("unroll") for (int mt = 0; mt < 4; ++mt) R##u[mt] = *(const u32x2*)(uc_ + 57344 + ((size_t)(col0 + cl) * 64 + 16 * mt + quad * 4) * 2); R##e = egl[bh * 128 + (c)]; } } while (0)
; __device__ __forceinline__ int scan_wait(unsigned char* lds, const unsigned* uflag, int ready, int need, unsigned fval) {
;     ...
;         if (lane == 0) *slot = r;
;     }
;     __syncthreads();
;     const int res = *slot;
;     __syncthreads();
;     return res;
; __device__ void scan_unit(unsigned char* lds, int bh, int half, unsigned char* prep, const float* egl, const unsigned* uflag  , unsigned fval) {
;     ...
;         CP_LOAD(r0, 0); CP_LOAD(r1, 1); CP_LOAD(r2, 2);
.LBB0_461:
	s_or_b64 exec, exec, s[2:3]
	s_mov_b64 s[2:3], src_shared_base
	s_lshl_b32 s2, s8, 4
	s_add_i32 s20, 0, 0x26404
	s_mov_b64 s[4:5], 0xe000
	s_cmp_lg_u32 s20, -1
	v_and_b32_e32 v4, 1, v90
	v_lshl_add_u64 v[2:3], v[180:181], 0, s[4:5]
	s_cselect_b32 s4, s20, 0
	s_cselect_b32 s3, s3, 0
	v_lshl_add_u32 v8, v4, 6, s2
	v_and_b32_e32 v0, 15, v50
	v_mov_b32_e32 v6, s4
	v_mov_b32_e32 v7, s3
	s_waitcnt lgkmcnt(0)
	s_barrier
	flat_load_dword v51, v[6:7] sc0 sc1
	s_waitcnt vmcnt(0)
	v_or_b32_e32 v6, v8, v0
	v_ashrrev_i32_e32 v7, 31, v6
	v_bfe_u32 v5, v50, 4, 2
	v_lshlrev_b64 v[56:57], 7, v[6:7]
	v_lshl_or_b32 v56, v5, 3, v56
	v_or_b32_e32 v58, 32, v56
	v_mov_b32_e32 v59, v57
	v_or_b32_e32 v60, 64, v56
	v_mov_b32_e32 v61, v57
	v_or_b32_e32 v62, 0x60, v56
	v_mov_b32_e32 v63, v57
	v_lshl_add_u64 v[6:7], v[2:3], 0, v[56:57]
	v_lshl_add_u64 v[8:9], v[2:3], 0, v[58:59]
	v_lshl_add_u64 v[10:11], v[2:3], 0, v[60:61]
	v_lshl_add_u64 v[2:3], v[2:3], 0, v[62:63]
	v_lshl_add_u64 v[54:55], v[52:53], 2, s[54:55]
	s_waitcnt lgkmcnt(0)
	s_barrier
	global_load_dwordx2 v[106:107], v[2:3], off
	global_load_dwordx2 v[112:113], v[6:7], off
	global_load_dwordx2 v[110:111], v[8:9], off
	global_load_dwordx2 v[108:109], v[10:11], off
	global_load_dword v98, v[54:55], off
	v_cmp_gt_i32_e32 vcc, 2, v51
	s_and_saveexec_b64 s[4:5], vcc
	s_cbranch_execz .LBB0_472
	s_mov_b64 s[6:7], exec
	v_readlane_b32 s8, v254, 13
	v_readlane_b32 s9, v254, 14
	s_and_b64 s[8:9], s[6:7], s[8:9]
	s_mov_b64 exec, s[8:9]
	s_cbranch_execz .LBB0_471
	s_mov_b64 s[8:9], 0
	s_branch .LBB0_465

; __device__ __forceinline__ int scan_wait(unsigned char* lds, const unsigned* uflag, int ready, int need, unsigned fval) {
;     ...
;     if (threadIdx.x < 64) {
;         const int lane = threadIdx.x; int r = ready;
;         for (;;) {
;             const int idx = r + lane; unsigned v = fval;
;             if (idx < 128) v = __hip_atomic_load(uflag + idx, __ATOMIC_RELAXED, __HIP_MEMORY_SCOPE_AGENT);
;             const unsigned long long notready = __ballot(v < fval);
;             const int cnt = notready ? (int)__builtin_ctzll(notready) : 64;
;             r += cnt; if (r > 128) r = 128;
;             if (r >= need) break;
.LBB0_465:
	v_add_u32_e32 v2, v51, v212
	v_cmp_gt_i32_e32 vcc, s46, v2
	s_mov_b64 s[12:13], 0
	s_and_saveexec_b64 s[10:11], vcc
	s_cbranch_execz .LBB0_467
	v_ashrrev_i32_e32 v3, 31, v2
	v_lshl_add_u64 v[2:3], v[2:3], 2, v[178:179]
	global_load_dword v2, v[2:3], off sc1
	s_waitcnt vmcnt(0) lgkmcnt(0)
	v_cmp_gt_u32_e32 vcc, s73, v2
	s_and_b64 s[12:13], vcc, exec

; #define CP_LOAD(R, c) do { SCAN_WAIT(c); if ((c) < 128) { const unsigned char* uc_ = ubase + (size_t)(c) * PREP_UNIT; \
;             _Pragma("unroll") for (int mt = 0; mt < 4; ++mt) R##u[mt] = *(const u32x2*)(uc_ + 57344 + ((size_t)(col0 + cl) * 64 + 16 * mt + quad * 4) * 2); R##e = egl[bh * 128 + (c)]; } } while (0)
; __device__ void scan_unit(unsigned char* lds, int bh, int half, unsigned char* prep, const float* egl, const unsigned* uflag  , unsigned fval) {
;     ...
;         CP_LOAD(r0, 0); CP_LOAD(r1, 1); CP_LOAD(r2, 2);
.LBB0_472:
	s_or_b64 exec, exec, s[4:5]
	s_mov_b64 s[4:5], 0x20000
	v_lshl_add_u64 v[2:3], v[180:181], 0, s[4:5]
	v_lshl_add_u64 v[8:9], v[2:3], 0, v[56:57]
	v_lshl_add_u64 v[10:11], v[2:3], 0, v[58:59]
	v_lshl_add_u64 v[12:13], v[2:3], 0, v[60:61]
	v_lshl_add_u64 v[2:3], v[2:3], 0, v[62:63]
	global_load_dwordx2 v[88:89], v[2:3], off
	global_load_dwordx2 v[94:95], v[8:9], off
	global_load_dwordx2 v[92:93], v[10:11], off
	global_load_dwordx2 v[90:91], v[12:13], off
	global_load_dword v86, v[54:55], off offset:4
	v_and_b32_e32 v6, 63, v50
	v_cmp_gt_i32_e32 vcc, 3, v51
	s_and_saveexec_b64 s[4:5], vcc
	s_cbranch_execz .LBB0_483
	s_mov_b64 s[6:7], exec
	v_readlane_b32 s8, v254, 13
	v_readlane_b32 s9, v254, 14
	s_and_b64 s[8:9], s[6:7], s[8:9]
	s_mov_b64 exec, s[8:9]
	s_cbranch_execz .LBB0_482
	s_mov_b64 s[8:9], 0
	s_branch .LBB0_476

; __device__ __forceinline__ unsigned pack2(float lo, float hi) { return pg8::cvt_pk_bf16(lo, hi); }
; __device__ __forceinline__ void scan_compute(const unsigned char* B, const u32x2* ut, float eg, f32x4* Sacc, bf16x8* Sb, bf16_t* op0, int lane) {
;     const unsigned char* Bl = B + lane * 16;
;     bf16x8 fx[16], fy[8];
; #pragma unroll
;     for (int i = 0; i < 16; ++i) fx[i] = *(const bf16x8*)(Bl + i * 1024);
; #pragma unroll
;     for (int i = 0; i < 8; ++i) fy[i] = *(const bf16x8*)(Bl + 16384 + i * 1024);
;     f32x4 vn[4];
; #pragma unroll
;     for (int mt = 0; mt < 4; ++mt) { vn[mt][0] = __uint_as_float(ut[mt].x << 16); vn[mt][1] = __uint_as_float(ut[mt].x & 0xffff0000u); vn[mt][2] = __uint_as_float(ut[mt].y << 16); vn[mt][3] = __uint_as_float(ut[mt].y & 0xffff0000u); }
;     SCAN_SB;
; #pragma unroll
;     for (int ks = 0; ks < 4; ++ks)
; #pragma unroll
;         for (int mt = 0; mt < 4; ++mt) vn[mt] = MFMA16(fx[mt * 4 + ks], Sb[ks], vn[mt]);
;     SCAN_SB;
; #pragma unroll
;     for (int i = 0; i < 8; ++i) fx[i] = *(const bf16x8*)(Bl + 16384 + (8 + i) * 1024);
; #pragma unroll
;     for (int i = 0; i < 8; ++i) fx[8 + i] = *(const bf16x8*)(Bl + 49152 + i * 1024);
;     f32x4 oa[4];
; #pragma unroll
;     for (int mt = 0; mt < 4; ++mt) oa[mt] = (f32x4){0.f, 0.f, 0.f, 0.f};
;     SCAN_SB;
; #pragma unroll
;     for (int ks = 0; ks < 4; ++ks)
; #pragma unroll
;         for (int mt = 0; mt < 2; ++mt) oa[mt] = MFMA16(fy[mt * 4 + ks], Sb[ks], oa[mt]);
;     bf16x8 Vb[2];
; #pragma unroll
;     for (int ks = 0; ks < 2; ++ks) { u32x4 w; w.x = pack2(vn[2 * ks][0], vn[2 * ks][1]); w.y = pack2(vn[2 * ks][2], vn[2 * ks][3]); w.z = pack2(vn[2 * ks + 1][0], vn[2 * ks + 1][1]); w.w = pack2(vn[2 * ks + 1][2], vn[2 * ks + 1][3]);
;         Vb[ks] = __builtin_bit_cast(bf16x8, w); }
; __device__ void scan_unit(unsigned char* lds, int bh, int half, unsigned char* prep, const float* egl, const unsigned* uflag  , unsigned fval) {
;     ...
;         u32x2 r0u[4], r1u[4], r2u[4]; float r0e = 0.f, r1e = 0.f, r2e = 0.f;
; #pragma unroll
;         for (int mt = 0; mt < 4; ++mt) { r0u[mt] = (u32x2){0u, 0u}; r1u[mt] = (u32x2){0u, 0u}; r2u[mt] = (u32x2){0u, 0u}; }
;     ...
;         CP_LOAD(r0, 0); CP_LOAD(r1, 1); CP_LOAD(r2, 2);
;         __syncthreads();
;         for (int n = 0; n < 128; n += 3) { CP_STEP(n, r0); CP_STEP(n + 1, r1); CP_STEP(n + 2, r2); }
.LBB0_483:
	s_or_b64 exec, exec, s[4:5]
	s_mov_b64 s[4:5], 0x32000
	v_lshl_add_u64 v[2:3], v[180:181], 0, s[4:5]
	v_lshl_add_u64 v[8:9], v[2:3], 0, v[56:57]
	v_lshl_add_u64 v[10:11], v[2:3], 0, v[58:59]
	v_lshl_add_u64 v[12:13], v[2:3], 0, v[60:61]
	v_lshl_add_u64 v[2:3], v[2:3], 0, v[62:63]
	global_load_dwordx2 v[70:71], v[2:3], off
	global_load_dwordx2 v[76:77], v[8:9], off
	global_load_dwordx2 v[74:75], v[10:11], off
	global_load_dwordx2 v[72:73], v[12:13], off
	global_load_dword v68, v[54:55], off offset:8
	v_lshlrev_b32_e32 v2, 8, v5
	v_mov_b32_e32 v22, v1
	v_mov_b32_e32 v23, v1
	v_mov_b32_e32 v24, v1
	v_mov_b32_e32 v25, v1
	v_lshlrev_b32_e32 v64, 13, v4
	v_lshl_add_u32 v53, v6, 4, 0
	v_lshlrev_b32_e32 v66, 1, v0
	v_lshlrev_b32_e32 v0, 1, v2
	v_mov_b64_e32 v[28:29], v[24:25]
	v_mov_b64_e32 v[32:33], v[24:25]
	v_mov_b64_e32 v[10:11], v[22:23]
	v_mov_b64_e32 v[2:3], v[22:23]
	v_mov_b64_e32 v[6:7], v[22:23]
	v_mov_b64_e32 v[14:15], v[22:23]
	v_mov_b64_e32 v[18:19], v[22:23]
	v_mov_b32_e32 v65, v1
	s_ashr_i32 s3, s2, 31
	s_mov_b32 s21, 0
	v_mov_b32_e32 v34, 0
	v_mov_b32_e32 v35, 0
	v_mov_b32_e32 v36, 0
	v_mov_b32_e32 v37, 0
	v_mov_b32_e32 v38, 0
	v_mov_b32_e32 v39, 0
	v_mov_b32_e32 v40, 0
	v_mov_b32_e32 v41, 0
	v_mov_b32_e32 v42, 0
	v_mov_b32_e32 v43, 0
	v_mov_b32_e32 v44, 0
	v_mov_b32_e32 v45, 0
	v_mov_b32_e32 v46, 0
	v_mov_b32_e32 v47, 0
	v_mov_b32_e32 v48, 0
	v_mov_b32_e32 v49, 0
	v_mov_b64_e32 v[26:27], v[22:23]
	v_mov_b64_e32 v[30:31], v[22:23]
	v_mov_b64_e32 v[12:13], v[24:25]
	v_mov_b64_e32 v[4:5], v[24:25]
	v_mov_b64_e32 v[8:9], v[24:25]
	v_mov_b64_e32 v[16:17], v[24:25]
	v_mov_b64_e32 v[20:21], v[24:25]
	s_waitcnt lgkmcnt(0)
	s_barrier
	s_branch .LBB0_486
.LBB0_484:
	ds_read_b128 v[108:111], v114
	ds_read_b128 v[116:119], v114 offset:1024
	ds_read_b128 v[120:123], v114 offset:2048
	ds_read_b128 v[124:127], v114 offset:3072
	ds_read_b128 v[128:131], v114 offset:4096
	ds_read_b128 v[132:135], v114 offset:5120
	ds_read_b128 v[136:139], v114 offset:6144
	ds_read_b128 v[140:143], v114 offset:7168
	ds_read_b128 v[144:147], v114 offset:8192
	ds_read_b128 v[148:151], v114 offset:9216
	ds_read_b128 v[152:155], v114 offset:10240
	ds_read_b128 v[156:159], v114 offset:11264
	ds_read_b128 v[160:163], v114 offset:12288
	ds_read_b128 v[164:167], v114 offset:13312
	ds_read_b128 v[182:185], v114 offset:14336
	ds_read_b128 v[186:189], v114 offset:15360
	ds_read_b128 v[190:193], v114 offset:16384
	ds_read_b128 v[194:197], v114 offset:17408
	ds_read_b128 v[198:201], v114 offset:18432
	ds_read_b128 v[202:205], v114 offset:19456
	ds_read_b128 v[206:209], v114 offset:20480
	ds_read_b128 v[228:231], v114 offset:21504
	ds_read_b128 v[232:235], v114 offset:22528
	ds_read_b128 v[236:239], v114 offset:23552
	v_lshl_add_u64 v[94:95], v[96:97], 0, v[0:1]
	v_lshl_add_u64 v[94:95], s[2:3], 1, v[94:95]
	v_mov_b32_e32 v67, v1
	v_lshl_add_u64 v[94:95], v[94:95], 0, v[66:67]
	s_mov_b64 s[4:5], 0x32000
	v_lshlrev_b32_e32 v240, 16, v76
	v_and_b32_e32 v241, 0xffff0000, v76
	v_lshlrev_b32_e32 v242, 16, v77
	v_and_b32_e32 v243, 0xffff0000, v77
	v_lshlrev_b32_e32 v244, 16, v74
	v_and_b32_e32 v245, 0xffff0000, v74
	v_lshlrev_b32_e32 v246, 16, v75
	v_and_b32_e32 v247, 0xffff0000, v75
	v_lshlrev_b32_e32 v74, 16, v72
	v_and_b32_e32 v75, 0xffff0000, v72
	v_lshlrev_b32_e32 v76, 16, v73
	v_and_b32_e32 v77, 0xffff0000, v73
	v_lshl_add_u64 v[96:97], v[94:95], 0, s[4:5]
	v_lshlrev_b32_e32 v248, 16, v70
	v_and_b32_e32 v249, 0xffff0000, v70
	v_lshlrev_b32_e32 v250, 16, v71
	v_and_b32_e32 v251, 0xffff0000, v71
	s_waitcnt lgkmcnt(0)
	v_mfma_f32_16x16x32_bf16 v[70:73], v[108:111], v[46:49], v[240:243]
	v_mfma_f32_16x16x32_bf16 v[74:77], v[144:147], v[46:49], v[74:77]
	v_mfma_f32_16x16x32_bf16 v[108:111], v[128:131], v[46:49], v[244:247]
	v_mfma_f32_16x16x32_bf16 v[128:131], v[160:163], v[46:49], v[248:251]
	v_mfma_f32_16x16x32_bf16 v[70:73], v[116:119], v[42:45], v[70:73]
	v_mfma_f32_16x16x32_bf16 v[74:77], v[148:151], v[42:45], v[74:77]
	v_mfma_f32_16x16x32_bf16 v[108:111], v[132:135], v[42:45], v[108:111]
	v_mfma_f32_16x16x32_bf16 v[116:119], v[164:167], v[42:45], v[128:131]
	v_mfma_f32_16x16x32_bf16 v[70:73], v[120:123], v[38:41], v[70:73]
	v_mfma_f32_16x16x32_bf16 v[74:77], v[152:155], v[38:41], v[74:77]
	v_mfma_f32_16x16x32_bf16 v[108:111], v[136:139], v[38:41], v[108:111]
	v_mfma_f32_16x16x32_bf16 v[116:119], v[182:185], v[38:41], v[116:119]
	v_mfma_f32_16x16x32_bf16 v[70:73], v[124:127], v[34:37], v[70:73]
	v_mfma_f32_16x16x32_bf16 v[74:77], v[156:159], v[34:37], v[74:77]
	v_mfma_f32_16x16x32_bf16 v[108:111], v[140:143], v[34:37], v[108:111]
	v_mfma_f32_16x16x32_bf16 v[116:119], v[186:189], v[34:37], v[116:119]
	ds_read_b128 v[120:123], v114 offset:24576
	ds_read_b128 v[124:127], v114 offset:25600
	ds_read_b128 v[128:131], v114 offset:26624
	ds_read_b128 v[132:135], v114 offset:27648
	ds_read_b128 v[136:139], v114 offset:28672
	ds_read_b128 v[140:143], v114 offset:29696
	ds_read_b128 v[144:147], v114 offset:30720
	ds_read_b128 v[148:151], v114 offset:31744
	ds_read_b128 v[152:155], v114 offset:49152
	ds_read_b128 v[156:159], v114 offset:50176
	ds_read_b128 v[160:163], v114 offset:51200
	ds_read_b128 v[164:167], v114 offset:52224
	ds_read_b128 v[182:185], v114 offset:53248
	ds_read_b128 v[186:189], v114 offset:54272
	ds_read_b128 v[240:243], v114 offset:55296
	ds_read_b128 v[244:247], v114 offset:56320
	v_mfma_f32_16x16x32_bf16 v[190:193], v[190:193], v[46:49], 0
	v_cvt_pk_bf16_f32 v70, v70, v71
	v_cvt_pk_bf16_f32 v71, v72, v73
	v_cvt_pk_bf16_f32 v72, v108, v109
	v_mfma_f32_16x16x32_bf16 v[206:209], v[206:209], v[46:49], 0
	v_cvt_pk_bf16_f32 v73, v110, v111
	v_cvt_pk_bf16_f32 v74, v74, v75
	v_cvt_pk_bf16_f32 v75, v76, v77
	v_mfma_f32_16x16x32_bf16 v[190:193], v[194:197], v[42:45], v[190:193]
	v_cvt_pk_bf16_f32 v76, v116, v117
	v_cvt_pk_bf16_f32 v77, v118, v119
	v_mfma_f32_16x16x32_bf16 v[194:197], v[228:231], v[42:45], v[206:209]
	v_mfma_f32_16x16x32_bf16 v[190:193], v[198:201], v[38:41], v[190:193]
	v_mfma_f32_16x16x32_bf16 v[194:197], v[232:235], v[38:41], v[194:197]
	v_mfma_f32_16x16x32_bf16 v[108:111], v[202:205], v[34:37], v[190:193]
	v_mfma_f32_16x16x32_bf16 v[116:119], v[236:239], v[34:37], v[194:197]
	s_nop 4
	ds_read_b128 v[190:193], v114 offset:32768
	ds_read_b128 v[194:197], v114 offset:33792
	ds_read_b128 v[198:201], v114 offset:34816
	ds_read_b128 v[202:205], v114 offset:35840
	ds_read_b128 v[206:209], v114 offset:36864
	ds_read_b128 v[228:231], v114 offset:37888
	ds_read_b128 v[232:235], v114 offset:38912
	ds_read_b128 v[236:239], v114 offset:39936
	s_waitcnt lgkmcnt(0)
; __device__ __forceinline__ unsigned pack2(float lo, float hi) { return pg8::cvt_pk_bf16(lo, hi); }
; #define MFMA16(a, b, c) __builtin_amdgcn_mfma_f32_16x16x32_bf16((a), (b), (c), 0, 0, 0)
; #define SCAN_SB __builtin_amdgcn_sched_barrier(0)
; __device__ __forceinline__ void scan_compute(const unsigned char* B, const u32x2* ut, float eg, f32x4* Sacc, bf16x8* Sb, bf16_t* op0, int lane) {
;     ...
; #pragma unroll
;     for (int i = 0; i < 8; ++i) fy[i] = *(const bf16x8*)(Bl + 32768 + i * 1024);
;     SCAN_SB;
; #pragma unroll
;     for (int ks = 0; ks < 4; ++ks)
; #pragma unroll
;         for (int mt = 2; mt < 4; ++mt) oa[mt] = MFMA16(fx[(mt - 2) * 4 + ks], Sb[ks], oa[mt]);
; #pragma unroll
;     for (int ks = 0; ks < 2; ++ks)
; #pragma unroll
;         for (int mt = 0; mt < 4; ++mt) oa[mt] = MFMA16(fx[8 + mt * 2 + ks], Vb[ks], oa[mt]);
;     SCAN_SB;
; #pragma unroll
;     for (int i = 0; i < 8; ++i) fx[i] = *(const bf16x8*)(Bl + 32768 + (8 + i) * 1024);
;     SCAN_SB;
; #pragma unroll
;     for (int m8 = 0; m8 < 4; ++m8) { f32x4 acc = Sacc[m8] * eg;
; #pragma unroll
;         for (int ks = 0; ks < 2; ++ks) acc = MFMA16(fy[m8 * 2 + ks], Vb[ks], acc);
;         Sacc[m8] = acc; }
;     SCAN_SB;
; #pragma unroll
;     for (int m8 = 4; m8 < 8; ++m8) { f32x4 acc = Sacc[m8] * eg;
; #pragma unroll
;         for (int ks = 0; ks < 2; ++ks) acc = MFMA16(fx[(m8 - 4) * 2 + ks], Vb[ks], acc);
;         Sacc[m8] = acc; }
; #pragma unroll
;     for (int mt = 0; mt < 4; ++mt) {
;         bf16_t* op = op0 + (16 * mt) * 64;
;         const unsigned p0 = pack2(oa[mt][0], oa[mt][1]), p1 = pack2(oa[mt][2], oa[mt][3]);
;         op[0] = (bf16_t)(p0 & 0xffffu); op[64] = (bf16_t)(p0 >> 16); op[128] = (bf16_t)(p1 & 0xffffu); op[192] = (bf16_t)(p1 >> 16);
;     }
; #pragma unroll
;     for (int ks = 0; ks < 4; ++ks) { u32x4 w; w.x = pack2(Sacc[2 * ks][0], Sacc[2 * ks][1]); w.y = pack2(Sacc[2 * ks][2], Sacc[2 * ks][3]); w.z = pack2(Sacc[2 * ks + 1][0], Sacc[2 * ks + 1][1]); w.w = pack2(Sacc[2 * ks + 1][2], Sacc[2 * ks + 1][3]);
;         Sb[ks] = __builtin_bit_cast(bf16x8, w); }
	v_mfma_f32_16x16x32_bf16 v[120:123], v[120:123], v[46:49], 0
	v_mfma_f32_16x16x32_bf16 v[46:49], v[136:139], v[46:49], 0
	v_mfma_f32_16x16x32_bf16 v[120:123], v[124:127], v[42:45], v[120:123]
	v_mfma_f32_16x16x32_bf16 v[42:45], v[140:143], v[42:45], v[46:49]
	v_mfma_f32_16x16x32_bf16 v[46:49], v[128:131], v[38:41], v[120:123]
	v_mfma_f32_16x16x32_bf16 v[38:41], v[144:147], v[38:41], v[42:45]
	v_mfma_f32_16x16x32_bf16 v[42:45], v[132:135], v[34:37], v[46:49]
	v_mfma_f32_16x16x32_bf16 v[34:37], v[148:151], v[34:37], v[38:41]
	v_mfma_f32_16x16x32_bf16 v[38:41], v[152:155], v[70:73], v[108:111]
	v_mfma_f32_16x16x32_bf16 v[46:49], v[160:163], v[70:73], v[116:119]
	v_mfma_f32_16x16x32_bf16 v[42:45], v[182:185], v[70:73], v[42:45]
	v_mfma_f32_16x16x32_bf16 v[34:37], v[240:243], v[70:73], v[34:37]
	v_mfma_f32_16x16x32_bf16 v[38:41], v[156:159], v[74:77], v[38:41]
	v_mfma_f32_16x16x32_bf16 v[46:49], v[164:167], v[74:77], v[46:49]
	v_mfma_f32_16x16x32_bf16 v[42:45], v[186:189], v[74:77], v[42:45]
	v_mfma_f32_16x16x32_bf16 v[34:37], v[244:247], v[74:77], v[34:37]
	ds_read_b128 v[108:111], v114 offset:40960
	ds_read_b128 v[116:119], v114 offset:41984
	ds_read_b128 v[120:123], v114 offset:43008
	ds_read_b128 v[124:127], v114 offset:44032
	ds_read_b128 v[128:131], v114 offset:45056
	ds_read_b128 v[132:135], v114 offset:46080
	ds_read_b128 v[136:139], v114 offset:47104
	ds_read_b128 v[140:143], v114 offset:48128
	s_waitcnt vmcnt(0)
	v_pk_mul_f32 v[20:21], v[68:69], v[20:21] op_sel_hi:[0,1]
	v_pk_mul_f32 v[18:19], v[68:69], v[18:19] op_sel_hi:[0,1]
	v_pk_mul_f32 v[16:17], v[68:69], v[16:17] op_sel_hi:[0,1]
	v_pk_mul_f32 v[14:15], v[68:69], v[14:15] op_sel_hi:[0,1]
	v_pk_mul_f32 v[8:9], v[68:69], v[8:9] op_sel_hi:[0,1]
	v_pk_mul_f32 v[6:7], v[68:69], v[6:7] op_sel_hi:[0,1]
	v_pk_mul_f32 v[4:5], v[68:69], v[4:5] op_sel_hi:[0,1]
	v_pk_mul_f32 v[2:3], v[68:69], v[2:3] op_sel_hi:[0,1]
	v_mfma_f32_16x16x32_bf16 v[18:21], v[190:193], v[70:73], v[18:21]
	v_mfma_f32_16x16x32_bf16 v[14:17], v[198:201], v[70:73], v[14:17]
	v_mfma_f32_16x16x32_bf16 v[6:9], v[206:209], v[70:73], v[6:9]
	v_mfma_f32_16x16x32_bf16 v[2:5], v[232:235], v[70:73], v[2:5]
	v_mfma_f32_16x16x32_bf16 v[18:21], v[194:197], v[74:77], v[18:21]
	v_mfma_f32_16x16x32_bf16 v[14:17], v[202:205], v[74:77], v[14:17]
	v_mfma_f32_16x16x32_bf16 v[6:9], v[228:231], v[74:77], v[6:9]
	v_mfma_f32_16x16x32_bf16 v[2:5], v[236:239], v[74:77], v[2:5]
	v_mul_f32_e64 v12, v68, v12
	v_mul_f32_e64 v13, v68, v13
	v_pk_mul_f32 v[10:11], v[68:69], v[10:11] op_sel_hi:[0,1]
	v_pk_mul_f32 v[32:33], v[68:69], v[32:33] op_sel_hi:[0,1]
	v_pk_mul_f32 v[30:31], v[68:69], v[30:31] op_sel_hi:[0,1]
	v_pk_mul_f32 v[28:29], v[68:69], v[28:29] op_sel_hi:[0,1]
	v_pk_mul_f32 v[26:27], v[68:69], v[26:27] op_sel_hi:[0,1]
	v_pk_mul_f32 v[24:25], v[68:69], v[24:25] op_sel_hi:[0,1]
	v_pk_mul_f32 v[22:23], v[68:69], v[22:23] op_sel_hi:[0,1]
	s_waitcnt lgkmcnt(7)
	v_mfma_f32_16x16x32_bf16 v[10:13], v[108:111], v[70:73], v[10:13]
	s_mov_b32 s4, 0x32000
	v_cvt_pk_bf16_f32 v67, v38, v39
	v_add_co_u32_e32 v38, vcc, s4, v94
	s_waitcnt lgkmcnt(5)
	v_mfma_f32_16x16x32_bf16 v[30:33], v[120:123], v[70:73], v[30:33]
	v_addc_co_u32_e32 v39, vcc, 0, v95, vcc
	v_cvt_pk_bf16_f32 v40, v40, v41
	s_waitcnt lgkmcnt(3)
	v_mfma_f32_16x16x32_bf16 v[26:29], v[128:131], v[70:73], v[26:29]
	global_store_short v[38:39], v67, off
	global_store_short_d16_hi v[96:97], v67, off offset:128
	global_store_short v[96:97], v40, off offset:256
	v_cvt_pk_bf16_f32 v38, v46, v47
	s_mov_b32 s4, 0x33000
	s_waitcnt lgkmcnt(0)
	v_mfma_f32_16x16x32_bf16 v[22:25], v[136:139], v[70:73], v[22:25]
	global_store_short_d16_hi v[96:97], v40, off offset:384
	v_cvt_pk_bf16_f32 v39, v48, v49
	global_store_short v[96:97], v38, off offset:2048
	global_store_short_d16_hi v[96:97], v38, off offset:2176
	global_store_short v[96:97], v39, off offset:2304
	v_mfma_f32_16x16x32_bf16 v[10:13], v[116:119], v[74:77], v[10:13]
	v_add_co_u32_e32 v38, vcc, s4, v94
	global_store_short_d16_hi v[96:97], v39, off offset:2432
	v_mfma_f32_16x16x32_bf16 v[30:33], v[124:127], v[74:77], v[30:33]
	v_cvt_pk_bf16_f32 v40, v42, v43
	v_cvt_pk_bf16_f32 v41, v44, v45
	v_addc_co_u32_e32 v39, vcc, 0, v95, vcc
	v_mfma_f32_16x16x32_bf16 v[26:29], v[132:135], v[74:77], v[26:29]
	v_cvt_pk_bf16_f32 v34, v34, v35
	v_cvt_pk_bf16_f32 v35, v36, v37
	global_store_short v[38:39], v40, off
	global_store_short_d16_hi v[38:39], v40, off offset:128
	global_store_short v[38:39], v41, off offset:256
	global_store_short_d16_hi v[38:39], v41, off offset:384
	v_mfma_f32_16x16x32_bf16 v[22:25], v[140:143], v[74:77], v[22:25]
	global_store_short v[38:39], v34, off offset:2048
	global_store_short_d16_hi v[38:39], v34, off offset:2176
	global_store_short v[38:39], v35, off offset:2304
	global_store_short_d16_hi v[38:39], v35, off offset:2432
	v_cvt_pk_bf16_f32 v46, v18, v19
	v_cvt_pk_bf16_f32 v47, v20, v21
	v_cvt_pk_bf16_f32 v48, v14, v15
	v_cvt_pk_bf16_f32 v49, v16, v17
	v_cvt_pk_bf16_f32 v42, v6, v7
	v_cvt_pk_bf16_f32 v43, v8, v9
	v_cvt_pk_bf16_f32 v44, v2, v3
	v_cvt_pk_bf16_f32 v45, v4, v5
	v_cvt_pk_bf16_f32 v38, v10, v11
	v_cvt_pk_bf16_f32 v39, v12, v13
	v_cvt_pk_bf16_f32 v40, v30, v31
	v_cvt_pk_bf16_f32 v41, v32, v33
	v_cvt_pk_bf16_f32 v34, v26, v27
	v_cvt_pk_bf16_f32 v35, v28, v29
	v_cvt_pk_bf16_f32 v36, v22, v23
	v_cvt_pk_bf16_f32 v37, v24, v25
	v_mov_b32_e32 v68, v106
	v_mov_b64_e32 v[76:77], v[92:93]
	v_mov_b64_e32 v[74:75], v[90:91]
	v_mov_b64_e32 v[72:73], v[88:89]
	v_mov_b64_e32 v[70:71], v[86:87]
	s_waitcnt lgkmcnt(0)
	s_barrier

; __device__ __forceinline__ int scan_wait(unsigned char* lds, const unsigned* uflag, int ready, int need, unsigned fval) {
;     ...
;     if (threadIdx.x < 64) {
;         const int lane = threadIdx.x; int r = ready;
;         for (;;) {
;             const int idx = r + lane; unsigned v = fval;
;             if (idx < 128) v = __hip_atomic_load(uflag + idx, __ATOMIC_RELAXED, __HIP_MEMORY_SCOPE_AGENT);
;             const unsigned long long notready = __ballot(v < fval);
;             const int cnt = notready ? (int)__builtin_ctzll(notready) : 64;
;             r += cnt; if (r > 128) r = 128;
;             if (r >= need) break;
;             __builtin_amdgcn_s_sleep(8);
.LBB0_491:
	v_add_u32_e32 v78, v51, v212
	v_cmp_gt_i32_e32 vcc, s46, v78
	s_mov_b64 s[16:17], 0
	s_and_saveexec_b64 s[14:15], vcc
	s_cbranch_execz .LBB0_493
	v_ashrrev_i32_e32 v79, 31, v78
	v_lshl_add_u64 v[78:79], v[78:79], 2, v[178:179]
	global_load_dword v67, v[78:79], off sc1
	s_waitcnt vmcnt(0) lgkmcnt(0)
	v_cmp_gt_u32_e32 vcc, s73, v67
	s_and_b64 s[16:17], vcc, exec

; __device__ __forceinline__ unsigned pack2(float lo, float hi) { return pg8::cvt_pk_bf16(lo, hi); }
; #define MFMA16(a, b, c) __builtin_amdgcn_mfma_f32_16x16x32_bf16((a), (b), (c), 0, 0, 0)
; #define SCAN_SB __builtin_amdgcn_sched_barrier(0)
; __device__ __forceinline__ void scan_compute(const unsigned char* B, const u32x2* ut, float eg, f32x4* Sacc, bf16x8* Sb, bf16_t* op0, int lane) {
;     const unsigned char* Bl = B + lane * 16;
;     bf16x8 fx[16], fy[8];
; #pragma unroll
;     for (int i = 0; i < 16; ++i) fx[i] = *(const bf16x8*)(Bl + i * 1024);
; #pragma unroll
;     for (int i = 0; i < 8; ++i) fy[i] = *(const bf16x8*)(Bl + 16384 + i * 1024);
;     f32x4 vn[4];
; #pragma unroll
;     for (int mt = 0; mt < 4; ++mt) { vn[mt][0] = __uint_as_float(ut[mt].x << 16); vn[mt][1] = __uint_as_float(ut[mt].x & 0xffff0000u); vn[mt][2] = __uint_as_float(ut[mt].y << 16); vn[mt][3] = __uint_as_float(ut[mt].y & 0xffff0000u); }
;     SCAN_SB;
; #pragma unroll
;     for (int ks = 0; ks < 4; ++ks)
; #pragma unroll
;         for (int mt = 0; mt < 4; ++mt) vn[mt] = MFMA16(fx[mt * 4 + ks], Sb[ks], vn[mt]);
;     SCAN_SB;
; #pragma unroll
;     for (int i = 0; i < 8; ++i) fx[i] = *(const bf16x8*)(Bl + 16384 + (8 + i) * 1024);
; #pragma unroll
;     for (int i = 0; i < 8; ++i) fx[8 + i] = *(const bf16x8*)(Bl + 49152 + i * 1024);
;     f32x4 oa[4];
; #pragma unroll
;     for (int mt = 0; mt < 4; ++mt) oa[mt] = (f32x4){0.f, 0.f, 0.f, 0.f};
;     SCAN_SB;
; #pragma unroll
;     for (int ks = 0; ks < 4; ++ks)
; #pragma unroll
;         for (int mt = 0; mt < 2; ++mt) oa[mt] = MFMA16(fy[mt * 4 + ks], Sb[ks], oa[mt]);
;     bf16x8 Vb[2];
; #pragma unroll
;     for (int ks = 0; ks < 2; ++ks) { u32x4 w; w.x = pack2(vn[2 * ks][0], vn[2 * ks][1]); w.y = pack2(vn[2 * ks][2], vn[2 * ks][3]); w.z = pack2(vn[2 * ks + 1][0], vn[2 * ks + 1][1]); w.w = pack2(vn[2 * ks + 1][2], vn[2 * ks + 1][3]);
;         Vb[ks] = __builtin_bit_cast(bf16x8, w); }
.LBB0_499:
	s_add_i32 s8, s21, 3
	s_andn2_b64 vcc, exec, s[4:5]
	s_waitcnt vmcnt(0)
	v_mov_b64_e32 v[84:85], v[106:107]
	v_mov_b64_e32 v[82:83], v[108:109]
	v_mov_b64_e32 v[80:81], v[110:111]
	v_mov_b64_e32 v[78:79], v[112:113]
	v_mov_b32_e32 v69, v98
	s_cbranch_vccnz .LBB0_501
	s_mul_i32 s84, s8, 0x12000
	v_lshl_add_u64 v[78:79], v[180:181], 0, s[84:85]
	s_mov_b64 s[4:5], 0xe000
	v_lshl_add_u64 v[78:79], v[78:79], 0, s[4:5]
	v_lshl_add_u64 v[80:81], v[78:79], 0, v[56:57]
	v_lshl_add_u64 v[82:83], v[78:79], 0, v[58:59]
	v_lshl_add_u64 v[84:85], v[78:79], 0, v[60:61]
	v_lshl_add_u64 v[96:97], v[78:79], 0, v[62:63]
	global_load_dwordx2 v[78:79], v[80:81], off
	s_nop 0
	global_load_dwordx2 v[80:81], v[82:83], off
	s_nop 0
	global_load_dwordx2 v[82:83], v[84:85], off
	s_nop 0
	global_load_dwordx2 v[84:85], v[96:97], off
	s_ashr_i32 s9, s8, 31
	v_lshl_add_u64 v[96:97], s[8:9], 2, v[54:55]
	global_load_dword v69, v[96:97], off
.LBB0_501:
	s_bitcmp1_b32 s21, 0
	s_cselect_b32 s4, 0xe000, 0
	v_add_u32_e32 v114, s4, v53
	ds_read_b128 v[116:119], v114
	ds_read_b128 v[120:123], v114 offset:1024
	ds_read_b128 v[124:127], v114 offset:2048
	ds_read_b128 v[128:131], v114 offset:3072
	ds_read_b128 v[132:135], v114 offset:4096
	ds_read_b128 v[136:139], v114 offset:5120
	ds_read_b128 v[140:143], v114 offset:6144
	ds_read_b128 v[144:147], v114 offset:7168
	ds_read_b128 v[148:151], v114 offset:8192
	ds_read_b128 v[152:155], v114 offset:9216
	ds_read_b128 v[156:159], v114 offset:10240
	ds_read_b128 v[160:163], v114 offset:11264
	ds_read_b128 v[164:167], v114 offset:12288
	ds_read_b128 v[182:185], v114 offset:13312
	ds_read_b128 v[186:189], v114 offset:14336
	ds_read_b128 v[190:193], v114 offset:15360
	ds_read_b128 v[194:197], v114 offset:16384
	ds_read_b128 v[198:201], v114 offset:17408
	ds_read_b128 v[202:205], v114 offset:18432
	ds_read_b128 v[206:209], v114 offset:19456
	ds_read_b128 v[228:231], v114 offset:20480
	ds_read_b128 v[232:235], v114 offset:21504
	ds_read_b128 v[236:239], v114 offset:22528
	ds_read_b128 v[240:243], v114 offset:23552
	s_mul_i32 s84, s21, 0x12000
	v_lshl_add_u64 v[96:97], v[180:181], 0, s[84:85]
	v_lshl_add_u64 v[96:97], v[96:97], 0, v[64:65]
	v_lshl_add_u64 v[100:101], v[96:97], 0, v[0:1]
	v_lshl_add_u64 v[100:101], s[2:3], 1, v[100:101]
	v_mov_b32_e32 v67, v1
	v_lshl_add_u64 v[100:101], v[100:101], 0, v[66:67]
	s_mov_b64 s[10:11], 0xe000
	v_lshl_add_u64 v[102:103], v[100:101], 0, s[10:11]
	v_lshlrev_b32_e32 v244, 16, v112
	v_and_b32_e32 v245, 0xffff0000, v112
	v_lshlrev_b32_e32 v246, 16, v113
	v_and_b32_e32 v247, 0xffff0000, v113
	v_lshlrev_b32_e32 v248, 16, v110
	v_and_b32_e32 v249, 0xffff0000, v110
	v_lshlrev_b32_e32 v250, 16, v111
	v_and_b32_e32 v251, 0xffff0000, v111
	v_lshlrev_b32_e32 v110, 16, v108
	v_and_b32_e32 v111, 0xffff0000, v108
	v_lshlrev_b32_e32 v112, 16, v109
	v_and_b32_e32 v113, 0xffff0000, v109
	v_lshlrev_b32_e32 v104, 16, v106
	v_and_b32_e32 v105, 0xffff0000, v106
	v_lshlrev_b32_e32 v106, 16, v107
	v_and_b32_e32 v107, 0xffff0000, v107
	s_waitcnt lgkmcnt(0)
	v_mfma_f32_16x16x32_bf16 v[116:119], v[116:119], v[46:49], v[244:247]
	v_mfma_f32_16x16x32_bf16 v[132:135], v[132:135], v[46:49], v[248:251]
	v_mfma_f32_16x16x32_bf16 v[108:111], v[148:151], v[46:49], v[110:113]
	v_mfma_f32_16x16x32_bf16 v[104:107], v[164:167], v[46:49], v[104:107]
	v_mfma_f32_16x16x32_bf16 v[116:119], v[120:123], v[42:45], v[116:119]
	v_mfma_f32_16x16x32_bf16 v[120:123], v[136:139], v[42:45], v[132:135]
	v_mfma_f32_16x16x32_bf16 v[108:111], v[152:155], v[42:45], v[108:111]
	v_mfma_f32_16x16x32_bf16 v[104:107], v[182:185], v[42:45], v[104:107]
	v_mfma_f32_16x16x32_bf16 v[116:119], v[124:127], v[38:41], v[116:119]
	v_mfma_f32_16x16x32_bf16 v[120:123], v[140:143], v[38:41], v[120:123]
	v_mfma_f32_16x16x32_bf16 v[108:111], v[156:159], v[38:41], v[108:111]
	v_mfma_f32_16x16x32_bf16 v[104:107], v[186:189], v[38:41], v[104:107]
	v_mfma_f32_16x16x32_bf16 v[116:119], v[128:131], v[34:37], v[116:119]
	v_mfma_f32_16x16x32_bf16 v[120:123], v[144:147], v[34:37], v[120:123]
	v_mfma_f32_16x16x32_bf16 v[108:111], v[160:163], v[34:37], v[108:111]
	v_mfma_f32_16x16x32_bf16 v[104:107], v[190:193], v[34:37], v[104:107]
	ds_read_b128 v[124:127], v114 offset:24576
	ds_read_b128 v[128:131], v114 offset:25600
	ds_read_b128 v[132:135], v114 offset:26624
	ds_read_b128 v[136:139], v114 offset:27648
	ds_read_b128 v[140:143], v114 offset:28672
	ds_read_b128 v[144:147], v114 offset:29696
	ds_read_b128 v[148:151], v114 offset:30720
	ds_read_b128 v[152:155], v114 offset:31744
	ds_read_b128 v[156:159], v114 offset:49152
	ds_read_b128 v[160:163], v114 offset:50176
	ds_read_b128 v[164:167], v114 offset:51200
	ds_read_b128 v[182:185], v114 offset:52224
	ds_read_b128 v[186:189], v114 offset:53248
	ds_read_b128 v[190:193], v114 offset:54272
	ds_read_b128 v[244:247], v114 offset:55296
	ds_read_b128 v[248:251], v114 offset:56320
	v_mfma_f32_16x16x32_bf16 v[194:197], v[194:197], v[46:49], 0
	v_cvt_pk_bf16_f32 v116, v116, v117
	v_cvt_pk_bf16_f32 v117, v118, v119
	v_cvt_pk_bf16_f32 v118, v120, v121
	v_mfma_f32_16x16x32_bf16 v[228:231], v[228:231], v[46:49], 0
	v_cvt_pk_bf16_f32 v119, v122, v123
	v_cvt_pk_bf16_f32 v108, v108, v109
	v_cvt_pk_bf16_f32 v109, v110, v111
	v_mfma_f32_16x16x32_bf16 v[194:197], v[198:201], v[42:45], v[194:197]
	v_cvt_pk_bf16_f32 v110, v104, v105
	v_cvt_pk_bf16_f32 v111, v106, v107
	v_mfma_f32_16x16x32_bf16 v[198:201], v[232:235], v[42:45], v[228:231]
	v_mfma_f32_16x16x32_bf16 v[194:197], v[202:205], v[38:41], v[194:197]
	v_mfma_f32_16x16x32_bf16 v[198:201], v[236:239], v[38:41], v[198:201]
	v_mfma_f32_16x16x32_bf16 v[120:123], v[206:209], v[34:37], v[194:197]
	v_mfma_f32_16x16x32_bf16 v[104:107], v[240:243], v[34:37], v[198:201]
	s_nop 4
	ds_read_b128 v[194:197], v114 offset:32768
	ds_read_b128 v[198:201], v114 offset:33792
	ds_read_b128 v[202:205], v114 offset:34816
	ds_read_b128 v[206:209], v114 offset:35840
	ds_read_b128 v[228:231], v114 offset:36864
	ds_read_b128 v[232:235], v114 offset:37888
	ds_read_b128 v[236:239], v114 offset:38912
	ds_read_b128 v[240:243], v114 offset:39936
	s_waitcnt lgkmcnt(0)
; __device__ __forceinline__ unsigned pack2(float lo, float hi) { return pg8::cvt_pk_bf16(lo, hi); }
; #define MFMA16(a, b, c) __builtin_amdgcn_mfma_f32_16x16x32_bf16((a), (b), (c), 0, 0, 0)
; #define SCAN_SB __builtin_amdgcn_sched_barrier(0)
; __device__ __forceinline__ void scan_compute(const unsigned char* B, const u32x2* ut, float eg, f32x4* Sacc, bf16x8* Sb, bf16_t* op0, int lane) {
;     ...
; #pragma unroll
;     for (int ks = 0; ks < 4; ++ks)
; #pragma unroll
;         for (int mt = 2; mt < 4; ++mt) oa[mt] = MFMA16(fx[(mt - 2) * 4 + ks], Sb[ks], oa[mt]);
; #pragma unroll
;     for (int ks = 0; ks < 2; ++ks)
; #pragma unroll
;         for (int mt = 0; mt < 4; ++mt) oa[mt] = MFMA16(fx[8 + mt * 2 + ks], Vb[ks], oa[mt]);
;     SCAN_SB;
; #pragma unroll
;     for (int i = 0; i < 8; ++i) fx[i] = *(const bf16x8*)(Bl + 32768 + (8 + i) * 1024);
;     SCAN_SB;
; #pragma unroll
;     for (int m8 = 0; m8 < 4; ++m8) { f32x4 acc = Sacc[m8] * eg;
; #pragma unroll
;         for (int ks = 0; ks < 2; ++ks) acc = MFMA16(fy[m8 * 2 + ks], Vb[ks], acc);
;         Sacc[m8] = acc; }
;     SCAN_SB;
; #pragma unroll
;     for (int m8 = 4; m8 < 8; ++m8) { f32x4 acc = Sacc[m8] * eg;
; #pragma unroll
;         for (int ks = 0; ks < 2; ++ks) acc = MFMA16(fx[(m8 - 4) * 2 + ks], Vb[ks], acc);
;         Sacc[m8] = acc; }
; #pragma unroll
;     for (int mt = 0; mt < 4; ++mt) {
;         bf16_t* op = op0 + (16 * mt) * 64;
;         const unsigned p0 = pack2(oa[mt][0], oa[mt][1]), p1 = pack2(oa[mt][2], oa[mt][3]);
;         op[0] = (bf16_t)(p0 & 0xffffu); op[64] = (bf16_t)(p0 >> 16); op[128] = (bf16_t)(p1 & 0xffffu); op[192] = (bf16_t)(p1 >> 16);
;     }
; #pragma unroll
;     for (int ks = 0; ks < 4; ++ks) { u32x4 w; w.x = pack2(Sacc[2 * ks][0], Sacc[2 * ks][1]); w.y = pack2(Sacc[2 * ks][2], Sacc[2 * ks][3]); w.z = pack2(Sacc[2 * ks + 1][0], Sacc[2 * ks + 1][1]); w.w = pack2(Sacc[2 * ks + 1][2], Sacc[2 * ks + 1][3]);
;         Sb[ks] = __builtin_bit_cast(bf16x8, w); }
	v_mfma_f32_16x16x32_bf16 v[124:127], v[124:127], v[46:49], 0
	v_mfma_f32_16x16x32_bf16 v[46:49], v[140:143], v[46:49], 0
	v_mfma_f32_16x16x32_bf16 v[124:127], v[128:131], v[42:45], v[124:127]
	v_mfma_f32_16x16x32_bf16 v[42:45], v[144:147], v[42:45], v[46:49]
	v_mfma_f32_16x16x32_bf16 v[46:49], v[132:135], v[38:41], v[124:127]
	v_mfma_f32_16x16x32_bf16 v[38:41], v[148:151], v[38:41], v[42:45]
	v_mfma_f32_16x16x32_bf16 v[42:45], v[136:139], v[34:37], v[46:49]
	v_mfma_f32_16x16x32_bf16 v[34:37], v[152:155], v[34:37], v[38:41]
	v_mfma_f32_16x16x32_bf16 v[38:41], v[156:159], v[116:119], v[120:123]
	v_mfma_f32_16x16x32_bf16 v[46:49], v[164:167], v[116:119], v[104:107]
	v_mfma_f32_16x16x32_bf16 v[42:45], v[186:189], v[116:119], v[42:45]
	v_mfma_f32_16x16x32_bf16 v[34:37], v[244:247], v[116:119], v[34:37]
	v_mfma_f32_16x16x32_bf16 v[38:41], v[160:163], v[108:111], v[38:41]
	v_mfma_f32_16x16x32_bf16 v[46:49], v[182:185], v[108:111], v[46:49]
	v_mfma_f32_16x16x32_bf16 v[42:45], v[190:193], v[108:111], v[42:45]
	v_mfma_f32_16x16x32_bf16 v[34:37], v[248:251], v[108:111], v[34:37]
	ds_read_b128 v[104:107], v114 offset:40960
	ds_read_b128 v[120:123], v114 offset:41984
	ds_read_b128 v[124:127], v114 offset:43008
	ds_read_b128 v[128:131], v114 offset:44032
	ds_read_b128 v[132:135], v114 offset:45056
	ds_read_b128 v[136:139], v114 offset:46080
	ds_read_b128 v[140:143], v114 offset:47104
	ds_read_b128 v[144:147], v114 offset:48128
	v_pk_mul_f32 v[20:21], v[20:21], v[98:99] op_sel_hi:[1,0]
	v_pk_mul_f32 v[18:19], v[18:19], v[98:99] op_sel_hi:[1,0]
	v_pk_mul_f32 v[16:17], v[16:17], v[98:99] op_sel_hi:[1,0]
	v_pk_mul_f32 v[14:15], v[14:15], v[98:99] op_sel_hi:[1,0]
	v_pk_mul_f32 v[8:9], v[8:9], v[98:99] op_sel_hi:[1,0]
	v_pk_mul_f32 v[6:7], v[6:7], v[98:99] op_sel_hi:[1,0]
	v_pk_mul_f32 v[4:5], v[4:5], v[98:99] op_sel_hi:[1,0]
	v_pk_mul_f32 v[2:3], v[2:3], v[98:99] op_sel_hi:[1,0]
	v_mfma_f32_16x16x32_bf16 v[18:21], v[194:197], v[116:119], v[18:21]
	v_mfma_f32_16x16x32_bf16 v[14:17], v[202:205], v[116:119], v[14:17]
	v_mfma_f32_16x16x32_bf16 v[6:9], v[228:231], v[116:119], v[6:9]
	v_mfma_f32_16x16x32_bf16 v[2:5], v[236:239], v[116:119], v[2:5]
	v_mfma_f32_16x16x32_bf16 v[18:21], v[198:201], v[108:111], v[18:21]
	v_mfma_f32_16x16x32_bf16 v[14:17], v[206:209], v[108:111], v[14:17]
	v_mfma_f32_16x16x32_bf16 v[6:9], v[232:235], v[108:111], v[6:9]
	v_mfma_f32_16x16x32_bf16 v[2:5], v[240:243], v[108:111], v[2:5]
	v_mul_f32_e64 v32, v32, v98
	v_mul_f32_e64 v33, v33, v98
	v_pk_mul_f32 v[30:31], v[30:31], v[98:99] op_sel_hi:[1,0]
	v_pk_mul_f32 v[28:29], v[28:29], v[98:99] op_sel_hi:[1,0]
	v_pk_mul_f32 v[26:27], v[26:27], v[98:99] op_sel_hi:[1,0]
	s_waitcnt lgkmcnt(0)
	v_mfma_f32_16x16x32_bf16 v[30:33], v[124:127], v[116:119], v[30:33]
	v_mul_f32_e64 v12, v12, v98
	v_mul_f32_e64 v13, v13, v98
	v_pk_mul_f32 v[10:11], v[10:11], v[98:99] op_sel_hi:[1,0]
	s_mov_b32 s4, 0xe000
	v_mfma_f32_16x16x32_bf16 v[26:29], v[132:135], v[116:119], v[26:29]
	v_cvt_pk_bf16_f32 v38, v38, v39
	v_cvt_pk_bf16_f32 v39, v40, v41
	s_cmpk_lt_u32 s21, 0x7c
	v_mfma_f32_16x16x32_bf16 v[10:13], v[104:107], v[116:119], v[10:13]
	v_mul_f32_e64 v106, v24, v98
	v_mul_f32_e64 v107, v25, v98
	v_pk_mul_f32 v[104:105], v[22:23], v[98:99] op_sel_hi:[1,0]
	v_cvt_pk_bf16_f32 v40, v42, v43
	v_mfma_f32_16x16x32_bf16 v[22:25], v[128:131], v[108:111], v[30:33]
	v_cvt_pk_bf16_f32 v34, v34, v35
	v_cvt_pk_bf16_f32 v41, v44, v45
	v_cvt_pk_bf16_f32 v35, v36, v37
	v_add_co_u32_e32 v30, vcc, s4, v100
	v_mfma_f32_16x16x32_bf16 v[10:13], v[120:123], v[108:111], v[10:13]
	s_nop 0
	v_addc_co_u32_e32 v31, vcc, 0, v101, vcc
	global_store_short v[30:31], v38, off
	global_store_short_d16_hi v[102:103], v38, off offset:128
	global_store_short v[102:103], v39, off offset:256
	v_mfma_f32_16x16x32_bf16 v[30:33], v[136:139], v[108:111], v[26:29]
	v_cvt_pk_bf16_f32 v38, v46, v47
	s_mov_b32 s4, 0xf000
	global_store_short_d16_hi v[102:103], v39, off offset:384
	v_mfma_f32_16x16x32_bf16 v[26:29], v[140:143], v[116:119], v[104:107]
	v_cvt_pk_bf16_f32 v39, v48, v49
	global_store_short v[102:103], v38, off offset:2048
	global_store_short_d16_hi v[102:103], v38, off offset:2176
	global_store_short v[102:103], v39, off offset:2304
	v_add_co_u32_e32 v38, vcc, s4, v100
	v_mfma_f32_16x16x32_bf16 v[26:29], v[144:147], v[108:111], v[26:29]
	global_store_short_d16_hi v[102:103], v39, off offset:2432
	v_addc_co_u32_e32 v39, vcc, 0, v101, vcc
	s_cselect_b64 s[4:5], -1, 0
	s_cmpk_gt_u32 s21, 0x7b
	global_store_short v[38:39], v40, off
	global_store_short_d16_hi v[38:39], v40, off offset:128
	global_store_short v[38:39], v41, off offset:256
	global_store_short_d16_hi v[38:39], v41, off offset:384
	global_store_short v[38:39], v34, off offset:2048
	global_store_short_d16_hi v[38:39], v34, off offset:2176
	global_store_short v[38:39], v35, off offset:2304
	global_store_short_d16_hi v[38:39], v35, off offset:2432
	s_waitcnt lgkmcnt(0)
	s_barrier
	s_cbranch_scc1 .LBB0_514
	s_add_i32 s9, s21, 5
	v_cmp_gt_i32_e32 vcc, s9, v51
	s_and_saveexec_b64 s[10:11], vcc
	s_cbranch_execz .LBB0_513
	s_mov_b64 s[12:13], exec
	v_readlane_b32 s14, v254, 13
	v_readlane_b32 s15, v254, 14
	s_and_b64 s[14:15], s[12:13], s[14:15]
	s_mov_b64 exec, s[14:15]
	s_cbranch_execz .LBB0_512
	s_mov_b64 s[14:15], 0
	s_branch .LBB0_506

; __device__ __forceinline__ int scan_wait(unsigned char* lds, const unsigned* uflag, int ready, int need, unsigned fval) {
;     ...
;     if (threadIdx.x < 64) {
;         const int lane = threadIdx.x; int r = ready;
;         for (;;) {
;             const int idx = r + lane; unsigned v = fval;
;             if (idx < 128) v = __hip_atomic_load(uflag + idx, __ATOMIC_RELAXED, __HIP_MEMORY_SCOPE_AGENT);
;             const unsigned long long notready = __ballot(v < fval);
;             const int cnt = notready ? (int)__builtin_ctzll(notready) : 64;
;             r += cnt; if (r > 128) r = 128;
;             if (r >= need) break;
;             __builtin_amdgcn_s_sleep(8);
.LBB0_506:
	v_add_u32_e32 v34, v51, v212
	v_cmp_gt_i32_e32 vcc, s46, v34
	s_mov_b64 s[18:19], 0
	s_and_saveexec_b64 s[16:17], vcc
	s_cbranch_execz .LBB0_508
	v_ashrrev_i32_e32 v35, 31, v34
	v_lshl_add_u64 v[34:35], v[34:35], 2, v[178:179]
	global_load_dword v34, v[34:35], off sc1
	s_waitcnt vmcnt(0) lgkmcnt(0)
	v_cmp_gt_u32_e32 vcc, s73, v34
	s_and_b64 s[18:19], vcc, exec

; __device__ __forceinline__ unsigned pack2(float lo, float hi) { return pg8::cvt_pk_bf16(lo, hi); }
; #define MFMA16(a, b, c) __builtin_amdgcn_mfma_f32_16x16x32_bf16((a), (b), (c), 0, 0, 0)
; #define SCAN_SB __builtin_amdgcn_sched_barrier(0)
; __device__ __forceinline__ void scan_compute(const unsigned char* B, const u32x2* ut, float eg, f32x4* Sacc, bf16x8* Sb, bf16_t* op0, int lane) {
;     const unsigned char* Bl = B + lane * 16;
;     bf16x8 fx[16], fy[8];
; #pragma unroll
;     for (int i = 0; i < 16; ++i) fx[i] = *(const bf16x8*)(Bl + i * 1024);
; #pragma unroll
;     for (int i = 0; i < 8; ++i) fy[i] = *(const bf16x8*)(Bl + 16384 + i * 1024);
;     f32x4 vn[4];
; #pragma unroll
;     for (int mt = 0; mt < 4; ++mt) { vn[mt][0] = __uint_as_float(ut[mt].x << 16); vn[mt][1] = __uint_as_float(ut[mt].x & 0xffff0000u); vn[mt][2] = __uint_as_float(ut[mt].y << 16); vn[mt][3] = __uint_as_float(ut[mt].y & 0xffff0000u); }
;     SCAN_SB;
; #pragma unroll
;     for (int ks = 0; ks < 4; ++ks)
; #pragma unroll
;         for (int mt = 0; mt < 4; ++mt) vn[mt] = MFMA16(fx[mt * 4 + ks], Sb[ks], vn[mt]);
;     SCAN_SB;
; #pragma unroll
;     for (int i = 0; i < 8; ++i) fx[i] = *(const bf16x8*)(Bl + 16384 + (8 + i) * 1024);
; #pragma unroll
;     for (int i = 0; i < 8; ++i) fx[8 + i] = *(const bf16x8*)(Bl + 49152 + i * 1024);
;     f32x4 oa[4];
; #pragma unroll
;     for (int mt = 0; mt < 4; ++mt) oa[mt] = (f32x4){0.f, 0.f, 0.f, 0.f};
;     SCAN_SB;
; #pragma unroll
;     for (int ks = 0; ks < 4; ++ks)
; #pragma unroll
;         for (int mt = 0; mt < 2; ++mt) oa[mt] = MFMA16(fy[mt * 4 + ks], Sb[ks], oa[mt]);
;     bf16x8 Vb[2];
; #pragma unroll
;     for (int ks = 0; ks < 2; ++ks) { u32x4 w; w.x = pack2(vn[2 * ks][0], vn[2 * ks][1]); w.y = pack2(vn[2 * ks][2], vn[2 * ks][3]); w.z = pack2(vn[2 * ks + 1][0], vn[2 * ks + 1][1]); w.w = pack2(vn[2 * ks + 1][2], vn[2 * ks + 1][3]);
;         Vb[ks] = __builtin_bit_cast(bf16x8, w); }
.LBB0_514:
	s_andn2_b64 vcc, exec, s[4:5]
	v_mov_b64_e32 v[104:105], v[88:89]
	v_mov_b64_e32 v[102:103], v[90:91]
	v_mov_b64_e32 v[100:101], v[92:93]
	v_mov_b64_e32 v[98:99], v[94:95]
	v_mov_b32_e32 v115, v86
	s_cbranch_vccnz .LBB0_516
	s_add_i32 s4, s21, 4
	s_mul_i32 s84, s4, 0x12000
	v_lshl_add_u64 v[34:35], v[180:181], 0, s[84:85]
	s_mov_b64 s[10:11], 0xe000
	v_lshl_add_u64 v[34:35], v[34:35], 0, s[10:11]
	v_lshl_add_u64 v[36:37], v[34:35], 0, v[56:57]
	v_lshl_add_u64 v[38:39], v[34:35], 0, v[58:59]
	v_lshl_add_u64 v[40:41], v[34:35], 0, v[60:61]
	v_lshl_add_u64 v[34:35], v[34:35], 0, v[62:63]
	global_load_dwordx2 v[98:99], v[36:37], off
	global_load_dwordx2 v[100:101], v[38:39], off
	global_load_dwordx2 v[102:103], v[40:41], off
	global_load_dwordx2 v[104:105], v[34:35], off
	v_add_u32_e32 v34, s4, v52
	v_mov_b32_e32 v35, v1
	v_lshl_add_u64 v[34:35], v[34:35], 2, s[54:55]
	global_load_dword v115, v[34:35], off
.LBB0_516:
	s_add_i32 s4, s21, 1
	s_mul_i32 s84, s4, 0x12000
	v_lshl_add_u64 v[106:107], v[180:181], 0, s[84:85]
	v_lshl_add_u64 v[106:107], v[106:107], 0, v[64:65]
	s_bitcmp1_b32 s4, 0
	v_lshl_add_u64 v[106:107], v[106:107], 0, v[0:1]
	s_cselect_b32 s5, 0xe000, 0
	v_lshl_add_u64 v[106:107], s[2:3], 1, v[106:107]
	v_mov_b32_e32 v67, v1
	v_lshl_add_u64 v[168:169], v[106:107], 0, v[66:67]
	v_add_u32_e32 v67, s5, v53
	ds_read_b128 v[106:109], v67
	ds_read_b128 v[110:113], v67 offset:1024
	ds_read_b128 v[116:119], v67 offset:2048
	ds_read_b128 v[120:123], v67 offset:3072
	ds_read_b128 v[124:127], v67 offset:4096
	ds_read_b128 v[128:131], v67 offset:5120
	ds_read_b128 v[132:135], v67 offset:6144
	ds_read_b128 v[136:139], v67 offset:7168
	ds_read_b128 v[140:143], v67 offset:8192
	ds_read_b128 v[144:147], v67 offset:9216
	ds_read_b128 v[148:151], v67 offset:10240
	ds_read_b128 v[152:155], v67 offset:11264
	ds_read_b128 v[156:159], v67 offset:12288
	ds_read_b128 v[160:163], v67 offset:13312
	ds_read_b128 v[164:167], v67 offset:14336
	ds_read_b128 v[182:185], v67 offset:15360
	ds_read_b128 v[186:189], v67 offset:16384
	ds_read_b128 v[190:193], v67 offset:17408
	ds_read_b128 v[194:197], v67 offset:18432
	ds_read_b128 v[198:201], v67 offset:19456
	ds_read_b128 v[202:205], v67 offset:20480
	ds_read_b128 v[206:209], v67 offset:21504
	ds_read_b128 v[228:231], v67 offset:22528
	ds_read_b128 v[232:235], v67 offset:23552
	v_cvt_pk_bf16_f32 v34, v18, v19
	v_cvt_pk_bf16_f32 v35, v20, v21
	v_cvt_pk_bf16_f32 v36, v14, v15
	v_cvt_pk_bf16_f32 v37, v16, v17
	v_cvt_pk_bf16_f32 v38, v6, v7
	v_cvt_pk_bf16_f32 v39, v8, v9
	v_cvt_pk_bf16_f32 v40, v2, v3
	v_cvt_pk_bf16_f32 v41, v4, v5
	v_cvt_pk_bf16_f32 v42, v10, v11
	v_cvt_pk_bf16_f32 v43, v12, v13
	v_cvt_pk_bf16_f32 v44, v22, v23
	v_cvt_pk_bf16_f32 v45, v24, v25
	v_cvt_pk_bf16_f32 v46, v30, v31
	v_cvt_pk_bf16_f32 v47, v32, v33
	v_cvt_pk_bf16_f32 v48, v26, v27
	v_cvt_pk_bf16_f32 v49, v28, v29
	s_mov_b64 s[10:11], 0xe000
	v_lshl_add_u64 v[210:211], v[168:169], 0, s[10:11]
	v_lshlrev_b32_e32 v236, 16, v94
	v_and_b32_e32 v237, 0xffff0000, v94
	v_lshlrev_b32_e32 v238, 16, v95
	v_and_b32_e32 v239, 0xffff0000, v95
	v_lshlrev_b32_e32 v240, 16, v92
	v_and_b32_e32 v241, 0xffff0000, v92
	v_lshlrev_b32_e32 v242, 16, v93
	v_and_b32_e32 v243, 0xffff0000, v93
	v_lshlrev_b32_e32 v92, 16, v90
	v_and_b32_e32 v93, 0xffff0000, v90
	v_lshlrev_b32_e32 v94, 16, v91
	v_and_b32_e32 v95, 0xffff0000, v91
	v_lshlrev_b32_e32 v244, 16, v88
	v_and_b32_e32 v245, 0xffff0000, v88
	v_lshlrev_b32_e32 v246, 16, v89
	v_and_b32_e32 v247, 0xffff0000, v89
	s_waitcnt lgkmcnt(0)
	v_mfma_f32_16x16x32_bf16 v[88:91], v[106:109], v[34:37], v[236:239]
	v_mfma_f32_16x16x32_bf16 v[106:109], v[124:127], v[34:37], v[240:243]
	v_mfma_f32_16x16x32_bf16 v[92:95], v[140:143], v[34:37], v[92:95]
	v_mfma_f32_16x16x32_bf16 v[124:127], v[156:159], v[34:37], v[244:247]
	v_mfma_f32_16x16x32_bf16 v[88:91], v[110:113], v[38:41], v[88:91]
	v_mfma_f32_16x16x32_bf16 v[106:109], v[128:131], v[38:41], v[106:109]
	v_mfma_f32_16x16x32_bf16 v[92:95], v[144:147], v[38:41], v[92:95]
	v_mfma_f32_16x16x32_bf16 v[110:113], v[160:163], v[38:41], v[124:127]
	v_mfma_f32_16x16x32_bf16 v[88:91], v[116:119], v[42:45], v[88:91]
	v_mfma_f32_16x16x32_bf16 v[106:109], v[132:135], v[42:45], v[106:109]
	v_mfma_f32_16x16x32_bf16 v[92:95], v[148:151], v[42:45], v[92:95]
	v_mfma_f32_16x16x32_bf16 v[110:113], v[164:167], v[42:45], v[110:113]
	v_mfma_f32_16x16x32_bf16 v[88:91], v[120:123], v[46:49], v[88:91]
	v_mfma_f32_16x16x32_bf16 v[106:109], v[136:139], v[46:49], v[106:109]
	v_mfma_f32_16x16x32_bf16 v[92:95], v[152:155], v[46:49], v[92:95]
	v_mfma_f32_16x16x32_bf16 v[110:113], v[182:185], v[46:49], v[110:113]
	ds_read_b128 v[116:119], v67 offset:24576
	ds_read_b128 v[120:123], v67 offset:25600
	ds_read_b128 v[124:127], v67 offset:26624
	ds_read_b128 v[128:131], v67 offset:27648
	ds_read_b128 v[132:135], v67 offset:28672
	ds_read_b128 v[136:139], v67 offset:29696
	ds_read_b128 v[140:143], v67 offset:30720
	ds_read_b128 v[144:147], v67 offset:31744
	ds_read_b128 v[148:151], v67 offset:49152
	ds_read_b128 v[152:155], v67 offset:50176
	ds_read_b128 v[156:159], v67 offset:51200
	ds_read_b128 v[160:163], v67 offset:52224
	ds_read_b128 v[164:167], v67 offset:53248
	ds_read_b128 v[182:185], v67 offset:54272
	ds_read_b128 v[236:239], v67 offset:55296
	ds_read_b128 v[240:243], v67 offset:56320
	v_mfma_f32_16x16x32_bf16 v[186:189], v[186:189], v[34:37], 0
	v_cvt_pk_bf16_f32 v88, v88, v89
	v_cvt_pk_bf16_f32 v89, v90, v91
	v_cvt_pk_bf16_f32 v90, v106, v107
	v_mfma_f32_16x16x32_bf16 v[202:205], v[202:205], v[34:37], 0
	v_cvt_pk_bf16_f32 v91, v108, v109
	v_cvt_pk_bf16_f32 v92, v92, v93
	v_cvt_pk_bf16_f32 v93, v94, v95
	v_mfma_f32_16x16x32_bf16 v[186:189], v[190:193], v[38:41], v[186:189]
	v_cvt_pk_bf16_f32 v94, v110, v111
	v_cvt_pk_bf16_f32 v95, v112, v113
	v_mfma_f32_16x16x32_bf16 v[190:193], v[206:209], v[38:41], v[202:205]
	v_mfma_f32_16x16x32_bf16 v[186:189], v[194:197], v[42:45], v[186:189]
	v_mfma_f32_16x16x32_bf16 v[190:193], v[228:231], v[42:45], v[190:193]
	v_mfma_f32_16x16x32_bf16 v[106:109], v[198:201], v[46:49], v[186:189]
	v_mfma_f32_16x16x32_bf16 v[110:113], v[232:235], v[46:49], v[190:193]
	s_nop 4
	ds_read_b128 v[186:189], v67 offset:32768
	ds_read_b128 v[190:193], v67 offset:33792
	ds_read_b128 v[194:197], v67 offset:34816
	ds_read_b128 v[198:201], v67 offset:35840
	ds_read_b128 v[202:205], v67 offset:36864
	ds_read_b128 v[206:209], v67 offset:37888
	ds_read_b128 v[228:231], v67 offset:38912
	ds_read_b128 v[232:235], v67 offset:39936
	s_waitcnt lgkmcnt(0)
; __device__ __forceinline__ unsigned pack2(float lo, float hi) { return pg8::cvt_pk_bf16(lo, hi); }
; #define MFMA16(a, b, c) __builtin_amdgcn_mfma_f32_16x16x32_bf16((a), (b), (c), 0, 0, 0)
; #define SCAN_SB __builtin_amdgcn_sched_barrier(0)
; __device__ __forceinline__ void scan_compute(const unsigned char* B, const u32x2* ut, float eg, f32x4* Sacc, bf16x8* Sb, bf16_t* op0, int lane) {
;     ...
; #pragma unroll
;     for (int ks = 0; ks < 4; ++ks)
; #pragma unroll
;         for (int mt = 2; mt < 4; ++mt) oa[mt] = MFMA16(fx[(mt - 2) * 4 + ks], Sb[ks], oa[mt]);
; #pragma unroll
;     for (int ks = 0; ks < 2; ++ks)
; #pragma unroll
;         for (int mt = 0; mt < 4; ++mt) oa[mt] = MFMA16(fx[8 + mt * 2 + ks], Vb[ks], oa[mt]);
;     SCAN_SB;
; #pragma unroll
;     for (int i = 0; i < 8; ++i) fx[i] = *(const bf16x8*)(Bl + 32768 + (8 + i) * 1024);
;     SCAN_SB;
; #pragma unroll
;     for (int m8 = 0; m8 < 4; ++m8) { f32x4 acc = Sacc[m8] * eg;
; #pragma unroll
;         for (int ks = 0; ks < 2; ++ks) acc = MFMA16(fy[m8 * 2 + ks], Vb[ks], acc);
;         Sacc[m8] = acc; }
;     SCAN_SB;
; #pragma unroll
;     for (int m8 = 4; m8 < 8; ++m8) { f32x4 acc = Sacc[m8] * eg;
; #pragma unroll
;         for (int ks = 0; ks < 2; ++ks) acc = MFMA16(fx[(m8 - 4) * 2 + ks], Vb[ks], acc);
;         Sacc[m8] = acc; }
; #pragma unroll
;     for (int mt = 0; mt < 4; ++mt) {
;         bf16_t* op = op0 + (16 * mt) * 64;
;         const unsigned p0 = pack2(oa[mt][0], oa[mt][1]), p1 = pack2(oa[mt][2], oa[mt][3]);
;         op[0] = (bf16_t)(p0 & 0xffffu); op[64] = (bf16_t)(p0 >> 16); op[128] = (bf16_t)(p1 & 0xffffu); op[192] = (bf16_t)(p1 >> 16);
;     }
; #pragma unroll
;     for (int ks = 0; ks < 4; ++ks) { u32x4 w; w.x = pack2(Sacc[2 * ks][0], Sacc[2 * ks][1]); w.y = pack2(Sacc[2 * ks][2], Sacc[2 * ks][3]); w.z = pack2(Sacc[2 * ks + 1][0], Sacc[2 * ks + 1][1]); w.w = pack2(Sacc[2 * ks + 1][2], Sacc[2 * ks + 1][3]);
;         Sb[ks] = __builtin_bit_cast(bf16x8, w); }
	v_mfma_f32_16x16x32_bf16 v[116:119], v[116:119], v[34:37], 0
	v_mfma_f32_16x16x32_bf16 v[34:37], v[132:135], v[34:37], 0
	v_mfma_f32_16x16x32_bf16 v[116:119], v[120:123], v[38:41], v[116:119]
	v_mfma_f32_16x16x32_bf16 v[34:37], v[136:139], v[38:41], v[34:37]
	v_mfma_f32_16x16x32_bf16 v[38:41], v[124:127], v[42:45], v[116:119]
	v_mfma_f32_16x16x32_bf16 v[34:37], v[140:143], v[42:45], v[34:37]
	v_mfma_f32_16x16x32_bf16 v[38:41], v[128:131], v[46:49], v[38:41]
	v_mfma_f32_16x16x32_bf16 v[34:37], v[144:147], v[46:49], v[34:37]
	v_mfma_f32_16x16x32_bf16 v[42:45], v[148:151], v[88:91], v[106:109]
	v_mfma_f32_16x16x32_bf16 v[46:49], v[156:159], v[88:91], v[110:113]
	v_mfma_f32_16x16x32_bf16 v[38:41], v[164:167], v[88:91], v[38:41]
	v_mfma_f32_16x16x32_bf16 v[34:37], v[236:239], v[88:91], v[34:37]
	v_mfma_f32_16x16x32_bf16 v[42:45], v[152:155], v[92:95], v[42:45]
	v_mfma_f32_16x16x32_bf16 v[46:49], v[160:163], v[92:95], v[46:49]
	v_mfma_f32_16x16x32_bf16 v[38:41], v[182:185], v[92:95], v[38:41]
	v_mfma_f32_16x16x32_bf16 v[34:37], v[240:243], v[92:95], v[34:37]
	ds_read_b128 v[106:109], v67 offset:40960
	ds_read_b128 v[110:113], v67 offset:41984
	ds_read_b128 v[116:119], v67 offset:43008
	ds_read_b128 v[120:123], v67 offset:44032
	ds_read_b128 v[124:127], v67 offset:45056
	ds_read_b128 v[128:131], v67 offset:46080
	ds_read_b128 v[132:135], v67 offset:47104
	ds_read_b128 v[136:139], v67 offset:48128
	v_pk_mul_f32 v[20:21], v[86:87], v[20:21] op_sel_hi:[0,1]
	v_pk_mul_f32 v[18:19], v[86:87], v[18:19] op_sel_hi:[0,1]
	v_pk_mul_f32 v[16:17], v[86:87], v[16:17] op_sel_hi:[0,1]
	v_pk_mul_f32 v[14:15], v[86:87], v[14:15] op_sel_hi:[0,1]
	v_pk_mul_f32 v[8:9], v[86:87], v[8:9] op_sel_hi:[0,1]
	v_pk_mul_f32 v[6:7], v[86:87], v[6:7] op_sel_hi:[0,1]
	v_pk_mul_f32 v[4:5], v[86:87], v[4:5] op_sel_hi:[0,1]
	v_pk_mul_f32 v[2:3], v[86:87], v[2:3] op_sel_hi:[0,1]
	v_mfma_f32_16x16x32_bf16 v[18:21], v[186:189], v[88:91], v[18:21]
	v_mfma_f32_16x16x32_bf16 v[14:17], v[194:197], v[88:91], v[14:17]
	v_mfma_f32_16x16x32_bf16 v[6:9], v[202:205], v[88:91], v[6:9]
	v_mfma_f32_16x16x32_bf16 v[2:5], v[228:231], v[88:91], v[2:5]
	v_mfma_f32_16x16x32_bf16 v[18:21], v[190:193], v[92:95], v[18:21]
	v_mfma_f32_16x16x32_bf16 v[14:17], v[198:201], v[92:95], v[14:17]
	v_mfma_f32_16x16x32_bf16 v[6:9], v[206:209], v[92:95], v[6:9]
	v_mfma_f32_16x16x32_bf16 v[2:5], v[232:235], v[92:95], v[2:5]
	v_mul_f32_e64 v24, v86, v24
	v_mul_f32_e64 v25, v86, v25
	v_pk_mul_f32 v[22:23], v[86:87], v[22:23] op_sel_hi:[0,1]
	v_pk_mul_f32 v[12:13], v[86:87], v[12:13] op_sel_hi:[0,1]
	v_pk_mul_f32 v[10:11], v[86:87], v[10:11] op_sel_hi:[0,1]
	s_waitcnt lgkmcnt(0)
	v_mfma_f32_16x16x32_bf16 v[22:25], v[116:119], v[88:91], v[22:25]
	s_mov_b32 s4, 0xe000
	v_cvt_pk_bf16_f32 v40, v40, v41
	v_cvt_pk_bf16_f32 v34, v34, v35
	v_mfma_f32_16x16x32_bf16 v[10:13], v[106:109], v[88:91], v[10:13]
	v_mul_f32_e64 v108, v86, v32
	v_mul_f32_e64 v109, v86, v33
	v_pk_mul_f32 v[106:107], v[86:87], v[30:31] op_sel_hi:[0,1]
	v_cvt_pk_bf16_f32 v35, v36, v37
	v_mfma_f32_16x16x32_bf16 v[30:33], v[120:123], v[92:95], v[22:25]
	s_cmpk_gt_u32 s21, 0x7d
	v_mfma_f32_16x16x32_bf16 v[22:25], v[124:127], v[88:91], v[106:109]
	v_mfma_f32_16x16x32_bf16 v[10:13], v[110:113], v[92:95], v[10:13]
	v_mul_f32_e64 v110, v86, v26
	v_mul_f32_e64 v111, v86, v27
	v_add_co_u32_e32 v26, vcc, s4, v168
	v_pk_mul_f32 v[112:113], v[86:87], v[28:29] op_sel_hi:[0,1]
	v_cvt_pk_bf16_f32 v28, v42, v43
	v_addc_co_u32_e32 v27, vcc, 0, v169, vcc
	v_cvt_pk_bf16_f32 v42, v44, v45
	global_store_short v[26:27], v28, off
	global_store_short_d16_hi v[210:211], v28, off offset:128
	global_store_short v[210:211], v42, off offset:256
	v_mfma_f32_16x16x32_bf16 v[26:29], v[128:131], v[92:95], v[22:25]
	global_store_short_d16_hi v[210:211], v42, off offset:384
	v_cvt_pk_bf16_f32 v42, v46, v47
	s_mov_b32 s4, 0xf000
	v_mfma_f32_16x16x32_bf16 v[22:25], v[132:135], v[88:91], v[110:113]
	v_cvt_pk_bf16_f32 v43, v48, v49
	global_store_short v[210:211], v42, off offset:2048
	global_store_short_d16_hi v[210:211], v42, off offset:2176
	global_store_short v[210:211], v43, off offset:2304
	v_cvt_pk_bf16_f32 v42, v38, v39
	v_mfma_f32_16x16x32_bf16 v[22:25], v[136:139], v[92:95], v[22:25]
	v_add_co_u32_e32 v38, vcc, s4, v168
	global_store_short_d16_hi v[210:211], v43, off offset:2432
	s_nop 0
	v_addc_co_u32_e32 v39, vcc, 0, v169, vcc
	global_store_short v[38:39], v42, off
	global_store_short_d16_hi v[38:39], v42, off offset:128
	global_store_short v[38:39], v40, off offset:256
	global_store_short_d16_hi v[38:39], v40, off offset:384
	global_store_short v[38:39], v34, off offset:2048
	global_store_short_d16_hi v[38:39], v34, off offset:2176
	global_store_short v[38:39], v35, off offset:2304
	global_store_short_d16_hi v[38:39], v35, off offset:2432
	v_cvt_pk_bf16_f32 v46, v18, v19
	v_cvt_pk_bf16_f32 v47, v20, v21
	v_cvt_pk_bf16_f32 v48, v14, v15
	v_cvt_pk_bf16_f32 v49, v16, v17
	v_cvt_pk_bf16_f32 v42, v6, v7
	v_cvt_pk_bf16_f32 v43, v8, v9
	v_cvt_pk_bf16_f32 v44, v2, v3
	v_cvt_pk_bf16_f32 v45, v4, v5
	v_cvt_pk_bf16_f32 v38, v10, v11
	v_cvt_pk_bf16_f32 v39, v12, v13
	v_cvt_pk_bf16_f32 v40, v30, v31
	v_cvt_pk_bf16_f32 v41, v32, v33
	v_cvt_pk_bf16_f32 v34, v26, v27
	v_cvt_pk_bf16_f32 v35, v28, v29
	v_cvt_pk_bf16_f32 v36, v22, v23
	v_cvt_pk_bf16_f32 v37, v24, v25
	s_waitcnt lgkmcnt(0)
	s_barrier
	s_cbranch_scc1 .LBB0_485
	s_cmpk_lt_u32 s21, 0x7b
	s_cselect_b64 s[4:5], -1, 0
	s_cmpk_gt_u32 s21, 0x7a
	s_cbranch_scc1 .LBB0_530
	s_add_i32 s9, s21, 6
	v_cmp_gt_i32_e32 vcc, s9, v51
	s_and_saveexec_b64 s[10:11], vcc
	s_cbranch_execz .LBB0_529
	s_mov_b64 s[12:13], exec
	v_readlane_b32 s14, v254, 13
	v_readlane_b32 s15, v254, 14
	s_and_b64 s[14:15], s[12:13], s[14:15]
	s_mov_b64 exec, s[14:15]
	s_cbranch_execz .LBB0_528
	s_mov_b64 s[14:15], 0
	s_branch .LBB0_522

; __device__ __forceinline__ int scan_wait(unsigned char* lds, const unsigned* uflag, int ready, int need, unsigned fval) {
;     ...
;     if (threadIdx.x < 64) {
;         const int lane = threadIdx.x; int r = ready;
;         for (;;) {
;             const int idx = r + lane; unsigned v = fval;
;             if (idx < 128) v = __hip_atomic_load(uflag + idx, __ATOMIC_RELAXED, __HIP_MEMORY_SCOPE_AGENT);
;             const unsigned long long notready = __ballot(v < fval);
;             const int cnt = notready ? (int)__builtin_ctzll(notready) : 64;
;             r += cnt; if (r > 128) r = 128;
;             if (r >= need) break;
;             __builtin_amdgcn_s_sleep(8);
.LBB0_522:
	v_add_u32_e32 v86, v51, v212
	v_cmp_gt_i32_e32 vcc, s46, v86
	s_mov_b64 s[18:19], 0
	s_and_saveexec_b64 s[16:17], vcc
	s_cbranch_execz .LBB0_524
	v_ashrrev_i32_e32 v87, 31, v86
	v_lshl_add_u64 v[86:87], v[86:87], 2, v[178:179]
	global_load_dword v67, v[86:87], off sc1
	s_waitcnt vmcnt(0) lgkmcnt(0)
	v_cmp_gt_u32_e32 vcc, s73, v67
	s_and_b64 s[18:19], vcc, exec

.LBB0_530:
	s_andn2_b64 vcc, exec, s[4:5]
	v_mov_b64_e32 v[86:87], v[70:71]
	v_mov_b64_e32 v[88:89], v[72:73]
	v_mov_b64_e32 v[90:91], v[74:75]
	v_mov_b64_e32 v[92:93], v[76:77]
	v_mov_b32_e32 v106, v68
	s_cbranch_vccnz .LBB0_484
	s_add_i32 s4, s21, 5
	s_mul_i32 s84, s4, 0x12000
	v_lshl_add_u64 v[86:87], v[180:181], 0, s[84:85]
	s_mov_b64 s[10:11], 0xe000
	v_lshl_add_u64 v[86:87], v[86:87], 0, s[10:11]
	v_lshl_add_u64 v[88:89], v[86:87], 0, v[56:57]
	v_lshl_add_u64 v[90:91], v[86:87], 0, v[58:59]
	v_lshl_add_u64 v[94:95], v[86:87], 0, v[60:61]
	v_lshl_add_u64 v[86:87], v[86:87], 0, v[62:63]
	global_load_dwordx2 v[92:93], v[88:89], off
	s_nop 0
	global_load_dwordx2 v[90:91], v[90:91], off
	s_nop 0
	global_load_dwordx2 v[88:89], v[94:95], off
	s_nop 0
	global_load_dwordx2 v[86:87], v[86:87], off
	v_add_u32_e32 v94, s4, v52
	v_mov_b32_e32 v95, v1
	v_lshl_add_u64 v[94:95], v[94:95], 2, s[54:55]
	global_load_dword v106, v[94:95], off
	s_branch .LBB0_484

; __device__ __forceinline__ int scan_wait(unsigned char* lds, const unsigned* uflag, int ready, int need, unsigned fval) {
;     ...
;     if (threadIdx.x < 64) {
;         const int lane = threadIdx.x; int r = ready;
;         for (;;) {
;             const int idx = r + lane; unsigned v = fval;
;             if (idx < 128) v = __hip_atomic_load(uflag + idx, __ATOMIC_RELAXED, __HIP_MEMORY_SCOPE_AGENT);
;             const unsigned long long notready = __ballot(v < fval);
;             const int cnt = notready ? (int)__builtin_ctzll(notready) : 64;
;             r += cnt; if (r > 128) r = 128;
;             if (r >= need) break;
;             __builtin_amdgcn_s_sleep(8);
.LBB0_538:
	v_add_u32_e32 v0, s8, v212
	v_cmp_gt_i32_e32 vcc, s46, v0
	s_mov_b64 s[6:7], 0
	s_and_saveexec_b64 s[4:5], vcc
	s_cbranch_execz .LBB0_536
	v_lshl_add_u64 v[2:3], v[0:1], 2, v[178:179]
	global_load_dword v0, v[2:3], off sc1
	s_waitcnt vmcnt(0) lgkmcnt(0)
	v_cmp_gt_u32_e32 vcc, s73, v0
	s_and_b64 s[6:7], vcc, exec
	s_branch .LBB0_536

; #define LD_LOAD(R, c) do { SCAN_WAIT(c); if ((c) < 128) { const unsigned char* uc_ = ubase + (size_t)(c) * PREP_UNIT; \
;             _Pragma("unroll") for (int i = 0; i < 14; ++i) R[i] = *(const u32x4*)(uc_ + (size_t)(lt + 256 * i) * 16); } } while (0)
; #define LD_STORE(R, c) do { if ((c) < 128) { _Pragma("unroll") for (int i = 0; i < 14; ++i) *(u32x4*)(lds + ((c) & 1) * 57344 + (size_t)(lt + 256 * i) * 16) = R[i]; } } while (0)
; __device__ __forceinline__ int scan_wait(unsigned char* lds, const unsigned* uflag, int ready, int need, unsigned fval) {
;     ...
;         if (lane == 0) *slot = r;
;     }
;     __syncthreads();
;     const int res = *slot;
;     __syncthreads();
;     return res;
; __device__ void scan_unit(unsigned char* lds, int bh, int half, unsigned char* prep, const float* egl, const unsigned* uflag  , unsigned fval) {
;     ...
;     if (wid >= 4) {
;         const int lt = tid - 256;
;         u32x4 r0[14], r1[14], r2[14];
;     ...
;         LD_LOAD(r0, 0); LD_LOAD(r1, 1); LD_LOAD(r2, 2);
;         LD_STORE(r0, 0);
.LBB0_543:
	s_or_b64 exec, exec, s[2:3]
	s_add_i32 s16, 0, 0x26404
	s_mov_b64 s[2:3], src_shared_base
	s_cmp_lg_u32 s16, -1
	s_cselect_b32 s2, s16, 0
	s_cselect_b32 s3, s3, 0
	v_ashrrev_i32_e32 v51, 31, v50
	v_mov_b32_e32 v2, s2
	v_mov_b32_e32 v3, s3
	v_lshlrev_b64 v[184:185], 4, v[50:51]
	s_mov_b64 s[2:3], 0x1000
	v_lshl_add_u64 v[186:187], v[184:185], 0, s[2:3]
	s_mov_b64 s[2:3], 0x2000
	v_lshl_add_u64 v[188:189], v[184:185], 0, s[2:3]
	s_mov_b64 s[2:3], 0x3000
	v_lshl_add_u64 v[190:191], v[184:185], 0, s[2:3]
	s_mov_b64 s[2:3], 0x4000
	v_lshl_add_u64 v[192:193], v[184:185], 0, s[2:3]
	s_mov_b64 s[2:3], 0x5000
	v_lshl_add_u64 v[194:195], v[184:185], 0, s[2:3]
	s_mov_b64 s[2:3], 0x6000
	v_lshl_add_u64 v[196:197], v[184:185], 0, s[2:3]
	s_mov_b64 s[2:3], 0x7000
	v_lshl_add_u64 v[198:199], v[184:185], 0, s[2:3]
	s_mov_b64 s[2:3], 0x8000
	v_lshl_add_u64 v[200:201], v[184:185], 0, s[2:3]
	s_mov_b64 s[2:3], 0x9000
	v_lshl_add_u64 v[202:203], v[184:185], 0, s[2:3]
	s_mov_b64 s[2:3], 0xa000
	v_add_u32_e32 v210, 0xffffff00, v50
	v_lshl_add_u64 v[204:205], v[184:185], 0, s[2:3]
	s_mov_b64 s[2:3], 0xb000
	v_ashrrev_i32_e32 v211, 31, v210
	v_lshl_add_u64 v[206:207], v[184:185], 0, s[2:3]
	s_mov_b64 s[2:3], 0xc000
	v_lshlrev_b64 v[182:183], 4, v[210:211]
	v_lshl_add_u64 v[208:209], v[184:185], 0, s[2:3]
	s_waitcnt lgkmcnt(0)
	s_barrier
	flat_load_dword v0, v[2:3] sc0 sc1
	s_waitcnt vmcnt(0)
	v_lshl_add_u64 v[2:3], v[180:181], 0, v[182:183]
	v_lshl_add_u64 v[6:7], v[180:181], 0, v[184:185]
	v_lshl_add_u64 v[10:11], v[180:181], 0, v[186:187]
	v_lshl_add_u64 v[14:15], v[180:181], 0, v[188:189]
	v_lshl_add_u64 v[18:19], v[180:181], 0, v[190:191]
	v_lshl_add_u64 v[22:23], v[180:181], 0, v[192:193]
	v_lshl_add_u64 v[26:27], v[180:181], 0, v[194:195]
	v_lshl_add_u64 v[30:31], v[180:181], 0, v[196:197]
	v_lshl_add_u64 v[34:35], v[180:181], 0, v[198:199]
	v_lshl_add_u64 v[38:39], v[180:181], 0, v[200:201]
	v_lshl_add_u64 v[42:43], v[180:181], 0, v[202:203]
	v_lshl_add_u64 v[46:47], v[180:181], 0, v[204:205]
	v_lshl_add_u64 v[50:51], v[180:181], 0, v[206:207]
	v_lshl_add_u64 v[54:55], v[180:181], 0, v[208:209]
	s_waitcnt lgkmcnt(0)
	s_barrier
	global_load_dwordx4 v[2:5], v[2:3], off
	s_nop 0
	global_load_dwordx4 v[6:9], v[6:7], off
	s_nop 0
	global_load_dwordx4 v[10:13], v[10:11], off
	s_nop 0
	global_load_dwordx4 v[14:17], v[14:15], off
	s_nop 0
	global_load_dwordx4 v[18:21], v[18:19], off
	s_nop 0
	global_load_dwordx4 v[22:25], v[22:23], off
	s_nop 0
	global_load_dwordx4 v[26:29], v[26:27], off
	s_nop 0
	global_load_dwordx4 v[30:33], v[30:31], off
	s_nop 0
	global_load_dwordx4 v[34:37], v[34:35], off
	s_nop 0
	global_load_dwordx4 v[38:41], v[38:39], off
	s_nop 0
	global_load_dwordx4 v[42:45], v[42:43], off
	s_nop 0
	global_load_dwordx4 v[46:49], v[46:47], off
	s_nop 0
	global_load_dwordx4 v[50:53], v[50:51], off
	s_nop 0
	global_load_dwordx4 v[54:57], v[54:55], off
	v_cmp_gt_i32_e32 vcc, 2, v0
	s_and_saveexec_b64 s[2:3], vcc
	s_cbranch_execz .LBB0_554
	s_mov_b64 s[4:5], exec
	v_readlane_b32 s6, v254, 13
	v_readlane_b32 s7, v254, 14
	s_and_b64 s[6:7], s[4:5], s[6:7]
	s_mov_b64 exec, s[6:7]
	s_cbranch_execz .LBB0_553
	s_mov_b64 s[6:7], 0
	s_branch .LBB0_547

; __device__ __forceinline__ int scan_wait(unsigned char* lds, const unsigned* uflag, int ready, int need, unsigned fval) {
;     ...
;     if (threadIdx.x < 64) {
;         const int lane = threadIdx.x; int r = ready;
;         for (;;) {
;             const int idx = r + lane; unsigned v = fval;
;             if (idx < 128) v = __hip_atomic_load(uflag + idx, __ATOMIC_RELAXED, __HIP_MEMORY_SCOPE_AGENT);
;             const unsigned long long notready = __ballot(v < fval);
;             const int cnt = notready ? (int)__builtin_ctzll(notready) : 64;
;             r += cnt; if (r > 128) r = 128;
;             if (r >= need) break;
;             __builtin_amdgcn_s_sleep(8);
.LBB0_547:
	v_add_u32_e32 v58, v0, v212
	v_cmp_gt_i32_e32 vcc, s46, v58
	s_mov_b64 s[10:11], 0
	s_and_saveexec_b64 s[8:9], vcc
	s_cbranch_execz .LBB0_549
	v_ashrrev_i32_e32 v59, 31, v58
	v_lshl_add_u64 v[58:59], v[58:59], 2, v[178:179]
	global_load_dword v58, v[58:59], off sc1
	s_waitcnt vmcnt(0) lgkmcnt(0)
	v_cmp_gt_u32_e32 vcc, s73, v58
	s_and_b64 s[10:11], vcc, exec

; #define LD_LOAD(R, c) do { SCAN_WAIT(c); if ((c) < 128) { const unsigned char* uc_ = ubase + (size_t)(c) * PREP_UNIT; \
;             _Pragma("unroll") for (int i = 0; i < 14; ++i) R[i] = *(const u32x4*)(uc_ + (size_t)(lt + 256 * i) * 16); } } while (0)
; __device__ void scan_unit(unsigned char* lds, int bh, int half, unsigned char* prep, const float* egl, const unsigned* uflag  , unsigned fval) {
;     ...
;         LD_LOAD(r0, 0); LD_LOAD(r1, 1); LD_LOAD(r2, 2);
.LBB0_554:
	s_or_b64 exec, exec, s[2:3]
	s_mov_b64 s[2:3], 0x12000
	v_lshl_add_u64 v[106:107], v[180:181], 0, s[2:3]
	v_lshl_add_u64 v[58:59], v[106:107], 0, v[182:183]
	v_lshl_add_u64 v[62:63], v[106:107], 0, v[184:185]
	v_lshl_add_u64 v[66:67], v[106:107], 0, v[186:187]
	v_lshl_add_u64 v[70:71], v[106:107], 0, v[188:189]
	v_lshl_add_u64 v[74:75], v[106:107], 0, v[190:191]
	v_lshl_add_u64 v[78:79], v[106:107], 0, v[192:193]
	v_lshl_add_u64 v[82:83], v[106:107], 0, v[194:195]
	v_lshl_add_u64 v[86:87], v[106:107], 0, v[196:197]
	v_lshl_add_u64 v[90:91], v[106:107], 0, v[198:199]
	v_lshl_add_u64 v[94:95], v[106:107], 0, v[200:201]
	v_lshl_add_u64 v[98:99], v[106:107], 0, v[202:203]
	v_lshl_add_u64 v[102:103], v[106:107], 0, v[204:205]
	v_lshl_add_u64 v[108:109], v[106:107], 0, v[206:207]
	v_lshl_add_u64 v[110:111], v[106:107], 0, v[208:209]
	global_load_dwordx4 v[58:61], v[58:59], off
	s_nop 0
	global_load_dwordx4 v[62:65], v[62:63], off
	s_nop 0
	global_load_dwordx4 v[66:69], v[66:67], off
	s_nop 0
	global_load_dwordx4 v[70:73], v[70:71], off
	s_nop 0
	global_load_dwordx4 v[74:77], v[74:75], off
	s_nop 0
	global_load_dwordx4 v[78:81], v[78:79], off
	s_nop 0
	global_load_dwordx4 v[82:85], v[82:83], off
	s_nop 0
	global_load_dwordx4 v[86:89], v[86:87], off
	s_nop 0
	global_load_dwordx4 v[90:93], v[90:91], off
	s_nop 0
	global_load_dwordx4 v[94:97], v[94:95], off
	s_nop 0
	global_load_dwordx4 v[98:101], v[98:99], off
	s_nop 0
	global_load_dwordx4 v[102:105], v[102:103], off
	s_nop 0
	global_load_dwordx4 v[106:109], v[108:109], off
	s_nop 0
	global_load_dwordx4 v[110:113], v[110:111], off
	v_cmp_gt_i32_e32 vcc, 3, v0
	s_and_saveexec_b64 s[2:3], vcc
	s_cbranch_execz .LBB0_565
	s_mov_b64 s[4:5], exec
	v_readlane_b32 s6, v254, 13
	v_readlane_b32 s7, v254, 14
	s_and_b64 s[6:7], s[4:5], s[6:7]
	s_mov_b64 exec, s[6:7]
	s_cbranch_execz .LBB0_564
	s_mov_b64 s[6:7], 0
	s_branch .LBB0_558

; __device__ __forceinline__ int scan_wait(unsigned char* lds, const unsigned* uflag, int ready, int need, unsigned fval) {
;     ...
;     if (threadIdx.x < 64) {
;         const int lane = threadIdx.x; int r = ready;
;         for (;;) {
;             const int idx = r + lane; unsigned v = fval;
;             if (idx < 128) v = __hip_atomic_load(uflag + idx, __ATOMIC_RELAXED, __HIP_MEMORY_SCOPE_AGENT);
;             const unsigned long long notready = __ballot(v < fval);
;             const int cnt = notready ? (int)__builtin_ctzll(notready) : 64;
;             r += cnt; if (r > 128) r = 128;
;             if (r >= need) break;
;             __builtin_amdgcn_s_sleep(8);
.LBB0_558:
	v_add_u32_e32 v114, v0, v212
	v_cmp_gt_i32_e32 vcc, s46, v114
	s_mov_b64 s[10:11], 0
	s_and_saveexec_b64 s[8:9], vcc
	s_cbranch_execz .LBB0_560
	v_ashrrev_i32_e32 v115, 31, v114
	v_lshl_add_u64 v[114:115], v[114:115], 2, v[178:179]
	global_load_dword v114, v[114:115], off sc1
	s_waitcnt vmcnt(0) lgkmcnt(0)
	v_cmp_gt_u32_e32 vcc, s73, v114
	s_and_b64 s[10:11], vcc, exec

; #define LD_LOAD(R, c) do { SCAN_WAIT(c); if ((c) < 128) { const unsigned char* uc_ = ubase + (size_t)(c) * PREP_UNIT; \
;             _Pragma("unroll") for (int i = 0; i < 14; ++i) R[i] = *(const u32x4*)(uc_ + (size_t)(lt + 256 * i) * 16); } } while (0)
; #define LD_STORE(R, c) do { if ((c) < 128) { _Pragma("unroll") for (int i = 0; i < 14; ++i) *(u32x4*)(lds + ((c) & 1) * 57344 + (size_t)(lt + 256 * i) * 16) = R[i]; } } while (0)
; __device__ void scan_unit(unsigned char* lds, int bh, int half, unsigned char* prep, const float* egl, const unsigned* uflag  , unsigned fval) {
;     ...
;         LD_LOAD(r0, 0); LD_LOAD(r1, 1); LD_LOAD(r2, 2);
;         LD_STORE(r0, 0);
;         __syncthreads();
.LBB0_565:
	s_or_b64 exec, exec, s[2:3]
	s_mov_b64 s[2:3], 0x24000
	v_lshl_add_u64 v[162:163], v[180:181], 0, s[2:3]
	v_lshl_add_u64 v[114:115], v[162:163], 0, v[182:183]
	v_lshl_add_u64 v[118:119], v[162:163], 0, v[184:185]
	v_lshl_add_u64 v[122:123], v[162:163], 0, v[186:187]
	v_lshl_add_u64 v[126:127], v[162:163], 0, v[188:189]
	v_lshl_add_u64 v[130:131], v[162:163], 0, v[190:191]
	v_lshl_add_u64 v[134:135], v[162:163], 0, v[192:193]
	v_lshl_add_u64 v[138:139], v[162:163], 0, v[194:195]
	v_lshl_add_u64 v[142:143], v[162:163], 0, v[196:197]
	v_lshl_add_u64 v[146:147], v[162:163], 0, v[198:199]
	v_lshl_add_u64 v[150:151], v[162:163], 0, v[200:201]
	v_lshl_add_u64 v[154:155], v[162:163], 0, v[202:203]
	v_lshl_add_u64 v[158:159], v[162:163], 0, v[204:205]
	v_lshl_add_u64 v[164:165], v[162:163], 0, v[206:207]
	v_lshl_add_u64 v[166:167], v[162:163], 0, v[208:209]
	global_load_dwordx4 v[114:117], v[114:115], off
	s_nop 0
	global_load_dwordx4 v[118:121], v[118:119], off
	s_nop 0
	global_load_dwordx4 v[122:125], v[122:123], off
	s_nop 0
	global_load_dwordx4 v[126:129], v[126:127], off
	s_nop 0
	global_load_dwordx4 v[130:133], v[130:131], off
	s_nop 0
	global_load_dwordx4 v[134:137], v[134:135], off
	s_nop 0
	global_load_dwordx4 v[138:141], v[138:139], off
	s_nop 0
	global_load_dwordx4 v[142:145], v[142:143], off
	s_nop 0
	global_load_dwordx4 v[146:149], v[146:147], off
	s_nop 0
	global_load_dwordx4 v[150:153], v[150:151], off
	s_nop 0
	global_load_dwordx4 v[154:157], v[154:155], off
	s_nop 0
	global_load_dwordx4 v[158:161], v[158:159], off
	s_nop 0
	global_load_dwordx4 v[162:165], v[164:165], off
	s_nop 0
	global_load_dwordx4 v[166:169], v[166:167], off
	v_lshl_add_u32 v224, v210, 4, 0
	s_mov_b32 s17, 0
	s_waitcnt vmcnt(0) lgkmcnt(0)
	ds_write_b128 v224, v[2:5]
	ds_write_b128 v224, v[6:9] offset:4096
	ds_write_b128 v224, v[10:13] offset:8192
	ds_write_b128 v224, v[14:17] offset:12288
	ds_write_b128 v224, v[18:21] offset:16384
	ds_write_b128 v224, v[22:25] offset:20480
	ds_write_b128 v224, v[26:29] offset:24576
	ds_write_b128 v224, v[30:33] offset:28672
	ds_write_b128 v224, v[34:37] offset:32768
	ds_write_b128 v224, v[38:41] offset:36864
	ds_write_b128 v224, v[42:45] offset:40960
	ds_write_b128 v224, v[46:49] offset:45056
	ds_write_b128 v224, v[50:53] offset:49152
	ds_write_b128 v224, v[54:57] offset:53248
	s_waitcnt lgkmcnt(0)
	s_barrier
	s_branch .LBB0_568

; __device__ __forceinline__ int scan_wait(unsigned char* lds, const unsigned* uflag, int ready, int need, unsigned fval) {
;     ...
;     if (threadIdx.x < 64) {
;         const int lane = threadIdx.x; int r = ready;
;         for (;;) {
;             const int idx = r + lane; unsigned v = fval;
;             if (idx < 128) v = __hip_atomic_load(uflag + idx, __ATOMIC_RELAXED, __HIP_MEMORY_SCOPE_AGENT);
;             const unsigned long long notready = __ballot(v < fval);
;             const int cnt = notready ? (int)__builtin_ctzll(notready) : 64;
;             r += cnt; if (r > 128) r = 128;
;             if (r >= need) break;
;             __builtin_amdgcn_s_sleep(8);
.LBB0_573:
	v_add_u32_e32 v210, v0, v212
	v_cmp_gt_i32_e32 vcc, s46, v210
	s_mov_b64 s[14:15], 0
	s_and_saveexec_b64 s[12:13], vcc
	s_cbranch_execz .LBB0_575
	v_ashrrev_i32_e32 v211, 31, v210
	v_lshl_add_u64 v[210:211], v[210:211], 2, v[178:179]
	global_load_dword v210, v[210:211], off sc1
	s_waitcnt vmcnt(0) lgkmcnt(0)
	v_cmp_gt_u32_e32 vcc, s73, v210
	s_and_b64 s[14:15], vcc, exec

; #define LD_LOAD(R, c) do { SCAN_WAIT(c); if ((c) < 128) { const unsigned char* uc_ = ubase + (size_t)(c) * PREP_UNIT; \
;             _Pragma("unroll") for (int i = 0; i < 14; ++i) R[i] = *(const u32x4*)(uc_ + (size_t)(lt + 256 * i) * 16); } } while (0)
; #define LD_STORE(R, c) do { if ((c) < 128) { _Pragma("unroll") for (int i = 0; i < 14; ++i) *(u32x4*)(lds + ((c) & 1) * 57344 + (size_t)(lt + 256 * i) * 16) = R[i]; } } while (0)
; #define LD_STEP(n, RL, RS) do { if ((n) < 128) { LD_LOAD(RL, (n) + 3); LD_STORE(RS, (n) + 1); __syncthreads(); } } while (0)
; __device__ void scan_unit(unsigned char* lds, int bh, int half, unsigned char* prep, const float* egl, const unsigned* uflag  , unsigned fval) {
;     ...
;         LD_LOAD(r0, 0); LD_LOAD(r1, 1); LD_LOAD(r2, 2);
;         LD_STORE(r0, 0);
;         __syncthreads();
;         for (int n = 0; n < 128; n += 3) { LD_STEP(n, r0, r1); LD_STEP(n + 1, r1, r2); LD_STEP(n + 2, r2, r0); }
.LBB0_581:
	s_andn2_b64 vcc, exec, s[4:5]
	s_cbranch_vccnz .LBB0_583
	s_mul_i32 s84, s17, 0x12000
	s_waitcnt vmcnt(0)
	v_lshl_add_u64 v[2:3], v[180:181], 0, s[84:85]
	s_mov_b64 s[4:5], 0x36000
	v_lshl_add_u64 v[50:51], v[2:3], 0, s[4:5]
	v_lshl_add_u64 v[2:3], v[50:51], 0, v[182:183]
	v_lshl_add_u64 v[6:7], v[50:51], 0, v[184:185]
	v_lshl_add_u64 v[10:11], v[50:51], 0, v[186:187]
	v_lshl_add_u64 v[14:15], v[50:51], 0, v[188:189]
	v_lshl_add_u64 v[18:19], v[50:51], 0, v[190:191]
	v_lshl_add_u64 v[22:23], v[50:51], 0, v[192:193]
	v_lshl_add_u64 v[26:27], v[50:51], 0, v[194:195]
	v_lshl_add_u64 v[30:31], v[50:51], 0, v[196:197]
	v_lshl_add_u64 v[34:35], v[50:51], 0, v[198:199]
	v_lshl_add_u64 v[38:39], v[50:51], 0, v[200:201]
	v_lshl_add_u64 v[42:43], v[50:51], 0, v[202:203]
	v_lshl_add_u64 v[46:47], v[50:51], 0, v[204:205]
	v_lshl_add_u64 v[52:53], v[50:51], 0, v[206:207]
	v_lshl_add_u64 v[54:55], v[50:51], 0, v[208:209]
	global_load_dwordx4 v[2:5], v[2:3], off
	s_nop 0
	global_load_dwordx4 v[6:9], v[6:7], off
	s_nop 0
	global_load_dwordx4 v[10:13], v[10:11], off
	s_nop 0
	global_load_dwordx4 v[14:17], v[14:15], off
	s_nop 0
	global_load_dwordx4 v[18:21], v[18:19], off
	s_nop 0
	global_load_dwordx4 v[22:25], v[22:23], off
	s_nop 0
	global_load_dwordx4 v[26:29], v[26:27], off
	s_nop 0
	global_load_dwordx4 v[30:33], v[30:31], off
	s_nop 0
	global_load_dwordx4 v[34:37], v[34:35], off
	s_nop 0
	global_load_dwordx4 v[38:41], v[38:39], off
	s_nop 0
	global_load_dwordx4 v[42:45], v[42:43], off
	s_nop 0
	global_load_dwordx4 v[46:49], v[46:47], off
	s_nop 0
	global_load_dwordx4 v[50:53], v[52:53], off
	s_nop 0
	global_load_dwordx4 v[54:57], v[54:55], off
	s_movk_i32 s84, 0x77

; #define LD_LOAD(R, c) do { SCAN_WAIT(c); if ((c) < 128) { const unsigned char* uc_ = ubase + (size_t)(c) * PREP_UNIT; \
;             _Pragma("unroll") for (int i = 0; i < 14; ++i) R[i] = *(const u32x4*)(uc_ + (size_t)(lt + 256 * i) * 16); } } while (0)
; #define LD_STORE(R, c) do { if ((c) < 128) { _Pragma("unroll") for (int i = 0; i < 14; ++i) *(u32x4*)(lds + ((c) & 1) * 57344 + (size_t)(lt + 256 * i) * 16) = R[i]; } } while (0)
; #define LD_STEP(n, RL, RS) do { if ((n) < 128) { LD_LOAD(RL, (n) + 3); LD_STORE(RS, (n) + 1); __syncthreads(); } } while (0)
; __device__ void scan_unit(unsigned char* lds, int bh, int half, unsigned char* prep, const float* egl, const unsigned* uflag  , unsigned fval) {
;     ...
;         LD_LOAD(r0, 0); LD_LOAD(r1, 1); LD_LOAD(r2, 2);
;         LD_STORE(r0, 0);
;         __syncthreads();
;         for (int n = 0; n < 128; n += 3) { LD_STEP(n, r0, r1); LD_STEP(n + 1, r1, r2); LD_STEP(n + 2, r2, r0); }
.LBB0_593:
	s_mul_i32 s84, s17, 0x12000
	v_lshl_add_u64 v[58:59], v[180:181], 0, s[84:85]
	s_mov_b64 s[4:5], 0x48000
	v_lshl_add_u64 v[106:107], v[58:59], 0, s[4:5]
	v_lshl_add_u64 v[58:59], v[106:107], 0, v[182:183]
	v_lshl_add_u64 v[62:63], v[106:107], 0, v[184:185]
	v_lshl_add_u64 v[66:67], v[106:107], 0, v[186:187]
	v_lshl_add_u64 v[70:71], v[106:107], 0, v[188:189]
	v_lshl_add_u64 v[74:75], v[106:107], 0, v[190:191]
	v_lshl_add_u64 v[78:79], v[106:107], 0, v[192:193]
	v_lshl_add_u64 v[82:83], v[106:107], 0, v[194:195]
	v_lshl_add_u64 v[86:87], v[106:107], 0, v[196:197]
	v_lshl_add_u64 v[90:91], v[106:107], 0, v[198:199]
	v_lshl_add_u64 v[94:95], v[106:107], 0, v[200:201]
	v_lshl_add_u64 v[98:99], v[106:107], 0, v[202:203]
	v_lshl_add_u64 v[102:103], v[106:107], 0, v[204:205]
	v_lshl_add_u64 v[108:109], v[106:107], 0, v[206:207]
	v_lshl_add_u64 v[110:111], v[106:107], 0, v[208:209]
	global_load_dwordx4 v[58:61], v[58:59], off
	s_nop 0
	global_load_dwordx4 v[62:65], v[62:63], off
	s_nop 0
	global_load_dwordx4 v[66:69], v[66:67], off
	s_nop 0
	global_load_dwordx4 v[70:73], v[70:71], off
	s_nop 0
	global_load_dwordx4 v[74:77], v[74:75], off
	s_nop 0
	global_load_dwordx4 v[78:81], v[78:79], off
	s_nop 0
	global_load_dwordx4 v[82:85], v[82:83], off
	s_nop 0
	global_load_dwordx4 v[86:89], v[86:87], off
	s_nop 0
	global_load_dwordx4 v[90:93], v[90:91], off
	s_nop 0
	global_load_dwordx4 v[94:97], v[94:95], off
	s_nop 0
	global_load_dwordx4 v[98:101], v[98:99], off
	s_nop 0
	global_load_dwordx4 v[102:105], v[102:103], off
	s_nop 0
	global_load_dwordx4 v[106:109], v[108:109], off
	s_nop 0
	global_load_dwordx4 v[110:113], v[110:111], off
	s_movk_i32 s84, 0x77
	s_cmpk_lt_u32 s17, 0x7e
	s_cselect_b64 s[4:5], -1, 0
	s_cmpk_gt_u32 s17, 0x7d
	s_cbranch_scc0 .LBB0_599
	s_branch .LBB0_600

; #define LD_LOAD(R, c) do { SCAN_WAIT(c); if ((c) < 128) { const unsigned char* uc_ = ubase + (size_t)(c) * PREP_UNIT; \
;             _Pragma("unroll") for (int i = 0; i < 14; ++i) R[i] = *(const u32x4*)(uc_ + (size_t)(lt + 256 * i) * 16); } } while (0)
; #define LD_STORE(R, c) do { if ((c) < 128) { _Pragma("unroll") for (int i = 0; i < 14; ++i) *(u32x4*)(lds + ((c) & 1) * 57344 + (size_t)(lt + 256 * i) * 16) = R[i]; } } while (0)
; #define LD_STEP(n, RL, RS) do { if ((n) < 128) { LD_LOAD(RL, (n) + 3); LD_STORE(RS, (n) + 1); __syncthreads(); } } while (0)
; __device__ void scan_unit(unsigned char* lds, int bh, int half, unsigned char* prep, const float* egl, const unsigned* uflag  , unsigned fval) {
;     ...
;         LD_LOAD(r0, 0); LD_LOAD(r1, 1); LD_LOAD(r2, 2);
;         LD_STORE(r0, 0);
;         __syncthreads();
;         for (int n = 0; n < 128; n += 3) { LD_STEP(n, r0, r1); LD_STEP(n + 1, r1, r2); LD_STEP(n + 2, r2, r0); }
.LBB0_611:
	s_mul_i32 s84, s17, 0x12000
	v_lshl_add_u64 v[114:115], v[180:181], 0, s[84:85]
	s_mov_b64 s[4:5], 0x5a000
	v_lshl_add_u64 v[162:163], v[114:115], 0, s[4:5]
	v_lshl_add_u64 v[114:115], v[162:163], 0, v[182:183]
	v_lshl_add_u64 v[118:119], v[162:163], 0, v[184:185]
	v_lshl_add_u64 v[122:123], v[162:163], 0, v[186:187]
	v_lshl_add_u64 v[126:127], v[162:163], 0, v[188:189]
	v_lshl_add_u64 v[130:131], v[162:163], 0, v[190:191]
	v_lshl_add_u64 v[134:135], v[162:163], 0, v[192:193]
	v_lshl_add_u64 v[138:139], v[162:163], 0, v[194:195]
	v_lshl_add_u64 v[142:143], v[162:163], 0, v[196:197]
	v_lshl_add_u64 v[146:147], v[162:163], 0, v[198:199]
	v_lshl_add_u64 v[150:151], v[162:163], 0, v[200:201]
	v_lshl_add_u64 v[154:155], v[162:163], 0, v[202:203]
	v_lshl_add_u64 v[158:159], v[162:163], 0, v[204:205]
	v_lshl_add_u64 v[164:165], v[162:163], 0, v[206:207]
	v_lshl_add_u64 v[166:167], v[162:163], 0, v[208:209]
	global_load_dwordx4 v[114:117], v[114:115], off
	s_nop 0
	global_load_dwordx4 v[118:121], v[118:119], off
	s_nop 0
	global_load_dwordx4 v[122:125], v[122:123], off
	s_nop 0
	global_load_dwordx4 v[126:129], v[126:127], off
	s_nop 0
	global_load_dwordx4 v[130:133], v[130:131], off
	s_nop 0
	global_load_dwordx4 v[134:137], v[134:135], off
	s_nop 0
	global_load_dwordx4 v[138:141], v[138:139], off
	s_nop 0
	global_load_dwordx4 v[142:145], v[142:143], off
	s_nop 0
	global_load_dwordx4 v[146:149], v[146:147], off
	s_nop 0
	global_load_dwordx4 v[150:153], v[150:151], off
	s_nop 0
	global_load_dwordx4 v[154:157], v[154:155], off
	s_nop 0
	global_load_dwordx4 v[158:161], v[158:159], off
	s_nop 0
	global_load_dwordx4 v[162:165], v[164:165], off
	s_nop 0
	global_load_dwordx4 v[166:169], v[166:167], off
	s_movk_i32 s84, 0x77
	s_cmpk_eq_i32 s17, 0x7d
	s_cbranch_scc1 .LBB0_566
	s_branch .LBB0_617

; __device__ __forceinline__ int my_tid() { int t = (int)threadIdx.x; asm volatile("" : "+v"(t)); return t; }
; __device__ void fcum_unit(unsigned char* lds, int bh, const float* scal, const float* fgb  , float* F, const bf16_t* kp  , float* knsuf  , const bf16_t* kpa  , const float* relh  , float* ab  , unsigned* flag, unsigned fval) {
;     const int tid = my_tid(), wid = tid >> 6, lane = tid & 63, b = bh >> 2, h = bh & 3;
;     float* wt = (float*)lds;
;     const float fb = fgb[h];
;     float v[16]; float run = 0.f;
; #pragma unroll
;     for (int i = 0; i < 16; ++i) { const float x = scal[((size_t)b * SEQ + tid * 16 + i) * 16 + h] + fb; run += fminf(x, 0.f) - log1pf(__expf(-fabsf(x))); v[i] = run; }
.LBB0_620:
	s_andn2_saveexec_b64 s[2:3], s[4:5]
	s_cbranch_execz .LBB0_172
	s_waitcnt vmcnt(0)
	v_and_b32_e32 v25, 3, v90
	v_readlane_b32 s0, v255, 43
	v_lshlrev_b32_e32 v0, 2, v25
	v_readlane_b32 s1, v255, 44
	v_mov_b32_e32 v2, v212
	v_ashrrev_i32_e32 v4, 2, v90
	v_lshl_add_u64 v[6:7], s[0:1], 0, v[0:1]
	global_load_dword v3, v[6:7], off
	v_readlane_b32 s0, v255, 37
	v_ashrrev_i32_e32 v5, 31, v4
	v_lshlrev_b32_e32 v6, 4, v2
	v_readlane_b32 s1, v255, 38
	v_ashrrev_i32_e32 v7, 31, v6
	v_lshlrev_b64 v[10:11], 19, v[4:5]
	v_lshl_add_u64 v[8:9], s[0:1], 0, v[0:1]
	v_lshlrev_b64 v[12:13], 6, v[6:7]
	v_lshl_add_u64 v[8:9], v[8:9], 0, v[10:11]
	v_lshl_add_u64 v[8:9], v[8:9], 0, v[12:13]
	global_load_dword v10, v[8:9], off
	global_load_dword v11, v[8:9], off offset:64
	global_load_dword v0, v[8:9], off offset:128
	global_load_dword v5, v[8:9], off offset:192
	global_load_dword v12, v[8:9], off offset:256
	global_load_dword v14, v[8:9], off offset:320
	global_load_dword v15, v[8:9], off offset:384
	global_load_dword v16, v[8:9], off offset:448
	s_mov_b32 s0, 0xbfb8aa3b
	s_mov_b32 s1, 0x3f2aaaab
	s_mov_b32 s4, 0x3f317218
	s_mov_b32 s5, 0x7f800000
	s_mov_b32 s6, 0x33800000
	s_waitcnt vmcnt(0) lgkmcnt(0)
	v_add_f32_e32 v10, v3, v10
	v_add_f32_e32 v11, v3, v11
	v_mul_f32_e64 v13, |v10|, s0
	v_mul_f32_e64 v17, |v11|, s0
	v_exp_f32_e32 v13, v13
	v_exp_f32_e32 v17, v17
	v_min_f32_e32 v20, 0, v10
	v_min_f32_e32 v21, 0, v11
	v_add_f32_e32 v22, 1.0, v13
	v_add_f32_e32 v23, 1.0, v17
	v_add_f32_e32 v24, -1.0, v22
	v_frexp_mant_f32_e32 v26, v22
	v_cvt_f64_f32_e32 v[10:11], v22
	v_cvt_f64_f32_e32 v[18:19], v23
	v_sub_f32_e32 v29, v24, v22
	v_frexp_exp_i32_f64_e32 v10, v[10:11]
	v_cmp_gt_f32_e32 vcc, s1, v26
	v_sub_f32_e32 v24, v13, v24
	v_frexp_exp_i32_f64_e32 v18, v[18:19]
	v_add_f32_e32 v19, 1.0, v29
	v_subbrev_co_u32_e32 v10, vcc, 0, v10, vcc
	v_add_f32_e32 v27, -1.0, v23
	v_add_f32_e32 v19, v24, v19
	v_sub_u32_e32 v24, 0, v10
	v_sub_f32_e32 v11, v27, v23
	v_cvt_f32_i32_e32 v10, v10
	v_ldexp_f32 v22, v22, v24
	v_frexp_mant_f32_e32 v28, v23
	v_sub_f32_e32 v27, v17, v27
	v_add_f32_e32 v11, 1.0, v11
	v_ldexp_f32 v19, v19, v24
	v_add_f32_e32 v24, -1.0, v22
	v_add_f32_e32 v26, 1.0, v22
	v_cmp_gt_f32_e32 vcc, s1, v28
	v_add_f32_e32 v11, v27, v11
	v_add_f32_e32 v27, 1.0, v24
	v_add_f32_e32 v28, -1.0, v26
	v_sub_f32_e32 v27, v22, v27
	v_sub_f32_e32 v22, v22, v28
	v_mul_f32_e32 v28, 0x3f317218, v10
	v_add_f32_e32 v27, v19, v27
	v_add_f32_e32 v19, v19, v22
	v_fma_f32 v22, v10, s4, -v28
	v_add_f32_e32 v29, v24, v27
	v_add_f32_e32 v30, v26, v19
	v_fmac_f32_e32 v22, 0xb102e308, v10
	v_sub_f32_e32 v10, v29, v24
	v_sub_f32_e32 v24, v30, v26
	v_rcp_f32_e32 v26, v30
	v_add_f32_e32 v31, v28, v22
	v_sub_f32_e32 v19, v19, v24
	v_sub_f32_e32 v24, v31, v28
	v_sub_f32_e32 v22, v22, v24
	v_mul_f32_e32 v24, v29, v26
	v_sub_f32_e32 v10, v27, v10
	v_mul_f32_e32 v27, v30, v24
	v_fma_f32 v28, v24, v30, -v27
	v_fmac_f32_e32 v28, v24, v19
	v_add_f32_e32 v32, v27, v28
	v_sub_f32_e32 v33, v29, v32
	v_sub_f32_e32 v27, v32, v27
	v_sub_f32_e32 v29, v29, v33
	v_sub_f32_e32 v27, v27, v28
	v_sub_f32_e32 v28, v29, v32
	v_add_f32_e32 v10, v10, v28
	v_add_f32_e32 v10, v27, v10
	v_add_f32_e32 v27, v33, v10
	v_mul_f32_e32 v28, v26, v27
	v_sub_f32_e32 v29, v33, v27
	v_mul_f32_e32 v32, v30, v28
	v_add_f32_e32 v10, v10, v29
	v_add_f32_e32 v29, v24, v28
	v_fma_f32 v30, v28, v30, -v32
	v_sub_f32_e32 v24, v29, v24
	v_fmac_f32_e32 v30, v28, v19
	v_sub_f32_e32 v19, v28, v24
	v_add_f32_e32 v24, v32, v30
	v_sub_f32_e32 v28, v24, v32
	v_sub_f32_e32 v32, v27, v24
	v_sub_f32_e32 v27, v27, v32
	v_sub_f32_e32 v24, v27, v24
	v_sub_f32_e32 v28, v28, v30
	v_add_f32_e32 v10, v10, v24
	v_add_f32_e32 v10, v28, v10
	v_add_f32_e32 v10, v32, v10
	v_mul_f32_e32 v10, v26, v10
	v_add_f32_e32 v10, v19, v10
	v_add_f32_e32 v19, v29, v10
	v_mul_f32_e32 v24, v19, v19
	v_fmamk_f32 v28, v24, 0x3e9b6dac, v216
	v_sub_f32_e32 v26, v19, v29
	v_ldexp_f32 v27, v19, 1
	v_mul_f32_e32 v19, v19, v24
	v_fmaak_f32 v24, v24, v28, 0x3f2aaada
	v_mul_f32_e32 v19, v19, v24
	v_add_f32_e32 v24, v27, v19
	v_sub_f32_e32 v10, v10, v26
	v_sub_f32_e32 v26, v24, v27
	v_ldexp_f32 v10, v10, 1
	v_sub_f32_e32 v19, v19, v26
	v_add_f32_e32 v10, v10, v19
	v_add_f32_e32 v19, v24, v10
	v_sub_f32_e32 v24, v19, v24
	v_add_f32_e32 v26, v31, v19
	v_sub_f32_e32 v10, v10, v24
	v_sub_f32_e32 v24, v26, v31
	v_sub_f32_e32 v27, v26, v24
	v_sub_f32_e32 v19, v19, v24
	v_add_f32_e32 v24, v22, v10
	v_sub_f32_e32 v27, v31, v27
	v_sub_f32_e32 v28, v24, v22
	v_add_f32_e32 v19, v19, v27
	v_sub_f32_e32 v27, v24, v28
	v_sub_f32_e32 v10, v10, v28
	v_sub_f32_e32 v22, v22, v27
	v_add_f32_e32 v19, v24, v19
	v_add_f32_e32 v10, v10, v22
	v_add_f32_e32 v22, v26, v19
	v_sub_f32_e32 v24, v22, v26
	v_sub_f32_e32 v19, v19, v24
	v_subbrev_co_u32_e32 v18, vcc, 0, v18, vcc
	v_add_f32_e32 v10, v10, v19
	v_add_f32_e32 v10, v22, v10
	v_cmp_neq_f32_e32 vcc, s5, v13
	v_add_f32_e32 v0, v3, v0
	v_add_f32_e32 v5, v3, v5
	v_cndmask_b32_e32 v10, v220, v10, vcc
	v_cmp_ngt_f32_e32 vcc, -1.0, v13
	v_add_f32_e32 v14, v3, v14
	v_add_f32_e32 v16, v3, v16
	v_cndmask_b32_e32 v10, v221, v10, vcc
	v_cmp_neq_f32_e32 vcc, -1.0, v13
	s_nop 1
	v_cndmask_b32_e32 v10, v222, v10, vcc
	v_cmp_lt_f32_e64 vcc, |v13|, s6
	s_nop 1
	v_cndmask_b32_e32 v10, v10, v13, vcc
	v_sub_u32_e32 v13, 0, v18
	v_ldexp_f32 v19, v23, v13
	v_ldexp_f32 v11, v11, v13
	v_add_f32_e32 v13, -1.0, v19
	v_add_f32_e32 v23, 1.0, v19
	v_sub_f32_e32 v10, v20, v10
	v_add_f32_e32 v20, 1.0, v13
	v_add_f32_e32 v24, -1.0, v23
	v_sub_f32_e32 v20, v19, v20
	v_sub_f32_e32 v19, v19, v24
	v_add_f32_e32 v20, v11, v20
	v_add_f32_e32 v11, v11, v19
	v_add_f32_e32 v19, v23, v11
; __device__ void fcum_unit(unsigned char* lds, int bh, const float* scal, const float* fgb  , float* F, const bf16_t* kp  , float* knsuf  , const bf16_t* kpa  , const float* relh  , float* ab  , unsigned* flag, unsigned fval) {
;     ...
;     float v[16]; float run = 0.f;
; #pragma unroll
;     for (int i = 0; i < 16; ++i) { const float x = scal[((size_t)b * SEQ + tid * 16 + i) * 16 + h] + fb; run += fminf(x, 0.f) - log1pf(__expf(-fabsf(x))); v[i] = run; }
	v_rcp_f32_e32 v24, v19
	v_add_f32_e32 v22, v13, v20
	v_sub_f32_e32 v13, v22, v13
	v_sub_f32_e32 v13, v20, v13
	v_sub_f32_e32 v20, v19, v23
	v_sub_f32_e32 v11, v11, v20
	v_mul_f32_e32 v20, v22, v24
	v_mul_f32_e32 v23, v19, v20
	v_fma_f32 v26, v20, v19, -v23
	v_fmac_f32_e32 v26, v20, v11
	v_add_f32_e32 v27, v23, v26
	v_sub_f32_e32 v28, v22, v27
	v_sub_f32_e32 v22, v22, v28
	v_sub_f32_e32 v23, v27, v23
	v_sub_f32_e32 v22, v22, v27
	v_add_f32_e32 v13, v13, v22
	v_sub_f32_e32 v22, v23, v26
	v_add_f32_e32 v13, v22, v13
	v_add_f32_e32 v22, v28, v13
	v_mul_f32_e32 v23, v24, v22
	v_mul_f32_e32 v26, v19, v23
	v_fma_f32 v19, v23, v19, -v26
	v_fmac_f32_e32 v19, v23, v11
	v_sub_f32_e32 v11, v28, v22
	v_add_f32_e32 v11, v13, v11
	v_add_f32_e32 v13, v26, v19
	v_sub_f32_e32 v27, v22, v13
	v_sub_f32_e32 v22, v22, v27
	v_sub_f32_e32 v26, v13, v26
	v_sub_f32_e32 v13, v22, v13
	v_add_f32_e32 v11, v11, v13
	v_sub_f32_e32 v13, v26, v19
	v_cvt_f32_i32_e32 v18, v18
	v_add_f32_e32 v11, v13, v11
	v_add_f32_e32 v13, v20, v23
	v_add_f32_e32 v11, v27, v11
	v_sub_f32_e32 v19, v13, v20
	v_mul_f32_e32 v11, v24, v11
	v_sub_f32_e32 v19, v23, v19
	v_add_f32_e32 v11, v19, v11
	v_mul_f32_e32 v23, 0x3f317218, v18
	v_add_f32_e32 v19, v13, v11
	v_fma_f32 v24, v18, s4, -v23
	v_mul_f32_e32 v20, v19, v19
	v_fmac_f32_e32 v24, 0xb102e308, v18
	v_sub_f32_e32 v13, v19, v13
	v_fmamk_f32 v22, v20, 0x3e9b6dac, v216
	v_sub_f32_e32 v11, v11, v13
	v_add_f32_e32 v13, v23, v24
	v_fmaak_f32 v22, v20, v22, 0x3f2aaada
	v_sub_f32_e32 v18, v13, v23
	v_ldexp_f32 v23, v19, 1
	v_mul_f32_e32 v19, v19, v20
	v_mul_f32_e32 v19, v19, v22
	v_add_f32_e32 v20, v23, v19
	v_sub_f32_e32 v22, v20, v23
	v_ldexp_f32 v11, v11, 1
	v_sub_f32_e32 v19, v19, v22
	v_add_f32_e32 v11, v11, v19
	v_add_f32_e32 v19, v20, v11
	v_sub_f32_e32 v20, v19, v20
	v_sub_f32_e32 v11, v11, v20
	v_add_f32_e32 v20, v13, v19
	v_sub_f32_e32 v22, v20, v13
	v_sub_f32_e32 v23, v20, v22
	v_sub_f32_e32 v18, v24, v18
	v_sub_f32_e32 v13, v13, v23
	v_sub_f32_e32 v19, v19, v22
	v_add_f32_e32 v13, v19, v13
	v_add_f32_e32 v19, v18, v11
	v_sub_f32_e32 v22, v19, v18
	v_sub_f32_e32 v23, v19, v22
	v_sub_f32_e32 v18, v18, v23
	v_sub_f32_e32 v11, v11, v22
	v_add_f32_e32 v13, v19, v13
	v_add_f32_e32 v11, v11, v18
	v_add_f32_e32 v18, v20, v13
	v_sub_f32_e32 v19, v18, v20
	v_sub_f32_e32 v13, v13, v19
	v_add_f32_e32 v11, v11, v13
	v_mul_f32_e64 v13, |v0|, s0
	v_add_f32_e32 v11, v18, v11
	v_cmp_neq_f32_e32 vcc, s5, v17
	v_exp_f32_e32 v13, v13
	v_min_f32_e32 v0, 0, v0
	v_cndmask_b32_e32 v11, v220, v11, vcc
	v_cmp_ngt_f32_e32 vcc, -1.0, v17
	v_add_f32_e32 v10, 0, v10
	s_nop 0
	v_cndmask_b32_e32 v11, v221, v11, vcc
	v_cmp_neq_f32_e32 vcc, -1.0, v17
	s_nop 1
	v_cndmask_b32_e32 v11, v222, v11, vcc
	v_cmp_lt_f32_e64 vcc, |v17|, s6
	s_nop 1
	v_cndmask_b32_e32 v11, v11, v17, vcc
	v_add_f32_e32 v17, 1.0, v13
	v_add_f32_e32 v18, -1.0, v17
	v_sub_f32_e32 v19, v18, v17
	v_add_f32_e32 v19, 1.0, v19
	v_sub_f32_e32 v18, v13, v18
	v_sub_f32_e32 v11, v21, v11
	v_add_f32_e32 v20, v18, v19
	v_frexp_mant_f32_e32 v21, v17
	v_cvt_f64_f32_e32 v[18:19], v17
	v_frexp_exp_i32_f64_e32 v18, v[18:19]
	v_cmp_gt_f32_e32 vcc, s1, v21
	v_add_f32_e32 v11, v10, v11
	s_nop 0
	v_subbrev_co_u32_e32 v18, vcc, 0, v18, vcc
	v_sub_u32_e32 v19, 0, v18
	v_ldexp_f32 v17, v17, v19
	v_ldexp_f32 v19, v20, v19
	v_add_f32_e32 v20, -1.0, v17
	v_add_f32_e32 v23, 1.0, v17
	v_add_f32_e32 v21, 1.0, v20
	v_add_f32_e32 v24, -1.0, v23
	v_sub_f32_e32 v21, v17, v21
	v_sub_f32_e32 v17, v17, v24
	v_add_f32_e32 v17, v19, v17
	v_add_f32_e32 v21, v19, v21
	v_add_f32_e32 v19, v23, v17
	v_rcp_f32_e32 v24, v19
	v_add_f32_e32 v22, v20, v21
	v_sub_f32_e32 v20, v22, v20
	v_sub_f32_e32 v20, v21, v20
	v_sub_f32_e32 v21, v19, v23
	v_sub_f32_e32 v17, v17, v21
	v_mul_f32_e32 v21, v22, v24
	v_mul_f32_e32 v23, v19, v21
	v_fma_f32 v26, v21, v19, -v23
	v_fmac_f32_e32 v26, v21, v17
	v_add_f32_e32 v27, v23, v26
	v_sub_f32_e32 v28, v22, v27
	v_sub_f32_e32 v22, v22, v28
	v_sub_f32_e32 v23, v27, v23
	v_sub_f32_e32 v22, v22, v27
	v_add_f32_e32 v20, v20, v22
	v_sub_f32_e32 v22, v23, v26
	v_add_f32_e32 v20, v22, v20
	v_add_f32_e32 v22, v28, v20
	v_mul_f32_e32 v23, v24, v22
	v_mul_f32_e32 v26, v19, v23
	v_fma_f32 v19, v23, v19, -v26
	v_fmac_f32_e32 v19, v23, v17
	v_sub_f32_e32 v17, v28, v22
	v_add_f32_e32 v17, v20, v17
	v_add_f32_e32 v20, v26, v19
	v_sub_f32_e32 v27, v22, v20
	v_sub_f32_e32 v22, v22, v27
	v_sub_f32_e32 v26, v20, v26
	v_sub_f32_e32 v20, v22, v20
	v_add_f32_e32 v17, v17, v20
	v_sub_f32_e32 v19, v26, v19
	v_cvt_f32_i32_e32 v18, v18
	v_add_f32_e32 v17, v19, v17
	v_add_f32_e32 v19, v21, v23
	v_add_f32_e32 v17, v27, v17
	v_sub_f32_e32 v20, v19, v21
	v_mul_f32_e32 v17, v24, v17
	v_sub_f32_e32 v20, v23, v20
	v_add_f32_e32 v17, v20, v17
	v_mul_f32_e32 v23, 0x3f317218, v18
	v_add_f32_e32 v20, v19, v17
	v_fma_f32 v24, v18, s4, -v23
	v_mul_f32_e32 v21, v20, v20
	v_fmac_f32_e32 v24, 0xb102e308, v18
	v_sub_f32_e32 v18, v20, v19
	v_fmamk_f32 v22, v21, 0x3e9b6dac, v216
	v_sub_f32_e32 v17, v17, v18
	v_add_f32_e32 v18, v23, v24
	v_fmaak_f32 v22, v21, v22, 0x3f2aaada
	v_sub_f32_e32 v19, v18, v23
	v_ldexp_f32 v23, v20, 1
	v_mul_f32_e32 v20, v20, v21
	v_mul_f32_e32 v20, v20, v22
	v_add_f32_e32 v21, v23, v20
	v_sub_f32_e32 v22, v21, v23
	v_ldexp_f32 v17, v17, 1
	v_sub_f32_e32 v20, v20, v22
	v_add_f32_e32 v17, v17, v20
	v_add_f32_e32 v20, v21, v17
	v_sub_f32_e32 v21, v20, v21
	v_sub_f32_e32 v17, v17, v21
	v_add_f32_e32 v21, v18, v20
	v_sub_f32_e32 v22, v21, v18
	v_sub_f32_e32 v23, v21, v22
	v_sub_f32_e32 v19, v24, v19
	v_sub_f32_e32 v18, v18, v23
	v_sub_f32_e32 v20, v20, v22
	v_add_f32_e32 v18, v20, v18
	v_add_f32_e32 v20, v19, v17
	v_sub_f32_e32 v22, v20, v19
; __device__ void fcum_unit(unsigned char* lds, int bh, const float* scal, const float* fgb  , float* F, const bf16_t* kp  , float* knsuf  , const bf16_t* kpa  , const float* relh  , float* ab  , unsigned* flag, unsigned fval) {
;     ...
;     float v[16]; float run = 0.f;
; #pragma unroll
;     for (int i = 0; i < 16; ++i) { const float x = scal[((size_t)b * SEQ + tid * 16 + i) * 16 + h] + fb; run += fminf(x, 0.f) - log1pf(__expf(-fabsf(x))); v[i] = run; }
	v_sub_f32_e32 v23, v20, v22
	v_sub_f32_e32 v19, v19, v23
	v_sub_f32_e32 v17, v17, v22
	v_add_f32_e32 v18, v20, v18
	v_add_f32_e32 v17, v17, v19
	v_add_f32_e32 v19, v21, v18
	v_sub_f32_e32 v20, v19, v21
	v_sub_f32_e32 v18, v18, v20
	v_add_f32_e32 v17, v17, v18
	v_add_f32_e32 v17, v19, v17
	v_cmp_neq_f32_e32 vcc, s5, v13
	v_mul_f32_e64 v18, |v5|, s0
	v_exp_f32_e32 v20, v18
	v_cndmask_b32_e32 v17, v220, v17, vcc
	v_cmp_ngt_f32_e32 vcc, -1.0, v13
	v_min_f32_e32 v5, 0, v5
	s_nop 0
	v_cndmask_b32_e32 v17, v221, v17, vcc
	v_cmp_neq_f32_e32 vcc, -1.0, v13
	s_nop 1
	v_cndmask_b32_e32 v17, v222, v17, vcc
	v_cmp_lt_f32_e64 vcc, |v13|, s6
	s_nop 1
	v_cndmask_b32_e32 v13, v17, v13, vcc
	v_sub_f32_e32 v0, v0, v13
	v_add_f32_e32 v13, 1.0, v20
	v_add_f32_e32 v17, -1.0, v13
	v_sub_f32_e32 v18, v17, v13
	v_add_f32_e32 v18, 1.0, v18
	v_sub_f32_e32 v17, v20, v17
	v_add_f32_e32 v17, v17, v18
	v_frexp_mant_f32_e32 v21, v13
	v_cvt_f64_f32_e32 v[18:19], v13
	v_frexp_exp_i32_f64_e32 v18, v[18:19]
	v_cmp_gt_f32_e32 vcc, s1, v21
	s_nop 1
	v_subbrev_co_u32_e32 v18, vcc, 0, v18, vcc
	v_sub_u32_e32 v19, 0, v18
	v_ldexp_f32 v13, v13, v19
	v_ldexp_f32 v17, v17, v19
	v_add_f32_e32 v19, -1.0, v13
	v_add_f32_e32 v23, 1.0, v13
	v_add_f32_e32 v21, 1.0, v19
	v_add_f32_e32 v24, -1.0, v23
	v_sub_f32_e32 v21, v13, v21
	v_sub_f32_e32 v13, v13, v24
	v_add_f32_e32 v13, v17, v13
	v_add_f32_e32 v21, v17, v21
	v_add_f32_e32 v17, v23, v13
	v_rcp_f32_e32 v24, v17
	v_add_f32_e32 v22, v19, v21
	v_sub_f32_e32 v19, v22, v19
	v_sub_f32_e32 v19, v21, v19
	v_sub_f32_e32 v21, v17, v23
	v_sub_f32_e32 v13, v13, v21
	v_mul_f32_e32 v21, v22, v24
	v_mul_f32_e32 v23, v17, v21
	v_fma_f32 v26, v21, v17, -v23
	v_fmac_f32_e32 v26, v21, v13
	v_add_f32_e32 v27, v23, v26
	v_sub_f32_e32 v28, v22, v27
	v_sub_f32_e32 v22, v22, v28
	v_sub_f32_e32 v23, v27, v23
	v_sub_f32_e32 v22, v22, v27
	v_add_f32_e32 v19, v19, v22
	v_sub_f32_e32 v22, v23, v26
	v_add_f32_e32 v19, v22, v19
	v_add_f32_e32 v22, v28, v19
	v_mul_f32_e32 v23, v24, v22
	v_mul_f32_e32 v26, v17, v23
	v_fma_f32 v17, v23, v17, -v26
	v_fmac_f32_e32 v17, v23, v13
	v_sub_f32_e32 v13, v28, v22
	v_add_f32_e32 v13, v19, v13
	v_add_f32_e32 v19, v26, v17
	v_sub_f32_e32 v27, v22, v19
	v_sub_f32_e32 v22, v22, v27
	v_sub_f32_e32 v26, v19, v26
	v_sub_f32_e32 v19, v22, v19
	v_add_f32_e32 v13, v13, v19
	v_sub_f32_e32 v17, v26, v17
	v_cvt_f32_i32_e32 v18, v18
	v_add_f32_e32 v13, v17, v13
	v_add_f32_e32 v17, v21, v23
	v_add_f32_e32 v13, v27, v13
	v_sub_f32_e32 v19, v17, v21
	v_mul_f32_e32 v13, v24, v13
	v_sub_f32_e32 v19, v23, v19
	v_add_f32_e32 v13, v19, v13
	v_mul_f32_e32 v23, 0x3f317218, v18
	v_add_f32_e32 v19, v17, v13
	v_fma_f32 v24, v18, s4, -v23
	v_mul_f32_e32 v21, v19, v19
	v_fmac_f32_e32 v24, 0xb102e308, v18
	v_sub_f32_e32 v17, v19, v17
	v_fmamk_f32 v22, v21, 0x3e9b6dac, v216
	v_sub_f32_e32 v13, v13, v17
	v_add_f32_e32 v17, v23, v24
	v_fmaak_f32 v22, v21, v22, 0x3f2aaada
	v_sub_f32_e32 v18, v17, v23
	v_ldexp_f32 v23, v19, 1
	v_mul_f32_e32 v19, v19, v21
	v_mul_f32_e32 v19, v19, v22
	v_add_f32_e32 v21, v23, v19
	v_sub_f32_e32 v22, v21, v23
	v_ldexp_f32 v13, v13, 1
	v_sub_f32_e32 v19, v19, v22
	v_add_f32_e32 v13, v13, v19
	v_add_f32_e32 v19, v21, v13
	v_sub_f32_e32 v21, v19, v21
	v_sub_f32_e32 v13, v13, v21
	v_add_f32_e32 v21, v17, v19
	v_sub_f32_e32 v22, v21, v17
	v_sub_f32_e32 v23, v21, v22
	v_sub_f32_e32 v18, v24, v18
	v_sub_f32_e32 v17, v17, v23
	v_sub_f32_e32 v19, v19, v22
	v_add_f32_e32 v17, v19, v17
	v_add_f32_e32 v19, v18, v13
	v_sub_f32_e32 v22, v19, v18
	v_sub_f32_e32 v23, v19, v22
	v_sub_f32_e32 v18, v18, v23
	v_sub_f32_e32 v13, v13, v22
	v_add_f32_e32 v17, v19, v17
	v_add_f32_e32 v13, v13, v18
	v_add_f32_e32 v18, v21, v17
	v_sub_f32_e32 v19, v18, v21
	v_sub_f32_e32 v17, v17, v19
	v_add_f32_e32 v13, v13, v17
	v_add_f32_e32 v13, v18, v13
	v_cmp_neq_f32_e32 vcc, s5, v20
	v_add_f32_e32 v17, v3, v12
	v_mul_f32_e64 v12, |v17|, s0
	v_cndmask_b32_e32 v13, v220, v13, vcc
	v_cmp_ngt_f32_e32 vcc, -1.0, v20
	s_nop 1
	v_cndmask_b32_e32 v13, v221, v13, vcc
	v_cmp_neq_f32_e32 vcc, -1.0, v20
	s_nop 1
	v_cndmask_b32_e32 v13, v222, v13, vcc
	v_cmp_lt_f32_e64 vcc, |v20|, s6
	s_nop 1
	v_cndmask_b32_e32 v13, v13, v20, vcc
	v_exp_f32_e32 v20, v12
	v_sub_f32_e32 v5, v5, v13
	v_add_f32_e32 v12, v11, v0
	v_add_f32_e32 v13, v12, v5
	v_add_f32_e32 v5, 1.0, v20
	v_min_f32_e32 v0, 0, v17
	v_add_f32_e32 v17, -1.0, v5
	v_sub_f32_e32 v18, v17, v5
	v_add_f32_e32 v18, 1.0, v18
	v_sub_f32_e32 v17, v20, v17
	v_add_f32_e32 v17, v17, v18
	v_frexp_mant_f32_e32 v21, v5
	v_cvt_f64_f32_e32 v[18:19], v5
	v_frexp_exp_i32_f64_e32 v18, v[18:19]
	v_cmp_gt_f32_e32 vcc, s1, v21
	s_nop 1
	v_subbrev_co_u32_e32 v18, vcc, 0, v18, vcc
	v_sub_u32_e32 v19, 0, v18
	v_ldexp_f32 v5, v5, v19
	v_ldexp_f32 v17, v17, v19
	v_add_f32_e32 v19, -1.0, v5
	v_add_f32_e32 v23, 1.0, v5
	v_add_f32_e32 v21, 1.0, v19
	v_add_f32_e32 v24, -1.0, v23
	v_sub_f32_e32 v21, v5, v21
	v_sub_f32_e32 v5, v5, v24
	v_add_f32_e32 v5, v17, v5
	v_add_f32_e32 v21, v17, v21
	v_add_f32_e32 v17, v23, v5
	v_rcp_f32_e32 v24, v17
	v_add_f32_e32 v22, v19, v21
	v_sub_f32_e32 v19, v22, v19
	v_sub_f32_e32 v19, v21, v19
	v_sub_f32_e32 v21, v17, v23
	v_sub_f32_e32 v5, v5, v21
	v_mul_f32_e32 v21, v22, v24
	v_mul_f32_e32 v23, v17, v21
	v_fma_f32 v26, v21, v17, -v23
	v_fmac_f32_e32 v26, v21, v5
	v_add_f32_e32 v27, v23, v26
	v_sub_f32_e32 v28, v22, v27
	v_sub_f32_e32 v22, v22, v28
	v_sub_f32_e32 v23, v27, v23
	v_sub_f32_e32 v22, v22, v27
	v_add_f32_e32 v19, v19, v22
	v_sub_f32_e32 v22, v23, v26
	v_add_f32_e32 v19, v22, v19
	v_add_f32_e32 v22, v28, v19
	v_mul_f32_e32 v23, v24, v22
	v_mul_f32_e32 v26, v17, v23
	v_fma_f32 v17, v23, v17, -v26
; __device__ void fcum_unit(unsigned char* lds, int bh, const float* scal, const float* fgb  , float* F, const bf16_t* kp  , float* knsuf  , const bf16_t* kpa  , const float* relh  , float* ab  , unsigned* flag, unsigned fval) {
;     ...
;     float v[16]; float run = 0.f;
; #pragma unroll
;     for (int i = 0; i < 16; ++i) { const float x = scal[((size_t)b * SEQ + tid * 16 + i) * 16 + h] + fb; run += fminf(x, 0.f) - log1pf(__expf(-fabsf(x))); v[i] = run; }
	v_fmac_f32_e32 v17, v23, v5
	v_sub_f32_e32 v5, v28, v22
	v_add_f32_e32 v5, v19, v5
	v_add_f32_e32 v19, v26, v17
	v_sub_f32_e32 v27, v22, v19
	v_sub_f32_e32 v22, v22, v27
	v_sub_f32_e32 v26, v19, v26
	v_sub_f32_e32 v19, v22, v19
	v_add_f32_e32 v5, v5, v19
	v_sub_f32_e32 v17, v26, v17
	v_cvt_f32_i32_e32 v18, v18
	v_add_f32_e32 v5, v17, v5
	v_add_f32_e32 v17, v21, v23
	v_add_f32_e32 v5, v27, v5
	v_sub_f32_e32 v19, v17, v21
	v_mul_f32_e32 v5, v24, v5
	v_sub_f32_e32 v19, v23, v19
	v_add_f32_e32 v5, v19, v5
	v_mul_f32_e32 v23, 0x3f317218, v18
	v_add_f32_e32 v19, v17, v5
	v_fma_f32 v24, v18, s4, -v23
	v_mul_f32_e32 v21, v19, v19
	v_fmac_f32_e32 v24, 0xb102e308, v18
	v_sub_f32_e32 v17, v19, v17
	v_fmamk_f32 v22, v21, 0x3e9b6dac, v216
	v_sub_f32_e32 v5, v5, v17
	v_add_f32_e32 v17, v23, v24
	v_fmaak_f32 v22, v21, v22, 0x3f2aaada
	v_sub_f32_e32 v18, v17, v23
	v_ldexp_f32 v23, v19, 1
	v_mul_f32_e32 v19, v19, v21
	v_mul_f32_e32 v19, v19, v22
	v_add_f32_e32 v21, v23, v19
	v_sub_f32_e32 v22, v21, v23
	v_ldexp_f32 v5, v5, 1
	v_sub_f32_e32 v19, v19, v22
	v_add_f32_e32 v5, v5, v19
	v_add_f32_e32 v19, v21, v5
	v_sub_f32_e32 v21, v19, v21
	v_sub_f32_e32 v5, v5, v21
	v_add_f32_e32 v21, v17, v19
	v_sub_f32_e32 v22, v21, v17
	v_sub_f32_e32 v23, v21, v22
	v_sub_f32_e32 v18, v24, v18
	v_sub_f32_e32 v17, v17, v23
	v_sub_f32_e32 v19, v19, v22
	v_add_f32_e32 v17, v19, v17
	v_add_f32_e32 v19, v18, v5
	v_sub_f32_e32 v22, v19, v18
	v_sub_f32_e32 v23, v19, v22
	v_sub_f32_e32 v18, v18, v23
	v_sub_f32_e32 v5, v5, v22
	v_add_f32_e32 v17, v19, v17
	v_add_f32_e32 v5, v5, v18
	v_add_f32_e32 v18, v21, v17
	v_sub_f32_e32 v19, v18, v21
	v_sub_f32_e32 v17, v17, v19
	v_add_f32_e32 v5, v5, v17
	v_add_f32_e32 v5, v18, v5
	v_cmp_neq_f32_e32 vcc, s5, v20
	v_mul_f32_e64 v17, |v14|, s0
	v_exp_f32_e32 v17, v17
	v_cndmask_b32_e32 v5, v220, v5, vcc
	v_cmp_ngt_f32_e32 vcc, -1.0, v20
	s_nop 1
	v_cndmask_b32_e32 v5, v221, v5, vcc
	v_cmp_neq_f32_e32 vcc, -1.0, v20
	s_nop 1
	v_cndmask_b32_e32 v5, v222, v5, vcc
	v_cmp_lt_f32_e64 vcc, |v20|, s6
	s_nop 1
	v_cndmask_b32_e32 v5, v5, v20, vcc
	v_sub_f32_e32 v0, v0, v5
	v_min_f32_e32 v5, 0, v14
	v_add_f32_e32 v14, 1.0, v17
	v_add_f32_e32 v18, -1.0, v14
	v_sub_f32_e32 v19, v18, v14
	v_add_f32_e32 v19, 1.0, v19
	v_sub_f32_e32 v18, v17, v18
	v_add_f32_e32 v20, v18, v19
	v_frexp_mant_f32_e32 v21, v14
	v_cvt_f64_f32_e32 v[18:19], v14
	v_frexp_exp_i32_f64_e32 v18, v[18:19]
	v_cmp_gt_f32_e32 vcc, s1, v21
	s_nop 1
	v_subbrev_co_u32_e32 v18, vcc, 0, v18, vcc
	v_sub_u32_e32 v19, 0, v18
	v_ldexp_f32 v14, v14, v19
	v_ldexp_f32 v19, v20, v19
	v_add_f32_e32 v20, -1.0, v14
	v_add_f32_e32 v23, 1.0, v14
	v_add_f32_e32 v21, 1.0, v20
	v_add_f32_e32 v24, -1.0, v23
	v_sub_f32_e32 v21, v14, v21
	v_sub_f32_e32 v14, v14, v24
	v_add_f32_e32 v14, v19, v14
	v_add_f32_e32 v21, v19, v21
	v_add_f32_e32 v19, v23, v14
	v_rcp_f32_e32 v24, v19
	v_add_f32_e32 v22, v20, v21
	v_sub_f32_e32 v20, v22, v20
	v_sub_f32_e32 v20, v21, v20
	v_sub_f32_e32 v21, v19, v23
	v_sub_f32_e32 v14, v14, v21
	v_mul_f32_e32 v21, v22, v24
	v_mul_f32_e32 v23, v19, v21
	v_fma_f32 v26, v21, v19, -v23
	v_fmac_f32_e32 v26, v21, v14
	v_add_f32_e32 v27, v23, v26
	v_sub_f32_e32 v28, v22, v27
	v_sub_f32_e32 v22, v22, v28
	v_sub_f32_e32 v23, v27, v23
	v_sub_f32_e32 v22, v22, v27
	v_add_f32_e32 v20, v20, v22
	v_sub_f32_e32 v22, v23, v26
	v_add_f32_e32 v20, v22, v20
	v_add_f32_e32 v22, v28, v20
	v_mul_f32_e32 v23, v24, v22
	v_mul_f32_e32 v26, v19, v23
	v_fma_f32 v19, v23, v19, -v26
	v_fmac_f32_e32 v19, v23, v14
	v_sub_f32_e32 v14, v28, v22
	v_add_f32_e32 v14, v20, v14
	v_add_f32_e32 v20, v26, v19
	v_sub_f32_e32 v27, v22, v20
	v_sub_f32_e32 v22, v22, v27
	v_sub_f32_e32 v26, v20, v26
	v_sub_f32_e32 v20, v22, v20
	v_add_f32_e32 v14, v14, v20
	v_sub_f32_e32 v19, v26, v19
	v_cvt_f32_i32_e32 v18, v18
	v_add_f32_e32 v14, v19, v14
	v_add_f32_e32 v19, v21, v23
	v_add_f32_e32 v14, v27, v14
	v_sub_f32_e32 v20, v19, v21
	v_mul_f32_e32 v14, v24, v14
	v_sub_f32_e32 v20, v23, v20
	v_add_f32_e32 v14, v20, v14
	v_mul_f32_e32 v23, 0x3f317218, v18
	v_add_f32_e32 v20, v19, v14
	v_fma_f32 v24, v18, s4, -v23
	v_mul_f32_e32 v21, v20, v20
	v_fmac_f32_e32 v24, 0xb102e308, v18
	v_sub_f32_e32 v18, v20, v19
	v_fmamk_f32 v22, v21, 0x3e9b6dac, v216
	v_sub_f32_e32 v14, v14, v18
	v_add_f32_e32 v18, v23, v24
	v_fmaak_f32 v22, v21, v22, 0x3f2aaada
	v_sub_f32_e32 v19, v18, v23
	v_ldexp_f32 v23, v20, 1
	v_mul_f32_e32 v20, v20, v21
	v_mul_f32_e32 v20, v20, v22
	v_add_f32_e32 v21, v23, v20
	v_sub_f32_e32 v22, v21, v23
	v_ldexp_f32 v14, v14, 1
	v_sub_f32_e32 v20, v20, v22
	v_add_f32_e32 v14, v14, v20
	v_add_f32_e32 v20, v21, v14
	v_sub_f32_e32 v21, v20, v21
	v_sub_f32_e32 v14, v14, v21
	v_add_f32_e32 v21, v18, v20
	v_sub_f32_e32 v22, v21, v18
	v_sub_f32_e32 v23, v21, v22
	v_sub_f32_e32 v19, v24, v19
	v_sub_f32_e32 v18, v18, v23
	v_sub_f32_e32 v20, v20, v22
	v_add_f32_e32 v18, v20, v18
	v_add_f32_e32 v20, v19, v14
	v_sub_f32_e32 v22, v20, v19
	v_sub_f32_e32 v23, v20, v22
	v_sub_f32_e32 v19, v19, v23
	v_sub_f32_e32 v14, v14, v22
	v_add_f32_e32 v18, v20, v18
	v_add_f32_e32 v14, v14, v19
	v_add_f32_e32 v19, v21, v18
	v_sub_f32_e32 v20, v19, v21
	v_sub_f32_e32 v18, v18, v20
	v_add_f32_e32 v14, v14, v18
	v_add_f32_e32 v14, v19, v14
	v_cmp_neq_f32_e32 vcc, s5, v17
	s_nop 1
	v_cndmask_b32_e32 v14, v220, v14, vcc
	v_cmp_ngt_f32_e32 vcc, -1.0, v17
	s_nop 1
	v_cndmask_b32_e32 v14, v221, v14, vcc
	v_cmp_neq_f32_e32 vcc, -1.0, v17
	s_nop 1
	v_cndmask_b32_e32 v14, v222, v14, vcc
	v_cmp_lt_f32_e64 vcc, |v17|, s6
	s_nop 1
	v_cndmask_b32_e32 v14, v14, v17, vcc
	v_add_f32_e32 v17, v3, v15
	v_sub_f32_e32 v5, v5, v14
	v_mul_f32_e64 v14, |v17|, s0
	v_exp_f32_e32 v20, v14
; __device__ void fcum_unit(unsigned char* lds, int bh, const float* scal, const float* fgb  , float* F, const bf16_t* kp  , float* knsuf  , const bf16_t* kpa  , const float* relh  , float* ab  , unsigned* flag, unsigned fval) {
;     ...
;     float v[16]; float run = 0.f;
; #pragma unroll
;     for (int i = 0; i < 16; ++i) { const float x = scal[((size_t)b * SEQ + tid * 16 + i) * 16 + h] + fb; run += fminf(x, 0.f) - log1pf(__expf(-fabsf(x))); v[i] = run; }
	v_add_f32_e32 v14, v13, v0
	v_add_f32_e32 v15, v14, v5
	v_min_f32_e32 v0, 0, v17
	v_add_f32_e32 v5, 1.0, v20
	v_add_f32_e32 v17, -1.0, v5
	v_sub_f32_e32 v18, v17, v5
	v_add_f32_e32 v18, 1.0, v18
	v_sub_f32_e32 v17, v20, v17
	v_add_f32_e32 v17, v17, v18
	v_frexp_mant_f32_e32 v21, v5
	v_cvt_f64_f32_e32 v[18:19], v5
	v_frexp_exp_i32_f64_e32 v18, v[18:19]
	v_cmp_gt_f32_e32 vcc, s1, v21
	s_nop 1
	v_subbrev_co_u32_e32 v18, vcc, 0, v18, vcc
	v_sub_u32_e32 v19, 0, v18
	v_ldexp_f32 v5, v5, v19
	v_ldexp_f32 v17, v17, v19
	v_add_f32_e32 v19, -1.0, v5
	v_add_f32_e32 v23, 1.0, v5
	v_add_f32_e32 v21, 1.0, v19
	v_add_f32_e32 v24, -1.0, v23
	v_sub_f32_e32 v21, v5, v21
	v_sub_f32_e32 v5, v5, v24
	v_add_f32_e32 v5, v17, v5
	v_add_f32_e32 v21, v17, v21
	v_add_f32_e32 v17, v23, v5
	v_rcp_f32_e32 v24, v17
	v_add_f32_e32 v22, v19, v21
	v_sub_f32_e32 v19, v22, v19
	v_sub_f32_e32 v19, v21, v19
	v_sub_f32_e32 v21, v17, v23
	v_sub_f32_e32 v5, v5, v21
	v_mul_f32_e32 v21, v22, v24
	v_mul_f32_e32 v23, v17, v21
	v_fma_f32 v26, v21, v17, -v23
	v_fmac_f32_e32 v26, v21, v5
	v_add_f32_e32 v27, v23, v26
	v_sub_f32_e32 v28, v22, v27
	v_sub_f32_e32 v22, v22, v28
	v_sub_f32_e32 v23, v27, v23
	v_sub_f32_e32 v22, v22, v27
	v_add_f32_e32 v19, v19, v22
	v_sub_f32_e32 v22, v23, v26
	v_add_f32_e32 v19, v22, v19
	v_add_f32_e32 v22, v28, v19
	v_mul_f32_e32 v23, v24, v22
	v_mul_f32_e32 v26, v17, v23
	v_fma_f32 v17, v23, v17, -v26
	v_fmac_f32_e32 v17, v23, v5
	v_sub_f32_e32 v5, v28, v22
	v_add_f32_e32 v5, v19, v5
	v_add_f32_e32 v19, v26, v17
	v_sub_f32_e32 v27, v22, v19
	v_sub_f32_e32 v22, v22, v27
	v_sub_f32_e32 v26, v19, v26
	v_sub_f32_e32 v19, v22, v19
	v_add_f32_e32 v5, v5, v19
	v_sub_f32_e32 v17, v26, v17
	v_cvt_f32_i32_e32 v18, v18
	v_add_f32_e32 v5, v17, v5
	v_add_f32_e32 v17, v21, v23
	v_add_f32_e32 v5, v27, v5
	v_sub_f32_e32 v19, v17, v21
	v_mul_f32_e32 v5, v24, v5
	v_sub_f32_e32 v19, v23, v19
	v_add_f32_e32 v5, v19, v5
	v_mul_f32_e32 v23, 0x3f317218, v18
	v_add_f32_e32 v19, v17, v5
	v_fma_f32 v24, v18, s4, -v23
	v_mul_f32_e32 v21, v19, v19
	v_fmac_f32_e32 v24, 0xb102e308, v18
	v_sub_f32_e32 v17, v19, v17
	v_fmamk_f32 v22, v21, 0x3e9b6dac, v216
	v_sub_f32_e32 v5, v5, v17
	v_add_f32_e32 v17, v23, v24
	v_fmaak_f32 v22, v21, v22, 0x3f2aaada
	v_sub_f32_e32 v18, v17, v23
	v_ldexp_f32 v23, v19, 1
	v_mul_f32_e32 v19, v19, v21
	v_mul_f32_e32 v19, v19, v22
	v_add_f32_e32 v21, v23, v19
	v_sub_f32_e32 v22, v21, v23
	v_ldexp_f32 v5, v5, 1
	v_sub_f32_e32 v19, v19, v22
	v_add_f32_e32 v5, v5, v19
	v_add_f32_e32 v19, v21, v5
	v_sub_f32_e32 v21, v19, v21
	v_sub_f32_e32 v5, v5, v21
	v_add_f32_e32 v21, v17, v19
	v_sub_f32_e32 v22, v21, v17
	v_sub_f32_e32 v23, v21, v22
	v_sub_f32_e32 v18, v24, v18
	v_sub_f32_e32 v17, v17, v23
	v_sub_f32_e32 v19, v19, v22
	v_add_f32_e32 v17, v19, v17
	v_add_f32_e32 v19, v18, v5
	v_sub_f32_e32 v22, v19, v18
	v_sub_f32_e32 v23, v19, v22
	v_sub_f32_e32 v18, v18, v23
	v_sub_f32_e32 v5, v5, v22
	v_add_f32_e32 v17, v19, v17
	v_add_f32_e32 v5, v5, v18
	v_add_f32_e32 v18, v21, v17
	v_sub_f32_e32 v19, v18, v21
	v_sub_f32_e32 v17, v17, v19
	v_add_f32_e32 v5, v5, v17
	v_add_f32_e32 v5, v18, v5
	v_cmp_neq_f32_e32 vcc, s5, v20
	v_mul_f32_e64 v17, |v16|, s0
	v_exp_f32_e32 v18, v17
	v_cndmask_b32_e32 v5, v220, v5, vcc
	v_cmp_ngt_f32_e32 vcc, -1.0, v20
	v_min_f32_e32 v19, 0, v16
	s_nop 0
	v_cndmask_b32_e32 v5, v221, v5, vcc
	v_cmp_neq_f32_e32 vcc, -1.0, v20
	s_nop 1
	v_cndmask_b32_e32 v5, v222, v5, vcc
	v_cmp_lt_f32_e64 vcc, |v20|, s6
	s_nop 1
	v_cndmask_b32_e32 v5, v5, v20, vcc
	v_sub_f32_e32 v0, v0, v5
	v_add_f32_e32 v5, 1.0, v18
	v_add_f32_e32 v16, -1.0, v5
	v_sub_f32_e32 v17, v16, v5
	v_add_f32_e32 v17, 1.0, v17
	v_sub_f32_e32 v16, v18, v16
	v_add_f32_e32 v20, v16, v17
	v_frexp_mant_f32_e32 v21, v5
	v_cvt_f64_f32_e32 v[16:17], v5
	v_frexp_exp_i32_f64_e32 v16, v[16:17]
	v_cmp_gt_f32_e32 vcc, s1, v21
	s_nop 1
	v_subbrev_co_u32_e32 v16, vcc, 0, v16, vcc
	v_sub_u32_e32 v17, 0, v16
	v_ldexp_f32 v5, v5, v17
	v_ldexp_f32 v17, v20, v17
	v_add_f32_e32 v20, -1.0, v5
	v_add_f32_e32 v23, 1.0, v5
	v_add_f32_e32 v21, 1.0, v20
	v_add_f32_e32 v24, -1.0, v23
	v_sub_f32_e32 v21, v5, v21
	v_sub_f32_e32 v5, v5, v24
	v_add_f32_e32 v5, v17, v5
	v_add_f32_e32 v21, v17, v21
	v_add_f32_e32 v17, v23, v5
	v_rcp_f32_e32 v24, v17
	v_add_f32_e32 v22, v20, v21
	v_sub_f32_e32 v20, v22, v20
	v_sub_f32_e32 v20, v21, v20
	v_sub_f32_e32 v21, v17, v23
	v_mul_f32_e32 v23, v22, v24
	v_sub_f32_e32 v21, v5, v21
	v_mul_f32_e32 v5, v17, v23
	v_fma_f32 v26, v23, v17, -v5
	v_fmac_f32_e32 v26, v23, v21
	v_add_f32_e32 v27, v5, v26
	v_sub_f32_e32 v28, v22, v27
	v_sub_f32_e32 v22, v22, v28
	v_sub_f32_e32 v5, v27, v5
	v_sub_f32_e32 v22, v22, v27
	v_add_f32_e32 v20, v20, v22
	v_sub_f32_e32 v5, v5, v26
	v_add_f32_e32 v20, v5, v20
	global_load_dword v5, v[8:9], off offset:512
	v_add_f32_e32 v22, v28, v20
	v_mul_f32_e32 v26, v24, v22
	v_mul_f32_e32 v27, v17, v26
	v_fma_f32 v17, v26, v17, -v27
	v_fmac_f32_e32 v17, v26, v21
	v_sub_f32_e32 v21, v28, v22
	v_add_f32_e32 v20, v20, v21
	v_add_f32_e32 v21, v27, v17
	v_sub_f32_e32 v28, v22, v21
	v_sub_f32_e32 v22, v22, v28
	v_sub_f32_e32 v27, v21, v27
	v_sub_f32_e32 v21, v22, v21
	v_add_f32_e32 v20, v20, v21
	v_sub_f32_e32 v17, v27, v17
	v_cvt_f32_i32_e32 v16, v16
	v_add_f32_e32 v17, v17, v20
	v_add_f32_e32 v20, v23, v26
	v_add_f32_e32 v17, v28, v17
	v_sub_f32_e32 v21, v20, v23
	v_mul_f32_e32 v17, v24, v17
	v_sub_f32_e32 v21, v26, v21
	v_add_f32_e32 v17, v21, v17
	v_mul_f32_e32 v24, 0x3f317218, v16
	v_add_f32_e32 v21, v20, v17
	v_fma_f32 v26, v16, s4, -v24
	v_mul_f32_e32 v22, v21, v21
	v_fmac_f32_e32 v26, 0xb102e308, v16
	v_sub_f32_e32 v16, v21, v20
	v_fmamk_f32 v23, v22, 0x3e9b6dac, v216
	v_sub_f32_e32 v16, v17, v16
	v_add_f32_e32 v17, v24, v26
	v_fmaak_f32 v23, v22, v23, 0x3f2aaada
	v_sub_f32_e32 v20, v17, v24
	v_ldexp_f32 v24, v21, 1
	v_mul_f32_e32 v21, v21, v22
	v_mul_f32_e32 v21, v21, v23
	v_add_f32_e32 v22, v24, v21
	v_sub_f32_e32 v23, v22, v24
	v_ldexp_f32 v16, v16, 1
	v_sub_f32_e32 v21, v21, v23
	v_add_f32_e32 v16, v16, v21
	v_add_f32_e32 v21, v22, v16
	v_sub_f32_e32 v22, v21, v22
	v_sub_f32_e32 v16, v16, v22
	v_add_f32_e32 v22, v17, v21
	v_sub_f32_e32 v23, v22, v17
	v_sub_f32_e32 v24, v22, v23
	v_sub_f32_e32 v20, v26, v20
	v_sub_f32_e32 v17, v17, v24
	v_sub_f32_e32 v21, v21, v23
	v_add_f32_e32 v17, v21, v17
	v_add_f32_e32 v21, v20, v16
	v_sub_f32_e32 v23, v21, v20
	v_sub_f32_e32 v24, v21, v23
	v_sub_f32_e32 v20, v20, v24
	v_sub_f32_e32 v16, v16, v23
	v_add_f32_e32 v17, v21, v17
	v_add_f32_e32 v16, v16, v20
	v_add_f32_e32 v20, v22, v17
	v_sub_f32_e32 v21, v20, v22
	v_sub_f32_e32 v17, v17, v21
	v_add_f32_e32 v16, v16, v17
	v_add_f32_e32 v16, v20, v16
	v_cmp_neq_f32_e32 vcc, s5, v18
	s_waitcnt vmcnt(0) lgkmcnt(0)
; __device__ void fcum_unit(unsigned char* lds, int bh, const float* scal, const float* fgb  , float* F, const bf16_t* kp  , float* knsuf  , const bf16_t* kpa  , const float* relh  , float* ab  , unsigned* flag, unsigned fval) {
;     ...
;     float v[16]; float run = 0.f;
; #pragma unroll
;     for (int i = 0; i < 16; ++i) { const float x = scal[((size_t)b * SEQ + tid * 16 + i) * 16 + h] + fb; run += fminf(x, 0.f) - log1pf(__expf(-fabsf(x))); v[i] = run; }
	v_add_f32_e32 v5, v3, v5
	v_cndmask_b32_e32 v16, v220, v16, vcc
	v_cmp_ngt_f32_e32 vcc, -1.0, v18
	s_nop 1
	v_cndmask_b32_e32 v16, v221, v16, vcc
	v_cmp_neq_f32_e32 vcc, -1.0, v18
	s_nop 1
	v_cndmask_b32_e32 v16, v222, v16, vcc
	v_cmp_lt_f32_e64 vcc, |v18|, s6
	s_nop 1
	v_cndmask_b32_e32 v16, v16, v18, vcc
	v_sub_f32_e32 v16, v19, v16
	global_load_dword v17, v[8:9], off offset:576
	global_load_dword v18, v[8:9], off offset:640
	global_load_dword v19, v[8:9], off offset:704
	global_load_dword v20, v[8:9], off offset:768
	global_load_dword v21, v[8:9], off offset:832
	global_load_dword v22, v[8:9], off offset:896
	global_load_dword v23, v[8:9], off offset:960
	v_mul_f32_e64 v8, |v5|, s0
	v_exp_f32_e32 v24, v8
	v_add_f32_e32 v8, v15, v0
	v_min_f32_e32 v0, 0, v5
	v_add_f32_e32 v9, v8, v16
	v_add_f32_e32 v5, 1.0, v24
	v_add_f32_e32 v16, -1.0, v5
	v_sub_f32_e32 v26, v16, v5
	v_add_f32_e32 v26, 1.0, v26
	v_sub_f32_e32 v16, v24, v16
	v_add_f32_e32 v16, v16, v26
	v_frexp_mant_f32_e32 v28, v5
	v_cvt_f64_f32_e32 v[26:27], v5
	v_frexp_exp_i32_f64_e32 v26, v[26:27]
	v_cmp_gt_f32_e32 vcc, s1, v28
	s_waitcnt vmcnt(0) lgkmcnt(0)
	v_add_f32_e32 v18, v3, v18
	v_subbrev_co_u32_e32 v26, vcc, 0, v26, vcc
	v_sub_u32_e32 v27, 0, v26
	v_ldexp_f32 v5, v5, v27
	v_ldexp_f32 v16, v16, v27
	v_add_f32_e32 v27, -1.0, v5
	v_add_f32_e32 v30, 1.0, v5
	v_add_f32_e32 v28, 1.0, v27
	v_add_f32_e32 v31, -1.0, v30
	v_sub_f32_e32 v28, v5, v28
	v_sub_f32_e32 v5, v5, v31
	v_add_f32_e32 v5, v16, v5
	v_add_f32_e32 v28, v16, v28
	v_add_f32_e32 v16, v30, v5
	v_rcp_f32_e32 v31, v16
	v_add_f32_e32 v29, v27, v28
	v_sub_f32_e32 v27, v29, v27
	v_sub_f32_e32 v27, v28, v27
	v_sub_f32_e32 v28, v16, v30
	v_sub_f32_e32 v5, v5, v28
	v_mul_f32_e32 v28, v29, v31
	v_mul_f32_e32 v30, v16, v28
	v_fma_f32 v32, v28, v16, -v30
	v_fmac_f32_e32 v32, v28, v5
	v_add_f32_e32 v33, v30, v32
	v_sub_f32_e32 v34, v29, v33
	v_sub_f32_e32 v29, v29, v34
	v_sub_f32_e32 v30, v33, v30
	v_sub_f32_e32 v29, v29, v33
	v_add_f32_e32 v27, v27, v29
	v_sub_f32_e32 v29, v30, v32
	v_add_f32_e32 v27, v29, v27
	v_add_f32_e32 v29, v34, v27
	v_mul_f32_e32 v30, v31, v29
	v_mul_f32_e32 v32, v16, v30
	v_fma_f32 v16, v30, v16, -v32
	v_fmac_f32_e32 v16, v30, v5
	v_sub_f32_e32 v5, v34, v29
	v_add_f32_e32 v5, v27, v5
	v_add_f32_e32 v27, v32, v16
	v_sub_f32_e32 v33, v29, v27
	v_sub_f32_e32 v29, v29, v33
	v_sub_f32_e32 v32, v27, v32
	v_sub_f32_e32 v27, v29, v27
	v_add_f32_e32 v5, v5, v27
	v_sub_f32_e32 v16, v32, v16
	v_cvt_f32_i32_e32 v26, v26
	v_add_f32_e32 v5, v16, v5
	v_add_f32_e32 v16, v28, v30
	v_add_f32_e32 v5, v33, v5
	v_sub_f32_e32 v27, v16, v28
	v_mul_f32_e32 v5, v31, v5
	v_sub_f32_e32 v27, v30, v27
	v_add_f32_e32 v5, v27, v5
	v_mul_f32_e32 v30, 0x3f317218, v26
	v_add_f32_e32 v27, v16, v5
	v_fma_f32 v31, v26, s4, -v30
	v_mul_f32_e32 v28, v27, v27
	v_fmac_f32_e32 v31, 0xb102e308, v26
	v_sub_f32_e32 v16, v27, v16
	v_fmamk_f32 v29, v28, 0x3e9b6dac, v216
	v_sub_f32_e32 v5, v5, v16
	v_add_f32_e32 v16, v30, v31
	v_fmaak_f32 v29, v28, v29, 0x3f2aaada
	v_sub_f32_e32 v26, v16, v30
	v_ldexp_f32 v30, v27, 1
	v_mul_f32_e32 v27, v27, v28
	v_mul_f32_e32 v27, v27, v29
	v_add_f32_e32 v28, v30, v27
	v_sub_f32_e32 v29, v28, v30
	v_ldexp_f32 v5, v5, 1
	v_sub_f32_e32 v27, v27, v29
	v_add_f32_e32 v5, v5, v27
	v_add_f32_e32 v27, v28, v5
	v_sub_f32_e32 v28, v27, v28
	v_sub_f32_e32 v5, v5, v28
	v_add_f32_e32 v28, v16, v27
	v_sub_f32_e32 v29, v28, v16
	v_sub_f32_e32 v30, v28, v29
	v_sub_f32_e32 v26, v31, v26
	v_sub_f32_e32 v16, v16, v30
	v_sub_f32_e32 v27, v27, v29
	v_add_f32_e32 v16, v27, v16
	v_add_f32_e32 v27, v26, v5
	v_sub_f32_e32 v29, v27, v26
	v_sub_f32_e32 v30, v27, v29
	v_sub_f32_e32 v26, v26, v30
	v_sub_f32_e32 v5, v5, v29
	v_add_f32_e32 v16, v27, v16
	v_add_f32_e32 v5, v5, v26
	v_add_f32_e32 v26, v28, v16
	v_sub_f32_e32 v27, v26, v28
	v_sub_f32_e32 v16, v16, v27
	v_add_f32_e32 v5, v5, v16
	v_add_f32_e32 v16, v3, v17
	v_mul_f32_e64 v17, |v16|, s0
	v_add_f32_e32 v5, v26, v5
	v_cmp_neq_f32_e32 vcc, s5, v24
	v_exp_f32_e32 v26, v17
	v_add_f32_e32 v20, v3, v20
	v_cndmask_b32_e32 v5, v220, v5, vcc
	v_cmp_ngt_f32_e32 vcc, -1.0, v24
	v_add_f32_e32 v22, v3, v22
	s_nop 0
	v_cndmask_b32_e32 v5, v221, v5, vcc
	v_cmp_neq_f32_e32 vcc, -1.0, v24
	s_nop 1
	v_cndmask_b32_e32 v5, v222, v5, vcc
	v_cmp_lt_f32_e64 vcc, |v24|, s6
	s_nop 1
	v_cndmask_b32_e32 v5, v5, v24, vcc
	v_add_f32_e32 v24, 1.0, v26
	v_sub_f32_e32 v0, v0, v5
	v_min_f32_e32 v5, 0, v16
	v_add_f32_e32 v16, -1.0, v24
	v_sub_f32_e32 v17, v16, v24
	v_add_f32_e32 v17, 1.0, v17
	v_sub_f32_e32 v16, v26, v16
	v_add_f32_e32 v27, v16, v17
	v_frexp_mant_f32_e32 v28, v24
	v_cvt_f64_f32_e32 v[16:17], v24
	v_frexp_exp_i32_f64_e32 v16, v[16:17]
	v_cmp_gt_f32_e32 vcc, s1, v28
	s_nop 1
	v_subbrev_co_u32_e32 v16, vcc, 0, v16, vcc
	v_sub_u32_e32 v17, 0, v16
	v_ldexp_f32 v24, v24, v17
	v_ldexp_f32 v17, v27, v17
	v_add_f32_e32 v27, -1.0, v24
	v_add_f32_e32 v30, 1.0, v24
	v_add_f32_e32 v28, 1.0, v27
	v_add_f32_e32 v31, -1.0, v30
	v_sub_f32_e32 v28, v24, v28
	v_sub_f32_e32 v24, v24, v31
	v_add_f32_e32 v28, v17, v28
	v_add_f32_e32 v17, v17, v24
	v_add_f32_e32 v24, v30, v17
	v_rcp_f32_e32 v31, v24
	v_add_f32_e32 v29, v27, v28
	v_sub_f32_e32 v27, v29, v27
	v_sub_f32_e32 v27, v28, v27
	v_sub_f32_e32 v28, v24, v30
	v_sub_f32_e32 v17, v17, v28
	v_mul_f32_e32 v28, v29, v31
	v_mul_f32_e32 v30, v24, v28
	v_fma_f32 v32, v28, v24, -v30
	v_fmac_f32_e32 v32, v28, v17
	v_add_f32_e32 v33, v30, v32
	v_sub_f32_e32 v34, v29, v33
	v_sub_f32_e32 v29, v29, v34
	v_sub_f32_e32 v30, v33, v30
	v_sub_f32_e32 v29, v29, v33
	v_add_f32_e32 v27, v27, v29
	v_sub_f32_e32 v29, v30, v32
	v_add_f32_e32 v27, v29, v27
	v_add_f32_e32 v29, v34, v27
; __device__ void fcum_unit(unsigned char* lds, int bh, const float* scal, const float* fgb  , float* F, const bf16_t* kp  , float* knsuf  , const bf16_t* kpa  , const float* relh  , float* ab  , unsigned* flag, unsigned fval) {
;     ...
;     float v[16]; float run = 0.f;
; #pragma unroll
;     for (int i = 0; i < 16; ++i) { const float x = scal[((size_t)b * SEQ + tid * 16 + i) * 16 + h] + fb; run += fminf(x, 0.f) - log1pf(__expf(-fabsf(x))); v[i] = run; }
	v_mul_f32_e32 v30, v31, v29
	v_mul_f32_e32 v32, v24, v30
	v_fma_f32 v24, v30, v24, -v32
	v_fmac_f32_e32 v24, v30, v17
	v_sub_f32_e32 v17, v34, v29
	v_add_f32_e32 v17, v27, v17
	v_add_f32_e32 v27, v32, v24
	v_sub_f32_e32 v33, v29, v27
	v_sub_f32_e32 v29, v29, v33
	v_sub_f32_e32 v32, v27, v32
	v_sub_f32_e32 v27, v29, v27
	v_add_f32_e32 v17, v17, v27
	v_sub_f32_e32 v24, v32, v24
	v_cvt_f32_i32_e32 v16, v16
	v_add_f32_e32 v17, v24, v17
	v_add_f32_e32 v24, v28, v30
	v_add_f32_e32 v17, v33, v17
	v_sub_f32_e32 v27, v24, v28
	v_mul_f32_e32 v17, v31, v17
	v_sub_f32_e32 v27, v30, v27
	v_add_f32_e32 v17, v27, v17
	v_mul_f32_e32 v30, 0x3f317218, v16
	v_add_f32_e32 v27, v24, v17
	v_fma_f32 v31, v16, s4, -v30
	v_mul_f32_e32 v28, v27, v27
	v_fmac_f32_e32 v31, 0xb102e308, v16
	v_sub_f32_e32 v16, v27, v24
	v_fmamk_f32 v29, v28, 0x3e9b6dac, v216
	v_sub_f32_e32 v16, v17, v16
	v_add_f32_e32 v17, v30, v31
	v_fmaak_f32 v29, v28, v29, 0x3f2aaada
	v_sub_f32_e32 v24, v17, v30
	v_ldexp_f32 v30, v27, 1
	v_mul_f32_e32 v27, v27, v28
	v_mul_f32_e32 v27, v27, v29
	v_add_f32_e32 v28, v30, v27
	v_sub_f32_e32 v29, v28, v30
	v_ldexp_f32 v16, v16, 1
	v_sub_f32_e32 v27, v27, v29
	v_add_f32_e32 v16, v16, v27
	v_add_f32_e32 v27, v28, v16
	v_sub_f32_e32 v28, v27, v28
	v_sub_f32_e32 v16, v16, v28
	v_add_f32_e32 v28, v17, v27
	v_sub_f32_e32 v29, v28, v17
	v_sub_f32_e32 v30, v28, v29
	v_sub_f32_e32 v24, v31, v24
	v_sub_f32_e32 v17, v17, v30
	v_sub_f32_e32 v27, v27, v29
	v_add_f32_e32 v17, v27, v17
	v_add_f32_e32 v27, v24, v16
	v_sub_f32_e32 v29, v27, v24
	v_sub_f32_e32 v30, v27, v29
	v_sub_f32_e32 v24, v24, v30
	v_sub_f32_e32 v16, v16, v29
	v_add_f32_e32 v17, v27, v17
	v_add_f32_e32 v16, v16, v24
	v_add_f32_e32 v24, v28, v17
	v_sub_f32_e32 v27, v24, v28
	v_sub_f32_e32 v17, v17, v27
	v_add_f32_e32 v16, v16, v17
	v_add_f32_e32 v16, v24, v16
	v_cmp_neq_f32_e32 vcc, s5, v26
	s_nop 1
	v_cndmask_b32_e32 v16, v220, v16, vcc
	v_cmp_ngt_f32_e32 vcc, -1.0, v26
	s_nop 1
	v_cndmask_b32_e32 v16, v221, v16, vcc
	v_cmp_neq_f32_e32 vcc, -1.0, v26
	s_nop 1
	v_cndmask_b32_e32 v16, v222, v16, vcc
	v_cmp_lt_f32_e64 vcc, |v26|, s6
	s_nop 1
	v_cndmask_b32_e32 v16, v16, v26, vcc
	v_sub_f32_e32 v5, v5, v16
	v_mul_f32_e64 v16, |v18|, s0
	v_exp_f32_e32 v24, v16
	v_add_f32_e32 v16, v9, v0
	v_add_f32_e32 v17, v16, v5
	v_min_f32_e32 v0, 0, v18
	v_add_f32_e32 v5, 1.0, v24
	v_add_f32_e32 v18, -1.0, v5
	v_sub_f32_e32 v26, v18, v5
	v_add_f32_e32 v26, 1.0, v26
	v_sub_f32_e32 v18, v24, v18
	v_add_f32_e32 v18, v18, v26
	v_frexp_mant_f32_e32 v28, v5
	v_cvt_f64_f32_e32 v[26:27], v5
	v_frexp_exp_i32_f64_e32 v26, v[26:27]
	v_cmp_gt_f32_e32 vcc, s1, v28
	s_nop 1
	v_subbrev_co_u32_e32 v26, vcc, 0, v26, vcc
	v_sub_u32_e32 v27, 0, v26
	v_ldexp_f32 v5, v5, v27
	v_ldexp_f32 v18, v18, v27
	v_add_f32_e32 v27, -1.0, v5
	v_add_f32_e32 v30, 1.0, v5
	v_add_f32_e32 v28, 1.0, v27
	v_add_f32_e32 v31, -1.0, v30
	v_sub_f32_e32 v28, v5, v28
	v_sub_f32_e32 v5, v5, v31
	v_add_f32_e32 v5, v18, v5
	v_add_f32_e32 v28, v18, v28
	v_add_f32_e32 v18, v30, v5
	v_rcp_f32_e32 v31, v18
	v_add_f32_e32 v29, v27, v28
	v_sub_f32_e32 v27, v29, v27
	v_sub_f32_e32 v27, v28, v27
	v_sub_f32_e32 v28, v18, v30
	v_sub_f32_e32 v5, v5, v28
	v_mul_f32_e32 v28, v29, v31
	v_mul_f32_e32 v30, v18, v28
	v_fma_f32 v32, v28, v18, -v30
	v_fmac_f32_e32 v32, v28, v5
	v_add_f32_e32 v33, v30, v32
	v_sub_f32_e32 v34, v29, v33
	v_sub_f32_e32 v29, v29, v34
	v_sub_f32_e32 v30, v33, v30
	v_sub_f32_e32 v29, v29, v33
	v_add_f32_e32 v27, v27, v29
	v_sub_f32_e32 v29, v30, v32
	v_add_f32_e32 v27, v29, v27
	v_add_f32_e32 v29, v34, v27
	v_mul_f32_e32 v30, v31, v29
	v_mul_f32_e32 v32, v18, v30
	v_fma_f32 v18, v30, v18, -v32
	v_fmac_f32_e32 v18, v30, v5
	v_sub_f32_e32 v5, v34, v29
	v_add_f32_e32 v5, v27, v5
	v_add_f32_e32 v27, v32, v18
	v_sub_f32_e32 v33, v29, v27
	v_sub_f32_e32 v29, v29, v33
	v_sub_f32_e32 v32, v27, v32
	v_sub_f32_e32 v27, v29, v27
	v_add_f32_e32 v5, v5, v27
	v_sub_f32_e32 v18, v32, v18
	v_cvt_f32_i32_e32 v26, v26
	v_add_f32_e32 v5, v18, v5
	v_add_f32_e32 v18, v28, v30
	v_add_f32_e32 v5, v33, v5
	v_sub_f32_e32 v27, v18, v28
	v_mul_f32_e32 v5, v31, v5
	v_sub_f32_e32 v27, v30, v27
	v_add_f32_e32 v5, v27, v5
	v_mul_f32_e32 v30, 0x3f317218, v26
	v_add_f32_e32 v27, v18, v5
	v_fma_f32 v31, v26, s4, -v30
	v_mul_f32_e32 v28, v27, v27
	v_fmac_f32_e32 v31, 0xb102e308, v26
	v_sub_f32_e32 v18, v27, v18
	v_fmamk_f32 v29, v28, 0x3e9b6dac, v216
	v_sub_f32_e32 v5, v5, v18
	v_add_f32_e32 v18, v30, v31
	v_fmaak_f32 v29, v28, v29, 0x3f2aaada
	v_sub_f32_e32 v26, v18, v30
	v_ldexp_f32 v30, v27, 1
	v_mul_f32_e32 v27, v27, v28
	v_mul_f32_e32 v27, v27, v29
	v_add_f32_e32 v28, v30, v27
	v_sub_f32_e32 v29, v28, v30
	v_ldexp_f32 v5, v5, 1
	v_sub_f32_e32 v27, v27, v29
	v_add_f32_e32 v5, v5, v27
	v_add_f32_e32 v27, v28, v5
	v_sub_f32_e32 v28, v27, v28
	v_sub_f32_e32 v5, v5, v28
	v_add_f32_e32 v28, v18, v27
	v_sub_f32_e32 v29, v28, v18
	v_sub_f32_e32 v30, v28, v29
	v_sub_f32_e32 v26, v31, v26
	v_sub_f32_e32 v18, v18, v30
	v_sub_f32_e32 v27, v27, v29
	v_add_f32_e32 v18, v27, v18
	v_add_f32_e32 v27, v26, v5
	v_sub_f32_e32 v29, v27, v26
	v_sub_f32_e32 v30, v27, v29
	v_sub_f32_e32 v26, v26, v30
	v_sub_f32_e32 v5, v5, v29
	v_add_f32_e32 v18, v27, v18
	v_add_f32_e32 v5, v5, v26
	v_add_f32_e32 v26, v28, v18
	v_sub_f32_e32 v27, v26, v28
	v_sub_f32_e32 v18, v18, v27
	v_add_f32_e32 v5, v5, v18
	v_add_f32_e32 v18, v3, v19
	v_mul_f32_e64 v19, |v18|, s0
	v_add_f32_e32 v5, v26, v5
	v_cmp_neq_f32_e32 vcc, s5, v24
	v_exp_f32_e32 v26, v19
	s_nop 0
	v_cndmask_b32_e32 v5, v220, v5, vcc
	v_cmp_ngt_f32_e32 vcc, -1.0, v24
	s_nop 1
	v_cndmask_b32_e32 v5, v221, v5, vcc
	v_cmp_neq_f32_e32 vcc, -1.0, v24
	s_nop 1
; __device__ void fcum_unit(unsigned char* lds, int bh, const float* scal, const float* fgb  , float* F, const bf16_t* kp  , float* knsuf  , const bf16_t* kpa  , const float* relh  , float* ab  , unsigned* flag, unsigned fval) {
;     ...
;     float v[16]; float run = 0.f;
; #pragma unroll
;     for (int i = 0; i < 16; ++i) { const float x = scal[((size_t)b * SEQ + tid * 16 + i) * 16 + h] + fb; run += fminf(x, 0.f) - log1pf(__expf(-fabsf(x))); v[i] = run; }
	v_cndmask_b32_e32 v5, v222, v5, vcc
	v_cmp_lt_f32_e64 vcc, |v24|, s6
	s_nop 1
	v_cndmask_b32_e32 v5, v5, v24, vcc
	v_add_f32_e32 v24, 1.0, v26
	v_sub_f32_e32 v0, v0, v5
	v_min_f32_e32 v5, 0, v18
	v_add_f32_e32 v18, -1.0, v24
	v_sub_f32_e32 v19, v18, v24
	v_add_f32_e32 v19, 1.0, v19
	v_sub_f32_e32 v18, v26, v18
	v_add_f32_e32 v27, v18, v19
	v_frexp_mant_f32_e32 v28, v24
	v_cvt_f64_f32_e32 v[18:19], v24
	v_frexp_exp_i32_f64_e32 v18, v[18:19]
	v_cmp_gt_f32_e32 vcc, s1, v28
	s_nop 1
	v_subbrev_co_u32_e32 v18, vcc, 0, v18, vcc
	v_sub_u32_e32 v19, 0, v18
	v_ldexp_f32 v24, v24, v19
	v_ldexp_f32 v19, v27, v19
	v_add_f32_e32 v27, -1.0, v24
	v_add_f32_e32 v30, 1.0, v24
	v_add_f32_e32 v28, 1.0, v27
	v_add_f32_e32 v31, -1.0, v30
	v_sub_f32_e32 v28, v24, v28
	v_sub_f32_e32 v24, v24, v31
	v_add_f32_e32 v28, v19, v28
	v_add_f32_e32 v19, v19, v24
	v_add_f32_e32 v24, v30, v19
	v_rcp_f32_e32 v31, v24
	v_add_f32_e32 v29, v27, v28
	v_sub_f32_e32 v27, v29, v27
	v_sub_f32_e32 v27, v28, v27
	v_sub_f32_e32 v28, v24, v30
	v_sub_f32_e32 v19, v19, v28
	v_mul_f32_e32 v28, v29, v31
	v_mul_f32_e32 v30, v24, v28
	v_fma_f32 v32, v28, v24, -v30
	v_fmac_f32_e32 v32, v28, v19
	v_add_f32_e32 v33, v30, v32
	v_sub_f32_e32 v34, v29, v33
	v_sub_f32_e32 v29, v29, v34
	v_sub_f32_e32 v30, v33, v30
	v_sub_f32_e32 v29, v29, v33
	v_add_f32_e32 v27, v27, v29
	v_sub_f32_e32 v29, v30, v32
	v_add_f32_e32 v27, v29, v27
	v_add_f32_e32 v29, v34, v27
	v_mul_f32_e32 v30, v31, v29
	v_mul_f32_e32 v32, v24, v30
	v_fma_f32 v24, v30, v24, -v32
	v_fmac_f32_e32 v24, v30, v19
	v_sub_f32_e32 v19, v34, v29
	v_add_f32_e32 v19, v27, v19
	v_add_f32_e32 v27, v32, v24
	v_sub_f32_e32 v33, v29, v27
	v_sub_f32_e32 v29, v29, v33
	v_sub_f32_e32 v32, v27, v32
	v_sub_f32_e32 v27, v29, v27
	v_add_f32_e32 v19, v19, v27
	v_sub_f32_e32 v24, v32, v24
	v_cvt_f32_i32_e32 v18, v18
	v_add_f32_e32 v19, v24, v19
	v_add_f32_e32 v24, v28, v30
	v_add_f32_e32 v19, v33, v19
	v_sub_f32_e32 v27, v24, v28
	v_mul_f32_e32 v19, v31, v19
	v_sub_f32_e32 v27, v30, v27
	v_add_f32_e32 v19, v27, v19
	v_mul_f32_e32 v30, 0x3f317218, v18
	v_add_f32_e32 v27, v24, v19
	v_fma_f32 v31, v18, s4, -v30
	v_mul_f32_e32 v28, v27, v27
	v_fmac_f32_e32 v31, 0xb102e308, v18
	v_sub_f32_e32 v18, v27, v24
	v_fmamk_f32 v29, v28, 0x3e9b6dac, v216
	v_sub_f32_e32 v18, v19, v18
	v_add_f32_e32 v19, v30, v31
	v_fmaak_f32 v29, v28, v29, 0x3f2aaada
	v_sub_f32_e32 v24, v19, v30
	v_ldexp_f32 v30, v27, 1
	v_mul_f32_e32 v27, v27, v28
	v_mul_f32_e32 v27, v27, v29
	v_add_f32_e32 v28, v30, v27
	v_sub_f32_e32 v29, v28, v30
	v_ldexp_f32 v18, v18, 1
	v_sub_f32_e32 v27, v27, v29
	v_add_f32_e32 v18, v18, v27
	v_add_f32_e32 v27, v28, v18
	v_sub_f32_e32 v28, v27, v28
	v_sub_f32_e32 v18, v18, v28
	v_add_f32_e32 v28, v19, v27
	v_sub_f32_e32 v29, v28, v19
	v_sub_f32_e32 v30, v28, v29
	v_sub_f32_e32 v24, v31, v24
	v_sub_f32_e32 v19, v19, v30
	v_sub_f32_e32 v27, v27, v29
	v_add_f32_e32 v19, v27, v19
	v_add_f32_e32 v27, v24, v18
	v_sub_f32_e32 v29, v27, v24
	v_sub_f32_e32 v30, v27, v29
	v_sub_f32_e32 v24, v24, v30
	v_sub_f32_e32 v18, v18, v29
	v_add_f32_e32 v19, v27, v19
	v_add_f32_e32 v18, v18, v24
	v_add_f32_e32 v24, v28, v19
	v_sub_f32_e32 v27, v24, v28
	v_sub_f32_e32 v19, v19, v27
	v_add_f32_e32 v18, v18, v19
	v_add_f32_e32 v18, v24, v18
	v_cmp_neq_f32_e32 vcc, s5, v26
	s_nop 1
	v_cndmask_b32_e32 v18, v220, v18, vcc
	v_cmp_ngt_f32_e32 vcc, -1.0, v26
	s_nop 1
	v_cndmask_b32_e32 v18, v221, v18, vcc
	v_cmp_neq_f32_e32 vcc, -1.0, v26
	s_nop 1
	v_cndmask_b32_e32 v18, v222, v18, vcc
	v_cmp_lt_f32_e64 vcc, |v26|, s6
	s_nop 1
	v_cndmask_b32_e32 v18, v18, v26, vcc
	v_sub_f32_e32 v5, v5, v18
	v_mul_f32_e64 v18, |v20|, s0
	v_exp_f32_e32 v24, v18
	v_add_f32_e32 v18, v17, v0
	v_add_f32_e32 v19, v18, v5
	v_min_f32_e32 v0, 0, v20
	v_add_f32_e32 v5, 1.0, v24
	v_add_f32_e32 v20, -1.0, v5
	v_sub_f32_e32 v26, v20, v5
	v_add_f32_e32 v26, 1.0, v26
	v_sub_f32_e32 v20, v24, v20
	v_add_f32_e32 v20, v20, v26
	v_frexp_mant_f32_e32 v28, v5
	v_cvt_f64_f32_e32 v[26:27], v5
	v_frexp_exp_i32_f64_e32 v26, v[26:27]
	v_cmp_gt_f32_e32 vcc, s1, v28
	s_nop 1
	v_subbrev_co_u32_e32 v26, vcc, 0, v26, vcc
	v_sub_u32_e32 v27, 0, v26
	v_ldexp_f32 v5, v5, v27
	v_ldexp_f32 v20, v20, v27
	v_add_f32_e32 v27, -1.0, v5
	v_add_f32_e32 v30, 1.0, v5
	v_add_f32_e32 v28, 1.0, v27
	v_add_f32_e32 v31, -1.0, v30
	v_sub_f32_e32 v28, v5, v28
	v_sub_f32_e32 v5, v5, v31
	v_add_f32_e32 v5, v20, v5
	v_add_f32_e32 v28, v20, v28
	v_add_f32_e32 v20, v30, v5
	v_rcp_f32_e32 v31, v20
	v_add_f32_e32 v29, v27, v28
	v_sub_f32_e32 v27, v29, v27
	v_sub_f32_e32 v27, v28, v27
	v_sub_f32_e32 v28, v20, v30
	v_sub_f32_e32 v5, v5, v28
	v_mul_f32_e32 v28, v29, v31
	v_mul_f32_e32 v30, v20, v28
	v_fma_f32 v32, v28, v20, -v30
	v_fmac_f32_e32 v32, v28, v5
	v_add_f32_e32 v33, v30, v32
	v_sub_f32_e32 v34, v29, v33
	v_sub_f32_e32 v29, v29, v34
	v_sub_f32_e32 v30, v33, v30
	v_sub_f32_e32 v29, v29, v33
	v_add_f32_e32 v27, v27, v29
	v_sub_f32_e32 v29, v30, v32
	v_add_f32_e32 v27, v29, v27
	v_add_f32_e32 v29, v34, v27
	v_mul_f32_e32 v30, v31, v29
	v_mul_f32_e32 v32, v20, v30
	v_fma_f32 v20, v30, v20, -v32
	v_fmac_f32_e32 v20, v30, v5
	v_sub_f32_e32 v5, v34, v29
	v_add_f32_e32 v5, v27, v5
	v_add_f32_e32 v27, v32, v20
	v_sub_f32_e32 v33, v29, v27
	v_sub_f32_e32 v29, v29, v33
	v_sub_f32_e32 v32, v27, v32
	v_sub_f32_e32 v27, v29, v27
	v_add_f32_e32 v5, v5, v27
	v_sub_f32_e32 v20, v32, v20
	v_cvt_f32_i32_e32 v26, v26
	v_add_f32_e32 v5, v20, v5
	v_add_f32_e32 v20, v28, v30
	v_add_f32_e32 v5, v33, v5
	v_sub_f32_e32 v27, v20, v28
	v_mul_f32_e32 v5, v31, v5
	v_sub_f32_e32 v27, v30, v27
	v_add_f32_e32 v5, v27, v5
	v_mul_f32_e32 v30, 0x3f317218, v26
	v_add_f32_e32 v27, v20, v5
; __device__ void fcum_unit(unsigned char* lds, int bh, const float* scal, const float* fgb  , float* F, const bf16_t* kp  , float* knsuf  , const bf16_t* kpa  , const float* relh  , float* ab  , unsigned* flag, unsigned fval) {
;     ...
;     float v[16]; float run = 0.f;
; #pragma unroll
;     for (int i = 0; i < 16; ++i) { const float x = scal[((size_t)b * SEQ + tid * 16 + i) * 16 + h] + fb; run += fminf(x, 0.f) - log1pf(__expf(-fabsf(x))); v[i] = run; }
	v_fma_f32 v31, v26, s4, -v30
	v_mul_f32_e32 v28, v27, v27
	v_fmac_f32_e32 v31, 0xb102e308, v26
	v_sub_f32_e32 v20, v27, v20
	v_fmamk_f32 v29, v28, 0x3e9b6dac, v216
	v_sub_f32_e32 v5, v5, v20
	v_add_f32_e32 v20, v30, v31
	v_fmaak_f32 v29, v28, v29, 0x3f2aaada
	v_sub_f32_e32 v26, v20, v30
	v_ldexp_f32 v30, v27, 1
	v_mul_f32_e32 v27, v27, v28
	v_mul_f32_e32 v27, v27, v29
	v_add_f32_e32 v28, v30, v27
	v_sub_f32_e32 v29, v28, v30
	v_ldexp_f32 v5, v5, 1
	v_sub_f32_e32 v27, v27, v29
	v_add_f32_e32 v5, v5, v27
	v_add_f32_e32 v27, v28, v5
	v_sub_f32_e32 v28, v27, v28
	v_sub_f32_e32 v5, v5, v28
	v_add_f32_e32 v28, v20, v27
	v_sub_f32_e32 v29, v28, v20
	v_sub_f32_e32 v30, v28, v29
	v_sub_f32_e32 v26, v31, v26
	v_sub_f32_e32 v20, v20, v30
	v_sub_f32_e32 v27, v27, v29
	v_add_f32_e32 v20, v27, v20
	v_add_f32_e32 v27, v26, v5
	v_sub_f32_e32 v29, v27, v26
	v_sub_f32_e32 v30, v27, v29
	v_sub_f32_e32 v26, v26, v30
	v_sub_f32_e32 v5, v5, v29
	v_add_f32_e32 v20, v27, v20
	v_add_f32_e32 v5, v5, v26
	v_add_f32_e32 v26, v28, v20
	v_sub_f32_e32 v27, v26, v28
	v_sub_f32_e32 v20, v20, v27
	v_add_f32_e32 v5, v5, v20
	v_add_f32_e32 v20, v3, v21
	v_mul_f32_e64 v21, |v20|, s0
	v_add_f32_e32 v5, v26, v5
	v_cmp_neq_f32_e32 vcc, s5, v24
	v_exp_f32_e32 v26, v21
	v_add_f32_e32 v3, v3, v23
	v_cndmask_b32_e32 v5, v220, v5, vcc
	v_cmp_ngt_f32_e32 vcc, -1.0, v24
	s_nop 1
	v_cndmask_b32_e32 v5, v221, v5, vcc
	v_cmp_neq_f32_e32 vcc, -1.0, v24
	s_nop 1
	v_cndmask_b32_e32 v5, v222, v5, vcc
	v_cmp_lt_f32_e64 vcc, |v24|, s6
	s_nop 1
	v_cndmask_b32_e32 v5, v5, v24, vcc
	v_add_f32_e32 v24, 1.0, v26
	v_sub_f32_e32 v0, v0, v5
	v_min_f32_e32 v5, 0, v20
	v_add_f32_e32 v20, -1.0, v24
	v_sub_f32_e32 v21, v20, v24
	v_add_f32_e32 v21, 1.0, v21
	v_sub_f32_e32 v20, v26, v20
	v_add_f32_e32 v27, v20, v21
	v_frexp_mant_f32_e32 v28, v24
	v_cvt_f64_f32_e32 v[20:21], v24
	v_frexp_exp_i32_f64_e32 v20, v[20:21]
	v_cmp_gt_f32_e32 vcc, s1, v28
	s_nop 1
	v_subbrev_co_u32_e32 v20, vcc, 0, v20, vcc
	v_sub_u32_e32 v21, 0, v20
	v_ldexp_f32 v24, v24, v21
	v_ldexp_f32 v21, v27, v21
	v_add_f32_e32 v27, -1.0, v24
	v_add_f32_e32 v30, 1.0, v24
	v_add_f32_e32 v28, 1.0, v27
	v_add_f32_e32 v31, -1.0, v30
	v_sub_f32_e32 v28, v24, v28
	v_sub_f32_e32 v24, v24, v31
	v_add_f32_e32 v28, v21, v28
	v_add_f32_e32 v21, v21, v24
	v_add_f32_e32 v24, v30, v21
	v_rcp_f32_e32 v31, v24
	v_add_f32_e32 v29, v27, v28
	v_sub_f32_e32 v27, v29, v27
	v_sub_f32_e32 v27, v28, v27
	v_sub_f32_e32 v28, v24, v30
	v_sub_f32_e32 v21, v21, v28
	v_mul_f32_e32 v28, v29, v31
	v_mul_f32_e32 v30, v24, v28
	v_fma_f32 v32, v28, v24, -v30
	v_fmac_f32_e32 v32, v28, v21
	v_add_f32_e32 v33, v30, v32
	v_sub_f32_e32 v34, v29, v33
	v_sub_f32_e32 v29, v29, v34
	v_sub_f32_e32 v30, v33, v30
	v_sub_f32_e32 v29, v29, v33
	v_add_f32_e32 v27, v27, v29
	v_sub_f32_e32 v29, v30, v32
	v_add_f32_e32 v27, v29, v27
	v_add_f32_e32 v29, v34, v27
	v_mul_f32_e32 v30, v31, v29
	v_mul_f32_e32 v32, v24, v30
	v_fma_f32 v24, v30, v24, -v32
	v_fmac_f32_e32 v24, v30, v21
	v_sub_f32_e32 v21, v34, v29
	v_add_f32_e32 v21, v27, v21
	v_add_f32_e32 v27, v32, v24
	v_sub_f32_e32 v33, v29, v27
	v_sub_f32_e32 v29, v29, v33
	v_sub_f32_e32 v32, v27, v32
	v_sub_f32_e32 v27, v29, v27
	v_add_f32_e32 v21, v21, v27
	v_sub_f32_e32 v24, v32, v24
	v_cvt_f32_i32_e32 v20, v20
	v_add_f32_e32 v21, v24, v21
	v_add_f32_e32 v24, v28, v30
	v_add_f32_e32 v21, v33, v21
	v_sub_f32_e32 v27, v24, v28
	v_mul_f32_e32 v21, v31, v21
	v_sub_f32_e32 v27, v30, v27
	v_add_f32_e32 v21, v27, v21
	v_mul_f32_e32 v30, 0x3f317218, v20
	v_add_f32_e32 v27, v24, v21
	v_fma_f32 v31, v20, s4, -v30
	v_mul_f32_e32 v28, v27, v27
	v_fmac_f32_e32 v31, 0xb102e308, v20
	v_sub_f32_e32 v20, v27, v24
	v_fmamk_f32 v29, v28, 0x3e9b6dac, v216
	v_sub_f32_e32 v20, v21, v20
	v_add_f32_e32 v21, v30, v31
	v_fmaak_f32 v29, v28, v29, 0x3f2aaada
	v_sub_f32_e32 v24, v21, v30
	v_ldexp_f32 v30, v27, 1
	v_mul_f32_e32 v27, v27, v28
	v_mul_f32_e32 v27, v27, v29
	v_add_f32_e32 v28, v30, v27
	v_sub_f32_e32 v29, v28, v30
	v_ldexp_f32 v20, v20, 1
	v_sub_f32_e32 v27, v27, v29
	v_add_f32_e32 v20, v20, v27
	v_add_f32_e32 v27, v28, v20
	v_sub_f32_e32 v28, v27, v28
	v_sub_f32_e32 v20, v20, v28
	v_add_f32_e32 v28, v21, v27
	v_sub_f32_e32 v29, v28, v21
	v_sub_f32_e32 v30, v28, v29
	v_sub_f32_e32 v24, v31, v24
	v_sub_f32_e32 v21, v21, v30
	v_sub_f32_e32 v27, v27, v29
	v_add_f32_e32 v21, v27, v21
	v_add_f32_e32 v27, v24, v20
	v_sub_f32_e32 v29, v27, v24
	v_sub_f32_e32 v30, v27, v29
	v_sub_f32_e32 v24, v24, v30
	v_sub_f32_e32 v20, v20, v29
	v_add_f32_e32 v21, v27, v21
	v_add_f32_e32 v20, v20, v24
	v_add_f32_e32 v24, v28, v21
	v_sub_f32_e32 v27, v24, v28
	v_sub_f32_e32 v21, v21, v27
	v_add_f32_e32 v20, v20, v21
	v_add_f32_e32 v20, v24, v20
	v_cmp_neq_f32_e32 vcc, s5, v26
	s_nop 1
	v_cndmask_b32_e32 v20, v220, v20, vcc
	v_cmp_ngt_f32_e32 vcc, -1.0, v26
	s_nop 1
	v_cndmask_b32_e32 v20, v221, v20, vcc
	v_cmp_neq_f32_e32 vcc, -1.0, v26
	s_nop 1
	v_cndmask_b32_e32 v20, v222, v20, vcc
	v_cmp_lt_f32_e64 vcc, |v26|, s6
	s_nop 1
	v_cndmask_b32_e32 v20, v20, v26, vcc
	v_sub_f32_e32 v5, v5, v20
	v_mul_f32_e64 v20, |v22|, s0
	v_exp_f32_e32 v24, v20
	v_add_f32_e32 v20, v19, v0
	v_add_f32_e32 v21, v20, v5
	v_min_f32_e32 v0, 0, v22
	v_add_f32_e32 v5, 1.0, v24
	v_add_f32_e32 v22, -1.0, v5
	v_sub_f32_e32 v26, v22, v5
	v_add_f32_e32 v26, 1.0, v26
	v_sub_f32_e32 v22, v24, v22
	v_add_f32_e32 v22, v22, v26
	v_frexp_mant_f32_e32 v28, v5
	v_cvt_f64_f32_e32 v[26:27], v5
	v_frexp_exp_i32_f64_e32 v26, v[26:27]
	v_cmp_gt_f32_e32 vcc, s1, v28
	s_nop 1
	v_subbrev_co_u32_e32 v26, vcc, 0, v26, vcc
	v_sub_u32_e32 v27, 0, v26
	v_ldexp_f32 v5, v5, v27
	v_ldexp_f32 v22, v22, v27
	v_add_f32_e32 v27, -1.0, v5
; __device__ void fcum_unit(unsigned char* lds, int bh, const float* scal, const float* fgb  , float* F, const bf16_t* kp  , float* knsuf  , const bf16_t* kpa  , const float* relh  , float* ab  , unsigned* flag, unsigned fval) {
;     ...
;     float v[16]; float run = 0.f;
; #pragma unroll
;     for (int i = 0; i < 16; ++i) { const float x = scal[((size_t)b * SEQ + tid * 16 + i) * 16 + h] + fb; run += fminf(x, 0.f) - log1pf(__expf(-fabsf(x))); v[i] = run; }
;     float inc = run;
; #pragma unroll
;     for (int o = 1; o < 64; o <<= 1) { const float y = __shfl_up(inc, o); if (lane >= o) inc += y; }
	v_add_f32_e32 v30, 1.0, v5
	v_add_f32_e32 v28, 1.0, v27
	v_add_f32_e32 v31, -1.0, v30
	v_sub_f32_e32 v28, v5, v28
	v_sub_f32_e32 v5, v5, v31
	v_add_f32_e32 v5, v22, v5
	v_add_f32_e32 v28, v22, v28
	v_add_f32_e32 v22, v30, v5
	v_rcp_f32_e32 v31, v22
	v_add_f32_e32 v29, v27, v28
	v_sub_f32_e32 v27, v29, v27
	v_sub_f32_e32 v27, v28, v27
	v_sub_f32_e32 v28, v22, v30
	v_sub_f32_e32 v5, v5, v28
	v_mul_f32_e32 v28, v29, v31
	v_mul_f32_e32 v30, v22, v28
	v_fma_f32 v32, v28, v22, -v30
	v_fmac_f32_e32 v32, v28, v5
	v_add_f32_e32 v33, v30, v32
	v_sub_f32_e32 v34, v29, v33
	v_sub_f32_e32 v29, v29, v34
	v_sub_f32_e32 v30, v33, v30
	v_sub_f32_e32 v29, v29, v33
	v_add_f32_e32 v27, v27, v29
	v_sub_f32_e32 v29, v30, v32
	v_add_f32_e32 v27, v29, v27
	v_add_f32_e32 v29, v34, v27
	v_mul_f32_e32 v30, v31, v29
	v_mul_f32_e32 v32, v22, v30
	v_fma_f32 v22, v30, v22, -v32
	v_fmac_f32_e32 v22, v30, v5
	v_sub_f32_e32 v5, v34, v29
	v_add_f32_e32 v5, v27, v5
	v_add_f32_e32 v27, v32, v22
	v_sub_f32_e32 v33, v29, v27
	v_sub_f32_e32 v29, v29, v33
	v_sub_f32_e32 v32, v27, v32
	v_sub_f32_e32 v27, v29, v27
	v_add_f32_e32 v5, v5, v27
	v_sub_f32_e32 v22, v32, v22
	v_cvt_f32_i32_e32 v26, v26
	v_add_f32_e32 v5, v22, v5
	v_add_f32_e32 v22, v28, v30
	v_add_f32_e32 v5, v33, v5
	v_sub_f32_e32 v27, v22, v28
	v_mul_f32_e32 v5, v31, v5
	v_sub_f32_e32 v27, v30, v27
	v_add_f32_e32 v5, v27, v5
	v_mul_f32_e32 v30, 0x3f317218, v26
	v_add_f32_e32 v27, v22, v5
	v_fma_f32 v31, v26, s4, -v30
	v_mul_f32_e32 v28, v27, v27
	v_fmac_f32_e32 v31, 0xb102e308, v26
	v_sub_f32_e32 v22, v27, v22
	v_fmamk_f32 v29, v28, 0x3e9b6dac, v216
	v_sub_f32_e32 v5, v5, v22
	v_add_f32_e32 v22, v30, v31
	v_fmaak_f32 v29, v28, v29, 0x3f2aaada
	v_sub_f32_e32 v26, v22, v30
	v_ldexp_f32 v30, v27, 1
	v_mul_f32_e32 v27, v27, v28
	v_mul_f32_e32 v27, v27, v29
	v_add_f32_e32 v28, v30, v27
	v_sub_f32_e32 v29, v28, v30
	v_ldexp_f32 v5, v5, 1
	v_sub_f32_e32 v27, v27, v29
	v_add_f32_e32 v5, v5, v27
	v_add_f32_e32 v27, v28, v5
	v_sub_f32_e32 v28, v27, v28
	v_sub_f32_e32 v5, v5, v28
	v_add_f32_e32 v28, v22, v27
	v_sub_f32_e32 v29, v28, v22
	v_sub_f32_e32 v30, v28, v29
	v_sub_f32_e32 v26, v31, v26
	v_sub_f32_e32 v22, v22, v30
	v_sub_f32_e32 v27, v27, v29
	v_add_f32_e32 v22, v27, v22
	v_add_f32_e32 v27, v26, v5
	v_sub_f32_e32 v29, v27, v26
	v_sub_f32_e32 v30, v27, v29
	v_sub_f32_e32 v26, v26, v30
	v_sub_f32_e32 v5, v5, v29
	v_add_f32_e32 v22, v27, v22
	v_add_f32_e32 v5, v5, v26
	v_add_f32_e32 v26, v28, v22
	v_sub_f32_e32 v27, v26, v28
	v_sub_f32_e32 v22, v22, v27
	v_add_f32_e32 v5, v5, v22
	v_add_f32_e32 v5, v26, v5
	v_cmp_neq_f32_e32 vcc, s5, v24
	v_mul_f32_e64 v22, |v3|, s0
	v_exp_f32_e32 v26, v22
	v_cndmask_b32_e32 v5, v220, v5, vcc
	v_cmp_ngt_f32_e32 vcc, -1.0, v24
	v_min_f32_e32 v3, 0, v3
	s_nop 0
	v_cndmask_b32_e32 v5, v221, v5, vcc
	v_cmp_neq_f32_e32 vcc, -1.0, v24
	s_nop 1
	v_cndmask_b32_e32 v5, v222, v5, vcc
	v_cmp_lt_f32_e64 vcc, |v24|, s6
	s_nop 1
	v_cndmask_b32_e32 v5, v5, v24, vcc
	v_sub_f32_e32 v0, v0, v5
	v_add_f32_e32 v5, 1.0, v26
	v_add_f32_e32 v22, -1.0, v5
	v_sub_f32_e32 v23, v22, v5
	v_add_f32_e32 v23, 1.0, v23
	v_sub_f32_e32 v22, v26, v22
	v_add_f32_e32 v24, v22, v23
	v_frexp_mant_f32_e32 v27, v5
	v_cvt_f64_f32_e32 v[22:23], v5
	v_frexp_exp_i32_f64_e32 v22, v[22:23]
	v_cmp_gt_f32_e32 vcc, s1, v27
	s_nop 1
	v_subbrev_co_u32_e32 v22, vcc, 0, v22, vcc
	v_sub_u32_e32 v23, 0, v22
	v_ldexp_f32 v5, v5, v23
	v_ldexp_f32 v23, v24, v23
	v_add_f32_e32 v24, -1.0, v5
	v_add_f32_e32 v29, 1.0, v5
	v_add_f32_e32 v27, 1.0, v24
	v_add_f32_e32 v30, -1.0, v29
	v_sub_f32_e32 v27, v5, v27
	v_sub_f32_e32 v5, v5, v30
	v_add_f32_e32 v5, v23, v5
	v_add_f32_e32 v27, v23, v27
	v_add_f32_e32 v23, v29, v5
	v_rcp_f32_e32 v30, v23
	v_add_f32_e32 v28, v24, v27
	v_sub_f32_e32 v24, v28, v24
	v_sub_f32_e32 v24, v27, v24
	v_sub_f32_e32 v27, v23, v29
	v_sub_f32_e32 v5, v5, v27
	v_mul_f32_e32 v27, v28, v30
	v_mul_f32_e32 v29, v23, v27
	v_fma_f32 v31, v27, v23, -v29
	v_fmac_f32_e32 v31, v27, v5
	v_add_f32_e32 v32, v29, v31
	v_sub_f32_e32 v33, v28, v32
	v_sub_f32_e32 v28, v28, v33
	v_sub_f32_e32 v29, v32, v29
	v_sub_f32_e32 v28, v28, v32
	v_add_f32_e32 v24, v24, v28
	v_sub_f32_e32 v28, v29, v31
	v_add_f32_e32 v24, v28, v24
	v_add_f32_e32 v28, v33, v24
	v_mul_f32_e32 v29, v30, v28
	v_mul_f32_e32 v31, v23, v29
	v_fma_f32 v23, v29, v23, -v31
	v_fmac_f32_e32 v23, v29, v5
	v_sub_f32_e32 v5, v33, v28
	v_add_f32_e32 v5, v24, v5
	v_add_f32_e32 v24, v31, v23
	v_sub_f32_e32 v32, v28, v24
	v_sub_f32_e32 v28, v28, v32
	v_sub_f32_e32 v31, v24, v31
	v_sub_f32_e32 v24, v28, v24
	v_add_f32_e32 v5, v5, v24
	v_sub_f32_e32 v23, v31, v23
	v_cvt_f32_i32_e32 v22, v22
	v_add_f32_e32 v5, v23, v5
	v_add_f32_e32 v23, v27, v29
	v_add_f32_e32 v5, v32, v5
	v_sub_f32_e32 v24, v23, v27
	v_mul_f32_e32 v5, v30, v5
	v_sub_f32_e32 v24, v29, v24
	v_add_f32_e32 v5, v24, v5
	v_mul_f32_e32 v29, 0x3f317218, v22
	v_add_f32_e32 v24, v23, v5
	v_fma_f32 v30, v22, s4, -v29
	v_mul_f32_e32 v27, v24, v24
	v_fmac_f32_e32 v30, 0xb102e308, v22
	v_sub_f32_e32 v22, v24, v23
	v_fmamk_f32 v28, v27, 0x3e9b6dac, v216
	v_sub_f32_e32 v5, v5, v22
	v_add_f32_e32 v22, v29, v30
	v_fmaak_f32 v28, v27, v28, 0x3f2aaada
	v_sub_f32_e32 v23, v22, v29
	v_ldexp_f32 v29, v24, 1
	v_mul_f32_e32 v24, v24, v27
	v_mul_f32_e32 v24, v24, v28
	v_add_f32_e32 v27, v29, v24
	v_sub_f32_e32 v28, v27, v29
	v_ldexp_f32 v5, v5, 1
	v_sub_f32_e32 v24, v24, v28
	v_add_f32_e32 v5, v5, v24
	v_add_f32_e32 v24, v27, v5
	v_sub_f32_e32 v27, v24, v27
	v_sub_f32_e32 v5, v5, v27
	v_add_f32_e32 v27, v22, v24
	v_sub_f32_e32 v28, v27, v22
	v_sub_f32_e32 v29, v27, v28
	v_sub_f32_e32 v23, v30, v23
	v_sub_f32_e32 v22, v22, v29
	v_sub_f32_e32 v24, v24, v28
	v_add_f32_e32 v22, v24, v22
	v_add_f32_e32 v24, v23, v5
	v_sub_f32_e32 v28, v24, v23
	v_sub_f32_e32 v29, v24, v28
	v_sub_f32_e32 v23, v23, v29
	v_sub_f32_e32 v5, v5, v28
	v_add_f32_e32 v22, v24, v22
	v_add_f32_e32 v5, v5, v23
	v_add_f32_e32 v23, v27, v22
	v_sub_f32_e32 v24, v23, v27
	v_sub_f32_e32 v22, v22, v24
	v_add_f32_e32 v5, v5, v22
	v_add_f32_e32 v5, v23, v5
	v_cmp_neq_f32_e32 vcc, s5, v26
	v_add_f32_e32 v22, v21, v0
	v_add_u32_e32 v0, -1, v218
	v_cndmask_b32_e32 v5, v220, v5, vcc
	v_cmp_ngt_f32_e32 vcc, -1.0, v26
	v_and_b32_e32 v27, 63, v2
	v_ashrrev_i32_e32 v28, 6, v2
	v_cndmask_b32_e32 v5, v221, v5, vcc
	v_cmp_neq_f32_e32 vcc, -1.0, v26
	s_nop 1
	v_cndmask_b32_e32 v5, v222, v5, vcc
	v_cmp_lt_f32_e64 vcc, |v26|, s6
	s_nop 1
	v_cndmask_b32_e32 v5, v5, v26, vcc
	v_sub_f32_e32 v3, v3, v5
	v_add_f32_e32 v23, v22, v3
	v_and_b32_e32 v3, 64, v218
	v_cmp_lt_i32_e32 vcc, v0, v3
	v_add_u32_e32 v5, -2, v218
	v_cmp_lt_i32_e64 s[0:1], v5, v3
	v_cndmask_b32_e32 v0, v0, v218, vcc
	v_lshlrev_b32_e32 v0, 2, v0
	ds_bpermute_b32 v0, v0, v23
	v_cmp_eq_u32_e32 vcc, 0, v27
	v_cndmask_b32_e64 v5, v5, v218, s[0:1]
	v_lshlrev_b32_e32 v5, 2, v5
	v_cmp_gt_u32_e64 s[0:1], 2, v27
	s_waitcnt lgkmcnt(0)
; __device__ void fcum_unit(unsigned char* lds, int bh, const float* scal, const float* fgb  , float* F, const bf16_t* kp  , float* knsuf  , const bf16_t* kpa  , const float* relh  , float* ab  , unsigned* flag, unsigned fval) {
;     ...
;     for (int o = 1; o < 64; o <<= 1) { const float y = __shfl_up(inc, o); if (lane >= o) inc += y; }
;     if (lane == 63) wt[wid] = inc;
;     __syncthreads();
;     float off = inc - run;
;     for (int w = 0; w < wid; ++w) off += wt[w];
	v_add_f32_e32 v0, v23, v0
	v_cndmask_b32_e32 v0, v0, v23, vcc
	ds_bpermute_b32 v5, v5, v0
	v_lshl_add_u32 v26, v28, 2, 0
	s_waitcnt lgkmcnt(0)
	v_add_f32_e32 v5, v0, v5
	v_cndmask_b32_e64 v0, v5, v0, s[0:1]
	v_add_u32_e32 v5, -4, v218
	v_cmp_lt_i32_e64 s[0:1], v5, v3
	s_nop 1
	v_cndmask_b32_e64 v5, v5, v218, s[0:1]
	v_lshlrev_b32_e32 v5, 2, v5
	ds_bpermute_b32 v5, v5, v0
	v_cmp_gt_u32_e64 s[0:1], 4, v27
	s_waitcnt lgkmcnt(0)
	v_add_f32_e32 v5, v0, v5
	v_cndmask_b32_e64 v0, v5, v0, s[0:1]
	v_add_u32_e32 v5, -8, v218
	v_cmp_lt_i32_e64 s[0:1], v5, v3
	s_nop 1
	v_cndmask_b32_e64 v5, v5, v218, s[0:1]
	v_lshlrev_b32_e32 v5, 2, v5
	ds_bpermute_b32 v5, v5, v0
	v_cmp_gt_u32_e64 s[0:1], 8, v27
	s_waitcnt lgkmcnt(0)
	v_add_f32_e32 v5, v0, v5
	v_cndmask_b32_e64 v0, v5, v0, s[0:1]
	v_add_u32_e32 v5, -16, v218
	v_cmp_lt_i32_e64 s[0:1], v5, v3
	s_nop 1
	v_cndmask_b32_e64 v5, v5, v218, s[0:1]
	v_lshlrev_b32_e32 v5, 2, v5
	ds_bpermute_b32 v5, v5, v0
	v_cmp_gt_u32_e64 s[0:1], 16, v27
	s_waitcnt lgkmcnt(0)
	v_add_f32_e32 v5, v0, v5
	v_cndmask_b32_e64 v0, v5, v0, s[0:1]
	v_subrev_u32_e32 v5, 32, v218
	v_cmp_lt_i32_e64 s[0:1], v5, v3
	s_nop 1
	v_cndmask_b32_e64 v5, v5, v218, s[0:1]
	v_lshlrev_b32_e32 v5, 2, v5
	ds_bpermute_b32 v5, v5, v0
	v_cmp_eq_u32_e64 s[0:1], 63, v27
	s_waitcnt lgkmcnt(0)
	v_add_f32_e32 v5, v0, v5
	s_and_saveexec_b64 s[4:5], s[0:1]
	ds_write_b32 v26, v5
	s_or_b64 exec, exec, s[4:5]
	v_cmp_gt_u32_e64 s[0:1], 32, v27
	s_waitcnt lgkmcnt(0)
	s_barrier
	v_cndmask_b32_e64 v0, v5, v0, s[0:1]
	v_sub_f32_e32 v24, v0, v23
	v_cmp_lt_i32_e64 s[0:1], 0, v28
	s_and_saveexec_b64 s[4:5], s[0:1]
	s_cbranch_execz .LBB0_627
	s_mov_b32 s8, 0
	s_mov_b64 s[6:7], 0
	v_mov_b32_e32 v0, v28

; __device__ void fcum_unit(unsigned char* lds, int bh, const float* scal, const float* fgb  , float* F, const bf16_t* kp  , float* knsuf  , const bf16_t* kpa  , const float* relh  , float* ab  , unsigned* flag, unsigned fval) {
;     ...
;     for (int i = 0; i < 16; ++i) F[(size_t)bh * SEQ + tid * 16 + i] = v[i] + off;
;     float* km = (float*)(lds + 1024);
;     for (int t = wid; t < 128; t += 8) {
;         const bf16_t* kr = kp + (size_t)(t * 64 + lane) * 1536; float ss = 0.f;
; #pragma unroll
;         for (int q = 0; q < 8; ++q) { float f[8]; unpack8(*(const u32x4*)(kr + 8 * q), f);
; #pragma unroll
;             for (int j = 0; j < 8; ++j) ss += f[j] * f[j]; }
;         float m = sqrtf(ss);
; #pragma unroll
;         for (int o = 32; o > 0; o >>= 1) m = fmaxf(m, __shfl_xor(m, o));
.LBB0_627:
	s_or_b64 exec, exec, s[4:5]
	v_readlane_b32 s0, v255, 13
	v_readlane_b32 s1, v255, 14
	v_ashrrev_i32_e32 v91, 31, v90
	v_pk_add_f32 v[8:9], v[8:9], v[24:25] op_sel_hi:[1,0]
	v_mov_b64_e32 v[30:31], s[0:1]
	s_mov_b32 s0, 0x1800000
	v_mad_i64_i32 v[4:5], s[0:1], v4, s0, v[30:31]
	v_readlane_b32 s0, v255, 23
	v_lshlrev_b64 v[30:31], 15, v[90:91]
	v_readlane_b32 s1, v255, 24
	v_lshlrev_b32_e32 v0, 7, v25
	v_pk_add_f32 v[10:11], v[10:11], v[24:25] op_sel_hi:[1,0]
	v_lshl_add_u64 v[30:31], s[0:1], 0, v[30:31]
	v_lshl_add_u64 v[30:31], v[6:7], 2, v[30:31]
	v_pk_add_f32 v[6:7], v[14:15], v[24:25] op_sel_hi:[1,0]
	global_store_dwordx4 v[30:31], v[6:9], off offset:16
	v_pk_add_f32 v[12:13], v[12:13], v[24:25] op_sel_hi:[1,0]
	v_lshl_add_u64 v[4:5], v[4:5], 0, v[0:1]
	v_pk_add_f32 v[6:7], v[16:17], v[24:25] op_sel_hi:[1,0]
	v_pk_add_f32 v[8:9], v[18:19], v[24:25] op_sel_hi:[1,0]
	global_store_dwordx4 v[30:31], v[6:9], off offset:32
	global_store_dwordx4 v[30:31], v[10:13], off
	v_cmp_gt_i32_e64 s[6:7], s46, v28
	v_pk_add_f32 v[6:7], v[20:21], v[24:25] op_sel_hi:[1,0]
	v_pk_add_f32 v[8:9], v[22:23], v[24:25] op_sel_hi:[1,0]
	global_store_dwordx4 v[30:31], v[6:9], off offset:48
	v_add_u32_e32 v0, 64, v3
	v_xor_b32_e32 v13, 32, v218
	v_xor_b32_e32 v12, 16, v218
	v_xor_b32_e32 v11, 8, v218
	v_xor_b32_e32 v10, 4, v218
	v_xor_b32_e32 v9, 2, v218
	v_xor_b32_e32 v8, 1, v218
	v_add_u32_e32 v14, -8, v28
	v_lshl_or_b32 v15, v28, 6, v27
	s_and_saveexec_b64 s[10:11], s[6:7]
	s_cbranch_execz .LBB0_632
	v_cmp_lt_i32_e64 s[0:1], v13, v0
	v_add_u32_e32 v22, -8, v28
	v_lshl_or_b32 v23, v28, 6, v27
	v_cndmask_b32_e64 v3, v218, v13, s[0:1]
	v_cmp_lt_i32_e64 s[0:1], v12, v0
	v_lshlrev_b32_e32 v3, 2, v3
	s_mov_b64 s[12:13], 0
	v_cndmask_b32_e64 v6, v218, v12, s[0:1]
	v_cmp_lt_i32_e64 s[0:1], v11, v0
	v_lshlrev_b32_e32 v16, 2, v6
	s_nop 0
	v_cndmask_b32_e64 v6, v218, v11, s[0:1]
	v_cmp_lt_i32_e64 s[0:1], v10, v0
	v_lshlrev_b32_e32 v17, 2, v6
	s_nop 0
	v_cndmask_b32_e64 v6, v218, v10, s[0:1]
	v_cmp_lt_i32_e64 s[0:1], v9, v0
	v_lshlrev_b32_e32 v18, 2, v6
	s_nop 0
	v_cndmask_b32_e64 v6, v218, v9, s[0:1]
	v_cmp_lt_i32_e64 s[0:1], v8, v0
	v_lshlrev_b32_e32 v19, 2, v6
	s_nop 0
	v_cndmask_b32_e64 v6, v218, v8, s[0:1]
	s_add_i32 s0, 0, 0x400
	v_lshlrev_b32_e32 v20, 2, v6
	v_lshl_add_u32 v21, v28, 2, s0
	s_branch .LBB0_630

; __device__ void fcum_unit(unsigned char* lds, int bh, const float* scal, const float* fgb  , float* F, const bf16_t* kp  , float* knsuf  , const bf16_t* kpa  , const float* relh  , float* ab  , unsigned* flag, unsigned fval) {
;     ...
;     for (int t = wid; t < 128; t += 8) {
;         const bf16_t* kr = kp + (size_t)(t * 64 + lane) * 1536; float ss = 0.f;
; #pragma unroll
;         for (int q = 0; q < 8; ++q) { float f[8]; unpack8(*(const u32x4*)(kr + 8 * q), f);
; #pragma unroll
;             for (int j = 0; j < 8; ++j) ss += f[j] * f[j]; }
;         float m = sqrtf(ss);
; #pragma unroll
;         for (int o = 32; o > 0; o >>= 1) m = fmaxf(m, __shfl_xor(m, o));
;         if (lane == 0) km[t] = m;
;     }
.LBB0_630:
	s_waitcnt lgkmcnt(0)
	v_mad_i64_i32 v[6:7], s[0:1], v23, s53, v[4:5]
	global_load_dwordx4 v[28:31], v[6:7], off offset:2048
	s_waitcnt vmcnt(0) lgkmcnt(0)
	v_and_b32_e32 v24, 0xffff0000, v28
	v_lshlrev_b32_e32 v27, 16, v28
	v_mul_f32_e32 v24, v24, v24
	v_lshlrev_b32_e32 v28, 16, v29
	v_fmac_f32_e32 v24, v27, v27
	v_and_b32_e32 v29, 0xffff0000, v29
	v_fmac_f32_e32 v24, v28, v28
	v_lshlrev_b32_e32 v32, 16, v30
	v_fmac_f32_e32 v24, v29, v29
	v_and_b32_e32 v30, 0xffff0000, v30
	v_fmac_f32_e32 v24, v32, v32
	v_lshlrev_b32_e32 v33, 16, v31
	v_fmac_f32_e32 v24, v30, v30
	v_and_b32_e32 v31, 0xffff0000, v31
	v_fmac_f32_e32 v24, v33, v33
	v_fmac_f32_e32 v24, v31, v31
	global_load_dwordx4 v[28:31], v[6:7], off offset:2064
	s_waitcnt vmcnt(0) lgkmcnt(0)
	v_lshlrev_b32_e32 v27, 16, v28
	v_and_b32_e32 v28, 0xffff0000, v28
	v_fmac_f32_e32 v24, v27, v27
	v_lshlrev_b32_e32 v32, 16, v29
	v_fmac_f32_e32 v24, v28, v28
	v_and_b32_e32 v29, 0xffff0000, v29
	v_fmac_f32_e32 v24, v32, v32
	v_lshlrev_b32_e32 v33, 16, v30
	v_fmac_f32_e32 v24, v29, v29
	v_and_b32_e32 v30, 0xffff0000, v30
	v_fmac_f32_e32 v24, v33, v33
	v_lshlrev_b32_e32 v34, 16, v31
	v_fmac_f32_e32 v24, v30, v30
	v_and_b32_e32 v31, 0xffff0000, v31
	v_fmac_f32_e32 v24, v34, v34
	v_fmac_f32_e32 v24, v31, v31
	global_load_dwordx4 v[28:31], v[6:7], off offset:2080
	s_waitcnt vmcnt(0) lgkmcnt(0)
	v_lshlrev_b32_e32 v27, 16, v28
	v_and_b32_e32 v28, 0xffff0000, v28
	v_fmac_f32_e32 v24, v27, v27
	v_lshlrev_b32_e32 v32, 16, v29
	v_fmac_f32_e32 v24, v28, v28
	v_and_b32_e32 v29, 0xffff0000, v29
	v_fmac_f32_e32 v24, v32, v32
	v_lshlrev_b32_e32 v33, 16, v30
	v_fmac_f32_e32 v24, v29, v29
	v_and_b32_e32 v30, 0xffff0000, v30
	v_fmac_f32_e32 v24, v33, v33
	v_lshlrev_b32_e32 v34, 16, v31
	v_fmac_f32_e32 v24, v30, v30
	v_and_b32_e32 v31, 0xffff0000, v31
	v_fmac_f32_e32 v24, v34, v34
	v_fmac_f32_e32 v24, v31, v31
	global_load_dwordx4 v[28:31], v[6:7], off offset:2096
	s_waitcnt vmcnt(0) lgkmcnt(0)
	v_lshlrev_b32_e32 v27, 16, v28
	v_and_b32_e32 v28, 0xffff0000, v28
	v_fmac_f32_e32 v24, v27, v27
	v_lshlrev_b32_e32 v32, 16, v29
	v_fmac_f32_e32 v24, v28, v28
	v_and_b32_e32 v29, 0xffff0000, v29
	v_fmac_f32_e32 v24, v32, v32
	v_lshlrev_b32_e32 v33, 16, v30
	v_fmac_f32_e32 v24, v29, v29
	v_and_b32_e32 v30, 0xffff0000, v30
	v_fmac_f32_e32 v24, v33, v33
	v_lshlrev_b32_e32 v34, 16, v31
	v_fmac_f32_e32 v24, v30, v30
	v_and_b32_e32 v31, 0xffff0000, v31
	v_fmac_f32_e32 v24, v34, v34
	v_fmac_f32_e32 v24, v31, v31
	global_load_dwordx4 v[28:31], v[6:7], off offset:2112
	s_waitcnt vmcnt(0) lgkmcnt(0)
	v_lshlrev_b32_e32 v27, 16, v28
	v_and_b32_e32 v28, 0xffff0000, v28
	v_fmac_f32_e32 v24, v27, v27
	v_lshlrev_b32_e32 v32, 16, v29
	v_fmac_f32_e32 v24, v28, v28
	v_and_b32_e32 v29, 0xffff0000, v29
	v_fmac_f32_e32 v24, v32, v32
	v_lshlrev_b32_e32 v33, 16, v30
	v_fmac_f32_e32 v24, v29, v29
	v_and_b32_e32 v30, 0xffff0000, v30
	v_fmac_f32_e32 v24, v33, v33
	v_lshlrev_b32_e32 v34, 16, v31
	v_fmac_f32_e32 v24, v30, v30
	v_and_b32_e32 v31, 0xffff0000, v31
	v_fmac_f32_e32 v24, v34, v34
	v_fmac_f32_e32 v24, v31, v31
	global_load_dwordx4 v[28:31], v[6:7], off offset:2128
	s_waitcnt vmcnt(0) lgkmcnt(0)
	v_lshlrev_b32_e32 v27, 16, v28
	v_and_b32_e32 v28, 0xffff0000, v28
	v_fmac_f32_e32 v24, v27, v27
	v_lshlrev_b32_e32 v32, 16, v29
	v_fmac_f32_e32 v24, v28, v28
	v_and_b32_e32 v29, 0xffff0000, v29
	v_fmac_f32_e32 v24, v32, v32
	v_lshlrev_b32_e32 v33, 16, v30
	v_fmac_f32_e32 v24, v29, v29
	v_and_b32_e32 v30, 0xffff0000, v30
	v_fmac_f32_e32 v24, v33, v33
	v_lshlrev_b32_e32 v34, 16, v31
	v_fmac_f32_e32 v24, v30, v30
	v_and_b32_e32 v31, 0xffff0000, v31
	v_fmac_f32_e32 v24, v34, v34
	v_fmac_f32_e32 v24, v31, v31
	global_load_dwordx4 v[28:31], v[6:7], off offset:2144
	s_waitcnt vmcnt(0) lgkmcnt(0)
	v_lshlrev_b32_e32 v27, 16, v28
	v_and_b32_e32 v28, 0xffff0000, v28
	v_fmac_f32_e32 v24, v27, v27
	v_lshlrev_b32_e32 v32, 16, v29
	v_fmac_f32_e32 v24, v28, v28
	v_and_b32_e32 v29, 0xffff0000, v29
	v_fmac_f32_e32 v24, v32, v32
	v_lshlrev_b32_e32 v33, 16, v30
	v_fmac_f32_e32 v24, v29, v29
	v_and_b32_e32 v30, 0xffff0000, v30
	v_fmac_f32_e32 v24, v33, v33
	v_lshlrev_b32_e32 v34, 16, v31
	v_fmac_f32_e32 v24, v30, v30
	v_and_b32_e32 v31, 0xffff0000, v31
	v_fmac_f32_e32 v24, v34, v34
	v_fmac_f32_e32 v24, v31, v31
	global_load_dwordx4 v[28:31], v[6:7], off offset:2160
	s_waitcnt vmcnt(0) lgkmcnt(0)
	v_lshlrev_b32_e32 v6, 16, v28
	v_and_b32_e32 v7, 0xffff0000, v28
	v_fmac_f32_e32 v24, v6, v6
	v_lshlrev_b32_e32 v27, 16, v29
	v_fmac_f32_e32 v24, v7, v7
	v_and_b32_e32 v28, 0xffff0000, v29
	v_fmac_f32_e32 v24, v27, v27
	v_lshlrev_b32_e32 v29, 16, v30
	v_fmac_f32_e32 v24, v28, v28
	v_and_b32_e32 v30, 0xffff0000, v30
	v_fmac_f32_e32 v24, v29, v29
	v_lshlrev_b32_e32 v32, 16, v31
	v_fmac_f32_e32 v24, v30, v30
	v_and_b32_e32 v31, 0xffff0000, v31
	v_fmac_f32_e32 v24, v32, v32
	v_fmac_f32_e32 v24, v31, v31
	v_cmp_gt_f32_e64 s[0:1], s50, v24
	v_mul_f32_e32 v6, 0x4f800000, v24
	s_nop 0
	v_cndmask_b32_e64 v6, v24, v6, s[0:1]
	v_sqrt_f32_e32 v7, v6
	s_nop 0
	v_add_u32_e32 v24, -1, v7
	v_fma_f32 v27, -v24, v7, v6
	v_cmp_ge_f32_e64 s[8:9], 0, v27
	v_add_u32_e32 v27, 1, v7
	s_nop 0
	v_cndmask_b32_e64 v24, v7, v24, s[8:9]
	v_fma_f32 v7, -v27, v7, v6
	v_cmp_lt_f32_e64 s[8:9], 0, v7
	s_nop 1
	v_cndmask_b32_e64 v7, v24, v27, s[8:9]
	v_mul_f32_e32 v24, 0x37800000, v7
	v_cndmask_b32_e64 v7, v7, v24, s[0:1]
	v_cmp_class_f32_e64 s[0:1], v6, v215
	s_nop 1
	v_cndmask_b32_e64 v6, v7, v6, s[0:1]
	ds_bpermute_b32 v7, v3, v6
	s_waitcnt lgkmcnt(0)
	v_max_f32_e32 v7, v7, v7
	v_max_f32_e32 v6, v6, v7
	ds_bpermute_b32 v7, v16, v6
	s_waitcnt lgkmcnt(0)
	v_max_f32_e32 v7, v7, v7
	v_max_f32_e32 v6, v6, v7
	ds_bpermute_b32 v7, v17, v6
	s_waitcnt lgkmcnt(0)
	v_max_f32_e32 v7, v7, v7
	v_max_f32_e32 v6, v6, v7
	ds_bpermute_b32 v7, v18, v6
	s_waitcnt lgkmcnt(0)
	v_max_f32_e32 v7, v7, v7
	v_max_f32_e32 v6, v6, v7
	ds_bpermute_b32 v7, v19, v6
	s_waitcnt lgkmcnt(0)
	v_max_f32_e32 v7, v7, v7
	v_max_f32_e32 v6, v6, v7
	ds_bpermute_b32 v7, v20, v6
	s_and_saveexec_b64 s[0:1], vcc
	s_cbranch_execz .LBB0_629
	s_waitcnt lgkmcnt(0)
	v_max_f32_e32 v7, v7, v7
	v_max_f32_e32 v6, v6, v6
	v_max_f32_e32 v6, v6, v7
	ds_write_b32 v21, v6
	s_branch .LBB0_629

; __device__ void fcum_unit(unsigned char* lds, int bh, const float* scal, const float* fgb  , float* F, const bf16_t* kp  , float* knsuf  , const bf16_t* kpa  , const float* relh  , float* ab  , unsigned* flag, unsigned fval) {
;     ...
;     if (tid < 128) { float m = 0.f; for (int t = 0; t <= tid; ++t) m = fmaxf(m, km[t]); knsuf[tid] = m; }
.LBB0_643:
	s_or_b64 exec, exec, s[10:11]
	v_lshlrev_b32_e32 v16, 7, v90
	v_readlane_b32 s0, v255, 25
	v_ashrrev_i32_e32 v17, 31, v16
	v_readlane_b32 s1, v255, 26
	v_ashrrev_i32_e32 v3, 31, v2
	s_nop 0
	v_lshl_add_u64 v[16:17], v[16:17], 2, s[0:1]
	v_lshl_add_u64 v[16:17], v[2:3], 2, v[16:17]
	global_store_dword v[16:17], v7, off

; __device__ void fcum_unit(unsigned char* lds, int bh, const float* scal, const float* fgb  , float* F, const bf16_t* kp  , float* knsuf  , const bf16_t* kpa  , const float* relh  , float* ab  , unsigned* flag, unsigned fval) {
;     ...
;       for (int t = wid; t < 128; t += 8) {
;           const bf16_t* kr = kpa + (size_t)(t * 64 + lane) * 1536; float ss = 0.f;
; #pragma unroll
;           for (int q = 0; q < 8; ++q) { float f[8]; unpack8(*(const u32x4*)(kr + 8 * q), f);
; #pragma unroll
;               for (int j = 0; j < 8; ++j) ss += f[j] * f[j]; }
;           mw = fmaxf(mw, sqrtf(ss)); }
.LBB0_646:
	v_mad_i64_i32 v[6:7], s[0:1], v15, s53, v[4:5]
	global_load_dwordx4 v[16:19], v[6:7], off offset:512
	v_add_u32_e32 v14, 8, v14
	v_max_f32_e32 v3, v3, v3
	v_add_u32_e32 v15, 0x200, v15
	s_waitcnt vmcnt(0) lgkmcnt(0)
	v_lshlrev_b32_e32 v20, 16, v16
	v_and_b32_e32 v16, 0xffff0000, v16
	v_mul_f32_e32 v24, v16, v16
	v_lshlrev_b32_e32 v21, 16, v17
	v_fmac_f32_e32 v24, v20, v20
	v_and_b32_e32 v17, 0xffff0000, v17
	v_fmac_f32_e32 v24, v21, v21
	v_lshlrev_b32_e32 v22, 16, v18
	v_fmac_f32_e32 v24, v17, v17
	v_and_b32_e32 v18, 0xffff0000, v18
	v_fmac_f32_e32 v24, v22, v22
	v_lshlrev_b32_e32 v23, 16, v19
	v_fmac_f32_e32 v24, v18, v18
	v_and_b32_e32 v19, 0xffff0000, v19
	v_fmac_f32_e32 v24, v23, v23
	v_fmac_f32_e32 v24, v19, v19
	global_load_dwordx4 v[16:19], v[6:7], off offset:528
	s_waitcnt vmcnt(0) lgkmcnt(0)
	v_lshlrev_b32_e32 v20, 16, v16
	v_and_b32_e32 v16, 0xffff0000, v16
	v_fmac_f32_e32 v24, v20, v20
	v_lshlrev_b32_e32 v21, 16, v17
	v_fmac_f32_e32 v24, v16, v16
	v_and_b32_e32 v17, 0xffff0000, v17
	v_fmac_f32_e32 v24, v21, v21
	v_lshlrev_b32_e32 v22, 16, v18
	v_fmac_f32_e32 v24, v17, v17
	v_and_b32_e32 v18, 0xffff0000, v18
	v_fmac_f32_e32 v24, v22, v22
	v_lshlrev_b32_e32 v23, 16, v19
	v_fmac_f32_e32 v24, v18, v18
	v_and_b32_e32 v19, 0xffff0000, v19
	v_fmac_f32_e32 v24, v23, v23
	v_fmac_f32_e32 v24, v19, v19
	global_load_dwordx4 v[16:19], v[6:7], off offset:544
	s_waitcnt vmcnt(0) lgkmcnt(0)
	v_lshlrev_b32_e32 v20, 16, v16
	v_and_b32_e32 v16, 0xffff0000, v16
	v_fmac_f32_e32 v24, v20, v20
	v_lshlrev_b32_e32 v21, 16, v17
	v_fmac_f32_e32 v24, v16, v16
	v_and_b32_e32 v17, 0xffff0000, v17
	v_fmac_f32_e32 v24, v21, v21
	v_lshlrev_b32_e32 v22, 16, v18
	v_fmac_f32_e32 v24, v17, v17
	v_and_b32_e32 v18, 0xffff0000, v18
	v_fmac_f32_e32 v24, v22, v22
	v_lshlrev_b32_e32 v23, 16, v19
	v_fmac_f32_e32 v24, v18, v18
	v_and_b32_e32 v19, 0xffff0000, v19
	v_fmac_f32_e32 v24, v23, v23
	v_fmac_f32_e32 v24, v19, v19
	global_load_dwordx4 v[16:19], v[6:7], off offset:560
	s_waitcnt vmcnt(0) lgkmcnt(0)
	v_lshlrev_b32_e32 v20, 16, v16
	v_and_b32_e32 v16, 0xffff0000, v16
	v_fmac_f32_e32 v24, v20, v20
	v_lshlrev_b32_e32 v21, 16, v17
	v_fmac_f32_e32 v24, v16, v16
	v_and_b32_e32 v17, 0xffff0000, v17
	v_fmac_f32_e32 v24, v21, v21
	v_lshlrev_b32_e32 v22, 16, v18
	v_fmac_f32_e32 v24, v17, v17
	v_and_b32_e32 v18, 0xffff0000, v18
	v_fmac_f32_e32 v24, v22, v22
	v_lshlrev_b32_e32 v23, 16, v19
	v_fmac_f32_e32 v24, v18, v18
	v_and_b32_e32 v19, 0xffff0000, v19
	v_fmac_f32_e32 v24, v23, v23
	v_fmac_f32_e32 v24, v19, v19
	global_load_dwordx4 v[16:19], v[6:7], off offset:576
	s_waitcnt vmcnt(0) lgkmcnt(0)
	v_lshlrev_b32_e32 v20, 16, v16
	v_and_b32_e32 v16, 0xffff0000, v16
	v_fmac_f32_e32 v24, v20, v20
	v_lshlrev_b32_e32 v21, 16, v17
	v_fmac_f32_e32 v24, v16, v16
	v_and_b32_e32 v17, 0xffff0000, v17
	v_fmac_f32_e32 v24, v21, v21
	v_lshlrev_b32_e32 v22, 16, v18
	v_fmac_f32_e32 v24, v17, v17
	v_and_b32_e32 v18, 0xffff0000, v18
	v_fmac_f32_e32 v24, v22, v22
	v_lshlrev_b32_e32 v23, 16, v19
	v_fmac_f32_e32 v24, v18, v18
	v_and_b32_e32 v19, 0xffff0000, v19
	v_fmac_f32_e32 v24, v23, v23
	v_fmac_f32_e32 v24, v19, v19
	global_load_dwordx4 v[16:19], v[6:7], off offset:592
	s_waitcnt vmcnt(0) lgkmcnt(0)
	v_lshlrev_b32_e32 v20, 16, v16
	v_and_b32_e32 v16, 0xffff0000, v16
	v_fmac_f32_e32 v24, v20, v20
	v_lshlrev_b32_e32 v21, 16, v17
	v_fmac_f32_e32 v24, v16, v16
	v_and_b32_e32 v17, 0xffff0000, v17
	v_fmac_f32_e32 v24, v21, v21
	v_lshlrev_b32_e32 v22, 16, v18
	v_fmac_f32_e32 v24, v17, v17
	v_and_b32_e32 v18, 0xffff0000, v18
	v_fmac_f32_e32 v24, v22, v22
	v_lshlrev_b32_e32 v23, 16, v19
	v_fmac_f32_e32 v24, v18, v18
	v_and_b32_e32 v19, 0xffff0000, v19
	v_fmac_f32_e32 v24, v23, v23
	v_fmac_f32_e32 v24, v19, v19
	global_load_dwordx4 v[16:19], v[6:7], off offset:608
	s_waitcnt vmcnt(0) lgkmcnt(0)
	v_lshlrev_b32_e32 v20, 16, v16
	v_and_b32_e32 v16, 0xffff0000, v16
	v_fmac_f32_e32 v24, v20, v20
	v_lshlrev_b32_e32 v21, 16, v17
	v_fmac_f32_e32 v24, v16, v16
	v_and_b32_e32 v17, 0xffff0000, v17
	v_fmac_f32_e32 v24, v21, v21
	v_lshlrev_b32_e32 v22, 16, v18
	v_fmac_f32_e32 v24, v17, v17
	v_and_b32_e32 v18, 0xffff0000, v18
	v_fmac_f32_e32 v24, v22, v22
	v_and_b32_e32 v16, 0xffff0000, v19
	v_lshlrev_b32_e32 v17, 16, v19
	v_fmac_f32_e32 v24, v18, v18
	v_pk_mul_f32 v[16:17], v[16:17], v[16:17]
	s_nop 0
	v_add_f32_e32 v17, v17, v24
	v_add_f32_e32 v20, v16, v17
	global_load_dwordx4 v[16:19], v[6:7], off offset:624
	s_waitcnt vmcnt(0) lgkmcnt(0)
	v_and_b32_e32 v6, 0xffff0000, v16
	v_lshlrev_b32_e32 v7, 16, v16
	v_pk_mul_f32 v[6:7], v[6:7], v[6:7]
	s_nop 0
	v_add_f32_e32 v7, v7, v20
	v_add_f32_e32 v16, v6, v7
	v_and_b32_e32 v6, 0xffff0000, v17
	v_lshlrev_b32_e32 v7, 16, v17
	v_pk_mul_f32 v[6:7], v[6:7], v[6:7]
	s_nop 0
	v_add_f32_e32 v7, v7, v16
	v_add_f32_e32 v16, v6, v7
	v_and_b32_e32 v6, 0xffff0000, v18
	v_lshlrev_b32_e32 v7, 16, v18
	v_pk_mul_f32 v[6:7], v[6:7], v[6:7]
	s_nop 0
	v_add_f32_e32 v7, v7, v16
	v_add_f32_e32 v16, v6, v7
	v_and_b32_e32 v6, 0xffff0000, v19
	v_lshlrev_b32_e32 v7, 16, v19
	v_pk_mul_f32 v[6:7], v[6:7], v[6:7]
	s_nop 0
	v_add_f32_e32 v7, v7, v16
	v_add_f32_e32 v6, v6, v7
	v_cmp_gt_f32_e64 s[0:1], s50, v6
	v_mul_f32_e32 v7, 0x4f800000, v6
	s_nop 0
	v_cndmask_b32_e64 v6, v6, v7, s[0:1]
	v_sqrt_f32_e32 v7, v6
	s_nop 0
	v_add_u32_e32 v16, -1, v7
	v_fma_f32 v17, -v16, v7, v6
	v_cmp_ge_f32_e64 s[6:7], 0, v17
	v_add_u32_e32 v17, 1, v7
	s_nop 0
	v_cndmask_b32_e64 v16, v7, v16, s[6:7]
	v_fma_f32 v7, -v17, v7, v6
	v_cmp_lt_f32_e64 s[6:7], 0, v7
	s_nop 1
	v_cndmask_b32_e64 v7, v16, v17, s[6:7]
	v_mul_f32_e32 v16, 0x37800000, v7
	v_cndmask_b32_e64 v7, v7, v16, s[0:1]
	v_cmp_class_f32_e64 s[0:1], v6, v215
	s_nop 1
	v_cndmask_b32_e64 v6, v7, v6, s[0:1]
	v_cmp_lt_i32_e64 s[0:1], s84, v14
	v_max_f32_e32 v3, v3, v6
	s_or_b64 s[10:11], s[0:1], s[10:11]
	s_andn2_b64 exec, exec, s[10:11]
	s_cbranch_execnz .LBB0_646
	s_or_b64 exec, exec, s[10:11]

; __device__ void fcum_unit(unsigned char* lds, int bh, const float* scal, const float* fgb  , float* F, const bf16_t* kp  , float* knsuf  , const bf16_t* kpa  , const float* relh  , float* ab  , unsigned* flag, unsigned fval) {
;     ...
;       float bm = -1e30f;
;       for (int i = tid; i < 320; i += NTHR) bm = fmaxf(bm, relh[i] * LOG2E);
.LBB0_651:
	v_ashrrev_i32_e32 v21, 31, v6
	v_mov_b32_e32 v20, v6
	v_mov_b32_e32 v17, v18
	v_ashrrev_i32_e32 v19, 31, v7
	v_mov_b32_e32 v18, v7
	v_lshl_add_u64 v[20:21], v[20:21], 2, v[4:5]
	v_lshl_add_u64 v[18:19], v[18:19], 2, v[4:5]
	global_load_dword v20, v[20:21], off
	s_nop 0
	global_load_dword v21, v[18:19], off
	s_mov_b32 s0, 0x3fb8aa3b
	v_mov_b32_e32 v19, v3
	v_max_f32_e32 v3, v19, v19
	v_max_f32_e32 v18, v17, v17
	v_cmp_eq_u32_e64 s[6:7], s14, v16
	s_add_i32 s14, s14, 2
	v_add_u32_e32 v7, 0x400, v7
	v_add_u32_e32 v6, 0x400, v6
	s_waitcnt vmcnt(0) lgkmcnt(0)
	v_pk_mul_f32 v[20:21], v[20:21], s[0:1] op_sel_hi:[1,0]
	s_nop 0
	v_cmp_u_f32_e64 s[0:1], v21, v21
	v_max_f32_e32 v3, v3, v21
	v_max_f32_e32 v18, v18, v20
	v_cndmask_b32_e64 v21, 0, 1, s[0:1]
	v_cmp_u_f32_e64 s[0:1], v20, v20
	v_lshlrev_b16_e32 v21, 1, v21
	s_nop 0
	v_cndmask_b32_e64 v20, 0, 1, s[0:1]
	v_bitop3_b16 v20, v20, 3, v21 bitop3:0xc8
	v_cmp_ne_u16_e64 s[0:1], 0, v20
	s_or_b64 s[6:7], s[0:1], s[6:7]
	s_and_b64 s[6:7], exec, s[6:7]
	s_or_b64 s[12:13], s[6:7], s[12:13]
	s_andn2_b64 s[6:7], s[10:11], exec
	s_and_b64 s[0:1], s[0:1], exec
	v_mov_b32_e32 v20, s14
	s_or_b64 s[10:11], s[6:7], s[0:1]
	s_andn2_b64 exec, exec, s[12:13]
	s_cbranch_execnz .LBB0_651
	s_or_b64 exec, exec, s[12:13]
	v_add_u32_e32 v4, -4, v20
	v_cndmask_b32_e64 v5, v18, v17, s[10:11]
	v_cndmask_b32_e64 v3, v3, v19, s[10:11]
	v_cmp_ne_u32_e64 s[0:1], v15, v16
	v_cndmask_b32_e64 v4, v16, v4, s[10:11]
	v_max_f32_e32 v3, v3, v3
	v_max_f32_e32 v5, v5, v5
	s_or_b64 s[0:1], s[0:1], s[10:11]
	v_max_f32_e32 v3, v5, v3
	v_lshl_add_u32 v4, v4, 9, v2
	s_orn2_b64 s[10:11], s[0:1], exec

; __device__ void fcum_unit(unsigned char* lds, int bh, const float* scal, const float* fgb  , float* F, const bf16_t* kp  , float* knsuf  , const bf16_t* kpa  , const float* relh  , float* ab  , unsigned* flag, unsigned fval) {
;     ...
;       for (int i = tid; i < 320; i += NTHR) bm = fmaxf(bm, relh[i] * LOG2E);
.LBB0_655:
	global_load_dword v7, v[4:5], off
	v_add_u32_e32 v6, 0x200, v6
	s_movk_i32 s0, 0xff3f
	v_max_f32_e32 v3, v3, v3
	v_cmp_lt_i32_e64 s[0:1], s0, v6
	v_lshl_add_u64 v[4:5], v[4:5], 0, s[94:95]
	s_or_b64 s[8:9], s[0:1], s[8:9]
	s_waitcnt vmcnt(0) lgkmcnt(0)
	v_mul_f32_e32 v7, 0x3fb8aa3b, v7
	v_max_f32_e32 v3, v3, v7
	s_andn2_b64 exec, exec, s[8:9]
	s_cbranch_execnz .LBB0_655
	s_or_b64 exec, exec, s[8:9]

; __device__ __forceinline__ void handoff_publish(unsigned* flag, unsigned val) {
;     asm volatile("s_waitcnt vmcnt(0)" ::: "memory");
;     __syncthreads();
;     if (threadIdx.x == 0) {
;         __builtin_amdgcn_fence(__ATOMIC_RELEASE, "agent");
;         asm volatile("s_waitcnt vmcnt(0)" ::: "memory");
;         __hip_atomic_store(flag, val, __ATOMIC_RELAXED, __HIP_MEMORY_SCOPE_AGENT);
;     }
; __device__ void fcum_unit(unsigned char* lds, int bh, const float* scal, const float* fgb  , float* F, const bf16_t* kp  , float* knsuf  , const bf16_t* kpa  , const float* relh  , float* ab  , unsigned* flag, unsigned fval) {
;     ...
;       if (lane == 0) { km2[wid] = mw; km2[8 + wid] = bm; }
;       __syncthreads();
;       if (tid == 0) { float a = 0.f, c = -1e30f; for (int w = 0; w < 8; ++w) { a = fmaxf(a, km2[w]); c = fmaxf(c, km2[8 + w]); } ab[0] = a * 1.0001f; ab[1] = c; }
;     }
;     handoff_publish(flag, fval);
.LBB0_660:
	s_or_b64 exec, exec, s[0:1]
	v_cmp_eq_u32_e32 vcc, 0, v2
	s_waitcnt lgkmcnt(0)
	s_barrier
	s_and_saveexec_b64 s[0:1], vcc
	s_cbranch_execz .LBB0_662
	v_lshlrev_b32_e32 v10, 1, v90
	ds_read_b128 v[2:5], v1 offset:2048
	ds_read_b128 v[6:9], v1 offset:2080
	v_readlane_b32 s4, v255, 33
	v_ashrrev_i32_e32 v11, 31, v10
	v_readlane_b32 s5, v255, 34
	s_waitcnt lgkmcnt(0)
	v_max3_f32 v0, v2, 0, v3
	v_max3_f32 v0, v0, v4, v5
	v_lshl_add_u64 v[18:19], v[10:11], 2, s[4:5]
	ds_read_b128 v[10:13], v1 offset:2064
	ds_read_b128 v[14:17], v1 offset:2096
	s_mov_b32 s4, 0xf149f2ca
	v_max3_f32 v2, v6, s4, v7
	v_max3_f32 v2, v2, v8, v9
	s_waitcnt lgkmcnt(0)
	v_max3_f32 v0, v0, v10, v11
	v_max3_f32 v2, v2, v14, v15
	v_max3_f32 v0, v0, v12, v13
	v_max3_f32 v3, v2, v16, v17
	v_mul_f32_e32 v2, 0x3f800347, v0
	global_store_dwordx2 v[18:19], v[2:3], off
.LBB0_662:
	s_or_b64 exec, exec, s[0:1]
	s_waitcnt vmcnt(0)
	s_waitcnt lgkmcnt(0)
	s_barrier
	s_mov_b64 s[0:1], exec
	v_readlane_b32 s4, v254, 1
	v_readlane_b32 s5, v254, 2
	s_and_b64 s[4:5], s[0:1], s[4:5]
	s_mov_b64 exec, s[4:5]
	s_cbranch_execz .LBB0_171
	v_readlane_b32 s4, v255, 27
	buffer_wbl2 sc1
	s_waitcnt vmcnt(0)
	s_waitcnt vmcnt(0)
	v_readlane_b32 s5, v255, 28
	s_nop 1
	v_lshl_add_u64 v[2:3], v[90:91], 2, s[4:5]
	global_store_dword v[2:3], v226, off sc1
	s_branch .LBB0_171

; __device__ __forceinline__ unsigned cvt_pk_bf16(float lo, float hi) { f32x2_t_ v = {lo, hi}; bf16x2_t_ b = __builtin_convertvector(v, bf16x2_t_); return __builtin_bit_cast(unsigned, b); }
;     __device__ __forceinline__ void operator()(const f32x4 (&acc)[2][2][4][2], const Unit& u, int wr, int wc, int fr, int fq) const {
;         bf16_t* base; int ldc, colt; float sc = 1.f;
;         if (u.pn < 6) { base = pab; ldc = 1536; colt = u.pn * 256; if (u.pn == 0 || u.pn == 3) sc = QSCALE; }
;         else if (u.pn < 12) { base = pc; ldc = 1536; colt = (u.pn - 6) * 256; }
;         else { base = pz; ldc = 512; colt = (u.pn - 12) * 256; }
;         const int row0 = u.pm * BM + wr * 64 + fr, col0 = colt + wc * 32 + 8 * fq;
; #pragma unroll
;         for (int ai = 0; ai < 2; ++ai)
; #pragma unroll
;             for (int m = 0; m < 4; ++m) { bf16_t* rowp = base + (size_t)(row0 + ai * HALF + m * 16) * ldc + col0;
; #pragma unroll
;                 for (int bj = 0; bj < 2; ++bj) { const f32x4 v0 = acc[ai][bj][m][0] * sc, v1 = acc[ai][bj][m][1] * sc;
;                     u32x4 w; w.x = cvt_pk_bf16(v0[0], v0[1]); w.y = cvt_pk_bf16(v0[2], v0[3]); w.z = cvt_pk_bf16(v1[0], v1[1]); w.w = cvt_pk_bf16(v1[2], v1[3]);
;                     *(u32x4*)(rowp + bj * HALF) = w; } }
;     }
.LBB0_694:
	v_lshl_add_u32 v150, s20, 8, v142
	v_add_u32_e32 v140, s15, v144
	v_ashrrev_i32_e32 v141, 31, v140
	v_ashrrev_i32_e32 v146, 31, v150
	v_lshl_add_u64 v[140:141], v[140:141], 1, s[28:29]
	v_mul_lo_u32 v151, s22, v146
	v_mul_lo_u32 v148, s23, v150
	v_mad_u64_u32 v[146:147], s[28:29], s22, v150, 0
	v_add3_u32 v147, v147, v151, v148
	v_pk_mul_f32 v[128:129], v[128:129], s[24:25] op_sel_hi:[1,0]
	v_pk_mul_f32 v[126:127], v[126:127], s[24:25] op_sel_hi:[1,0]
	v_pk_mul_f32 v[148:149], v[124:125], s[24:25] op_sel_hi:[1,0]
	v_pk_mul_f32 v[124:125], v[122:123], s[24:25] op_sel_hi:[1,0]
	v_lshl_add_u64 v[146:147], v[146:147], 1, v[140:141]
	v_cvt_pk_bf16_f32 v122, v126, v127
	v_cvt_pk_bf16_f32 v123, v128, v129
	v_cvt_pk_bf16_f32 v124, v124, v125
	v_cvt_pk_bf16_f32 v125, v148, v149
	global_store_dwordx4 v[146:147], v[122:125], off
	v_pk_mul_f32 v[116:117], v[116:117], s[24:25] op_sel_hi:[1,0]
	v_pk_mul_f32 v[114:115], v[114:115], s[24:25] op_sel_hi:[1,0]
	v_pk_mul_f32 v[122:123], v[108:109], s[24:25] op_sel_hi:[1,0]
	v_pk_mul_f32 v[108:109], v[106:107], s[24:25] op_sel_hi:[1,0]
	v_cvt_pk_bf16_f32 v106, v114, v115
	v_cvt_pk_bf16_f32 v107, v116, v117
	v_cvt_pk_bf16_f32 v108, v108, v109
	v_cvt_pk_bf16_f32 v109, v122, v123
	global_store_dwordx4 v[146:147], v[106:109], off offset:256
	v_pk_mul_f32 v[112:113], v[112:113], s[24:25] op_sel_hi:[1,0]
	v_pk_mul_f32 v[110:111], v[110:111], s[24:25] op_sel_hi:[1,0]
	v_or_b32_e32 v106, 16, v150
	v_mul_lo_u32 v108, s23, v106
	v_mad_u64_u32 v[106:107], s[28:29], s22, v106, 0
	v_add3_u32 v107, v107, v151, v108
	v_lshl_add_u64 v[114:115], v[106:107], 1, v[140:141]
	v_pk_mul_f32 v[108:109], v[120:121], s[24:25] op_sel_hi:[1,0]
	v_pk_mul_f32 v[106:107], v[118:119], s[24:25] op_sel_hi:[1,0]
	v_pk_mul_f32 v[100:101], v[100:101], s[24:25] op_sel_hi:[1,0]
	v_cvt_pk_bf16_f32 v106, v106, v107
	v_cvt_pk_bf16_f32 v107, v108, v109
	v_cvt_pk_bf16_f32 v108, v110, v111
	v_cvt_pk_bf16_f32 v109, v112, v113
	global_store_dwordx4 v[114:115], v[106:109], off
	v_pk_mul_f32 v[98:99], v[98:99], s[24:25] op_sel_hi:[1,0]
	v_pk_mul_f32 v[96:97], v[96:97], s[24:25] op_sel_hi:[1,0]
	v_pk_mul_f32 v[106:107], v[92:93], s[24:25] op_sel_hi:[1,0]
	v_pk_mul_f32 v[92:93], v[90:91], s[24:25] op_sel_hi:[1,0]
	v_cvt_pk_bf16_f32 v90, v98, v99
	v_cvt_pk_bf16_f32 v91, v100, v101
	v_cvt_pk_bf16_f32 v92, v92, v93
	v_cvt_pk_bf16_f32 v93, v106, v107
	global_store_dwordx4 v[114:115], v[90:93], off offset:256
	v_pk_mul_f32 v[94:95], v[94:95], s[24:25] op_sel_hi:[1,0]
	v_pk_mul_f32 v[84:85], v[84:85], s[24:25] op_sel_hi:[1,0]
	v_or_b32_e32 v90, 32, v150
	v_mul_lo_u32 v92, s23, v90
	v_mad_u64_u32 v[90:91], s[28:29], s22, v90, 0
	v_add3_u32 v91, v91, v151, v92
	v_lshl_add_u64 v[98:99], v[90:91], 1, v[140:141]
	v_pk_mul_f32 v[92:93], v[104:105], s[24:25] op_sel_hi:[1,0]
	v_pk_mul_f32 v[90:91], v[102:103], s[24:25] op_sel_hi:[1,0]
	v_pk_mul_f32 v[82:83], v[82:83], s[24:25] op_sel_hi:[1,0]
	v_cvt_pk_bf16_f32 v90, v90, v91
	v_cvt_pk_bf16_f32 v91, v92, v93
	v_cvt_pk_bf16_f32 v92, v94, v95
	v_cvt_pk_bf16_f32 v93, v96, v97
	global_store_dwordx4 v[98:99], v[90:93], off
	v_pk_mul_f32 v[80:81], v[80:81], s[24:25] op_sel_hi:[1,0]
	v_pk_mul_f32 v[78:79], v[78:79], s[24:25] op_sel_hi:[1,0]
	v_pk_mul_f32 v[90:91], v[76:77], s[24:25] op_sel_hi:[1,0]
	v_pk_mul_f32 v[76:77], v[74:75], s[24:25] op_sel_hi:[1,0]
	v_cvt_pk_bf16_f32 v74, v82, v83
	v_cvt_pk_bf16_f32 v75, v84, v85
	v_cvt_pk_bf16_f32 v76, v76, v77
	v_cvt_pk_bf16_f32 v77, v90, v91
	global_store_dwordx4 v[98:99], v[74:77], off offset:256
	v_pk_mul_f32 v[72:73], v[72:73], s[24:25] op_sel_hi:[1,0]
	v_pk_mul_f32 v[70:71], v[70:71], s[24:25] op_sel_hi:[1,0]
	v_or_b32_e32 v74, 48, v150
	v_mul_lo_u32 v76, s23, v74
	v_mad_u64_u32 v[74:75], s[28:29], s22, v74, 0
	v_add3_u32 v75, v75, v151, v76
	v_lshl_add_u64 v[82:83], v[74:75], 1, v[140:141]
	v_pk_mul_f32 v[76:77], v[88:89], s[24:25] op_sel_hi:[1,0]
	v_pk_mul_f32 v[74:75], v[86:87], s[24:25] op_sel_hi:[1,0]
	v_pk_mul_f32 v[64:65], v[64:65], s[24:25] op_sel_hi:[1,0]
	v_cvt_pk_bf16_f32 v74, v74, v75
	v_cvt_pk_bf16_f32 v75, v76, v77
	v_cvt_pk_bf16_f32 v76, v78, v79
	v_cvt_pk_bf16_f32 v77, v80, v81
	global_store_dwordx4 v[82:83], v[74:77], off
	v_pk_mul_f32 v[62:63], v[62:63], s[24:25] op_sel_hi:[1,0]
	v_pk_mul_f32 v[56:57], v[56:57], s[24:25] op_sel_hi:[1,0]
	v_pk_mul_f32 v[74:75], v[68:69], s[24:25] op_sel_hi:[1,0]
	v_pk_mul_f32 v[68:69], v[66:67], s[24:25] op_sel_hi:[1,0]
	v_cvt_pk_bf16_f32 v66, v70, v71
; __device__ __forceinline__ unsigned cvt_pk_bf16(float lo, float hi) { f32x2_t_ v = {lo, hi}; bf16x2_t_ b = __builtin_convertvector(v, bf16x2_t_); return __builtin_bit_cast(unsigned, b); }
;     __device__ __forceinline__ void operator()(const f32x4 (&acc)[2][2][4][2], const Unit& u, int wr, int wc, int fr, int fq) const {
;     ...
;             for (int m = 0; m < 4; ++m) { bf16_t* rowp = base + (size_t)(row0 + ai * HALF + m * 16) * ldc + col0;
; #pragma unroll
;                 for (int bj = 0; bj < 2; ++bj) { const f32x4 v0 = acc[ai][bj][m][0] * sc, v1 = acc[ai][bj][m][1] * sc;
;                     u32x4 w; w.x = cvt_pk_bf16(v0[0], v0[1]); w.y = cvt_pk_bf16(v0[2], v0[3]); w.z = cvt_pk_bf16(v1[0], v1[1]); w.w = cvt_pk_bf16(v1[2], v1[3]);
;                     *(u32x4*)(rowp + bj * HALF) = w; } }
;     }
	v_cvt_pk_bf16_f32 v67, v72, v73
	v_cvt_pk_bf16_f32 v68, v68, v69
	v_cvt_pk_bf16_f32 v69, v74, v75
	global_store_dwordx4 v[82:83], v[66:69], off offset:256
	v_pk_mul_f32 v[54:55], v[54:55], s[24:25] op_sel_hi:[1,0]
	v_pk_mul_f32 v[50:51], v[50:51], s[24:25] op_sel_hi:[1,0]
	v_add_u32_e32 v66, 0x80, v150
	v_ashrrev_i32_e32 v67, 31, v66
	v_mul_lo_u32 v68, s22, v67
	v_mul_lo_u32 v69, s23, v66
	v_mad_u64_u32 v[66:67], s[28:29], s22, v66, 0
	v_add3_u32 v67, v67, v68, v69
	v_pk_mul_f32 v[68:69], v[60:61], s[24:25] op_sel_hi:[1,0]
	v_pk_mul_f32 v[60:61], v[58:59], s[24:25] op_sel_hi:[1,0]
	v_lshl_add_u64 v[66:67], v[66:67], 1, v[140:141]
	v_cvt_pk_bf16_f32 v58, v62, v63
	v_cvt_pk_bf16_f32 v59, v64, v65
	v_cvt_pk_bf16_f32 v60, v60, v61
	v_cvt_pk_bf16_f32 v61, v68, v69
	global_store_dwordx4 v[66:67], v[58:61], off
	v_pk_mul_f32 v[40:41], v[40:41], s[24:25] op_sel_hi:[1,0]
	v_pk_mul_f32 v[38:39], v[38:39], s[24:25] op_sel_hi:[1,0]
	v_pk_mul_f32 v[58:59], v[48:49], s[24:25] op_sel_hi:[1,0]
	v_pk_mul_f32 v[48:49], v[46:47], s[24:25] op_sel_hi:[1,0]
	v_cvt_pk_bf16_f32 v46, v54, v55
	v_cvt_pk_bf16_f32 v47, v56, v57
	v_cvt_pk_bf16_f32 v48, v48, v49
	v_cvt_pk_bf16_f32 v49, v58, v59
	global_store_dwordx4 v[66:67], v[46:49], off offset:256
	v_pk_mul_f32 v[34:35], v[34:35], s[24:25] op_sel_hi:[1,0]
	v_pk_mul_f32 v[24:25], v[24:25], s[24:25] op_sel_hi:[1,0]
	v_add_u32_e32 v46, 0x90, v150
	v_ashrrev_i32_e32 v47, 31, v46
	v_mul_lo_u32 v48, s22, v47
	v_mul_lo_u32 v49, s23, v46
	v_mad_u64_u32 v[46:47], s[28:29], s22, v46, 0
	v_add3_u32 v47, v47, v48, v49
	v_pk_mul_f32 v[48:49], v[52:53], s[24:25] op_sel_hi:[1,0]
	v_pk_mul_f32 v[52:53], v[44:45], s[24:25] op_sel_hi:[1,0]
	v_pk_mul_f32 v[44:45], v[42:43], s[24:25] op_sel_hi:[1,0]
	v_lshl_add_u64 v[46:47], v[46:47], 1, v[140:141]
	v_cvt_pk_bf16_f32 v42, v50, v51
	v_cvt_pk_bf16_f32 v43, v48, v49
	v_cvt_pk_bf16_f32 v44, v44, v45
	v_cvt_pk_bf16_f32 v45, v52, v53
	global_store_dwordx4 v[46:47], v[42:45], off
	v_pk_mul_f32 v[22:23], v[22:23], s[24:25] op_sel_hi:[1,0]
	v_pk_mul_f32 v[18:19], v[18:19], s[24:25] op_sel_hi:[1,0]
	v_pk_mul_f32 v[42:43], v[32:33], s[24:25] op_sel_hi:[1,0]
	v_pk_mul_f32 v[32:33], v[30:31], s[24:25] op_sel_hi:[1,0]
	v_cvt_pk_bf16_f32 v30, v38, v39
	v_cvt_pk_bf16_f32 v31, v40, v41
	v_cvt_pk_bf16_f32 v32, v32, v33
	v_cvt_pk_bf16_f32 v33, v42, v43
	global_store_dwordx4 v[46:47], v[30:33], off offset:256
	v_pk_mul_f32 v[8:9], v[8:9], s[24:25] op_sel_hi:[1,0]
	v_pk_mul_f32 v[6:7], v[6:7], s[24:25] op_sel_hi:[1,0]
	v_add_u32_e32 v30, 0xa0, v150
	v_ashrrev_i32_e32 v31, 31, v30
	v_mul_lo_u32 v32, s22, v31
	v_mul_lo_u32 v33, s23, v30
	v_mad_u64_u32 v[30:31], s[28:29], s22, v30, 0
	v_add3_u32 v31, v31, v32, v33
	v_pk_mul_f32 v[32:33], v[36:37], s[24:25] op_sel_hi:[1,0]
	v_pk_mul_f32 v[36:37], v[28:29], s[24:25] op_sel_hi:[1,0]
	v_pk_mul_f32 v[28:29], v[26:27], s[24:25] op_sel_hi:[1,0]
	v_lshl_add_u64 v[30:31], v[30:31], 1, v[140:141]
	v_cvt_pk_bf16_f32 v26, v34, v35
	v_cvt_pk_bf16_f32 v27, v32, v33
	v_cvt_pk_bf16_f32 v28, v28, v29
	v_cvt_pk_bf16_f32 v29, v36, v37
	global_store_dwordx4 v[30:31], v[26:29], off
	s_andn2_b64 vcc, exec, s[6:7]
	s_mov_b64 s[6:7], -1
	v_pk_mul_f32 v[26:27], v[16:17], s[24:25] op_sel_hi:[1,0]
	v_pk_mul_f32 v[16:17], v[14:15], s[24:25] op_sel_hi:[1,0]
	v_cvt_pk_bf16_f32 v14, v22, v23
	v_cvt_pk_bf16_f32 v15, v24, v25
	v_cvt_pk_bf16_f32 v16, v16, v17
	v_cvt_pk_bf16_f32 v17, v26, v27
	global_store_dwordx4 v[30:31], v[14:17], off offset:256
	s_nop 1
	v_add_u32_e32 v14, 0xb0, v150
	v_ashrrev_i32_e32 v15, 31, v14
	v_mul_lo_u32 v16, s22, v15
	v_mul_lo_u32 v17, s23, v14
	v_mad_u64_u32 v[14:15], s[22:23], s22, v14, 0
	v_add3_u32 v15, v15, v16, v17
	v_pk_mul_f32 v[16:17], v[20:21], s[24:25] op_sel_hi:[1,0]
	v_pk_mul_f32 v[20:21], v[12:13], s[24:25] op_sel_hi:[1,0]
	v_pk_mul_f32 v[12:13], v[10:11], s[24:25] op_sel_hi:[1,0]
	v_lshl_add_u64 v[14:15], v[14:15], 1, v[140:141]
	v_cvt_pk_bf16_f32 v10, v18, v19
	v_cvt_pk_bf16_f32 v11, v16, v17
	v_cvt_pk_bf16_f32 v12, v12, v13
	v_cvt_pk_bf16_f32 v13, v20, v21
	global_store_dwordx4 v[14:15], v[10:13], off
	s_nop 1
	v_pk_mul_f32 v[10:11], v[4:5], s[24:25] op_sel_hi:[1,0]
	v_pk_mul_f32 v[4:5], v[2:3], s[24:25] op_sel_hi:[1,0]
	v_cvt_pk_bf16_f32 v2, v6, v7
	v_cvt_pk_bf16_f32 v3, v8, v9
	v_cvt_pk_bf16_f32 v4, v4, v5
	v_cvt_pk_bf16_f32 v5, v10, v11
	global_store_dwordx4 v[14:15], v[2:5], off offset:256
	s_cbranch_vccnz .LBB0_673
	s_andn2_b64 vcc, exec, s[0:1]
	s_cbranch_vccnz .LBB0_672
	s_barrier
	s_branch .LBB0_672

; __device__ __forceinline__ int my_bid() { int t = (int)blockIdx.x; asm volatile("" : "+s"(t)); return t; }
; __device__ void phase_prologue(const Params& p, unsigned char* lds) {
;     ...
;     if (my_bid() == 0 && tid < 64) ((unsigned*)(p.ws + WS_CTRL))[tid] = 0u;
.LBB0_704:
	s_waitcnt vmcnt(0)
	v_mov_b32_e32 v18, v212
	v_readlane_b32 s0, v254, 0
	s_cmp_eq_u32 s0, 0
	s_cselect_b64 s[0:1], -1, 0
	v_cmp_gt_i32_e32 vcc, 64, v18
	s_and_b64 s[2:3], vcc, s[0:1]
	v_ashrrev_i32_e32 v19, 31, v18
	s_and_saveexec_b64 s[0:1], s[2:3]
	s_cbranch_execz .LBB0_706
	v_lshl_add_u64 v[2:3], v[18:19], 2, s[86:87]
	global_store_dword v[2:3], v1, off

; __device__ __forceinline__ int my_bid() { int t = (int)blockIdx.x; asm volatile("" : "+s"(t)); return t; }
; __device__ __forceinline__ int my_gdim() { int t = (int)gridDim.x; asm volatile("" : "+s"(t)); return t; }
; __device__ __forceinline__ unsigned pack2(float lo, float hi) { return pg8::cvt_pk_bf16(lo, hi); }
; __device__ void phase_prologue(const Params& p, unsigned char* lds) {
;     ...
;         const int kk0 = tid >> 4, n4 = (tid & 15) * 4;
;         const int nn = tid >> 3, k8 = (tid & 7) * 8;
;         int it = my_bid(); TD d{nullptr, nullptr, 0, 0}; f32x4 v0 = (f32x4){0.f, 0.f, 0.f, 0.f}, v1 = v0;
;         if (it < N_T) { d = tdesc(it); v0 = *(const f32x4*)(d.src + (size_t)kk0 * d.ldsrc + n4); v1 = *(const f32x4*)(d.src + (size_t)(kk0 + 32) * d.ldsrc + n4); }
;         while (it < N_T) {
;             const int itn = it + my_gdim(); TD dn{nullptr, nullptr, 0, 0}; f32x4 w0 = (f32x4){0.f, 0.f, 0.f, 0.f}, w1 = w0;
;             if (itn < N_T) { dn = tdesc(itn); w0 = *(const f32x4*)(dn.src + (size_t)kk0 * dn.ldsrc + n4); w1 = *(const f32x4*)(dn.src + (size_t)(kk0 + 32) * dn.ldsrc + n4); }
;             tile[kk0 * 65 + n4] = v0[0]; tile[kk0 * 65 + n4 + 1] = v0[1]; tile[kk0 * 65 + n4 + 2] = v0[2]; tile[kk0 * 65 + n4 + 3] = v0[3];
;             tile[(kk0 + 32) * 65 + n4] = v1[0]; tile[(kk0 + 32) * 65 + n4 + 1] = v1[1]; tile[(kk0 + 32) * 65 + n4 + 2] = v1[2]; tile[(kk0 + 32) * 65 + n4 + 3] = v1[3];
;             __syncthreads();
;             u32x4 w;
;             w.x = pack2(tile[(k8 + 0) * 65 + nn], tile[(k8 + 1) * 65 + nn]); w.y = pack2(tile[(k8 + 2) * 65 + nn], tile[(k8 + 3) * 65 + nn]);
;             w.z = pack2(tile[(k8 + 4) * 65 + nn], tile[(k8 + 5) * 65 + nn]); w.w = pack2(tile[(k8 + 6) * 65 + nn], tile[(k8 + 7) * 65 + nn]);
;             *(u32x4*)(d.dst + (size_t)nn * d.ldd + k8) = w;
;             __syncthreads();
;             it = itn; d = dn; v0 = w0; v1 = w1;
;         }
.LBB0_718:
	v_add_u32_e32 v24, 32, v20
	v_ashrrev_i32_e32 v21, 31, v24
	v_mul_lo_u32 v0, s8, v21
	v_mul_lo_u32 v4, s9, v24
	v_mad_u64_u32 v[2:3], s[4:5], s8, v24, 0
	v_ashrrev_i32_e32 v23, 31, v20
	v_add3_u32 v3, v3, v0, v4
	v_mul_lo_u32 v6, s9, v20
	v_mul_lo_u32 v7, s8, v23
	v_mad_u64_u32 v[4:5], s[4:5], s8, v20, 0
	v_add3_u32 v5, v5, v7, v6
	v_lshl_add_u64 v[2:3], v[2:3], 2, s[6:7]
	v_lshlrev_b32_e32 v0, 2, v22
	v_lshl_add_u64 v[4:5], v[4:5], 2, s[6:7]
	v_lshl_add_u64 v[2:3], v[2:3], 0, v[0:1]
	v_lshl_add_u64 v[6:7], v[4:5], 0, v[0:1]
	global_load_dwordx4 v[2:5], v[2:3], off
	s_nop 0
	global_load_dwordx4 v[6:9], v[6:7], off
	s_add_u32 s19, s86, 0x2b00000
	s_addc_u32 s20, s87, 0
	s_add_u32 s21, s86, 0x1500000
	v_lshlrev_b32_e32 v10, 3, v18
	s_movk_i32 s4, 0x104
	s_addc_u32 s22, s87, 0
	v_and_b32_e32 v10, 56, v10
	v_mul_lo_u32 v12, v20, s4
	s_add_u32 s23, s86, 0x1100000
	v_ashrrev_i32_e32 v26, 3, v18
	v_add3_u32 v27, 0, v0, v12
	v_add3_u32 v30, 0, v12, v0
	v_mul_u32_u24_e32 v0, 0x41, v10
	s_addc_u32 s24, s87, 0
	v_lshlrev_b32_e32 v11, 2, v26
	v_lshlrev_b32_e32 v0, 2, v0
	s_add_u32 s25, s86, 0x300000
	v_add3_u32 v31, 0, v11, v0
	v_add3_u32 v32, 0, v0, v11
	v_ashrrev_i32_e32 v25, 31, v26
	s_addc_u32 s26, s87, 0
	v_lshlrev_b32_e32 v0, 2, v22
	v_lshlrev_b32_e32 v28, 1, v10
	s_branch .LBB0_721
.LBB0_719:
	v_mul_lo_u32 v12, s15, v20
	v_mul_lo_u32 v13, s14, v23
	v_mad_u64_u32 v[10:11], s[6:7], s14, v20, 0
	v_add3_u32 v11, v11, v13, v12
	v_mul_lo_u32 v14, s15, v24
	v_mul_lo_u32 v15, s14, v21
	v_mad_u64_u32 v[12:13], s[6:7], s14, v24, 0
	v_add3_u32 v13, v13, v15, v14
	v_lshl_add_u64 v[10:11], v[10:11], 2, s[10:11]
	v_lshl_add_u64 v[12:13], v[12:13], 2, s[10:11]
	v_lshl_add_u64 v[10:11], v[10:11], 0, v[0:1]
	v_lshl_add_u64 v[14:15], v[12:13], 0, v[0:1]
	global_load_dwordx4 v[10:13], v[10:11], off
	s_nop 0
	global_load_dwordx4 v[14:17], v[14:15], off
.LBB0_720:
	s_waitcnt vmcnt(0)
	ds_write2_b32 v27, v6, v7 offset1:1
	ds_write2_b32 v27, v8, v9 offset0:2 offset1:3
	v_add_u32_e32 v6, 0x2080, v30
	ds_write2_b32 v6, v2, v3 offset1:1
	v_add_u32_e32 v2, 0x2088, v30
	ds_write2_b32 v2, v4, v5 offset1:1
	v_add_u32_e32 v4, 0x200, v32
	v_add_u32_e32 v6, 0x400, v32
	s_waitcnt lgkmcnt(0)
	s_barrier
	ds_read_b32 v8, v31
	ds_read2_b32 v[2:3], v32 offset0:65 offset1:130
	ds_read2_b32 v[4:5], v4 offset0:67 offset1:132
	ds_read2_b32 v[6:7], v6 offset0:69 offset1:134
	ds_read_b32 v9, v32 offset:1820
	v_mov_b32_e32 v29, v1
	s_andn2_b64 vcc, exec, s[4:5]
	s_waitcnt lgkmcnt(3)
	v_cvt_pk_bf16_f32 v2, v8, v2
	s_waitcnt lgkmcnt(2)
	v_cvt_pk_bf16_f32 v3, v3, v4
	s_waitcnt lgkmcnt(1)
	v_cvt_pk_bf16_f32 v4, v5, v6
	s_waitcnt lgkmcnt(0)
	v_cvt_pk_bf16_f32 v5, v7, v9
	v_mul_lo_u32 v8, s3, v26
	v_mul_lo_u32 v9, s2, v25
	v_mad_u64_u32 v[6:7], s[2:3], s2, v26, 0
	v_add3_u32 v7, v7, v9, v8
	v_lshl_add_u64 v[6:7], v[6:7], 1, s[0:1]
	v_lshl_add_u64 v[6:7], v[6:7], 0, v[28:29]
	global_store_dwordx4 v[6:7], v[2:5], off
	v_mov_b64_e32 v[6:7], v[10:11]
	s_mov_b64 s[0:1], s[8:9]
	v_mov_b64_e32 v[2:3], v[14:15]
	s_mov_b64 s[2:3], s[12:13]
	v_mov_b64_e32 v[8:9], v[12:13]
	v_mov_b64_e32 v[4:5], v[16:17]
	s_waitcnt lgkmcnt(0)
	s_barrier
	s_cbranch_vccz .LBB0_735

; __device__ void phase_prologue(const Params& p, unsigned char* lds) {
;     ...
;             const int r = it - N_T - N_MOD, l = r / 12, j = r % 12; const int sc = j < 4 ? 1536 + j : (j < 8 ? 3076 + (j - 4) : 3080 + (j - 8));
;             float* dst = (float*)(p.ws + WS_WSC) + ((size_t)l * 12 + j) * DM; const float* src = p.in[I_WIN] + (size_t)l * DM * DIN + sc;
;             for (int k = tid; k < DM; k += NTHR) dst[k] = src[(size_t)k * DIN];
.LBB0_743:
	global_load_dword v7, v[4:5], off
	v_add_u32_e32 v6, 0x200, v6
	s_mov_b64 s[12:13], 0x706000
	v_cmp_lt_i32_e32 vcc, s49, v6
	v_lshl_add_u64 v[4:5], v[4:5], 0, s[12:13]
	s_or_b64 s[4:5], vcc, s[4:5]
	s_waitcnt vmcnt(0) lgkmcnt(0)
	global_store_dword v[2:3], v7, off
	v_lshl_add_u64 v[2:3], v[2:3], 0, s[94:95]
	s_andn2_b64 exec, exec, s[4:5]
	s_cbranch_execnz .LBB0_743

; __device__ __forceinline__ float silu_f(float x) { return x * __builtin_amdgcn_rcpf(1.0f + __expf(-x)); }
; __device__ void phase_prologue(const Params& p, unsigned char* lds) {
;     ...
;             for (int k0 = kg; k0 < DM; k0 += 256) {
;                 f32x4 wv[8]; float cv[4][8];
; #pragma unroll
;                 for (int u = 0; u < 8; ++u) wv[u] = *(const f32x4*)(aw + (size_t)(k0 + 32 * u) * 6144);
; #pragma unroll
;                 for (int b = 0; b < 4; ++b)
; #pragma unroll
;                     for (int u = 0; u < 8; ++u) cv[b][u] = cc[b * DM + k0 + 32 * u];
; #pragma unroll
;                 for (int u = 0; u < 8; ++u)
; #pragma unroll
;                     for (int b = 0; b < 4; ++b) ac[b] += wv[u] * silu_f(cv[b][u]);
;             }
.LBB0_748:
	s_mov_b32 s15, 0xffac0000
	v_add_co_u32_e32 v6, vcc, s15, v36
	s_mov_b32 s15, 0xffb80000
	s_nop 0
	v_addc_co_u32_e32 v7, vcc, -1, v37, vcc
	v_add_co_u32_e32 v8, vcc, s15, v36
	s_mov_b32 s15, 0xffc40000
	s_nop 0
	v_addc_co_u32_e32 v9, vcc, -1, v37, vcc
	v_add_co_u32_e32 v42, vcc, s15, v36
	s_mov_b32 s15, 0xffd00000
	s_nop 0
	v_addc_co_u32_e32 v43, vcc, -1, v37, vcc
	v_add_co_u32_e32 v40, vcc, s15, v36
	s_mov_b32 s15, 0xffdc0000
	s_nop 0
	v_addc_co_u32_e32 v41, vcc, -1, v37, vcc
	v_add_co_u32_e32 v44, vcc, s15, v36
	s_movk_i32 s15, 0xcc80
	s_nop 0
	v_addc_co_u32_e32 v45, vcc, -1, v37, vcc
	v_add_co_u32_e32 v22, vcc, s15, v38
	s_movk_i32 s15, 0xcd00
	s_nop 0
	v_addc_co_u32_e32 v23, vcc, -1, v39, vcc
	global_load_dword v49, v[22:23], off
	v_add_co_u32_e32 v24, vcc, s15, v38
	s_movk_i32 s15, 0xcd80
	s_nop 0
	v_addc_co_u32_e32 v25, vcc, -1, v39, vcc
	v_add_co_u32_e32 v50, vcc, s15, v38
	s_movk_i32 s15, 0xce00
	s_nop 0
	v_addc_co_u32_e32 v51, vcc, -1, v39, vcc
	v_add_co_u32_e32 v52, vcc, s15, v38
	s_movk_i32 s15, 0xce80
	s_nop 0
	v_addc_co_u32_e32 v53, vcc, -1, v39, vcc
	v_add_co_u32_e32 v54, vcc, s15, v38
	s_movk_i32 s15, 0xcf00
	s_nop 0
	v_addc_co_u32_e32 v55, vcc, -1, v39, vcc
	v_add_co_u32_e32 v56, vcc, s15, v38
	s_movk_i32 s15, 0xcf80
	s_nop 0
	v_addc_co_u32_e32 v57, vcc, -1, v39, vcc
	v_add_co_u32_e32 v58, vcc, s15, v38
	s_movk_i32 s15, 0xdc80
	s_nop 0
	v_addc_co_u32_e32 v59, vcc, -1, v39, vcc
	v_add_co_u32_e32 v68, vcc, s33, v38
	v_add_u32_e32 v63, 0x100, v63
	s_nop 0
	v_addc_co_u32_e32 v69, vcc, -1, v39, vcc
	global_load_dword v48, v[24:25], off
	global_load_dword v86, v[50:51], off
	s_nop 0
	global_load_dwordx4 v[22:25], v[6:7], off
	global_load_dword v80, v[52:53], off
	global_load_dword v79, v[54:55], off
	s_nop 0
	global_load_dwordx4 v[6:9], v[8:9], off
	s_nop 0
	global_load_dword v66, v[56:57], off
	global_load_dword v65, v[58:59], off
	global_load_dword v64, v[68:69], off
	v_add_co_u32_e32 v70, vcc, s15, v38
	s_movk_i32 s15, 0xdd00
	s_nop 0
	v_addc_co_u32_e32 v71, vcc, -1, v39, vcc
	v_add_co_u32_e32 v72, vcc, s15, v38
	s_movk_i32 s15, 0xdd80
	s_nop 0
	v_addc_co_u32_e32 v73, vcc, -1, v39, vcc
	v_add_co_u32_e32 v46, vcc, s15, v38
	s_movk_i32 s15, 0xde00
	s_nop 0
	v_addc_co_u32_e32 v47, vcc, -1, v39, vcc
	v_add_co_u32_e32 v74, vcc, s15, v38
	s_movk_i32 s15, 0xde80
	s_nop 0
	v_addc_co_u32_e32 v75, vcc, -1, v39, vcc
	v_add_co_u32_e32 v76, vcc, s15, v38
	s_movk_i32 s15, 0xdf00
	s_nop 0
	v_addc_co_u32_e32 v77, vcc, -1, v39, vcc
	v_add_co_u32_e32 v82, vcc, s15, v38
	s_movk_i32 s15, 0xdf80
	s_nop 0
	v_addc_co_u32_e32 v83, vcc, -1, v39, vcc
	v_add_co_u32_e32 v84, vcc, s15, v38
	s_movk_i32 s15, 0xec80
	s_nop 0
	v_addc_co_u32_e32 v85, vcc, -1, v39, vcc
	v_add_co_u32_e32 v88, vcc, s40, v38
	s_mov_b64 s[16:17], 0x600000
	s_nop 0
	v_addc_co_u32_e32 v89, vcc, -1, v39, vcc
	v_add_co_u32_e32 v90, vcc, s15, v38
	s_movk_i32 s15, 0xed00
	s_nop 0
	v_addc_co_u32_e32 v91, vcc, -1, v39, vcc
	global_load_dword v71, v[70:71], off
	s_nop 0
	global_load_dword v90, v[90:91], off
	s_waitcnt vmcnt(0) lgkmcnt(0)
	v_mul_f32_e32 v50, 0xbfb8aa3b, v49
	v_exp_f32_e32 v50, v50
	v_add_co_u32_e32 v92, vcc, s15, v38
	s_movk_i32 s15, 0xed80
	v_add_f32_e32 v50, 1.0, v50
	v_rcp_f32_e32 v50, v50
	v_addc_co_u32_e32 v93, vcc, -1, v39, vcc
	v_add_co_u32_e32 v94, vcc, s15, v38
	v_mul_f32_e32 v50, v49, v50
	s_nop 0
	v_addc_co_u32_e32 v95, vcc, -1, v39, vcc
	s_movk_i32 s15, 0xee00
	v_pk_fma_f32 v[20:21], v[24:25], v[50:51], v[20:21] op_sel_hi:[1,0,1]
	v_pk_fma_f32 v[18:19], v[22:23], v[50:51], v[18:19] op_sel_hi:[1,0,1]
	v_add_co_u32_e32 v50, vcc, s15, v38
	s_movk_i32 s15, 0xee80
	s_nop 0
	v_addc_co_u32_e32 v51, vcc, -1, v39, vcc
	v_add_co_u32_e32 v52, vcc, s15, v38
	s_movk_i32 s15, 0xfc80
	s_nop 0
	v_addc_co_u32_e32 v53, vcc, -1, v39, vcc
	v_add_co_u32_e32 v54, vcc, s15, v38
	s_movk_i32 s15, 0xef00
	s_nop 0
	v_addc_co_u32_e32 v55, vcc, -1, v39, vcc
	global_load_dword v49, v[72:73], off
	global_load_dword v91, v[54:55], off
	v_add_co_u32_e32 v54, vcc, s15, v38
	s_movk_i32 s15, 0xef80
	s_nop 0
	v_addc_co_u32_e32 v55, vcc, -1, v39, vcc
	global_load_dword v87, v[46:47], off
	global_load_dword v81, v[74:75], off
	v_add_co_u32_e32 v46, vcc, s15, v38
	global_load_dword v68, v[76:77], off
	global_load_dword v67, v[82:83], off
	global_load_dword v70, v[84:85], off
	global_load_dword v69, v[88:89], off
	s_nop 0
	global_load_dword v92, v[92:93], off
	s_nop 0
	global_load_dword v84, v[94:95], off
	v_addc_co_u32_e32 v47, vcc, -1, v39, vcc
	v_add_co_u32_e32 v56, vcc, s42, v38
	s_movk_i32 s15, 0xfd00
	s_nop 0
	v_addc_co_u32_e32 v57, vcc, -1, v39, vcc
	v_add_co_u32_e32 v58, vcc, s15, v38
	s_movk_i32 s15, 0xfd80
	s_nop 0
	v_addc_co_u32_e32 v59, vcc, -1, v39, vcc
	v_add_co_u32_e32 v76, vcc, s15, v38
	s_movk_i32 s15, 0xfe00
	s_nop 0
	v_addc_co_u32_e32 v77, vcc, -1, v39, vcc
	global_load_dword v82, v[50:51], off
	global_load_dword v72, v[52:53], off
	v_add_co_u32_e32 v50, vcc, s15, v38
	s_movk_i32 s15, 0xfe80
	s_nop 0
	v_addc_co_u32_e32 v51, vcc, -1, v39, vcc
	global_load_dword v74, v[54:55], off
	global_load_dword v73, v[46:47], off
	v_add_co_u32_e32 v46, vcc, s15, v38
	global_load_dword v75, v[56:57], off
	global_load_dword v93, v[58:59], off
	v_addc_co_u32_e32 v47, vcc, -1, v39, vcc
	s_movk_i32 s15, 0xff00
	v_add_co_u32_e32 v52, vcc, s15, v38
	s_movk_i32 s15, 0xff80
	s_nop 0
	v_addc_co_u32_e32 v53, vcc, -1, v39, vcc
	global_load_dword v85, v[76:77], off
	global_load_dword v83, v[50:51], off
	v_add_co_u32_e32 v50, vcc, s15, v38
	s_mov_b32 s15, 0xffe80000
	s_nop 0
	v_addc_co_u32_e32 v51, vcc, -1, v39, vcc
	global_load_dword v78, v[46:47], off
	global_load_dword v77, v[52:53], off
	global_load_dword v76, v[50:51], off
	v_mul_f32_e32 v46, 0xbfb8aa3b, v71
	v_exp_f32_e32 v46, v46
	v_add_co_u32_e32 v56, vcc, s15, v36
	s_mov_b32 s15, 0xfff40000
	v_add_f32_e32 v46, 1.0, v46
	v_rcp_f32_e32 v46, v46
	v_addc_co_u32_e32 v57, vcc, -1, v37, vcc
	v_add_co_u32_e32 v58, vcc, s15, v36
	v_mul_f32_e32 v46, v71, v46
	v_pk_fma_f32 v[16:17], v[24:25], v[46:47], v[16:17] op_sel_hi:[1,0,1]
	v_pk_fma_f32 v[14:15], v[22:23], v[46:47], v[14:15] op_sel_hi:[1,0,1]
	v_mul_f32_e32 v46, 0xbfb8aa3b, v90
	v_exp_f32_e32 v46, v46
	global_load_dword v71, v[38:39], off
	v_addc_co_u32_e32 v59, vcc, -1, v37, vcc
	v_add_f32_e32 v46, 1.0, v46
	v_rcp_f32_e32 v46, v46
	s_movk_i32 s15, 0x2ff
	v_cmp_lt_i32_e32 vcc, s15, v63
	s_or_b64 s[12:13], vcc, s[12:13]
	v_mul_f32_e32 v46, v90, v46
	v_pk_fma_f32 v[12:13], v[24:25], v[46:47], v[12:13] op_sel_hi:[1,0,1]
	v_pk_fma_f32 v[10:11], v[22:23], v[46:47], v[10:11] op_sel_hi:[1,0,1]
	s_waitcnt vmcnt(0) lgkmcnt(0)
; __device__ __forceinline__ float silu_f(float x) { return x * __builtin_amdgcn_rcpf(1.0f + __expf(-x)); }
; __device__ void phase_prologue(const Params& p, unsigned char* lds) {
;     ...
;             for (int k0 = kg; k0 < DM; k0 += 256) {
;                 f32x4 wv[8]; float cv[4][8];
; #pragma unroll
;                 for (int u = 0; u < 8; ++u) wv[u] = *(const f32x4*)(aw + (size_t)(k0 + 32 * u) * 6144);
; #pragma unroll
;                 for (int b = 0; b < 4; ++b)
; #pragma unroll
;                     for (int u = 0; u < 8; ++u) cv[b][u] = cc[b * DM + k0 + 32 * u];
; #pragma unroll
;                 for (int u = 0; u < 8; ++u)
; #pragma unroll
;                     for (int b = 0; b < 4; ++b) ac[b] += wv[u] * silu_f(cv[b][u]);
;             }
	v_mul_f32_e32 v46, 0xbfb8aa3b, v91
	v_exp_f32_e32 v46, v46
	s_nop 0
	v_add_f32_e32 v46, 1.0, v46
	v_rcp_f32_e32 v46, v46
	s_nop 0
	v_mul_f32_e32 v50, v91, v46
	v_pk_fma_f32 v[46:47], v[24:25], v[50:51], v[4:5] op_sel_hi:[1,0,1]
	v_pk_fma_f32 v[50:51], v[22:23], v[50:51], v[2:3] op_sel_hi:[1,0,1]
	v_mul_f32_e32 v22, 0xbfb8aa3b, v48
	v_exp_f32_e32 v22, v22
	global_load_dwordx4 v[2:5], v[36:37], off
	v_lshl_add_u64 v[36:37], v[36:37], 0, s[16:17]
	s_mov_b64 s[16:17], 0x400
	v_add_f32_e32 v22, 1.0, v22
	v_rcp_f32_e32 v22, v22
	v_lshl_add_u64 v[38:39], v[38:39], 0, s[16:17]
	v_mul_f32_e32 v22, v48, v22
	v_pk_fma_f32 v[88:89], v[8:9], v[22:23], v[20:21] op_sel_hi:[1,0,1]
	v_pk_fma_f32 v[90:91], v[6:7], v[22:23], v[18:19] op_sel_hi:[1,0,1]
	global_load_dwordx4 v[22:25], v[42:43], off
	v_mul_f32_e32 v18, 0xbfb8aa3b, v49
	v_exp_f32_e32 v18, v18
	s_nop 0
	v_add_f32_e32 v18, 1.0, v18
	v_rcp_f32_e32 v18, v18
	s_nop 0
	v_mul_f32_e32 v18, v49, v18
	v_pk_fma_f32 v[16:17], v[8:9], v[18:19], v[16:17] op_sel_hi:[1,0,1]
	v_pk_fma_f32 v[14:15], v[6:7], v[18:19], v[14:15] op_sel_hi:[1,0,1]
	v_mul_f32_e32 v18, 0xbfb8aa3b, v92
	v_exp_f32_e32 v18, v18
	s_nop 0
	v_add_f32_e32 v18, 1.0, v18
	v_rcp_f32_e32 v18, v18
	s_nop 0
	v_mul_f32_e32 v18, v92, v18
	v_pk_fma_f32 v[54:55], v[6:7], v[18:19], v[10:11] op_sel_hi:[1,0,1]
	v_mul_f32_e32 v10, 0xbfb8aa3b, v93
	v_exp_f32_e32 v10, v10
	v_pk_fma_f32 v[52:53], v[8:9], v[18:19], v[12:13] op_sel_hi:[1,0,1]
	v_add_f32_e32 v10, 1.0, v10
	v_rcp_f32_e32 v10, v10
	s_nop 0
	v_mul_f32_e32 v10, v93, v10
	v_pk_fma_f32 v[48:49], v[8:9], v[10:11], v[46:47] op_sel_hi:[1,0,1]
	v_pk_fma_f32 v[50:51], v[6:7], v[10:11], v[50:51] op_sel_hi:[1,0,1]
	global_load_dwordx4 v[18:21], v[40:41], off
	global_load_dwordx4 v[10:13], v[44:45], off
	global_load_dwordx4 v[6:9], v[56:57], off
	v_mul_f32_e32 v40, 0xbfb8aa3b, v86
	v_exp_f32_e32 v40, v40
	v_mul_f32_e32 v56, 0xbfb8aa3b, v84
	v_exp_f32_e32 v56, v56
	v_add_f32_e32 v40, 1.0, v40
	v_rcp_f32_e32 v40, v40
	v_add_f32_e32 v56, 1.0, v56
	v_rcp_f32_e32 v56, v56
	v_mul_f32_e32 v40, v86, v40
	v_mul_f32_e32 v86, 0xbfb8aa3b, v74
	v_mul_f32_e32 v56, v84, v56
	v_mul_f32_e32 v84, 0xbfb8aa3b, v68
	s_waitcnt vmcnt(0) lgkmcnt(0)
	v_pk_fma_f32 v[44:45], v[22:23], v[40:41], v[90:91] op_sel_hi:[1,0,1]
	v_pk_fma_f32 v[46:47], v[24:25], v[40:41], v[88:89] op_sel_hi:[1,0,1]
	v_mul_f32_e32 v40, 0xbfb8aa3b, v87
	v_exp_f32_e32 v40, v40
	v_pk_fma_f32 v[54:55], v[22:23], v[56:57], v[54:55] op_sel_hi:[1,0,1]
	v_pk_fma_f32 v[52:53], v[24:25], v[56:57], v[52:53] op_sel_hi:[1,0,1]
	v_mul_f32_e32 v56, 0xbfb8aa3b, v85
	v_add_f32_e32 v40, 1.0, v40
	v_rcp_f32_e32 v40, v40
	v_exp_f32_e32 v56, v56
	v_mul_f32_e32 v57, 0xbfb8aa3b, v80
	v_mul_f32_e32 v42, v87, v40
	v_pk_fma_f32 v[40:41], v[22:23], v[42:43], v[14:15] op_sel_hi:[1,0,1]
	v_pk_fma_f32 v[42:43], v[24:25], v[42:43], v[16:17] op_sel_hi:[1,0,1]
	global_load_dwordx4 v[14:17], v[58:59], off
	v_add_f32_e32 v56, 1.0, v56
	v_rcp_f32_e32 v56, v56
	v_mul_f32_e32 v58, 0xbfb8aa3b, v83
	v_mul_f32_e32 v59, 0xbfb8aa3b, v79
	v_mul_f32_e32 v56, v85, v56
	v_pk_fma_f32 v[50:51], v[22:23], v[56:57], v[50:51] op_sel_hi:[1,0,1]
	v_exp_f32_e32 v22, v57
	v_mul_f32_e32 v23, 0xbfb8aa3b, v81
	v_pk_fma_f32 v[48:49], v[24:25], v[56:57], v[48:49] op_sel_hi:[1,0,1]
	v_mul_f32_e32 v56, 0xbfb8aa3b, v82
	v_add_f32_e32 v22, 1.0, v22
	v_rcp_f32_e32 v22, v22
	v_mul_f32_e32 v85, 0xbfb8aa3b, v72
	v_mul_f32_e32 v57, 0xbfb8aa3b, v78
	v_exp_f32_e32 v57, v57
	v_mul_f32_e32 v22, v80, v22
	v_mul_f32_e32 v80, 0xbfb8aa3b, v66
	v_add_f32_e32 v57, 1.0, v57
	v_rcp_f32_e32 v57, v57
	v_pk_fma_f32 v[46:47], v[20:21], v[22:23], v[46:47] op_sel_hi:[1,0,1]
	v_pk_fma_f32 v[44:45], v[18:19], v[22:23], v[44:45] op_sel_hi:[1,0,1]
	v_exp_f32_e32 v22, v23
	s_nop 0
	v_add_f32_e32 v22, 1.0, v22
	v_rcp_f32_e32 v22, v22
	s_nop 0
	v_mul_f32_e32 v24, v81, v22
	v_pk_fma_f32 v[22:23], v[20:21], v[24:25], v[42:43] op_sel_hi:[1,0,1]
	v_pk_fma_f32 v[24:25], v[18:19], v[24:25], v[40:41] op_sel_hi:[1,0,1]
	v_exp_f32_e32 v40, v56
	v_mul_f32_e32 v81, 0xbfb8aa3b, v67
	v_mul_f32_e32 v56, 0xbfb8aa3b, v75
	v_exp_f32_e32 v56, v56
	v_add_f32_e32 v40, 1.0, v40
	v_rcp_f32_e32 v40, v40
	v_add_f32_e32 v56, 1.0, v56
	v_mul_f32_e32 v42, v82, v40
	v_pk_fma_f32 v[40:41], v[20:21], v[42:43], v[52:53] op_sel_hi:[1,0,1]
	v_exp_f32_e32 v52, v58
	v_mul_f32_e32 v53, 0xbfb8aa3b, v77
	v_pk_fma_f32 v[42:43], v[18:19], v[42:43], v[54:55] op_sel_hi:[1,0,1]
	v_exp_f32_e32 v58, v84
	v_add_f32_e32 v52, 1.0, v52
	v_rcp_f32_e32 v52, v52
	v_mul_f32_e32 v54, 0xbfb8aa3b, v65
	v_mul_f32_e32 v55, 0xbfb8aa3b, v69
	v_exp_f32_e32 v54, v54
	v_mul_f32_e32 v52, v83, v52
	v_pk_fma_f32 v[20:21], v[20:21], v[52:53], v[48:49] op_sel_hi:[1,0,1]
	v_exp_f32_e32 v48, v59
	v_pk_fma_f32 v[18:19], v[18:19], v[52:53], v[50:51] op_sel_hi:[1,0,1]
	v_mul_f32_e32 v49, 0xbfb8aa3b, v70
	v_mul_f32_e32 v51, 0xbfb8aa3b, v76
	v_add_f32_e32 v48, 1.0, v48
	v_rcp_f32_e32 v48, v48
	v_exp_f32_e32 v59, v85
	v_mul_f32_e32 v50, 0xbfb8aa3b, v73
	v_exp_f32_e32 v53, v53
	v_mul_f32_e32 v48, v79, v48
	v_pk_fma_f32 v[44:45], v[10:11], v[48:49], v[44:45] op_sel_hi:[1,0,1]
	v_pk_fma_f32 v[46:47], v[12:13], v[48:49], v[46:47] op_sel_hi:[1,0,1]
	v_exp_f32_e32 v79, v80
	v_exp_f32_e32 v80, v81
	v_exp_f32_e32 v81, v86
	v_exp_f32_e32 v49, v49
	v_exp_f32_e32 v51, v51
	v_mul_f32_e32 v52, 0xbfb8aa3b, v64
	v_mul_f32_e32 v48, 0xbfb8aa3b, v71
	v_exp_f32_e32 v50, v50
	v_exp_f32_e32 v55, v55
	v_exp_f32_e32 v52, v52
	v_exp_f32_e32 v48, v48
	v_add_f32_e32 v58, 1.0, v58
	v_add_f32_e32 v59, 1.0, v59
	v_add_f32_e32 v79, 1.0, v79
	v_add_f32_e32 v80, 1.0, v80
	v_add_f32_e32 v81, 1.0, v81
	v_add_f32_e32 v53, 1.0, v53
	v_add_f32_e32 v49, 1.0, v49
; __device__ __forceinline__ float silu_f(float x) { return x * __builtin_amdgcn_rcpf(1.0f + __expf(-x)); }
; __device__ void phase_prologue(const Params& p, unsigned char* lds) {
;     ...
;                 for (int u = 0; u < 8; ++u)
; #pragma unroll
;                     for (int b = 0; b < 4; ++b) ac[b] += wv[u] * silu_f(cv[b][u]);
;             }
;             float* red = tile;
; #pragma unroll
;             for (int b = 0; b < 4; ++b) *(f32x4*)(red + (kg * 4 + b) * 64 + c4) = ac[b];
;             __syncthreads();
;             if (tid < 256) { const int b = tid >> 6, col = tid & 63; float s = 0.f;
; #pragma unroll
;                 for (int g = 0; g < 32; ++g) s += red[(g * 4 + b) * 64 + col];
;                 ((float*)(p.ws + WS_MOD))[((size_t)l * 4 + b) * 6144 + n0 + col] = s + p.in[I_ADAB][(size_t)l * 6144 + n0 + col]; }
	v_add_f32_e32 v51, 1.0, v51
	v_rcp_f32_e32 v58, v58
	v_rcp_f32_e32 v59, v59
	v_add_f32_e32 v54, 1.0, v54
	v_add_f32_e32 v50, 1.0, v50
	v_add_f32_e32 v55, 1.0, v55
	v_rcp_f32_e32 v79, v79
	v_rcp_f32_e32 v80, v80
	v_rcp_f32_e32 v81, v81
	v_rcp_f32_e32 v53, v53
	v_rcp_f32_e32 v49, v49
	v_rcp_f32_e32 v51, v51
	v_add_f32_e32 v52, 1.0, v52
	v_add_f32_e32 v48, 1.0, v48
	v_rcp_f32_e32 v82, v54
	v_rcp_f32_e32 v83, v50
	v_rcp_f32_e32 v55, v55
	v_rcp_f32_e32 v84, v52
	v_rcp_f32_e32 v85, v56
	v_rcp_f32_e32 v86, v48
	v_mul_f32_e32 v48, v68, v58
	v_mul_f32_e32 v50, v72, v59
	v_mul_f32_e32 v52, v78, v57
	v_mul_f32_e32 v54, v66, v79
	v_mul_f32_e32 v56, v67, v80
	v_mul_f32_e32 v58, v74, v81
	v_mul_f32_e32 v66, v77, v53
	v_pk_fma_f32 v[24:25], v[10:11], v[48:49], v[24:25] op_sel_hi:[1,0,1]
	v_pk_fma_f32 v[22:23], v[12:13], v[48:49], v[22:23] op_sel_hi:[1,0,1]
	v_pk_fma_f32 v[42:43], v[10:11], v[50:51], v[42:43] op_sel_hi:[1,0,1]
	v_pk_fma_f32 v[40:41], v[12:13], v[50:51], v[40:41] op_sel_hi:[1,0,1]
	v_pk_fma_f32 v[10:11], v[10:11], v[52:53], v[18:19] op_sel_hi:[1,0,1]
	v_pk_fma_f32 v[12:13], v[12:13], v[52:53], v[20:21] op_sel_hi:[1,0,1]
	v_mul_f32_e32 v68, v65, v82
	v_mul_f32_e32 v70, v70, v49
	v_mul_f32_e32 v72, v73, v83
	v_mul_f32_e32 v74, v76, v51
	v_pk_fma_f32 v[18:19], v[8:9], v[54:55], v[46:47] op_sel_hi:[1,0,1]
	v_pk_fma_f32 v[20:21], v[6:7], v[54:55], v[44:45] op_sel_hi:[1,0,1]
	v_pk_fma_f32 v[22:23], v[8:9], v[56:57], v[22:23] op_sel_hi:[1,0,1]
	v_pk_fma_f32 v[24:25], v[6:7], v[56:57], v[24:25] op_sel_hi:[1,0,1]
	v_pk_fma_f32 v[40:41], v[8:9], v[58:59], v[40:41] op_sel_hi:[1,0,1]
	v_pk_fma_f32 v[42:43], v[6:7], v[58:59], v[42:43] op_sel_hi:[1,0,1]
	v_pk_fma_f32 v[8:9], v[8:9], v[66:67], v[12:13] op_sel_hi:[1,0,1]
	v_pk_fma_f32 v[6:7], v[6:7], v[66:67], v[10:11] op_sel_hi:[1,0,1]
	v_mul_f32_e32 v64, v64, v84
	v_mul_f32_e32 v76, v69, v55
	v_mul_f32_e32 v78, v75, v85
	v_mul_f32_e32 v80, v71, v86
	s_waitcnt vmcnt(0) lgkmcnt(0)
	v_pk_fma_f32 v[10:11], v[14:15], v[68:69], v[20:21] op_sel_hi:[1,0,1]
	v_pk_fma_f32 v[12:13], v[16:17], v[68:69], v[18:19] op_sel_hi:[1,0,1]
	v_pk_fma_f32 v[24:25], v[14:15], v[70:71], v[24:25] op_sel_hi:[1,0,1]
	v_pk_fma_f32 v[22:23], v[16:17], v[70:71], v[22:23] op_sel_hi:[1,0,1]
	v_pk_fma_f32 v[42:43], v[14:15], v[72:73], v[42:43] op_sel_hi:[1,0,1]
	v_pk_fma_f32 v[40:41], v[16:17], v[72:73], v[40:41] op_sel_hi:[1,0,1]
	v_pk_fma_f32 v[6:7], v[14:15], v[74:75], v[6:7] op_sel_hi:[1,0,1]
	v_pk_fma_f32 v[8:9], v[16:17], v[74:75], v[8:9] op_sel_hi:[1,0,1]
	v_pk_fma_f32 v[20:21], v[4:5], v[64:65], v[12:13] op_sel_hi:[1,0,1]
	v_pk_fma_f32 v[18:19], v[2:3], v[64:65], v[10:11] op_sel_hi:[1,0,1]
	v_pk_fma_f32 v[16:17], v[4:5], v[76:77], v[22:23] op_sel_hi:[1,0,1]
	v_pk_fma_f32 v[14:15], v[2:3], v[76:77], v[24:25] op_sel_hi:[1,0,1]
	v_pk_fma_f32 v[12:13], v[4:5], v[78:79], v[40:41] op_sel_hi:[1,0,1]
	v_pk_fma_f32 v[10:11], v[2:3], v[78:79], v[42:43] op_sel_hi:[1,0,1]
	v_pk_fma_f32 v[4:5], v[4:5], v[80:81], v[8:9] op_sel_hi:[1,0,1]
	v_pk_fma_f32 v[2:3], v[2:3], v[80:81], v[6:7] op_sel_hi:[1,0,1]
	s_andn2_b64 exec, exec, s[12:13]
	s_cbranch_execnz .LBB0_748
	s_or_b64 exec, exec, s[12:13]
.LBB0_750:
	s_or_b64 exec, exec, s[4:5]
	ds_write_b128 v62, v[18:21]
	ds_write_b128 v62, v[14:17] offset:256
	ds_write_b128 v62, v[10:13] offset:512
	ds_write_b128 v62, v[2:5] offset:768
	s_waitcnt lgkmcnt(0)
	s_barrier
	s_and_saveexec_b64 s[4:5], s[10:11]
	s_cbranch_execz .LBB0_737
	s_and_b64 s[12:13], s[2:3], exec
	s_cselect_b32 s12, 0x6000, 0
	s_add_u32 s15, s82, s12
	s_addc_u32 s17, s83, 0
	s_lshl_b64 s[12:13], s[84:85], 2
	s_add_u32 s16, s15, s12
	s_addc_u32 s17, s17, s13
	v_lshl_add_u64 v[2:3], s[16:17], 0, v[0:1]
	global_load_dword v46, v[2:3], off
	ds_read2st64_b32 v[2:3], v27 offset1:4
	ds_read2st64_b32 v[4:5], v27 offset0:8 offset1:12
	ds_read2st64_b32 v[6:7], v27 offset0:16 offset1:20
	ds_read2st64_b32 v[8:9], v27 offset0:24 offset1:28
	ds_read2st64_b32 v[10:11], v27 offset0:32 offset1:36
	ds_read2st64_b32 v[12:13], v27 offset0:40 offset1:44
	ds_read2st64_b32 v[14:15], v27 offset0:48 offset1:52
	ds_read2st64_b32 v[16:17], v27 offset0:56 offset1:60
	ds_read2st64_b32 v[18:19], v27 offset0:64 offset1:68
	ds_read2st64_b32 v[20:21], v27 offset0:72 offset1:76
	ds_read2st64_b32 v[22:23], v27 offset0:80 offset1:84
	ds_read2st64_b32 v[24:25], v27 offset0:88 offset1:92
	ds_read2st64_b32 v[36:37], v27 offset0:96 offset1:100
	ds_read2st64_b32 v[38:39], v27 offset0:104 offset1:108
	ds_read2st64_b32 v[40:41], v27 offset0:112 offset1:116
	ds_read2st64_b32 v[42:43], v27 offset0:120 offset1:124
	s_waitcnt lgkmcnt(0)
	v_add_f32_e32 v2, 0, v2
	v_add_f32_e32 v2, v2, v3
	v_add_f32_e32 v2, v2, v4
	v_add_f32_e32 v2, v2, v5
	v_add_f32_e32 v4, v2, v6
	v_add_f32_e32 v4, v4, v7
	v_add_f32_e32 v4, v4, v8
	v_add_f32_e32 v4, v4, v9
	v_add_f32_e32 v4, v4, v10
	v_add_f32_e32 v4, v4, v11
	v_add_f32_e32 v4, v4, v12
	v_add_f32_e32 v4, v4, v13
	v_add_f32_e32 v4, v4, v14
	v_add_f32_e32 v4, v4, v15
	v_add_f32_e32 v4, v4, v16
	v_add_f32_e32 v4, v4, v17
	v_add_f32_e32 v4, v4, v18
	v_add_f32_e32 v4, v4, v19
	v_add_f32_e32 v4, v4, v20
	v_add_f32_e32 v4, v4, v21
	v_add_f32_e32 v4, v4, v22
	v_add_f32_e32 v4, v4, v23
	v_add_f32_e32 v4, v4, v24
	v_add_f32_e32 v4, v4, v25
	v_add_f32_e32 v4, v4, v36
	v_add_f32_e32 v4, v4, v37
	v_add_f32_e32 v4, v4, v38
	s_and_b64 s[2:3], s[2:3], exec
	v_add_f32_e32 v4, v4, v39
	s_cselect_b32 s2, 4, 0
	v_add_f32_e32 v4, v4, v40
	v_mov_b64_e32 v[44:45], s[0:1]
	v_add_u32_e32 v3, s2, v26
	s_movk_i32 s2, 0x6000
	v_add_f32_e32 v4, v4, v41
	v_mad_i64_i32 v[2:3], s[2:3], v3, s2, v[44:45]
	v_add_f32_e32 v4, v4, v42
	v_lshl_add_u64 v[2:3], v[2:3], 0, s[12:13]
	v_add_f32_e32 v4, v4, v43
	v_lshl_add_u64 v[2:3], v[2:3], 0, v[0:1]
	s_waitcnt vmcnt(0)
	v_add_f32_e32 v4, v4, v46
	global_store_dword v[2:3], v4, off
	s_branch .LBB0_737

; __device__ __forceinline__ void phase_norm(const Params& p, unsigned char* lds, const float* __restrict__ xin, const float* g, const float* mod  , int shift_off, int scale_off, bf16_t* __restrict__ hout, const float* wsc  , float* scal) {
;     ...
;     if (wsc) { for (int i = tid; i < 12 * DM; i += NTHR) wl[i] = wsc[i]; __syncthreads(); }
.LBB0_754:
	global_load_dword v3, v[4:5], off
	v_add_u32_e32 v0, 0x200, v0
	s_movk_i32 s4, 0x2dff
	v_cmp_lt_i32_e32 vcc, s4, v0
	v_lshl_add_u64 v[4:5], v[4:5], 0, s[94:95]
	s_or_b64 s[2:3], vcc, s[2:3]
	s_waitcnt vmcnt(0) lgkmcnt(0)
	ds_write_b32 v6, v3
	v_add_u32_e32 v6, 0x800, v6
	s_andn2_b64 exec, exec, s[2:3]
	s_cbranch_execnz .LBB0_754

; __device__ __forceinline__ void phase_norm(const Params& p, unsigned char* lds, const float* __restrict__ xin, const float* g, const float* mod  , int shift_off, int scale_off, bf16_t* __restrict__ hout, const float* wsc  , float* scal) {
;     ...
;     for (int rb = gw * 4; rb < MTOK; rb += nw * 4) {
;         const int b = rb >> 13;
;         float cs[16], sh[16];
; #pragma unroll
;         for (int i = 0; i < 2; ++i)
; #pragma unroll
;             for (int j = 0; j < 8; ++j) { const int k = i * 512 + lane * 8 + j; cs[i * 8 + j] = g[k] * (1.0f + mod[(size_t)b * 6144 + scale_off + k]); sh[i * 8 + j] = mod[(size_t)b * 6144 + shift_off + k]; }
;         { const int r4 = 0;
;             f32x4 xq[4][4];
; #pragma unroll
;             for (int q = 0; q < 4; ++q) { const float* xp = xin + (size_t)(rb + r4 + q) * DM + lane * 8;
;                 xq[q][0] = __builtin_nontemporal_load((const f32x4*)xp); xq[q][1] = __builtin_nontemporal_load((const f32x4*)(xp + 4)); xq[q][2] = __builtin_nontemporal_load((const f32x4*)(xp + 512)); xq[q][3] = __builtin_nontemporal_load((const f32x4*)(xp + 516)); }
; #pragma unroll
;             for (int q = 0; q < 4; ++q) {
;             const int row = rb + r4 + q;
;             const f32x4 x0 = xq[q][0], x1 = xq[q][1], x2 = xq[q][2], x3 = xq[q][3];
;             float xv[16] = {x0[0], x0[1], x0[2], x0[3], x1[0], x1[1], x1[2], x1[3], x2[0], x2[1], x2[2], x2[3], x3[0], x3[1], x3[2], x3[3]};
;             float ss = 0.f;
; #pragma unroll
;             for (int i = 0; i < 16; ++i) ss += xv[i] * xv[i];
;             ss = wave_sum(ss);
;             const float rstd = rsqrtf(ss * (1.0f / DM) + EPS);
.LBB0_758:
	v_ashrrev_i32_e32 v2, 13, v66
	v_mul_i32_i24_e32 v2, 0x1800, v2
	v_ashrrev_i32_e32 v3, 31, v2
	v_lshl_add_u64 v[2:3], v[2:3], 2, s[70:71]
	s_mov_b64 s[0:1], 0x1000
	v_lshl_add_u64 v[4:5], v[2:3], 0, s[0:1]
	v_lshl_add_u64 v[6:7], v[4:5], 0, v[0:1]
	v_mov_b32_e32 v77, v1
	global_load_dwordx4 v[18:21], v[6:7], off
	v_lshl_add_u64 v[6:7], v[4:5], 0, v[76:77]
	v_mov_b32_e32 v79, v1
	v_mov_b32_e32 v81, v1
	global_load_dwordx4 v[22:25], v[6:7], off
	v_lshl_add_u64 v[6:7], v[4:5], 0, v[78:79]
	v_lshl_add_u64 v[4:5], v[4:5], 0, v[80:81]
	s_movk_i32 s0, 0xc7f0
	global_load_dwordx4 v[26:29], v[6:7], off
	global_load_dwordx4 v[30:33], v[4:5], off
	global_load_dwordx4 v[34:37], v[68:69], off
	global_load_dwordx4 v[38:41], v[68:69], off offset:16
	global_load_dwordx4 v[42:45], v[68:69], off offset:2048
	global_load_dwordx4 v[46:49], v[68:69], off offset:2064
	v_add_co_u32_e32 v4, vcc, s0, v74
	s_movk_i32 s0, 0xc800
	s_nop 0
	v_addc_co_u32_e32 v5, vcc, -1, v75, vcc
	global_load_dwordx4 v[98:101], v[4:5], off nt
	v_add_co_u32_e32 v6, vcc, s0, v74
	s_movk_i32 s0, 0xcff0
	s_nop 0
	v_addc_co_u32_e32 v7, vcc, -1, v75, vcc
	global_load_dwordx4 v[102:105], v[6:7], off nt
	v_add_co_u32_e32 v4, vcc, s0, v74
	s_movk_i32 s0, 0xd7f0
	s_nop 0
	v_addc_co_u32_e32 v5, vcc, -1, v75, vcc
	global_load_dwordx4 v[106:109], v[4:5], off nt
	v_add_co_u32_e32 v6, vcc, s33, v74
	v_lshl_add_u64 v[2:3], v[2:3], 0, v[0:1]
	s_nop 0
	v_addc_co_u32_e32 v7, vcc, -1, v75, vcc
	global_load_dwordx4 v[120:123], v[6:7], off nt
	v_add_co_u32_e32 v4, vcc, s0, v74
	s_movk_i32 s0, 0xd800
	s_nop 0
	v_addc_co_u32_e32 v5, vcc, -1, v75, vcc
	v_add_co_u32_e32 v6, vcc, s0, v74
	s_movk_i32 s0, 0xdff0
	s_nop 0
	v_addc_co_u32_e32 v7, vcc, -1, v75, vcc
	v_add_co_u32_e32 v8, vcc, s0, v74
	s_movk_i32 s0, 0xe7f0
	s_nop 0
	v_addc_co_u32_e32 v9, vcc, -1, v75, vcc
	v_add_co_u32_e32 v10, vcc, s40, v74
	s_waitcnt vmcnt(0) lgkmcnt(0)
	v_pk_add_f32 v[18:19], v[18:19], 1.0 op_sel_hi:[1,0]
	v_addc_co_u32_e32 v11, vcc, -1, v75, vcc
	global_load_dwordx4 v[62:65], v[4:5], off nt
	global_load_dwordx4 v[58:61], v[6:7], off nt
	global_load_dwordx4 v[54:57], v[8:9], off nt
	global_load_dwordx4 v[50:53], v[10:11], off nt
	s_nop 0
	global_load_dwordx4 v[10:13], v[2:3], off offset:16
	global_load_dwordx4 v[6:9], v[2:3], off offset:2048
	global_load_dwordx4 v[14:17], v[2:3], off
	s_nop 0
	global_load_dwordx4 v[2:5], v[2:3], off offset:2064
	v_pk_add_f32 v[30:31], v[30:31], 1.0 op_sel_hi:[1,0]
	v_add_co_u32_e32 v110, vcc, s0, v74
	v_pk_add_f32 v[28:29], v[28:29], 1.0 op_sel_hi:[1,0]
	v_pk_mul_f32 v[84:85], v[46:47], v[30:31]
	v_pk_mul_f32 v[86:87], v[44:45], v[28:29]
	v_pk_add_f32 v[26:27], v[26:27], 1.0 op_sel_hi:[1,0]
	v_addc_co_u32_e32 v111, vcc, -1, v75, vcc
	v_pk_mul_f32 v[88:89], v[42:43], v[26:27]
	v_mul_f32_e32 v30, v99, v99
	v_fmac_f32_e32 v30, v98, v98
	v_fmac_f32_e32 v30, v100, v100
	v_fmac_f32_e32 v30, v101, v101
	s_movk_i32 s0, 0xe800
	v_pk_mul_f32 v[96:97], v[34:35], v[18:19]
	v_fmac_f32_e32 v30, v102, v102
	v_fmac_f32_e32 v30, v103, v103
	v_fmac_f32_e32 v30, v104, v104
	v_fmac_f32_e32 v30, v105, v105
	v_add_co_u32_e32 v18, vcc, s0, v74
	v_fmac_f32_e32 v30, v106, v106
	v_fmac_f32_e32 v30, v107, v107
	v_fmac_f32_e32 v30, v108, v108
	v_fmac_f32_e32 v30, v109, v109
	v_pk_add_f32 v[20:21], v[20:21], 1.0 op_sel_hi:[1,0]
	v_addc_co_u32_e32 v19, vcc, -1, v75, vcc
	v_pk_mul_f32 v[28:29], v[120:121], v[120:121]
	v_pk_mul_f32 v[26:27], v[122:123], v[122:123]
	v_add_f32_e32 v28, v28, v30
	v_add_f32_e32 v28, v29, v28
	v_add_f32_e32 v26, v26, v28
	v_add_f32_e32 v26, v27, v26
	s_movk_i32 s0, 0xeff0
	v_pk_mul_f32 v[94:95], v[36:37], v[20:21]
	v_add_f32_dpp v26, v26, v26 row_shr:1 row_mask:0xf bank_mask:0xf bound_ctrl:1
	global_load_dwordx4 v[42:45], v[110:111], off nt
	global_load_dwordx4 v[34:37], v[18:19], off nt
	v_add_f32_dpp v26, v26, v26 row_shr:2 row_mask:0xf bank_mask:0xf bound_ctrl:1
	v_add_co_u32_e32 v18, vcc, s0, v74
	s_nop 0
	v_add_f32_dpp v26, v26, v26 row_shr:4 row_mask:0xf bank_mask:0xf bound_ctrl:1
	v_addc_co_u32_e32 v19, vcc, -1, v75, vcc
	s_nop 0
	v_add_f32_dpp v26, v26, v26 row_shr:8 row_mask:0xf bank_mask:0xf bound_ctrl:1
	v_mov_b32_e32 v27, v1
	v_add_co_u32_e32 v20, vcc, s42, v74
	s_nop 0
	v_mov_b32_dpp v27, v26 row_bcast:15 row_mask:0xa bank_mask:0xf
	v_pk_add_f32 v[22:23], v[22:23], 1.0 op_sel_hi:[1,0]
	v_pk_add_f32 v[24:25], v[24:25], 1.0 op_sel_hi:[1,0]
	v_pk_add_f32 v[32:33], v[32:33], 1.0 op_sel_hi:[1,0]
	v_addc_co_u32_e32 v21, vcc, -1, v75, vcc
	s_movk_i32 s0, 0xf7f0
	v_add_f32_e32 v26, v26, v27
	v_mov_b32_e32 v27, v1
	v_pk_mul_f32 v[92:93], v[38:39], v[22:23]
	v_pk_mul_f32 v[90:91], v[40:41], v[24:25]
	v_pk_mul_f32 v[82:83], v[48:49], v[32:33]
	global_load_dwordx4 v[46:49], v[18:19], off nt
	global_load_dwordx4 v[38:41], v[20:21], off nt
	v_add_co_u32_e32 v18, vcc, s0, v74
	v_mov_b32_dpp v27, v26 row_bcast:31 row_mask:0xc bank_mask:0xf
	s_nop 0
	v_addc_co_u32_e32 v19, vcc, -1, v75, vcc
	v_add_f32_e32 v26, v26, v27
	v_add_co_u32_e32 v20, vcc, s75, v74
	v_readlane_b32 s0, v26, 63
	s_nop 0
	v_addc_co_u32_e32 v21, vcc, -1, v75, vcc
	v_fma_f32 v26, s0, v217, v213
	v_mul_f32_e32 v27, 0x4b800000, v26
	v_cmp_gt_f32_e32 vcc, s44, v26
	global_load_dwordx4 v[22:25], v[18:19], off nt
	s_nop 0
	global_load_dwordx4 v[18:21], v[20:21], off nt
	v_cndmask_b32_e32 v26, v26, v27, vcc
	v_rsq_f32_e32 v67, v26
	v_add_co_u32_e64 v26, s[0:1], -16, v74
	v_mul_f32_e32 v77, 0x45800000, v67
	v_cndmask_b32_e32 v124, v67, v77, vcc
	v_pk_mul_f32 v[98:99], v[98:99], v[124:125] op_sel_hi:[1,0]
	v_addc_co_u32_e64 v27, s[0:1], -1, v75, s[0:1]
	s_waitcnt vmcnt(0) lgkmcnt(0)
; __device__ __forceinline__ unsigned pack2(float lo, float hi) { return pg8::cvt_pk_bf16(lo, hi); }
; __device__ __forceinline__ void phase_norm(const Params& p, unsigned char* lds, const float* __restrict__ xin, const float* g, const float* mod  , int shift_off, int scale_off, bf16_t* __restrict__ hout, const float* wsc  , float* scal) {
;     ...
;             const float rstd = rsqrtf(ss * (1.0f / DM) + EPS);
;             float h[16];
; #pragma unroll
;             for (int i = 0; i < 16; ++i) h[i] = xv[i] * rstd * cs[i] + sh[i];
;             u32x4 w0, w1;
;             w0.x = pack2(h[0], h[1]); w0.y = pack2(h[2], h[3]); w0.z = pack2(h[4], h[5]); w0.w = pack2(h[6], h[7]);
;             w1.x = pack2(h[8], h[9]); w1.y = pack2(h[10], h[11]); w1.z = pack2(h[12], h[13]); w1.w = pack2(h[14], h[15]);
;             bf16_t* hp = hout + (size_t)row * DM + lane * 8;
;             *(u32x4*)hp = w0; *(u32x4*)(hp + 512) = w1;
;             if (wsc) {
;                 float mine = 0.f;
; #pragma unroll
;                 for (int j = 0; j < 12; ++j) {
;                     const float* wj = wl + j * DM + lane * 8;
;                     const f32x4 a0 = *(const f32x4*)wj, a1 = *(const f32x4*)(wj + 4), a2 = *(const f32x4*)(wj + 512), a3 = *(const f32x4*)(wj + 516);
;                     float s = h[0] * a0[0] + h[1] * a0[1] + h[2] * a0[2] + h[3] * a0[3] + h[4] * a1[0] + h[5] * a1[1] + h[6] * a1[2] + h[7] * a1[3]
;                             + h[8] * a2[0] + h[9] * a2[1] + h[10] * a2[2] + h[11] * a2[3] + h[12] * a3[0] + h[13] * a3[1] + h[14] * a3[2] + h[15] * a3[3];
;                     s = wave_sum(s);
;                     mine = (lane == j) ? s : mine;
;                 }
	v_pk_fma_f32 v[114:115], v[96:97], v[98:99], v[14:15]
	v_pk_mul_f32 v[98:99], v[100:101], v[124:125] op_sel_hi:[1,0]
	v_lshl_add_u64 v[100:101], s[86:87], 0, v[72:73]
	v_pk_fma_f32 v[116:117], v[94:95], v[98:99], v[16:17]
	v_pk_mul_f32 v[98:99], v[102:103], v[124:125] op_sel_hi:[1,0]
	s_mov_b32 s0, 0x3600000
	v_pk_fma_f32 v[110:111], v[92:93], v[98:99], v[10:11]
	v_pk_mul_f32 v[98:99], v[104:105], v[124:125] op_sel_hi:[1,0]
	v_add_co_u32_e32 v102, vcc, s0, v100
	v_pk_fma_f32 v[112:113], v[90:91], v[98:99], v[12:13]
	v_pk_mul_f32 v[98:99], v[106:107], v[124:125] op_sel_hi:[1,0]
	v_addc_co_u32_e32 v103, vcc, 0, v101, vcc
	v_pk_fma_f32 v[106:107], v[88:89], v[98:99], v[6:7]
	v_pk_mul_f32 v[98:99], v[108:109], v[124:125] op_sel_hi:[1,0]
	global_load_dwordx4 v[30:33], v[26:27], off nt
	s_nop 0
	global_load_dwordx4 v[26:29], v[74:75], off nt
	v_pk_fma_f32 v[108:109], v[86:87], v[98:99], v[8:9]
	v_pk_mul_f32 v[98:99], v[120:121], v[124:125] op_sel_hi:[1,0]
	v_cvt_pk_bf16_f32 v120, v114, v115
	v_pk_fma_f32 v[104:105], v[84:85], v[98:99], v[2:3]
	v_pk_mul_f32 v[98:99], v[122:123], v[124:125] op_sel_hi:[1,0]
	v_cvt_pk_bf16_f32 v121, v116, v117
	v_cvt_pk_bf16_f32 v122, v110, v111
	v_cvt_pk_bf16_f32 v123, v112, v113
	global_store_dwordx4 v[102:103], v[120:123], off
	ds_read_b128 v[120:123], v118
	v_pk_fma_f32 v[98:99], v[82:83], v[98:99], v[4:5]
	v_cvt_pk_bf16_f32 v124, v106, v107
	v_cvt_pk_bf16_f32 v125, v108, v109
	v_cvt_pk_bf16_f32 v126, v104, v105
	v_cvt_pk_bf16_f32 v127, v98, v99
	global_store_dwordx4 v[102:103], v[124:127], off offset:1024
	s_waitcnt lgkmcnt(0)
	v_mul_f32_e32 v67, v121, v115
	ds_read_b128 v[124:127], v118 offset:16
	ds_read_b128 v[128:131], v118 offset:2048
	ds_read_b128 v[132:135], v118 offset:2064
	v_fmac_f32_e32 v67, v120, v114
	v_fmac_f32_e32 v67, v122, v116
	v_fmac_f32_e32 v67, v123, v117
	s_waitcnt lgkmcnt(0)
	v_fmac_f32_e32 v67, v124, v110
	v_fmac_f32_e32 v67, v125, v111
	v_fmac_f32_e32 v67, v126, v112
	v_fmac_f32_e32 v67, v127, v113
	v_fmac_f32_e32 v67, v128, v106
	v_fmac_f32_e32 v67, v129, v107
	v_fmac_f32_e32 v67, v130, v108
	v_fmac_f32_e32 v67, v131, v109
	v_fmac_f32_e32 v67, v132, v104
	v_fmac_f32_e32 v67, v133, v105
	v_fmac_f32_e32 v67, v134, v98
	v_fmac_f32_e32 v67, v135, v99
	v_mov_b32_e32 v77, v1
	ds_read_b128 v[120:123], v118 offset:4096
	v_add_f32_dpp v67, v67, v67 row_shr:1 row_mask:0xf bank_mask:0xf bound_ctrl:1
	ds_read_b128 v[124:127], v118 offset:4112
	ds_read_b128 v[128:131], v118 offset:6144
	ds_read_b128 v[132:135], v118 offset:6160
	v_add_f32_dpp v67, v67, v67 row_shr:2 row_mask:0xf bank_mask:0xf bound_ctrl:1
	s_nop 1
	v_add_f32_dpp v67, v67, v67 row_shr:4 row_mask:0xf bank_mask:0xf bound_ctrl:1
	s_nop 1
	v_add_f32_dpp v67, v67, v67 row_shr:8 row_mask:0xf bank_mask:0xf bound_ctrl:1
	s_nop 1
	v_mov_b32_dpp v77, v67 row_bcast:15 row_mask:0xa bank_mask:0xf
	v_add_f32_e32 v67, v67, v77
	v_mov_b32_e32 v77, v1
	s_nop 1
	v_mov_b32_dpp v77, v67 row_bcast:31 row_mask:0xc bank_mask:0xf
	v_add_f32_e32 v67, v67, v77
	v_mov_b32_e32 v77, v1
	v_readlane_b32 s5, v67, 63
	s_waitcnt lgkmcnt(0)
	v_mul_f32_e32 v67, v115, v121
	v_fmac_f32_e32 v67, v114, v120
	v_fmac_f32_e32 v67, v116, v122
	v_fmac_f32_e32 v67, v117, v123
	v_fmac_f32_e32 v67, v110, v124
	v_fmac_f32_e32 v67, v111, v125
	v_fmac_f32_e32 v67, v112, v126
	v_fmac_f32_e32 v67, v113, v127
	v_fmac_f32_e32 v67, v106, v128
	v_fmac_f32_e32 v67, v107, v129
	v_fmac_f32_e32 v67, v108, v130
	v_fmac_f32_e32 v67, v109, v131
	v_fmac_f32_e32 v67, v104, v132
	v_fmac_f32_e32 v67, v105, v133
	v_fmac_f32_e32 v67, v98, v134
	v_fmac_f32_e32 v67, v99, v135
	ds_read_b128 v[120:123], v118 offset:8192
	ds_read_b128 v[124:127], v118 offset:8208
	ds_read_b128 v[128:131], v118 offset:10240
	ds_read_b128 v[132:135], v118 offset:10256
	v_add_f32_dpp v67, v67, v67 row_shr:1 row_mask:0xf bank_mask:0xf bound_ctrl:1
	s_nop 1
	v_add_f32_dpp v67, v67, v67 row_shr:2 row_mask:0xf bank_mask:0xf bound_ctrl:1
	s_nop 1
	v_add_f32_dpp v67, v67, v67 row_shr:4 row_mask:0xf bank_mask:0xf bound_ctrl:1
	s_nop 1
	v_add_f32_dpp v67, v67, v67 row_shr:8 row_mask:0xf bank_mask:0xf bound_ctrl:1
	s_nop 1
	v_mov_b32_dpp v77, v67 row_bcast:15 row_mask:0xa bank_mask:0xf
	v_add_f32_e32 v67, v67, v77
	v_mov_b32_e32 v77, v1
	s_nop 1
	v_mov_b32_dpp v77, v67 row_bcast:31 row_mask:0xc bank_mask:0xf
	v_add_f32_e32 v67, v67, v77
	v_mov_b32_e32 v77, v1
	v_readlane_b32 s36, v67, 63
	s_waitcnt lgkmcnt(0)
	v_mul_f32_e32 v67, v115, v121
	v_fmac_f32_e32 v67, v114, v120
	v_fmac_f32_e32 v67, v116, v122
	v_fmac_f32_e32 v67, v117, v123
	v_fmac_f32_e32 v67, v110, v124
	v_fmac_f32_e32 v67, v111, v125
	v_fmac_f32_e32 v67, v112, v126
	v_fmac_f32_e32 v67, v113, v127
	v_fmac_f32_e32 v67, v106, v128
	v_fmac_f32_e32 v67, v107, v129
	v_fmac_f32_e32 v67, v108, v130
	v_fmac_f32_e32 v67, v109, v131
	v_fmac_f32_e32 v67, v104, v132
	v_fmac_f32_e32 v67, v105, v133
	v_fmac_f32_e32 v67, v98, v134
	v_fmac_f32_e32 v67, v99, v135
	ds_read_b128 v[120:123], v118 offset:12288
	ds_read_b128 v[124:127], v118 offset:12304
	ds_read_b128 v[128:131], v118 offset:14336
	ds_read_b128 v[132:135], v118 offset:14352
	v_add_f32_dpp v67, v67, v67 row_shr:1 row_mask:0xf bank_mask:0xf bound_ctrl:1
	s_nop 1
	v_add_f32_dpp v67, v67, v67 row_shr:2 row_mask:0xf bank_mask:0xf bound_ctrl:1
	s_nop 1
	v_add_f32_dpp v67, v67, v67 row_shr:4 row_mask:0xf bank_mask:0xf bound_ctrl:1
	s_nop 1
	v_add_f32_dpp v67, v67, v67 row_shr:8 row_mask:0xf bank_mask:0xf bound_ctrl:1
	s_nop 1
	v_mov_b32_dpp v77, v67 row_bcast:15 row_mask:0xa bank_mask:0xf
	v_add_f32_e32 v67, v67, v77
	v_mov_b32_e32 v77, v1
	s_nop 1
	v_mov_b32_dpp v77, v67 row_bcast:31 row_mask:0xc bank_mask:0xf
	v_add_f32_e32 v67, v67, v77
	v_mov_b32_e32 v77, v1
	v_readlane_b32 s37, v67, 63
	s_waitcnt lgkmcnt(0)
; __device__ __forceinline__ void phase_norm(const Params& p, unsigned char* lds, const float* __restrict__ xin, const float* g, const float* mod  , int shift_off, int scale_off, bf16_t* __restrict__ hout, const float* wsc  , float* scal) {
;     ...
;                 for (int j = 0; j < 12; ++j) {
;                     const float* wj = wl + j * DM + lane * 8;
;                     const f32x4 a0 = *(const f32x4*)wj, a1 = *(const f32x4*)(wj + 4), a2 = *(const f32x4*)(wj + 512), a3 = *(const f32x4*)(wj + 516);
;                     float s = h[0] * a0[0] + h[1] * a0[1] + h[2] * a0[2] + h[3] * a0[3] + h[4] * a1[0] + h[5] * a1[1] + h[6] * a1[2] + h[7] * a1[3]
;                             + h[8] * a2[0] + h[9] * a2[1] + h[10] * a2[2] + h[11] * a2[3] + h[12] * a3[0] + h[13] * a3[1] + h[14] * a3[2] + h[15] * a3[3];
;                     s = wave_sum(s);
;                     mine = (lane == j) ? s : mine;
;                 }
	v_mul_f32_e32 v67, v115, v121
	v_fmac_f32_e32 v67, v114, v120
	v_fmac_f32_e32 v67, v116, v122
	v_fmac_f32_e32 v67, v117, v123
	v_fmac_f32_e32 v67, v110, v124
	v_fmac_f32_e32 v67, v111, v125
	v_fmac_f32_e32 v67, v112, v126
	v_fmac_f32_e32 v67, v113, v127
	v_fmac_f32_e32 v67, v106, v128
	v_fmac_f32_e32 v67, v107, v129
	v_fmac_f32_e32 v67, v108, v130
	v_fmac_f32_e32 v67, v109, v131
	v_fmac_f32_e32 v67, v104, v132
	v_fmac_f32_e32 v67, v105, v133
	v_fmac_f32_e32 v67, v98, v134
	v_fmac_f32_e32 v67, v99, v135
	ds_read_b128 v[120:123], v118 offset:16384
	ds_read_b128 v[124:127], v118 offset:16400
	ds_read_b128 v[128:131], v118 offset:18432
	ds_read_b128 v[132:135], v118 offset:18448
	v_add_f32_dpp v67, v67, v67 row_shr:1 row_mask:0xf bank_mask:0xf bound_ctrl:1
	s_nop 1
	v_add_f32_dpp v67, v67, v67 row_shr:2 row_mask:0xf bank_mask:0xf bound_ctrl:1
	s_nop 1
	v_add_f32_dpp v67, v67, v67 row_shr:4 row_mask:0xf bank_mask:0xf bound_ctrl:1
	s_nop 1
	v_add_f32_dpp v67, v67, v67 row_shr:8 row_mask:0xf bank_mask:0xf bound_ctrl:1
	s_nop 1
	v_mov_b32_dpp v77, v67 row_bcast:15 row_mask:0xa bank_mask:0xf
	v_add_f32_e32 v67, v67, v77
	v_mov_b32_e32 v77, v1
	s_nop 1
	v_mov_b32_dpp v77, v67 row_bcast:31 row_mask:0xc bank_mask:0xf
	v_add_f32_e32 v67, v67, v77
	v_mov_b32_e32 v77, v1
	v_readlane_b32 s41, v67, 63
	s_waitcnt lgkmcnt(0)
	v_mul_f32_e32 v67, v115, v121
	v_fmac_f32_e32 v67, v114, v120
	v_fmac_f32_e32 v67, v116, v122
	v_fmac_f32_e32 v67, v117, v123
	v_fmac_f32_e32 v67, v110, v124
	v_fmac_f32_e32 v67, v111, v125
	v_fmac_f32_e32 v67, v112, v126
	v_fmac_f32_e32 v67, v113, v127
	v_fmac_f32_e32 v67, v106, v128
	v_fmac_f32_e32 v67, v107, v129
	v_fmac_f32_e32 v67, v108, v130
	v_fmac_f32_e32 v67, v109, v131
	v_fmac_f32_e32 v67, v104, v132
	v_fmac_f32_e32 v67, v105, v133
	v_fmac_f32_e32 v67, v98, v134
	v_fmac_f32_e32 v67, v99, v135
	ds_read_b128 v[120:123], v118 offset:20480
	ds_read_b128 v[124:127], v118 offset:20496
	ds_read_b128 v[128:131], v118 offset:22528
	ds_read_b128 v[132:135], v118 offset:22544
	v_add_f32_dpp v67, v67, v67 row_shr:1 row_mask:0xf bank_mask:0xf bound_ctrl:1
	s_nop 1
	v_add_f32_dpp v67, v67, v67 row_shr:2 row_mask:0xf bank_mask:0xf bound_ctrl:1
	s_nop 1
	v_add_f32_dpp v67, v67, v67 row_shr:4 row_mask:0xf bank_mask:0xf bound_ctrl:1
	s_nop 1
	v_add_f32_dpp v67, v67, v67 row_shr:8 row_mask:0xf bank_mask:0xf bound_ctrl:1
	s_nop 1
	v_mov_b32_dpp v77, v67 row_bcast:15 row_mask:0xa bank_mask:0xf
	v_add_f32_e32 v67, v67, v77
	v_mov_b32_e32 v77, v1
	s_nop 1
	v_mov_b32_dpp v77, v67 row_bcast:31 row_mask:0xc bank_mask:0xf
	v_add_f32_e32 v67, v67, v77
	v_mov_b32_e32 v77, v1
	v_readlane_b32 s43, v67, 63
	s_waitcnt lgkmcnt(0)
	v_mul_f32_e32 v67, v115, v121
	v_fmac_f32_e32 v67, v114, v120
	v_fmac_f32_e32 v67, v116, v122
	v_fmac_f32_e32 v67, v117, v123
	v_fmac_f32_e32 v67, v110, v124
	v_fmac_f32_e32 v67, v111, v125
	v_fmac_f32_e32 v67, v112, v126
	v_fmac_f32_e32 v67, v113, v127
	v_fmac_f32_e32 v67, v106, v128
	v_fmac_f32_e32 v67, v107, v129
	v_fmac_f32_e32 v67, v108, v130
	v_fmac_f32_e32 v67, v109, v131
	v_fmac_f32_e32 v67, v104, v132
	v_fmac_f32_e32 v67, v105, v133
	v_fmac_f32_e32 v67, v98, v134
	v_fmac_f32_e32 v67, v99, v135
	ds_read_b128 v[120:123], v118 offset:24576
	ds_read_b128 v[124:127], v118 offset:24592
	ds_read_b128 v[128:131], v118 offset:26624
	ds_read_b128 v[132:135], v118 offset:26640
	v_add_f32_dpp v67, v67, v67 row_shr:1 row_mask:0xf bank_mask:0xf bound_ctrl:1
	s_nop 1
	v_add_f32_dpp v67, v67, v67 row_shr:2 row_mask:0xf bank_mask:0xf bound_ctrl:1
	s_nop 1
	v_add_f32_dpp v67, v67, v67 row_shr:4 row_mask:0xf bank_mask:0xf bound_ctrl:1
	s_nop 1
	v_add_f32_dpp v67, v67, v67 row_shr:8 row_mask:0xf bank_mask:0xf bound_ctrl:1
	s_nop 1
	v_mov_b32_dpp v77, v67 row_bcast:15 row_mask:0xa bank_mask:0xf
	v_add_f32_e32 v67, v67, v77
	v_mov_b32_e32 v77, v1
	s_nop 1
	v_mov_b32_dpp v77, v67 row_bcast:31 row_mask:0xc bank_mask:0xf
	v_add_f32_e32 v67, v67, v77
	v_mov_b32_e32 v77, v1
	v_readlane_b32 s45, v67, 63
	s_waitcnt lgkmcnt(0)
	v_mul_f32_e32 v67, v115, v121
	v_fmac_f32_e32 v67, v114, v120
	v_fmac_f32_e32 v67, v116, v122
	v_fmac_f32_e32 v67, v117, v123
	v_fmac_f32_e32 v67, v110, v124
	v_fmac_f32_e32 v67, v111, v125
	v_fmac_f32_e32 v67, v112, v126
	v_fmac_f32_e32 v67, v113, v127
	v_fmac_f32_e32 v67, v106, v128
	v_fmac_f32_e32 v67, v107, v129
	v_fmac_f32_e32 v67, v108, v130
	v_fmac_f32_e32 v67, v109, v131
	v_fmac_f32_e32 v67, v104, v132
	v_fmac_f32_e32 v67, v105, v133
	v_fmac_f32_e32 v67, v98, v134
	v_fmac_f32_e32 v67, v99, v135
	ds_read_b128 v[120:123], v118 offset:28672
	ds_read_b128 v[124:127], v118 offset:28688
	ds_read_b128 v[128:131], v118 offset:30720
	ds_read_b128 v[132:135], v118 offset:30736
	v_add_f32_dpp v67, v67, v67 row_shr:1 row_mask:0xf bank_mask:0xf bound_ctrl:1
	s_nop 1
	v_add_f32_dpp v67, v67, v67 row_shr:2 row_mask:0xf bank_mask:0xf bound_ctrl:1
	s_nop 1
	v_add_f32_dpp v67, v67, v67 row_shr:4 row_mask:0xf bank_mask:0xf bound_ctrl:1
	s_nop 1
	v_add_f32_dpp v67, v67, v67 row_shr:8 row_mask:0xf bank_mask:0xf bound_ctrl:1
	s_nop 1
	v_mov_b32_dpp v77, v67 row_bcast:15 row_mask:0xa bank_mask:0xf
	v_add_f32_e32 v67, v67, v77
	v_mov_b32_e32 v77, v1
	s_nop 1
	v_mov_b32_dpp v77, v67 row_bcast:31 row_mask:0xc bank_mask:0xf
	v_add_f32_e32 v67, v67, v77
	v_mov_b32_e32 v77, v1
	v_readlane_b32 s47, v67, 63
	s_waitcnt lgkmcnt(0)
; __device__ __forceinline__ void phase_norm(const Params& p, unsigned char* lds, const float* __restrict__ xin, const float* g, const float* mod  , int shift_off, int scale_off, bf16_t* __restrict__ hout, const float* wsc  , float* scal) {
;     ...
;                 for (int j = 0; j < 12; ++j) {
;                     const float* wj = wl + j * DM + lane * 8;
;                     const f32x4 a0 = *(const f32x4*)wj, a1 = *(const f32x4*)(wj + 4), a2 = *(const f32x4*)(wj + 512), a3 = *(const f32x4*)(wj + 516);
;                     float s = h[0] * a0[0] + h[1] * a0[1] + h[2] * a0[2] + h[3] * a0[3] + h[4] * a1[0] + h[5] * a1[1] + h[6] * a1[2] + h[7] * a1[3]
;                             + h[8] * a2[0] + h[9] * a2[1] + h[10] * a2[2] + h[11] * a2[3] + h[12] * a3[0] + h[13] * a3[1] + h[14] * a3[2] + h[15] * a3[3];
;                     s = wave_sum(s);
;                     mine = (lane == j) ? s : mine;
;                 }
;                 if (lane < 12) scal[(size_t)row * 16 + lane] = mine;
	v_mul_f32_e32 v67, v115, v121
	v_fmac_f32_e32 v67, v114, v120
	v_fmac_f32_e32 v67, v116, v122
	v_fmac_f32_e32 v67, v117, v123
	v_fmac_f32_e32 v67, v110, v124
	v_fmac_f32_e32 v67, v111, v125
	v_fmac_f32_e32 v67, v112, v126
	v_fmac_f32_e32 v67, v113, v127
	v_fmac_f32_e32 v67, v106, v128
	v_fmac_f32_e32 v67, v107, v129
	v_fmac_f32_e32 v67, v108, v130
	v_fmac_f32_e32 v67, v109, v131
	v_fmac_f32_e32 v67, v104, v132
	v_fmac_f32_e32 v67, v105, v133
	v_fmac_f32_e32 v67, v98, v134
	v_fmac_f32_e32 v67, v99, v135
	ds_read_b128 v[120:123], v118 offset:32768
	ds_read_b128 v[124:127], v118 offset:32784
	ds_read_b128 v[128:131], v118 offset:34816
	ds_read_b128 v[132:135], v118 offset:34832
	v_add_f32_dpp v67, v67, v67 row_shr:1 row_mask:0xf bank_mask:0xf bound_ctrl:1
	s_nop 1
	v_add_f32_dpp v67, v67, v67 row_shr:2 row_mask:0xf bank_mask:0xf bound_ctrl:1
	s_nop 1
	v_add_f32_dpp v67, v67, v67 row_shr:4 row_mask:0xf bank_mask:0xf bound_ctrl:1
	s_nop 1
	v_add_f32_dpp v67, v67, v67 row_shr:8 row_mask:0xf bank_mask:0xf bound_ctrl:1
	s_nop 1
	v_mov_b32_dpp v77, v67 row_bcast:15 row_mask:0xa bank_mask:0xf
	v_add_f32_e32 v67, v67, v77
	v_mov_b32_e32 v77, v1
	s_nop 1
	v_mov_b32_dpp v77, v67 row_bcast:31 row_mask:0xc bank_mask:0xf
	v_add_f32_e32 v67, v67, v77
	v_mov_b32_e32 v77, v1
	v_readlane_b32 s48, v67, 63
	s_waitcnt lgkmcnt(0)
	v_mul_f32_e32 v67, v115, v121
	v_fmac_f32_e32 v67, v114, v120
	v_fmac_f32_e32 v67, v116, v122
	v_fmac_f32_e32 v67, v117, v123
	v_fmac_f32_e32 v67, v110, v124
	v_fmac_f32_e32 v67, v111, v125
	v_fmac_f32_e32 v67, v112, v126
	v_fmac_f32_e32 v67, v113, v127
	v_fmac_f32_e32 v67, v106, v128
	v_fmac_f32_e32 v67, v107, v129
	v_fmac_f32_e32 v67, v108, v130
	v_fmac_f32_e32 v67, v109, v131
	v_fmac_f32_e32 v67, v104, v132
	v_fmac_f32_e32 v67, v105, v133
	v_fmac_f32_e32 v67, v98, v134
	v_fmac_f32_e32 v67, v99, v135
	ds_read_b128 v[120:123], v118 offset:36864
	ds_read_b128 v[124:127], v118 offset:36880
	ds_read_b128 v[128:131], v118 offset:38912
	ds_read_b128 v[132:135], v118 offset:38928
	v_add_f32_dpp v67, v67, v67 row_shr:1 row_mask:0xf bank_mask:0xf bound_ctrl:1
	s_nop 1
	v_add_f32_dpp v67, v67, v67 row_shr:2 row_mask:0xf bank_mask:0xf bound_ctrl:1
	s_nop 1
	v_add_f32_dpp v67, v67, v67 row_shr:4 row_mask:0xf bank_mask:0xf bound_ctrl:1
	s_nop 1
	v_add_f32_dpp v67, v67, v67 row_shr:8 row_mask:0xf bank_mask:0xf bound_ctrl:1
	s_nop 1
	v_mov_b32_dpp v77, v67 row_bcast:15 row_mask:0xa bank_mask:0xf
	v_add_f32_e32 v67, v67, v77
	v_mov_b32_e32 v77, v1
	s_nop 1
	v_mov_b32_dpp v77, v67 row_bcast:31 row_mask:0xc bank_mask:0xf
	v_add_f32_e32 v67, v67, v77
	v_mov_b32_e32 v77, v1
	v_readlane_b32 s51, v67, 63
	s_waitcnt lgkmcnt(0)
	v_mul_f32_e32 v67, v115, v121
	v_fmac_f32_e32 v67, v114, v120
	v_fmac_f32_e32 v67, v116, v122
	v_fmac_f32_e32 v67, v117, v123
	v_fmac_f32_e32 v67, v110, v124
	v_fmac_f32_e32 v67, v111, v125
	v_fmac_f32_e32 v67, v112, v126
	v_fmac_f32_e32 v67, v113, v127
	v_fmac_f32_e32 v67, v106, v128
	v_fmac_f32_e32 v67, v107, v129
	v_fmac_f32_e32 v67, v108, v130
	v_fmac_f32_e32 v67, v109, v131
	v_fmac_f32_e32 v67, v104, v132
	v_fmac_f32_e32 v67, v105, v133
	v_fmac_f32_e32 v67, v98, v134
	v_fmac_f32_e32 v67, v99, v135
	ds_read_b128 v[120:123], v118 offset:40960
	ds_read_b128 v[124:127], v118 offset:40976
	ds_read_b128 v[128:131], v118 offset:43008
	ds_read_b128 v[132:135], v118 offset:43024
	v_add_f32_dpp v67, v67, v67 row_shr:1 row_mask:0xf bank_mask:0xf bound_ctrl:1
	s_nop 1
	v_add_f32_dpp v67, v67, v67 row_shr:2 row_mask:0xf bank_mask:0xf bound_ctrl:1
	s_nop 1
	v_add_f32_dpp v67, v67, v67 row_shr:4 row_mask:0xf bank_mask:0xf bound_ctrl:1
	s_nop 1
	v_add_f32_dpp v67, v67, v67 row_shr:8 row_mask:0xf bank_mask:0xf bound_ctrl:1
	s_nop 1
	v_mov_b32_dpp v77, v67 row_bcast:15 row_mask:0xa bank_mask:0xf
	v_add_f32_e32 v67, v67, v77
	v_mov_b32_e32 v77, v1
	s_nop 1
	v_mov_b32_dpp v77, v67 row_bcast:31 row_mask:0xc bank_mask:0xf
	v_add_f32_e32 v67, v67, v77
	v_mov_b32_e32 v77, v1
	v_readlane_b32 s52, v67, 63
	s_waitcnt lgkmcnt(0)
	v_mul_f32_e32 v67, v115, v121
	v_fmac_f32_e32 v67, v114, v120
	v_fmac_f32_e32 v67, v116, v122
	v_fmac_f32_e32 v67, v117, v123
	v_fmac_f32_e32 v67, v110, v124
	v_fmac_f32_e32 v67, v111, v125
	v_fmac_f32_e32 v67, v112, v126
	v_fmac_f32_e32 v67, v113, v127
	v_fmac_f32_e32 v67, v106, v128
	v_fmac_f32_e32 v67, v107, v129
	v_fmac_f32_e32 v67, v108, v130
	v_fmac_f32_e32 v67, v109, v131
	v_fmac_f32_e32 v67, v104, v132
	v_fmac_f32_e32 v67, v105, v133
	v_fmac_f32_e32 v67, v98, v134
	v_fmac_f32_e32 v67, v99, v135
	ds_read_b128 v[120:123], v118 offset:45056
	ds_read_b128 v[124:127], v118 offset:45072
	ds_read_b128 v[128:131], v118 offset:47104
	ds_read_b128 v[132:135], v118 offset:47120
	v_add_f32_dpp v67, v67, v67 row_shr:1 row_mask:0xf bank_mask:0xf bound_ctrl:1
	s_nop 1
	v_add_f32_dpp v67, v67, v67 row_shr:2 row_mask:0xf bank_mask:0xf bound_ctrl:1
	s_nop 1
	v_add_f32_dpp v67, v67, v67 row_shr:4 row_mask:0xf bank_mask:0xf bound_ctrl:1
	s_nop 1
	v_add_f32_dpp v67, v67, v67 row_shr:8 row_mask:0xf bank_mask:0xf bound_ctrl:1
	s_nop 1
	v_mov_b32_dpp v77, v67 row_bcast:15 row_mask:0xa bank_mask:0xf
	v_add_f32_e32 v67, v67, v77
	v_mov_b32_e32 v77, v1
	s_nop 1
	v_mov_b32_dpp v77, v67 row_bcast:31 row_mask:0xc bank_mask:0xf
	v_add_f32_e32 v67, v67, v77
	v_mov_b32_e32 v77, v1
	v_readlane_b32 s54, v67, 63
	s_waitcnt lgkmcnt(0)
	v_mul_f32_e32 v67, v115, v121
	v_fmac_f32_e32 v67, v114, v120
	v_fmac_f32_e32 v67, v116, v122
	v_fmac_f32_e32 v67, v117, v123
	v_fmac_f32_e32 v67, v110, v124
	v_fmac_f32_e32 v67, v111, v125
	v_fmac_f32_e32 v67, v112, v126
	v_fmac_f32_e32 v67, v113, v127
	v_fmac_f32_e32 v67, v106, v128
	v_fmac_f32_e32 v67, v107, v129
	v_fmac_f32_e32 v67, v108, v130
	v_fmac_f32_e32 v67, v109, v131
	v_fmac_f32_e32 v67, v104, v132
	v_fmac_f32_e32 v67, v105, v133
	v_fmac_f32_e32 v67, v98, v134
	v_fmac_f32_e32 v67, v99, v135
	v_lshl_add_u64 v[98:99], s[86:87], 0, v[70:71]
	s_nop 0
	v_add_f32_dpp v67, v67, v67 row_shr:1 row_mask:0xf bank_mask:0xf bound_ctrl:1
	s_nop 1
	v_add_f32_dpp v67, v67, v67 row_shr:2 row_mask:0xf bank_mask:0xf bound_ctrl:1
	s_nop 1
	v_add_f32_dpp v67, v67, v67 row_shr:4 row_mask:0xf bank_mask:0xf bound_ctrl:1
	s_nop 1
	v_add_f32_dpp v67, v67, v67 row_shr:8 row_mask:0xf bank_mask:0xf bound_ctrl:1
	s_nop 1
	v_mov_b32_dpp v77, v67 row_bcast:15 row_mask:0xa bank_mask:0xf
	v_add_f32_e32 v67, v67, v77
	v_mov_b32_e32 v77, v1
	s_nop 1
	v_mov_b32_dpp v77, v67 row_bcast:31 row_mask:0xc bank_mask:0xf
	v_add_f32_e32 v67, v67, v77
	s_nop 0
	v_readlane_b32 s55, v67, 63
	s_and_saveexec_b64 s[0:1], s[6:7]
	s_cbranch_execz .LBB0_760
; __device__ __forceinline__ unsigned pack2(float lo, float hi) { return pg8::cvt_pk_bf16(lo, hi); }
; __device__ __forceinline__ void phase_norm(const Params& p, unsigned char* lds, const float* __restrict__ xin, const float* g, const float* mod  , int shift_off, int scale_off, bf16_t* __restrict__ hout, const float* wsc  , float* scal) {
;     ...
;             const int row = rb + r4 + q;
;             const f32x4 x0 = xq[q][0], x1 = xq[q][1], x2 = xq[q][2], x3 = xq[q][3];
;             float xv[16] = {x0[0], x0[1], x0[2], x0[3], x1[0], x1[1], x1[2], x1[3], x2[0], x2[1], x2[2], x2[3], x3[0], x3[1], x3[2], x3[3]};
;             float ss = 0.f;
; #pragma unroll
;             for (int i = 0; i < 16; ++i) ss += xv[i] * xv[i];
;             ss = wave_sum(ss);
;             const float rstd = rsqrtf(ss * (1.0f / DM) + EPS);
;             float h[16];
; #pragma unroll
;             for (int i = 0; i < 16; ++i) h[i] = xv[i] * rstd * cs[i] + sh[i];
;             u32x4 w0, w1;
;             w0.x = pack2(h[0], h[1]); w0.y = pack2(h[2], h[3]); w0.z = pack2(h[4], h[5]); w0.w = pack2(h[6], h[7]);
;             w1.x = pack2(h[8], h[9]); w1.y = pack2(h[10], h[11]); w1.z = pack2(h[12], h[13]); w1.w = pack2(h[14], h[15]);
;             bf16_t* hp = hout + (size_t)row * DM + lane * 8;
;             *(u32x4*)hp = w0; *(u32x4*)(hp + 512) = w1;
;             if (wsc) {
;                 float mine = 0.f;
; #pragma unroll
;                 for (int j = 0; j < 12; ++j) {
;                     const float* wj = wl + j * DM + lane * 8;
;                     const f32x4 a0 = *(const f32x4*)wj, a1 = *(const f32x4*)(wj + 4), a2 = *(const f32x4*)(wj + 512), a3 = *(const f32x4*)(wj + 516);
;                     float s = h[0] * a0[0] + h[1] * a0[1] + h[2] * a0[2] + h[3] * a0[3] + h[4] * a1[0] + h[5] * a1[1] + h[6] * a1[2] + h[7] * a1[3]
;                             + h[8] * a2[0] + h[9] * a2[1] + h[10] * a2[2] + h[11] * a2[3] + h[12] * a3[0] + h[13] * a3[1] + h[14] * a3[2] + h[15] * a3[3];
;                     s = wave_sum(s);
;                     mine = (lane == j) ? s : mine;
;                 }
;                 if (lane < 12) scal[(size_t)row * 16 + lane] = mine;
	v_mov_b32_e32 v67, s5
	v_cndmask_b32_e64 v67, 0, v67, s[30:31]
	v_mov_b32_e32 v77, s36
	v_cndmask_b32_e64 v67, v67, v77, s[28:29]
	v_mov_b32_e32 v77, s37
	v_cndmask_b32_e64 v67, v67, v77, s[26:27]
	v_mov_b32_e32 v77, s41
	v_cndmask_b32_e64 v67, v67, v77, s[24:25]
	v_mov_b32_e32 v77, s43
	v_cndmask_b32_e64 v67, v67, v77, s[22:23]
	v_mov_b32_e32 v77, s45
	v_cndmask_b32_e64 v67, v67, v77, s[20:21]
	v_mov_b32_e32 v77, s47
	v_cndmask_b32_e64 v67, v67, v77, s[18:19]
	v_mov_b32_e32 v77, s48
	v_cndmask_b32_e64 v67, v67, v77, s[16:17]
	v_mov_b32_e32 v77, s51
	v_cndmask_b32_e64 v67, v67, v77, s[14:15]
	v_mov_b32_e32 v77, s52
	v_cndmask_b32_e64 v67, v67, v77, s[12:13]
	v_mov_b32_e32 v77, s54
	v_cndmask_b32_e64 v67, v67, v77, s[10:11]
	v_mov_b32_e32 v77, s55
	v_add_co_u32_e32 v104, vcc, 0x100000, v98
	v_cndmask_b32_e64 v67, v67, v77, s[8:9]
	s_nop 0
	v_addc_co_u32_e32 v105, vcc, 0, v99, vcc
	global_store_dword v[104:105], v67, off
.LBB0_760:
	s_or_b64 exec, exec, s[0:1]
	v_mul_f32_e32 v67, v63, v63
	v_fmac_f32_e32 v67, v62, v62
	v_fmac_f32_e32 v67, v64, v64
	v_fmac_f32_e32 v67, v65, v65
	v_fmac_f32_e32 v67, v58, v58
	v_fmac_f32_e32 v67, v59, v59
	v_fmac_f32_e32 v67, v60, v60
	v_fmac_f32_e32 v67, v61, v61
	v_fmac_f32_e32 v67, v54, v54
	v_fmac_f32_e32 v67, v55, v55
	v_fmac_f32_e32 v67, v56, v56
	v_fmac_f32_e32 v67, v57, v57
	v_pk_mul_f32 v[106:107], v[50:51], v[50:51]
	v_pk_mul_f32 v[104:105], v[52:53], v[52:53]
	v_add_f32_e32 v67, v106, v67
	v_add_f32_e32 v67, v107, v67
	v_add_f32_e32 v67, v104, v67
	v_add_f32_e32 v67, v105, v67
	v_mov_b32_e32 v77, v1
	s_nop 0
	v_add_f32_dpp v67, v67, v67 row_shr:1 row_mask:0xf bank_mask:0xf bound_ctrl:1
	s_nop 1
	v_add_f32_dpp v67, v67, v67 row_shr:2 row_mask:0xf bank_mask:0xf bound_ctrl:1
	s_nop 1
	v_add_f32_dpp v67, v67, v67 row_shr:4 row_mask:0xf bank_mask:0xf bound_ctrl:1
	s_nop 1
	v_add_f32_dpp v67, v67, v67 row_shr:8 row_mask:0xf bank_mask:0xf bound_ctrl:1
	s_nop 1
	v_mov_b32_dpp v77, v67 row_bcast:15 row_mask:0xa bank_mask:0xf
	v_add_f32_e32 v67, v67, v77
	v_mov_b32_e32 v77, v1
	s_nop 1
	v_mov_b32_dpp v77, v67 row_bcast:31 row_mask:0xc bank_mask:0xf
	v_add_f32_e32 v67, v67, v77
	s_nop 0
	v_readlane_b32 s0, v67, 63
	s_nop 1
	v_fma_f32 v67, s0, v217, v213
	v_mul_f32_e32 v77, 0x4b800000, v67
	v_cmp_gt_f32_e32 vcc, s44, v67
	s_nop 1
	v_cndmask_b32_e32 v67, v67, v77, vcc
	v_rsq_f32_e32 v67, v67
	s_nop 0
	v_mul_f32_e32 v77, 0x45800000, v67
	v_cndmask_b32_e32 v106, v67, v77, vcc
	v_pk_mul_f32 v[62:63], v[62:63], v[106:107] op_sel_hi:[1,0]
	v_pk_mul_f32 v[58:59], v[58:59], v[106:107] op_sel_hi:[1,0]
	v_pk_fma_f32 v[104:105], v[96:97], v[62:63], v[14:15]
	v_pk_mul_f32 v[62:63], v[64:65], v[106:107] op_sel_hi:[1,0]
	v_pk_mul_f32 v[54:55], v[54:55], v[106:107] op_sel_hi:[1,0]
	v_pk_fma_f32 v[64:65], v[94:95], v[62:63], v[16:17]
	v_pk_fma_f32 v[62:63], v[92:93], v[58:59], v[10:11]
	v_pk_mul_f32 v[58:59], v[60:61], v[106:107] op_sel_hi:[1,0]
	v_pk_mul_f32 v[50:51], v[50:51], v[106:107] op_sel_hi:[1,0]
	v_pk_fma_f32 v[60:61], v[90:91], v[58:59], v[12:13]
	v_pk_fma_f32 v[58:59], v[88:89], v[54:55], v[6:7]
	v_pk_mul_f32 v[54:55], v[56:57], v[106:107] op_sel_hi:[1,0]
	v_cvt_pk_bf16_f32 v108, v62, v63
	v_pk_fma_f32 v[56:57], v[86:87], v[54:55], v[8:9]
	v_pk_fma_f32 v[54:55], v[84:85], v[50:51], v[2:3]
	v_pk_mul_f32 v[50:51], v[52:53], v[106:107] op_sel_hi:[1,0]
	v_cvt_pk_bf16_f32 v106, v104, v105
	v_cvt_pk_bf16_f32 v107, v64, v65
	v_cvt_pk_bf16_f32 v109, v60, v61
	global_store_dwordx4 v[102:103], v[106:109], off offset:2048
	ds_read_b128 v[106:109], v118
	v_pk_fma_f32 v[50:51], v[82:83], v[50:51], v[4:5]
	v_cvt_pk_bf16_f32 v110, v58, v59
	v_cvt_pk_bf16_f32 v111, v56, v57
	v_cvt_pk_bf16_f32 v112, v54, v55
	v_cvt_pk_bf16_f32 v113, v50, v51
	global_store_dwordx4 v[102:103], v[110:113], off offset:3072
	s_waitcnt lgkmcnt(0)
	v_mul_f32_e32 v52, v107, v105
	ds_read_b128 v[110:113], v118 offset:16
	ds_read_b128 v[114:117], v118 offset:2048
	ds_read_b128 v[120:123], v118 offset:2064
	v_fmac_f32_e32 v52, v106, v104
	v_fmac_f32_e32 v52, v108, v64
	v_fmac_f32_e32 v52, v109, v65
	s_waitcnt lgkmcnt(0)
	v_fmac_f32_e32 v52, v110, v62
	v_fmac_f32_e32 v52, v111, v63
	v_fmac_f32_e32 v52, v112, v60
	v_fmac_f32_e32 v52, v113, v61
	v_fmac_f32_e32 v52, v114, v58
	v_fmac_f32_e32 v52, v115, v59
	v_fmac_f32_e32 v52, v116, v56
	v_fmac_f32_e32 v52, v117, v57
	v_fmac_f32_e32 v52, v120, v54
	v_fmac_f32_e32 v52, v121, v55
	v_fmac_f32_e32 v52, v122, v50
	v_fmac_f32_e32 v52, v123, v51
	v_mov_b32_e32 v53, v1
	ds_read_b128 v[106:109], v118 offset:4096
	v_add_f32_dpp v52, v52, v52 row_shr:1 row_mask:0xf bank_mask:0xf bound_ctrl:1
	ds_read_b128 v[110:113], v118 offset:4112
	ds_read_b128 v[114:117], v118 offset:6144
	ds_read_b128 v[120:123], v118 offset:6160
	v_add_f32_dpp v52, v52, v52 row_shr:2 row_mask:0xf bank_mask:0xf bound_ctrl:1
	s_nop 1
	v_add_f32_dpp v52, v52, v52 row_shr:4 row_mask:0xf bank_mask:0xf bound_ctrl:1
	s_nop 1
	v_add_f32_dpp v52, v52, v52 row_shr:8 row_mask:0xf bank_mask:0xf bound_ctrl:1
	s_nop 1
	v_mov_b32_dpp v53, v52 row_bcast:15 row_mask:0xa bank_mask:0xf
	v_add_f32_e32 v52, v52, v53
	v_mov_b32_e32 v53, v1
	s_nop 1
	v_mov_b32_dpp v53, v52 row_bcast:31 row_mask:0xc bank_mask:0xf
	v_add_f32_e32 v52, v52, v53
	v_mov_b32_e32 v53, v1
	v_readlane_b32 s5, v52, 63
	s_waitcnt lgkmcnt(0)
; __device__ __forceinline__ void phase_norm(const Params& p, unsigned char* lds, const float* __restrict__ xin, const float* g, const float* mod  , int shift_off, int scale_off, bf16_t* __restrict__ hout, const float* wsc  , float* scal) {
;     ...
;                 for (int j = 0; j < 12; ++j) {
;                     const float* wj = wl + j * DM + lane * 8;
;                     const f32x4 a0 = *(const f32x4*)wj, a1 = *(const f32x4*)(wj + 4), a2 = *(const f32x4*)(wj + 512), a3 = *(const f32x4*)(wj + 516);
;                     float s = h[0] * a0[0] + h[1] * a0[1] + h[2] * a0[2] + h[3] * a0[3] + h[4] * a1[0] + h[5] * a1[1] + h[6] * a1[2] + h[7] * a1[3]
;                             + h[8] * a2[0] + h[9] * a2[1] + h[10] * a2[2] + h[11] * a2[3] + h[12] * a3[0] + h[13] * a3[1] + h[14] * a3[2] + h[15] * a3[3];
;                     s = wave_sum(s);
;                     mine = (lane == j) ? s : mine;
;                 }
	v_mul_f32_e32 v52, v105, v107
	v_fmac_f32_e32 v52, v104, v106
	v_fmac_f32_e32 v52, v64, v108
	v_fmac_f32_e32 v52, v65, v109
	v_fmac_f32_e32 v52, v62, v110
	v_fmac_f32_e32 v52, v63, v111
	v_fmac_f32_e32 v52, v60, v112
	v_fmac_f32_e32 v52, v61, v113
	v_fmac_f32_e32 v52, v58, v114
	v_fmac_f32_e32 v52, v59, v115
	v_fmac_f32_e32 v52, v56, v116
	v_fmac_f32_e32 v52, v57, v117
	v_fmac_f32_e32 v52, v54, v120
	v_fmac_f32_e32 v52, v55, v121
	v_fmac_f32_e32 v52, v50, v122
	v_fmac_f32_e32 v52, v51, v123
	ds_read_b128 v[106:109], v118 offset:8192
	ds_read_b128 v[110:113], v118 offset:8208
	ds_read_b128 v[114:117], v118 offset:10240
	ds_read_b128 v[120:123], v118 offset:10256
	v_add_f32_dpp v52, v52, v52 row_shr:1 row_mask:0xf bank_mask:0xf bound_ctrl:1
	s_nop 1
	v_add_f32_dpp v52, v52, v52 row_shr:2 row_mask:0xf bank_mask:0xf bound_ctrl:1
	s_nop 1
	v_add_f32_dpp v52, v52, v52 row_shr:4 row_mask:0xf bank_mask:0xf bound_ctrl:1
	s_nop 1
	v_add_f32_dpp v52, v52, v52 row_shr:8 row_mask:0xf bank_mask:0xf bound_ctrl:1
	s_nop 1
	v_mov_b32_dpp v53, v52 row_bcast:15 row_mask:0xa bank_mask:0xf
	v_add_f32_e32 v52, v52, v53
	v_mov_b32_e32 v53, v1
	s_nop 1
	v_mov_b32_dpp v53, v52 row_bcast:31 row_mask:0xc bank_mask:0xf
	v_add_f32_e32 v52, v52, v53
	v_mov_b32_e32 v53, v1
	v_readlane_b32 s36, v52, 63
	s_waitcnt lgkmcnt(0)
	v_mul_f32_e32 v52, v105, v107
	v_fmac_f32_e32 v52, v104, v106
	v_fmac_f32_e32 v52, v64, v108
	v_fmac_f32_e32 v52, v65, v109
	v_fmac_f32_e32 v52, v62, v110
	v_fmac_f32_e32 v52, v63, v111
	v_fmac_f32_e32 v52, v60, v112
	v_fmac_f32_e32 v52, v61, v113
	v_fmac_f32_e32 v52, v58, v114
	v_fmac_f32_e32 v52, v59, v115
	v_fmac_f32_e32 v52, v56, v116
	v_fmac_f32_e32 v52, v57, v117
	v_fmac_f32_e32 v52, v54, v120
	v_fmac_f32_e32 v52, v55, v121
	v_fmac_f32_e32 v52, v50, v122
	v_fmac_f32_e32 v52, v51, v123
	ds_read_b128 v[106:109], v118 offset:12288
	ds_read_b128 v[110:113], v118 offset:12304
	ds_read_b128 v[114:117], v118 offset:14336
	ds_read_b128 v[120:123], v118 offset:14352
	v_add_f32_dpp v52, v52, v52 row_shr:1 row_mask:0xf bank_mask:0xf bound_ctrl:1
	s_nop 1
	v_add_f32_dpp v52, v52, v52 row_shr:2 row_mask:0xf bank_mask:0xf bound_ctrl:1
	s_nop 1
	v_add_f32_dpp v52, v52, v52 row_shr:4 row_mask:0xf bank_mask:0xf bound_ctrl:1
	s_nop 1
	v_add_f32_dpp v52, v52, v52 row_shr:8 row_mask:0xf bank_mask:0xf bound_ctrl:1
	s_nop 1
	v_mov_b32_dpp v53, v52 row_bcast:15 row_mask:0xa bank_mask:0xf
	v_add_f32_e32 v52, v52, v53
	v_mov_b32_e32 v53, v1
	s_nop 1
	v_mov_b32_dpp v53, v52 row_bcast:31 row_mask:0xc bank_mask:0xf
	v_add_f32_e32 v52, v52, v53
	v_mov_b32_e32 v53, v1
	v_readlane_b32 s37, v52, 63
	s_waitcnt lgkmcnt(0)
	v_mul_f32_e32 v52, v105, v107
	v_fmac_f32_e32 v52, v104, v106
	v_fmac_f32_e32 v52, v64, v108
	v_fmac_f32_e32 v52, v65, v109
	v_fmac_f32_e32 v52, v62, v110
	v_fmac_f32_e32 v52, v63, v111
	v_fmac_f32_e32 v52, v60, v112
	v_fmac_f32_e32 v52, v61, v113
	v_fmac_f32_e32 v52, v58, v114
	v_fmac_f32_e32 v52, v59, v115
	v_fmac_f32_e32 v52, v56, v116
	v_fmac_f32_e32 v52, v57, v117
	v_fmac_f32_e32 v52, v54, v120
	v_fmac_f32_e32 v52, v55, v121
	v_fmac_f32_e32 v52, v50, v122
	v_fmac_f32_e32 v52, v51, v123
	ds_read_b128 v[106:109], v118 offset:16384
	ds_read_b128 v[110:113], v118 offset:16400
	ds_read_b128 v[114:117], v118 offset:18432
	ds_read_b128 v[120:123], v118 offset:18448
	v_add_f32_dpp v52, v52, v52 row_shr:1 row_mask:0xf bank_mask:0xf bound_ctrl:1
	s_nop 1
	v_add_f32_dpp v52, v52, v52 row_shr:2 row_mask:0xf bank_mask:0xf bound_ctrl:1
	s_nop 1
	v_add_f32_dpp v52, v52, v52 row_shr:4 row_mask:0xf bank_mask:0xf bound_ctrl:1
	s_nop 1
	v_add_f32_dpp v52, v52, v52 row_shr:8 row_mask:0xf bank_mask:0xf bound_ctrl:1
	s_nop 1
	v_mov_b32_dpp v53, v52 row_bcast:15 row_mask:0xa bank_mask:0xf
	v_add_f32_e32 v52, v52, v53
	v_mov_b32_e32 v53, v1
	s_nop 1
	v_mov_b32_dpp v53, v52 row_bcast:31 row_mask:0xc bank_mask:0xf
	v_add_f32_e32 v52, v52, v53
	v_mov_b32_e32 v53, v1
	v_readlane_b32 s41, v52, 63
	s_waitcnt lgkmcnt(0)
	v_mul_f32_e32 v52, v105, v107
	v_fmac_f32_e32 v52, v104, v106
	v_fmac_f32_e32 v52, v64, v108
	v_fmac_f32_e32 v52, v65, v109
	v_fmac_f32_e32 v52, v62, v110
	v_fmac_f32_e32 v52, v63, v111
	v_fmac_f32_e32 v52, v60, v112
	v_fmac_f32_e32 v52, v61, v113
	v_fmac_f32_e32 v52, v58, v114
	v_fmac_f32_e32 v52, v59, v115
	v_fmac_f32_e32 v52, v56, v116
	v_fmac_f32_e32 v52, v57, v117
	v_fmac_f32_e32 v52, v54, v120
	v_fmac_f32_e32 v52, v55, v121
	v_fmac_f32_e32 v52, v50, v122
	v_fmac_f32_e32 v52, v51, v123
	ds_read_b128 v[106:109], v118 offset:20480
	ds_read_b128 v[110:113], v118 offset:20496
	ds_read_b128 v[114:117], v118 offset:22528
	ds_read_b128 v[120:123], v118 offset:22544
	v_add_f32_dpp v52, v52, v52 row_shr:1 row_mask:0xf bank_mask:0xf bound_ctrl:1
	s_nop 1
	v_add_f32_dpp v52, v52, v52 row_shr:2 row_mask:0xf bank_mask:0xf bound_ctrl:1
	s_nop 1
	v_add_f32_dpp v52, v52, v52 row_shr:4 row_mask:0xf bank_mask:0xf bound_ctrl:1
	s_nop 1
	v_add_f32_dpp v52, v52, v52 row_shr:8 row_mask:0xf bank_mask:0xf bound_ctrl:1
	s_nop 1
	v_mov_b32_dpp v53, v52 row_bcast:15 row_mask:0xa bank_mask:0xf
	v_add_f32_e32 v52, v52, v53
	v_mov_b32_e32 v53, v1
	s_nop 1
	v_mov_b32_dpp v53, v52 row_bcast:31 row_mask:0xc bank_mask:0xf
	v_add_f32_e32 v52, v52, v53
	v_mov_b32_e32 v53, v1
	v_readlane_b32 s43, v52, 63
	s_waitcnt lgkmcnt(0)
; __device__ __forceinline__ void phase_norm(const Params& p, unsigned char* lds, const float* __restrict__ xin, const float* g, const float* mod  , int shift_off, int scale_off, bf16_t* __restrict__ hout, const float* wsc  , float* scal) {
;     ...
;                 for (int j = 0; j < 12; ++j) {
;                     const float* wj = wl + j * DM + lane * 8;
;                     const f32x4 a0 = *(const f32x4*)wj, a1 = *(const f32x4*)(wj + 4), a2 = *(const f32x4*)(wj + 512), a3 = *(const f32x4*)(wj + 516);
;                     float s = h[0] * a0[0] + h[1] * a0[1] + h[2] * a0[2] + h[3] * a0[3] + h[4] * a1[0] + h[5] * a1[1] + h[6] * a1[2] + h[7] * a1[3]
;                             + h[8] * a2[0] + h[9] * a2[1] + h[10] * a2[2] + h[11] * a2[3] + h[12] * a3[0] + h[13] * a3[1] + h[14] * a3[2] + h[15] * a3[3];
;                     s = wave_sum(s);
;                     mine = (lane == j) ? s : mine;
;                 }
	v_mul_f32_e32 v52, v105, v107
	v_fmac_f32_e32 v52, v104, v106
	v_fmac_f32_e32 v52, v64, v108
	v_fmac_f32_e32 v52, v65, v109
	v_fmac_f32_e32 v52, v62, v110
	v_fmac_f32_e32 v52, v63, v111
	v_fmac_f32_e32 v52, v60, v112
	v_fmac_f32_e32 v52, v61, v113
	v_fmac_f32_e32 v52, v58, v114
	v_fmac_f32_e32 v52, v59, v115
	v_fmac_f32_e32 v52, v56, v116
	v_fmac_f32_e32 v52, v57, v117
	v_fmac_f32_e32 v52, v54, v120
	v_fmac_f32_e32 v52, v55, v121
	v_fmac_f32_e32 v52, v50, v122
	v_fmac_f32_e32 v52, v51, v123
	ds_read_b128 v[106:109], v118 offset:24576
	ds_read_b128 v[110:113], v118 offset:24592
	ds_read_b128 v[114:117], v118 offset:26624
	ds_read_b128 v[120:123], v118 offset:26640
	v_add_f32_dpp v52, v52, v52 row_shr:1 row_mask:0xf bank_mask:0xf bound_ctrl:1
	s_nop 1
	v_add_f32_dpp v52, v52, v52 row_shr:2 row_mask:0xf bank_mask:0xf bound_ctrl:1
	s_nop 1
	v_add_f32_dpp v52, v52, v52 row_shr:4 row_mask:0xf bank_mask:0xf bound_ctrl:1
	s_nop 1
	v_add_f32_dpp v52, v52, v52 row_shr:8 row_mask:0xf bank_mask:0xf bound_ctrl:1
	s_nop 1
	v_mov_b32_dpp v53, v52 row_bcast:15 row_mask:0xa bank_mask:0xf
	v_add_f32_e32 v52, v52, v53
	v_mov_b32_e32 v53, v1
	s_nop 1
	v_mov_b32_dpp v53, v52 row_bcast:31 row_mask:0xc bank_mask:0xf
	v_add_f32_e32 v52, v52, v53
	v_mov_b32_e32 v53, v1
	v_readlane_b32 s45, v52, 63
	s_waitcnt lgkmcnt(0)
	v_mul_f32_e32 v52, v105, v107
	v_fmac_f32_e32 v52, v104, v106
	v_fmac_f32_e32 v52, v64, v108
	v_fmac_f32_e32 v52, v65, v109
	v_fmac_f32_e32 v52, v62, v110
	v_fmac_f32_e32 v52, v63, v111
	v_fmac_f32_e32 v52, v60, v112
	v_fmac_f32_e32 v52, v61, v113
	v_fmac_f32_e32 v52, v58, v114
	v_fmac_f32_e32 v52, v59, v115
	v_fmac_f32_e32 v52, v56, v116
	v_fmac_f32_e32 v52, v57, v117
	v_fmac_f32_e32 v52, v54, v120
	v_fmac_f32_e32 v52, v55, v121
	v_fmac_f32_e32 v52, v50, v122
	v_fmac_f32_e32 v52, v51, v123
	ds_read_b128 v[106:109], v118 offset:28672
	ds_read_b128 v[110:113], v118 offset:28688
	ds_read_b128 v[114:117], v118 offset:30720
	ds_read_b128 v[120:123], v118 offset:30736
	v_add_f32_dpp v52, v52, v52 row_shr:1 row_mask:0xf bank_mask:0xf bound_ctrl:1
	s_nop 1
	v_add_f32_dpp v52, v52, v52 row_shr:2 row_mask:0xf bank_mask:0xf bound_ctrl:1
	s_nop 1
	v_add_f32_dpp v52, v52, v52 row_shr:4 row_mask:0xf bank_mask:0xf bound_ctrl:1
	s_nop 1
	v_add_f32_dpp v52, v52, v52 row_shr:8 row_mask:0xf bank_mask:0xf bound_ctrl:1
	s_nop 1
	v_mov_b32_dpp v53, v52 row_bcast:15 row_mask:0xa bank_mask:0xf
	v_add_f32_e32 v52, v52, v53
	v_mov_b32_e32 v53, v1
	s_nop 1
	v_mov_b32_dpp v53, v52 row_bcast:31 row_mask:0xc bank_mask:0xf
	v_add_f32_e32 v52, v52, v53
	v_mov_b32_e32 v53, v1
	v_readlane_b32 s47, v52, 63
	s_waitcnt lgkmcnt(0)
	v_mul_f32_e32 v52, v105, v107
	v_fmac_f32_e32 v52, v104, v106
	v_fmac_f32_e32 v52, v64, v108
	v_fmac_f32_e32 v52, v65, v109
	v_fmac_f32_e32 v52, v62, v110
	v_fmac_f32_e32 v52, v63, v111
	v_fmac_f32_e32 v52, v60, v112
	v_fmac_f32_e32 v52, v61, v113
	v_fmac_f32_e32 v52, v58, v114
	v_fmac_f32_e32 v52, v59, v115
	v_fmac_f32_e32 v52, v56, v116
	v_fmac_f32_e32 v52, v57, v117
	v_fmac_f32_e32 v52, v54, v120
	v_fmac_f32_e32 v52, v55, v121
	v_fmac_f32_e32 v52, v50, v122
	v_fmac_f32_e32 v52, v51, v123
	ds_read_b128 v[106:109], v118 offset:32768
	ds_read_b128 v[110:113], v118 offset:32784
	ds_read_b128 v[114:117], v118 offset:34816
	ds_read_b128 v[120:123], v118 offset:34832
	v_add_f32_dpp v52, v52, v52 row_shr:1 row_mask:0xf bank_mask:0xf bound_ctrl:1
	s_nop 1
	v_add_f32_dpp v52, v52, v52 row_shr:2 row_mask:0xf bank_mask:0xf bound_ctrl:1
	s_nop 1
	v_add_f32_dpp v52, v52, v52 row_shr:4 row_mask:0xf bank_mask:0xf bound_ctrl:1
	s_nop 1
	v_add_f32_dpp v52, v52, v52 row_shr:8 row_mask:0xf bank_mask:0xf bound_ctrl:1
	s_nop 1
	v_mov_b32_dpp v53, v52 row_bcast:15 row_mask:0xa bank_mask:0xf
	v_add_f32_e32 v52, v52, v53
	v_mov_b32_e32 v53, v1
	s_nop 1
	v_mov_b32_dpp v53, v52 row_bcast:31 row_mask:0xc bank_mask:0xf
	v_add_f32_e32 v52, v52, v53
	v_mov_b32_e32 v53, v1
	v_readlane_b32 s48, v52, 63
	s_waitcnt lgkmcnt(0)
	v_mul_f32_e32 v52, v105, v107
	v_fmac_f32_e32 v52, v104, v106
	v_fmac_f32_e32 v52, v64, v108
	v_fmac_f32_e32 v52, v65, v109
	v_fmac_f32_e32 v52, v62, v110
	v_fmac_f32_e32 v52, v63, v111
	v_fmac_f32_e32 v52, v60, v112
	v_fmac_f32_e32 v52, v61, v113
	v_fmac_f32_e32 v52, v58, v114
	v_fmac_f32_e32 v52, v59, v115
	v_fmac_f32_e32 v52, v56, v116
	v_fmac_f32_e32 v52, v57, v117
	v_fmac_f32_e32 v52, v54, v120
	v_fmac_f32_e32 v52, v55, v121
	v_fmac_f32_e32 v52, v50, v122
	v_fmac_f32_e32 v52, v51, v123
	ds_read_b128 v[106:109], v118 offset:36864
	ds_read_b128 v[110:113], v118 offset:36880
	ds_read_b128 v[114:117], v118 offset:38912
	ds_read_b128 v[120:123], v118 offset:38928
	v_add_f32_dpp v52, v52, v52 row_shr:1 row_mask:0xf bank_mask:0xf bound_ctrl:1
	s_nop 1
	v_add_f32_dpp v52, v52, v52 row_shr:2 row_mask:0xf bank_mask:0xf bound_ctrl:1
	s_nop 1
	v_add_f32_dpp v52, v52, v52 row_shr:4 row_mask:0xf bank_mask:0xf bound_ctrl:1
	s_nop 1
	v_add_f32_dpp v52, v52, v52 row_shr:8 row_mask:0xf bank_mask:0xf bound_ctrl:1
	s_nop 1
	v_mov_b32_dpp v53, v52 row_bcast:15 row_mask:0xa bank_mask:0xf
	v_add_f32_e32 v52, v52, v53
	v_mov_b32_e32 v53, v1
	s_nop 1
	v_mov_b32_dpp v53, v52 row_bcast:31 row_mask:0xc bank_mask:0xf
	v_add_f32_e32 v52, v52, v53
	v_mov_b32_e32 v53, v1
	v_readlane_b32 s51, v52, 63
	s_waitcnt lgkmcnt(0)
; __device__ __forceinline__ void phase_norm(const Params& p, unsigned char* lds, const float* __restrict__ xin, const float* g, const float* mod  , int shift_off, int scale_off, bf16_t* __restrict__ hout, const float* wsc  , float* scal) {
;     ...
;                 for (int j = 0; j < 12; ++j) {
;                     const float* wj = wl + j * DM + lane * 8;
;                     const f32x4 a0 = *(const f32x4*)wj, a1 = *(const f32x4*)(wj + 4), a2 = *(const f32x4*)(wj + 512), a3 = *(const f32x4*)(wj + 516);
;                     float s = h[0] * a0[0] + h[1] * a0[1] + h[2] * a0[2] + h[3] * a0[3] + h[4] * a1[0] + h[5] * a1[1] + h[6] * a1[2] + h[7] * a1[3]
;                             + h[8] * a2[0] + h[9] * a2[1] + h[10] * a2[2] + h[11] * a2[3] + h[12] * a3[0] + h[13] * a3[1] + h[14] * a3[2] + h[15] * a3[3];
;                     s = wave_sum(s);
;                     mine = (lane == j) ? s : mine;
;                 }
;                 if (lane < 12) scal[(size_t)row * 16 + lane] = mine;
	v_mul_f32_e32 v52, v105, v107
	v_fmac_f32_e32 v52, v104, v106
	v_fmac_f32_e32 v52, v64, v108
	v_fmac_f32_e32 v52, v65, v109
	v_fmac_f32_e32 v52, v62, v110
	v_fmac_f32_e32 v52, v63, v111
	v_fmac_f32_e32 v52, v60, v112
	v_fmac_f32_e32 v52, v61, v113
	v_fmac_f32_e32 v52, v58, v114
	v_fmac_f32_e32 v52, v59, v115
	v_fmac_f32_e32 v52, v56, v116
	v_fmac_f32_e32 v52, v57, v117
	v_fmac_f32_e32 v52, v54, v120
	v_fmac_f32_e32 v52, v55, v121
	v_fmac_f32_e32 v52, v50, v122
	v_fmac_f32_e32 v52, v51, v123
	ds_read_b128 v[106:109], v118 offset:40960
	ds_read_b128 v[110:113], v118 offset:40976
	ds_read_b128 v[114:117], v118 offset:43008
	ds_read_b128 v[120:123], v118 offset:43024
	v_add_f32_dpp v52, v52, v52 row_shr:1 row_mask:0xf bank_mask:0xf bound_ctrl:1
	s_nop 1
	v_add_f32_dpp v52, v52, v52 row_shr:2 row_mask:0xf bank_mask:0xf bound_ctrl:1
	s_nop 1
	v_add_f32_dpp v52, v52, v52 row_shr:4 row_mask:0xf bank_mask:0xf bound_ctrl:1
	s_nop 1
	v_add_f32_dpp v52, v52, v52 row_shr:8 row_mask:0xf bank_mask:0xf bound_ctrl:1
	s_nop 1
	v_mov_b32_dpp v53, v52 row_bcast:15 row_mask:0xa bank_mask:0xf
	v_add_f32_e32 v52, v52, v53
	v_mov_b32_e32 v53, v1
	s_nop 1
	v_mov_b32_dpp v53, v52 row_bcast:31 row_mask:0xc bank_mask:0xf
	v_add_f32_e32 v52, v52, v53
	v_mov_b32_e32 v53, v1
	v_readlane_b32 s52, v52, 63
	s_waitcnt lgkmcnt(0)
	v_mul_f32_e32 v52, v105, v107
	v_fmac_f32_e32 v52, v104, v106
	v_fmac_f32_e32 v52, v64, v108
	v_fmac_f32_e32 v52, v65, v109
	v_fmac_f32_e32 v52, v62, v110
	v_fmac_f32_e32 v52, v63, v111
	v_fmac_f32_e32 v52, v60, v112
	v_fmac_f32_e32 v52, v61, v113
	v_fmac_f32_e32 v52, v58, v114
	v_fmac_f32_e32 v52, v59, v115
	v_fmac_f32_e32 v52, v56, v116
	v_fmac_f32_e32 v52, v57, v117
	v_fmac_f32_e32 v52, v54, v120
	v_fmac_f32_e32 v52, v55, v121
	v_fmac_f32_e32 v52, v50, v122
	v_fmac_f32_e32 v52, v51, v123
	ds_read_b128 v[106:109], v118 offset:45056
	ds_read_b128 v[110:113], v118 offset:45072
	ds_read_b128 v[114:117], v118 offset:47104
	ds_read_b128 v[120:123], v118 offset:47120
	v_add_f32_dpp v52, v52, v52 row_shr:1 row_mask:0xf bank_mask:0xf bound_ctrl:1
	s_nop 1
	v_add_f32_dpp v52, v52, v52 row_shr:2 row_mask:0xf bank_mask:0xf bound_ctrl:1
	s_nop 1
	v_add_f32_dpp v52, v52, v52 row_shr:4 row_mask:0xf bank_mask:0xf bound_ctrl:1
	s_nop 1
	v_add_f32_dpp v52, v52, v52 row_shr:8 row_mask:0xf bank_mask:0xf bound_ctrl:1
	s_nop 1
	v_mov_b32_dpp v53, v52 row_bcast:15 row_mask:0xa bank_mask:0xf
	v_add_f32_e32 v52, v52, v53
	v_mov_b32_e32 v53, v1
	s_nop 1
	v_mov_b32_dpp v53, v52 row_bcast:31 row_mask:0xc bank_mask:0xf
	v_add_f32_e32 v52, v52, v53
	s_nop 0
	v_readlane_b32 s54, v52, 63
	s_waitcnt lgkmcnt(0)
	v_mul_f32_e32 v52, v105, v107
	v_fmac_f32_e32 v52, v104, v106
	v_fmac_f32_e32 v52, v64, v108
	v_fmac_f32_e32 v52, v65, v109
	v_fmac_f32_e32 v52, v62, v110
	v_fmac_f32_e32 v52, v63, v111
	v_fmac_f32_e32 v52, v60, v112
	v_fmac_f32_e32 v52, v61, v113
	v_fmac_f32_e32 v52, v58, v114
	v_fmac_f32_e32 v52, v59, v115
	v_fmac_f32_e32 v52, v56, v116
	v_fmac_f32_e32 v52, v57, v117
	v_fmac_f32_e32 v52, v54, v120
	v_fmac_f32_e32 v52, v55, v121
	v_fmac_f32_e32 v52, v50, v122
	v_fmac_f32_e32 v52, v51, v123
	v_mov_b32_e32 v51, v1
	s_nop 0
	v_add_f32_dpp v50, v52, v52 row_shr:1 row_mask:0xf bank_mask:0xf bound_ctrl:1
	s_nop 1
	v_add_f32_dpp v50, v50, v50 row_shr:2 row_mask:0xf bank_mask:0xf bound_ctrl:1
	s_nop 1
	v_add_f32_dpp v50, v50, v50 row_shr:4 row_mask:0xf bank_mask:0xf bound_ctrl:1
	s_nop 1
	v_add_f32_dpp v50, v50, v50 row_shr:8 row_mask:0xf bank_mask:0xf bound_ctrl:1
	s_nop 1
	v_mov_b32_dpp v51, v50 row_bcast:15 row_mask:0xa bank_mask:0xf
	v_add_f32_e32 v50, v50, v51
	v_mov_b32_e32 v51, v1
	s_nop 1
	v_mov_b32_dpp v51, v50 row_bcast:31 row_mask:0xc bank_mask:0xf
	v_add_f32_e32 v50, v50, v51
	s_nop 0
	v_readlane_b32 s55, v50, 63
	s_and_saveexec_b64 s[0:1], s[6:7]
	s_cbranch_execz .LBB0_762
	v_mov_b32_e32 v50, s5
	v_cndmask_b32_e64 v50, 0, v50, s[30:31]
	v_mov_b32_e32 v51, s36
	v_cndmask_b32_e64 v50, v50, v51, s[28:29]
	v_mov_b32_e32 v51, s37
	v_cndmask_b32_e64 v50, v50, v51, s[26:27]
	v_mov_b32_e32 v51, s41
	v_cndmask_b32_e64 v50, v50, v51, s[24:25]
	v_mov_b32_e32 v51, s43
	v_cndmask_b32_e64 v50, v50, v51, s[22:23]
	v_mov_b32_e32 v51, s45
	v_cndmask_b32_e64 v50, v50, v51, s[20:21]
	v_mov_b32_e32 v51, s47
	v_cndmask_b32_e64 v50, v50, v51, s[18:19]
	v_mov_b32_e32 v51, s48
	v_cndmask_b32_e64 v50, v50, v51, s[16:17]
	v_mov_b32_e32 v51, s51
	v_cndmask_b32_e64 v50, v50, v51, s[14:15]
	v_mov_b32_e32 v51, s52
	v_cndmask_b32_e64 v50, v50, v51, s[12:13]
	v_mov_b32_e32 v51, s54
	v_cndmask_b32_e64 v50, v50, v51, s[10:11]
	v_mov_b32_e32 v51, s55
	v_cndmask_b32_e64 v52, v50, v51, s[8:9]
	v_add_co_u32_e32 v50, vcc, 0x100000, v98
	s_nop 1
	v_addc_co_u32_e32 v51, vcc, 0, v99, vcc
	global_store_dword v[50:51], v52, off offset:64
; __device__ __forceinline__ unsigned pack2(float lo, float hi) { return pg8::cvt_pk_bf16(lo, hi); }
; __device__ __forceinline__ void phase_norm(const Params& p, unsigned char* lds, const float* __restrict__ xin, const float* g, const float* mod  , int shift_off, int scale_off, bf16_t* __restrict__ hout, const float* wsc  , float* scal) {
;     ...
;             const int row = rb + r4 + q;
;             const f32x4 x0 = xq[q][0], x1 = xq[q][1], x2 = xq[q][2], x3 = xq[q][3];
;             float xv[16] = {x0[0], x0[1], x0[2], x0[3], x1[0], x1[1], x1[2], x1[3], x2[0], x2[1], x2[2], x2[3], x3[0], x3[1], x3[2], x3[3]};
;             float ss = 0.f;
; #pragma unroll
;             for (int i = 0; i < 16; ++i) ss += xv[i] * xv[i];
;             ss = wave_sum(ss);
;             const float rstd = rsqrtf(ss * (1.0f / DM) + EPS);
;             float h[16];
; #pragma unroll
;             for (int i = 0; i < 16; ++i) h[i] = xv[i] * rstd * cs[i] + sh[i];
;             u32x4 w0, w1;
;             w0.x = pack2(h[0], h[1]); w0.y = pack2(h[2], h[3]); w0.z = pack2(h[4], h[5]); w0.w = pack2(h[6], h[7]);
;             w1.x = pack2(h[8], h[9]); w1.y = pack2(h[10], h[11]); w1.z = pack2(h[12], h[13]); w1.w = pack2(h[14], h[15]);
;             bf16_t* hp = hout + (size_t)row * DM + lane * 8;
;             *(u32x4*)hp = w0; *(u32x4*)(hp + 512) = w1;
;             if (wsc) {
;                 float mine = 0.f;
; #pragma unroll
;                 for (int j = 0; j < 12; ++j) {
;                     const float* wj = wl + j * DM + lane * 8;
;                     const f32x4 a0 = *(const f32x4*)wj, a1 = *(const f32x4*)(wj + 4), a2 = *(const f32x4*)(wj + 512), a3 = *(const f32x4*)(wj + 516);
;                     float s = h[0] * a0[0] + h[1] * a0[1] + h[2] * a0[2] + h[3] * a0[3] + h[4] * a1[0] + h[5] * a1[1] + h[6] * a1[2] + h[7] * a1[3]
;                             + h[8] * a2[0] + h[9] * a2[1] + h[10] * a2[2] + h[11] * a2[3] + h[12] * a3[0] + h[13] * a3[1] + h[14] * a3[2] + h[15] * a3[3];
;                     s = wave_sum(s);
;                     mine = (lane == j) ? s : mine;
;                 }
.LBB0_762:
	s_or_b64 exec, exec, s[0:1]
	v_mul_f32_e32 v54, v43, v43
	v_fmac_f32_e32 v54, v42, v42
	v_fmac_f32_e32 v54, v44, v44
	v_fmac_f32_e32 v54, v45, v45
	v_fmac_f32_e32 v54, v34, v34
	v_fmac_f32_e32 v54, v35, v35
	v_fmac_f32_e32 v54, v36, v36
	v_fmac_f32_e32 v54, v37, v37
	v_fmac_f32_e32 v54, v46, v46
	v_fmac_f32_e32 v54, v47, v47
	v_fmac_f32_e32 v54, v48, v48
	v_fmac_f32_e32 v54, v49, v49
	v_pk_mul_f32 v[52:53], v[38:39], v[38:39]
	v_pk_mul_f32 v[50:51], v[40:41], v[40:41]
	v_add_f32_e32 v52, v52, v54
	v_add_f32_e32 v52, v53, v52
	v_add_f32_e32 v50, v50, v52
	v_add_f32_e32 v50, v51, v50
	v_mov_b32_e32 v51, v1
	s_nop 0
	v_add_f32_dpp v50, v50, v50 row_shr:1 row_mask:0xf bank_mask:0xf bound_ctrl:1
	s_nop 1
	v_add_f32_dpp v50, v50, v50 row_shr:2 row_mask:0xf bank_mask:0xf bound_ctrl:1
	s_nop 1
	v_add_f32_dpp v50, v50, v50 row_shr:4 row_mask:0xf bank_mask:0xf bound_ctrl:1
	s_nop 1
	v_add_f32_dpp v50, v50, v50 row_shr:8 row_mask:0xf bank_mask:0xf bound_ctrl:1
	s_nop 1
	v_mov_b32_dpp v51, v50 row_bcast:15 row_mask:0xa bank_mask:0xf
	v_add_f32_e32 v50, v50, v51
	v_mov_b32_e32 v51, v1
	s_nop 1
	v_mov_b32_dpp v51, v50 row_bcast:31 row_mask:0xc bank_mask:0xf
	v_add_f32_e32 v50, v50, v51
	s_nop 0
	v_readlane_b32 s0, v50, 63
	s_nop 1
	v_fma_f32 v50, s0, v217, v213
	v_mul_f32_e32 v51, 0x4b800000, v50
	v_cmp_gt_f32_e32 vcc, s44, v50
	s_mov_b32 s0, 0x3601000
	s_nop 0
	v_cndmask_b32_e32 v50, v50, v51, vcc
	v_rsq_f32_e32 v50, v50
	s_nop 0
	v_mul_f32_e32 v51, 0x45800000, v50
	v_cndmask_b32_e32 v58, v50, v51, vcc
	v_pk_mul_f32 v[34:35], v[34:35], v[58:59] op_sel_hi:[1,0]
	v_pk_mul_f32 v[42:43], v[42:43], v[58:59] op_sel_hi:[1,0]
	v_pk_fma_f32 v[50:51], v[92:93], v[34:35], v[10:11]
	v_pk_mul_f32 v[34:35], v[36:37], v[58:59] op_sel_hi:[1,0]
	v_pk_fma_f32 v[54:55], v[96:97], v[42:43], v[14:15]
	v_pk_mul_f32 v[42:43], v[44:45], v[58:59] op_sel_hi:[1,0]
	v_pk_fma_f32 v[52:53], v[90:91], v[34:35], v[12:13]
	v_pk_mul_f32 v[34:35], v[46:47], v[58:59] op_sel_hi:[1,0]
	v_pk_fma_f32 v[56:57], v[94:95], v[42:43], v[16:17]
	v_pk_fma_f32 v[42:43], v[88:89], v[34:35], v[6:7]
	v_pk_mul_f32 v[34:35], v[48:49], v[58:59] op_sel_hi:[1,0]
	v_cvt_pk_bf16_f32 v46, v54, v55
	v_pk_fma_f32 v[44:45], v[86:87], v[34:35], v[8:9]
	v_pk_mul_f32 v[34:35], v[38:39], v[58:59] op_sel_hi:[1,0]
	v_cvt_pk_bf16_f32 v47, v56, v57
	v_pk_fma_f32 v[38:39], v[84:85], v[34:35], v[2:3]
	v_pk_mul_f32 v[34:35], v[40:41], v[58:59] op_sel_hi:[1,0]
	v_cvt_pk_bf16_f32 v48, v50, v51
	v_pk_fma_f32 v[36:37], v[82:83], v[34:35], v[4:5]
	v_add_co_u32_e32 v34, vcc, s0, v100
	v_cvt_pk_bf16_f32 v49, v52, v53
	s_nop 0
	v_addc_co_u32_e32 v35, vcc, 0, v101, vcc
	global_store_dwordx4 v[34:35], v[46:49], off
	ds_read_b128 v[46:49], v118
	v_cvt_pk_bf16_f32 v58, v42, v43
	v_cvt_pk_bf16_f32 v59, v44, v45
	v_cvt_pk_bf16_f32 v60, v38, v39
	v_cvt_pk_bf16_f32 v61, v36, v37
	global_store_dwordx4 v[34:35], v[58:61], off offset:1024
	s_waitcnt lgkmcnt(0)
	v_mul_f32_e32 v40, v47, v55
	ds_read_b128 v[58:61], v118 offset:16
	ds_read_b128 v[62:65], v118 offset:2048
	ds_read_b128 v[100:103], v118 offset:2064
	v_fmac_f32_e32 v40, v46, v54
	v_fmac_f32_e32 v40, v48, v56
	v_fmac_f32_e32 v40, v49, v57
	s_waitcnt lgkmcnt(0)
	v_fmac_f32_e32 v40, v58, v50
	v_fmac_f32_e32 v40, v59, v51
	v_fmac_f32_e32 v40, v60, v52
	v_fmac_f32_e32 v40, v61, v53
	v_fmac_f32_e32 v40, v62, v42
	v_fmac_f32_e32 v40, v63, v43
	v_fmac_f32_e32 v40, v64, v44
	v_fmac_f32_e32 v40, v65, v45
	v_fmac_f32_e32 v40, v100, v38
	v_fmac_f32_e32 v40, v101, v39
	v_fmac_f32_e32 v40, v102, v36
	v_fmac_f32_e32 v40, v103, v37
	v_mov_b32_e32 v41, v1
	ds_read_b128 v[46:49], v118 offset:4096
	v_add_f32_dpp v40, v40, v40 row_shr:1 row_mask:0xf bank_mask:0xf bound_ctrl:1
	ds_read_b128 v[58:61], v118 offset:4112
	ds_read_b128 v[62:65], v118 offset:6144
	ds_read_b128 v[100:103], v118 offset:6160
	v_add_f32_dpp v40, v40, v40 row_shr:2 row_mask:0xf bank_mask:0xf bound_ctrl:1
	s_nop 1
	v_add_f32_dpp v40, v40, v40 row_shr:4 row_mask:0xf bank_mask:0xf bound_ctrl:1
	s_nop 1
	v_add_f32_dpp v40, v40, v40 row_shr:8 row_mask:0xf bank_mask:0xf bound_ctrl:1
	s_nop 1
	v_mov_b32_dpp v41, v40 row_bcast:15 row_mask:0xa bank_mask:0xf
	v_add_f32_e32 v40, v40, v41
	v_mov_b32_e32 v41, v1
	s_nop 1
	v_mov_b32_dpp v41, v40 row_bcast:31 row_mask:0xc bank_mask:0xf
	v_add_f32_e32 v40, v40, v41
	v_mov_b32_e32 v41, v1
	v_readlane_b32 s5, v40, 63
	s_waitcnt lgkmcnt(0)
	v_mul_f32_e32 v40, v55, v47
	v_fmac_f32_e32 v40, v54, v46
	v_fmac_f32_e32 v40, v56, v48
	v_fmac_f32_e32 v40, v57, v49
	v_fmac_f32_e32 v40, v50, v58
	v_fmac_f32_e32 v40, v51, v59
	v_fmac_f32_e32 v40, v52, v60
	v_fmac_f32_e32 v40, v53, v61
	v_fmac_f32_e32 v40, v42, v62
	v_fmac_f32_e32 v40, v43, v63
	v_fmac_f32_e32 v40, v44, v64
	v_fmac_f32_e32 v40, v45, v65
	v_fmac_f32_e32 v40, v38, v100
	v_fmac_f32_e32 v40, v39, v101
	v_fmac_f32_e32 v40, v36, v102
	v_fmac_f32_e32 v40, v37, v103
	ds_read_b128 v[46:49], v118 offset:8192
	ds_read_b128 v[58:61], v118 offset:8208
	ds_read_b128 v[62:65], v118 offset:10240
	ds_read_b128 v[100:103], v118 offset:10256
	v_add_f32_dpp v40, v40, v40 row_shr:1 row_mask:0xf bank_mask:0xf bound_ctrl:1
	s_nop 1
	v_add_f32_dpp v40, v40, v40 row_shr:2 row_mask:0xf bank_mask:0xf bound_ctrl:1
	s_nop 1
	v_add_f32_dpp v40, v40, v40 row_shr:4 row_mask:0xf bank_mask:0xf bound_ctrl:1
	s_nop 1
	v_add_f32_dpp v40, v40, v40 row_shr:8 row_mask:0xf bank_mask:0xf bound_ctrl:1
	s_nop 1
	v_mov_b32_dpp v41, v40 row_bcast:15 row_mask:0xa bank_mask:0xf
	v_add_f32_e32 v40, v40, v41
	v_mov_b32_e32 v41, v1
	s_nop 1
	v_mov_b32_dpp v41, v40 row_bcast:31 row_mask:0xc bank_mask:0xf
	v_add_f32_e32 v40, v40, v41
	v_mov_b32_e32 v41, v1
	v_readlane_b32 s36, v40, 63
	s_waitcnt lgkmcnt(0)
; __device__ __forceinline__ void phase_norm(const Params& p, unsigned char* lds, const float* __restrict__ xin, const float* g, const float* mod  , int shift_off, int scale_off, bf16_t* __restrict__ hout, const float* wsc  , float* scal) {
;     ...
;                 for (int j = 0; j < 12; ++j) {
;                     const float* wj = wl + j * DM + lane * 8;
;                     const f32x4 a0 = *(const f32x4*)wj, a1 = *(const f32x4*)(wj + 4), a2 = *(const f32x4*)(wj + 512), a3 = *(const f32x4*)(wj + 516);
;                     float s = h[0] * a0[0] + h[1] * a0[1] + h[2] * a0[2] + h[3] * a0[3] + h[4] * a1[0] + h[5] * a1[1] + h[6] * a1[2] + h[7] * a1[3]
;                             + h[8] * a2[0] + h[9] * a2[1] + h[10] * a2[2] + h[11] * a2[3] + h[12] * a3[0] + h[13] * a3[1] + h[14] * a3[2] + h[15] * a3[3];
;                     s = wave_sum(s);
;                     mine = (lane == j) ? s : mine;
;                 }
	v_mul_f32_e32 v40, v55, v47
	v_fmac_f32_e32 v40, v54, v46
	v_fmac_f32_e32 v40, v56, v48
	v_fmac_f32_e32 v40, v57, v49
	v_fmac_f32_e32 v40, v50, v58
	v_fmac_f32_e32 v40, v51, v59
	v_fmac_f32_e32 v40, v52, v60
	v_fmac_f32_e32 v40, v53, v61
	v_fmac_f32_e32 v40, v42, v62
	v_fmac_f32_e32 v40, v43, v63
	v_fmac_f32_e32 v40, v44, v64
	v_fmac_f32_e32 v40, v45, v65
	v_fmac_f32_e32 v40, v38, v100
	v_fmac_f32_e32 v40, v39, v101
	v_fmac_f32_e32 v40, v36, v102
	v_fmac_f32_e32 v40, v37, v103
	ds_read_b128 v[46:49], v118 offset:12288
	ds_read_b128 v[58:61], v118 offset:12304
	ds_read_b128 v[62:65], v118 offset:14336
	ds_read_b128 v[100:103], v118 offset:14352
	v_add_f32_dpp v40, v40, v40 row_shr:1 row_mask:0xf bank_mask:0xf bound_ctrl:1
	s_nop 1
	v_add_f32_dpp v40, v40, v40 row_shr:2 row_mask:0xf bank_mask:0xf bound_ctrl:1
	s_nop 1
	v_add_f32_dpp v40, v40, v40 row_shr:4 row_mask:0xf bank_mask:0xf bound_ctrl:1
	s_nop 1
	v_add_f32_dpp v40, v40, v40 row_shr:8 row_mask:0xf bank_mask:0xf bound_ctrl:1
	s_nop 1
	v_mov_b32_dpp v41, v40 row_bcast:15 row_mask:0xa bank_mask:0xf
	v_add_f32_e32 v40, v40, v41
	v_mov_b32_e32 v41, v1
	s_nop 1
	v_mov_b32_dpp v41, v40 row_bcast:31 row_mask:0xc bank_mask:0xf
	v_add_f32_e32 v40, v40, v41
	v_mov_b32_e32 v41, v1
	v_readlane_b32 s37, v40, 63
	s_waitcnt lgkmcnt(0)
	v_mul_f32_e32 v40, v55, v47
	v_fmac_f32_e32 v40, v54, v46
	v_fmac_f32_e32 v40, v56, v48
	v_fmac_f32_e32 v40, v57, v49
	v_fmac_f32_e32 v40, v50, v58
	v_fmac_f32_e32 v40, v51, v59
	v_fmac_f32_e32 v40, v52, v60
	v_fmac_f32_e32 v40, v53, v61
	v_fmac_f32_e32 v40, v42, v62
	v_fmac_f32_e32 v40, v43, v63
	v_fmac_f32_e32 v40, v44, v64
	v_fmac_f32_e32 v40, v45, v65
	v_fmac_f32_e32 v40, v38, v100
	v_fmac_f32_e32 v40, v39, v101
	v_fmac_f32_e32 v40, v36, v102
	v_fmac_f32_e32 v40, v37, v103
	ds_read_b128 v[46:49], v118 offset:16384
	ds_read_b128 v[58:61], v118 offset:16400
	ds_read_b128 v[62:65], v118 offset:18432
	ds_read_b128 v[100:103], v118 offset:18448
	v_add_f32_dpp v40, v40, v40 row_shr:1 row_mask:0xf bank_mask:0xf bound_ctrl:1
	s_nop 1
	v_add_f32_dpp v40, v40, v40 row_shr:2 row_mask:0xf bank_mask:0xf bound_ctrl:1
	s_nop 1
	v_add_f32_dpp v40, v40, v40 row_shr:4 row_mask:0xf bank_mask:0xf bound_ctrl:1
	s_nop 1
	v_add_f32_dpp v40, v40, v40 row_shr:8 row_mask:0xf bank_mask:0xf bound_ctrl:1
	s_nop 1
	v_mov_b32_dpp v41, v40 row_bcast:15 row_mask:0xa bank_mask:0xf
	v_add_f32_e32 v40, v40, v41
	v_mov_b32_e32 v41, v1
	s_nop 1
	v_mov_b32_dpp v41, v40 row_bcast:31 row_mask:0xc bank_mask:0xf
	v_add_f32_e32 v40, v40, v41
	v_mov_b32_e32 v41, v1
	v_readlane_b32 s41, v40, 63
	s_waitcnt lgkmcnt(0)
	v_mul_f32_e32 v40, v55, v47
	v_fmac_f32_e32 v40, v54, v46
	v_fmac_f32_e32 v40, v56, v48
	v_fmac_f32_e32 v40, v57, v49
	v_fmac_f32_e32 v40, v50, v58
	v_fmac_f32_e32 v40, v51, v59
	v_fmac_f32_e32 v40, v52, v60
	v_fmac_f32_e32 v40, v53, v61
	v_fmac_f32_e32 v40, v42, v62
	v_fmac_f32_e32 v40, v43, v63
	v_fmac_f32_e32 v40, v44, v64
	v_fmac_f32_e32 v40, v45, v65
	v_fmac_f32_e32 v40, v38, v100
	v_fmac_f32_e32 v40, v39, v101
	v_fmac_f32_e32 v40, v36, v102
	v_fmac_f32_e32 v40, v37, v103
	ds_read_b128 v[46:49], v118 offset:20480
	ds_read_b128 v[58:61], v118 offset:20496
	ds_read_b128 v[62:65], v118 offset:22528
	ds_read_b128 v[100:103], v118 offset:22544
	v_add_f32_dpp v40, v40, v40 row_shr:1 row_mask:0xf bank_mask:0xf bound_ctrl:1
	s_nop 1
	v_add_f32_dpp v40, v40, v40 row_shr:2 row_mask:0xf bank_mask:0xf bound_ctrl:1
	s_nop 1
	v_add_f32_dpp v40, v40, v40 row_shr:4 row_mask:0xf bank_mask:0xf bound_ctrl:1
	s_nop 1
	v_add_f32_dpp v40, v40, v40 row_shr:8 row_mask:0xf bank_mask:0xf bound_ctrl:1
	s_nop 1
	v_mov_b32_dpp v41, v40 row_bcast:15 row_mask:0xa bank_mask:0xf
	v_add_f32_e32 v40, v40, v41
	v_mov_b32_e32 v41, v1
	s_nop 1
	v_mov_b32_dpp v41, v40 row_bcast:31 row_mask:0xc bank_mask:0xf
	v_add_f32_e32 v40, v40, v41
	v_mov_b32_e32 v41, v1
	v_readlane_b32 s43, v40, 63
	s_waitcnt lgkmcnt(0)
	v_mul_f32_e32 v40, v55, v47
	v_fmac_f32_e32 v40, v54, v46
	v_fmac_f32_e32 v40, v56, v48
	v_fmac_f32_e32 v40, v57, v49
	v_fmac_f32_e32 v40, v50, v58
	v_fmac_f32_e32 v40, v51, v59
	v_fmac_f32_e32 v40, v52, v60
	v_fmac_f32_e32 v40, v53, v61
	v_fmac_f32_e32 v40, v42, v62
	v_fmac_f32_e32 v40, v43, v63
	v_fmac_f32_e32 v40, v44, v64
	v_fmac_f32_e32 v40, v45, v65
	v_fmac_f32_e32 v40, v38, v100
	v_fmac_f32_e32 v40, v39, v101
	v_fmac_f32_e32 v40, v36, v102
	v_fmac_f32_e32 v40, v37, v103
	ds_read_b128 v[46:49], v118 offset:24576
	ds_read_b128 v[58:61], v118 offset:24592
	ds_read_b128 v[62:65], v118 offset:26624
	ds_read_b128 v[100:103], v118 offset:26640
	v_add_f32_dpp v40, v40, v40 row_shr:1 row_mask:0xf bank_mask:0xf bound_ctrl:1
	s_nop 1
	v_add_f32_dpp v40, v40, v40 row_shr:2 row_mask:0xf bank_mask:0xf bound_ctrl:1
	s_nop 1
	v_add_f32_dpp v40, v40, v40 row_shr:4 row_mask:0xf bank_mask:0xf bound_ctrl:1
	s_nop 1
	v_add_f32_dpp v40, v40, v40 row_shr:8 row_mask:0xf bank_mask:0xf bound_ctrl:1
	s_nop 1
	v_mov_b32_dpp v41, v40 row_bcast:15 row_mask:0xa bank_mask:0xf
	v_add_f32_e32 v40, v40, v41
	v_mov_b32_e32 v41, v1
	s_nop 1
	v_mov_b32_dpp v41, v40 row_bcast:31 row_mask:0xc bank_mask:0xf
	v_add_f32_e32 v40, v40, v41
	v_mov_b32_e32 v41, v1
	v_readlane_b32 s45, v40, 63
	s_waitcnt lgkmcnt(0)
; __device__ __forceinline__ void phase_norm(const Params& p, unsigned char* lds, const float* __restrict__ xin, const float* g, const float* mod  , int shift_off, int scale_off, bf16_t* __restrict__ hout, const float* wsc  , float* scal) {
;     ...
;                 for (int j = 0; j < 12; ++j) {
;                     const float* wj = wl + j * DM + lane * 8;
;                     const f32x4 a0 = *(const f32x4*)wj, a1 = *(const f32x4*)(wj + 4), a2 = *(const f32x4*)(wj + 512), a3 = *(const f32x4*)(wj + 516);
;                     float s = h[0] * a0[0] + h[1] * a0[1] + h[2] * a0[2] + h[3] * a0[3] + h[4] * a1[0] + h[5] * a1[1] + h[6] * a1[2] + h[7] * a1[3]
;                             + h[8] * a2[0] + h[9] * a2[1] + h[10] * a2[2] + h[11] * a2[3] + h[12] * a3[0] + h[13] * a3[1] + h[14] * a3[2] + h[15] * a3[3];
;                     s = wave_sum(s);
;                     mine = (lane == j) ? s : mine;
;                 }
	v_mul_f32_e32 v40, v55, v47
	v_fmac_f32_e32 v40, v54, v46
	v_fmac_f32_e32 v40, v56, v48
	v_fmac_f32_e32 v40, v57, v49
	v_fmac_f32_e32 v40, v50, v58
	v_fmac_f32_e32 v40, v51, v59
	v_fmac_f32_e32 v40, v52, v60
	v_fmac_f32_e32 v40, v53, v61
	v_fmac_f32_e32 v40, v42, v62
	v_fmac_f32_e32 v40, v43, v63
	v_fmac_f32_e32 v40, v44, v64
	v_fmac_f32_e32 v40, v45, v65
	v_fmac_f32_e32 v40, v38, v100
	v_fmac_f32_e32 v40, v39, v101
	v_fmac_f32_e32 v40, v36, v102
	v_fmac_f32_e32 v40, v37, v103
	ds_read_b128 v[46:49], v118 offset:28672
	ds_read_b128 v[58:61], v118 offset:28688
	ds_read_b128 v[62:65], v118 offset:30720
	ds_read_b128 v[100:103], v118 offset:30736
	v_add_f32_dpp v40, v40, v40 row_shr:1 row_mask:0xf bank_mask:0xf bound_ctrl:1
	s_nop 1
	v_add_f32_dpp v40, v40, v40 row_shr:2 row_mask:0xf bank_mask:0xf bound_ctrl:1
	s_nop 1
	v_add_f32_dpp v40, v40, v40 row_shr:4 row_mask:0xf bank_mask:0xf bound_ctrl:1
	s_nop 1
	v_add_f32_dpp v40, v40, v40 row_shr:8 row_mask:0xf bank_mask:0xf bound_ctrl:1
	s_nop 1
	v_mov_b32_dpp v41, v40 row_bcast:15 row_mask:0xa bank_mask:0xf
	v_add_f32_e32 v40, v40, v41
	v_mov_b32_e32 v41, v1
	s_nop 1
	v_mov_b32_dpp v41, v40 row_bcast:31 row_mask:0xc bank_mask:0xf
	v_add_f32_e32 v40, v40, v41
	v_mov_b32_e32 v41, v1
	v_readlane_b32 s47, v40, 63
	s_waitcnt lgkmcnt(0)
	v_mul_f32_e32 v40, v55, v47
	v_fmac_f32_e32 v40, v54, v46
	v_fmac_f32_e32 v40, v56, v48
	v_fmac_f32_e32 v40, v57, v49
	v_fmac_f32_e32 v40, v50, v58
	v_fmac_f32_e32 v40, v51, v59
	v_fmac_f32_e32 v40, v52, v60
	v_fmac_f32_e32 v40, v53, v61
	v_fmac_f32_e32 v40, v42, v62
	v_fmac_f32_e32 v40, v43, v63
	v_fmac_f32_e32 v40, v44, v64
	v_fmac_f32_e32 v40, v45, v65
	v_fmac_f32_e32 v40, v38, v100
	v_fmac_f32_e32 v40, v39, v101
	v_fmac_f32_e32 v40, v36, v102
	v_fmac_f32_e32 v40, v37, v103
	ds_read_b128 v[46:49], v118 offset:32768
	ds_read_b128 v[58:61], v118 offset:32784
	ds_read_b128 v[62:65], v118 offset:34816
	ds_read_b128 v[100:103], v118 offset:34832
	v_add_f32_dpp v40, v40, v40 row_shr:1 row_mask:0xf bank_mask:0xf bound_ctrl:1
	s_nop 1
	v_add_f32_dpp v40, v40, v40 row_shr:2 row_mask:0xf bank_mask:0xf bound_ctrl:1
	s_nop 1
	v_add_f32_dpp v40, v40, v40 row_shr:4 row_mask:0xf bank_mask:0xf bound_ctrl:1
	s_nop 1
	v_add_f32_dpp v40, v40, v40 row_shr:8 row_mask:0xf bank_mask:0xf bound_ctrl:1
	s_nop 1
	v_mov_b32_dpp v41, v40 row_bcast:15 row_mask:0xa bank_mask:0xf
	v_add_f32_e32 v40, v40, v41
	v_mov_b32_e32 v41, v1
	s_nop 1
	v_mov_b32_dpp v41, v40 row_bcast:31 row_mask:0xc bank_mask:0xf
	v_add_f32_e32 v40, v40, v41
	v_mov_b32_e32 v41, v1
	v_readlane_b32 s48, v40, 63
	s_waitcnt lgkmcnt(0)
	v_mul_f32_e32 v40, v55, v47
	v_fmac_f32_e32 v40, v54, v46
	v_fmac_f32_e32 v40, v56, v48
	v_fmac_f32_e32 v40, v57, v49
	v_fmac_f32_e32 v40, v50, v58
	v_fmac_f32_e32 v40, v51, v59
	v_fmac_f32_e32 v40, v52, v60
	v_fmac_f32_e32 v40, v53, v61
	v_fmac_f32_e32 v40, v42, v62
	v_fmac_f32_e32 v40, v43, v63
	v_fmac_f32_e32 v40, v44, v64
	v_fmac_f32_e32 v40, v45, v65
	v_fmac_f32_e32 v40, v38, v100
	v_fmac_f32_e32 v40, v39, v101
	v_fmac_f32_e32 v40, v36, v102
	v_fmac_f32_e32 v40, v37, v103
	ds_read_b128 v[46:49], v118 offset:36864
	ds_read_b128 v[58:61], v118 offset:36880
	ds_read_b128 v[62:65], v118 offset:38912
	ds_read_b128 v[100:103], v118 offset:38928
	v_add_f32_dpp v40, v40, v40 row_shr:1 row_mask:0xf bank_mask:0xf bound_ctrl:1
	s_nop 1
	v_add_f32_dpp v40, v40, v40 row_shr:2 row_mask:0xf bank_mask:0xf bound_ctrl:1
	s_nop 1
	v_add_f32_dpp v40, v40, v40 row_shr:4 row_mask:0xf bank_mask:0xf bound_ctrl:1
	s_nop 1
	v_add_f32_dpp v40, v40, v40 row_shr:8 row_mask:0xf bank_mask:0xf bound_ctrl:1
	s_nop 1
	v_mov_b32_dpp v41, v40 row_bcast:15 row_mask:0xa bank_mask:0xf
	v_add_f32_e32 v40, v40, v41
	v_mov_b32_e32 v41, v1
	s_nop 1
	v_mov_b32_dpp v41, v40 row_bcast:31 row_mask:0xc bank_mask:0xf
	v_add_f32_e32 v40, v40, v41
	v_mov_b32_e32 v41, v1
	v_readlane_b32 s51, v40, 63
	s_waitcnt lgkmcnt(0)
	v_mul_f32_e32 v40, v55, v47
	v_fmac_f32_e32 v40, v54, v46
	v_fmac_f32_e32 v40, v56, v48
	v_fmac_f32_e32 v40, v57, v49
	v_fmac_f32_e32 v40, v50, v58
	v_fmac_f32_e32 v40, v51, v59
	v_fmac_f32_e32 v40, v52, v60
	v_fmac_f32_e32 v40, v53, v61
	v_fmac_f32_e32 v40, v42, v62
	v_fmac_f32_e32 v40, v43, v63
	v_fmac_f32_e32 v40, v44, v64
	v_fmac_f32_e32 v40, v45, v65
	v_fmac_f32_e32 v40, v38, v100
	v_fmac_f32_e32 v40, v39, v101
	v_fmac_f32_e32 v40, v36, v102
	v_fmac_f32_e32 v40, v37, v103
	ds_read_b128 v[46:49], v118 offset:40960
	ds_read_b128 v[58:61], v118 offset:40976
	ds_read_b128 v[62:65], v118 offset:43008
	ds_read_b128 v[100:103], v118 offset:43024
	v_add_f32_dpp v40, v40, v40 row_shr:1 row_mask:0xf bank_mask:0xf bound_ctrl:1
	s_nop 1
	v_add_f32_dpp v40, v40, v40 row_shr:2 row_mask:0xf bank_mask:0xf bound_ctrl:1
	s_nop 1
	v_add_f32_dpp v40, v40, v40 row_shr:4 row_mask:0xf bank_mask:0xf bound_ctrl:1
	s_nop 1
	v_add_f32_dpp v40, v40, v40 row_shr:8 row_mask:0xf bank_mask:0xf bound_ctrl:1
	s_nop 1
	v_mov_b32_dpp v41, v40 row_bcast:15 row_mask:0xa bank_mask:0xf
	v_add_f32_e32 v40, v40, v41
	v_mov_b32_e32 v41, v1
	s_nop 1
	v_mov_b32_dpp v41, v40 row_bcast:31 row_mask:0xc bank_mask:0xf
	v_add_f32_e32 v40, v40, v41
	v_mov_b32_e32 v41, v1
	v_readlane_b32 s52, v40, 63
	s_waitcnt lgkmcnt(0)
; __device__ __forceinline__ unsigned pack2(float lo, float hi) { return pg8::cvt_pk_bf16(lo, hi); }
; __device__ __forceinline__ void phase_norm(const Params& p, unsigned char* lds, const float* __restrict__ xin, const float* g, const float* mod  , int shift_off, int scale_off, bf16_t* __restrict__ hout, const float* wsc  , float* scal) {
;     ...
;             const int row = rb + r4 + q;
;             const f32x4 x0 = xq[q][0], x1 = xq[q][1], x2 = xq[q][2], x3 = xq[q][3];
;             float xv[16] = {x0[0], x0[1], x0[2], x0[3], x1[0], x1[1], x1[2], x1[3], x2[0], x2[1], x2[2], x2[3], x3[0], x3[1], x3[2], x3[3]};
;             float ss = 0.f;
; #pragma unroll
;             for (int i = 0; i < 16; ++i) ss += xv[i] * xv[i];
;             ss = wave_sum(ss);
;             const float rstd = rsqrtf(ss * (1.0f / DM) + EPS);
;             float h[16];
; #pragma unroll
;             for (int i = 0; i < 16; ++i) h[i] = xv[i] * rstd * cs[i] + sh[i];
;             u32x4 w0, w1;
;             w0.x = pack2(h[0], h[1]); w0.y = pack2(h[2], h[3]); w0.z = pack2(h[4], h[5]); w0.w = pack2(h[6], h[7]);
;             w1.x = pack2(h[8], h[9]); w1.y = pack2(h[10], h[11]); w1.z = pack2(h[12], h[13]); w1.w = pack2(h[14], h[15]);
;             bf16_t* hp = hout + (size_t)row * DM + lane * 8;
;             *(u32x4*)hp = w0; *(u32x4*)(hp + 512) = w1;
;             if (wsc) {
;                 float mine = 0.f;
; #pragma unroll
;                 for (int j = 0; j < 12; ++j) {
;                     const float* wj = wl + j * DM + lane * 8;
;                     const f32x4 a0 = *(const f32x4*)wj, a1 = *(const f32x4*)(wj + 4), a2 = *(const f32x4*)(wj + 512), a3 = *(const f32x4*)(wj + 516);
;                     float s = h[0] * a0[0] + h[1] * a0[1] + h[2] * a0[2] + h[3] * a0[3] + h[4] * a1[0] + h[5] * a1[1] + h[6] * a1[2] + h[7] * a1[3]
;                             + h[8] * a2[0] + h[9] * a2[1] + h[10] * a2[2] + h[11] * a2[3] + h[12] * a3[0] + h[13] * a3[1] + h[14] * a3[2] + h[15] * a3[3];
;                     s = wave_sum(s);
;                     mine = (lane == j) ? s : mine;
;                 }
;                 if (lane < 12) scal[(size_t)row * 16 + lane] = mine;
	v_mul_f32_e32 v40, v55, v47
	v_fmac_f32_e32 v40, v54, v46
	v_fmac_f32_e32 v40, v56, v48
	v_fmac_f32_e32 v40, v57, v49
	v_fmac_f32_e32 v40, v50, v58
	v_fmac_f32_e32 v40, v51, v59
	v_fmac_f32_e32 v40, v52, v60
	v_fmac_f32_e32 v40, v53, v61
	v_fmac_f32_e32 v40, v42, v62
	v_fmac_f32_e32 v40, v43, v63
	v_fmac_f32_e32 v40, v44, v64
	v_fmac_f32_e32 v40, v45, v65
	v_fmac_f32_e32 v40, v38, v100
	v_fmac_f32_e32 v40, v39, v101
	v_fmac_f32_e32 v40, v36, v102
	v_fmac_f32_e32 v40, v37, v103
	ds_read_b128 v[46:49], v118 offset:45056
	ds_read_b128 v[58:61], v118 offset:45072
	ds_read_b128 v[62:65], v118 offset:47104
	ds_read_b128 v[100:103], v118 offset:47120
	v_add_f32_dpp v40, v40, v40 row_shr:1 row_mask:0xf bank_mask:0xf bound_ctrl:1
	s_nop 1
	v_add_f32_dpp v40, v40, v40 row_shr:2 row_mask:0xf bank_mask:0xf bound_ctrl:1
	s_nop 1
	v_add_f32_dpp v40, v40, v40 row_shr:4 row_mask:0xf bank_mask:0xf bound_ctrl:1
	s_nop 1
	v_add_f32_dpp v40, v40, v40 row_shr:8 row_mask:0xf bank_mask:0xf bound_ctrl:1
	s_nop 1
	v_mov_b32_dpp v41, v40 row_bcast:15 row_mask:0xa bank_mask:0xf
	v_add_f32_e32 v40, v40, v41
	v_mov_b32_e32 v41, v1
	s_nop 1
	v_mov_b32_dpp v41, v40 row_bcast:31 row_mask:0xc bank_mask:0xf
	v_add_f32_e32 v40, v40, v41
	s_nop 0
	v_readlane_b32 s54, v40, 63
	s_waitcnt lgkmcnt(0)
	v_mul_f32_e32 v40, v55, v47
	v_fmac_f32_e32 v40, v54, v46
	v_fmac_f32_e32 v40, v56, v48
	v_fmac_f32_e32 v40, v57, v49
	v_fmac_f32_e32 v40, v50, v58
	v_fmac_f32_e32 v40, v51, v59
	v_fmac_f32_e32 v40, v52, v60
	v_fmac_f32_e32 v40, v53, v61
	v_fmac_f32_e32 v40, v42, v62
	v_fmac_f32_e32 v40, v43, v63
	v_fmac_f32_e32 v40, v44, v64
	v_fmac_f32_e32 v40, v45, v65
	v_fmac_f32_e32 v40, v38, v100
	v_fmac_f32_e32 v40, v39, v101
	v_fmac_f32_e32 v40, v36, v102
	v_fmac_f32_e32 v40, v37, v103
	v_mov_b32_e32 v37, v1
	s_nop 0
	v_add_f32_dpp v36, v40, v40 row_shr:1 row_mask:0xf bank_mask:0xf bound_ctrl:1
	s_nop 1
	v_add_f32_dpp v36, v36, v36 row_shr:2 row_mask:0xf bank_mask:0xf bound_ctrl:1
	s_nop 1
	v_add_f32_dpp v36, v36, v36 row_shr:4 row_mask:0xf bank_mask:0xf bound_ctrl:1
	s_nop 1
	v_add_f32_dpp v36, v36, v36 row_shr:8 row_mask:0xf bank_mask:0xf bound_ctrl:1
	s_nop 1
	v_mov_b32_dpp v37, v36 row_bcast:15 row_mask:0xa bank_mask:0xf
	v_add_f32_e32 v36, v36, v37
	v_mov_b32_e32 v37, v1
	s_nop 1
	v_mov_b32_dpp v37, v36 row_bcast:31 row_mask:0xc bank_mask:0xf
	v_add_f32_e32 v36, v36, v37
	s_nop 0
	v_readlane_b32 s55, v36, 63
	s_and_saveexec_b64 s[0:1], s[6:7]
	s_cbranch_execz .LBB0_764
	v_mov_b32_e32 v36, s5
	v_cndmask_b32_e64 v36, 0, v36, s[30:31]
	v_mov_b32_e32 v37, s36
	v_cndmask_b32_e64 v36, v36, v37, s[28:29]
	v_mov_b32_e32 v37, s37
	v_cndmask_b32_e64 v36, v36, v37, s[26:27]
	v_mov_b32_e32 v37, s41
	v_cndmask_b32_e64 v36, v36, v37, s[24:25]
	v_mov_b32_e32 v37, s43
	v_cndmask_b32_e64 v36, v36, v37, s[22:23]
	v_mov_b32_e32 v37, s45
	v_cndmask_b32_e64 v36, v36, v37, s[20:21]
	v_mov_b32_e32 v37, s47
	v_cndmask_b32_e64 v36, v36, v37, s[18:19]
	v_mov_b32_e32 v37, s48
	v_cndmask_b32_e64 v36, v36, v37, s[16:17]
	v_mov_b32_e32 v37, s51
	v_cndmask_b32_e64 v36, v36, v37, s[14:15]
	v_mov_b32_e32 v37, s52
	v_cndmask_b32_e64 v36, v36, v37, s[12:13]
	v_mov_b32_e32 v37, s54
	v_cndmask_b32_e64 v36, v36, v37, s[10:11]
	v_mov_b32_e32 v37, s55
	v_cndmask_b32_e64 v38, v36, v37, s[8:9]
	v_add_co_u32_e32 v36, vcc, 0x100000, v98
	s_nop 1
	v_addc_co_u32_e32 v37, vcc, 0, v99, vcc
	global_store_dword v[36:37], v38, off offset:128
.LBB0_764:
	s_or_b64 exec, exec, s[0:1]
	v_mul_f32_e32 v40, v23, v23
	v_fmac_f32_e32 v40, v22, v22
	v_fmac_f32_e32 v40, v24, v24
	v_fmac_f32_e32 v40, v25, v25
	v_fmac_f32_e32 v40, v18, v18
	v_fmac_f32_e32 v40, v19, v19
	v_fmac_f32_e32 v40, v20, v20
	v_fmac_f32_e32 v40, v21, v21
	s_waitcnt vmcnt(0)
	v_fmac_f32_e32 v40, v30, v30
	v_fmac_f32_e32 v40, v31, v31
	v_fmac_f32_e32 v40, v32, v32
	v_fmac_f32_e32 v40, v33, v33
	v_pk_mul_f32 v[38:39], v[26:27], v[26:27]
	v_pk_mul_f32 v[36:37], v[28:29], v[28:29]
	v_add_f32_e32 v38, v38, v40
	v_add_f32_e32 v38, v39, v38
	v_add_f32_e32 v36, v36, v38
	v_add_f32_e32 v36, v37, v36
	v_mov_b32_e32 v37, v1
	s_nop 0
	v_add_f32_dpp v36, v36, v36 row_shr:1 row_mask:0xf bank_mask:0xf bound_ctrl:1
	s_nop 1
	v_add_f32_dpp v36, v36, v36 row_shr:2 row_mask:0xf bank_mask:0xf bound_ctrl:1
	s_nop 1
	v_add_f32_dpp v36, v36, v36 row_shr:4 row_mask:0xf bank_mask:0xf bound_ctrl:1
	s_nop 1
	v_add_f32_dpp v36, v36, v36 row_shr:8 row_mask:0xf bank_mask:0xf bound_ctrl:1
	s_nop 1
	v_mov_b32_dpp v37, v36 row_bcast:15 row_mask:0xa bank_mask:0xf
	v_add_f32_e32 v36, v36, v37
	v_mov_b32_e32 v37, v1
	s_nop 1
	v_mov_b32_dpp v37, v36 row_bcast:31 row_mask:0xc bank_mask:0xf
	v_add_f32_e32 v36, v36, v37
	s_nop 0
	v_readlane_b32 s0, v36, 63
	s_nop 1
	v_fma_f32 v36, s0, v217, v213
	v_mul_f32_e32 v37, 0x4b800000, v36
	v_cmp_gt_f32_e32 vcc, s44, v36
	s_nop 1
	v_cndmask_b32_e32 v36, v36, v37, vcc
	v_rsq_f32_e32 v36, v36
	s_nop 0
	v_mul_f32_e32 v37, 0x45800000, v36
	v_cndmask_b32_e32 v36, v36, v37, vcc
	v_pk_mul_f32 v[22:23], v[22:23], v[36:37] op_sel_hi:[1,0]
	s_nop 0
	v_pk_fma_f32 v[22:23], v[96:97], v[22:23], v[14:15]
	v_pk_mul_f32 v[14:15], v[24:25], v[36:37] op_sel_hi:[1,0]
	s_nop 0
	v_pk_fma_f32 v[16:17], v[94:95], v[14:15], v[16:17]
	v_pk_mul_f32 v[14:15], v[18:19], v[36:37] op_sel_hi:[1,0]
	v_cvt_pk_bf16_f32 v18, v22, v23
	v_pk_fma_f32 v[14:15], v[92:93], v[14:15], v[10:11]
	v_pk_mul_f32 v[10:11], v[20:21], v[36:37] op_sel_hi:[1,0]
	v_cvt_pk_bf16_f32 v19, v16, v17
	v_pk_fma_f32 v[12:13], v[90:91], v[10:11], v[12:13]
	v_pk_mul_f32 v[10:11], v[30:31], v[36:37] op_sel_hi:[1,0]
	v_cvt_pk_bf16_f32 v20, v14, v15
	v_cvt_pk_bf16_f32 v21, v12, v13
	v_pk_fma_f32 v[10:11], v[88:89], v[10:11], v[6:7]
	v_pk_mul_f32 v[6:7], v[32:33], v[36:37] op_sel_hi:[1,0]
	global_store_dwordx4 v[34:35], v[18:21], off offset:2048
	ds_read_b128 v[18:21], v118
	v_pk_fma_f32 v[8:9], v[86:87], v[6:7], v[8:9]
	v_pk_mul_f32 v[6:7], v[26:27], v[36:37] op_sel_hi:[1,0]
	v_cvt_pk_bf16_f32 v24, v10, v11
	v_pk_fma_f32 v[6:7], v[84:85], v[6:7], v[2:3]
	v_pk_mul_f32 v[2:3], v[28:29], v[36:37] op_sel_hi:[1,0]
	v_cvt_pk_bf16_f32 v25, v8, v9
	v_pk_fma_f32 v[2:3], v[82:83], v[2:3], v[4:5]
	v_cvt_pk_bf16_f32 v26, v6, v7
	v_cvt_pk_bf16_f32 v27, v2, v3
	global_store_dwordx4 v[34:35], v[24:27], off offset:3072
	s_waitcnt lgkmcnt(0)
; __device__ __forceinline__ void phase_norm(const Params& p, unsigned char* lds, const float* __restrict__ xin, const float* g, const float* mod  , int shift_off, int scale_off, bf16_t* __restrict__ hout, const float* wsc  , float* scal) {
;     ...
;                 for (int j = 0; j < 12; ++j) {
;                     const float* wj = wl + j * DM + lane * 8;
;                     const f32x4 a0 = *(const f32x4*)wj, a1 = *(const f32x4*)(wj + 4), a2 = *(const f32x4*)(wj + 512), a3 = *(const f32x4*)(wj + 516);
;                     float s = h[0] * a0[0] + h[1] * a0[1] + h[2] * a0[2] + h[3] * a0[3] + h[4] * a1[0] + h[5] * a1[1] + h[6] * a1[2] + h[7] * a1[3]
;                             + h[8] * a2[0] + h[9] * a2[1] + h[10] * a2[2] + h[11] * a2[3] + h[12] * a3[0] + h[13] * a3[1] + h[14] * a3[2] + h[15] * a3[3];
;                     s = wave_sum(s);
;                     mine = (lane == j) ? s : mine;
;                 }
	v_mul_f32_e32 v4, v19, v23
	ds_read_b128 v[24:27], v118 offset:16
	ds_read_b128 v[28:31], v118 offset:2048
	ds_read_b128 v[32:35], v118 offset:2064
	v_fmac_f32_e32 v4, v18, v22
	v_fmac_f32_e32 v4, v20, v16
	v_fmac_f32_e32 v4, v21, v17
	s_waitcnt lgkmcnt(0)
	v_fmac_f32_e32 v4, v24, v14
	v_fmac_f32_e32 v4, v25, v15
	v_fmac_f32_e32 v4, v26, v12
	v_fmac_f32_e32 v4, v27, v13
	v_fmac_f32_e32 v4, v28, v10
	v_fmac_f32_e32 v4, v29, v11
	v_fmac_f32_e32 v4, v30, v8
	v_fmac_f32_e32 v4, v31, v9
	v_fmac_f32_e32 v4, v32, v6
	v_fmac_f32_e32 v4, v33, v7
	v_fmac_f32_e32 v4, v34, v2
	v_fmac_f32_e32 v4, v35, v3
	v_mov_b32_e32 v5, v1
	ds_read_b128 v[18:21], v118 offset:4096
	v_add_f32_dpp v4, v4, v4 row_shr:1 row_mask:0xf bank_mask:0xf bound_ctrl:1
	ds_read_b128 v[24:27], v118 offset:4112
	ds_read_b128 v[28:31], v118 offset:6144
	ds_read_b128 v[32:35], v118 offset:6160
	v_add_f32_dpp v4, v4, v4 row_shr:2 row_mask:0xf bank_mask:0xf bound_ctrl:1
	s_nop 1
	v_add_f32_dpp v4, v4, v4 row_shr:4 row_mask:0xf bank_mask:0xf bound_ctrl:1
	s_nop 1
	v_add_f32_dpp v4, v4, v4 row_shr:8 row_mask:0xf bank_mask:0xf bound_ctrl:1
	s_nop 1
	v_mov_b32_dpp v5, v4 row_bcast:15 row_mask:0xa bank_mask:0xf
	v_add_f32_e32 v4, v4, v5
	v_mov_b32_e32 v5, v1
	s_nop 1
	v_mov_b32_dpp v5, v4 row_bcast:31 row_mask:0xc bank_mask:0xf
	v_add_f32_e32 v4, v4, v5
	v_mov_b32_e32 v5, v1
	v_readlane_b32 s5, v4, 63
	s_waitcnt lgkmcnt(0)
	v_mul_f32_e32 v4, v23, v19
	v_fmac_f32_e32 v4, v22, v18
	v_fmac_f32_e32 v4, v16, v20
	v_fmac_f32_e32 v4, v17, v21
	v_fmac_f32_e32 v4, v14, v24
	v_fmac_f32_e32 v4, v15, v25
	v_fmac_f32_e32 v4, v12, v26
	v_fmac_f32_e32 v4, v13, v27
	v_fmac_f32_e32 v4, v10, v28
	v_fmac_f32_e32 v4, v11, v29
	v_fmac_f32_e32 v4, v8, v30
	v_fmac_f32_e32 v4, v9, v31
	v_fmac_f32_e32 v4, v6, v32
	v_fmac_f32_e32 v4, v7, v33
	v_fmac_f32_e32 v4, v2, v34
	v_fmac_f32_e32 v4, v3, v35
	ds_read_b128 v[18:21], v118 offset:8192
	ds_read_b128 v[24:27], v118 offset:8208
	ds_read_b128 v[28:31], v118 offset:10240
	ds_read_b128 v[32:35], v118 offset:10256
	v_add_f32_dpp v4, v4, v4 row_shr:1 row_mask:0xf bank_mask:0xf bound_ctrl:1
	s_nop 1
	v_add_f32_dpp v4, v4, v4 row_shr:2 row_mask:0xf bank_mask:0xf bound_ctrl:1
	s_nop 1
	v_add_f32_dpp v4, v4, v4 row_shr:4 row_mask:0xf bank_mask:0xf bound_ctrl:1
	s_nop 1
	v_add_f32_dpp v4, v4, v4 row_shr:8 row_mask:0xf bank_mask:0xf bound_ctrl:1
	s_nop 1
	v_mov_b32_dpp v5, v4 row_bcast:15 row_mask:0xa bank_mask:0xf
	v_add_f32_e32 v4, v4, v5
	v_mov_b32_e32 v5, v1
	s_nop 1
	v_mov_b32_dpp v5, v4 row_bcast:31 row_mask:0xc bank_mask:0xf
	v_add_f32_e32 v4, v4, v5
	v_mov_b32_e32 v5, v1
	v_readlane_b32 s36, v4, 63
	s_waitcnt lgkmcnt(0)
	v_mul_f32_e32 v4, v23, v19
	v_fmac_f32_e32 v4, v22, v18
	v_fmac_f32_e32 v4, v16, v20
	v_fmac_f32_e32 v4, v17, v21
	v_fmac_f32_e32 v4, v14, v24
	v_fmac_f32_e32 v4, v15, v25
	v_fmac_f32_e32 v4, v12, v26
	v_fmac_f32_e32 v4, v13, v27
	v_fmac_f32_e32 v4, v10, v28
	v_fmac_f32_e32 v4, v11, v29
	v_fmac_f32_e32 v4, v8, v30
	v_fmac_f32_e32 v4, v9, v31
	v_fmac_f32_e32 v4, v6, v32
	v_fmac_f32_e32 v4, v7, v33
	v_fmac_f32_e32 v4, v2, v34
	v_fmac_f32_e32 v4, v3, v35
	ds_read_b128 v[18:21], v118 offset:12288
	ds_read_b128 v[24:27], v118 offset:12304
	ds_read_b128 v[28:31], v118 offset:14336
	ds_read_b128 v[32:35], v118 offset:14352
	v_add_f32_dpp v4, v4, v4 row_shr:1 row_mask:0xf bank_mask:0xf bound_ctrl:1
	s_nop 1
	v_add_f32_dpp v4, v4, v4 row_shr:2 row_mask:0xf bank_mask:0xf bound_ctrl:1
	s_nop 1
	v_add_f32_dpp v4, v4, v4 row_shr:4 row_mask:0xf bank_mask:0xf bound_ctrl:1
	s_nop 1
	v_add_f32_dpp v4, v4, v4 row_shr:8 row_mask:0xf bank_mask:0xf bound_ctrl:1
	s_nop 1
	v_mov_b32_dpp v5, v4 row_bcast:15 row_mask:0xa bank_mask:0xf
	v_add_f32_e32 v4, v4, v5
	v_mov_b32_e32 v5, v1
	s_nop 1
	v_mov_b32_dpp v5, v4 row_bcast:31 row_mask:0xc bank_mask:0xf
	v_add_f32_e32 v4, v4, v5
	v_mov_b32_e32 v5, v1
	v_readlane_b32 s37, v4, 63
	s_waitcnt lgkmcnt(0)
	v_mul_f32_e32 v4, v23, v19
	v_fmac_f32_e32 v4, v22, v18
	v_fmac_f32_e32 v4, v16, v20
	v_fmac_f32_e32 v4, v17, v21
	v_fmac_f32_e32 v4, v14, v24
	v_fmac_f32_e32 v4, v15, v25
	v_fmac_f32_e32 v4, v12, v26
	v_fmac_f32_e32 v4, v13, v27
	v_fmac_f32_e32 v4, v10, v28
	v_fmac_f32_e32 v4, v11, v29
	v_fmac_f32_e32 v4, v8, v30
	v_fmac_f32_e32 v4, v9, v31
	v_fmac_f32_e32 v4, v6, v32
	v_fmac_f32_e32 v4, v7, v33
	v_fmac_f32_e32 v4, v2, v34
	v_fmac_f32_e32 v4, v3, v35
	ds_read_b128 v[18:21], v118 offset:16384
	ds_read_b128 v[24:27], v118 offset:16400
	ds_read_b128 v[28:31], v118 offset:18432
	ds_read_b128 v[32:35], v118 offset:18448
	v_add_f32_dpp v4, v4, v4 row_shr:1 row_mask:0xf bank_mask:0xf bound_ctrl:1
	s_nop 1
	v_add_f32_dpp v4, v4, v4 row_shr:2 row_mask:0xf bank_mask:0xf bound_ctrl:1
	s_nop 1
	v_add_f32_dpp v4, v4, v4 row_shr:4 row_mask:0xf bank_mask:0xf bound_ctrl:1
	s_nop 1
	v_add_f32_dpp v4, v4, v4 row_shr:8 row_mask:0xf bank_mask:0xf bound_ctrl:1
	s_nop 1
	v_mov_b32_dpp v5, v4 row_bcast:15 row_mask:0xa bank_mask:0xf
	v_add_f32_e32 v4, v4, v5
	v_mov_b32_e32 v5, v1
	s_nop 1
	v_mov_b32_dpp v5, v4 row_bcast:31 row_mask:0xc bank_mask:0xf
	v_add_f32_e32 v4, v4, v5
	v_mov_b32_e32 v5, v1
	v_readlane_b32 s41, v4, 63
	s_waitcnt lgkmcnt(0)
; __device__ __forceinline__ void phase_norm(const Params& p, unsigned char* lds, const float* __restrict__ xin, const float* g, const float* mod  , int shift_off, int scale_off, bf16_t* __restrict__ hout, const float* wsc  , float* scal) {
;     ...
;                 for (int j = 0; j < 12; ++j) {
;                     const float* wj = wl + j * DM + lane * 8;
;                     const f32x4 a0 = *(const f32x4*)wj, a1 = *(const f32x4*)(wj + 4), a2 = *(const f32x4*)(wj + 512), a3 = *(const f32x4*)(wj + 516);
;                     float s = h[0] * a0[0] + h[1] * a0[1] + h[2] * a0[2] + h[3] * a0[3] + h[4] * a1[0] + h[5] * a1[1] + h[6] * a1[2] + h[7] * a1[3]
;                             + h[8] * a2[0] + h[9] * a2[1] + h[10] * a2[2] + h[11] * a2[3] + h[12] * a3[0] + h[13] * a3[1] + h[14] * a3[2] + h[15] * a3[3];
;                     s = wave_sum(s);
;                     mine = (lane == j) ? s : mine;
;                 }
	v_mul_f32_e32 v4, v23, v19
	v_fmac_f32_e32 v4, v22, v18
	v_fmac_f32_e32 v4, v16, v20
	v_fmac_f32_e32 v4, v17, v21
	v_fmac_f32_e32 v4, v14, v24
	v_fmac_f32_e32 v4, v15, v25
	v_fmac_f32_e32 v4, v12, v26
	v_fmac_f32_e32 v4, v13, v27
	v_fmac_f32_e32 v4, v10, v28
	v_fmac_f32_e32 v4, v11, v29
	v_fmac_f32_e32 v4, v8, v30
	v_fmac_f32_e32 v4, v9, v31
	v_fmac_f32_e32 v4, v6, v32
	v_fmac_f32_e32 v4, v7, v33
	v_fmac_f32_e32 v4, v2, v34
	v_fmac_f32_e32 v4, v3, v35
	ds_read_b128 v[18:21], v118 offset:20480
	ds_read_b128 v[24:27], v118 offset:20496
	ds_read_b128 v[28:31], v118 offset:22528
	ds_read_b128 v[32:35], v118 offset:22544
	v_add_f32_dpp v4, v4, v4 row_shr:1 row_mask:0xf bank_mask:0xf bound_ctrl:1
	s_nop 1
	v_add_f32_dpp v4, v4, v4 row_shr:2 row_mask:0xf bank_mask:0xf bound_ctrl:1
	s_nop 1
	v_add_f32_dpp v4, v4, v4 row_shr:4 row_mask:0xf bank_mask:0xf bound_ctrl:1
	s_nop 1
	v_add_f32_dpp v4, v4, v4 row_shr:8 row_mask:0xf bank_mask:0xf bound_ctrl:1
	s_nop 1
	v_mov_b32_dpp v5, v4 row_bcast:15 row_mask:0xa bank_mask:0xf
	v_add_f32_e32 v4, v4, v5
	v_mov_b32_e32 v5, v1
	s_nop 1
	v_mov_b32_dpp v5, v4 row_bcast:31 row_mask:0xc bank_mask:0xf
	v_add_f32_e32 v4, v4, v5
	v_mov_b32_e32 v5, v1
	v_readlane_b32 s43, v4, 63
	s_waitcnt lgkmcnt(0)
	v_mul_f32_e32 v4, v23, v19
	v_fmac_f32_e32 v4, v22, v18
	v_fmac_f32_e32 v4, v16, v20
	v_fmac_f32_e32 v4, v17, v21
	v_fmac_f32_e32 v4, v14, v24
	v_fmac_f32_e32 v4, v15, v25
	v_fmac_f32_e32 v4, v12, v26
	v_fmac_f32_e32 v4, v13, v27
	v_fmac_f32_e32 v4, v10, v28
	v_fmac_f32_e32 v4, v11, v29
	v_fmac_f32_e32 v4, v8, v30
	v_fmac_f32_e32 v4, v9, v31
	v_fmac_f32_e32 v4, v6, v32
	v_fmac_f32_e32 v4, v7, v33
	v_fmac_f32_e32 v4, v2, v34
	v_fmac_f32_e32 v4, v3, v35
	ds_read_b128 v[18:21], v118 offset:24576
	ds_read_b128 v[24:27], v118 offset:24592
	ds_read_b128 v[28:31], v118 offset:26624
	ds_read_b128 v[32:35], v118 offset:26640
	v_add_f32_dpp v4, v4, v4 row_shr:1 row_mask:0xf bank_mask:0xf bound_ctrl:1
	s_nop 1
	v_add_f32_dpp v4, v4, v4 row_shr:2 row_mask:0xf bank_mask:0xf bound_ctrl:1
	s_nop 1
	v_add_f32_dpp v4, v4, v4 row_shr:4 row_mask:0xf bank_mask:0xf bound_ctrl:1
	s_nop 1
	v_add_f32_dpp v4, v4, v4 row_shr:8 row_mask:0xf bank_mask:0xf bound_ctrl:1
	s_nop 1
	v_mov_b32_dpp v5, v4 row_bcast:15 row_mask:0xa bank_mask:0xf
	v_add_f32_e32 v4, v4, v5
	v_mov_b32_e32 v5, v1
	s_nop 1
	v_mov_b32_dpp v5, v4 row_bcast:31 row_mask:0xc bank_mask:0xf
	v_add_f32_e32 v4, v4, v5
	v_mov_b32_e32 v5, v1
	v_readlane_b32 s45, v4, 63
	s_waitcnt lgkmcnt(0)
	v_mul_f32_e32 v4, v23, v19
	v_fmac_f32_e32 v4, v22, v18
	v_fmac_f32_e32 v4, v16, v20
	v_fmac_f32_e32 v4, v17, v21
	v_fmac_f32_e32 v4, v14, v24
	v_fmac_f32_e32 v4, v15, v25
	v_fmac_f32_e32 v4, v12, v26
	v_fmac_f32_e32 v4, v13, v27
	v_fmac_f32_e32 v4, v10, v28
	v_fmac_f32_e32 v4, v11, v29
	v_fmac_f32_e32 v4, v8, v30
	v_fmac_f32_e32 v4, v9, v31
	v_fmac_f32_e32 v4, v6, v32
	v_fmac_f32_e32 v4, v7, v33
	v_fmac_f32_e32 v4, v2, v34
	v_fmac_f32_e32 v4, v3, v35
	ds_read_b128 v[18:21], v118 offset:28672
	ds_read_b128 v[24:27], v118 offset:28688
	ds_read_b128 v[28:31], v118 offset:30720
	ds_read_b128 v[32:35], v118 offset:30736
	v_add_f32_dpp v4, v4, v4 row_shr:1 row_mask:0xf bank_mask:0xf bound_ctrl:1
	s_nop 1
	v_add_f32_dpp v4, v4, v4 row_shr:2 row_mask:0xf bank_mask:0xf bound_ctrl:1
	s_nop 1
	v_add_f32_dpp v4, v4, v4 row_shr:4 row_mask:0xf bank_mask:0xf bound_ctrl:1
	s_nop 1
	v_add_f32_dpp v4, v4, v4 row_shr:8 row_mask:0xf bank_mask:0xf bound_ctrl:1
	s_nop 1
	v_mov_b32_dpp v5, v4 row_bcast:15 row_mask:0xa bank_mask:0xf
	v_add_f32_e32 v4, v4, v5
	v_mov_b32_e32 v5, v1
	s_nop 1
	v_mov_b32_dpp v5, v4 row_bcast:31 row_mask:0xc bank_mask:0xf
	v_add_f32_e32 v4, v4, v5
	v_mov_b32_e32 v5, v1
	v_readlane_b32 s47, v4, 63
	s_waitcnt lgkmcnt(0)
	v_mul_f32_e32 v4, v23, v19
	v_fmac_f32_e32 v4, v22, v18
	v_fmac_f32_e32 v4, v16, v20
	v_fmac_f32_e32 v4, v17, v21
	v_fmac_f32_e32 v4, v14, v24
	v_fmac_f32_e32 v4, v15, v25
	v_fmac_f32_e32 v4, v12, v26
	v_fmac_f32_e32 v4, v13, v27
	v_fmac_f32_e32 v4, v10, v28
	v_fmac_f32_e32 v4, v11, v29
	v_fmac_f32_e32 v4, v8, v30
	v_fmac_f32_e32 v4, v9, v31
	v_fmac_f32_e32 v4, v6, v32
	v_fmac_f32_e32 v4, v7, v33
	v_fmac_f32_e32 v4, v2, v34
	v_fmac_f32_e32 v4, v3, v35
	ds_read_b128 v[18:21], v118 offset:32768
	ds_read_b128 v[24:27], v118 offset:32784
	ds_read_b128 v[28:31], v118 offset:34816
	ds_read_b128 v[32:35], v118 offset:34832
	v_add_f32_dpp v4, v4, v4 row_shr:1 row_mask:0xf bank_mask:0xf bound_ctrl:1
	s_nop 1
	v_add_f32_dpp v4, v4, v4 row_shr:2 row_mask:0xf bank_mask:0xf bound_ctrl:1
	s_nop 1
	v_add_f32_dpp v4, v4, v4 row_shr:4 row_mask:0xf bank_mask:0xf bound_ctrl:1
	s_nop 1
	v_add_f32_dpp v4, v4, v4 row_shr:8 row_mask:0xf bank_mask:0xf bound_ctrl:1
	s_nop 1
	v_mov_b32_dpp v5, v4 row_bcast:15 row_mask:0xa bank_mask:0xf
	v_add_f32_e32 v4, v4, v5
	v_mov_b32_e32 v5, v1
	s_nop 1
	v_mov_b32_dpp v5, v4 row_bcast:31 row_mask:0xc bank_mask:0xf
	v_add_f32_e32 v4, v4, v5
	v_mov_b32_e32 v5, v1
	v_readlane_b32 s48, v4, 63
	s_waitcnt lgkmcnt(0)
; __device__ __forceinline__ void phase_norm(const Params& p, unsigned char* lds, const float* __restrict__ xin, const float* g, const float* mod  , int shift_off, int scale_off, bf16_t* __restrict__ hout, const float* wsc  , float* scal) {
;     ...
;             if (wsc) {
;                 float mine = 0.f;
; #pragma unroll
;                 for (int j = 0; j < 12; ++j) {
;                     const float* wj = wl + j * DM + lane * 8;
;                     const f32x4 a0 = *(const f32x4*)wj, a1 = *(const f32x4*)(wj + 4), a2 = *(const f32x4*)(wj + 512), a3 = *(const f32x4*)(wj + 516);
;                     float s = h[0] * a0[0] + h[1] * a0[1] + h[2] * a0[2] + h[3] * a0[3] + h[4] * a1[0] + h[5] * a1[1] + h[6] * a1[2] + h[7] * a1[3]
;                             + h[8] * a2[0] + h[9] * a2[1] + h[10] * a2[2] + h[11] * a2[3] + h[12] * a3[0] + h[13] * a3[1] + h[14] * a3[2] + h[15] * a3[3];
;                     s = wave_sum(s);
;                     mine = (lane == j) ? s : mine;
;                 }
;                 if (lane < 12) scal[(size_t)row * 16 + lane] = mine;
	v_mul_f32_e32 v4, v23, v19
	v_fmac_f32_e32 v4, v22, v18
	v_fmac_f32_e32 v4, v16, v20
	v_fmac_f32_e32 v4, v17, v21
	v_fmac_f32_e32 v4, v14, v24
	v_fmac_f32_e32 v4, v15, v25
	v_fmac_f32_e32 v4, v12, v26
	v_fmac_f32_e32 v4, v13, v27
	v_fmac_f32_e32 v4, v10, v28
	v_fmac_f32_e32 v4, v11, v29
	v_fmac_f32_e32 v4, v8, v30
	v_fmac_f32_e32 v4, v9, v31
	v_fmac_f32_e32 v4, v6, v32
	v_fmac_f32_e32 v4, v7, v33
	v_fmac_f32_e32 v4, v2, v34
	v_fmac_f32_e32 v4, v3, v35
	ds_read_b128 v[18:21], v118 offset:36864
	ds_read_b128 v[24:27], v118 offset:36880
	ds_read_b128 v[28:31], v118 offset:38912
	ds_read_b128 v[32:35], v118 offset:38928
	v_add_f32_dpp v4, v4, v4 row_shr:1 row_mask:0xf bank_mask:0xf bound_ctrl:1
	s_nop 1
	v_add_f32_dpp v4, v4, v4 row_shr:2 row_mask:0xf bank_mask:0xf bound_ctrl:1
	s_nop 1
	v_add_f32_dpp v4, v4, v4 row_shr:4 row_mask:0xf bank_mask:0xf bound_ctrl:1
	s_nop 1
	v_add_f32_dpp v4, v4, v4 row_shr:8 row_mask:0xf bank_mask:0xf bound_ctrl:1
	s_nop 1
	v_mov_b32_dpp v5, v4 row_bcast:15 row_mask:0xa bank_mask:0xf
	v_add_f32_e32 v4, v4, v5
	v_mov_b32_e32 v5, v1
	s_nop 1
	v_mov_b32_dpp v5, v4 row_bcast:31 row_mask:0xc bank_mask:0xf
	v_add_f32_e32 v4, v4, v5
	v_mov_b32_e32 v5, v1
	v_readlane_b32 s51, v4, 63
	s_waitcnt lgkmcnt(0)
	v_mul_f32_e32 v4, v23, v19
	v_fmac_f32_e32 v4, v22, v18
	v_fmac_f32_e32 v4, v16, v20
	v_fmac_f32_e32 v4, v17, v21
	v_fmac_f32_e32 v4, v14, v24
	v_fmac_f32_e32 v4, v15, v25
	v_fmac_f32_e32 v4, v12, v26
	v_fmac_f32_e32 v4, v13, v27
	v_fmac_f32_e32 v4, v10, v28
	v_fmac_f32_e32 v4, v11, v29
	v_fmac_f32_e32 v4, v8, v30
	v_fmac_f32_e32 v4, v9, v31
	v_fmac_f32_e32 v4, v6, v32
	v_fmac_f32_e32 v4, v7, v33
	v_fmac_f32_e32 v4, v2, v34
	v_fmac_f32_e32 v4, v3, v35
	ds_read_b128 v[18:21], v118 offset:40960
	ds_read_b128 v[24:27], v118 offset:40976
	ds_read_b128 v[28:31], v118 offset:43008
	ds_read_b128 v[32:35], v118 offset:43024
	v_add_f32_dpp v4, v4, v4 row_shr:1 row_mask:0xf bank_mask:0xf bound_ctrl:1
	s_nop 1
	v_add_f32_dpp v4, v4, v4 row_shr:2 row_mask:0xf bank_mask:0xf bound_ctrl:1
	s_nop 1
	v_add_f32_dpp v4, v4, v4 row_shr:4 row_mask:0xf bank_mask:0xf bound_ctrl:1
	s_nop 1
	v_add_f32_dpp v4, v4, v4 row_shr:8 row_mask:0xf bank_mask:0xf bound_ctrl:1
	s_nop 1
	v_mov_b32_dpp v5, v4 row_bcast:15 row_mask:0xa bank_mask:0xf
	v_add_f32_e32 v4, v4, v5
	v_mov_b32_e32 v5, v1
	s_nop 1
	v_mov_b32_dpp v5, v4 row_bcast:31 row_mask:0xc bank_mask:0xf
	v_add_f32_e32 v4, v4, v5
	v_mov_b32_e32 v5, v1
	v_readlane_b32 s52, v4, 63
	s_waitcnt lgkmcnt(0)
	v_mul_f32_e32 v4, v23, v19
	v_fmac_f32_e32 v4, v22, v18
	v_fmac_f32_e32 v4, v16, v20
	v_fmac_f32_e32 v4, v17, v21
	v_fmac_f32_e32 v4, v14, v24
	v_fmac_f32_e32 v4, v15, v25
	v_fmac_f32_e32 v4, v12, v26
	v_fmac_f32_e32 v4, v13, v27
	v_fmac_f32_e32 v4, v10, v28
	v_fmac_f32_e32 v4, v11, v29
	v_fmac_f32_e32 v4, v8, v30
	v_fmac_f32_e32 v4, v9, v31
	v_fmac_f32_e32 v4, v6, v32
	v_fmac_f32_e32 v4, v7, v33
	v_fmac_f32_e32 v4, v2, v34
	v_fmac_f32_e32 v4, v3, v35
	ds_read_b128 v[18:21], v118 offset:45056
	ds_read_b128 v[24:27], v118 offset:45072
	ds_read_b128 v[28:31], v118 offset:47104
	ds_read_b128 v[32:35], v118 offset:47120
	v_add_f32_dpp v4, v4, v4 row_shr:1 row_mask:0xf bank_mask:0xf bound_ctrl:1
	s_nop 1
	v_add_f32_dpp v4, v4, v4 row_shr:2 row_mask:0xf bank_mask:0xf bound_ctrl:1
	s_nop 1
	v_add_f32_dpp v4, v4, v4 row_shr:4 row_mask:0xf bank_mask:0xf bound_ctrl:1
	s_nop 1
	v_add_f32_dpp v4, v4, v4 row_shr:8 row_mask:0xf bank_mask:0xf bound_ctrl:1
	s_nop 1
	v_mov_b32_dpp v5, v4 row_bcast:15 row_mask:0xa bank_mask:0xf
	v_add_f32_e32 v4, v4, v5
	v_mov_b32_e32 v5, v1
	s_nop 1
	v_mov_b32_dpp v5, v4 row_bcast:31 row_mask:0xc bank_mask:0xf
	v_add_f32_e32 v4, v4, v5
	s_nop 0
	v_readlane_b32 s54, v4, 63
	s_waitcnt lgkmcnt(0)
	v_mul_f32_e32 v4, v23, v19
	v_fmac_f32_e32 v4, v22, v18
	v_fmac_f32_e32 v4, v16, v20
	v_fmac_f32_e32 v4, v17, v21
	v_fmac_f32_e32 v4, v14, v24
	v_fmac_f32_e32 v4, v15, v25
	v_fmac_f32_e32 v4, v12, v26
	v_fmac_f32_e32 v4, v13, v27
	v_fmac_f32_e32 v4, v10, v28
	v_fmac_f32_e32 v4, v11, v29
	v_fmac_f32_e32 v4, v8, v30
	v_fmac_f32_e32 v4, v9, v31
	v_fmac_f32_e32 v4, v6, v32
	v_fmac_f32_e32 v4, v7, v33
	v_fmac_f32_e32 v4, v2, v34
	v_fmac_f32_e32 v4, v3, v35
	v_mov_b32_e32 v3, v1
	s_nop 0
	v_add_f32_dpp v2, v4, v4 row_shr:1 row_mask:0xf bank_mask:0xf bound_ctrl:1
	s_nop 1
	v_add_f32_dpp v2, v2, v2 row_shr:2 row_mask:0xf bank_mask:0xf bound_ctrl:1
	s_nop 1
	v_add_f32_dpp v2, v2, v2 row_shr:4 row_mask:0xf bank_mask:0xf bound_ctrl:1
	s_nop 1
	v_add_f32_dpp v2, v2, v2 row_shr:8 row_mask:0xf bank_mask:0xf bound_ctrl:1
	s_nop 1
	v_mov_b32_dpp v3, v2 row_bcast:15 row_mask:0xa bank_mask:0xf
	v_add_f32_e32 v2, v2, v3
	v_mov_b32_e32 v3, v1
	s_nop 1
	v_mov_b32_dpp v3, v2 row_bcast:31 row_mask:0xc bank_mask:0xf
	v_add_f32_e32 v2, v2, v3
	s_nop 0
	v_readlane_b32 s55, v2, 63
	s_and_saveexec_b64 s[0:1], s[6:7]
	s_cbranch_execz .LBB0_757
	v_mov_b32_e32 v2, s5
	v_cndmask_b32_e64 v2, 0, v2, s[30:31]
	v_mov_b32_e32 v3, s36
	v_cndmask_b32_e64 v2, v2, v3, s[28:29]
	v_mov_b32_e32 v3, s37
	v_cndmask_b32_e64 v2, v2, v3, s[26:27]
	v_mov_b32_e32 v3, s41
	v_cndmask_b32_e64 v2, v2, v3, s[24:25]
	v_mov_b32_e32 v3, s43
	v_cndmask_b32_e64 v2, v2, v3, s[22:23]
	v_mov_b32_e32 v3, s45
	v_cndmask_b32_e64 v2, v2, v3, s[20:21]
	v_mov_b32_e32 v3, s47
	v_cndmask_b32_e64 v2, v2, v3, s[18:19]
	v_mov_b32_e32 v3, s48
	v_cndmask_b32_e64 v2, v2, v3, s[16:17]
	v_mov_b32_e32 v3, s51
	v_cndmask_b32_e64 v2, v2, v3, s[14:15]
	v_mov_b32_e32 v3, s52
	v_cndmask_b32_e64 v2, v2, v3, s[12:13]
	v_mov_b32_e32 v3, s54
	v_cndmask_b32_e64 v2, v2, v3, s[10:11]
	v_mov_b32_e32 v3, s55
	v_cndmask_b32_e64 v4, v2, v3, s[8:9]
	v_add_co_u32_e32 v2, vcc, 0x100000, v98
	s_nop 1
	v_addc_co_u32_e32 v3, vcc, 0, v99, vcc
	global_store_dword v[2:3], v4, off offset:192
	s_branch .LBB0_757

; __device__ __forceinline__ unsigned xb_ld(unsigned* p)              { return __hip_atomic_load(p, __ATOMIC_RELAXED, __HIP_MEMORY_SCOPE_AGENT); }
; __device__ __forceinline__ void xcd_barrier_complete(unsigned* bar, unsigned x, unsigned& nloc, unsigned& nx) {
;     ...
;     for (;;) {
;         sum = 0u; cnt = 0u; mine = 0u;
; #pragma unroll
;         for (unsigned j = 0; j < 16; ++j) { const unsigned c = xb_ld(&bar[XB_XCNT(j)]); sum += c; cnt += (c > 0u) ? 1u : 0u; mine = (j == x) ? c : mine; }
;         if (sum == G) break;
;         __builtin_amdgcn_s_sleep(1);
;         if ((++sp & 255u) == 0u) { if (xb_ld(&bar[XB_TMO])) break; if (sp > XB_SPIN_CAP) { atomicAdd(&bar[XB_TMO], 1u); break; } }
;     }
.LBB0_774:
	v_mov_b64_e32 v[2:3], s[4:5]
	global_load_dword v0, v[2:3], off sc1
	v_mov_b64_e32 v[2:3], s[6:7]
	global_load_dword v2, v[2:3], off sc1
	v_mov_b64_e32 v[4:5], s[8:9]
	global_load_dword v3, v[4:5], off sc1
	v_mov_b64_e32 v[4:5], s[10:11]
	global_load_dword v4, v[4:5], off sc1
	s_or_b64 s[90:91], s[90:91], exec
	s_or_b64 s[78:79], s[78:79], exec
	s_waitcnt vmcnt(0) lgkmcnt(0)
	v_add_u32_e32 v6, v2, v0
	v_add_u32_e32 v6, v6, v3
	v_add_u32_e32 v8, v6, v4
	v_mov_b64_e32 v[6:7], s[12:13]
	global_load_dword v5, v[6:7], off sc1
	v_mov_b64_e32 v[6:7], s[14:15]
	global_load_dword v6, v[6:7], off sc1
	s_waitcnt vmcnt(0) lgkmcnt(0)
	v_add_u32_e32 v8, v8, v5
	v_add_u32_e32 v10, v8, v6
	v_mov_b64_e32 v[8:9], s[16:17]
	global_load_dword v7, v[8:9], off sc1
	v_mov_b64_e32 v[8:9], s[18:19]
	global_load_dword v8, v[8:9], off sc1
	s_waitcnt vmcnt(0) lgkmcnt(0)
	v_add_u32_e32 v10, v10, v7
	v_add_u32_e32 v12, v10, v8
	v_mov_b64_e32 v[10:11], s[20:21]
	global_load_dword v9, v[10:11], off sc1
	v_mov_b64_e32 v[10:11], s[22:23]
	global_load_dword v10, v[10:11], off sc1
	s_waitcnt vmcnt(0) lgkmcnt(0)
	v_add_u32_e32 v12, v12, v9
	v_add_u32_e32 v14, v12, v10
	v_mov_b64_e32 v[12:13], s[24:25]
	global_load_dword v11, v[12:13], off sc1
	v_mov_b64_e32 v[12:13], s[26:27]
	global_load_dword v12, v[12:13], off sc1
	s_waitcnt vmcnt(0) lgkmcnt(0)
	v_add_u32_e32 v14, v14, v11
	v_add_u32_e32 v16, v14, v12
	v_mov_b64_e32 v[14:15], s[28:29]
	global_load_dword v13, v[14:15], off sc1
	v_mov_b64_e32 v[14:15], s[30:31]
	global_load_dword v14, v[14:15], off sc1
	s_waitcnt vmcnt(0) lgkmcnt(0)
	v_add_u32_e32 v16, v16, v13
	v_add_u32_e32 v18, v16, v14
	v_mov_b64_e32 v[16:17], s[34:35]
	global_load_dword v15, v[16:17], off sc1
	v_mov_b64_e32 v[16:17], s[36:37]
	global_load_dword v16, v[16:17], off sc1
	s_waitcnt vmcnt(0) lgkmcnt(0)
	v_add_u32_e32 v18, v18, v15
	v_add_u32_e32 v17, v18, v16
	v_cmp_ne_u32_e32 vcc, s43, v17
	s_and_saveexec_b64 s[92:93], vcc
	s_cbranch_execz .LBB0_773
	s_and_b32 s47, s45, 0xff
	s_mov_b64 s[96:97], -1
	s_cmp_eq_u32 s47, 0
	s_mov_b64 s[72:73], -1
	s_mov_b64 s[82:83], -1
	s_sleep 1
	s_cbranch_scc1 .LBB0_777
	s_and_saveexec_b64 s[74:75], s[72:73]
	s_cbranch_execz .LBB0_772
	s_branch .LBB0_780
.LBB0_777:
	v_mov_b64_e32 v[18:19], s[0:1]
	global_load_dword v17, v[18:19], off sc1
	s_mov_b64 s[72:73], 0
	s_waitcnt vmcnt(0) lgkmcnt(0)
	v_cmp_eq_u32_e32 vcc, 0, v17
	s_and_saveexec_b64 s[74:75], vcc
	s_cmp_lt_u32 s45, 0x40001
	s_cselect_b64 s[54:55], -1, 0
	s_xor_b64 s[82:83], exec, -1
	s_and_b64 s[72:73], s[54:55], exec
	s_or_b64 exec, exec, s[74:75]
	s_and_saveexec_b64 s[74:75], s[72:73]
	s_cbranch_execz .LBB0_772

; __device__ __forceinline__ unsigned xb_ld(unsigned* p)              { return __hip_atomic_load(p, __ATOMIC_RELAXED, __HIP_MEMORY_SCOPE_AGENT); }
; __device__ __forceinline__ void xcd_barrier_complete(unsigned* bar, unsigned x, unsigned& nloc, unsigned& nx) {
;     ...
;         if ((++sp & 255u) == 0u) { if (xb_ld(&bar[XB_TMO])) break; if (sp > XB_SPIN_CAP) { atomicAdd(&bar[XB_TMO], 1u); break; } }
.LBB0_781:
	s_or_b64 exec, exec, s[38:39]
	s_xor_b64 s[4:5], s[76:77], -1
	s_and_saveexec_b64 s[6:7], s[4:5]
	s_xor_b64 s[4:5], exec, s[6:7]
	s_cbranch_execz .LBB0_783
	v_mov_b64_e32 v[18:19], s[0:1]
	global_atomic_add v[18:19], v214, off

; __device__ __forceinline__ unsigned xb_ld(unsigned* p)              { return __hip_atomic_load(p, __ATOMIC_RELAXED, __HIP_MEMORY_SCOPE_AGENT); }
; __device__ __forceinline__ unsigned xb_add(unsigned* p, unsigned v) { return __hip_atomic_fetch_add(p, v, __ATOMIC_RELAXED, __HIP_MEMORY_SCOPE_AGENT); }
; #define XB_SPIN(cond, bar) do { unsigned _sp = 0; while (cond) { __builtin_amdgcn_s_sleep(1); \
;     if ((++_sp & 255u) == 0u) { if (xb_ld(&(bar)[XB_TMO])) break; if (_sp > XB_SPIN_CAP) { atomicAdd(&(bar)[XB_TMO], 1u); break; } } } } while (0)
; __device__ __forceinline__ void xcd_barrier(const XcdBarrier& b) {
;     ...
;         unsigned nloc = b.st[0], nx = b.st[1];
;         if (nloc == 0u) { xcd_barrier_complete(bar, b.x, nloc, nx); b.st[0] = nloc; b.st[1] = nx; }
;         const unsigned old = xb_add(&bar[XB_XSUB(b.x)], 1u);
;         const unsigned gen = old / nloc;
;         if (old + 1u == (gen + 1u) * nloc) {
;             __builtin_amdgcn_fence(__ATOMIC_RELEASE, "agent");
;             asm volatile("s_waitcnt vmcnt(0)" ::: "memory");
;             const unsigned og = xb_add(&bar[XB_TOP], 1u);
;             const unsigned tg = og / nx;
;             if (og + 1u == (tg + 1u) * nx) xb_add(&bar[XB_TOPGEN], 1u);
;             else XB_SPIN(xb_ld(&bar[XB_TOPGEN]) == tg, bar);
;             __builtin_amdgcn_fence(__ATOMIC_ACQUIRE, "agent");
;             xb_add(&bar[XB_XGEN(b.x)], 1u);
;             asm volatile("s_waitcnt vmcnt(0)" ::: "memory");
;         } else {
;             XB_SPIN(xb_ld(&bar[XB_XGEN(b.x)]) == gen, bar);
.LBB0_784:
	s_lshl_b32 s0, s41, 8
	s_add_u32 s0, s86, s0
	s_addc_u32 s1, s87, 0
	v_mov_b32_e32 v3, s0
	v_add_co_u32_e32 v4, vcc, 0xe2000, v3
	v_mov_b32_e32 v3, s1
	s_nop 0
	v_addc_co_u32_e32 v5, vcc, 0, v3, vcc
	global_atomic_add v4, v[4:5], v214, off offset:1024 sc0
	v_cvt_f32_u32_e32 v3, v2
	v_sub_u32_e32 v5, 0, v2
	s_add_u32 s25, s0, 0xe1000
	s_addc_u32 s24, s1, 0
	v_rcp_iflag_f32_e32 v3, v3
	s_nop 0
	v_mul_f32_e32 v3, 0x4f7ffffe, v3
	v_cvt_u32_f32_e32 v3, v3
	v_mul_lo_u32 v5, v5, v3
	v_mul_hi_u32 v5, v3, v5
	v_add_u32_e32 v3, v3, v5
	s_waitcnt vmcnt(0) lgkmcnt(0)
	v_mul_hi_u32 v3, v4, v3
	v_mul_lo_u32 v5, v3, v2
	v_sub_u32_e32 v5, v4, v5
	v_cmp_ge_u32_e32 vcc, v5, v2
	v_add_u32_e32 v6, 1, v3
	s_nop 0
	v_cndmask_b32_e32 v3, v3, v6, vcc
	v_sub_u32_e32 v6, v5, v2
	v_cndmask_b32_e32 v5, v5, v6, vcc
	v_cmp_ge_u32_e32 vcc, v5, v2
	v_add_u32_e32 v5, 1, v3
	v_add_u32_e32 v6, 1, v4
	v_cndmask_b32_e32 v3, v3, v5, vcc
	v_mad_u64_u32 v[4:5], s[0:1], v2, v3, v[2:3]
	v_cmp_ne_u32_e32 vcc, v6, v4
	s_and_saveexec_b64 s[0:1], vcc
	s_xor_b64 s[0:1], exec, s[0:1]
	s_cbranch_execz .LBB0_798
	v_mov_b32_e32 v0, s25
	v_add_co_u32_e32 v4, vcc, 0x2000, v0
	v_mov_b32_e32 v0, s24
	s_nop 0
	v_addc_co_u32_e32 v5, vcc, 0, v0, vcc
	global_load_dword v0, v[4:5], off offset:1024 sc1
	s_add_u32 s6, s25, 0x2400
	s_addc_u32 s7, s24, 0
	s_waitcnt vmcnt(0) lgkmcnt(0)
	v_cmp_eq_u32_e32 vcc, v0, v3
	s_and_saveexec_b64 s[4:5], vcc
	s_cbranch_execz .LBB0_797
	s_add_u32 s8, s86, 0xe1200
	s_addc_u32 s9, s87, 0
	s_mov_b32 s26, 1
	s_mov_b64 s[10:11], 0
	s_branch .LBB0_788

; __device__ __forceinline__ unsigned xb_ld(unsigned* p)              { return __hip_atomic_load(p, __ATOMIC_RELAXED, __HIP_MEMORY_SCOPE_AGENT); }
; #define XB_SPIN(cond, bar) do { unsigned _sp = 0; while (cond) { __builtin_amdgcn_s_sleep(1); \
;     if ((++_sp & 255u) == 0u) { if (xb_ld(&(bar)[XB_TMO])) break; if (_sp > XB_SPIN_CAP) { atomicAdd(&(bar)[XB_TMO], 1u); break; } } } } while (0)
; __device__ __forceinline__ void xcd_barrier(const XcdBarrier& b) {
;     ...
;             XB_SPIN(xb_ld(&bar[XB_XGEN(b.x)]) == gen, bar);
.LBB0_788:
	s_and_b32 s18, s26, 0xff
	s_mov_b64 s[16:17], -1
	s_cmp_lg_u32 s18, 0
	s_mov_b64 s[18:19], -1
	s_sleep 1
	s_cbranch_scc1 .LBB0_792
	v_mov_b64_e32 v[4:5], s[8:9]
	global_load_dword v0, v[4:5], off sc1
	s_mov_b64 s[18:19], 0
	s_mov_b64 s[20:21], -1
	s_waitcnt vmcnt(0) lgkmcnt(0)
	v_cmp_eq_u32_e32 vcc, 0, v0
	s_and_saveexec_b64 s[22:23], vcc
	s_cmp_lt_u32 s26, 0x40001
	s_cselect_b64 s[18:19], -1, 0
	s_xor_b64 s[20:21], exec, -1
	s_and_b64 s[18:19], s[18:19], exec
	s_or_b64 exec, exec, s[22:23]
.LBB0_792:
	s_andn2_b64 s[14:15], s[14:15], exec
	s_and_b64 s[20:21], s[20:21], exec
	s_or_b64 s[14:15], s[14:15], s[20:21]
	s_and_saveexec_b64 s[20:21], s[18:19]
	s_cbranch_execz .LBB0_787
	v_mov_b64_e32 v[4:5], s[6:7]
	global_load_dword v0, v[4:5], off sc1
	s_add_i32 s26, s26, 1
	s_or_b64 s[14:15], s[14:15], exec
	s_waitcnt vmcnt(0) lgkmcnt(0)
	v_cmp_ne_u32_e32 vcc, v0, v3
	s_orn2_b64 s[16:17], vcc, exec
	s_branch .LBB0_787

.LBB0_795:
	s_or_b64 exec, exec, s[10:11]
	s_xor_b64 s[6:7], s[12:13], -1
	s_and_saveexec_b64 s[10:11], s[6:7]
	s_xor_b64 s[10:11], exec, s[10:11]
	s_cbranch_execz .LBB0_797
	v_mov_b64_e32 v[2:3], s[8:9]
	global_atomic_add v[2:3], v214, off

; __device__ __forceinline__ unsigned xb_ld(unsigned* p)              { return __hip_atomic_load(p, __ATOMIC_RELAXED, __HIP_MEMORY_SCOPE_AGENT); }
; __device__ __forceinline__ unsigned xb_add(unsigned* p, unsigned v) { return __hip_atomic_fetch_add(p, v, __ATOMIC_RELAXED, __HIP_MEMORY_SCOPE_AGENT); }
; #define XB_SPIN(cond, bar) do { unsigned _sp = 0; while (cond) { __builtin_amdgcn_s_sleep(1); \
;     if ((++_sp & 255u) == 0u) { if (xb_ld(&(bar)[XB_TMO])) break; if (_sp > XB_SPIN_CAP) { atomicAdd(&(bar)[XB_TMO], 1u); break; } } } } while (0)
; __device__ __forceinline__ void xcd_barrier(const XcdBarrier& b) {
;     ...
;         if (old + 1u == (gen + 1u) * nloc) {
;             __builtin_amdgcn_fence(__ATOMIC_RELEASE, "agent");
;             asm volatile("s_waitcnt vmcnt(0)" ::: "memory");
;             const unsigned og = xb_add(&bar[XB_TOP], 1u);
;             const unsigned tg = og / nx;
;             if (og + 1u == (tg + 1u) * nx) xb_add(&bar[XB_TOPGEN], 1u);
;             else XB_SPIN(xb_ld(&bar[XB_TOPGEN]) == tg, bar);
.LBB0_798:
	s_andn2_saveexec_b64 s[0:1], s[0:1]
	s_cbranch_execz .LBB0_816
	v_mov_b32_e32 v2, s86
	v_add_co_u32_e32 v2, vcc, 0xe4000, v2
	v_mov_b32_e32 v3, s87
	buffer_wbl2 sc1
	s_waitcnt vmcnt(0)
	v_addc_co_u32_e32 v3, vcc, 0, v3, vcc
	global_atomic_add v2, v[2:3], v214, off offset:1024 sc0
	v_cvt_f32_u32_e32 v3, v0
	v_sub_u32_e32 v4, 0, v0
	s_mov_b64 s[6:7], -1
	v_rcp_iflag_f32_e32 v3, v3
	s_nop 0
	v_mul_f32_e32 v3, 0x4f7ffffe, v3
	v_cvt_u32_f32_e32 v3, v3
	v_mul_lo_u32 v4, v4, v3
	v_mul_hi_u32 v4, v3, v4
	v_add_u32_e32 v3, v3, v4
	s_waitcnt vmcnt(0) lgkmcnt(0)
	v_mul_hi_u32 v3, v2, v3
	v_mul_lo_u32 v4, v3, v0
	v_sub_u32_e32 v4, v2, v4
	v_cmp_ge_u32_e32 vcc, v4, v0
	v_add_u32_e32 v5, 1, v3
	s_nop 0
	v_cndmask_b32_e32 v3, v3, v5, vcc
	v_sub_u32_e32 v5, v4, v0
	v_cndmask_b32_e32 v4, v4, v5, vcc
	v_cmp_ge_u32_e32 vcc, v4, v0
	v_add_u32_e32 v4, 1, v3
	v_add_u32_e32 v5, 1, v2
	v_cndmask_b32_e32 v4, v3, v4, vcc
	v_mad_u64_u32 v[2:3], s[0:1], v0, v4, v[0:1]
	s_add_u32 s0, s86, 0xe4500
	s_addc_u32 s1, s87, 0
	v_cmp_ne_u32_e32 vcc, v5, v2
	v_mov_b64_e32 v[2:3], s[0:1]
	s_and_saveexec_b64 s[4:5], vcc
	s_cbranch_execz .LBB0_813
	v_mov_b64_e32 v[2:3], s[0:1]
	global_load_dword v0, v[2:3], off sc1
	s_mov_b64 s[10:11], 0
	s_waitcnt vmcnt(0) lgkmcnt(0)
	v_cmp_eq_u32_e32 vcc, v0, v4
	s_and_saveexec_b64 s[8:9], vcc
	s_cbranch_execz .LBB0_812
	s_add_u32 s6, s86, 0xe1200
	s_addc_u32 s7, s87, 0
	s_mov_b32 s22, 1
	s_branch .LBB0_803

; __device__ __forceinline__ unsigned xb_ld(unsigned* p)              { return __hip_atomic_load(p, __ATOMIC_RELAXED, __HIP_MEMORY_SCOPE_AGENT); }
; #define XB_SPIN(cond, bar) do { unsigned _sp = 0; while (cond) { __builtin_amdgcn_s_sleep(1); \
;     if ((++_sp & 255u) == 0u) { if (xb_ld(&(bar)[XB_TMO])) break; if (_sp > XB_SPIN_CAP) { atomicAdd(&(bar)[XB_TMO], 1u); break; } } } } while (0)
; __device__ __forceinline__ void xcd_barrier(const XcdBarrier& b) {
;     ...
;             else XB_SPIN(xb_ld(&bar[XB_TOPGEN]) == tg, bar);
.LBB0_805:
	v_mov_b64_e32 v[2:3], s[6:7]
	global_load_dword v0, v[2:3], off sc1
	s_mov_b64 s[18:19], 0
	s_mov_b64 s[16:17], -1
	s_waitcnt vmcnt(0) lgkmcnt(0)
	v_cmp_eq_u32_e32 vcc, 0, v0
	s_and_saveexec_b64 s[20:21], vcc
	s_cmp_lt_u32 s22, 0x40001
	s_cselect_b64 s[18:19], -1, 0
	s_xor_b64 s[16:17], exec, -1
	s_and_b64 s[18:19], s[18:19], exec
	s_or_b64 exec, exec, s[20:21]
	s_and_saveexec_b64 s[20:21], s[18:19]
	s_cbranch_execz .LBB0_802
.LBB0_808:
	v_mov_b64_e32 v[2:3], s[0:1]
	global_load_dword v0, v[2:3], off sc1
	s_add_i32 s22, s22, 1
	s_or_b64 s[16:17], s[16:17], exec
	s_waitcnt vmcnt(0) lgkmcnt(0)
	v_cmp_ne_u32_e32 vcc, v0, v4
	s_orn2_b64 s[14:15], vcc, exec
	s_branch .LBB0_802

; __device__ __forceinline__ unsigned xb_ld(unsigned* p)              { return __hip_atomic_load(p, __ATOMIC_RELAXED, __HIP_MEMORY_SCOPE_AGENT); }
; __device__ __forceinline__ unsigned xb_add(unsigned* p, unsigned v) { return __hip_atomic_fetch_add(p, v, __ATOMIC_RELAXED, __HIP_MEMORY_SCOPE_AGENT); }
; #define XB_SPIN(cond, bar) do { unsigned _sp = 0; while (cond) { __builtin_amdgcn_s_sleep(1); \
;     if ((++_sp & 255u) == 0u) { if (xb_ld(&(bar)[XB_TMO])) break; if (_sp > XB_SPIN_CAP) { atomicAdd(&(bar)[XB_TMO], 1u); break; } } } } while (0)
; __device__ __forceinline__ void xcd_barrier(const XcdBarrier& b) {
;     ...
;             if (og + 1u == (tg + 1u) * nx) xb_add(&bar[XB_TOPGEN], 1u);
;             else XB_SPIN(xb_ld(&bar[XB_TOPGEN]) == tg, bar);
;             __builtin_amdgcn_fence(__ATOMIC_ACQUIRE, "agent");
;             xb_add(&bar[XB_XGEN(b.x)], 1u);
;             asm volatile("s_waitcnt vmcnt(0)" ::: "memory");
.LBB0_813:
	s_or_b64 exec, exec, s[4:5]
	s_and_saveexec_b64 s[0:1], s[6:7]
	s_cbranch_execz .LBB0_815
	global_atomic_add v[2:3], v214, off
.LBB0_815:
	s_or_b64 exec, exec, s[0:1]
	v_mov_b32_e32 v0, s25
	v_add_co_u32_e32 v2, vcc, 0x2000, v0
	v_mov_b32_e32 v0, s24
	s_nop 0
	v_addc_co_u32_e32 v3, vcc, 0, v0, vcc
	s_waitcnt vmcnt(0) lgkmcnt(0)
	buffer_inv sc1
	global_atomic_add v[2:3], v214, off offset:1024
	s_waitcnt vmcnt(0)
